# v8 plus kf_units load section rewritten by hand (all loads issued first, one wait) and Hyena neighbour-element loads without per-element waits
# speedup vs baseline: 1.0272x; 1.0073x over previous
.LBB0_262:
	s_and_b32 s49, s48, 0x3ff
	s_and_b32 s3, s11, 0x3ff
	s_cmpk_lt_u32 s11, 0x400
	s_mul_i32 s4, s3, 0xc000
	s_cselect_b32 s10, 0, 0x8000
	s_add_u32 s4, s44, s4
	s_addc_u32 s5, s45, 0
	s_add_u32 s4, s4, s10
	s_addc_u32 s5, s5, 0
	s_add_u32 s38, s4, 0x6000000
	s_addc_u32 s39, s5, 0
	s_bitset1_b32 s3, 10
	s_mul_i32 s3, s3, 0xc000
	s_add_u32 s3, s44, s3
	s_addc_u32 s12, s45, 0
	s_add_u32 s22, s3, s10
	s_addc_u32 s23, s12, 0
	s_add_u32 s40, s4, 0x9000000
	s_addc_u32 s41, s5, 0
	s_cmpk_gt_u32 s11, 0x3ff
	s_mov_b64 s[30:31], -1
	s_cbranch_scc0 .LBB0_286
	v_mov_b32_e32 v2, v0
	v_ashrrev_i32_e32 v1, 4, v2
	v_lshlrev_b32_e32 v1, 3, v1
	v_lshlrev_b32_e32 v3, 3, v2
	v_add3_u32 v1, 0, v1, v3
	v_lshlrev_b32_e32 v4, 2, v2
	v_sub_u32_e32 v5, 0x4000, v4
	global_load_dword v20, v4, s[4:5]
	global_load_dword v21, v4, s[22:23]
	global_load_dword v24, v4, s[4:5] offset:2048
	global_load_dword v25, v4, s[22:23] offset:2048
	v_add_u32_e32 v4, 0x1000, v4
	global_load_dword v28, v4, s[4:5]
	global_load_dword v29, v4, s[22:23]
	global_load_dword v32, v4, s[4:5] offset:2048
	global_load_dword v33, v4, s[22:23] offset:2048
	v_add_u32_e32 v4, 0x1000, v4
	global_load_dword v36, v4, s[4:5]
	global_load_dword v37, v4, s[22:23]
	global_load_dword v40, v4, s[4:5] offset:2048
	global_load_dword v41, v4, s[22:23] offset:2048
	v_add_u32_e32 v4, 0x1000, v4
	global_load_dword v44, v4, s[4:5]
	global_load_dword v45, v4, s[22:23]
	global_load_dword v48, v4, s[4:5] offset:2048
	global_load_dword v49, v4, s[22:23] offset:2048
	global_load_dword v22, v5, s[38:39]
	global_load_dword v23, v5, s[40:41]
	global_load_dword v26, v5, s[38:39] offset:-2048
	global_load_dword v27, v5, s[40:41] offset:-2048
	v_add_u32_e32 v5, 0xfffff000, v5
	global_load_dword v30, v5, s[38:39]
	global_load_dword v31, v5, s[40:41]
	global_load_dword v34, v5, s[38:39] offset:-2048
	global_load_dword v35, v5, s[40:41] offset:-2048
	v_add_u32_e32 v5, 0xfffff000, v5
	global_load_dword v38, v5, s[38:39]
	global_load_dword v39, v5, s[40:41]
	global_load_dword v42, v5, s[38:39] offset:-2048
	global_load_dword v43, v5, s[40:41] offset:-2048
	v_add_u32_e32 v5, 0xfffff000, v5
	global_load_dword v46, v5, s[38:39]
	global_load_dword v47, v5, s[40:41]
	global_load_dword v50, v5, s[38:39] offset:-2048
	global_load_dword v51, v5, s[40:41] offset:-2048
	v_cmp_eq_u32_e32 vcc, 0, v2
	s_waitcnt vmcnt(0)
	s_nop 1
	v_cndmask_b32_e64 v22, v22, 0, vcc
	v_cndmask_b32_e64 v23, v23, 0, vcc
	ds_write_b64 v1, v[20:21]
	ds_write_b64 v1, v[22:23] offset:34816
	ds_write_b64 v1, v[24:25] offset:4352
	ds_write_b64 v1, v[26:27] offset:39168
	ds_write_b64 v1, v[28:29] offset:8704
	ds_write_b64 v1, v[30:31] offset:43520
	ds_write_b64 v1, v[32:33] offset:13056
	ds_write_b64 v1, v[34:35] offset:47872
	ds_write_b64 v1, v[36:37] offset:17408
	ds_write_b64 v1, v[38:39] offset:52224
	ds_write_b64 v1, v[40:41] offset:21760
	ds_write_b64 v1, v[42:43] offset:56576
	ds_write_b64 v1, v[44:45] offset:26112
	ds_write_b64 v1, v[46:47] offset:60928
	ds_write_b64 v1, v[48:49] offset:30464
	ds_write_b64 v1, v[50:51] offset:65280
	v_mov_b32_e32 v1, v0
	s_waitcnt lgkmcnt(0)
	s_barrier
	s_movk_i32 s3, 0xe000
	v_and_b32_e32 v2, 0x1ff, v1
	v_lshlrev_b32_e32 v1, 4, v1
	v_and_or_b32 v1, v1, s3, v2
	v_ashrrev_i32_e32 v3, 4, v1
	v_cvt_f32_u32_e32 v2, v2
	v_lshlrev_b32_e32 v3, 3, v3
	v_lshlrev_b32_e32 v1, 3, v1
	v_add3_u32 v1, 0, v3, v1
	ds_read_b64 v[16:17], v1
	ds_read_b64 v[6:7], v1 offset:4352
	ds_read_b64 v[10:11], v1 offset:8704
	ds_read_b64 v[12:13], v1 offset:13056
	ds_read_b64 v[18:19], v1 offset:17408
	ds_read_b64 v[20:21], v1 offset:21760
	ds_read_b64 v[22:23], v1 offset:26112
	ds_read_b64 v[24:25], v1 offset:30464
	ds_read_b64 v[26:27], v1 offset:34816
	ds_read_b64 v[28:29], v1 offset:39168
	ds_read_b64 v[30:31], v1 offset:43520
	ds_read_b64 v[32:33], v1 offset:47872
	ds_read_b64 v[34:35], v1 offset:56576
	ds_read_b64 v[36:37], v1 offset:60928
	ds_read_b64 v[38:39], v1 offset:65280
	ds_read_b64 v[40:41], v1 offset:52224
	v_mul_f32_e32 v2, 0x39000000, v2
	v_cos_f32_e32 v14, v2
	v_sin_f32_e32 v15, v2
	s_waitcnt lgkmcnt(6)
	v_pk_add_f32 v[2:3], v[6:7], v[28:29] neg_lo:[0,1] neg_hi:[0,1]
	s_waitcnt lgkmcnt(3)
	v_pk_add_f32 v[4:5], v[20:21], v[34:35] neg_lo:[0,1] neg_hi:[0,1]
	v_pk_add_f32 v[6:7], v[6:7], v[28:29]
	v_pk_add_f32 v[8:9], v[2:3], v[4:5] op_sel:[0,1] op_sel_hi:[1,0]
	v_pk_add_f32 v[42:43], v[2:3], v[4:5] op_sel:[0,1] op_sel_hi:[1,0] neg_lo:[0,1] neg_hi:[0,1]
	v_mov_b32_e32 v2, v8
	v_mov_b32_e32 v3, v43
	v_mov_b32_e32 v43, v9
	v_pk_add_f32 v[4:5], v[10:11], v[30:31] neg_lo:[0,1] neg_hi:[0,1]
	s_waitcnt lgkmcnt(2)
	v_pk_add_f32 v[8:9], v[22:23], v[36:37] neg_lo:[0,1] neg_hi:[0,1]
	v_pk_add_f32 v[20:21], v[20:21], v[34:35]
	v_pk_add_f32 v[44:45], v[4:5], v[8:9] op_sel:[0,1] op_sel_hi:[1,0]
	v_pk_add_f32 v[46:47], v[4:5], v[8:9] op_sel:[0,1] op_sel_hi:[1,0] neg_lo:[0,1] neg_hi:[0,1]
	v_pk_add_f32 v[4:5], v[12:13], v[32:33] neg_lo:[0,1] neg_hi:[0,1]
	s_waitcnt lgkmcnt(1)
	v_pk_add_f32 v[8:9], v[24:25], v[38:39] neg_lo:[0,1] neg_hi:[0,1]
	v_pk_add_f32 v[28:29], v[6:7], v[20:21]
	v_pk_add_f32 v[6:7], v[6:7], v[20:21] neg_lo:[0,1] neg_hi:[0,1]
	v_pk_add_f32 v[10:11], v[10:11], v[30:31]
	v_pk_add_f32 v[20:21], v[22:23], v[36:37]
	v_mov_b32_e32 v48, v44
	v_mov_b32_e32 v49, v47
	v_mov_b32_e32 v47, v45
	v_pk_add_f32 v[44:45], v[4:5], v[8:9] op_sel:[0,1] op_sel_hi:[1,0]
	v_pk_add_f32 v[50:51], v[4:5], v[8:9] op_sel:[0,1] op_sel_hi:[1,0] neg_lo:[0,1] neg_hi:[0,1]
	v_mov_b64_e32 v[8:9], s[6:7]
	v_pk_mul_f32 v[4:5], v[2:3], v[8:9] op_sel:[0,0] op_sel_hi:[0,1]
	v_pk_add_f32 v[22:23], v[10:11], v[20:21]
	v_pk_add_f32 v[20:21], v[10:11], v[20:21] neg_lo:[0,1] neg_hi:[0,1]
	v_pk_add_f32 v[10:11], v[12:13], v[32:33]
	v_pk_add_f32 v[12:13], v[24:25], v[38:39]
	v_mov_b32_e32 v52, v44
	v_mov_b32_e32 v53, v51
	v_mov_b32_e32 v51, v45
	v_pk_fma_f32 v[44:45], v[2:3], v[8:9], v[4:5] op_sel:[1,1,0] op_sel_hi:[1,0,1] neg_lo:[1,0,0]
	v_mov_b64_e32 v[4:5], s[16:17]
	v_pk_add_f32 v[24:25], v[10:11], v[12:13]
	v_pk_add_f32 v[12:13], v[10:11], v[12:13] neg_lo:[0,1] neg_hi:[0,1]
	v_pk_mul_f32 v[10:11], v[6:7], v[4:5] op_sel:[0,0] op_sel_hi:[0,1]
	v_pk_mul_f32 v[2:3], v[48:49], v[4:5] op_sel:[0,0] op_sel_hi:[0,1]
	s_waitcnt lgkmcnt(0)
	v_pk_add_f32 v[56:57], v[18:19], v[40:41]
	v_pk_fma_f32 v[30:31], v[6:7], v[4:5], v[10:11] op_sel:[1,1,0] op_sel_hi:[1,0,1] neg_lo:[1,0,0]
	v_mov_b64_e32 v[10:11], s[60:61]
	v_pk_mul_f32 v[6:7], v[20:21], v[10:11] op_sel:[0,0] op_sel_hi:[0,1]
	v_pk_fma_f32 v[48:49], v[48:49], v[4:5], v[2:3] op_sel:[1,1,0] op_sel_hi:[1,0,1] neg_lo:[1,0,0]
	v_mov_b64_e32 v[2:3], s[18:19]
	v_pk_mul_f32 v[54:55], v[52:53], v[2:3] op_sel:[0,0] op_sel_hi:[0,1]
	v_pk_fma_f32 v[20:21], v[20:21], v[10:11], v[6:7] op_sel:[1,1,0] op_sel_hi:[1,0,1] neg_lo:[1,0,0]
	v_mov_b64_e32 v[6:7], s[20:21]
	v_pk_mul_f32 v[32:33], v[12:13], v[6:7] op_sel:[0,0] op_sel_hi:[0,1]
	v_pk_fma_f32 v[52:53], v[52:53], v[2:3], v[54:55] op_sel:[1,1,0] op_sel_hi:[1,0,1] neg_lo:[1,0,0]
	v_pk_add_f32 v[54:55], v[16:17], v[26:27]
	v_pk_fma_f32 v[32:33], v[12:13], v[6:7], v[32:33] op_sel:[1,1,0] op_sel_hi:[1,0,1] neg_lo:[1,0,0]
	v_pk_mul_f32 v[12:13], v[42:43], v[2:3] op_sel:[0,0] op_sel_hi:[0,1]
	v_pk_add_f32 v[16:17], v[16:17], v[26:27] neg_lo:[0,1] neg_hi:[0,1]
	v_pk_add_f32 v[58:59], v[54:55], v[56:57]
	v_pk_fma_f32 v[34:35], v[42:43], v[2:3], v[12:13] op_sel:[1,1,0] op_sel_hi:[1,0,1] neg_lo:[1,0,0]
	v_pk_mul_f32 v[12:13], v[46:47], v[6:7] op_sel:[0,0] op_sel_hi:[0,1]
	v_pk_add_f32 v[18:19], v[18:19], v[40:41] neg_lo:[0,1] neg_hi:[0,1]
	v_pk_fma_f32 v[36:37], v[46:47], v[6:7], v[12:13] op_sel:[1,1,0] op_sel_hi:[1,0,1] neg_lo:[1,0,0]
	v_mov_b64_e32 v[12:13], s[8:9]
	v_pk_mul_f32 v[38:39], v[50:51], v[12:13] op_sel:[0,0] op_sel_hi:[0,1]
	v_pk_add_f32 v[42:43], v[58:59], v[22:23]
	v_pk_add_f32 v[46:47], v[28:29], v[24:25]
	v_pk_fma_f32 v[38:39], v[50:51], v[12:13], v[38:39] op_sel:[1,1,0] op_sel_hi:[1,0,1] neg_lo:[1,0,0]
	v_pk_add_f32 v[26:27], v[16:17], v[18:19] op_sel:[0,1] op_sel_hi:[1,0] neg_lo:[0,1] neg_hi:[0,1]
	v_pk_add_f32 v[50:51], v[42:43], v[46:47]
	v_pk_add_f32 v[42:43], v[42:43], v[46:47] neg_lo:[0,1] neg_hi:[0,1]
	v_pk_add_f32 v[46:47], v[54:55], v[56:57] neg_lo:[0,1] neg_hi:[0,1]
	v_pk_add_f32 v[16:17], v[16:17], v[18:19] op_sel:[0,1] op_sel_hi:[1,0]
	v_pk_add_f32 v[54:55], v[46:47], v[20:21] neg_lo:[0,1] neg_hi:[0,1]
	v_pk_add_f32 v[56:57], v[30:31], v[32:33] neg_lo:[0,1] neg_hi:[0,1]
	v_pk_add_f32 v[30:31], v[30:31], v[32:33]
	v_pk_add_f32 v[20:21], v[46:47], v[20:21]
	v_mov_b32_e32 v18, v26
	v_mov_b32_e32 v19, v17
	v_pk_add_f32 v[32:33], v[20:21], v[30:31]
	v_pk_add_f32 v[20:21], v[20:21], v[30:31] neg_lo:[0,1] neg_hi:[0,1]
	v_pk_add_f32 v[30:31], v[54:55], v[56:57] op_sel:[0,1] op_sel_hi:[1,0]
	v_pk_add_f32 v[46:47], v[54:55], v[56:57] op_sel:[0,1] op_sel_hi:[1,0] neg_lo:[0,1] neg_hi:[0,1]
	v_pk_add_f32 v[40:41], v[44:45], v[52:53] neg_lo:[0,1] neg_hi:[0,1]
	v_pk_add_f32 v[44:45], v[44:45], v[52:53]
	v_pk_add_f32 v[52:53], v[18:19], v[36:37] neg_lo:[0,1] neg_hi:[0,1]
	v_pk_add_f32 v[56:57], v[34:35], v[38:39] neg_lo:[0,1] neg_hi:[0,1]
	v_pk_add_f32 v[34:35], v[34:35], v[38:39]
	v_pk_add_f32 v[18:19], v[18:19], v[36:37]
	s_nop 1
	v_pk_add_f32 v[38:39], v[52:53], v[56:57] op_sel:[0,1] op_sel_hi:[1,0] neg_lo:[0,1] neg_hi:[0,1]
	v_pk_add_f32 v[36:37], v[18:19], v[34:35]
	v_pk_add_f32 v[18:19], v[18:19], v[34:35] neg_lo:[0,1] neg_hi:[0,1]
	v_pk_add_f32 v[34:35], v[52:53], v[56:57] op_sel:[0,1] op_sel_hi:[1,0]
	v_xor_b32_e32 v15, 0x80000000, v15
	v_pk_mul_f32 v[56:57], v[14:15], v[14:15] op_sel:[0,0] op_sel_hi:[0,1]
	v_mov_b32_e32 v17, v27
	v_pk_fma_f32 v[56:57], v[14:15], v[14:15], v[56:57] op_sel:[1,1,0] op_sel_hi:[1,0,1] neg_lo:[1,0,0]
	v_pk_add_f32 v[22:23], v[58:59], v[22:23] neg_lo:[0,1] neg_hi:[0,1]
	v_pk_mul_f32 v[60:61], v[56:57], v[56:57] op_sel:[0,0] op_sel_hi:[0,1]
	v_pk_add_f32 v[24:25], v[28:29], v[24:25] neg_lo:[0,1] neg_hi:[0,1]
	v_pk_fma_f32 v[60:61], v[56:57], v[56:57], v[60:61] op_sel:[1,1,0] op_sel_hi:[1,0,1] neg_lo:[1,0,0]
	v_pk_add_f32 v[26:27], v[16:17], v[48:49] neg_lo:[0,1] neg_hi:[0,1]
	v_pk_mul_f32 v[68:69], v[60:61], v[60:61] op_sel:[0,0] op_sel_hi:[0,1]
	v_pk_add_f32 v[16:17], v[16:17], v[48:49]
	v_pk_mul_f32 v[62:63], v[60:61], v[14:15] op_sel:[0,0] op_sel_hi:[0,1]
	v_pk_fma_f32 v[68:69], v[60:61], v[60:61], v[68:69] op_sel:[1,1,0] op_sel_hi:[1,0,1] neg_lo:[1,0,0]
	v_pk_add_f32 v[28:29], v[22:23], v[24:25] op_sel:[0,1] op_sel_hi:[1,0]
	v_pk_mul_f32 v[70:71], v[68:69], v[14:15] op_sel:[0,0] op_sel_hi:[0,1]
	v_pk_add_f32 v[22:23], v[22:23], v[24:25] op_sel:[0,1] op_sel_hi:[1,0] neg_lo:[0,1] neg_hi:[0,1]
	v_pk_add_f32 v[48:49], v[16:17], v[44:45]
	v_pk_add_f32 v[16:17], v[16:17], v[44:45] neg_lo:[0,1] neg_hi:[0,1]
	v_mov_b32_e32 v52, v38
	v_mov_b32_e32 v53, v35
	v_pk_mul_f32 v[58:59], v[56:57], v[14:15] op_sel:[0,0] op_sel_hi:[0,1]
	v_pk_fma_f32 v[62:63], v[60:61], v[14:15], v[62:63] op_sel:[1,1,0] op_sel_hi:[1,0,1] neg_lo:[1,0,0]
	v_pk_fma_f32 v[70:71], v[68:69], v[14:15], v[70:71] op_sel:[1,1,0] op_sel_hi:[1,0,1] neg_lo:[1,0,0]
	v_mov_b32_e32 v35, v39
	v_pk_mul_f32 v[72:73], v[62:63], v[62:63] op_sel:[0,0] op_sel_hi:[0,1]
	v_pk_mul_f32 v[38:39], v[16:17], v[70:71] op_sel:[0,0] op_sel_hi:[0,1]
	v_mov_b32_e32 v24, v22
	v_mov_b32_e32 v25, v29
	v_pk_fma_f32 v[58:59], v[56:57], v[14:15], v[58:59] op_sel:[1,1,0] op_sel_hi:[1,0,1] neg_lo:[1,0,0]
	v_pk_fma_f32 v[72:73], v[62:63], v[62:63], v[72:73] op_sel:[1,1,0] op_sel_hi:[1,0,1] neg_lo:[1,0,0]
	v_mov_b32_e32 v29, v23
	v_pk_mul_f32 v[64:65], v[58:59], v[58:59] op_sel:[0,0] op_sel_hi:[0,1]
	v_pk_mul_f32 v[74:75], v[68:69], v[58:59] op_sel:[0,0] op_sel_hi:[0,1]
	v_pk_mul_f32 v[22:23], v[28:29], v[60:61] op_sel:[0,0] op_sel_hi:[0,1]
	v_pk_fma_f32 v[16:17], v[16:17], v[70:71], v[38:39] op_sel:[1,1,0] op_sel_hi:[1,0,1] neg_lo:[1,0,0]
	v_pk_mul_f32 v[38:39], v[20:21], v[72:73] op_sel:[0,0] op_sel_hi:[0,1]
	v_mov_b32_e32 v55, v31
	v_pk_fma_f32 v[64:65], v[58:59], v[58:59], v[64:65] op_sel:[1,1,0] op_sel_hi:[1,0,1] neg_lo:[1,0,0]
	v_pk_mul_f32 v[66:67], v[60:61], v[58:59] op_sel:[0,0] op_sel_hi:[0,1]
	v_pk_fma_f32 v[74:75], v[68:69], v[58:59], v[74:75] op_sel:[1,1,0] op_sel_hi:[1,0,1] neg_lo:[1,0,0]
	v_pk_fma_f32 v[22:23], v[28:29], v[60:61], v[22:23] op_sel:[1,1,0] op_sel_hi:[1,0,1] neg_lo:[1,0,0]
	v_mov_b32_e32 v31, v47
	v_pk_mul_f32 v[76:77], v[64:65], v[64:65] op_sel:[0,0] op_sel_hi:[0,1]
	v_pk_mul_f32 v[28:29], v[30:31], v[64:65] op_sel:[0,0] op_sel_hi:[0,1]
	v_pk_fma_f32 v[20:21], v[20:21], v[72:73], v[38:39] op_sel:[1,1,0] op_sel_hi:[1,0,1] neg_lo:[1,0,0]
	v_pk_mul_f32 v[38:39], v[18:19], v[74:75] op_sel:[0,0] op_sel_hi:[0,1]
	v_pk_add_f32 v[44:45], v[26:27], v[40:41] op_sel:[0,1] op_sel_hi:[1,0]
	v_pk_add_f32 v[26:27], v[26:27], v[40:41] op_sel:[0,1] op_sel_hi:[1,0] neg_lo:[0,1] neg_hi:[0,1]
	v_pk_fma_f32 v[66:67], v[60:61], v[58:59], v[66:67] op_sel:[1,1,0] op_sel_hi:[1,0,1] neg_lo:[1,0,0]
	v_pk_fma_f32 v[76:77], v[64:65], v[64:65], v[76:77] op_sel:[1,1,0] op_sel_hi:[1,0,1] neg_lo:[1,0,0]
	v_pk_mul_f32 v[78:79], v[68:69], v[62:63] op_sel:[0,0] op_sel_hi:[0,1]
	v_pk_fma_f32 v[28:29], v[30:31], v[64:65], v[28:29] op_sel:[1,1,0] op_sel_hi:[1,0,1] neg_lo:[1,0,0]
	v_pk_fma_f32 v[18:19], v[18:19], v[74:75], v[38:39] op_sel:[1,1,0] op_sel_hi:[1,0,1] neg_lo:[1,0,0]
	s_nop 0
	v_mov_b32_e32 v40, v26
	v_pk_mul_f32 v[30:31], v[34:35], v[66:67] op_sel:[0,0] op_sel_hi:[0,1]
	v_pk_mul_f32 v[38:39], v[24:25], v[76:77] op_sel:[0,0] op_sel_hi:[0,1]
	v_mov_b32_e32 v41, v45
	v_pk_fma_f32 v[78:79], v[68:69], v[62:63], v[78:79] op_sel:[1,1,0] op_sel_hi:[1,0,1] neg_lo:[1,0,0]
	v_pk_mul_f32 v[80:81], v[66:67], v[66:67] op_sel:[0,0] op_sel_hi:[0,1]
	v_pk_mul_f32 v[82:83], v[68:69], v[66:67] op_sel:[0,0] op_sel_hi:[0,1]
	v_pk_fma_f32 v[30:31], v[34:35], v[66:67], v[30:31] op_sel:[1,1,0] op_sel_hi:[1,0,1] neg_lo:[1,0,0]
	v_pk_mul_f32 v[34:35], v[42:43], v[68:69] op_sel:[0,0] op_sel_hi:[0,1]
	v_pk_fma_f32 v[24:25], v[24:25], v[76:77], v[38:39] op_sel:[1,1,0] op_sel_hi:[1,0,1] neg_lo:[1,0,0]
	s_nop 0
	v_pk_mul_f32 v[38:39], v[40:41], v[78:79] op_sel:[0,0] op_sel_hi:[0,1]
	v_mov_b32_e32 v54, v46
	v_pk_fma_f32 v[80:81], v[66:67], v[66:67], v[80:81] op_sel:[1,1,0] op_sel_hi:[1,0,1] neg_lo:[1,0,0]
	v_pk_fma_f32 v[82:83], v[68:69], v[66:67], v[82:83] op_sel:[1,1,0] op_sel_hi:[1,0,1] neg_lo:[1,0,0]
	v_pk_mul_f32 v[84:85], v[48:49], v[14:15] op_sel:[0,0] op_sel_hi:[0,1]
	v_mov_b32_e32 v45, v27
	v_pk_fma_f32 v[14:15], v[48:49], v[14:15], v[84:85] op_sel:[1,1,0] op_sel_hi:[1,0,1] neg_lo:[1,0,0]
	v_pk_mul_f32 v[48:49], v[32:33], v[56:57] op_sel:[0,0] op_sel_hi:[0,1]
	v_pk_mul_f32 v[26:27], v[44:45], v[62:63] op_sel:[0,0] op_sel_hi:[0,1]
	v_pk_fma_f32 v[34:35], v[42:43], v[68:69], v[34:35] op_sel:[1,1,0] op_sel_hi:[1,0,1] neg_lo:[1,0,0]
	v_pk_fma_f32 v[38:39], v[40:41], v[78:79], v[38:39] op_sel:[1,1,0] op_sel_hi:[1,0,1] neg_lo:[1,0,0]
	v_pk_mul_f32 v[40:41], v[54:55], v[80:81] op_sel:[0,0] op_sel_hi:[0,1]
	v_pk_mul_f32 v[42:43], v[52:53], v[82:83] op_sel:[0,0] op_sel_hi:[0,1]
	s_nop 0
	v_pk_fma_f32 v[32:33], v[32:33], v[56:57], v[48:49] op_sel:[1,1,0] op_sel_hi:[1,0,1] neg_lo:[1,0,0]
	v_pk_mul_f32 v[48:49], v[36:37], v[58:59] op_sel:[0,0] op_sel_hi:[0,1]
	v_pk_fma_f32 v[26:27], v[44:45], v[62:63], v[26:27] op_sel:[1,1,0] op_sel_hi:[1,0,1] neg_lo:[1,0,0]
	s_movk_i32 s3, 0xfe00
	v_pk_fma_f32 v[36:37], v[36:37], v[58:59], v[48:49] op_sel:[1,1,0] op_sel_hi:[1,0,1] neg_lo:[1,0,0]
	v_pk_fma_f32 v[40:41], v[54:55], v[80:81], v[40:41] op_sel:[1,1,0] op_sel_hi:[1,0,1] neg_lo:[1,0,0]
	v_pk_fma_f32 v[42:43], v[52:53], v[82:83], v[42:43] op_sel:[1,1,0] op_sel_hi:[1,0,1] neg_lo:[1,0,0]
	ds_write_b64 v1, v[50:51]
	ds_write_b64 v1, v[14:15] offset:4352
	ds_write_b64 v1, v[32:33] offset:8704
	ds_write_b64 v1, v[36:37] offset:13056
	ds_write_b64 v1, v[22:23] offset:17408
	ds_write_b64 v1, v[26:27] offset:21760
	ds_write_b64 v1, v[28:29] offset:26112
	ds_write_b64 v1, v[30:31] offset:30464
	ds_write_b64 v1, v[34:35] offset:34816
	ds_write_b64 v1, v[16:17] offset:39168
	ds_write_b64 v1, v[20:21] offset:43520
	ds_write_b64 v1, v[18:19] offset:47872
	ds_write_b64 v1, v[24:25] offset:52224
	ds_write_b64 v1, v[38:39] offset:56576
	ds_write_b64 v1, v[40:41] offset:60928
	ds_write_b64 v1, v[42:43] offset:65280
	v_mov_b32_e32 v1, v0
	s_waitcnt lgkmcnt(0)
	s_barrier
	s_nop 0
	v_and_b32_e32 v14, 31, v1
	v_lshlrev_b32_e32 v1, 4, v1
	v_and_or_b32 v1, v1, s3, v14
	v_ashrrev_i32_e32 v15, 4, v1
	v_lshlrev_b32_e32 v15, 3, v15
	v_lshlrev_b32_e32 v1, 3, v1
	v_cvt_f32_ubyte0_e32 v14, v14
	v_add3_u32 v1, 0, v15, v1
	v_mul_f32_e32 v14, 0x3b000000, v14
	v_cos_f32_e32 v46, v14
	v_sin_f32_e32 v47, v14
	ds_read2_b64 v[14:17], v1 offset1:34
	ds_read2_b64 v[18:21], v1 offset0:68 offset1:102
	ds_read2_b64 v[22:25], v1 offset0:136 offset1:170
	v_add_u32_e32 v86, 0x800, v1
	ds_read2_b64 v[26:29], v86 offset0:16 offset1:50
	ds_read2_b64 v[30:33], v86 offset0:152 offset1:186
	ds_read2_b64 v[34:37], v1 offset0:204 offset1:238
	ds_read2_b64 v[38:41], v86 offset0:84 offset1:118
	ds_read2_b64 v[42:45], v86 offset0:220 offset1:254
	s_waitcnt lgkmcnt(4)
	v_pk_add_f32 v[48:49], v[16:17], v[28:29] neg_lo:[0,1] neg_hi:[0,1]
	v_pk_add_f32 v[16:17], v[16:17], v[28:29]
	s_waitcnt lgkmcnt(3)
	v_pk_add_f32 v[50:51], v[24:25], v[32:33] neg_lo:[0,1] neg_hi:[0,1]
	v_pk_add_f32 v[24:25], v[24:25], v[32:33]
	v_pk_add_f32 v[52:53], v[48:49], v[50:51] op_sel:[0,1] op_sel_hi:[1,0]
	v_pk_add_f32 v[48:49], v[48:49], v[50:51] op_sel:[0,1] op_sel_hi:[1,0] neg_lo:[0,1] neg_hi:[0,1]
	v_mov_b32_e32 v50, v52
	v_mov_b32_e32 v51, v49
	v_mov_b32_e32 v49, v53
	s_waitcnt lgkmcnt(1)
	v_pk_add_f32 v[52:53], v[18:19], v[38:39] neg_lo:[0,1] neg_hi:[0,1]
	s_waitcnt lgkmcnt(0)
	v_pk_add_f32 v[54:55], v[34:35], v[42:43] neg_lo:[0,1] neg_hi:[0,1]
	v_pk_add_f32 v[58:59], v[36:37], v[44:45] neg_lo:[0,1] neg_hi:[0,1]
	v_pk_add_f32 v[56:57], v[52:53], v[54:55] op_sel:[0,1] op_sel_hi:[1,0]
	v_pk_add_f32 v[52:53], v[52:53], v[54:55] op_sel:[0,1] op_sel_hi:[1,0] neg_lo:[0,1] neg_hi:[0,1]
	v_mov_b32_e32 v54, v56
	v_mov_b32_e32 v55, v53
	v_mov_b32_e32 v53, v57
	v_pk_add_f32 v[56:57], v[20:21], v[40:41] neg_lo:[0,1] neg_hi:[0,1]
	v_pk_add_f32 v[28:29], v[16:17], v[24:25]
	v_pk_add_f32 v[60:61], v[56:57], v[58:59] op_sel:[0,1] op_sel_hi:[1,0]
	v_pk_add_f32 v[56:57], v[56:57], v[58:59] op_sel:[0,1] op_sel_hi:[1,0] neg_lo:[0,1] neg_hi:[0,1]
	v_pk_add_f32 v[16:17], v[16:17], v[24:25] neg_lo:[0,1] neg_hi:[0,1]
	v_pk_add_f32 v[18:19], v[18:19], v[38:39]
	v_pk_add_f32 v[24:25], v[34:35], v[42:43]
	v_mov_b32_e32 v58, v60
	v_mov_b32_e32 v59, v57
	v_mov_b32_e32 v57, v61
	v_pk_mul_f32 v[60:61], v[50:51], v[8:9] op_sel:[0,0] op_sel_hi:[0,1]
	v_pk_add_f32 v[32:33], v[18:19], v[24:25]
	v_pk_add_f32 v[18:19], v[18:19], v[24:25] neg_lo:[0,1] neg_hi:[0,1]
	v_pk_add_f32 v[20:21], v[20:21], v[40:41]
	v_pk_add_f32 v[24:25], v[36:37], v[44:45]
	v_pk_fma_f32 v[50:51], v[50:51], v[8:9], v[60:61] op_sel:[1,1,0] op_sel_hi:[1,0,1] neg_lo:[1,0,0]
	v_pk_mul_f32 v[60:61], v[54:55], v[4:5] op_sel:[0,0] op_sel_hi:[0,1]
	v_pk_add_f32 v[62:63], v[22:23], v[30:31]
	v_pk_add_f32 v[34:35], v[20:21], v[24:25]
	v_pk_add_f32 v[20:21], v[20:21], v[24:25] neg_lo:[0,1] neg_hi:[0,1]
	v_pk_mul_f32 v[24:25], v[16:17], v[4:5] op_sel:[0,0] op_sel_hi:[0,1]
	v_pk_fma_f32 v[54:55], v[54:55], v[4:5], v[60:61] op_sel:[1,1,0] op_sel_hi:[1,0,1] neg_lo:[1,0,0]
	v_pk_mul_f32 v[60:61], v[58:59], v[2:3] op_sel:[0,0] op_sel_hi:[0,1]
	v_pk_add_f32 v[22:23], v[22:23], v[30:31] neg_lo:[0,1] neg_hi:[0,1]
	v_pk_fma_f32 v[16:17], v[16:17], v[4:5], v[24:25] op_sel:[1,1,0] op_sel_hi:[1,0,1] neg_lo:[1,0,0]
	v_pk_mul_f32 v[24:25], v[18:19], v[10:11] op_sel:[0,0] op_sel_hi:[0,1]
	v_pk_fma_f32 v[58:59], v[58:59], v[2:3], v[60:61] op_sel:[1,1,0] op_sel_hi:[1,0,1] neg_lo:[1,0,0]
	v_pk_add_f32 v[60:61], v[14:15], v[26:27]
	v_pk_fma_f32 v[18:19], v[18:19], v[10:11], v[24:25] op_sel:[1,1,0] op_sel_hi:[1,0,1] neg_lo:[1,0,0]
	v_pk_mul_f32 v[24:25], v[20:21], v[6:7] op_sel:[0,0] op_sel_hi:[0,1]
	v_pk_add_f32 v[14:15], v[14:15], v[26:27] neg_lo:[0,1] neg_hi:[0,1]
	v_pk_fma_f32 v[20:21], v[20:21], v[6:7], v[24:25] op_sel:[1,1,0] op_sel_hi:[1,0,1] neg_lo:[1,0,0]
	v_pk_mul_f32 v[24:25], v[48:49], v[2:3] op_sel:[0,0] op_sel_hi:[0,1]
	v_pk_mul_f32 v[36:37], v[52:53], v[6:7] op_sel:[0,0] op_sel_hi:[0,1]
	v_pk_mul_f32 v[38:39], v[56:57], v[12:13] op_sel:[0,0] op_sel_hi:[0,1]
	v_pk_add_f32 v[64:65], v[60:61], v[62:63]
	v_pk_add_f32 v[26:27], v[14:15], v[22:23] op_sel:[0,1] op_sel_hi:[1,0] neg_lo:[0,1] neg_hi:[0,1]
	v_pk_add_f32 v[14:15], v[14:15], v[22:23] op_sel:[0,1] op_sel_hi:[1,0]
	v_pk_fma_f32 v[24:25], v[48:49], v[2:3], v[24:25] op_sel:[1,1,0] op_sel_hi:[1,0,1] neg_lo:[1,0,0]
	v_mov_b32_e32 v22, v26
	v_mov_b32_e32 v23, v15
	v_mov_b32_e32 v15, v27
	v_pk_fma_f32 v[36:37], v[52:53], v[6:7], v[36:37] op_sel:[1,1,0] op_sel_hi:[1,0,1] neg_lo:[1,0,0]
	v_pk_fma_f32 v[38:39], v[56:57], v[12:13], v[38:39] op_sel:[1,1,0] op_sel_hi:[1,0,1] neg_lo:[1,0,0]
	v_pk_add_f32 v[26:27], v[14:15], v[54:55] neg_lo:[0,1] neg_hi:[0,1]
	v_pk_add_f32 v[14:15], v[14:15], v[54:55]
	v_pk_add_f32 v[54:55], v[22:23], v[36:37] neg_lo:[0,1] neg_hi:[0,1]
	v_pk_add_f32 v[56:57], v[24:25], v[38:39] neg_lo:[0,1] neg_hi:[0,1]
	v_pk_add_f32 v[24:25], v[24:25], v[38:39]
	v_pk_add_f32 v[22:23], v[22:23], v[36:37]
	s_nop 1
	v_pk_add_f32 v[40:41], v[64:65], v[32:33]
	v_pk_add_f32 v[42:43], v[28:29], v[34:35]
	v_pk_add_f32 v[36:37], v[22:23], v[24:25]
	v_pk_add_f32 v[22:23], v[22:23], v[24:25] neg_lo:[0,1] neg_hi:[0,1]
	v_pk_add_f32 v[24:25], v[54:55], v[56:57] op_sel:[0,1] op_sel_hi:[1,0]
	v_pk_add_f32 v[38:39], v[54:55], v[56:57] op_sel:[0,1] op_sel_hi:[1,0] neg_lo:[0,1] neg_hi:[0,1]
	v_xor_b32_e32 v47, 0x80000000, v47
	v_pk_mul_f32 v[56:57], v[46:47], v[46:47] op_sel:[0,0] op_sel_hi:[0,1]
	v_pk_add_f32 v[44:45], v[40:41], v[42:43]
	v_pk_add_f32 v[40:41], v[40:41], v[42:43] neg_lo:[0,1] neg_hi:[0,1]
	v_pk_add_f32 v[42:43], v[60:61], v[62:63] neg_lo:[0,1] neg_hi:[0,1]
	v_pk_fma_f32 v[56:57], v[46:47], v[46:47], v[56:57] op_sel:[1,1,0] op_sel_hi:[1,0,1] neg_lo:[1,0,0]
	v_pk_add_f32 v[32:33], v[64:65], v[32:33] neg_lo:[0,1] neg_hi:[0,1]
	v_pk_mul_f32 v[60:61], v[56:57], v[56:57] op_sel:[0,0] op_sel_hi:[0,1]
	v_pk_add_f32 v[28:29], v[28:29], v[34:35] neg_lo:[0,1] neg_hi:[0,1]
	v_pk_fma_f32 v[60:61], v[56:57], v[56:57], v[60:61] op_sel:[1,1,0] op_sel_hi:[1,0,1] neg_lo:[1,0,0]
	v_pk_add_f32 v[48:49], v[42:43], v[18:19] neg_lo:[0,1] neg_hi:[0,1]
	v_pk_mul_f32 v[68:69], v[60:61], v[60:61] op_sel:[0,0] op_sel_hi:[0,1]
	v_pk_add_f32 v[52:53], v[16:17], v[20:21] neg_lo:[0,1] neg_hi:[0,1]
	v_pk_add_f32 v[16:17], v[16:17], v[20:21]
	v_pk_add_f32 v[18:19], v[42:43], v[18:19]
	v_pk_add_f32 v[30:31], v[50:51], v[58:59] neg_lo:[0,1] neg_hi:[0,1]
	v_pk_add_f32 v[50:51], v[50:51], v[58:59]
	v_pk_mul_f32 v[62:63], v[60:61], v[46:47] op_sel:[0,0] op_sel_hi:[0,1]
	v_pk_fma_f32 v[68:69], v[60:61], v[60:61], v[68:69] op_sel:[1,1,0] op_sel_hi:[1,0,1] neg_lo:[1,0,0]
	v_pk_add_f32 v[34:35], v[32:33], v[28:29] op_sel:[0,1] op_sel_hi:[1,0]
	v_pk_mul_f32 v[70:71], v[68:69], v[46:47] op_sel:[0,0] op_sel_hi:[0,1]
	v_pk_add_f32 v[28:29], v[32:33], v[28:29] op_sel:[0,1] op_sel_hi:[1,0] neg_lo:[0,1] neg_hi:[0,1]
	v_pk_add_f32 v[20:21], v[18:19], v[16:17]
	v_pk_add_f32 v[16:17], v[18:19], v[16:17] neg_lo:[0,1] neg_hi:[0,1]
	v_pk_add_f32 v[18:19], v[48:49], v[52:53] op_sel:[0,1] op_sel_hi:[1,0]
	v_pk_add_f32 v[42:43], v[48:49], v[52:53] op_sel:[0,1] op_sel_hi:[1,0] neg_lo:[0,1] neg_hi:[0,1]
	v_pk_add_f32 v[52:53], v[14:15], v[50:51]
	v_pk_add_f32 v[14:15], v[14:15], v[50:51] neg_lo:[0,1] neg_hi:[0,1]
	v_mov_b32_e32 v54, v38
	v_mov_b32_e32 v55, v25
	v_pk_mul_f32 v[58:59], v[56:57], v[46:47] op_sel:[0,0] op_sel_hi:[0,1]
	v_pk_fma_f32 v[62:63], v[60:61], v[46:47], v[62:63] op_sel:[1,1,0] op_sel_hi:[1,0,1] neg_lo:[1,0,0]
	v_pk_fma_f32 v[70:71], v[68:69], v[46:47], v[70:71] op_sel:[1,1,0] op_sel_hi:[1,0,1] neg_lo:[1,0,0]
	v_mov_b32_e32 v25, v39
	v_pk_mul_f32 v[72:73], v[62:63], v[62:63] op_sel:[0,0] op_sel_hi:[0,1]
	v_pk_mul_f32 v[38:39], v[14:15], v[70:71] op_sel:[0,0] op_sel_hi:[0,1]
	v_mov_b32_e32 v32, v28
	v_mov_b32_e32 v33, v35
	v_pk_fma_f32 v[58:59], v[56:57], v[46:47], v[58:59] op_sel:[1,1,0] op_sel_hi:[1,0,1] neg_lo:[1,0,0]
	v_pk_fma_f32 v[72:73], v[62:63], v[62:63], v[72:73] op_sel:[1,1,0] op_sel_hi:[1,0,1] neg_lo:[1,0,0]
	v_mov_b32_e32 v35, v29
	v_pk_mul_f32 v[64:65], v[58:59], v[58:59] op_sel:[0,0] op_sel_hi:[0,1]
	v_pk_mul_f32 v[74:75], v[68:69], v[58:59] op_sel:[0,0] op_sel_hi:[0,1]
	v_pk_mul_f32 v[28:29], v[34:35], v[60:61] op_sel:[0,0] op_sel_hi:[0,1]
	v_pk_fma_f32 v[14:15], v[14:15], v[70:71], v[38:39] op_sel:[1,1,0] op_sel_hi:[1,0,1] neg_lo:[1,0,0]
	v_pk_mul_f32 v[38:39], v[16:17], v[72:73] op_sel:[0,0] op_sel_hi:[0,1]
	v_mov_b32_e32 v49, v19
	v_pk_fma_f32 v[64:65], v[58:59], v[58:59], v[64:65] op_sel:[1,1,0] op_sel_hi:[1,0,1] neg_lo:[1,0,0]
	v_pk_mul_f32 v[66:67], v[60:61], v[58:59] op_sel:[0,0] op_sel_hi:[0,1]
	v_pk_fma_f32 v[74:75], v[68:69], v[58:59], v[74:75] op_sel:[1,1,0] op_sel_hi:[1,0,1] neg_lo:[1,0,0]
	v_pk_fma_f32 v[28:29], v[34:35], v[60:61], v[28:29] op_sel:[1,1,0] op_sel_hi:[1,0,1] neg_lo:[1,0,0]
	v_mov_b32_e32 v19, v43
	v_pk_mul_f32 v[76:77], v[64:65], v[64:65] op_sel:[0,0] op_sel_hi:[0,1]
	v_pk_mul_f32 v[34:35], v[18:19], v[64:65] op_sel:[0,0] op_sel_hi:[0,1]
	v_pk_fma_f32 v[16:17], v[16:17], v[72:73], v[38:39] op_sel:[1,1,0] op_sel_hi:[1,0,1] neg_lo:[1,0,0]
	v_pk_mul_f32 v[38:39], v[22:23], v[74:75] op_sel:[0,0] op_sel_hi:[0,1]
	v_pk_add_f32 v[50:51], v[26:27], v[30:31] op_sel:[0,1] op_sel_hi:[1,0]
	v_pk_add_f32 v[26:27], v[26:27], v[30:31] op_sel:[0,1] op_sel_hi:[1,0] neg_lo:[0,1] neg_hi:[0,1]
	v_pk_fma_f32 v[66:67], v[60:61], v[58:59], v[66:67] op_sel:[1,1,0] op_sel_hi:[1,0,1] neg_lo:[1,0,0]
	v_pk_fma_f32 v[76:77], v[64:65], v[64:65], v[76:77] op_sel:[1,1,0] op_sel_hi:[1,0,1] neg_lo:[1,0,0]
	v_pk_mul_f32 v[78:79], v[68:69], v[62:63] op_sel:[0,0] op_sel_hi:[0,1]
	v_pk_fma_f32 v[18:19], v[18:19], v[64:65], v[34:35] op_sel:[1,1,0] op_sel_hi:[1,0,1] neg_lo:[1,0,0]
	v_pk_fma_f32 v[22:23], v[22:23], v[74:75], v[38:39] op_sel:[1,1,0] op_sel_hi:[1,0,1] neg_lo:[1,0,0]
	s_nop 0
	v_mov_b32_e32 v30, v26
	v_pk_mul_f32 v[34:35], v[24:25], v[66:67] op_sel:[0,0] op_sel_hi:[0,1]
	v_pk_mul_f32 v[38:39], v[32:33], v[76:77] op_sel:[0,0] op_sel_hi:[0,1]
	v_mov_b32_e32 v31, v51
	v_pk_fma_f32 v[78:79], v[68:69], v[62:63], v[78:79] op_sel:[1,1,0] op_sel_hi:[1,0,1] neg_lo:[1,0,0]
	v_pk_mul_f32 v[80:81], v[66:67], v[66:67] op_sel:[0,0] op_sel_hi:[0,1]
	v_pk_mul_f32 v[82:83], v[68:69], v[66:67] op_sel:[0,0] op_sel_hi:[0,1]
	v_pk_fma_f32 v[24:25], v[24:25], v[66:67], v[34:35] op_sel:[1,1,0] op_sel_hi:[1,0,1] neg_lo:[1,0,0]
	v_pk_mul_f32 v[34:35], v[40:41], v[68:69] op_sel:[0,0] op_sel_hi:[0,1]
	v_pk_fma_f32 v[32:33], v[32:33], v[76:77], v[38:39] op_sel:[1,1,0] op_sel_hi:[1,0,1] neg_lo:[1,0,0]
	s_nop 0
	v_pk_mul_f32 v[38:39], v[30:31], v[78:79] op_sel:[0,0] op_sel_hi:[0,1]
	v_mov_b32_e32 v48, v42
	v_pk_fma_f32 v[80:81], v[66:67], v[66:67], v[80:81] op_sel:[1,1,0] op_sel_hi:[1,0,1] neg_lo:[1,0,0]
	v_pk_fma_f32 v[82:83], v[68:69], v[66:67], v[82:83] op_sel:[1,1,0] op_sel_hi:[1,0,1] neg_lo:[1,0,0]
	v_pk_mul_f32 v[84:85], v[52:53], v[46:47] op_sel:[0,0] op_sel_hi:[0,1]
	v_mov_b32_e32 v51, v27
	v_pk_fma_f32 v[46:47], v[52:53], v[46:47], v[84:85] op_sel:[1,1,0] op_sel_hi:[1,0,1] neg_lo:[1,0,0]
	v_pk_mul_f32 v[52:53], v[20:21], v[56:57] op_sel:[0,0] op_sel_hi:[0,1]
	v_pk_mul_f32 v[26:27], v[50:51], v[62:63] op_sel:[0,0] op_sel_hi:[0,1]
	v_pk_fma_f32 v[34:35], v[40:41], v[68:69], v[34:35] op_sel:[1,1,0] op_sel_hi:[1,0,1] neg_lo:[1,0,0]
	v_pk_fma_f32 v[30:31], v[30:31], v[78:79], v[38:39] op_sel:[1,1,0] op_sel_hi:[1,0,1] neg_lo:[1,0,0]
	v_pk_mul_f32 v[38:39], v[48:49], v[80:81] op_sel:[0,0] op_sel_hi:[0,1]
	v_pk_mul_f32 v[40:41], v[54:55], v[82:83] op_sel:[0,0] op_sel_hi:[0,1]
	s_nop 0
	v_pk_fma_f32 v[20:21], v[20:21], v[56:57], v[52:53] op_sel:[1,1,0] op_sel_hi:[1,0,1] neg_lo:[1,0,0]
	v_pk_mul_f32 v[52:53], v[36:37], v[58:59] op_sel:[0,0] op_sel_hi:[0,1]
	v_pk_fma_f32 v[26:27], v[50:51], v[62:63], v[26:27] op_sel:[1,1,0] op_sel_hi:[1,0,1] neg_lo:[1,0,0]
	s_nop 0
	v_pk_fma_f32 v[36:37], v[36:37], v[58:59], v[52:53] op_sel:[1,1,0] op_sel_hi:[1,0,1] neg_lo:[1,0,0]
	v_pk_fma_f32 v[38:39], v[48:49], v[80:81], v[38:39] op_sel:[1,1,0] op_sel_hi:[1,0,1] neg_lo:[1,0,0]
	v_pk_fma_f32 v[40:41], v[54:55], v[82:83], v[40:41] op_sel:[1,1,0] op_sel_hi:[1,0,1] neg_lo:[1,0,0]
	ds_write2_b64 v1, v[44:45], v[46:47] offset1:34
	ds_write2_b64 v1, v[20:21], v[36:37] offset0:68 offset1:102
	ds_write2_b64 v1, v[28:29], v[26:27] offset0:136 offset1:170
	ds_write2_b64 v1, v[18:19], v[24:25] offset0:204 offset1:238
	ds_write2_b64 v86, v[34:35], v[14:15] offset0:16 offset1:50
	ds_write2_b64 v86, v[16:17], v[22:23] offset0:84 offset1:118
	ds_write2_b64 v86, v[32:33], v[30:31] offset0:152 offset1:186
	ds_write2_b64 v86, v[38:39], v[40:41] offset0:220 offset1:254
	v_mov_b32_e32 v1, v0
	s_waitcnt lgkmcnt(0)
	s_barrier
	s_nop 0
	v_and_b32_e32 v14, 1, v1
	v_lshlrev_b32_e32 v1, 4, v1
	v_and_b32_e32 v1, 0xffffffe0, v1
	v_ashrrev_i32_e32 v15, 1, v1
	v_add_u32_e32 v15, 0, v15
	v_lshlrev_b32_e32 v1, 3, v1
	v_lshlrev_b32_e32 v16, 3, v14
	v_cvt_f32_ubyte0_e32 v14, v14
	v_add3_u32 v1, v15, v1, v16
	v_mul_f32_e32 v14, 0x3d000000, v14
	v_cos_f32_e32 v46, v14
	v_sin_f32_e32 v47, v14
	ds_read2_b64 v[14:17], v1 offset1:2
	ds_read2_b64 v[18:21], v1 offset0:4 offset1:6
	ds_read2_b64 v[22:25], v1 offset0:8 offset1:10
	ds_read2_b64 v[26:29], v1 offset0:17 offset1:19
	ds_read2_b64 v[30:33], v1 offset0:25 offset1:27
	ds_read2_b64 v[34:37], v1 offset0:12 offset1:14
	ds_read2_b64 v[38:41], v1 offset0:21 offset1:23
	ds_read2_b64 v[42:45], v1 offset0:29 offset1:31
	s_waitcnt lgkmcnt(4)
	v_pk_add_f32 v[48:49], v[16:17], v[28:29] neg_lo:[0,1] neg_hi:[0,1]
	s_waitcnt lgkmcnt(3)
	v_pk_add_f32 v[50:51], v[24:25], v[32:33] neg_lo:[0,1] neg_hi:[0,1]
	v_pk_add_f32 v[16:17], v[16:17], v[28:29]
	v_pk_add_f32 v[52:53], v[48:49], v[50:51] op_sel:[0,1] op_sel_hi:[1,0]
	v_pk_add_f32 v[48:49], v[48:49], v[50:51] op_sel:[0,1] op_sel_hi:[1,0] neg_lo:[0,1] neg_hi:[0,1]
	v_mov_b32_e32 v50, v52
	v_mov_b32_e32 v51, v49
	v_mov_b32_e32 v49, v53
	s_waitcnt lgkmcnt(1)
	v_pk_add_f32 v[52:53], v[18:19], v[38:39] neg_lo:[0,1] neg_hi:[0,1]
	s_waitcnt lgkmcnt(0)
	v_pk_add_f32 v[54:55], v[34:35], v[42:43] neg_lo:[0,1] neg_hi:[0,1]
	v_pk_add_f32 v[58:59], v[36:37], v[44:45] neg_lo:[0,1] neg_hi:[0,1]
	v_pk_add_f32 v[56:57], v[52:53], v[54:55] op_sel:[0,1] op_sel_hi:[1,0]
	v_pk_add_f32 v[52:53], v[52:53], v[54:55] op_sel:[0,1] op_sel_hi:[1,0] neg_lo:[0,1] neg_hi:[0,1]
	v_mov_b32_e32 v54, v56
	v_mov_b32_e32 v55, v53
	v_mov_b32_e32 v53, v57
	v_pk_add_f32 v[56:57], v[20:21], v[40:41] neg_lo:[0,1] neg_hi:[0,1]
	v_pk_add_f32 v[24:25], v[24:25], v[32:33]
	v_pk_add_f32 v[60:61], v[56:57], v[58:59] op_sel:[0,1] op_sel_hi:[1,0]
	v_pk_add_f32 v[56:57], v[56:57], v[58:59] op_sel:[0,1] op_sel_hi:[1,0] neg_lo:[0,1] neg_hi:[0,1]
	v_mov_b32_e32 v58, v60
	v_mov_b32_e32 v59, v57
	v_mov_b32_e32 v57, v61
	v_pk_mul_f32 v[60:61], v[50:51], v[8:9] op_sel:[0,0] op_sel_hi:[0,1]
	v_pk_add_f32 v[28:29], v[16:17], v[24:25]
	v_pk_fma_f32 v[8:9], v[50:51], v[8:9], v[60:61] op_sel:[1,1,0] op_sel_hi:[1,0,1] neg_lo:[1,0,0]
	v_pk_mul_f32 v[50:51], v[54:55], v[4:5] op_sel:[0,0] op_sel_hi:[0,1]
	v_pk_add_f32 v[16:17], v[16:17], v[24:25] neg_lo:[0,1] neg_hi:[0,1]
	v_pk_add_f32 v[18:19], v[18:19], v[38:39]
	v_pk_add_f32 v[24:25], v[34:35], v[42:43]
	v_pk_fma_f32 v[50:51], v[54:55], v[4:5], v[50:51] op_sel:[1,1,0] op_sel_hi:[1,0,1] neg_lo:[1,0,0]
	v_pk_mul_f32 v[54:55], v[58:59], v[2:3] op_sel:[0,0] op_sel_hi:[0,1]
	v_pk_add_f32 v[20:21], v[20:21], v[40:41]
	v_pk_add_f32 v[32:33], v[18:19], v[24:25]
	v_pk_add_f32 v[18:19], v[18:19], v[24:25] neg_lo:[0,1] neg_hi:[0,1]
	v_pk_add_f32 v[24:25], v[36:37], v[44:45]
	v_pk_fma_f32 v[54:55], v[58:59], v[2:3], v[54:55] op_sel:[1,1,0] op_sel_hi:[1,0,1] neg_lo:[1,0,0]
	v_pk_add_f32 v[58:59], v[14:15], v[26:27]
	v_pk_add_f32 v[60:61], v[22:23], v[30:31]
	v_pk_add_f32 v[34:35], v[20:21], v[24:25]
	v_pk_add_f32 v[20:21], v[20:21], v[24:25] neg_lo:[0,1] neg_hi:[0,1]
	v_pk_mul_f32 v[24:25], v[16:17], v[4:5] op_sel:[0,0] op_sel_hi:[0,1]
	v_pk_add_f32 v[14:15], v[14:15], v[26:27] neg_lo:[0,1] neg_hi:[0,1]
	v_pk_fma_f32 v[4:5], v[16:17], v[4:5], v[24:25] op_sel:[1,1,0] op_sel_hi:[1,0,1] neg_lo:[1,0,0]
	v_pk_mul_f32 v[16:17], v[18:19], v[10:11] op_sel:[0,0] op_sel_hi:[0,1]
	v_pk_add_f32 v[22:23], v[22:23], v[30:31] neg_lo:[0,1] neg_hi:[0,1]
	v_pk_fma_f32 v[10:11], v[18:19], v[10:11], v[16:17] op_sel:[1,1,0] op_sel_hi:[1,0,1] neg_lo:[1,0,0]
	v_pk_mul_f32 v[16:17], v[20:21], v[6:7] op_sel:[0,0] op_sel_hi:[0,1]
	v_pk_mul_f32 v[18:19], v[48:49], v[2:3] op_sel:[0,0] op_sel_hi:[0,1]
	s_nop 1
	v_pk_add_f32 v[62:63], v[58:59], v[60:61]
	v_pk_add_f32 v[26:27], v[14:15], v[22:23] op_sel:[0,1] op_sel_hi:[1,0] neg_lo:[0,1] neg_hi:[0,1]
	v_pk_add_f32 v[14:15], v[14:15], v[22:23] op_sel:[0,1] op_sel_hi:[1,0]
	v_pk_fma_f32 v[16:17], v[20:21], v[6:7], v[16:17] op_sel:[1,1,0] op_sel_hi:[1,0,1] neg_lo:[1,0,0]
	v_pk_fma_f32 v[2:3], v[48:49], v[2:3], v[18:19] op_sel:[1,1,0] op_sel_hi:[1,0,1] neg_lo:[1,0,0]
	v_pk_mul_f32 v[18:19], v[52:53], v[6:7] op_sel:[0,0] op_sel_hi:[0,1]
	v_mov_b32_e32 v22, v26
	v_pk_fma_f32 v[6:7], v[52:53], v[6:7], v[18:19] op_sel:[1,1,0] op_sel_hi:[1,0,1] neg_lo:[1,0,0]
	v_mov_b32_e32 v23, v15
	v_pk_mul_f32 v[18:19], v[56:57], v[12:13] op_sel:[0,0] op_sel_hi:[0,1]
	v_pk_add_f32 v[40:41], v[22:23], v[6:7] neg_lo:[0,1] neg_hi:[0,1]
	v_pk_fma_f32 v[12:13], v[56:57], v[12:13], v[18:19] op_sel:[1,1,0] op_sel_hi:[1,0,1] neg_lo:[1,0,0]
	v_pk_add_f32 v[6:7], v[22:23], v[6:7]
	v_pk_add_f32 v[42:43], v[2:3], v[12:13] neg_lo:[0,1] neg_hi:[0,1]
	v_pk_add_f32 v[2:3], v[2:3], v[12:13]
	v_pk_add_f32 v[22:23], v[40:41], v[42:43] op_sel:[0,1] op_sel_hi:[1,0] neg_lo:[0,1] neg_hi:[0,1]
	v_pk_add_f32 v[12:13], v[6:7], v[2:3]
	v_pk_add_f32 v[2:3], v[6:7], v[2:3] neg_lo:[0,1] neg_hi:[0,1]
	v_pk_add_f32 v[6:7], v[40:41], v[42:43] op_sel:[0,1] op_sel_hi:[1,0]
	v_xor_b32_e32 v47, 0x80000000, v47
	v_pk_mul_f32 v[42:43], v[46:47], v[46:47] op_sel:[0,0] op_sel_hi:[0,1]
	v_pk_add_f32 v[30:31], v[8:9], v[54:55] neg_lo:[0,1] neg_hi:[0,1]
	v_pk_fma_f32 v[42:43], v[46:47], v[46:47], v[42:43] op_sel:[1,1,0] op_sel_hi:[1,0,1] neg_lo:[1,0,0]
	v_pk_add_f32 v[8:9], v[8:9], v[54:55]
	v_pk_mul_f32 v[44:45], v[42:43], v[46:47] op_sel:[0,0] op_sel_hi:[0,1]
	v_pk_mul_f32 v[48:49], v[42:43], v[42:43] op_sel:[0,0] op_sel_hi:[0,1]
	v_pk_add_f32 v[18:19], v[62:63], v[32:33]
	v_pk_fma_f32 v[44:45], v[42:43], v[46:47], v[44:45] op_sel:[1,1,0] op_sel_hi:[1,0,1] neg_lo:[1,0,0]
	v_pk_fma_f32 v[48:49], v[42:43], v[42:43], v[48:49] op_sel:[1,1,0] op_sel_hi:[1,0,1] neg_lo:[1,0,0]
	v_pk_add_f32 v[20:21], v[28:29], v[34:35]
	v_pk_mul_f32 v[54:55], v[48:49], v[44:45] op_sel:[0,0] op_sel_hi:[0,1]
	v_pk_add_f32 v[28:29], v[28:29], v[34:35] neg_lo:[0,1] neg_hi:[0,1]
	v_pk_add_f32 v[34:35], v[58:59], v[60:61] neg_lo:[0,1] neg_hi:[0,1]
	v_mov_b32_e32 v15, v27
	v_mov_b32_e32 v40, v22
	v_mov_b32_e32 v41, v7
	v_pk_fma_f32 v[54:55], v[48:49], v[44:45], v[54:55] op_sel:[1,1,0] op_sel_hi:[1,0,1] neg_lo:[1,0,0]
	v_pk_mul_f32 v[56:57], v[48:49], v[48:49] op_sel:[0,0] op_sel_hi:[0,1]
	v_mov_b32_e32 v7, v23
	v_pk_mul_f32 v[22:23], v[6:7], v[54:55] op_sel:[0,0] op_sel_hi:[0,1]
	v_pk_add_f32 v[24:25], v[18:19], v[20:21]
	v_pk_add_f32 v[18:19], v[18:19], v[20:21] neg_lo:[0,1] neg_hi:[0,1]
	v_pk_add_f32 v[36:37], v[34:35], v[10:11] neg_lo:[0,1] neg_hi:[0,1]
	v_pk_add_f32 v[38:39], v[4:5], v[16:17] neg_lo:[0,1] neg_hi:[0,1]
	v_pk_add_f32 v[4:5], v[4:5], v[16:17]
	v_pk_add_f32 v[10:11], v[34:35], v[10:11]
	v_pk_add_f32 v[26:27], v[14:15], v[50:51] neg_lo:[0,1] neg_hi:[0,1]
	v_pk_add_f32 v[14:15], v[14:15], v[50:51]
	v_pk_mul_f32 v[50:51], v[48:49], v[46:47] op_sel:[0,0] op_sel_hi:[0,1]
	v_pk_fma_f32 v[56:57], v[48:49], v[48:49], v[56:57] op_sel:[1,1,0] op_sel_hi:[1,0,1] neg_lo:[1,0,0]
	v_pk_fma_f32 v[6:7], v[6:7], v[54:55], v[22:23] op_sel:[1,1,0] op_sel_hi:[1,0,1] neg_lo:[1,0,0]
	v_pk_add_f32 v[16:17], v[10:11], v[4:5]
	v_pk_mul_f32 v[58:59], v[56:57], v[46:47] op_sel:[0,0] op_sel_hi:[0,1]
	v_pk_mul_f32 v[22:23], v[18:19], v[56:57] op_sel:[0,0] op_sel_hi:[0,1]
	v_pk_add_f32 v[4:5], v[10:11], v[4:5] neg_lo:[0,1] neg_hi:[0,1]
	v_pk_add_f32 v[10:11], v[36:37], v[38:39] op_sel:[0,1] op_sel_hi:[1,0]
	v_pk_add_f32 v[34:35], v[36:37], v[38:39] op_sel:[0,1] op_sel_hi:[1,0] neg_lo:[0,1] neg_hi:[0,1]
	v_pk_add_f32 v[38:39], v[14:15], v[8:9]
	v_pk_add_f32 v[8:9], v[14:15], v[8:9] neg_lo:[0,1] neg_hi:[0,1]
	v_pk_add_f32 v[14:15], v[26:27], v[30:31] op_sel:[0,1] op_sel_hi:[1,0]
	v_pk_add_f32 v[26:27], v[26:27], v[30:31] op_sel:[0,1] op_sel_hi:[1,0] neg_lo:[0,1] neg_hi:[0,1]
	v_pk_fma_f32 v[50:51], v[48:49], v[46:47], v[50:51] op_sel:[1,1,0] op_sel_hi:[1,0,1] neg_lo:[1,0,0]
	v_pk_fma_f32 v[58:59], v[56:57], v[46:47], v[58:59] op_sel:[1,1,0] op_sel_hi:[1,0,1] neg_lo:[1,0,0]
	v_pk_fma_f32 v[18:19], v[18:19], v[56:57], v[22:23] op_sel:[1,1,0] op_sel_hi:[1,0,1] neg_lo:[1,0,0]
	v_pk_add_f32 v[20:21], v[62:63], v[32:33] neg_lo:[0,1] neg_hi:[0,1]
	v_pk_mul_f32 v[60:61], v[50:51], v[50:51] op_sel:[0,0] op_sel_hi:[0,1]
	v_pk_mul_f32 v[22:23], v[8:9], v[58:59] op_sel:[0,0] op_sel_hi:[0,1]
	v_mov_b32_e32 v30, v26
	v_mov_b32_e32 v31, v15
	v_pk_mul_f32 v[52:53], v[44:45], v[44:45] op_sel:[0,0] op_sel_hi:[0,1]
	v_pk_fma_f32 v[60:61], v[50:51], v[50:51], v[60:61] op_sel:[1,1,0] op_sel_hi:[1,0,1] neg_lo:[1,0,0]
	v_pk_mul_f32 v[62:63], v[56:57], v[44:45] op_sel:[0,0] op_sel_hi:[0,1]
	v_mov_b32_e32 v15, v27
	v_pk_mul_f32 v[26:27], v[14:15], v[50:51] op_sel:[0,0] op_sel_hi:[0,1]
	v_pk_fma_f32 v[8:9], v[8:9], v[58:59], v[22:23] op_sel:[1,1,0] op_sel_hi:[1,0,1] neg_lo:[1,0,0]
	v_pk_mul_f32 v[22:23], v[4:5], v[60:61] op_sel:[0,0] op_sel_hi:[0,1]
	v_pk_add_f32 v[32:33], v[20:21], v[28:29] op_sel:[0,1] op_sel_hi:[1,0]
	v_pk_add_f32 v[20:21], v[20:21], v[28:29] op_sel:[0,1] op_sel_hi:[1,0] neg_lo:[0,1] neg_hi:[0,1]
	v_mov_b32_e32 v37, v11
	v_pk_fma_f32 v[52:53], v[44:45], v[44:45], v[52:53] op_sel:[1,1,0] op_sel_hi:[1,0,1] neg_lo:[1,0,0]
	v_pk_fma_f32 v[62:63], v[56:57], v[44:45], v[62:63] op_sel:[1,1,0] op_sel_hi:[1,0,1] neg_lo:[1,0,0]
	v_pk_mul_f32 v[66:67], v[56:57], v[50:51] op_sel:[0,0] op_sel_hi:[0,1]
	v_pk_fma_f32 v[14:15], v[14:15], v[50:51], v[26:27] op_sel:[1,1,0] op_sel_hi:[1,0,1] neg_lo:[1,0,0]
	v_mov_b32_e32 v11, v35
	v_pk_mul_f32 v[64:65], v[52:53], v[52:53] op_sel:[0,0] op_sel_hi:[0,1]
	v_pk_mul_f32 v[26:27], v[10:11], v[52:53] op_sel:[0,0] op_sel_hi:[0,1]
	v_pk_fma_f32 v[4:5], v[4:5], v[60:61], v[22:23] op_sel:[1,1,0] op_sel_hi:[1,0,1] neg_lo:[1,0,0]
	v_pk_mul_f32 v[22:23], v[2:3], v[62:63] op_sel:[0,0] op_sel_hi:[0,1]
	v_mov_b32_e32 v28, v20
	v_mov_b32_e32 v29, v33
	v_pk_fma_f32 v[64:65], v[52:53], v[52:53], v[64:65] op_sel:[1,1,0] op_sel_hi:[1,0,1] neg_lo:[1,0,0]
	v_pk_fma_f32 v[66:67], v[56:57], v[50:51], v[66:67] op_sel:[1,1,0] op_sel_hi:[1,0,1] neg_lo:[1,0,0]
	v_pk_mul_f32 v[68:69], v[54:55], v[54:55] op_sel:[0,0] op_sel_hi:[0,1]
	v_pk_mul_f32 v[70:71], v[56:57], v[54:55] op_sel:[0,0] op_sel_hi:[0,1]
	v_pk_fma_f32 v[10:11], v[10:11], v[52:53], v[26:27] op_sel:[1,1,0] op_sel_hi:[1,0,1] neg_lo:[1,0,0]
	v_pk_fma_f32 v[2:3], v[2:3], v[62:63], v[22:23] op_sel:[1,1,0] op_sel_hi:[1,0,1] neg_lo:[1,0,0]
	s_nop 0
	v_pk_mul_f32 v[22:23], v[28:29], v[64:65] op_sel:[0,0] op_sel_hi:[0,1]
	v_pk_mul_f32 v[26:27], v[30:31], v[66:67] op_sel:[0,0] op_sel_hi:[0,1]
	v_mov_b32_e32 v36, v34
	v_pk_fma_f32 v[68:69], v[54:55], v[54:55], v[68:69] op_sel:[1,1,0] op_sel_hi:[1,0,1] neg_lo:[1,0,0]
	v_pk_fma_f32 v[70:71], v[56:57], v[54:55], v[70:71] op_sel:[1,1,0] op_sel_hi:[1,0,1] neg_lo:[1,0,0]
	v_pk_mul_f32 v[72:73], v[38:39], v[46:47] op_sel:[0,0] op_sel_hi:[0,1]
	v_mov_b32_e32 v33, v21
	v_pk_fma_f32 v[38:39], v[38:39], v[46:47], v[72:73] op_sel:[1,1,0] op_sel_hi:[1,0,1] neg_lo:[1,0,0]
	v_pk_mul_f32 v[20:21], v[32:33], v[48:49] op_sel:[0,0] op_sel_hi:[0,1]
	v_pk_fma_f32 v[22:23], v[28:29], v[64:65], v[22:23] op_sel:[1,1,0] op_sel_hi:[1,0,1] neg_lo:[1,0,0]
	v_pk_fma_f32 v[26:27], v[30:31], v[66:67], v[26:27] op_sel:[1,1,0] op_sel_hi:[1,0,1] neg_lo:[1,0,0]
	v_pk_mul_f32 v[28:29], v[36:37], v[68:69] op_sel:[0,0] op_sel_hi:[0,1]
	v_pk_mul_f32 v[30:31], v[40:41], v[70:71] op_sel:[0,0] op_sel_hi:[0,1]
	v_pk_mul_f32 v[46:47], v[16:17], v[42:43] op_sel:[0,0] op_sel_hi:[0,1]
	s_nop 0
	v_pk_fma_f32 v[20:21], v[32:33], v[48:49], v[20:21] op_sel:[1,1,0] op_sel_hi:[1,0,1] neg_lo:[1,0,0]
	v_pk_fma_f32 v[16:17], v[16:17], v[42:43], v[46:47] op_sel:[1,1,0] op_sel_hi:[1,0,1] neg_lo:[1,0,0]
	v_pk_mul_f32 v[42:43], v[12:13], v[44:45] op_sel:[0,0] op_sel_hi:[0,1]
	v_pk_fma_f32 v[28:29], v[36:37], v[68:69], v[28:29] op_sel:[1,1,0] op_sel_hi:[1,0,1] neg_lo:[1,0,0]
	v_pk_fma_f32 v[30:31], v[40:41], v[70:71], v[30:31] op_sel:[1,1,0] op_sel_hi:[1,0,1] neg_lo:[1,0,0]
	s_nop 0
	v_pk_fma_f32 v[12:13], v[12:13], v[44:45], v[42:43] op_sel:[1,1,0] op_sel_hi:[1,0,1] neg_lo:[1,0,0]
	ds_write2_b64 v1, v[24:25], v[38:39] offset1:2
	ds_write2_b64 v1, v[16:17], v[12:13] offset0:4 offset1:6
	ds_write2_b64 v1, v[20:21], v[14:15] offset0:8 offset1:10
	ds_write2_b64 v1, v[10:11], v[6:7] offset0:12 offset1:14
	ds_write2_b64 v1, v[18:19], v[8:9] offset0:17 offset1:19
	ds_write2_b64 v1, v[4:5], v[2:3] offset0:21 offset1:23
	ds_write2_b64 v1, v[22:23], v[26:27] offset0:25 offset1:27
	ds_write2_b64 v1, v[28:29], v[30:31] offset0:29 offset1:31
	v_mov_b32_e32 v1, v0
	s_waitcnt lgkmcnt(0)
	s_barrier
	s_nop 0
	v_cmp_gt_i32_e32 vcc, s59, v1
	s_and_saveexec_b64 s[30:31], vcc
	s_cbranch_execz .LBB0_282
	v_lshl_add_u32 v2, v1, 4, 0
	s_mov_b64 s[42:43], 0

.LBB0_286:
	s_and_b64 vcc, exec, s[30:31]
	s_cbranch_vccz .LBB0_261
	v_mov_b32_e32 v2, v0
	v_ashrrev_i32_e32 v1, 4, v2
	v_lshlrev_b32_e32 v1, 3, v1
	v_lshlrev_b32_e32 v3, 3, v2
	v_add3_u32 v1, 0, v1, v3
	v_lshlrev_b32_e32 v4, 2, v2
	v_sub_u32_e32 v5, 0x8000, v4
	global_load_dword v20, v4, s[4:5]
	global_load_dword v21, v4, s[22:23]
	global_load_dword v24, v4, s[4:5] offset:2048
	global_load_dword v25, v4, s[22:23] offset:2048
	v_add_u32_e32 v4, 0x1000, v4
	global_load_dword v28, v4, s[4:5]
	global_load_dword v29, v4, s[22:23]
	global_load_dword v32, v4, s[4:5] offset:2048
	global_load_dword v33, v4, s[22:23] offset:2048
	v_add_u32_e32 v4, 0x1000, v4
	global_load_dword v36, v4, s[4:5]
	global_load_dword v37, v4, s[22:23]
	global_load_dword v40, v4, s[4:5] offset:2048
	global_load_dword v41, v4, s[22:23] offset:2048
	v_add_u32_e32 v4, 0x1000, v4
	global_load_dword v44, v4, s[4:5]
	global_load_dword v45, v4, s[22:23]
	global_load_dword v48, v4, s[4:5] offset:2048
	global_load_dword v49, v4, s[22:23] offset:2048
	v_add_u32_e32 v4, 0x1000, v4
	global_load_dword v52, v4, s[4:5]
	global_load_dword v53, v4, s[22:23]
	global_load_dword v56, v4, s[4:5] offset:2048
	global_load_dword v57, v4, s[22:23] offset:2048
	v_add_u32_e32 v4, 0x1000, v4
	global_load_dword v60, v4, s[4:5]
	global_load_dword v61, v4, s[22:23]
	global_load_dword v64, v4, s[4:5] offset:2048
	global_load_dword v65, v4, s[22:23] offset:2048
	v_add_u32_e32 v4, 0x1000, v4
	global_load_dword v68, v4, s[4:5]
	global_load_dword v69, v4, s[22:23]
	global_load_dword v72, v4, s[4:5] offset:2048
	global_load_dword v73, v4, s[22:23] offset:2048
	v_add_u32_e32 v4, 0x1000, v4
	global_load_dword v76, v4, s[4:5]
	global_load_dword v77, v4, s[22:23]
	global_load_dword v80, v4, s[4:5] offset:2048
	global_load_dword v81, v4, s[22:23] offset:2048
	global_load_dword v22, v5, s[38:39]
	global_load_dword v23, v5, s[40:41]
	global_load_dword v26, v5, s[38:39] offset:-2048
	global_load_dword v27, v5, s[40:41] offset:-2048
	v_add_u32_e32 v5, 0xfffff000, v5
	global_load_dword v30, v5, s[38:39]
	global_load_dword v31, v5, s[40:41]
	global_load_dword v34, v5, s[38:39] offset:-2048
	global_load_dword v35, v5, s[40:41] offset:-2048
	v_add_u32_e32 v5, 0xfffff000, v5
	global_load_dword v38, v5, s[38:39]
	global_load_dword v39, v5, s[40:41]
	global_load_dword v42, v5, s[38:39] offset:-2048
	global_load_dword v43, v5, s[40:41] offset:-2048
	v_add_u32_e32 v5, 0xfffff000, v5
	global_load_dword v46, v5, s[38:39]
	global_load_dword v47, v5, s[40:41]
	global_load_dword v50, v5, s[38:39] offset:-2048
	global_load_dword v51, v5, s[40:41] offset:-2048
	v_add_u32_e32 v5, 0xfffff000, v5
	global_load_dword v54, v5, s[38:39]
	global_load_dword v55, v5, s[40:41]
	global_load_dword v58, v5, s[38:39] offset:-2048
	global_load_dword v59, v5, s[40:41] offset:-2048
	v_add_u32_e32 v5, 0xfffff000, v5
	global_load_dword v62, v5, s[38:39]
	global_load_dword v63, v5, s[40:41]
	global_load_dword v66, v5, s[38:39] offset:-2048
	global_load_dword v67, v5, s[40:41] offset:-2048
	v_add_u32_e32 v5, 0xfffff000, v5
	global_load_dword v70, v5, s[38:39]
	global_load_dword v71, v5, s[40:41]
	global_load_dword v74, v5, s[38:39] offset:-2048
	global_load_dword v75, v5, s[40:41] offset:-2048
	v_add_u32_e32 v5, 0xfffff000, v5
	global_load_dword v78, v5, s[38:39]
	global_load_dword v79, v5, s[40:41]
	global_load_dword v82, v5, s[38:39] offset:-2048
	global_load_dword v83, v5, s[40:41] offset:-2048
	v_cmp_eq_u32_e32 vcc, 0, v2
	v_add_u32_e32 v3, 0x11000, v1
	s_waitcnt vmcnt(0)
	s_nop 1
	v_cndmask_b32_e64 v22, v22, 0, vcc
	v_cndmask_b32_e64 v23, v23, 0, vcc
	ds_write_b64 v1, v[20:21]
	ds_write_b64 v3, v[22:23]
	ds_write_b64 v1, v[24:25] offset:4352
	ds_write_b64 v3, v[26:27] offset:4352
	ds_write_b64 v1, v[28:29] offset:8704
	ds_write_b64 v3, v[30:31] offset:8704
	ds_write_b64 v1, v[32:33] offset:13056
	ds_write_b64 v3, v[34:35] offset:13056
	ds_write_b64 v1, v[36:37] offset:17408
	ds_write_b64 v3, v[38:39] offset:17408
	ds_write_b64 v1, v[40:41] offset:21760
	ds_write_b64 v3, v[42:43] offset:21760
	ds_write_b64 v1, v[44:45] offset:26112
	ds_write_b64 v3, v[46:47] offset:26112
	ds_write_b64 v1, v[48:49] offset:30464
	ds_write_b64 v3, v[50:51] offset:30464
	ds_write_b64 v1, v[52:53] offset:34816
	ds_write_b64 v3, v[54:55] offset:34816
	ds_write_b64 v1, v[56:57] offset:39168
	ds_write_b64 v3, v[58:59] offset:39168
	ds_write_b64 v1, v[60:61] offset:43520
	ds_write_b64 v3, v[62:63] offset:43520
	ds_write_b64 v1, v[64:65] offset:47872
	ds_write_b64 v3, v[66:67] offset:47872
	ds_write_b64 v1, v[68:69] offset:52224
	ds_write_b64 v3, v[70:71] offset:52224
	ds_write_b64 v1, v[72:73] offset:56576
	ds_write_b64 v3, v[74:75] offset:56576
	ds_write_b64 v1, v[76:77] offset:60928
	ds_write_b64 v3, v[78:79] offset:60928
	ds_write_b64 v1, v[80:81] offset:65280
	ds_write_b64 v3, v[82:83] offset:65280
	v_mov_b32_e32 v1, v0
	s_waitcnt lgkmcnt(0)
	s_barrier
	s_movk_i32 s3, 0xc000
	v_and_b32_e32 v58, 0x3ff, v1
	v_lshlrev_b32_e32 v2, 4, v1
	v_and_or_b32 v2, v2, s3, v58
	v_ashrrev_i32_e32 v3, 4, v2
	v_lshlrev_b32_e32 v3, 3, v3
	v_lshlrev_b32_e32 v2, 3, v2
	v_add3_u32 v86, 0, v3, v2
	ds_read2st64_b64 v[14:17], v86 offset1:17
	ds_read2st64_b64 v[10:13], v86 offset0:34 offset1:51
	ds_read2st64_b64 v[18:21], v86 offset0:68 offset1:85
	ds_read2st64_b64 v[22:25], v86 offset0:102 offset1:119
	v_add_u32_e32 v87, 0x11000, v86
	v_add_u32_e32 v88, 0x13200, v86
	v_add_u32_e32 v89, 0x15400, v86
	v_add_u32_e32 v90, 0x17600, v86
	ds_read_b64 v[26:27], v87
	ds_read_b64 v[6:7], v88
	ds_read_b64 v[28:29], v89
	ds_read_b64 v[30:31], v90
	v_add_u32_e32 v92, 0x1ba00, v86
	v_add_u32_e32 v91, 0x19800, v86
	v_add_u32_e32 v93, 0x1dc00, v86
	v_add_u32_e32 v94, 0x1fe00, v86
	ds_read_b64 v[32:33], v92
	ds_read_b64 v[34:35], v93
	ds_read_b64 v[36:37], v94
	ds_read_b64 v[38:39], v91
	s_waitcnt lgkmcnt(6)
	v_pk_add_f32 v[2:3], v[16:17], v[6:7] neg_lo:[0,1] neg_hi:[0,1]
	s_waitcnt lgkmcnt(3)
	v_pk_add_f32 v[4:5], v[20:21], v[32:33] neg_lo:[0,1] neg_hi:[0,1]
	v_pk_add_f32 v[6:7], v[16:17], v[6:7]
	v_pk_add_f32 v[8:9], v[2:3], v[4:5] op_sel:[0,1] op_sel_hi:[1,0]
	v_pk_add_f32 v[40:41], v[2:3], v[4:5] op_sel:[0,1] op_sel_hi:[1,0] neg_lo:[0,1] neg_hi:[0,1]
	v_mov_b32_e32 v2, v8
	v_mov_b32_e32 v3, v41
	v_mov_b32_e32 v41, v9
	v_pk_add_f32 v[4:5], v[10:11], v[28:29] neg_lo:[0,1] neg_hi:[0,1]
	s_waitcnt lgkmcnt(2)
	v_pk_add_f32 v[8:9], v[22:23], v[34:35] neg_lo:[0,1] neg_hi:[0,1]
	v_pk_add_f32 v[16:17], v[20:21], v[32:33]
	v_pk_add_f32 v[42:43], v[4:5], v[8:9] op_sel:[0,1] op_sel_hi:[1,0]
	v_pk_add_f32 v[44:45], v[4:5], v[8:9] op_sel:[0,1] op_sel_hi:[1,0] neg_lo:[0,1] neg_hi:[0,1]
	v_pk_add_f32 v[4:5], v[12:13], v[30:31] neg_lo:[0,1] neg_hi:[0,1]
	s_waitcnt lgkmcnt(1)
	v_pk_add_f32 v[8:9], v[24:25], v[36:37] neg_lo:[0,1] neg_hi:[0,1]
	v_pk_add_f32 v[20:21], v[6:7], v[16:17]
	v_pk_add_f32 v[6:7], v[6:7], v[16:17] neg_lo:[0,1] neg_hi:[0,1]
	v_pk_add_f32 v[10:11], v[10:11], v[28:29]
	v_pk_add_f32 v[16:17], v[22:23], v[34:35]
	v_mov_b32_e32 v46, v42
	v_mov_b32_e32 v47, v45
	v_mov_b32_e32 v45, v43
	v_pk_add_f32 v[42:43], v[4:5], v[8:9] op_sel:[0,1] op_sel_hi:[1,0]
	v_pk_add_f32 v[48:49], v[4:5], v[8:9] op_sel:[0,1] op_sel_hi:[1,0] neg_lo:[0,1] neg_hi:[0,1]
	v_mov_b64_e32 v[8:9], s[6:7]
	v_pk_mul_f32 v[4:5], v[2:3], v[8:9] op_sel:[0,0] op_sel_hi:[0,1]
	v_pk_add_f32 v[22:23], v[10:11], v[16:17]
	v_pk_add_f32 v[16:17], v[10:11], v[16:17] neg_lo:[0,1] neg_hi:[0,1]
	v_pk_add_f32 v[10:11], v[12:13], v[30:31]
	v_pk_add_f32 v[12:13], v[24:25], v[36:37]
	v_mov_b32_e32 v50, v42
	v_mov_b32_e32 v51, v49
	v_mov_b32_e32 v49, v43
	v_pk_fma_f32 v[42:43], v[2:3], v[8:9], v[4:5] op_sel:[1,1,0] op_sel_hi:[1,0,1] neg_lo:[1,0,0]
	v_mov_b64_e32 v[4:5], s[16:17]
	v_pk_mul_f32 v[2:3], v[46:47], v[4:5] op_sel:[0,0] op_sel_hi:[0,1]
	v_pk_add_f32 v[24:25], v[10:11], v[12:13]
	v_pk_add_f32 v[12:13], v[10:11], v[12:13] neg_lo:[0,1] neg_hi:[0,1]
	v_pk_mul_f32 v[10:11], v[6:7], v[4:5] op_sel:[0,0] op_sel_hi:[0,1]
	v_pk_fma_f32 v[46:47], v[46:47], v[4:5], v[2:3] op_sel:[1,1,0] op_sel_hi:[1,0,1] neg_lo:[1,0,0]
	v_mov_b64_e32 v[2:3], s[18:19]
	v_pk_mul_f32 v[52:53], v[50:51], v[2:3] op_sel:[0,0] op_sel_hi:[0,1]
	v_pk_fma_f32 v[28:29], v[6:7], v[4:5], v[10:11] op_sel:[1,1,0] op_sel_hi:[1,0,1] neg_lo:[1,0,0]
	v_mov_b64_e32 v[10:11], s[60:61]
	v_pk_mul_f32 v[6:7], v[16:17], v[10:11] op_sel:[0,0] op_sel_hi:[0,1]
	v_pk_fma_f32 v[50:51], v[50:51], v[2:3], v[52:53] op_sel:[1,1,0] op_sel_hi:[1,0,1] neg_lo:[1,0,0]
	v_pk_add_f32 v[52:53], v[14:15], v[26:27]
	s_waitcnt lgkmcnt(0)
	v_pk_add_f32 v[54:55], v[18:19], v[38:39]
	v_pk_fma_f32 v[16:17], v[16:17], v[10:11], v[6:7] op_sel:[1,1,0] op_sel_hi:[1,0,1] neg_lo:[1,0,0]
	v_mov_b64_e32 v[6:7], s[20:21]
	v_pk_mul_f32 v[30:31], v[12:13], v[6:7] op_sel:[0,0] op_sel_hi:[0,1]
	v_pk_add_f32 v[56:57], v[52:53], v[54:55]
	v_pk_fma_f32 v[30:31], v[12:13], v[6:7], v[30:31] op_sel:[1,1,0] op_sel_hi:[1,0,1] neg_lo:[1,0,0]
	v_pk_mul_f32 v[12:13], v[40:41], v[2:3] op_sel:[0,0] op_sel_hi:[0,1]
	v_pk_add_f32 v[14:15], v[14:15], v[26:27] neg_lo:[0,1] neg_hi:[0,1]
	v_pk_fma_f32 v[32:33], v[40:41], v[2:3], v[12:13] op_sel:[1,1,0] op_sel_hi:[1,0,1] neg_lo:[1,0,0]
	v_pk_mul_f32 v[12:13], v[44:45], v[6:7] op_sel:[0,0] op_sel_hi:[0,1]
	v_pk_add_f32 v[40:41], v[56:57], v[22:23]
	v_pk_fma_f32 v[34:35], v[44:45], v[6:7], v[12:13] op_sel:[1,1,0] op_sel_hi:[1,0,1] neg_lo:[1,0,0]
	v_pk_add_f32 v[44:45], v[20:21], v[24:25]
	v_pk_add_f32 v[22:23], v[56:57], v[22:23] neg_lo:[0,1] neg_hi:[0,1]
	v_pk_add_f32 v[20:21], v[20:21], v[24:25] neg_lo:[0,1] neg_hi:[0,1]
	v_mov_b64_e32 v[12:13], s[8:9]
	v_pk_add_f32 v[24:25], v[22:23], v[20:21] op_sel:[0,1] op_sel_hi:[1,0]
	v_pk_add_f32 v[20:21], v[22:23], v[20:21] op_sel:[0,1] op_sel_hi:[1,0] neg_lo:[0,1] neg_hi:[0,1]
	v_pk_mul_f32 v[36:37], v[48:49], v[12:13] op_sel:[0,0] op_sel_hi:[0,1]
	v_pk_add_f32 v[18:19], v[18:19], v[38:39] neg_lo:[0,1] neg_hi:[0,1]
	v_mov_b32_e32 v22, v20
	v_cvt_f32_u32_e32 v20, v58
	v_pk_fma_f32 v[36:37], v[48:49], v[12:13], v[36:37] op_sel:[1,1,0] op_sel_hi:[1,0,1] neg_lo:[1,0,0]
	v_pk_add_f32 v[48:49], v[40:41], v[44:45]
	v_pk_add_f32 v[40:41], v[40:41], v[44:45] neg_lo:[0,1] neg_hi:[0,1]
	v_pk_add_f32 v[44:45], v[52:53], v[54:55] neg_lo:[0,1] neg_hi:[0,1]
	v_pk_add_f32 v[54:55], v[28:29], v[30:31] neg_lo:[0,1] neg_hi:[0,1]
	v_pk_add_f32 v[52:53], v[44:45], v[16:17] neg_lo:[0,1] neg_hi:[0,1]
	v_pk_add_f32 v[28:29], v[28:29], v[30:31]
	v_pk_add_f32 v[16:17], v[44:45], v[16:17]
	v_mul_f32_e32 v20, 0x38800000, v20
	v_pk_add_f32 v[30:31], v[16:17], v[28:29]
	v_pk_add_f32 v[16:17], v[16:17], v[28:29] neg_lo:[0,1] neg_hi:[0,1]
	v_pk_add_f32 v[28:29], v[52:53], v[54:55] op_sel:[0,1] op_sel_hi:[1,0]
	v_pk_add_f32 v[44:45], v[52:53], v[54:55] op_sel:[0,1] op_sel_hi:[1,0] neg_lo:[0,1] neg_hi:[0,1]
	v_pk_add_f32 v[26:27], v[14:15], v[18:19] op_sel:[0,1] op_sel_hi:[1,0] neg_lo:[0,1] neg_hi:[0,1]
	v_pk_add_f32 v[14:15], v[14:15], v[18:19] op_sel:[0,1] op_sel_hi:[1,0]
	v_pk_add_f32 v[54:55], v[32:33], v[36:37] neg_lo:[0,1] neg_hi:[0,1]
	v_pk_add_f32 v[32:33], v[32:33], v[36:37]
	v_cos_f32_e32 v36, v20
	v_sin_f32_e32 v20, v20
	v_mov_b32_e32 v19, v15
	v_mov_b32_e32 v15, v27
	s_nop 1
	v_mov_b32_e32 v18, v26
	v_xor_b32_e32 v37, 0x80000000, v20
	v_pk_mul_f32 v[56:57], v[36:37], v[36:37] op_sel:[0,0] op_sel_hi:[0,1]
	v_pk_add_f32 v[38:39], v[42:43], v[50:51] neg_lo:[0,1] neg_hi:[0,1]
	v_pk_add_f32 v[26:27], v[14:15], v[46:47] neg_lo:[0,1] neg_hi:[0,1]
	v_pk_add_f32 v[42:43], v[42:43], v[50:51]
	v_pk_add_f32 v[14:15], v[14:15], v[46:47]
	v_pk_fma_f32 v[56:57], v[36:37], v[36:37], v[56:57] op_sel:[1,1,0] op_sel_hi:[1,0,1] neg_lo:[1,0,0]
	v_pk_add_f32 v[50:51], v[18:19], v[34:35] neg_lo:[0,1] neg_hi:[0,1]
	v_pk_mul_f32 v[58:59], v[56:57], v[36:37] op_sel:[0,0] op_sel_hi:[0,1]
	v_pk_add_f32 v[46:47], v[14:15], v[42:43]
	v_pk_add_f32 v[14:15], v[14:15], v[42:43] neg_lo:[0,1] neg_hi:[0,1]
	v_pk_add_f32 v[42:43], v[26:27], v[38:39] op_sel:[0,1] op_sel_hi:[1,0]
	v_pk_add_f32 v[26:27], v[26:27], v[38:39] op_sel:[0,1] op_sel_hi:[1,0] neg_lo:[0,1] neg_hi:[0,1]
	v_pk_add_f32 v[18:19], v[18:19], v[34:35]
	v_pk_fma_f32 v[58:59], v[56:57], v[36:37], v[58:59] op_sel:[1,1,0] op_sel_hi:[1,0,1] neg_lo:[1,0,0]
	v_pk_mul_f32 v[60:61], v[56:57], v[56:57] op_sel:[0,0] op_sel_hi:[0,1]
	v_mov_b32_e32 v53, v29
	v_pk_mul_f32 v[64:65], v[58:59], v[58:59] op_sel:[0,0] op_sel_hi:[0,1]
	v_mov_b32_e32 v38, v26
	v_mov_b32_e32 v39, v43
	v_pk_add_f32 v[34:35], v[18:19], v[32:33]
	v_pk_add_f32 v[18:19], v[18:19], v[32:33] neg_lo:[0,1] neg_hi:[0,1]
	v_pk_add_f32 v[32:33], v[50:51], v[54:55] op_sel:[0,1] op_sel_hi:[1,0]
	v_pk_add_f32 v[50:51], v[50:51], v[54:55] op_sel:[0,1] op_sel_hi:[1,0] neg_lo:[0,1] neg_hi:[0,1]
	v_pk_fma_f32 v[60:61], v[56:57], v[56:57], v[60:61] op_sel:[1,1,0] op_sel_hi:[1,0,1] neg_lo:[1,0,0]
	v_pk_fma_f32 v[64:65], v[58:59], v[58:59], v[64:65] op_sel:[1,1,0] op_sel_hi:[1,0,1] neg_lo:[1,0,0]
	v_mov_b32_e32 v43, v27
	v_pk_mul_f32 v[66:67], v[60:61], v[58:59] op_sel:[0,0] op_sel_hi:[0,1]
	v_mov_b32_e32 v29, v45
	v_pk_mul_f32 v[26:27], v[28:29], v[64:65] op_sel:[0,0] op_sel_hi:[0,1]
	v_mov_b32_e32 v55, v33
	v_pk_fma_f32 v[66:67], v[60:61], v[58:59], v[66:67] op_sel:[1,1,0] op_sel_hi:[1,0,1] neg_lo:[1,0,0]
	v_pk_mul_f32 v[68:69], v[60:61], v[60:61] op_sel:[0,0] op_sel_hi:[0,1]
	v_pk_fma_f32 v[26:27], v[28:29], v[64:65], v[26:27] op_sel:[1,1,0] op_sel_hi:[1,0,1] neg_lo:[1,0,0]
	v_mov_b32_e32 v33, v51
	v_pk_mul_f32 v[28:29], v[32:33], v[66:67] op_sel:[0,0] op_sel_hi:[0,1]
	v_pk_mul_f32 v[62:63], v[60:61], v[36:37] op_sel:[0,0] op_sel_hi:[0,1]
	v_pk_fma_f32 v[68:69], v[60:61], v[60:61], v[68:69] op_sel:[1,1,0] op_sel_hi:[1,0,1] neg_lo:[1,0,0]
	v_pk_mul_f32 v[76:77], v[64:65], v[64:65] op_sel:[0,0] op_sel_hi:[0,1]
	v_mov_b32_e32 v23, v25
	v_pk_mul_f32 v[70:71], v[68:69], v[36:37] op_sel:[0,0] op_sel_hi:[0,1]
	v_pk_fma_f32 v[28:29], v[32:33], v[66:67], v[28:29] op_sel:[1,1,0] op_sel_hi:[1,0,1] neg_lo:[1,0,0]
	v_pk_mul_f32 v[32:33], v[40:41], v[68:69] op_sel:[0,0] op_sel_hi:[0,1]
	v_pk_fma_f32 v[62:63], v[60:61], v[36:37], v[62:63] op_sel:[1,1,0] op_sel_hi:[1,0,1] neg_lo:[1,0,0]
	v_pk_mul_f32 v[74:75], v[68:69], v[58:59] op_sel:[0,0] op_sel_hi:[0,1]
	v_pk_fma_f32 v[76:77], v[64:65], v[64:65], v[76:77] op_sel:[1,1,0] op_sel_hi:[1,0,1] neg_lo:[1,0,0]
	s_nop 0
	v_pk_fma_f32 v[70:71], v[68:69], v[36:37], v[70:71] op_sel:[1,1,0] op_sel_hi:[1,0,1] neg_lo:[1,0,0]
	v_mov_b32_e32 v25, v21
	v_pk_mul_f32 v[72:73], v[62:63], v[62:63] op_sel:[0,0] op_sel_hi:[0,1]
	v_pk_fma_f32 v[32:33], v[40:41], v[68:69], v[32:33] op_sel:[1,1,0] op_sel_hi:[1,0,1] neg_lo:[1,0,0]
	v_pk_mul_f32 v[40:41], v[14:15], v[70:71] op_sel:[0,0] op_sel_hi:[0,1]
	v_pk_fma_f32 v[74:75], v[68:69], v[58:59], v[74:75] op_sel:[1,1,0] op_sel_hi:[1,0,1] neg_lo:[1,0,0]
	v_pk_mul_f32 v[78:79], v[68:69], v[62:63] op_sel:[0,0] op_sel_hi:[0,1]
	v_pk_mul_f32 v[20:21], v[24:25], v[60:61] op_sel:[0,0] op_sel_hi:[0,1]
	s_nop 0
	v_pk_fma_f32 v[72:73], v[62:63], v[62:63], v[72:73] op_sel:[1,1,0] op_sel_hi:[1,0,1] neg_lo:[1,0,0]
	v_add_u32_e32 v1, 0x200, v1
	v_pk_fma_f32 v[14:15], v[14:15], v[70:71], v[40:41] op_sel:[1,1,0] op_sel_hi:[1,0,1] neg_lo:[1,0,0]
	v_pk_mul_f32 v[40:41], v[16:17], v[72:73] op_sel:[0,0] op_sel_hi:[0,1]
	v_pk_fma_f32 v[78:79], v[68:69], v[62:63], v[78:79] op_sel:[1,1,0] op_sel_hi:[1,0,1] neg_lo:[1,0,0]
	v_pk_mul_f32 v[80:81], v[66:67], v[66:67] op_sel:[0,0] op_sel_hi:[0,1]
	v_pk_mul_f32 v[82:83], v[68:69], v[66:67] op_sel:[0,0] op_sel_hi:[0,1]
	v_pk_fma_f32 v[20:21], v[24:25], v[60:61], v[20:21] op_sel:[1,1,0] op_sel_hi:[1,0,1] neg_lo:[1,0,0]
	v_pk_mul_f32 v[24:25], v[42:43], v[62:63] op_sel:[0,0] op_sel_hi:[0,1]
	s_nop 0
	v_pk_fma_f32 v[16:17], v[16:17], v[72:73], v[40:41] op_sel:[1,1,0] op_sel_hi:[1,0,1] neg_lo:[1,0,0]
	v_pk_mul_f32 v[40:41], v[18:19], v[74:75] op_sel:[0,0] op_sel_hi:[0,1]
	v_and_b32_e32 v64, 0x3ff, v1
	v_pk_fma_f32 v[18:19], v[18:19], v[74:75], v[40:41] op_sel:[1,1,0] op_sel_hi:[1,0,1] neg_lo:[1,0,0]
	v_pk_mul_f32 v[40:41], v[22:23], v[76:77] op_sel:[0,0] op_sel_hi:[0,1]
	v_lshlrev_b32_e32 v1, 4, v1
	v_pk_fma_f32 v[22:23], v[22:23], v[76:77], v[40:41] op_sel:[1,1,0] op_sel_hi:[1,0,1] neg_lo:[1,0,0]
	v_pk_mul_f32 v[40:41], v[38:39], v[78:79] op_sel:[0,0] op_sel_hi:[0,1]
	v_mov_b32_e32 v52, v44
	v_mov_b32_e32 v54, v50
	v_pk_fma_f32 v[80:81], v[66:67], v[66:67], v[80:81] op_sel:[1,1,0] op_sel_hi:[1,0,1] neg_lo:[1,0,0]
	v_pk_fma_f32 v[82:83], v[68:69], v[66:67], v[82:83] op_sel:[1,1,0] op_sel_hi:[1,0,1] neg_lo:[1,0,0]
	v_pk_mul_f32 v[84:85], v[46:47], v[36:37] op_sel:[0,0] op_sel_hi:[0,1]
	v_pk_fma_f32 v[24:25], v[42:43], v[62:63], v[24:25] op_sel:[1,1,0] op_sel_hi:[1,0,1] neg_lo:[1,0,0]
	v_pk_fma_f32 v[38:39], v[38:39], v[78:79], v[40:41] op_sel:[1,1,0] op_sel_hi:[1,0,1] neg_lo:[1,0,0]
	v_and_or_b32 v1, v1, s3, v64
	v_pk_fma_f32 v[36:37], v[46:47], v[36:37], v[84:85] op_sel:[1,1,0] op_sel_hi:[1,0,1] neg_lo:[1,0,0]
	v_pk_mul_f32 v[46:47], v[30:31], v[56:57] op_sel:[0,0] op_sel_hi:[0,1]
	v_pk_mul_f32 v[40:41], v[52:53], v[80:81] op_sel:[0,0] op_sel_hi:[0,1]
	v_pk_mul_f32 v[42:43], v[54:55], v[82:83] op_sel:[0,0] op_sel_hi:[0,1]
	s_nop 0
	v_pk_fma_f32 v[30:31], v[30:31], v[56:57], v[46:47] op_sel:[1,1,0] op_sel_hi:[1,0,1] neg_lo:[1,0,0]
	v_pk_mul_f32 v[46:47], v[34:35], v[58:59] op_sel:[0,0] op_sel_hi:[0,1]
	v_pk_fma_f32 v[40:41], v[52:53], v[80:81], v[40:41] op_sel:[1,1,0] op_sel_hi:[1,0,1] neg_lo:[1,0,0]
	v_pk_fma_f32 v[42:43], v[54:55], v[82:83], v[42:43] op_sel:[1,1,0] op_sel_hi:[1,0,1] neg_lo:[1,0,0]
	s_nop 0
	v_pk_fma_f32 v[34:35], v[34:35], v[58:59], v[46:47] op_sel:[1,1,0] op_sel_hi:[1,0,1] neg_lo:[1,0,0]
	ds_write2st64_b64 v86, v[48:49], v[36:37] offset1:17
	ds_write2st64_b64 v86, v[30:31], v[34:35] offset0:34 offset1:51
	ds_write2st64_b64 v86, v[20:21], v[24:25] offset0:68 offset1:85
	ds_write2st64_b64 v86, v[26:27], v[28:29] offset0:102 offset1:119
	ds_write_b64 v87, v[32:33]
	ds_write_b64 v88, v[14:15]
	ds_write_b64 v89, v[16:17]
	ds_write_b64 v90, v[18:19]
	ds_write_b64 v91, v[22:23]
	ds_write_b64 v92, v[38:39]
	ds_write_b64 v93, v[40:41]
	ds_write_b64 v94, v[42:43]
	v_ashrrev_i32_e32 v14, 4, v1
	v_lshlrev_b32_e32 v14, 3, v14
	v_lshlrev_b32_e32 v1, 3, v1
	v_add3_u32 v1, 0, v14, v1
	ds_read2st64_b64 v[14:17], v1 offset1:17
	ds_read2st64_b64 v[18:21], v1 offset0:34 offset1:51
	ds_read2st64_b64 v[22:25], v1 offset0:68 offset1:85
	ds_read2st64_b64 v[26:29], v1 offset0:102 offset1:119
	v_add_u32_e32 v86, 0x11000, v1
	v_add_u32_e32 v87, 0x13200, v1
	v_add_u32_e32 v88, 0x15400, v1
	v_add_u32_e32 v89, 0x17600, v1
	ds_read_b64 v[30:31], v86
	ds_read_b64 v[32:33], v87
	ds_read_b64 v[34:35], v88
	ds_read_b64 v[36:37], v89
	v_add_u32_e32 v91, 0x1ba00, v1
	v_add_u32_e32 v90, 0x19800, v1
	v_add_u32_e32 v92, 0x1dc00, v1
	v_add_u32_e32 v93, 0x1fe00, v1
	ds_read_b64 v[38:39], v91
	ds_read_b64 v[40:41], v92
	ds_read_b64 v[42:43], v93
	ds_read_b64 v[44:45], v90
	s_waitcnt lgkmcnt(6)
	v_pk_add_f32 v[46:47], v[16:17], v[32:33] neg_lo:[0,1] neg_hi:[0,1]
	s_waitcnt lgkmcnt(3)
	v_pk_add_f32 v[48:49], v[24:25], v[38:39] neg_lo:[0,1] neg_hi:[0,1]
	s_waitcnt lgkmcnt(2)
	v_pk_add_f32 v[52:53], v[26:27], v[40:41] neg_lo:[0,1] neg_hi:[0,1]
	v_pk_add_f32 v[50:51], v[46:47], v[48:49] op_sel:[0,1] op_sel_hi:[1,0]
	v_pk_add_f32 v[46:47], v[46:47], v[48:49] op_sel:[0,1] op_sel_hi:[1,0] neg_lo:[0,1] neg_hi:[0,1]
	v_mov_b32_e32 v48, v50
	v_mov_b32_e32 v49, v47
	v_mov_b32_e32 v47, v51
	v_pk_add_f32 v[50:51], v[18:19], v[34:35] neg_lo:[0,1] neg_hi:[0,1]
	s_waitcnt lgkmcnt(1)
	v_pk_add_f32 v[56:57], v[28:29], v[42:43] neg_lo:[0,1] neg_hi:[0,1]
	v_pk_add_f32 v[54:55], v[50:51], v[52:53] op_sel:[0,1] op_sel_hi:[1,0]
	v_pk_add_f32 v[50:51], v[50:51], v[52:53] op_sel:[0,1] op_sel_hi:[1,0] neg_lo:[0,1] neg_hi:[0,1]
	v_mov_b32_e32 v52, v54
	v_mov_b32_e32 v53, v51
	v_mov_b32_e32 v51, v55
	v_pk_add_f32 v[54:55], v[20:21], v[36:37] neg_lo:[0,1] neg_hi:[0,1]
	v_pk_add_f32 v[16:17], v[16:17], v[32:33]
	v_pk_add_f32 v[58:59], v[54:55], v[56:57] op_sel:[0,1] op_sel_hi:[1,0]
	v_pk_add_f32 v[54:55], v[54:55], v[56:57] op_sel:[0,1] op_sel_hi:[1,0] neg_lo:[0,1] neg_hi:[0,1]
	v_mov_b32_e32 v56, v58
	v_mov_b32_e32 v57, v55
	v_mov_b32_e32 v55, v59
	v_pk_mul_f32 v[58:59], v[48:49], v[8:9] op_sel:[0,0] op_sel_hi:[0,1]
	v_pk_add_f32 v[24:25], v[24:25], v[38:39]
	v_pk_fma_f32 v[48:49], v[48:49], v[8:9], v[58:59] op_sel:[1,1,0] op_sel_hi:[1,0,1] neg_lo:[1,0,0]
	v_pk_mul_f32 v[58:59], v[52:53], v[4:5] op_sel:[0,0] op_sel_hi:[0,1]
	v_pk_add_f32 v[18:19], v[18:19], v[34:35]
	v_pk_add_f32 v[32:33], v[16:17], v[24:25]
	v_pk_add_f32 v[16:17], v[16:17], v[24:25] neg_lo:[0,1] neg_hi:[0,1]
	v_pk_add_f32 v[24:25], v[26:27], v[40:41]
	v_pk_fma_f32 v[52:53], v[52:53], v[4:5], v[58:59] op_sel:[1,1,0] op_sel_hi:[1,0,1] neg_lo:[1,0,0]
	v_pk_mul_f32 v[58:59], v[56:57], v[2:3] op_sel:[0,0] op_sel_hi:[0,1]
	v_pk_add_f32 v[20:21], v[20:21], v[36:37]
	v_pk_add_f32 v[26:27], v[18:19], v[24:25]
	v_pk_add_f32 v[18:19], v[18:19], v[24:25] neg_lo:[0,1] neg_hi:[0,1]
	v_pk_add_f32 v[24:25], v[28:29], v[42:43]
	v_pk_fma_f32 v[56:57], v[56:57], v[2:3], v[58:59] op_sel:[1,1,0] op_sel_hi:[1,0,1] neg_lo:[1,0,0]
	v_pk_add_f32 v[58:59], v[14:15], v[30:31]
	s_waitcnt lgkmcnt(0)
	v_pk_add_f32 v[60:61], v[22:23], v[44:45]
	v_pk_add_f32 v[28:29], v[20:21], v[24:25]
	v_pk_add_f32 v[20:21], v[20:21], v[24:25] neg_lo:[0,1] neg_hi:[0,1]
	v_pk_mul_f32 v[24:25], v[16:17], v[4:5] op_sel:[0,0] op_sel_hi:[0,1]
	v_pk_add_f32 v[62:63], v[58:59], v[60:61]
	v_pk_fma_f32 v[16:17], v[16:17], v[4:5], v[24:25] op_sel:[1,1,0] op_sel_hi:[1,0,1] neg_lo:[1,0,0]
	v_pk_mul_f32 v[24:25], v[18:19], v[10:11] op_sel:[0,0] op_sel_hi:[0,1]
	v_pk_add_f32 v[40:41], v[32:33], v[28:29]
	v_pk_fma_f32 v[18:19], v[18:19], v[10:11], v[24:25] op_sel:[1,1,0] op_sel_hi:[1,0,1] neg_lo:[1,0,0]
	v_pk_mul_f32 v[24:25], v[20:21], v[6:7] op_sel:[0,0] op_sel_hi:[0,1]
	v_pk_add_f32 v[38:39], v[62:63], v[26:27]
	v_pk_fma_f32 v[20:21], v[20:21], v[6:7], v[24:25] op_sel:[1,1,0] op_sel_hi:[1,0,1] neg_lo:[1,0,0]
	v_pk_mul_f32 v[24:25], v[46:47], v[2:3] op_sel:[0,0] op_sel_hi:[0,1]
	v_pk_mul_f32 v[34:35], v[50:51], v[6:7] op_sel:[0,0] op_sel_hi:[0,1]
	v_pk_mul_f32 v[36:37], v[54:55], v[12:13] op_sel:[0,0] op_sel_hi:[0,1]
	v_pk_add_f32 v[14:15], v[14:15], v[30:31] neg_lo:[0,1] neg_hi:[0,1]
	v_pk_add_f32 v[42:43], v[38:39], v[40:41]
	v_pk_add_f32 v[38:39], v[38:39], v[40:41] neg_lo:[0,1] neg_hi:[0,1]
	v_pk_add_f32 v[40:41], v[58:59], v[60:61] neg_lo:[0,1] neg_hi:[0,1]
	v_pk_fma_f32 v[24:25], v[46:47], v[2:3], v[24:25] op_sel:[1,1,0] op_sel_hi:[1,0,1] neg_lo:[1,0,0]
	v_pk_fma_f32 v[34:35], v[50:51], v[6:7], v[34:35] op_sel:[1,1,0] op_sel_hi:[1,0,1] neg_lo:[1,0,0]
	v_pk_add_f32 v[50:51], v[16:17], v[20:21] neg_lo:[0,1] neg_hi:[0,1]
	v_pk_add_f32 v[46:47], v[40:41], v[18:19] neg_lo:[0,1] neg_hi:[0,1]
	v_pk_add_f32 v[16:17], v[16:17], v[20:21]
	v_pk_add_f32 v[18:19], v[40:41], v[18:19]
	v_pk_add_f32 v[40:41], v[46:47], v[50:51] op_sel:[0,1] op_sel_hi:[1,0] neg_lo:[0,1] neg_hi:[0,1]
	v_pk_add_f32 v[20:21], v[18:19], v[16:17]
	v_pk_add_f32 v[16:17], v[18:19], v[16:17] neg_lo:[0,1] neg_hi:[0,1]
	v_pk_add_f32 v[18:19], v[46:47], v[50:51] op_sel:[0,1] op_sel_hi:[1,0]
	v_pk_fma_f32 v[36:37], v[54:55], v[12:13], v[36:37] op_sel:[1,1,0] op_sel_hi:[1,0,1] neg_lo:[1,0,0]
	v_pk_add_f32 v[22:23], v[22:23], v[44:45] neg_lo:[0,1] neg_hi:[0,1]
	v_mov_b32_e32 v47, v19
	v_cvt_f32_u32_e32 v19, v64
	v_pk_add_f32 v[54:55], v[24:25], v[36:37] neg_lo:[0,1] neg_hi:[0,1]
	v_pk_add_f32 v[24:25], v[24:25], v[36:37]
	v_pk_add_f32 v[26:27], v[62:63], v[26:27] neg_lo:[0,1] neg_hi:[0,1]
	v_mul_f32_e32 v19, 0x38800000, v19
	v_cos_f32_e32 v36, v19
	v_sin_f32_e32 v19, v19
	v_pk_add_f32 v[28:29], v[32:33], v[28:29] neg_lo:[0,1] neg_hi:[0,1]
	v_pk_add_f32 v[30:31], v[14:15], v[22:23] op_sel:[0,1] op_sel_hi:[1,0] neg_lo:[0,1] neg_hi:[0,1]
	v_pk_add_f32 v[14:15], v[14:15], v[22:23] op_sel:[0,1] op_sel_hi:[1,0]
	v_pk_add_f32 v[44:45], v[48:49], v[56:57] neg_lo:[0,1] neg_hi:[0,1]
	v_pk_add_f32 v[48:49], v[48:49], v[56:57]
	s_nop 1
	v_pk_add_f32 v[32:33], v[26:27], v[28:29] op_sel:[0,1] op_sel_hi:[1,0]
	v_xor_b32_e32 v37, 0x80000000, v19
	v_pk_mul_f32 v[56:57], v[36:37], v[36:37] op_sel:[0,0] op_sel_hi:[0,1]
	v_pk_add_f32 v[26:27], v[26:27], v[28:29] op_sel:[0,1] op_sel_hi:[1,0] neg_lo:[0,1] neg_hi:[0,1]
	v_mov_b32_e32 v22, v30
	v_mov_b32_e32 v23, v15
	v_mov_b32_e32 v15, v31
	v_pk_fma_f32 v[56:57], v[36:37], v[36:37], v[56:57] op_sel:[1,1,0] op_sel_hi:[1,0,1] neg_lo:[1,0,0]
	v_mov_b32_e32 v28, v26
	v_pk_mul_f32 v[58:59], v[56:57], v[36:37] op_sel:[0,0] op_sel_hi:[0,1]
	v_pk_mul_f32 v[60:61], v[56:57], v[56:57] op_sel:[0,0] op_sel_hi:[0,1]
	v_mov_b32_e32 v29, v33
	v_pk_add_f32 v[30:31], v[14:15], v[52:53] neg_lo:[0,1] neg_hi:[0,1]
	v_pk_add_f32 v[14:15], v[14:15], v[52:53]
	v_pk_add_f32 v[52:53], v[22:23], v[34:35] neg_lo:[0,1] neg_hi:[0,1]
	v_pk_add_f32 v[22:23], v[22:23], v[34:35]
	v_pk_fma_f32 v[58:59], v[56:57], v[36:37], v[58:59] op_sel:[1,1,0] op_sel_hi:[1,0,1] neg_lo:[1,0,0]
	v_pk_fma_f32 v[60:61], v[56:57], v[56:57], v[60:61] op_sel:[1,1,0] op_sel_hi:[1,0,1] neg_lo:[1,0,0]
	v_mov_b32_e32 v33, v27
	v_pk_mul_f32 v[64:65], v[58:59], v[58:59] op_sel:[0,0] op_sel_hi:[0,1]
	v_pk_mul_f32 v[26:27], v[32:33], v[60:61] op_sel:[0,0] op_sel_hi:[0,1]
	v_pk_add_f32 v[34:35], v[22:23], v[24:25]
	v_pk_add_f32 v[22:23], v[22:23], v[24:25] neg_lo:[0,1] neg_hi:[0,1]
	v_pk_add_f32 v[24:25], v[52:53], v[54:55] op_sel:[0,1] op_sel_hi:[1,0]
	v_pk_add_f32 v[52:53], v[52:53], v[54:55] op_sel:[0,1] op_sel_hi:[1,0] neg_lo:[0,1] neg_hi:[0,1]
	v_pk_fma_f32 v[64:65], v[58:59], v[58:59], v[64:65] op_sel:[1,1,0] op_sel_hi:[1,0,1] neg_lo:[1,0,0]
	v_pk_mul_f32 v[66:67], v[60:61], v[58:59] op_sel:[0,0] op_sel_hi:[0,1]
	v_pk_fma_f32 v[26:27], v[32:33], v[60:61], v[26:27] op_sel:[1,1,0] op_sel_hi:[1,0,1] neg_lo:[1,0,0]
	v_mov_b32_e32 v19, v41
	v_pk_mul_f32 v[32:33], v[18:19], v[64:65] op_sel:[0,0] op_sel_hi:[0,1]
	v_mov_b32_e32 v55, v25
	v_pk_fma_f32 v[66:67], v[60:61], v[58:59], v[66:67] op_sel:[1,1,0] op_sel_hi:[1,0,1] neg_lo:[1,0,0]
	v_pk_mul_f32 v[68:69], v[60:61], v[60:61] op_sel:[0,0] op_sel_hi:[0,1]
	v_pk_fma_f32 v[18:19], v[18:19], v[64:65], v[32:33] op_sel:[1,1,0] op_sel_hi:[1,0,1] neg_lo:[1,0,0]
	v_mov_b32_e32 v25, v53
	v_pk_mul_f32 v[32:33], v[24:25], v[66:67] op_sel:[0,0] op_sel_hi:[0,1]
	v_pk_mul_f32 v[62:63], v[60:61], v[36:37] op_sel:[0,0] op_sel_hi:[0,1]
	v_pk_fma_f32 v[68:69], v[60:61], v[60:61], v[68:69] op_sel:[1,1,0] op_sel_hi:[1,0,1] neg_lo:[1,0,0]
	v_pk_add_f32 v[50:51], v[14:15], v[48:49]
	v_pk_mul_f32 v[70:71], v[68:69], v[36:37] op_sel:[0,0] op_sel_hi:[0,1]
	v_pk_fma_f32 v[24:25], v[24:25], v[66:67], v[32:33] op_sel:[1,1,0] op_sel_hi:[1,0,1] neg_lo:[1,0,0]
	v_pk_mul_f32 v[32:33], v[38:39], v[68:69] op_sel:[0,0] op_sel_hi:[0,1]
	v_pk_add_f32 v[14:15], v[14:15], v[48:49] neg_lo:[0,1] neg_hi:[0,1]
	v_pk_fma_f32 v[62:63], v[60:61], v[36:37], v[62:63] op_sel:[1,1,0] op_sel_hi:[1,0,1] neg_lo:[1,0,0]
	v_pk_fma_f32 v[70:71], v[68:69], v[36:37], v[70:71] op_sel:[1,1,0] op_sel_hi:[1,0,1] neg_lo:[1,0,0]
	v_pk_fma_f32 v[32:33], v[38:39], v[68:69], v[32:33] op_sel:[1,1,0] op_sel_hi:[1,0,1] neg_lo:[1,0,0]
	v_pk_mul_f32 v[74:75], v[68:69], v[58:59] op_sel:[0,0] op_sel_hi:[0,1]
	v_pk_mul_f32 v[76:77], v[64:65], v[64:65] op_sel:[0,0] op_sel_hi:[0,1]
	v_pk_add_f32 v[48:49], v[30:31], v[44:45] op_sel:[0,1] op_sel_hi:[1,0]
	v_pk_mul_f32 v[72:73], v[62:63], v[62:63] op_sel:[0,0] op_sel_hi:[0,1]
	v_pk_mul_f32 v[38:39], v[14:15], v[70:71] op_sel:[0,0] op_sel_hi:[0,1]
	v_pk_fma_f32 v[74:75], v[68:69], v[58:59], v[74:75] op_sel:[1,1,0] op_sel_hi:[1,0,1] neg_lo:[1,0,0]
	v_pk_add_f32 v[30:31], v[30:31], v[44:45] op_sel:[0,1] op_sel_hi:[1,0] neg_lo:[0,1] neg_hi:[0,1]
	v_pk_fma_f32 v[72:73], v[62:63], v[62:63], v[72:73] op_sel:[1,1,0] op_sel_hi:[1,0,1] neg_lo:[1,0,0]
	v_pk_fma_f32 v[14:15], v[14:15], v[70:71], v[38:39] op_sel:[1,1,0] op_sel_hi:[1,0,1] neg_lo:[1,0,0]
	v_pk_fma_f32 v[76:77], v[64:65], v[64:65], v[76:77] op_sel:[1,1,0] op_sel_hi:[1,0,1] neg_lo:[1,0,0]
	v_pk_mul_f32 v[78:79], v[68:69], v[62:63] op_sel:[0,0] op_sel_hi:[0,1]
	v_mov_b32_e32 v45, v49
	v_pk_mul_f32 v[38:39], v[16:17], v[72:73] op_sel:[0,0] op_sel_hi:[0,1]
	v_mov_b32_e32 v44, v30
	v_pk_fma_f32 v[16:17], v[16:17], v[72:73], v[38:39] op_sel:[1,1,0] op_sel_hi:[1,0,1] neg_lo:[1,0,0]
	v_pk_mul_f32 v[38:39], v[22:23], v[74:75] op_sel:[0,0] op_sel_hi:[0,1]
	v_pk_fma_f32 v[78:79], v[68:69], v[62:63], v[78:79] op_sel:[1,1,0] op_sel_hi:[1,0,1] neg_lo:[1,0,0]
	v_pk_mul_f32 v[80:81], v[66:67], v[66:67] op_sel:[0,0] op_sel_hi:[0,1]
	v_pk_mul_f32 v[82:83], v[68:69], v[66:67] op_sel:[0,0] op_sel_hi:[0,1]
	v_mov_b32_e32 v46, v40
	v_pk_fma_f32 v[22:23], v[22:23], v[74:75], v[38:39] op_sel:[1,1,0] op_sel_hi:[1,0,1] neg_lo:[1,0,0]
	v_pk_mul_f32 v[38:39], v[28:29], v[76:77] op_sel:[0,0] op_sel_hi:[0,1]
	v_mov_b32_e32 v54, v52
	v_pk_fma_f32 v[28:29], v[28:29], v[76:77], v[38:39] op_sel:[1,1,0] op_sel_hi:[1,0,1] neg_lo:[1,0,0]
	v_pk_mul_f32 v[38:39], v[44:45], v[78:79] op_sel:[0,0] op_sel_hi:[0,1]
	v_pk_fma_f32 v[80:81], v[66:67], v[66:67], v[80:81] op_sel:[1,1,0] op_sel_hi:[1,0,1] neg_lo:[1,0,0]
	v_pk_fma_f32 v[82:83], v[68:69], v[66:67], v[82:83] op_sel:[1,1,0] op_sel_hi:[1,0,1] neg_lo:[1,0,0]
	v_pk_mul_f32 v[84:85], v[50:51], v[36:37] op_sel:[0,0] op_sel_hi:[0,1]
	v_mov_b32_e32 v49, v31
	v_pk_fma_f32 v[36:37], v[50:51], v[36:37], v[84:85] op_sel:[1,1,0] op_sel_hi:[1,0,1] neg_lo:[1,0,0]
	v_pk_mul_f32 v[50:51], v[20:21], v[56:57] op_sel:[0,0] op_sel_hi:[0,1]
	v_pk_mul_f32 v[30:31], v[48:49], v[62:63] op_sel:[0,0] op_sel_hi:[0,1]
	v_pk_fma_f32 v[38:39], v[44:45], v[78:79], v[38:39] op_sel:[1,1,0] op_sel_hi:[1,0,1] neg_lo:[1,0,0]
	v_pk_mul_f32 v[40:41], v[46:47], v[80:81] op_sel:[0,0] op_sel_hi:[0,1]
	v_pk_mul_f32 v[44:45], v[54:55], v[82:83] op_sel:[0,0] op_sel_hi:[0,1]
	s_nop 0
	v_pk_fma_f32 v[20:21], v[20:21], v[56:57], v[50:51] op_sel:[1,1,0] op_sel_hi:[1,0,1] neg_lo:[1,0,0]
	v_pk_mul_f32 v[50:51], v[34:35], v[58:59] op_sel:[0,0] op_sel_hi:[0,1]
	v_pk_fma_f32 v[30:31], v[48:49], v[62:63], v[30:31] op_sel:[1,1,0] op_sel_hi:[1,0,1] neg_lo:[1,0,0]
	v_pk_fma_f32 v[40:41], v[46:47], v[80:81], v[40:41] op_sel:[1,1,0] op_sel_hi:[1,0,1] neg_lo:[1,0,0]
	v_pk_fma_f32 v[44:45], v[54:55], v[82:83], v[44:45] op_sel:[1,1,0] op_sel_hi:[1,0,1] neg_lo:[1,0,0]
	s_nop 0
	v_pk_fma_f32 v[34:35], v[34:35], v[58:59], v[50:51] op_sel:[1,1,0] op_sel_hi:[1,0,1] neg_lo:[1,0,0]
	ds_write2st64_b64 v1, v[42:43], v[36:37] offset1:17
	ds_write2st64_b64 v1, v[20:21], v[34:35] offset0:34 offset1:51
	ds_write2st64_b64 v1, v[26:27], v[30:31] offset0:68 offset1:85
	ds_write2st64_b64 v1, v[18:19], v[24:25] offset0:102 offset1:119
	ds_write_b64 v86, v[32:33]
	ds_write_b64 v87, v[14:15]
	ds_write_b64 v88, v[16:17]
	ds_write_b64 v89, v[22:23]
	ds_write_b64 v90, v[28:29]
	ds_write_b64 v91, v[38:39]
	ds_write_b64 v92, v[40:41]
	ds_write_b64 v93, v[44:45]
	v_mov_b32_e32 v1, v0
	s_waitcnt lgkmcnt(0)
	s_barrier
	s_nop 0
	v_and_b32_e32 v15, 63, v1
	v_lshlrev_b32_e32 v1, 4, v1
	v_cvt_f32_ubyte0_e32 v14, v15
	v_and_or_b32 v1, v1, s13, v15
	v_mul_f32_e32 v16, 0x3a800000, v14
	v_ashrrev_i32_e32 v15, 4, v1
	v_cos_f32_e32 v14, v16
	v_sin_f32_e32 v88, v16
	v_lshlrev_b32_e32 v15, 3, v15
	v_lshlrev_b32_e32 v16, 3, v1
	v_add3_u32 v15, 0, v15, v16
	v_add_u32_e32 v89, 0x800, v15
	v_add_u32_e32 v90, 0x1000, v15
	ds_read2_b64 v[16:19], v15 offset1:68
	ds_read2_b64 v[20:23], v15 offset0:136 offset1:204
	ds_read2_b64 v[24:27], v89 offset0:16 offset1:84
	ds_read2_b64 v[28:31], v90 offset0:32 offset1:100
	v_add_u32_e32 v91, 0x1800, v15
	ds_read2_b64 v[32:35], v91 offset0:48 offset1:116
	ds_read2_b64 v[36:39], v89 offset0:152 offset1:220
	ds_read2_b64 v[40:43], v90 offset0:168 offset1:236
	ds_read2_b64 v[44:47], v91 offset0:184 offset1:252
	v_add_u32_e32 v1, 0x2000, v1
	s_waitcnt lgkmcnt(3)
	v_pk_add_f32 v[50:51], v[26:27], v[34:35] neg_lo:[0,1] neg_hi:[0,1]
	v_pk_add_f32 v[48:49], v[18:19], v[30:31] neg_lo:[0,1] neg_hi:[0,1]
	v_pk_add_f32 v[18:19], v[18:19], v[30:31]
	v_pk_add_f32 v[52:53], v[48:49], v[50:51] op_sel:[0,1] op_sel_hi:[1,0]
	v_pk_add_f32 v[48:49], v[48:49], v[50:51] op_sel:[0,1] op_sel_hi:[1,0] neg_lo:[0,1] neg_hi:[0,1]
	v_mov_b32_e32 v50, v52
	v_mov_b32_e32 v51, v49
	v_mov_b32_e32 v49, v53
	s_waitcnt lgkmcnt(1)
	v_pk_add_f32 v[52:53], v[20:21], v[40:41] neg_lo:[0,1] neg_hi:[0,1]
	s_waitcnt lgkmcnt(0)
	v_pk_add_f32 v[54:55], v[36:37], v[44:45] neg_lo:[0,1] neg_hi:[0,1]
	v_pk_add_f32 v[58:59], v[38:39], v[46:47] neg_lo:[0,1] neg_hi:[0,1]
	v_pk_add_f32 v[56:57], v[52:53], v[54:55] op_sel:[0,1] op_sel_hi:[1,0]
	v_pk_add_f32 v[52:53], v[52:53], v[54:55] op_sel:[0,1] op_sel_hi:[1,0] neg_lo:[0,1] neg_hi:[0,1]
	v_mov_b32_e32 v54, v56
	v_mov_b32_e32 v55, v53
	v_mov_b32_e32 v53, v57
	v_pk_add_f32 v[56:57], v[22:23], v[42:43] neg_lo:[0,1] neg_hi:[0,1]
	v_pk_add_f32 v[26:27], v[26:27], v[34:35]
	v_pk_add_f32 v[60:61], v[56:57], v[58:59] op_sel:[0,1] op_sel_hi:[1,0]
	v_pk_add_f32 v[56:57], v[56:57], v[58:59] op_sel:[0,1] op_sel_hi:[1,0] neg_lo:[0,1] neg_hi:[0,1]
	v_mov_b32_e32 v58, v60
	v_mov_b32_e32 v59, v57
	v_mov_b32_e32 v57, v61
	v_pk_mul_f32 v[60:61], v[50:51], v[8:9] op_sel:[0,0] op_sel_hi:[0,1]
	v_pk_add_f32 v[30:31], v[18:19], v[26:27]
	v_pk_fma_f32 v[50:51], v[50:51], v[8:9], v[60:61] op_sel:[1,1,0] op_sel_hi:[1,0,1] neg_lo:[1,0,0]
	v_pk_mul_f32 v[60:61], v[54:55], v[4:5] op_sel:[0,0] op_sel_hi:[0,1]
	v_pk_add_f32 v[18:19], v[18:19], v[26:27] neg_lo:[0,1] neg_hi:[0,1]
	v_pk_add_f32 v[20:21], v[20:21], v[40:41]
	v_pk_add_f32 v[26:27], v[36:37], v[44:45]
	v_pk_fma_f32 v[54:55], v[54:55], v[4:5], v[60:61] op_sel:[1,1,0] op_sel_hi:[1,0,1] neg_lo:[1,0,0]
	v_pk_mul_f32 v[60:61], v[58:59], v[2:3] op_sel:[0,0] op_sel_hi:[0,1]
	v_pk_add_f32 v[22:23], v[22:23], v[42:43]
	v_pk_add_f32 v[34:35], v[20:21], v[26:27]
	v_pk_add_f32 v[20:21], v[20:21], v[26:27] neg_lo:[0,1] neg_hi:[0,1]
	v_pk_add_f32 v[26:27], v[38:39], v[46:47]
	v_pk_fma_f32 v[58:59], v[58:59], v[2:3], v[60:61] op_sel:[1,1,0] op_sel_hi:[1,0,1] neg_lo:[1,0,0]
	v_pk_add_f32 v[60:61], v[16:17], v[28:29]
	v_pk_add_f32 v[62:63], v[24:25], v[32:33]
	v_pk_add_f32 v[36:37], v[22:23], v[26:27]
	v_pk_add_f32 v[22:23], v[22:23], v[26:27] neg_lo:[0,1] neg_hi:[0,1]
	v_pk_mul_f32 v[26:27], v[18:19], v[4:5] op_sel:[0,0] op_sel_hi:[0,1]
	v_pk_add_f32 v[64:65], v[60:61], v[62:63]
	v_pk_fma_f32 v[18:19], v[18:19], v[4:5], v[26:27] op_sel:[1,1,0] op_sel_hi:[1,0,1] neg_lo:[1,0,0]
	v_pk_mul_f32 v[26:27], v[20:21], v[10:11] op_sel:[0,0] op_sel_hi:[0,1]
	v_pk_add_f32 v[44:45], v[30:31], v[36:37]
	v_pk_fma_f32 v[20:21], v[20:21], v[10:11], v[26:27] op_sel:[1,1,0] op_sel_hi:[1,0,1] neg_lo:[1,0,0]
	v_pk_mul_f32 v[26:27], v[22:23], v[6:7] op_sel:[0,0] op_sel_hi:[0,1]
	v_pk_add_f32 v[42:43], v[64:65], v[34:35]
	v_pk_add_f32 v[16:17], v[16:17], v[28:29] neg_lo:[0,1] neg_hi:[0,1]
	v_pk_add_f32 v[24:25], v[24:25], v[32:33] neg_lo:[0,1] neg_hi:[0,1]
	v_pk_fma_f32 v[22:23], v[22:23], v[6:7], v[26:27] op_sel:[1,1,0] op_sel_hi:[1,0,1] neg_lo:[1,0,0]
	v_pk_mul_f32 v[26:27], v[48:49], v[2:3] op_sel:[0,0] op_sel_hi:[0,1]
	v_pk_mul_f32 v[38:39], v[52:53], v[6:7] op_sel:[0,0] op_sel_hi:[0,1]
	v_pk_add_f32 v[46:47], v[42:43], v[44:45]
	v_pk_add_f32 v[42:43], v[42:43], v[44:45] neg_lo:[0,1] neg_hi:[0,1]
	v_pk_add_f32 v[44:45], v[60:61], v[62:63] neg_lo:[0,1] neg_hi:[0,1]
	v_pk_add_f32 v[28:29], v[16:17], v[24:25] op_sel:[0,1] op_sel_hi:[1,0] neg_lo:[0,1] neg_hi:[0,1]
	v_pk_add_f32 v[16:17], v[16:17], v[24:25] op_sel:[0,1] op_sel_hi:[1,0]
	v_pk_fma_f32 v[26:27], v[48:49], v[2:3], v[26:27] op_sel:[1,1,0] op_sel_hi:[1,0,1] neg_lo:[1,0,0]
	v_pk_fma_f32 v[38:39], v[52:53], v[6:7], v[38:39] op_sel:[1,1,0] op_sel_hi:[1,0,1] neg_lo:[1,0,0]
	v_pk_mul_f32 v[40:41], v[56:57], v[12:13] op_sel:[0,0] op_sel_hi:[0,1]
	v_pk_add_f32 v[48:49], v[44:45], v[20:21] neg_lo:[0,1] neg_hi:[0,1]
	v_pk_add_f32 v[52:53], v[18:19], v[22:23] neg_lo:[0,1] neg_hi:[0,1]
	v_pk_add_f32 v[18:19], v[18:19], v[22:23]
	v_pk_add_f32 v[20:21], v[44:45], v[20:21]
	v_mov_b32_e32 v24, v28
	v_mov_b32_e32 v25, v17
	v_mov_b32_e32 v17, v29
	v_pk_fma_f32 v[40:41], v[56:57], v[12:13], v[40:41] op_sel:[1,1,0] op_sel_hi:[1,0,1] neg_lo:[1,0,0]
	v_pk_add_f32 v[22:23], v[20:21], v[18:19]
	v_pk_add_f32 v[18:19], v[20:21], v[18:19] neg_lo:[0,1] neg_hi:[0,1]
	v_pk_add_f32 v[20:21], v[48:49], v[52:53] op_sel:[0,1] op_sel_hi:[1,0]
	v_pk_add_f32 v[28:29], v[16:17], v[54:55] neg_lo:[0,1] neg_hi:[0,1]
	v_pk_add_f32 v[16:17], v[16:17], v[54:55]
	v_pk_add_f32 v[54:55], v[24:25], v[38:39] neg_lo:[0,1] neg_hi:[0,1]
	v_pk_add_f32 v[56:57], v[26:27], v[40:41] neg_lo:[0,1] neg_hi:[0,1]
	v_pk_add_f32 v[26:27], v[26:27], v[40:41]
	v_pk_add_f32 v[24:25], v[24:25], v[38:39]
	v_pk_add_f32 v[44:45], v[48:49], v[52:53] op_sel:[0,1] op_sel_hi:[1,0] neg_lo:[0,1] neg_hi:[0,1]
	v_mov_b32_e32 v49, v21
	v_pk_add_f32 v[38:39], v[24:25], v[26:27]
	v_pk_add_f32 v[24:25], v[24:25], v[26:27] neg_lo:[0,1] neg_hi:[0,1]
	v_pk_add_f32 v[26:27], v[54:55], v[56:57] op_sel:[0,1] op_sel_hi:[1,0]
	v_pk_add_f32 v[40:41], v[54:55], v[56:57] op_sel:[0,1] op_sel_hi:[1,0] neg_lo:[0,1] neg_hi:[0,1]
	v_mov_b32_e32 v56, v14
	v_mov_b32_e32 v21, v88
	v_pk_add_f32 v[32:33], v[50:51], v[58:59] neg_lo:[0,1] neg_hi:[0,1]
	v_pk_add_f32 v[50:51], v[50:51], v[58:59]
	s_nop 1
	v_pk_add_f32 v[34:35], v[64:65], v[34:35] neg_lo:[0,1] neg_hi:[0,1]
	v_xor_b32_e32 v57, 0x80000000, v21
	v_pk_mul_f32 v[58:59], v[56:57], v[56:57] op_sel:[0,0] op_sel_hi:[0,1]
	v_pk_add_f32 v[30:31], v[30:31], v[36:37] neg_lo:[0,1] neg_hi:[0,1]
	v_pk_fma_f32 v[58:59], v[56:57], v[56:57], v[58:59] op_sel:[1,1,0] op_sel_hi:[1,0,1] neg_lo:[1,0,0]
	v_pk_add_f32 v[52:53], v[16:17], v[50:51]
	v_pk_mul_f32 v[62:63], v[58:59], v[58:59] op_sel:[0,0] op_sel_hi:[0,1]
	v_pk_add_f32 v[36:37], v[34:35], v[30:31] op_sel:[0,1] op_sel_hi:[1,0]
	v_pk_fma_f32 v[62:63], v[58:59], v[58:59], v[62:63] op_sel:[1,1,0] op_sel_hi:[1,0,1] neg_lo:[1,0,0]
	v_pk_add_f32 v[30:31], v[34:35], v[30:31] op_sel:[0,1] op_sel_hi:[1,0] neg_lo:[0,1] neg_hi:[0,1]
	v_pk_mul_f32 v[70:71], v[62:63], v[62:63] op_sel:[0,0] op_sel_hi:[0,1]
	v_pk_mul_f32 v[64:65], v[62:63], v[56:57] op_sel:[0,0] op_sel_hi:[0,1]
	v_pk_add_f32 v[16:17], v[16:17], v[50:51] neg_lo:[0,1] neg_hi:[0,1]
	v_pk_fma_f32 v[70:71], v[62:63], v[62:63], v[70:71] op_sel:[1,1,0] op_sel_hi:[1,0,1] neg_lo:[1,0,0]
	v_mov_b32_e32 v54, v40
	v_pk_mul_f32 v[72:73], v[70:71], v[56:57] op_sel:[0,0] op_sel_hi:[0,1]
	v_mov_b32_e32 v55, v27
	v_pk_mul_f32 v[60:61], v[58:59], v[56:57] op_sel:[0,0] op_sel_hi:[0,1]
	v_pk_fma_f32 v[64:65], v[62:63], v[56:57], v[64:65] op_sel:[1,1,0] op_sel_hi:[1,0,1] neg_lo:[1,0,0]
	v_pk_fma_f32 v[72:73], v[70:71], v[56:57], v[72:73] op_sel:[1,1,0] op_sel_hi:[1,0,1] neg_lo:[1,0,0]
	v_mov_b32_e32 v27, v41
	v_pk_mul_f32 v[74:75], v[64:65], v[64:65] op_sel:[0,0] op_sel_hi:[0,1]
	v_pk_mul_f32 v[40:41], v[16:17], v[72:73] op_sel:[0,0] op_sel_hi:[0,1]
	v_mov_b32_e32 v34, v30
	v_mov_b32_e32 v35, v37
	v_pk_fma_f32 v[60:61], v[58:59], v[56:57], v[60:61] op_sel:[1,1,0] op_sel_hi:[1,0,1] neg_lo:[1,0,0]
	v_pk_fma_f32 v[74:75], v[64:65], v[64:65], v[74:75] op_sel:[1,1,0] op_sel_hi:[1,0,1] neg_lo:[1,0,0]
	v_mov_b32_e32 v37, v31
	v_pk_mul_f32 v[66:67], v[60:61], v[60:61] op_sel:[0,0] op_sel_hi:[0,1]
	v_pk_mul_f32 v[76:77], v[70:71], v[60:61] op_sel:[0,0] op_sel_hi:[0,1]
	v_pk_mul_f32 v[30:31], v[36:37], v[62:63] op_sel:[0,0] op_sel_hi:[0,1]
	v_pk_fma_f32 v[16:17], v[16:17], v[72:73], v[40:41] op_sel:[1,1,0] op_sel_hi:[1,0,1] neg_lo:[1,0,0]
	v_pk_mul_f32 v[40:41], v[18:19], v[74:75] op_sel:[0,0] op_sel_hi:[0,1]
	v_pk_mul_f32 v[68:69], v[62:63], v[60:61] op_sel:[0,0] op_sel_hi:[0,1]
	s_nop 0
	v_pk_fma_f32 v[66:67], v[60:61], v[60:61], v[66:67] op_sel:[1,1,0] op_sel_hi:[1,0,1] neg_lo:[1,0,0]
	v_pk_fma_f32 v[76:77], v[70:71], v[60:61], v[76:77] op_sel:[1,1,0] op_sel_hi:[1,0,1] neg_lo:[1,0,0]
	v_pk_fma_f32 v[30:31], v[36:37], v[62:63], v[30:31] op_sel:[1,1,0] op_sel_hi:[1,0,1] neg_lo:[1,0,0]
	v_mov_b32_e32 v21, v45
	v_pk_mul_f32 v[78:79], v[66:67], v[66:67] op_sel:[0,0] op_sel_hi:[0,1]
	v_pk_mul_f32 v[36:37], v[20:21], v[66:67] op_sel:[0,0] op_sel_hi:[0,1]
	v_pk_fma_f32 v[18:19], v[18:19], v[74:75], v[40:41] op_sel:[1,1,0] op_sel_hi:[1,0,1] neg_lo:[1,0,0]
	v_pk_mul_f32 v[40:41], v[24:25], v[76:77] op_sel:[0,0] op_sel_hi:[0,1]
	v_pk_add_f32 v[50:51], v[28:29], v[32:33] op_sel:[0,1] op_sel_hi:[1,0]
	v_pk_add_f32 v[28:29], v[28:29], v[32:33] op_sel:[0,1] op_sel_hi:[1,0] neg_lo:[0,1] neg_hi:[0,1]
	v_pk_fma_f32 v[68:69], v[62:63], v[60:61], v[68:69] op_sel:[1,1,0] op_sel_hi:[1,0,1] neg_lo:[1,0,0]
	v_pk_fma_f32 v[78:79], v[66:67], v[66:67], v[78:79] op_sel:[1,1,0] op_sel_hi:[1,0,1] neg_lo:[1,0,0]
	v_pk_mul_f32 v[80:81], v[70:71], v[64:65] op_sel:[0,0] op_sel_hi:[0,1]
	v_pk_fma_f32 v[20:21], v[20:21], v[66:67], v[36:37] op_sel:[1,1,0] op_sel_hi:[1,0,1] neg_lo:[1,0,0]
	v_pk_fma_f32 v[24:25], v[24:25], v[76:77], v[40:41] op_sel:[1,1,0] op_sel_hi:[1,0,1] neg_lo:[1,0,0]
	s_nop 0
	v_mov_b32_e32 v32, v28
	v_pk_mul_f32 v[36:37], v[26:27], v[68:69] op_sel:[0,0] op_sel_hi:[0,1]
	v_pk_mul_f32 v[40:41], v[34:35], v[78:79] op_sel:[0,0] op_sel_hi:[0,1]
	v_mov_b32_e32 v33, v51
	v_pk_fma_f32 v[80:81], v[70:71], v[64:65], v[80:81] op_sel:[1,1,0] op_sel_hi:[1,0,1] neg_lo:[1,0,0]
	v_pk_mul_f32 v[82:83], v[68:69], v[68:69] op_sel:[0,0] op_sel_hi:[0,1]
	v_pk_mul_f32 v[84:85], v[70:71], v[68:69] op_sel:[0,0] op_sel_hi:[0,1]
	v_pk_fma_f32 v[26:27], v[26:27], v[68:69], v[36:37] op_sel:[1,1,0] op_sel_hi:[1,0,1] neg_lo:[1,0,0]
	v_pk_mul_f32 v[36:37], v[42:43], v[70:71] op_sel:[0,0] op_sel_hi:[0,1]
	v_pk_fma_f32 v[34:35], v[34:35], v[78:79], v[40:41] op_sel:[1,1,0] op_sel_hi:[1,0,1] neg_lo:[1,0,0]
	s_nop 0
	v_pk_mul_f32 v[40:41], v[32:33], v[80:81] op_sel:[0,0] op_sel_hi:[0,1]
	v_mov_b32_e32 v48, v44
	v_pk_fma_f32 v[82:83], v[68:69], v[68:69], v[82:83] op_sel:[1,1,0] op_sel_hi:[1,0,1] neg_lo:[1,0,0]
	v_pk_fma_f32 v[84:85], v[70:71], v[68:69], v[84:85] op_sel:[1,1,0] op_sel_hi:[1,0,1] neg_lo:[1,0,0]
	v_pk_mul_f32 v[86:87], v[52:53], v[56:57] op_sel:[0,0] op_sel_hi:[0,1]
	v_mov_b32_e32 v51, v29
	v_pk_fma_f32 v[52:53], v[52:53], v[56:57], v[86:87] op_sel:[1,1,0] op_sel_hi:[1,0,1] neg_lo:[1,0,0]
	v_pk_mul_f32 v[56:57], v[22:23], v[58:59] op_sel:[0,0] op_sel_hi:[0,1]
	v_pk_mul_f32 v[28:29], v[50:51], v[64:65] op_sel:[0,0] op_sel_hi:[0,1]
	v_pk_fma_f32 v[36:37], v[42:43], v[70:71], v[36:37] op_sel:[1,1,0] op_sel_hi:[1,0,1] neg_lo:[1,0,0]
	v_pk_fma_f32 v[32:33], v[32:33], v[80:81], v[40:41] op_sel:[1,1,0] op_sel_hi:[1,0,1] neg_lo:[1,0,0]
	v_pk_mul_f32 v[40:41], v[48:49], v[82:83] op_sel:[0,0] op_sel_hi:[0,1]
	v_pk_mul_f32 v[42:43], v[54:55], v[84:85] op_sel:[0,0] op_sel_hi:[0,1]
	s_nop 0
	v_pk_fma_f32 v[22:23], v[22:23], v[58:59], v[56:57] op_sel:[1,1,0] op_sel_hi:[1,0,1] neg_lo:[1,0,0]
	v_pk_mul_f32 v[56:57], v[38:39], v[60:61] op_sel:[0,0] op_sel_hi:[0,1]
	v_pk_fma_f32 v[28:29], v[50:51], v[64:65], v[28:29] op_sel:[1,1,0] op_sel_hi:[1,0,1] neg_lo:[1,0,0]
	s_nop 0
	v_pk_fma_f32 v[38:39], v[38:39], v[60:61], v[56:57] op_sel:[1,1,0] op_sel_hi:[1,0,1] neg_lo:[1,0,0]
	v_pk_fma_f32 v[40:41], v[48:49], v[82:83], v[40:41] op_sel:[1,1,0] op_sel_hi:[1,0,1] neg_lo:[1,0,0]
	v_pk_fma_f32 v[42:43], v[54:55], v[84:85], v[42:43] op_sel:[1,1,0] op_sel_hi:[1,0,1] neg_lo:[1,0,0]
	ds_write2_b64 v15, v[46:47], v[52:53] offset1:68
	ds_write2_b64 v15, v[22:23], v[38:39] offset0:136 offset1:204
	ds_write2_b64 v89, v[30:31], v[28:29] offset0:16 offset1:84
	ds_write2_b64 v89, v[20:21], v[26:27] offset0:152 offset1:220
	ds_write2_b64 v90, v[36:37], v[16:17] offset0:32 offset1:100
	ds_write2_b64 v90, v[18:19], v[24:25] offset0:168 offset1:236
	ds_write2_b64 v91, v[34:35], v[32:33] offset0:48 offset1:116
	ds_write2_b64 v91, v[40:41], v[42:43] offset0:184 offset1:252
	v_ashrrev_i32_e32 v15, 4, v1
	v_lshlrev_b32_e32 v15, 3, v15
	v_lshlrev_b32_e32 v1, 3, v1
	v_add3_u32 v1, 0, v15, v1
	v_add_u32_e32 v86, 0x800, v1
	v_add_u32_e32 v87, 0x1000, v1
	ds_read2_b64 v[16:19], v1 offset1:68
	ds_read2_b64 v[20:23], v1 offset0:136 offset1:204
	ds_read2_b64 v[24:27], v86 offset0:16 offset1:84
	ds_read2_b64 v[28:31], v87 offset0:32 offset1:100
	v_add_u32_e32 v89, 0x1800, v1
	ds_read2_b64 v[32:35], v89 offset0:48 offset1:116
	ds_read2_b64 v[36:39], v86 offset0:152 offset1:220
	ds_read2_b64 v[40:43], v87 offset0:168 offset1:236
	ds_read2_b64 v[44:47], v89 offset0:184 offset1:252
	s_nop 1
	s_waitcnt lgkmcnt(3)
	v_pk_add_f32 v[50:51], v[26:27], v[34:35] neg_lo:[0,1] neg_hi:[0,1]
	v_pk_add_f32 v[48:49], v[18:19], v[30:31] neg_lo:[0,1] neg_hi:[0,1]
	v_pk_add_f32 v[18:19], v[18:19], v[30:31]
	v_pk_add_f32 v[52:53], v[48:49], v[50:51] op_sel:[0,1] op_sel_hi:[1,0]
	v_pk_add_f32 v[48:49], v[48:49], v[50:51] op_sel:[0,1] op_sel_hi:[1,0] neg_lo:[0,1] neg_hi:[0,1]
	v_mov_b32_e32 v50, v52
	v_mov_b32_e32 v51, v49
	v_mov_b32_e32 v49, v53
	s_waitcnt lgkmcnt(1)
	v_pk_add_f32 v[52:53], v[20:21], v[40:41] neg_lo:[0,1] neg_hi:[0,1]
	s_waitcnt lgkmcnt(0)
	v_pk_add_f32 v[54:55], v[36:37], v[44:45] neg_lo:[0,1] neg_hi:[0,1]
	v_pk_add_f32 v[58:59], v[38:39], v[46:47] neg_lo:[0,1] neg_hi:[0,1]
	v_pk_add_f32 v[56:57], v[52:53], v[54:55] op_sel:[0,1] op_sel_hi:[1,0]
	v_pk_add_f32 v[52:53], v[52:53], v[54:55] op_sel:[0,1] op_sel_hi:[1,0] neg_lo:[0,1] neg_hi:[0,1]
	v_mov_b32_e32 v54, v56
	v_mov_b32_e32 v55, v53
	v_mov_b32_e32 v53, v57
	v_pk_add_f32 v[56:57], v[22:23], v[42:43] neg_lo:[0,1] neg_hi:[0,1]
	v_pk_add_f32 v[26:27], v[26:27], v[34:35]
	v_pk_add_f32 v[60:61], v[56:57], v[58:59] op_sel:[0,1] op_sel_hi:[1,0]
	v_pk_add_f32 v[56:57], v[56:57], v[58:59] op_sel:[0,1] op_sel_hi:[1,0] neg_lo:[0,1] neg_hi:[0,1]
	v_pk_add_f32 v[30:31], v[18:19], v[26:27]
	v_pk_add_f32 v[18:19], v[18:19], v[26:27] neg_lo:[0,1] neg_hi:[0,1]
	v_pk_add_f32 v[20:21], v[20:21], v[40:41]
	v_pk_add_f32 v[26:27], v[36:37], v[44:45]
	v_mov_b32_e32 v58, v60
	v_mov_b32_e32 v59, v57
	v_mov_b32_e32 v57, v61
	v_pk_mul_f32 v[60:61], v[50:51], v[8:9] op_sel:[0,0] op_sel_hi:[0,1]
	v_pk_add_f32 v[34:35], v[20:21], v[26:27]
	v_pk_add_f32 v[20:21], v[20:21], v[26:27] neg_lo:[0,1] neg_hi:[0,1]
	v_pk_add_f32 v[22:23], v[22:23], v[42:43]
	v_pk_add_f32 v[26:27], v[38:39], v[46:47]
	v_pk_fma_f32 v[50:51], v[50:51], v[8:9], v[60:61] op_sel:[1,1,0] op_sel_hi:[1,0,1] neg_lo:[1,0,0]
	v_pk_mul_f32 v[60:61], v[54:55], v[4:5] op_sel:[0,0] op_sel_hi:[0,1]
	v_pk_add_f32 v[62:63], v[24:25], v[32:33]
	v_pk_add_f32 v[36:37], v[22:23], v[26:27]
	v_pk_add_f32 v[22:23], v[22:23], v[26:27] neg_lo:[0,1] neg_hi:[0,1]
	v_pk_mul_f32 v[26:27], v[18:19], v[4:5] op_sel:[0,0] op_sel_hi:[0,1]
	v_pk_fma_f32 v[54:55], v[54:55], v[4:5], v[60:61] op_sel:[1,1,0] op_sel_hi:[1,0,1] neg_lo:[1,0,0]
	v_pk_mul_f32 v[60:61], v[58:59], v[2:3] op_sel:[0,0] op_sel_hi:[0,1]
	v_pk_add_f32 v[24:25], v[24:25], v[32:33] neg_lo:[0,1] neg_hi:[0,1]
	v_pk_fma_f32 v[18:19], v[18:19], v[4:5], v[26:27] op_sel:[1,1,0] op_sel_hi:[1,0,1] neg_lo:[1,0,0]
	v_pk_mul_f32 v[26:27], v[20:21], v[10:11] op_sel:[0,0] op_sel_hi:[0,1]
	v_pk_fma_f32 v[58:59], v[58:59], v[2:3], v[60:61] op_sel:[1,1,0] op_sel_hi:[1,0,1] neg_lo:[1,0,0]
	v_pk_add_f32 v[60:61], v[16:17], v[28:29]
	v_pk_fma_f32 v[20:21], v[20:21], v[10:11], v[26:27] op_sel:[1,1,0] op_sel_hi:[1,0,1] neg_lo:[1,0,0]
	v_pk_mul_f32 v[26:27], v[22:23], v[6:7] op_sel:[0,0] op_sel_hi:[0,1]
	v_pk_add_f32 v[16:17], v[16:17], v[28:29] neg_lo:[0,1] neg_hi:[0,1]
	v_pk_fma_f32 v[22:23], v[22:23], v[6:7], v[26:27] op_sel:[1,1,0] op_sel_hi:[1,0,1] neg_lo:[1,0,0]
	v_pk_mul_f32 v[26:27], v[48:49], v[2:3] op_sel:[0,0] op_sel_hi:[0,1]
	v_pk_mul_f32 v[38:39], v[52:53], v[6:7] op_sel:[0,0] op_sel_hi:[0,1]
	v_pk_mul_f32 v[40:41], v[56:57], v[12:13] op_sel:[0,0] op_sel_hi:[0,1]
	v_pk_add_f32 v[64:65], v[60:61], v[62:63]
	v_pk_add_f32 v[28:29], v[16:17], v[24:25] op_sel:[0,1] op_sel_hi:[1,0] neg_lo:[0,1] neg_hi:[0,1]
	v_pk_add_f32 v[16:17], v[16:17], v[24:25] op_sel:[0,1] op_sel_hi:[1,0]
	v_pk_fma_f32 v[26:27], v[48:49], v[2:3], v[26:27] op_sel:[1,1,0] op_sel_hi:[1,0,1] neg_lo:[1,0,0]
	v_mov_b32_e32 v24, v28
	v_mov_b32_e32 v25, v17
	v_mov_b32_e32 v17, v29
	v_pk_fma_f32 v[38:39], v[52:53], v[6:7], v[38:39] op_sel:[1,1,0] op_sel_hi:[1,0,1] neg_lo:[1,0,0]
	v_pk_fma_f32 v[40:41], v[56:57], v[12:13], v[40:41] op_sel:[1,1,0] op_sel_hi:[1,0,1] neg_lo:[1,0,0]
	v_pk_add_f32 v[28:29], v[16:17], v[54:55] neg_lo:[0,1] neg_hi:[0,1]
	v_pk_add_f32 v[16:17], v[16:17], v[54:55]
	v_pk_add_f32 v[54:55], v[24:25], v[38:39] neg_lo:[0,1] neg_hi:[0,1]
	v_pk_add_f32 v[56:57], v[26:27], v[40:41] neg_lo:[0,1] neg_hi:[0,1]
	v_pk_add_f32 v[26:27], v[26:27], v[40:41]
	v_pk_add_f32 v[24:25], v[24:25], v[38:39]
	v_pk_add_f32 v[42:43], v[64:65], v[34:35]
	v_pk_add_f32 v[44:45], v[30:31], v[36:37]
	v_pk_add_f32 v[38:39], v[24:25], v[26:27]
	v_pk_add_f32 v[24:25], v[24:25], v[26:27] neg_lo:[0,1] neg_hi:[0,1]
	v_pk_add_f32 v[26:27], v[54:55], v[56:57] op_sel:[0,1] op_sel_hi:[1,0]
	v_pk_add_f32 v[40:41], v[54:55], v[56:57] op_sel:[0,1] op_sel_hi:[1,0] neg_lo:[0,1] neg_hi:[0,1]
	v_xor_b32_e32 v15, 0x80000000, v88
	v_pk_mul_f32 v[56:57], v[14:15], v[14:15] op_sel:[0,0] op_sel_hi:[0,1]
	v_pk_add_f32 v[46:47], v[42:43], v[44:45]
	v_pk_add_f32 v[42:43], v[42:43], v[44:45] neg_lo:[0,1] neg_hi:[0,1]
	v_pk_add_f32 v[44:45], v[60:61], v[62:63] neg_lo:[0,1] neg_hi:[0,1]
	v_pk_fma_f32 v[56:57], v[14:15], v[14:15], v[56:57] op_sel:[1,1,0] op_sel_hi:[1,0,1] neg_lo:[1,0,0]
	v_pk_add_f32 v[34:35], v[64:65], v[34:35] neg_lo:[0,1] neg_hi:[0,1]
	v_pk_mul_f32 v[60:61], v[56:57], v[56:57] op_sel:[0,0] op_sel_hi:[0,1]
	v_pk_add_f32 v[30:31], v[30:31], v[36:37] neg_lo:[0,1] neg_hi:[0,1]
	v_pk_fma_f32 v[60:61], v[56:57], v[56:57], v[60:61] op_sel:[1,1,0] op_sel_hi:[1,0,1] neg_lo:[1,0,0]
	v_pk_add_f32 v[48:49], v[44:45], v[20:21] neg_lo:[0,1] neg_hi:[0,1]
	v_pk_mul_f32 v[68:69], v[60:61], v[60:61] op_sel:[0,0] op_sel_hi:[0,1]
	v_pk_add_f32 v[52:53], v[18:19], v[22:23] neg_lo:[0,1] neg_hi:[0,1]
	v_pk_add_f32 v[18:19], v[18:19], v[22:23]
	v_pk_add_f32 v[20:21], v[44:45], v[20:21]
	v_pk_add_f32 v[32:33], v[50:51], v[58:59] neg_lo:[0,1] neg_hi:[0,1]
	v_pk_add_f32 v[50:51], v[50:51], v[58:59]
	v_pk_mul_f32 v[62:63], v[60:61], v[14:15] op_sel:[0,0] op_sel_hi:[0,1]
	v_pk_fma_f32 v[68:69], v[60:61], v[60:61], v[68:69] op_sel:[1,1,0] op_sel_hi:[1,0,1] neg_lo:[1,0,0]
	v_pk_add_f32 v[36:37], v[34:35], v[30:31] op_sel:[0,1] op_sel_hi:[1,0]
	v_pk_mul_f32 v[70:71], v[68:69], v[14:15] op_sel:[0,0] op_sel_hi:[0,1]
	v_pk_add_f32 v[30:31], v[34:35], v[30:31] op_sel:[0,1] op_sel_hi:[1,0] neg_lo:[0,1] neg_hi:[0,1]
	v_pk_add_f32 v[22:23], v[20:21], v[18:19]
	v_pk_add_f32 v[18:19], v[20:21], v[18:19] neg_lo:[0,1] neg_hi:[0,1]
	v_pk_add_f32 v[20:21], v[48:49], v[52:53] op_sel:[0,1] op_sel_hi:[1,0]
	v_pk_add_f32 v[44:45], v[48:49], v[52:53] op_sel:[0,1] op_sel_hi:[1,0] neg_lo:[0,1] neg_hi:[0,1]
	v_pk_add_f32 v[52:53], v[16:17], v[50:51]
	v_pk_add_f32 v[16:17], v[16:17], v[50:51] neg_lo:[0,1] neg_hi:[0,1]
	v_mov_b32_e32 v54, v40
	v_mov_b32_e32 v55, v27
	v_pk_mul_f32 v[58:59], v[56:57], v[14:15] op_sel:[0,0] op_sel_hi:[0,1]
	v_pk_fma_f32 v[62:63], v[60:61], v[14:15], v[62:63] op_sel:[1,1,0] op_sel_hi:[1,0,1] neg_lo:[1,0,0]
	v_pk_fma_f32 v[70:71], v[68:69], v[14:15], v[70:71] op_sel:[1,1,0] op_sel_hi:[1,0,1] neg_lo:[1,0,0]
	v_mov_b32_e32 v27, v41
	v_pk_mul_f32 v[72:73], v[62:63], v[62:63] op_sel:[0,0] op_sel_hi:[0,1]
	v_pk_mul_f32 v[40:41], v[16:17], v[70:71] op_sel:[0,0] op_sel_hi:[0,1]
	v_mov_b32_e32 v34, v30
	v_mov_b32_e32 v35, v37
	v_pk_fma_f32 v[58:59], v[56:57], v[14:15], v[58:59] op_sel:[1,1,0] op_sel_hi:[1,0,1] neg_lo:[1,0,0]
	v_pk_fma_f32 v[72:73], v[62:63], v[62:63], v[72:73] op_sel:[1,1,0] op_sel_hi:[1,0,1] neg_lo:[1,0,0]
	v_mov_b32_e32 v37, v31
	v_pk_mul_f32 v[64:65], v[58:59], v[58:59] op_sel:[0,0] op_sel_hi:[0,1]
	v_pk_mul_f32 v[74:75], v[68:69], v[58:59] op_sel:[0,0] op_sel_hi:[0,1]
	v_pk_mul_f32 v[30:31], v[36:37], v[60:61] op_sel:[0,0] op_sel_hi:[0,1]
	v_pk_fma_f32 v[16:17], v[16:17], v[70:71], v[40:41] op_sel:[1,1,0] op_sel_hi:[1,0,1] neg_lo:[1,0,0]
	v_pk_mul_f32 v[40:41], v[18:19], v[72:73] op_sel:[0,0] op_sel_hi:[0,1]
	v_mov_b32_e32 v49, v21
	v_pk_fma_f32 v[64:65], v[58:59], v[58:59], v[64:65] op_sel:[1,1,0] op_sel_hi:[1,0,1] neg_lo:[1,0,0]
	v_pk_mul_f32 v[66:67], v[60:61], v[58:59] op_sel:[0,0] op_sel_hi:[0,1]
	v_pk_fma_f32 v[74:75], v[68:69], v[58:59], v[74:75] op_sel:[1,1,0] op_sel_hi:[1,0,1] neg_lo:[1,0,0]
	v_pk_fma_f32 v[30:31], v[36:37], v[60:61], v[30:31] op_sel:[1,1,0] op_sel_hi:[1,0,1] neg_lo:[1,0,0]
	v_mov_b32_e32 v21, v45
	v_pk_mul_f32 v[76:77], v[64:65], v[64:65] op_sel:[0,0] op_sel_hi:[0,1]
	v_pk_mul_f32 v[36:37], v[20:21], v[64:65] op_sel:[0,0] op_sel_hi:[0,1]
	v_pk_fma_f32 v[18:19], v[18:19], v[72:73], v[40:41] op_sel:[1,1,0] op_sel_hi:[1,0,1] neg_lo:[1,0,0]
	v_pk_mul_f32 v[40:41], v[24:25], v[74:75] op_sel:[0,0] op_sel_hi:[0,1]
	v_pk_add_f32 v[50:51], v[28:29], v[32:33] op_sel:[0,1] op_sel_hi:[1,0]
	v_pk_add_f32 v[28:29], v[28:29], v[32:33] op_sel:[0,1] op_sel_hi:[1,0] neg_lo:[0,1] neg_hi:[0,1]
	v_pk_fma_f32 v[66:67], v[60:61], v[58:59], v[66:67] op_sel:[1,1,0] op_sel_hi:[1,0,1] neg_lo:[1,0,0]
	v_pk_fma_f32 v[76:77], v[64:65], v[64:65], v[76:77] op_sel:[1,1,0] op_sel_hi:[1,0,1] neg_lo:[1,0,0]
	v_pk_mul_f32 v[78:79], v[68:69], v[62:63] op_sel:[0,0] op_sel_hi:[0,1]
	v_pk_fma_f32 v[20:21], v[20:21], v[64:65], v[36:37] op_sel:[1,1,0] op_sel_hi:[1,0,1] neg_lo:[1,0,0]
	v_pk_fma_f32 v[24:25], v[24:25], v[74:75], v[40:41] op_sel:[1,1,0] op_sel_hi:[1,0,1] neg_lo:[1,0,0]
	s_nop 0
	v_mov_b32_e32 v32, v28
	v_pk_mul_f32 v[36:37], v[26:27], v[66:67] op_sel:[0,0] op_sel_hi:[0,1]
	v_pk_mul_f32 v[40:41], v[34:35], v[76:77] op_sel:[0,0] op_sel_hi:[0,1]
	v_mov_b32_e32 v33, v51
	v_pk_fma_f32 v[78:79], v[68:69], v[62:63], v[78:79] op_sel:[1,1,0] op_sel_hi:[1,0,1] neg_lo:[1,0,0]
	v_pk_mul_f32 v[80:81], v[66:67], v[66:67] op_sel:[0,0] op_sel_hi:[0,1]
	v_pk_mul_f32 v[82:83], v[68:69], v[66:67] op_sel:[0,0] op_sel_hi:[0,1]
	v_pk_fma_f32 v[26:27], v[26:27], v[66:67], v[36:37] op_sel:[1,1,0] op_sel_hi:[1,0,1] neg_lo:[1,0,0]
	v_pk_mul_f32 v[36:37], v[42:43], v[68:69] op_sel:[0,0] op_sel_hi:[0,1]
	v_pk_fma_f32 v[34:35], v[34:35], v[76:77], v[40:41] op_sel:[1,1,0] op_sel_hi:[1,0,1] neg_lo:[1,0,0]
	s_nop 0
	v_pk_mul_f32 v[40:41], v[32:33], v[78:79] op_sel:[0,0] op_sel_hi:[0,1]
	v_mov_b32_e32 v48, v44
	v_pk_fma_f32 v[80:81], v[66:67], v[66:67], v[80:81] op_sel:[1,1,0] op_sel_hi:[1,0,1] neg_lo:[1,0,0]
	v_pk_fma_f32 v[82:83], v[68:69], v[66:67], v[82:83] op_sel:[1,1,0] op_sel_hi:[1,0,1] neg_lo:[1,0,0]
	v_pk_mul_f32 v[84:85], v[52:53], v[14:15] op_sel:[0,0] op_sel_hi:[0,1]
	v_mov_b32_e32 v51, v29
	v_pk_fma_f32 v[14:15], v[52:53], v[14:15], v[84:85] op_sel:[1,1,0] op_sel_hi:[1,0,1] neg_lo:[1,0,0]
	v_pk_mul_f32 v[52:53], v[22:23], v[56:57] op_sel:[0,0] op_sel_hi:[0,1]
	v_pk_mul_f32 v[28:29], v[50:51], v[62:63] op_sel:[0,0] op_sel_hi:[0,1]
	v_pk_fma_f32 v[36:37], v[42:43], v[68:69], v[36:37] op_sel:[1,1,0] op_sel_hi:[1,0,1] neg_lo:[1,0,0]
	v_pk_fma_f32 v[32:33], v[32:33], v[78:79], v[40:41] op_sel:[1,1,0] op_sel_hi:[1,0,1] neg_lo:[1,0,0]
	v_pk_mul_f32 v[40:41], v[48:49], v[80:81] op_sel:[0,0] op_sel_hi:[0,1]
	v_pk_mul_f32 v[42:43], v[54:55], v[82:83] op_sel:[0,0] op_sel_hi:[0,1]
	s_nop 0
	v_pk_fma_f32 v[22:23], v[22:23], v[56:57], v[52:53] op_sel:[1,1,0] op_sel_hi:[1,0,1] neg_lo:[1,0,0]
	v_pk_mul_f32 v[52:53], v[38:39], v[58:59] op_sel:[0,0] op_sel_hi:[0,1]
	v_pk_fma_f32 v[28:29], v[50:51], v[62:63], v[28:29] op_sel:[1,1,0] op_sel_hi:[1,0,1] neg_lo:[1,0,0]
	s_nop 0
	v_pk_fma_f32 v[38:39], v[38:39], v[58:59], v[52:53] op_sel:[1,1,0] op_sel_hi:[1,0,1] neg_lo:[1,0,0]
	v_pk_fma_f32 v[40:41], v[48:49], v[80:81], v[40:41] op_sel:[1,1,0] op_sel_hi:[1,0,1] neg_lo:[1,0,0]
	v_pk_fma_f32 v[42:43], v[54:55], v[82:83], v[42:43] op_sel:[1,1,0] op_sel_hi:[1,0,1] neg_lo:[1,0,0]
	ds_write2_b64 v1, v[46:47], v[14:15] offset1:68
	ds_write2_b64 v1, v[22:23], v[38:39] offset0:136 offset1:204
	ds_write2_b64 v86, v[30:31], v[28:29] offset0:16 offset1:84
	ds_write2_b64 v86, v[20:21], v[26:27] offset0:152 offset1:220
	ds_write2_b64 v87, v[36:37], v[16:17] offset0:32 offset1:100
	ds_write2_b64 v87, v[18:19], v[24:25] offset0:168 offset1:236
	ds_write2_b64 v89, v[34:35], v[32:33] offset0:48 offset1:116
	ds_write2_b64 v89, v[40:41], v[42:43] offset0:184 offset1:252
	v_mov_b32_e32 v1, v0
	s_waitcnt lgkmcnt(0)
	s_barrier
	s_nop 0
	v_and_b32_e32 v15, 3, v1
	v_lshlrev_b32_e32 v1, 4, v1
	v_cvt_f32_ubyte0_e32 v14, v15
	v_mul_f32_e32 v16, 0x3c800000, v14
	v_and_b32_e32 v1, 0xffffffc0, v1
	v_cos_f32_e32 v14, v16
	v_sin_f32_e32 v88, v16
	v_ashrrev_i32_e32 v16, 1, v1
	v_add_u32_e32 v16, 0, v16
	v_lshlrev_b32_e32 v17, 3, v1
	v_lshlrev_b32_e32 v15, 3, v15
	v_add3_u32 v89, v16, v17, v15
	ds_read2_b64 v[16:19], v89 offset1:4
	ds_read2_b64 v[20:23], v89 offset0:8 offset1:12
	ds_read2_b64 v[24:27], v89 offset0:17 offset1:21
	ds_read2_b64 v[28:31], v89 offset0:34 offset1:38
	ds_read2_b64 v[32:35], v89 offset0:51 offset1:55
	ds_read2_b64 v[36:39], v89 offset0:25 offset1:29
	ds_read2_b64 v[40:43], v89 offset0:42 offset1:46
	ds_read2_b64 v[44:47], v89 offset0:59 offset1:63
	s_waitcnt lgkmcnt(4)
	v_pk_add_f32 v[48:49], v[18:19], v[30:31] neg_lo:[0,1] neg_hi:[0,1]
	s_waitcnt lgkmcnt(3)
	v_pk_add_f32 v[50:51], v[26:27], v[34:35] neg_lo:[0,1] neg_hi:[0,1]
	v_pk_add_f32 v[18:19], v[18:19], v[30:31]
	v_pk_add_f32 v[52:53], v[48:49], v[50:51] op_sel:[0,1] op_sel_hi:[1,0]
	v_pk_add_f32 v[48:49], v[48:49], v[50:51] op_sel:[0,1] op_sel_hi:[1,0] neg_lo:[0,1] neg_hi:[0,1]
	v_mov_b32_e32 v50, v52
	v_mov_b32_e32 v51, v49
	v_mov_b32_e32 v49, v53
	s_waitcnt lgkmcnt(1)
	v_pk_add_f32 v[52:53], v[20:21], v[40:41] neg_lo:[0,1] neg_hi:[0,1]
	s_waitcnt lgkmcnt(0)
	v_pk_add_f32 v[54:55], v[36:37], v[44:45] neg_lo:[0,1] neg_hi:[0,1]
	v_pk_add_f32 v[58:59], v[38:39], v[46:47] neg_lo:[0,1] neg_hi:[0,1]
	v_pk_add_f32 v[56:57], v[52:53], v[54:55] op_sel:[0,1] op_sel_hi:[1,0]
	v_pk_add_f32 v[52:53], v[52:53], v[54:55] op_sel:[0,1] op_sel_hi:[1,0] neg_lo:[0,1] neg_hi:[0,1]
	v_mov_b32_e32 v54, v56
	v_mov_b32_e32 v55, v53
	v_mov_b32_e32 v53, v57
	v_pk_add_f32 v[56:57], v[22:23], v[42:43] neg_lo:[0,1] neg_hi:[0,1]
	v_pk_add_f32 v[26:27], v[26:27], v[34:35]
	v_pk_add_f32 v[60:61], v[56:57], v[58:59] op_sel:[0,1] op_sel_hi:[1,0]
	v_pk_add_f32 v[56:57], v[56:57], v[58:59] op_sel:[0,1] op_sel_hi:[1,0] neg_lo:[0,1] neg_hi:[0,1]
	v_mov_b32_e32 v58, v60
	v_mov_b32_e32 v59, v57
	v_mov_b32_e32 v57, v61
	v_pk_mul_f32 v[60:61], v[50:51], v[8:9] op_sel:[0,0] op_sel_hi:[0,1]
	v_pk_add_f32 v[30:31], v[18:19], v[26:27]
	v_pk_fma_f32 v[50:51], v[50:51], v[8:9], v[60:61] op_sel:[1,1,0] op_sel_hi:[1,0,1] neg_lo:[1,0,0]
	v_pk_mul_f32 v[60:61], v[54:55], v[4:5] op_sel:[0,0] op_sel_hi:[0,1]
	v_pk_add_f32 v[18:19], v[18:19], v[26:27] neg_lo:[0,1] neg_hi:[0,1]
	v_pk_add_f32 v[20:21], v[20:21], v[40:41]
	v_pk_add_f32 v[26:27], v[36:37], v[44:45]
	v_pk_fma_f32 v[54:55], v[54:55], v[4:5], v[60:61] op_sel:[1,1,0] op_sel_hi:[1,0,1] neg_lo:[1,0,0]
	v_pk_mul_f32 v[60:61], v[58:59], v[2:3] op_sel:[0,0] op_sel_hi:[0,1]
	v_pk_add_f32 v[22:23], v[22:23], v[42:43]
	v_pk_add_f32 v[34:35], v[20:21], v[26:27]
	v_pk_add_f32 v[20:21], v[20:21], v[26:27] neg_lo:[0,1] neg_hi:[0,1]
	v_pk_add_f32 v[26:27], v[38:39], v[46:47]
	v_pk_fma_f32 v[58:59], v[58:59], v[2:3], v[60:61] op_sel:[1,1,0] op_sel_hi:[1,0,1] neg_lo:[1,0,0]
	v_pk_add_f32 v[60:61], v[16:17], v[28:29]
	v_pk_add_f32 v[62:63], v[24:25], v[32:33]
	v_pk_add_f32 v[36:37], v[22:23], v[26:27]
	v_pk_add_f32 v[22:23], v[22:23], v[26:27] neg_lo:[0,1] neg_hi:[0,1]
	v_pk_mul_f32 v[26:27], v[18:19], v[4:5] op_sel:[0,0] op_sel_hi:[0,1]
	v_pk_add_f32 v[64:65], v[60:61], v[62:63]
	v_pk_fma_f32 v[18:19], v[18:19], v[4:5], v[26:27] op_sel:[1,1,0] op_sel_hi:[1,0,1] neg_lo:[1,0,0]
	v_pk_mul_f32 v[26:27], v[20:21], v[10:11] op_sel:[0,0] op_sel_hi:[0,1]
	v_pk_add_f32 v[44:45], v[30:31], v[36:37]
	v_pk_fma_f32 v[20:21], v[20:21], v[10:11], v[26:27] op_sel:[1,1,0] op_sel_hi:[1,0,1] neg_lo:[1,0,0]
	v_pk_mul_f32 v[26:27], v[22:23], v[6:7] op_sel:[0,0] op_sel_hi:[0,1]
	v_pk_add_f32 v[42:43], v[64:65], v[34:35]
	v_pk_add_f32 v[16:17], v[16:17], v[28:29] neg_lo:[0,1] neg_hi:[0,1]
	v_pk_add_f32 v[24:25], v[24:25], v[32:33] neg_lo:[0,1] neg_hi:[0,1]
	v_pk_fma_f32 v[22:23], v[22:23], v[6:7], v[26:27] op_sel:[1,1,0] op_sel_hi:[1,0,1] neg_lo:[1,0,0]
	v_pk_mul_f32 v[26:27], v[48:49], v[2:3] op_sel:[0,0] op_sel_hi:[0,1]
	v_pk_mul_f32 v[38:39], v[52:53], v[6:7] op_sel:[0,0] op_sel_hi:[0,1]
	v_pk_add_f32 v[46:47], v[42:43], v[44:45]
	v_pk_add_f32 v[42:43], v[42:43], v[44:45] neg_lo:[0,1] neg_hi:[0,1]
	v_pk_add_f32 v[44:45], v[60:61], v[62:63] neg_lo:[0,1] neg_hi:[0,1]
	v_pk_add_f32 v[28:29], v[16:17], v[24:25] op_sel:[0,1] op_sel_hi:[1,0] neg_lo:[0,1] neg_hi:[0,1]
	v_pk_add_f32 v[16:17], v[16:17], v[24:25] op_sel:[0,1] op_sel_hi:[1,0]
	v_pk_fma_f32 v[26:27], v[48:49], v[2:3], v[26:27] op_sel:[1,1,0] op_sel_hi:[1,0,1] neg_lo:[1,0,0]
	v_pk_fma_f32 v[38:39], v[52:53], v[6:7], v[38:39] op_sel:[1,1,0] op_sel_hi:[1,0,1] neg_lo:[1,0,0]
	v_pk_mul_f32 v[40:41], v[56:57], v[12:13] op_sel:[0,0] op_sel_hi:[0,1]
	v_pk_add_f32 v[48:49], v[44:45], v[20:21] neg_lo:[0,1] neg_hi:[0,1]
	v_pk_add_f32 v[52:53], v[18:19], v[22:23] neg_lo:[0,1] neg_hi:[0,1]
	v_pk_add_f32 v[18:19], v[18:19], v[22:23]
	v_pk_add_f32 v[20:21], v[44:45], v[20:21]
	v_mov_b32_e32 v24, v28
	v_mov_b32_e32 v25, v17
	v_mov_b32_e32 v17, v29
	v_pk_fma_f32 v[40:41], v[56:57], v[12:13], v[40:41] op_sel:[1,1,0] op_sel_hi:[1,0,1] neg_lo:[1,0,0]
	v_pk_add_f32 v[22:23], v[20:21], v[18:19]
	v_pk_add_f32 v[18:19], v[20:21], v[18:19] neg_lo:[0,1] neg_hi:[0,1]
	v_pk_add_f32 v[20:21], v[48:49], v[52:53] op_sel:[0,1] op_sel_hi:[1,0]
	v_pk_add_f32 v[28:29], v[16:17], v[54:55] neg_lo:[0,1] neg_hi:[0,1]
	v_pk_add_f32 v[16:17], v[16:17], v[54:55]
	v_pk_add_f32 v[54:55], v[24:25], v[38:39] neg_lo:[0,1] neg_hi:[0,1]
	v_pk_add_f32 v[56:57], v[26:27], v[40:41] neg_lo:[0,1] neg_hi:[0,1]
	v_pk_add_f32 v[26:27], v[26:27], v[40:41]
	v_pk_add_f32 v[24:25], v[24:25], v[38:39]
	v_pk_add_f32 v[44:45], v[48:49], v[52:53] op_sel:[0,1] op_sel_hi:[1,0] neg_lo:[0,1] neg_hi:[0,1]
	v_mov_b32_e32 v49, v21
	v_pk_add_f32 v[38:39], v[24:25], v[26:27]
	v_pk_add_f32 v[24:25], v[24:25], v[26:27] neg_lo:[0,1] neg_hi:[0,1]
	v_pk_add_f32 v[26:27], v[54:55], v[56:57] op_sel:[0,1] op_sel_hi:[1,0]
	v_pk_add_f32 v[40:41], v[54:55], v[56:57] op_sel:[0,1] op_sel_hi:[1,0] neg_lo:[0,1] neg_hi:[0,1]
	v_mov_b32_e32 v56, v14
	v_mov_b32_e32 v21, v88
	v_pk_add_f32 v[32:33], v[50:51], v[58:59] neg_lo:[0,1] neg_hi:[0,1]
	v_pk_add_f32 v[50:51], v[50:51], v[58:59]
	s_nop 1
	v_pk_add_f32 v[34:35], v[64:65], v[34:35] neg_lo:[0,1] neg_hi:[0,1]
	v_xor_b32_e32 v57, 0x80000000, v21
	v_pk_mul_f32 v[58:59], v[56:57], v[56:57] op_sel:[0,0] op_sel_hi:[0,1]
	v_pk_add_f32 v[30:31], v[30:31], v[36:37] neg_lo:[0,1] neg_hi:[0,1]
	v_pk_fma_f32 v[58:59], v[56:57], v[56:57], v[58:59] op_sel:[1,1,0] op_sel_hi:[1,0,1] neg_lo:[1,0,0]
	v_pk_add_f32 v[52:53], v[16:17], v[50:51]
	v_pk_mul_f32 v[62:63], v[58:59], v[58:59] op_sel:[0,0] op_sel_hi:[0,1]
	v_pk_add_f32 v[36:37], v[34:35], v[30:31] op_sel:[0,1] op_sel_hi:[1,0]
	v_pk_fma_f32 v[62:63], v[58:59], v[58:59], v[62:63] op_sel:[1,1,0] op_sel_hi:[1,0,1] neg_lo:[1,0,0]
	v_pk_add_f32 v[30:31], v[34:35], v[30:31] op_sel:[0,1] op_sel_hi:[1,0] neg_lo:[0,1] neg_hi:[0,1]
	v_pk_mul_f32 v[70:71], v[62:63], v[62:63] op_sel:[0,0] op_sel_hi:[0,1]
	v_pk_mul_f32 v[64:65], v[62:63], v[56:57] op_sel:[0,0] op_sel_hi:[0,1]
	v_pk_add_f32 v[16:17], v[16:17], v[50:51] neg_lo:[0,1] neg_hi:[0,1]
	v_pk_fma_f32 v[70:71], v[62:63], v[62:63], v[70:71] op_sel:[1,1,0] op_sel_hi:[1,0,1] neg_lo:[1,0,0]
	v_mov_b32_e32 v54, v40
	v_pk_mul_f32 v[72:73], v[70:71], v[56:57] op_sel:[0,0] op_sel_hi:[0,1]
	v_mov_b32_e32 v55, v27
	v_pk_mul_f32 v[60:61], v[58:59], v[56:57] op_sel:[0,0] op_sel_hi:[0,1]
	v_pk_fma_f32 v[64:65], v[62:63], v[56:57], v[64:65] op_sel:[1,1,0] op_sel_hi:[1,0,1] neg_lo:[1,0,0]
	v_pk_fma_f32 v[72:73], v[70:71], v[56:57], v[72:73] op_sel:[1,1,0] op_sel_hi:[1,0,1] neg_lo:[1,0,0]
	v_mov_b32_e32 v27, v41
	v_pk_mul_f32 v[74:75], v[64:65], v[64:65] op_sel:[0,0] op_sel_hi:[0,1]
	v_pk_mul_f32 v[40:41], v[16:17], v[72:73] op_sel:[0,0] op_sel_hi:[0,1]
	v_mov_b32_e32 v34, v30
	v_mov_b32_e32 v35, v37
	v_pk_fma_f32 v[60:61], v[58:59], v[56:57], v[60:61] op_sel:[1,1,0] op_sel_hi:[1,0,1] neg_lo:[1,0,0]
	v_pk_fma_f32 v[74:75], v[64:65], v[64:65], v[74:75] op_sel:[1,1,0] op_sel_hi:[1,0,1] neg_lo:[1,0,0]
	v_mov_b32_e32 v37, v31
	v_pk_mul_f32 v[66:67], v[60:61], v[60:61] op_sel:[0,0] op_sel_hi:[0,1]
	v_pk_mul_f32 v[76:77], v[70:71], v[60:61] op_sel:[0,0] op_sel_hi:[0,1]
	v_pk_mul_f32 v[30:31], v[36:37], v[62:63] op_sel:[0,0] op_sel_hi:[0,1]
	v_pk_fma_f32 v[16:17], v[16:17], v[72:73], v[40:41] op_sel:[1,1,0] op_sel_hi:[1,0,1] neg_lo:[1,0,0]
	v_pk_mul_f32 v[40:41], v[18:19], v[74:75] op_sel:[0,0] op_sel_hi:[0,1]
	v_pk_mul_f32 v[68:69], v[62:63], v[60:61] op_sel:[0,0] op_sel_hi:[0,1]
	s_nop 0
	v_pk_fma_f32 v[66:67], v[60:61], v[60:61], v[66:67] op_sel:[1,1,0] op_sel_hi:[1,0,1] neg_lo:[1,0,0]
	v_pk_fma_f32 v[76:77], v[70:71], v[60:61], v[76:77] op_sel:[1,1,0] op_sel_hi:[1,0,1] neg_lo:[1,0,0]
	v_pk_fma_f32 v[30:31], v[36:37], v[62:63], v[30:31] op_sel:[1,1,0] op_sel_hi:[1,0,1] neg_lo:[1,0,0]
	v_mov_b32_e32 v21, v45
	v_pk_mul_f32 v[78:79], v[66:67], v[66:67] op_sel:[0,0] op_sel_hi:[0,1]
	v_pk_mul_f32 v[36:37], v[20:21], v[66:67] op_sel:[0,0] op_sel_hi:[0,1]
	v_pk_fma_f32 v[18:19], v[18:19], v[74:75], v[40:41] op_sel:[1,1,0] op_sel_hi:[1,0,1] neg_lo:[1,0,0]
	v_pk_mul_f32 v[40:41], v[24:25], v[76:77] op_sel:[0,0] op_sel_hi:[0,1]
	v_pk_add_f32 v[50:51], v[28:29], v[32:33] op_sel:[0,1] op_sel_hi:[1,0]
	v_pk_add_f32 v[28:29], v[28:29], v[32:33] op_sel:[0,1] op_sel_hi:[1,0] neg_lo:[0,1] neg_hi:[0,1]
	v_pk_fma_f32 v[68:69], v[62:63], v[60:61], v[68:69] op_sel:[1,1,0] op_sel_hi:[1,0,1] neg_lo:[1,0,0]
	v_pk_fma_f32 v[78:79], v[66:67], v[66:67], v[78:79] op_sel:[1,1,0] op_sel_hi:[1,0,1] neg_lo:[1,0,0]
	v_pk_mul_f32 v[80:81], v[70:71], v[64:65] op_sel:[0,0] op_sel_hi:[0,1]
	v_pk_fma_f32 v[20:21], v[20:21], v[66:67], v[36:37] op_sel:[1,1,0] op_sel_hi:[1,0,1] neg_lo:[1,0,0]
	v_pk_fma_f32 v[24:25], v[24:25], v[76:77], v[40:41] op_sel:[1,1,0] op_sel_hi:[1,0,1] neg_lo:[1,0,0]
	s_nop 0
	v_mov_b32_e32 v32, v28
	v_pk_mul_f32 v[36:37], v[26:27], v[68:69] op_sel:[0,0] op_sel_hi:[0,1]
	v_pk_mul_f32 v[40:41], v[34:35], v[78:79] op_sel:[0,0] op_sel_hi:[0,1]
	v_mov_b32_e32 v33, v51
	v_pk_fma_f32 v[80:81], v[70:71], v[64:65], v[80:81] op_sel:[1,1,0] op_sel_hi:[1,0,1] neg_lo:[1,0,0]
	v_pk_mul_f32 v[82:83], v[68:69], v[68:69] op_sel:[0,0] op_sel_hi:[0,1]
	v_pk_mul_f32 v[84:85], v[70:71], v[68:69] op_sel:[0,0] op_sel_hi:[0,1]
	v_pk_fma_f32 v[26:27], v[26:27], v[68:69], v[36:37] op_sel:[1,1,0] op_sel_hi:[1,0,1] neg_lo:[1,0,0]
	v_pk_mul_f32 v[36:37], v[42:43], v[70:71] op_sel:[0,0] op_sel_hi:[0,1]
	v_pk_fma_f32 v[34:35], v[34:35], v[78:79], v[40:41] op_sel:[1,1,0] op_sel_hi:[1,0,1] neg_lo:[1,0,0]
	s_nop 0
	v_pk_mul_f32 v[40:41], v[32:33], v[80:81] op_sel:[0,0] op_sel_hi:[0,1]
	v_mov_b32_e32 v48, v44
	v_pk_fma_f32 v[82:83], v[68:69], v[68:69], v[82:83] op_sel:[1,1,0] op_sel_hi:[1,0,1] neg_lo:[1,0,0]
	v_pk_fma_f32 v[84:85], v[70:71], v[68:69], v[84:85] op_sel:[1,1,0] op_sel_hi:[1,0,1] neg_lo:[1,0,0]
	v_pk_mul_f32 v[86:87], v[52:53], v[56:57] op_sel:[0,0] op_sel_hi:[0,1]
	v_mov_b32_e32 v51, v29
	v_pk_fma_f32 v[52:53], v[52:53], v[56:57], v[86:87] op_sel:[1,1,0] op_sel_hi:[1,0,1] neg_lo:[1,0,0]
	v_pk_mul_f32 v[56:57], v[22:23], v[58:59] op_sel:[0,0] op_sel_hi:[0,1]
	v_pk_mul_f32 v[28:29], v[50:51], v[64:65] op_sel:[0,0] op_sel_hi:[0,1]
	v_pk_fma_f32 v[36:37], v[42:43], v[70:71], v[36:37] op_sel:[1,1,0] op_sel_hi:[1,0,1] neg_lo:[1,0,0]
	v_pk_fma_f32 v[32:33], v[32:33], v[80:81], v[40:41] op_sel:[1,1,0] op_sel_hi:[1,0,1] neg_lo:[1,0,0]
	v_pk_mul_f32 v[40:41], v[48:49], v[82:83] op_sel:[0,0] op_sel_hi:[0,1]
	v_pk_mul_f32 v[42:43], v[54:55], v[84:85] op_sel:[0,0] op_sel_hi:[0,1]
	v_add_u32_e32 v1, 0x2000, v1
	v_pk_fma_f32 v[22:23], v[22:23], v[58:59], v[56:57] op_sel:[1,1,0] op_sel_hi:[1,0,1] neg_lo:[1,0,0]
	v_pk_mul_f32 v[56:57], v[38:39], v[60:61] op_sel:[0,0] op_sel_hi:[0,1]
	v_pk_fma_f32 v[28:29], v[50:51], v[64:65], v[28:29] op_sel:[1,1,0] op_sel_hi:[1,0,1] neg_lo:[1,0,0]
	v_pk_fma_f32 v[40:41], v[48:49], v[82:83], v[40:41] op_sel:[1,1,0] op_sel_hi:[1,0,1] neg_lo:[1,0,0]
	v_pk_fma_f32 v[42:43], v[54:55], v[84:85], v[42:43] op_sel:[1,1,0] op_sel_hi:[1,0,1] neg_lo:[1,0,0]
	s_nop 0
	v_pk_fma_f32 v[38:39], v[38:39], v[60:61], v[56:57] op_sel:[1,1,0] op_sel_hi:[1,0,1] neg_lo:[1,0,0]
	ds_write2_b64 v89, v[46:47], v[52:53] offset1:4
	ds_write2_b64 v89, v[22:23], v[38:39] offset0:8 offset1:12
	ds_write2_b64 v89, v[30:31], v[28:29] offset0:17 offset1:21
	ds_write2_b64 v89, v[20:21], v[26:27] offset0:25 offset1:29
	ds_write2_b64 v89, v[36:37], v[16:17] offset0:34 offset1:38
	ds_write2_b64 v89, v[18:19], v[24:25] offset0:42 offset1:46
	ds_write2_b64 v89, v[34:35], v[32:33] offset0:51 offset1:55
	ds_write2_b64 v89, v[40:41], v[42:43] offset0:59 offset1:63
	v_ashrrev_i32_e32 v16, 1, v1
	v_add_u32_e32 v16, 0, v16
	v_lshlrev_b32_e32 v1, 3, v1
	v_add3_u32 v1, v16, v1, v15
	ds_read2_b64 v[16:19], v1 offset1:4
	ds_read2_b64 v[20:23], v1 offset0:8 offset1:12
	ds_read2_b64 v[24:27], v1 offset0:17 offset1:21
	ds_read2_b64 v[28:31], v1 offset0:34 offset1:38
	ds_read2_b64 v[32:35], v1 offset0:51 offset1:55
	ds_read2_b64 v[36:39], v1 offset0:25 offset1:29
	ds_read2_b64 v[40:43], v1 offset0:42 offset1:46
	ds_read2_b64 v[44:47], v1 offset0:59 offset1:63
	s_waitcnt lgkmcnt(4)
	v_pk_add_f32 v[48:49], v[18:19], v[30:31] neg_lo:[0,1] neg_hi:[0,1]
	s_waitcnt lgkmcnt(3)
	v_pk_add_f32 v[50:51], v[26:27], v[34:35] neg_lo:[0,1] neg_hi:[0,1]
	v_pk_add_f32 v[18:19], v[18:19], v[30:31]
	v_pk_add_f32 v[52:53], v[48:49], v[50:51] op_sel:[0,1] op_sel_hi:[1,0]
	v_pk_add_f32 v[48:49], v[48:49], v[50:51] op_sel:[0,1] op_sel_hi:[1,0] neg_lo:[0,1] neg_hi:[0,1]
	v_mov_b32_e32 v50, v52
	v_mov_b32_e32 v51, v49
	v_mov_b32_e32 v49, v53
	s_waitcnt lgkmcnt(1)
	v_pk_add_f32 v[52:53], v[20:21], v[40:41] neg_lo:[0,1] neg_hi:[0,1]
	s_waitcnt lgkmcnt(0)
	v_pk_add_f32 v[54:55], v[36:37], v[44:45] neg_lo:[0,1] neg_hi:[0,1]
	v_pk_add_f32 v[58:59], v[38:39], v[46:47] neg_lo:[0,1] neg_hi:[0,1]
	v_pk_add_f32 v[56:57], v[52:53], v[54:55] op_sel:[0,1] op_sel_hi:[1,0]
	v_pk_add_f32 v[52:53], v[52:53], v[54:55] op_sel:[0,1] op_sel_hi:[1,0] neg_lo:[0,1] neg_hi:[0,1]
	v_mov_b32_e32 v54, v56
	v_mov_b32_e32 v55, v53
	v_mov_b32_e32 v53, v57
	v_pk_add_f32 v[56:57], v[22:23], v[42:43] neg_lo:[0,1] neg_hi:[0,1]
	v_pk_add_f32 v[26:27], v[26:27], v[34:35]
	v_pk_add_f32 v[60:61], v[56:57], v[58:59] op_sel:[0,1] op_sel_hi:[1,0]
	v_pk_add_f32 v[56:57], v[56:57], v[58:59] op_sel:[0,1] op_sel_hi:[1,0] neg_lo:[0,1] neg_hi:[0,1]
	v_mov_b32_e32 v58, v60
	v_mov_b32_e32 v59, v57
	v_mov_b32_e32 v57, v61
	v_pk_mul_f32 v[60:61], v[50:51], v[8:9] op_sel:[0,0] op_sel_hi:[0,1]
	v_pk_add_f32 v[30:31], v[18:19], v[26:27]
	v_pk_fma_f32 v[8:9], v[50:51], v[8:9], v[60:61] op_sel:[1,1,0] op_sel_hi:[1,0,1] neg_lo:[1,0,0]
	v_pk_mul_f32 v[50:51], v[54:55], v[4:5] op_sel:[0,0] op_sel_hi:[0,1]
	v_pk_add_f32 v[18:19], v[18:19], v[26:27] neg_lo:[0,1] neg_hi:[0,1]
	v_pk_add_f32 v[20:21], v[20:21], v[40:41]
	v_pk_add_f32 v[26:27], v[36:37], v[44:45]
	v_pk_fma_f32 v[50:51], v[54:55], v[4:5], v[50:51] op_sel:[1,1,0] op_sel_hi:[1,0,1] neg_lo:[1,0,0]
	v_pk_mul_f32 v[54:55], v[58:59], v[2:3] op_sel:[0,0] op_sel_hi:[0,1]
	v_pk_add_f32 v[22:23], v[22:23], v[42:43]
	v_pk_add_f32 v[34:35], v[20:21], v[26:27]
	v_pk_add_f32 v[20:21], v[20:21], v[26:27] neg_lo:[0,1] neg_hi:[0,1]
	v_pk_add_f32 v[26:27], v[38:39], v[46:47]
	v_pk_fma_f32 v[54:55], v[58:59], v[2:3], v[54:55] op_sel:[1,1,0] op_sel_hi:[1,0,1] neg_lo:[1,0,0]
	v_pk_add_f32 v[58:59], v[16:17], v[28:29]
	v_pk_add_f32 v[60:61], v[24:25], v[32:33]
	v_pk_add_f32 v[36:37], v[22:23], v[26:27]
	v_pk_add_f32 v[22:23], v[22:23], v[26:27] neg_lo:[0,1] neg_hi:[0,1]
	v_pk_mul_f32 v[26:27], v[18:19], v[4:5] op_sel:[0,0] op_sel_hi:[0,1]
	v_pk_add_f32 v[16:17], v[16:17], v[28:29] neg_lo:[0,1] neg_hi:[0,1]
	v_pk_fma_f32 v[4:5], v[18:19], v[4:5], v[26:27] op_sel:[1,1,0] op_sel_hi:[1,0,1] neg_lo:[1,0,0]
	v_pk_mul_f32 v[18:19], v[20:21], v[10:11] op_sel:[0,0] op_sel_hi:[0,1]
	v_pk_add_f32 v[24:25], v[24:25], v[32:33] neg_lo:[0,1] neg_hi:[0,1]
	v_pk_fma_f32 v[10:11], v[20:21], v[10:11], v[18:19] op_sel:[1,1,0] op_sel_hi:[1,0,1] neg_lo:[1,0,0]
	v_pk_mul_f32 v[18:19], v[22:23], v[6:7] op_sel:[0,0] op_sel_hi:[0,1]
	v_pk_mul_f32 v[20:21], v[48:49], v[2:3] op_sel:[0,0] op_sel_hi:[0,1]
	s_nop 1
	v_pk_add_f32 v[62:63], v[58:59], v[60:61]
	v_pk_add_f32 v[28:29], v[16:17], v[24:25] op_sel:[0,1] op_sel_hi:[1,0] neg_lo:[0,1] neg_hi:[0,1]
	v_pk_add_f32 v[16:17], v[16:17], v[24:25] op_sel:[0,1] op_sel_hi:[1,0]
	v_pk_fma_f32 v[18:19], v[22:23], v[6:7], v[18:19] op_sel:[1,1,0] op_sel_hi:[1,0,1] neg_lo:[1,0,0]
	v_pk_fma_f32 v[2:3], v[48:49], v[2:3], v[20:21] op_sel:[1,1,0] op_sel_hi:[1,0,1] neg_lo:[1,0,0]
	v_pk_mul_f32 v[20:21], v[52:53], v[6:7] op_sel:[0,0] op_sel_hi:[0,1]
	v_mov_b32_e32 v24, v28
	v_pk_fma_f32 v[6:7], v[52:53], v[6:7], v[20:21] op_sel:[1,1,0] op_sel_hi:[1,0,1] neg_lo:[1,0,0]
	v_mov_b32_e32 v25, v17
	v_pk_mul_f32 v[20:21], v[56:57], v[12:13] op_sel:[0,0] op_sel_hi:[0,1]
	v_pk_add_f32 v[42:43], v[24:25], v[6:7] neg_lo:[0,1] neg_hi:[0,1]
	v_pk_fma_f32 v[12:13], v[56:57], v[12:13], v[20:21] op_sel:[1,1,0] op_sel_hi:[1,0,1] neg_lo:[1,0,0]
	v_pk_add_f32 v[6:7], v[24:25], v[6:7]
	v_pk_add_f32 v[44:45], v[2:3], v[12:13] neg_lo:[0,1] neg_hi:[0,1]
	v_pk_add_f32 v[2:3], v[2:3], v[12:13]
	v_pk_add_f32 v[24:25], v[42:43], v[44:45] op_sel:[0,1] op_sel_hi:[1,0] neg_lo:[0,1] neg_hi:[0,1]
	v_pk_add_f32 v[12:13], v[6:7], v[2:3]
	v_pk_add_f32 v[2:3], v[6:7], v[2:3] neg_lo:[0,1] neg_hi:[0,1]
	v_pk_add_f32 v[6:7], v[42:43], v[44:45] op_sel:[0,1] op_sel_hi:[1,0]
	v_xor_b32_e32 v15, 0x80000000, v88
	v_pk_mul_f32 v[44:45], v[14:15], v[14:15] op_sel:[0,0] op_sel_hi:[0,1]
	v_pk_add_f32 v[32:33], v[8:9], v[54:55] neg_lo:[0,1] neg_hi:[0,1]
	v_pk_fma_f32 v[44:45], v[14:15], v[14:15], v[44:45] op_sel:[1,1,0] op_sel_hi:[1,0,1] neg_lo:[1,0,0]
	v_pk_add_f32 v[8:9], v[8:9], v[54:55]
	v_pk_mul_f32 v[46:47], v[44:45], v[14:15] op_sel:[0,0] op_sel_hi:[0,1]
	v_pk_mul_f32 v[48:49], v[44:45], v[44:45] op_sel:[0,0] op_sel_hi:[0,1]
	v_pk_add_f32 v[20:21], v[62:63], v[34:35]
	v_pk_fma_f32 v[46:47], v[44:45], v[14:15], v[46:47] op_sel:[1,1,0] op_sel_hi:[1,0,1] neg_lo:[1,0,0]
	v_pk_fma_f32 v[48:49], v[44:45], v[44:45], v[48:49] op_sel:[1,1,0] op_sel_hi:[1,0,1] neg_lo:[1,0,0]
	v_pk_add_f32 v[22:23], v[30:31], v[36:37]
	v_pk_mul_f32 v[54:55], v[48:49], v[46:47] op_sel:[0,0] op_sel_hi:[0,1]
	v_pk_add_f32 v[30:31], v[30:31], v[36:37] neg_lo:[0,1] neg_hi:[0,1]
	v_pk_add_f32 v[36:37], v[58:59], v[60:61] neg_lo:[0,1] neg_hi:[0,1]
	v_mov_b32_e32 v17, v29
	v_mov_b32_e32 v42, v24
	v_mov_b32_e32 v43, v7
	v_pk_fma_f32 v[54:55], v[48:49], v[46:47], v[54:55] op_sel:[1,1,0] op_sel_hi:[1,0,1] neg_lo:[1,0,0]
	v_pk_mul_f32 v[56:57], v[48:49], v[48:49] op_sel:[0,0] op_sel_hi:[0,1]
	v_mov_b32_e32 v7, v25
	v_pk_mul_f32 v[24:25], v[6:7], v[54:55] op_sel:[0,0] op_sel_hi:[0,1]
	v_pk_add_f32 v[26:27], v[20:21], v[22:23]
	v_pk_add_f32 v[20:21], v[20:21], v[22:23] neg_lo:[0,1] neg_hi:[0,1]
	v_pk_add_f32 v[38:39], v[36:37], v[10:11] neg_lo:[0,1] neg_hi:[0,1]
	v_pk_add_f32 v[40:41], v[4:5], v[18:19] neg_lo:[0,1] neg_hi:[0,1]
	v_pk_add_f32 v[4:5], v[4:5], v[18:19]
	v_pk_add_f32 v[10:11], v[36:37], v[10:11]
	v_pk_add_f32 v[28:29], v[16:17], v[50:51] neg_lo:[0,1] neg_hi:[0,1]
	v_pk_add_f32 v[16:17], v[16:17], v[50:51]
	v_pk_mul_f32 v[50:51], v[48:49], v[14:15] op_sel:[0,0] op_sel_hi:[0,1]
	v_pk_fma_f32 v[56:57], v[48:49], v[48:49], v[56:57] op_sel:[1,1,0] op_sel_hi:[1,0,1] neg_lo:[1,0,0]
	v_pk_fma_f32 v[6:7], v[6:7], v[54:55], v[24:25] op_sel:[1,1,0] op_sel_hi:[1,0,1] neg_lo:[1,0,0]
	v_pk_add_f32 v[18:19], v[10:11], v[4:5]
	v_pk_mul_f32 v[58:59], v[56:57], v[14:15] op_sel:[0,0] op_sel_hi:[0,1]
	v_pk_mul_f32 v[24:25], v[20:21], v[56:57] op_sel:[0,0] op_sel_hi:[0,1]
	v_pk_add_f32 v[4:5], v[10:11], v[4:5] neg_lo:[0,1] neg_hi:[0,1]
	v_pk_add_f32 v[10:11], v[38:39], v[40:41] op_sel:[0,1] op_sel_hi:[1,0]
	v_pk_add_f32 v[36:37], v[38:39], v[40:41] op_sel:[0,1] op_sel_hi:[1,0] neg_lo:[0,1] neg_hi:[0,1]
	v_pk_add_f32 v[40:41], v[16:17], v[8:9]
	v_pk_add_f32 v[8:9], v[16:17], v[8:9] neg_lo:[0,1] neg_hi:[0,1]
	v_pk_add_f32 v[16:17], v[28:29], v[32:33] op_sel:[0,1] op_sel_hi:[1,0]
	v_pk_add_f32 v[28:29], v[28:29], v[32:33] op_sel:[0,1] op_sel_hi:[1,0] neg_lo:[0,1] neg_hi:[0,1]
	v_pk_fma_f32 v[50:51], v[48:49], v[14:15], v[50:51] op_sel:[1,1,0] op_sel_hi:[1,0,1] neg_lo:[1,0,0]
	v_pk_fma_f32 v[58:59], v[56:57], v[14:15], v[58:59] op_sel:[1,1,0] op_sel_hi:[1,0,1] neg_lo:[1,0,0]
	v_pk_fma_f32 v[20:21], v[20:21], v[56:57], v[24:25] op_sel:[1,1,0] op_sel_hi:[1,0,1] neg_lo:[1,0,0]
	v_pk_add_f32 v[22:23], v[62:63], v[34:35] neg_lo:[0,1] neg_hi:[0,1]
	v_pk_mul_f32 v[60:61], v[50:51], v[50:51] op_sel:[0,0] op_sel_hi:[0,1]
	v_pk_mul_f32 v[24:25], v[8:9], v[58:59] op_sel:[0,0] op_sel_hi:[0,1]
	v_mov_b32_e32 v32, v28
	v_mov_b32_e32 v33, v17
	v_pk_mul_f32 v[52:53], v[46:47], v[46:47] op_sel:[0,0] op_sel_hi:[0,1]
	v_pk_fma_f32 v[60:61], v[50:51], v[50:51], v[60:61] op_sel:[1,1,0] op_sel_hi:[1,0,1] neg_lo:[1,0,0]
	v_pk_mul_f32 v[62:63], v[56:57], v[46:47] op_sel:[0,0] op_sel_hi:[0,1]
	v_mov_b32_e32 v17, v29
	v_pk_mul_f32 v[28:29], v[16:17], v[50:51] op_sel:[0,0] op_sel_hi:[0,1]
	v_pk_fma_f32 v[8:9], v[8:9], v[58:59], v[24:25] op_sel:[1,1,0] op_sel_hi:[1,0,1] neg_lo:[1,0,0]
	v_pk_mul_f32 v[24:25], v[4:5], v[60:61] op_sel:[0,0] op_sel_hi:[0,1]
	v_pk_add_f32 v[34:35], v[22:23], v[30:31] op_sel:[0,1] op_sel_hi:[1,0]
	v_pk_add_f32 v[22:23], v[22:23], v[30:31] op_sel:[0,1] op_sel_hi:[1,0] neg_lo:[0,1] neg_hi:[0,1]
	v_mov_b32_e32 v39, v11
	v_pk_fma_f32 v[52:53], v[46:47], v[46:47], v[52:53] op_sel:[1,1,0] op_sel_hi:[1,0,1] neg_lo:[1,0,0]
	v_pk_fma_f32 v[62:63], v[56:57], v[46:47], v[62:63] op_sel:[1,1,0] op_sel_hi:[1,0,1] neg_lo:[1,0,0]
	v_pk_mul_f32 v[66:67], v[56:57], v[50:51] op_sel:[0,0] op_sel_hi:[0,1]
	v_pk_fma_f32 v[16:17], v[16:17], v[50:51], v[28:29] op_sel:[1,1,0] op_sel_hi:[1,0,1] neg_lo:[1,0,0]
	v_mov_b32_e32 v11, v37
	v_pk_mul_f32 v[64:65], v[52:53], v[52:53] op_sel:[0,0] op_sel_hi:[0,1]
	v_pk_mul_f32 v[28:29], v[10:11], v[52:53] op_sel:[0,0] op_sel_hi:[0,1]
	v_pk_fma_f32 v[4:5], v[4:5], v[60:61], v[24:25] op_sel:[1,1,0] op_sel_hi:[1,0,1] neg_lo:[1,0,0]
	v_pk_mul_f32 v[24:25], v[2:3], v[62:63] op_sel:[0,0] op_sel_hi:[0,1]
	v_mov_b32_e32 v30, v22
	v_mov_b32_e32 v31, v35
	v_pk_fma_f32 v[64:65], v[52:53], v[52:53], v[64:65] op_sel:[1,1,0] op_sel_hi:[1,0,1] neg_lo:[1,0,0]
	v_pk_fma_f32 v[66:67], v[56:57], v[50:51], v[66:67] op_sel:[1,1,0] op_sel_hi:[1,0,1] neg_lo:[1,0,0]
	v_pk_mul_f32 v[68:69], v[54:55], v[54:55] op_sel:[0,0] op_sel_hi:[0,1]
	v_pk_mul_f32 v[70:71], v[56:57], v[54:55] op_sel:[0,0] op_sel_hi:[0,1]
	v_pk_fma_f32 v[10:11], v[10:11], v[52:53], v[28:29] op_sel:[1,1,0] op_sel_hi:[1,0,1] neg_lo:[1,0,0]
	v_pk_fma_f32 v[2:3], v[2:3], v[62:63], v[24:25] op_sel:[1,1,0] op_sel_hi:[1,0,1] neg_lo:[1,0,0]
	s_nop 0
	v_pk_mul_f32 v[24:25], v[30:31], v[64:65] op_sel:[0,0] op_sel_hi:[0,1]
	v_pk_mul_f32 v[28:29], v[32:33], v[66:67] op_sel:[0,0] op_sel_hi:[0,1]
	v_mov_b32_e32 v38, v36
	v_pk_fma_f32 v[68:69], v[54:55], v[54:55], v[68:69] op_sel:[1,1,0] op_sel_hi:[1,0,1] neg_lo:[1,0,0]
	v_pk_fma_f32 v[70:71], v[56:57], v[54:55], v[70:71] op_sel:[1,1,0] op_sel_hi:[1,0,1] neg_lo:[1,0,0]
	v_pk_mul_f32 v[72:73], v[40:41], v[14:15] op_sel:[0,0] op_sel_hi:[0,1]
	v_mov_b32_e32 v35, v23
	v_pk_fma_f32 v[14:15], v[40:41], v[14:15], v[72:73] op_sel:[1,1,0] op_sel_hi:[1,0,1] neg_lo:[1,0,0]
	v_pk_mul_f32 v[40:41], v[18:19], v[44:45] op_sel:[0,0] op_sel_hi:[0,1]
	v_pk_mul_f32 v[22:23], v[34:35], v[48:49] op_sel:[0,0] op_sel_hi:[0,1]
	v_pk_fma_f32 v[24:25], v[30:31], v[64:65], v[24:25] op_sel:[1,1,0] op_sel_hi:[1,0,1] neg_lo:[1,0,0]
	v_pk_fma_f32 v[28:29], v[32:33], v[66:67], v[28:29] op_sel:[1,1,0] op_sel_hi:[1,0,1] neg_lo:[1,0,0]
	v_pk_mul_f32 v[30:31], v[38:39], v[68:69] op_sel:[0,0] op_sel_hi:[0,1]
	v_pk_mul_f32 v[32:33], v[42:43], v[70:71] op_sel:[0,0] op_sel_hi:[0,1]
	s_nop 0
	v_pk_fma_f32 v[18:19], v[18:19], v[44:45], v[40:41] op_sel:[1,1,0] op_sel_hi:[1,0,1] neg_lo:[1,0,0]
	v_pk_mul_f32 v[40:41], v[12:13], v[46:47] op_sel:[0,0] op_sel_hi:[0,1]
	v_pk_fma_f32 v[22:23], v[34:35], v[48:49], v[22:23] op_sel:[1,1,0] op_sel_hi:[1,0,1] neg_lo:[1,0,0]
	s_nop 0
	v_pk_fma_f32 v[12:13], v[12:13], v[46:47], v[40:41] op_sel:[1,1,0] op_sel_hi:[1,0,1] neg_lo:[1,0,0]
	v_pk_fma_f32 v[30:31], v[38:39], v[68:69], v[30:31] op_sel:[1,1,0] op_sel_hi:[1,0,1] neg_lo:[1,0,0]
	v_pk_fma_f32 v[32:33], v[42:43], v[70:71], v[32:33] op_sel:[1,1,0] op_sel_hi:[1,0,1] neg_lo:[1,0,0]
	ds_write2_b64 v1, v[26:27], v[14:15] offset1:4
	ds_write2_b64 v1, v[18:19], v[12:13] offset0:8 offset1:12
	ds_write2_b64 v1, v[22:23], v[16:17] offset0:17 offset1:21
	ds_write2_b64 v1, v[10:11], v[6:7] offset0:25 offset1:29
	ds_write2_b64 v1, v[20:21], v[8:9] offset0:34 offset1:38
	ds_write2_b64 v1, v[4:5], v[2:3] offset0:42 offset1:46
	ds_write2_b64 v1, v[24:25], v[28:29] offset0:51 offset1:55
	ds_write2_b64 v1, v[30:31], v[32:33] offset0:59 offset1:63
	v_mov_b32_e32 v1, v0
	s_waitcnt lgkmcnt(0)
	s_barrier
	s_nop 0
	v_cmp_gt_i32_e32 vcc, s59, v1
	s_and_saveexec_b64 s[4:5], vcc
	s_cbranch_execz .LBB0_322
	v_lshl_add_u32 v2, v1, 5, 0
	s_mov_b64 s[22:23], 0

.LBB0_381:
	s_or_b64 exec, exec, s[4:5]
	s_waitcnt vmcnt(0)
	v_lshlrev_b32_e32 v60, 16, v234
	v_lshlrev_b32_e32 v58, 16, v235
	v_lshlrev_b32_e32 v61, 16, v243
	v_lshlrev_b32_e32 v59, 16, v244
	v_lshlrev_b32_e32 v75, 16, v245
	v_lshlrev_b32_e32 v101, 16, v246
	v_lshlrev_b32_e32 v73, 16, v247
	v_lshlrev_b32_e32 v99, 16, v248
	v_lshlrev_b32_e32 v71, 16, v249
	v_lshlrev_b32_e32 v81, 16, v250
	v_lshlrev_b32_e32 v1, 16, v251
	v_lshlrev_b32_e32 v79, 16, v252
	v_lshlrev_b32_e32 v63, 16, v46
	v_lshlrev_b32_e32 v62, 16, v38
	v_and_b32_e32 v65, 0xffff0000, v46
	v_and_b32_e32 v64, 0xffff0000, v38
	v_lshlrev_b32_e32 v86, 16, v39
	v_and_b32_e32 v46, 0xffff0000, v39
	v_lshlrev_b32_e32 v39, 16, v48
	v_lshlrev_b32_e32 v38, 16, v40
	v_and_b32_e32 v89, 0xffff0000, v48
	v_and_b32_e32 v88, 0xffff0000, v40
	v_lshlrev_b32_e32 v90, 16, v41
	v_and_b32_e32 v48, 0xffff0000, v41
	v_pk_mul_f32 v[40:41], v[50:51], v[60:61] op_sel_hi:[0,1]
	v_lshlrev_b32_e32 v61, 16, v42
	v_lshlrev_b32_e32 v60, 16, v34
	v_and_b32_e32 v93, 0xffff0000, v42
	v_and_b32_e32 v92, 0xffff0000, v34
	v_lshlrev_b32_e32 v94, 16, v35
	v_and_b32_e32 v42, 0xffff0000, v35
	v_lshlrev_b32_e32 v35, 16, v44
	v_lshlrev_b32_e32 v34, 16, v36
	v_and_b32_e32 v97, 0xffff0000, v44
	v_and_b32_e32 v96, 0xffff0000, v36
	v_lshlrev_b32_e32 v118, 16, v37
	v_and_b32_e32 v44, 0xffff0000, v37
	v_pk_fma_f32 v[36:37], v[56:57], v[62:63], v[40:41] op_sel_hi:[0,1,1]
	v_pk_fma_f32 v[36:37], v[54:55], v[64:65], v[36:37] op_sel_hi:[0,1,1]
	v_pk_add_f32 v[130:131], v[52:53], v[36:37] op_sel_hi:[0,1]
	v_pk_mul_f32 v[36:37], v[56:57], v[64:65] op_sel_hi:[0,1]
	v_lshlrev_b32_e32 v87, 16, v47
	v_pk_fma_f32 v[36:37], v[50:51], v[62:63], v[36:37] op_sel_hi:[0,1,1]
	v_pk_fma_f32 v[36:37], v[54:55], v[86:87], v[36:37] op_sel_hi:[0,1,1]
	v_pk_add_f32 v[136:137], v[52:53], v[36:37] op_sel_hi:[0,1]
	v_pk_mul_f32 v[36:37], v[56:57], v[86:87] op_sel_hi:[0,1]
	v_and_b32_e32 v47, 0xffff0000, v47
	v_pk_fma_f32 v[36:37], v[50:51], v[64:65], v[36:37] op_sel_hi:[0,1,1]
	v_pk_fma_f32 v[36:37], v[54:55], v[46:47], v[36:37] op_sel_hi:[0,1,1]
	v_pk_add_f32 v[132:133], v[52:53], v[36:37] op_sel_hi:[0,1]
	v_pk_mul_f32 v[36:37], v[56:57], v[46:47] op_sel_hi:[0,1]
	v_pk_fma_f32 v[36:37], v[50:51], v[86:87], v[36:37] op_sel_hi:[0,1,1]
	v_pk_fma_f32 v[36:37], v[54:55], v[38:39], v[36:37] op_sel_hi:[0,1,1]
	v_pk_add_f32 v[134:135], v[52:53], v[36:37] op_sel_hi:[0,1]
	v_pk_mul_f32 v[36:37], v[56:57], v[38:39] op_sel_hi:[0,1]
	v_pk_fma_f32 v[36:37], v[50:51], v[46:47], v[36:37] op_sel_hi:[0,1,1]
	v_pk_fma_f32 v[36:37], v[54:55], v[88:89], v[36:37] op_sel_hi:[0,1,1]
	v_pk_add_f32 v[102:103], v[52:53], v[36:37] op_sel_hi:[0,1]
	v_pk_mul_f32 v[36:37], v[56:57], v[88:89] op_sel_hi:[0,1]
	v_lshlrev_b32_e32 v91, 16, v49
	v_pk_fma_f32 v[36:37], v[50:51], v[38:39], v[36:37] op_sel_hi:[0,1,1]
	v_pk_fma_f32 v[36:37], v[54:55], v[90:91], v[36:37] op_sel_hi:[0,1,1]
	v_pk_add_f32 v[128:129], v[52:53], v[36:37] op_sel_hi:[0,1]
	v_pk_mul_f32 v[36:37], v[56:57], v[90:91] op_sel_hi:[0,1]
	v_and_b32_e32 v49, 0xffff0000, v49
	v_pk_fma_f32 v[36:37], v[50:51], v[88:89], v[36:37] op_sel_hi:[0,1,1]
	v_pk_fma_f32 v[36:37], v[54:55], v[48:49], v[36:37] op_sel_hi:[0,1,1]
	v_pk_add_f32 v[106:107], v[52:53], v[36:37] op_sel_hi:[0,1]
	v_pk_mul_f32 v[36:37], v[56:57], v[48:49] op_sel_hi:[0,1]
	v_pk_fma_f32 v[36:37], v[50:51], v[90:91], v[36:37] op_sel_hi:[0,1,1]
	v_pk_fma_f32 v[36:37], v[54:55], v[60:61], v[36:37] op_sel_hi:[0,1,1]
	v_pk_add_f32 v[110:111], v[52:53], v[36:37] op_sel_hi:[0,1]
	v_pk_mul_f32 v[36:37], v[56:57], v[60:61] op_sel_hi:[0,1]
	v_pk_fma_f32 v[36:37], v[50:51], v[48:49], v[36:37] op_sel_hi:[0,1,1]
	v_pk_fma_f32 v[36:37], v[54:55], v[92:93], v[36:37] op_sel_hi:[0,1,1]
	v_pk_add_f32 v[104:105], v[52:53], v[36:37] op_sel_hi:[0,1]
	v_pk_mul_f32 v[36:37], v[56:57], v[92:93] op_sel_hi:[0,1]
	v_lshlrev_b32_e32 v95, 16, v43
	v_pk_fma_f32 v[36:37], v[50:51], v[60:61], v[36:37] op_sel_hi:[0,1,1]
	v_pk_fma_f32 v[36:37], v[54:55], v[94:95], v[36:37] op_sel_hi:[0,1,1]
	v_pk_add_f32 v[108:109], v[52:53], v[36:37] op_sel_hi:[0,1]
	v_pk_mul_f32 v[36:37], v[56:57], v[94:95] op_sel_hi:[0,1]
	v_and_b32_e32 v43, 0xffff0000, v43
	v_pk_fma_f32 v[36:37], v[50:51], v[92:93], v[36:37] op_sel_hi:[0,1,1]
	v_pk_fma_f32 v[36:37], v[54:55], v[42:43], v[36:37] op_sel_hi:[0,1,1]
	v_pk_add_f32 v[112:113], v[52:53], v[36:37] op_sel_hi:[0,1]
	v_pk_mul_f32 v[36:37], v[56:57], v[42:43] op_sel_hi:[0,1]
	v_pk_fma_f32 v[36:37], v[50:51], v[94:95], v[36:37] op_sel_hi:[0,1,1]
	v_pk_fma_f32 v[36:37], v[54:55], v[34:35], v[36:37] op_sel_hi:[0,1,1]
	v_pk_add_f32 v[116:117], v[52:53], v[36:37] op_sel_hi:[0,1]
	v_pk_mul_f32 v[36:37], v[56:57], v[34:35] op_sel_hi:[0,1]
	v_pk_fma_f32 v[36:37], v[50:51], v[42:43], v[36:37] op_sel_hi:[0,1,1]
	v_pk_fma_f32 v[36:37], v[54:55], v[96:97], v[36:37] op_sel_hi:[0,1,1]
	v_pk_add_f32 v[114:115], v[52:53], v[36:37] op_sel_hi:[0,1]
	v_pk_mul_f32 v[36:37], v[56:57], v[96:97] op_sel_hi:[0,1]
	v_lshlrev_b32_e32 v119, 16, v45
	v_pk_fma_f32 v[34:35], v[50:51], v[34:35], v[36:37] op_sel_hi:[0,1,1]
	v_pk_fma_f32 v[34:35], v[54:55], v[118:119], v[34:35] op_sel_hi:[0,1,1]
	v_pk_add_f32 v[120:121], v[52:53], v[34:35] op_sel_hi:[0,1]
	v_pk_mul_f32 v[34:35], v[56:57], v[118:119] op_sel_hi:[0,1]
	v_and_b32_e32 v45, 0xffff0000, v45
	v_pk_fma_f32 v[34:35], v[50:51], v[96:97], v[34:35] op_sel_hi:[0,1,1]
	v_pk_fma_f32 v[34:35], v[54:55], v[44:45], v[34:35] op_sel_hi:[0,1,1]
	v_pk_add_f32 v[122:123], v[52:53], v[34:35] op_sel_hi:[0,1]
	v_pk_mul_f32 v[34:35], v[56:57], v[44:45] op_sel_hi:[0,1]
	v_pk_fma_f32 v[34:35], v[50:51], v[118:119], v[34:35] op_sel_hi:[0,1,1]
	v_pk_fma_f32 v[34:35], v[54:55], v[58:59], v[34:35] op_sel_hi:[0,1,1]
	s_movk_i32 s33, 0x88
	v_pk_add_f32 v[118:119], v[52:53], v[34:35] op_sel_hi:[0,1]
	v_mul_lo_u32 v34, v51, s33
	v_add_u32_e32 v34, 0, v34
	s_mov_b32 s66, s67
	s_mov_b32 s4, s67
	s_mov_b32 s5, s67
	v_add_u32_e32 v35, 0x11000, v34
	v_mov_b64_e32 v[124:125], s[66:67]
	v_mov_b64_e32 v[126:127], s[4:5]
	ds_write2_b64 v35, v[124:125], v[126:127] offset1:1
	v_add_u32_e32 v35, 0x11010, v34
	ds_write2_b64 v34, v[130:131], v[136:137] offset1:1
	ds_write2_b64 v34, v[132:133], v[134:135] offset0:2 offset1:3
	ds_write2_b64 v35, v[124:125], v[126:127] offset1:1
	v_add_u32_e32 v35, 0x11020, v34
	ds_write2_b64 v34, v[102:103], v[128:129] offset0:4 offset1:5
	ds_write2_b64 v35, v[124:125], v[126:127] offset1:1
	v_add_u32_e32 v35, 0x11030, v34
	ds_write2_b64 v34, v[106:107], v[110:111] offset0:6 offset1:7
	ds_write2_b64 v35, v[124:125], v[126:127] offset1:1
	v_add_u32_e32 v35, 0x11040, v34
	ds_write2_b64 v34, v[104:105], v[108:109] offset0:8 offset1:9
	ds_write2_b64 v35, v[124:125], v[126:127] offset1:1
	v_add_u32_e32 v35, 0x11050, v34
	ds_write2_b64 v34, v[112:113], v[116:117] offset0:10 offset1:11
	ds_write2_b64 v35, v[124:125], v[126:127] offset1:1
	v_add_u32_e32 v35, 0x11060, v34
	ds_write2_b64 v34, v[114:115], v[120:121] offset0:12 offset1:13
	ds_write2_b64 v35, v[124:125], v[126:127] offset1:1
	v_add_u32_e32 v35, 0x11070, v34
	ds_write2_b64 v34, v[122:123], v[118:119] offset0:14 offset1:15
	ds_write2_b64 v35, v[124:125], v[126:127] offset1:1
	v_lshl_add_u64 v[34:35], v[68:69], 0, s[46:47]
	s_movk_i32 s13, 0x2000
	v_add_co_u32_e32 v36, vcc, s13, v34
	s_movk_i32 s22, 0x4000
	s_nop 0
	v_addc_co_u32_e32 v37, vcc, 0, v35, vcc
	s_waitcnt lgkmcnt(0)
	s_barrier
	global_load_dwordx4 v[62:65], v[34:35], off
	global_load_dwordx4 v[58:61], v[36:37], off
	v_add_co_u32_e32 v36, vcc, s22, v34
	s_movk_i32 s23, 0x6000
	s_nop 0
	v_addc_co_u32_e32 v37, vcc, 0, v35, vcc
	v_add_co_u32_e32 v38, vcc, s23, v34
	s_mov_b32 s3, 0x8000
	s_nop 0
	v_addc_co_u32_e32 v39, vcc, 0, v35, vcc
	global_load_dwordx4 v[54:57], v[36:37], off
	global_load_dwordx4 v[50:53], v[38:39], off
	v_add_co_u32_e32 v36, vcc, s3, v34
	s_mov_b32 s25, 0xa000
	s_nop 0
	v_addc_co_u32_e32 v37, vcc, 0, v35, vcc
	v_add_co_u32_e32 v38, vcc, s25, v34
	s_mov_b32 s29, 0xc000
	s_nop 0
	v_addc_co_u32_e32 v39, vcc, 0, v35, vcc
	global_load_dwordx4 v[46:49], v[36:37], off
	global_load_dwordx4 v[42:45], v[38:39], off
	v_add_co_u32_e32 v36, vcc, s29, v34
	s_mov_b32 s30, 0xe000
	s_nop 0
	v_addc_co_u32_e32 v37, vcc, 0, v35, vcc
	v_add_co_u32_e32 v34, vcc, s30, v34
	v_mov_b32_e32 v85, v0
	s_nop 0
	v_addc_co_u32_e32 v35, vcc, 0, v35, vcc
	global_load_dwordx4 v[38:41], v[36:37], off
	s_nop 0
	global_load_dwordx4 v[34:37], v[34:35], off
	s_movk_i32 s31, 0xc000
	v_and_b32_e32 v98, 0x3ff, v85
	v_lshlrev_b32_e32 v86, 4, v85
	v_and_or_b32 v86, v86, s31, v98
	v_ashrrev_i32_e32 v87, 4, v86
	v_lshlrev_b32_e32 v87, 3, v87
	v_lshlrev_b32_e32 v86, 3, v86
	v_add3_u32 v100, 0, v87, v86
	ds_read2st64_b64 v[138:141], v100 offset1:17
	ds_read2st64_b64 v[92:95], v100 offset0:34 offset1:51
	ds_read2st64_b64 v[142:145], v100 offset0:68 offset1:85
	ds_read2st64_b64 v[146:149], v100 offset0:102 offset1:119
	v_add_u32_e32 v190, 0x11000, v100
	v_add_u32_e32 v193, 0x13200, v100
	v_add_u32_e32 v195, 0x15400, v100
	v_add_u32_e32 v197, 0x17600, v100
	ds_read_b64 v[150:151], v190
	ds_read_b64 v[96:97], v193
	ds_read_b64 v[152:153], v195
	ds_read_b64 v[154:155], v197
	v_add_u32_e32 v231, 0x1ba00, v100
	v_add_u32_e32 v230, 0x19800, v100
	v_add_u32_e32 v232, 0x1dc00, v100
	v_add_u32_e32 v233, 0x1fe00, v100
	ds_read_b64 v[156:157], v231
	ds_read_b64 v[158:159], v232
	ds_read_b64 v[160:161], v233
	ds_read_b64 v[162:163], v230
	s_waitcnt lgkmcnt(6)
	v_pk_add_f32 v[86:87], v[140:141], v[96:97] neg_lo:[0,1] neg_hi:[0,1]
	s_waitcnt lgkmcnt(3)
	v_pk_add_f32 v[88:89], v[144:145], v[156:157] neg_lo:[0,1] neg_hi:[0,1]
	v_pk_add_f32 v[96:97], v[140:141], v[96:97]
	v_pk_add_f32 v[90:91], v[86:87], v[88:89] op_sel:[0,1] op_sel_hi:[1,0]
	v_pk_add_f32 v[164:165], v[86:87], v[88:89] op_sel:[0,1] op_sel_hi:[1,0] neg_lo:[0,1] neg_hi:[0,1]
	v_mov_b32_e32 v86, v90
	v_mov_b32_e32 v87, v165
	v_mov_b32_e32 v165, v91
	v_pk_add_f32 v[88:89], v[92:93], v[152:153] neg_lo:[0,1] neg_hi:[0,1]
	s_waitcnt lgkmcnt(2)
	v_pk_add_f32 v[90:91], v[146:147], v[158:159] neg_lo:[0,1] neg_hi:[0,1]
	v_pk_add_f32 v[140:141], v[144:145], v[156:157]
	v_pk_add_f32 v[166:167], v[88:89], v[90:91] op_sel:[0,1] op_sel_hi:[1,0]
	v_pk_add_f32 v[168:169], v[88:89], v[90:91] op_sel:[0,1] op_sel_hi:[1,0] neg_lo:[0,1] neg_hi:[0,1]
	v_pk_add_f32 v[88:89], v[94:95], v[154:155] neg_lo:[0,1] neg_hi:[0,1]
	s_waitcnt lgkmcnt(1)
	v_pk_add_f32 v[90:91], v[148:149], v[160:161] neg_lo:[0,1] neg_hi:[0,1]
	v_pk_add_f32 v[144:145], v[96:97], v[140:141]
	v_pk_add_f32 v[96:97], v[96:97], v[140:141] neg_lo:[0,1] neg_hi:[0,1]
	v_pk_add_f32 v[92:93], v[92:93], v[152:153]
	v_pk_add_f32 v[140:141], v[146:147], v[158:159]
	v_mov_b32_e32 v170, v166
	v_mov_b32_e32 v171, v169
	v_mov_b32_e32 v169, v167
	v_pk_add_f32 v[166:167], v[88:89], v[90:91] op_sel:[0,1] op_sel_hi:[1,0]
	v_pk_add_f32 v[172:173], v[88:89], v[90:91] op_sel:[0,1] op_sel_hi:[1,0] neg_lo:[0,1] neg_hi:[0,1]
	v_mov_b64_e32 v[90:91], s[6:7]
	v_pk_mul_f32 v[88:89], v[86:87], v[90:91] op_sel:[0,0] op_sel_hi:[0,1]
	v_pk_add_f32 v[146:147], v[92:93], v[140:141]
	v_pk_add_f32 v[92:93], v[92:93], v[140:141] neg_lo:[0,1] neg_hi:[0,1]
	v_pk_add_f32 v[94:95], v[94:95], v[154:155]
	v_pk_add_f32 v[140:141], v[148:149], v[160:161]
	v_mov_b32_e32 v174, v166
	v_mov_b32_e32 v175, v173
	v_mov_b32_e32 v173, v167
	v_pk_fma_f32 v[166:167], v[86:87], v[90:91], v[88:89] op_sel:[1,1,0] op_sel_hi:[1,0,1] neg_lo:[1,0,0]
	v_mov_b64_e32 v[88:89], s[16:17]
	v_pk_add_f32 v[148:149], v[94:95], v[140:141]
	v_pk_add_f32 v[140:141], v[94:95], v[140:141] neg_lo:[0,1] neg_hi:[0,1]
	v_pk_mul_f32 v[94:95], v[96:97], v[88:89] op_sel:[0,0] op_sel_hi:[0,1]
	v_pk_mul_f32 v[86:87], v[170:171], v[88:89] op_sel:[0,0] op_sel_hi:[0,1]
	s_waitcnt lgkmcnt(0)
	v_pk_add_f32 v[178:179], v[142:143], v[162:163]
	v_pk_fma_f32 v[152:153], v[96:97], v[88:89], v[94:95] op_sel:[1,1,0] op_sel_hi:[1,0,1] neg_lo:[1,0,0]
	v_mov_b64_e32 v[94:95], s[60:61]
	v_pk_mul_f32 v[96:97], v[92:93], v[94:95] op_sel:[0,0] op_sel_hi:[0,1]
	v_pk_fma_f32 v[170:171], v[170:171], v[88:89], v[86:87] op_sel:[1,1,0] op_sel_hi:[1,0,1] neg_lo:[1,0,0]
	v_mov_b64_e32 v[86:87], s[18:19]
	v_pk_mul_f32 v[176:177], v[174:175], v[86:87] op_sel:[0,0] op_sel_hi:[0,1]
	v_pk_fma_f32 v[154:155], v[92:93], v[94:95], v[96:97] op_sel:[1,1,0] op_sel_hi:[1,0,1] neg_lo:[1,0,0]
	v_mov_b64_e32 v[92:93], s[20:21]
	v_pk_mul_f32 v[96:97], v[140:141], v[92:93] op_sel:[0,0] op_sel_hi:[0,1]
	v_pk_fma_f32 v[174:175], v[174:175], v[86:87], v[176:177] op_sel:[1,1,0] op_sel_hi:[1,0,1] neg_lo:[1,0,0]
	v_pk_add_f32 v[176:177], v[138:139], v[150:151]
	v_pk_fma_f32 v[140:141], v[140:141], v[92:93], v[96:97] op_sel:[1,1,0] op_sel_hi:[1,0,1] neg_lo:[1,0,0]
	v_pk_mul_f32 v[96:97], v[164:165], v[86:87] op_sel:[0,0] op_sel_hi:[0,1]
	v_cvt_f32_u32_e32 v98, v98
	v_pk_add_f32 v[180:181], v[176:177], v[178:179]
	v_pk_fma_f32 v[156:157], v[164:165], v[86:87], v[96:97] op_sel:[1,1,0] op_sel_hi:[1,0,1] neg_lo:[1,0,0]
	v_pk_mul_f32 v[96:97], v[168:169], v[92:93] op_sel:[0,0] op_sel_hi:[0,1]
	v_pk_add_f32 v[138:139], v[138:139], v[150:151] neg_lo:[0,1] neg_hi:[0,1]
	v_pk_fma_f32 v[158:159], v[168:169], v[92:93], v[96:97] op_sel:[1,1,0] op_sel_hi:[1,0,1] neg_lo:[1,0,0]
	v_mov_b64_e32 v[96:97], s[8:9]
	v_pk_mul_f32 v[160:161], v[172:173], v[96:97] op_sel:[0,0] op_sel_hi:[0,1]
	v_pk_add_f32 v[164:165], v[180:181], v[146:147]
	v_pk_add_f32 v[168:169], v[144:145], v[148:149]
	v_pk_fma_f32 v[160:161], v[172:173], v[96:97], v[160:161] op_sel:[1,1,0] op_sel_hi:[1,0,1] neg_lo:[1,0,0]
	v_pk_add_f32 v[142:143], v[142:143], v[162:163] neg_lo:[0,1] neg_hi:[0,1]
	v_pk_add_f32 v[172:173], v[164:165], v[168:169]
	v_pk_add_f32 v[164:165], v[164:165], v[168:169] neg_lo:[0,1] neg_hi:[0,1]
	v_pk_add_f32 v[168:169], v[176:177], v[178:179] neg_lo:[0,1] neg_hi:[0,1]
	v_pk_add_f32 v[178:179], v[152:153], v[140:141] neg_lo:[0,1] neg_hi:[0,1]
	v_pk_add_f32 v[176:177], v[168:169], v[154:155] neg_lo:[0,1] neg_hi:[0,1]
	v_pk_add_f32 v[140:141], v[152:153], v[140:141]
	v_pk_add_f32 v[152:153], v[168:169], v[154:155]
	v_mul_f32_e32 v98, 0x38800000, v98
	v_pk_add_f32 v[154:155], v[152:153], v[140:141]
	v_pk_add_f32 v[140:141], v[152:153], v[140:141] neg_lo:[0,1] neg_hi:[0,1]
	v_pk_add_f32 v[152:153], v[176:177], v[178:179] op_sel:[0,1] op_sel_hi:[1,0]
	v_pk_add_f32 v[168:169], v[176:177], v[178:179] op_sel:[0,1] op_sel_hi:[1,0] neg_lo:[0,1] neg_hi:[0,1]
	v_pk_add_f32 v[150:151], v[138:139], v[142:143] op_sel:[0,1] op_sel_hi:[1,0] neg_lo:[0,1] neg_hi:[0,1]
	v_pk_add_f32 v[138:139], v[138:139], v[142:143] op_sel:[0,1] op_sel_hi:[1,0]
	v_pk_add_f32 v[178:179], v[156:157], v[160:161] neg_lo:[0,1] neg_hi:[0,1]
	v_pk_add_f32 v[156:157], v[156:157], v[160:161]
	v_cos_f32_e32 v160, v98
	v_sin_f32_e32 v98, v98
	v_pk_add_f32 v[146:147], v[180:181], v[146:147] neg_lo:[0,1] neg_hi:[0,1]
	v_mov_b32_e32 v143, v139
	v_mov_b32_e32 v139, v151
	s_nop 1
	v_mov_b32_e32 v142, v150
	v_xor_b32_e32 v161, 0x80000000, v98
	v_pk_mul_f32 v[180:181], v[160:161], v[160:161] op_sel:[0,0] op_sel_hi:[0,1]
	v_pk_add_f32 v[162:163], v[166:167], v[174:175] neg_lo:[0,1] neg_hi:[0,1]
	v_pk_add_f32 v[150:151], v[138:139], v[170:171] neg_lo:[0,1] neg_hi:[0,1]
	v_pk_add_f32 v[166:167], v[166:167], v[174:175]
	v_pk_add_f32 v[138:139], v[138:139], v[170:171]
	v_pk_fma_f32 v[180:181], v[160:161], v[160:161], v[180:181] op_sel:[1,1,0] op_sel_hi:[1,0,1] neg_lo:[1,0,0]
	v_pk_add_f32 v[174:175], v[142:143], v[158:159] neg_lo:[0,1] neg_hi:[0,1]
	v_pk_mul_f32 v[182:183], v[180:181], v[160:161] op_sel:[0,0] op_sel_hi:[0,1]
	v_pk_add_f32 v[170:171], v[138:139], v[166:167]
	v_pk_add_f32 v[138:139], v[138:139], v[166:167] neg_lo:[0,1] neg_hi:[0,1]
	v_pk_add_f32 v[166:167], v[150:151], v[162:163] op_sel:[0,1] op_sel_hi:[1,0]
	v_pk_add_f32 v[150:151], v[150:151], v[162:163] op_sel:[0,1] op_sel_hi:[1,0] neg_lo:[0,1] neg_hi:[0,1]
	v_pk_add_f32 v[142:143], v[142:143], v[158:159]
	v_pk_fma_f32 v[182:183], v[180:181], v[160:161], v[182:183] op_sel:[1,1,0] op_sel_hi:[1,0,1] neg_lo:[1,0,0]
	v_pk_mul_f32 v[184:185], v[180:181], v[180:181] op_sel:[0,0] op_sel_hi:[0,1]
	v_mov_b32_e32 v177, v153
	v_pk_mul_f32 v[188:189], v[182:183], v[182:183] op_sel:[0,0] op_sel_hi:[0,1]
	v_mov_b32_e32 v162, v150
	v_mov_b32_e32 v163, v167
	v_pk_add_f32 v[158:159], v[142:143], v[156:157]
	v_pk_add_f32 v[142:143], v[142:143], v[156:157] neg_lo:[0,1] neg_hi:[0,1]
	v_pk_add_f32 v[156:157], v[174:175], v[178:179] op_sel:[0,1] op_sel_hi:[1,0]
	v_pk_add_f32 v[174:175], v[174:175], v[178:179] op_sel:[0,1] op_sel_hi:[1,0] neg_lo:[0,1] neg_hi:[0,1]
	v_pk_fma_f32 v[184:185], v[180:181], v[180:181], v[184:185] op_sel:[1,1,0] op_sel_hi:[1,0,1] neg_lo:[1,0,0]
	v_pk_fma_f32 v[188:189], v[182:183], v[182:183], v[188:189] op_sel:[1,1,0] op_sel_hi:[1,0,1] neg_lo:[1,0,0]
	v_mov_b32_e32 v167, v151
	v_pk_mul_f32 v[210:211], v[184:185], v[182:183] op_sel:[0,0] op_sel_hi:[0,1]
	v_mov_b32_e32 v153, v169
	v_pk_mul_f32 v[150:151], v[152:153], v[188:189] op_sel:[0,0] op_sel_hi:[0,1]
	v_mov_b32_e32 v179, v157
	v_pk_fma_f32 v[210:211], v[184:185], v[182:183], v[210:211] op_sel:[1,1,0] op_sel_hi:[1,0,1] neg_lo:[1,0,0]
	v_pk_mul_f32 v[212:213], v[184:185], v[184:185] op_sel:[0,0] op_sel_hi:[0,1]
	v_pk_fma_f32 v[150:151], v[152:153], v[188:189], v[150:151] op_sel:[1,1,0] op_sel_hi:[1,0,1] neg_lo:[1,0,0]
	v_mov_b32_e32 v157, v175
	v_pk_mul_f32 v[152:153], v[156:157], v[210:211] op_sel:[0,0] op_sel_hi:[0,1]
	v_pk_mul_f32 v[186:187], v[184:185], v[160:161] op_sel:[0,0] op_sel_hi:[0,1]
	v_pk_fma_f32 v[212:213], v[184:185], v[184:185], v[212:213] op_sel:[1,1,0] op_sel_hi:[1,0,1] neg_lo:[1,0,0]
	v_pk_add_f32 v[144:145], v[144:145], v[148:149] neg_lo:[0,1] neg_hi:[0,1]
	v_pk_mul_f32 v[214:215], v[212:213], v[160:161] op_sel:[0,0] op_sel_hi:[0,1]
	v_pk_fma_f32 v[152:153], v[156:157], v[210:211], v[152:153] op_sel:[1,1,0] op_sel_hi:[1,0,1] neg_lo:[1,0,0]
	v_pk_mul_f32 v[156:157], v[164:165], v[212:213] op_sel:[0,0] op_sel_hi:[0,1]
	v_pk_fma_f32 v[186:187], v[184:185], v[160:161], v[186:187] op_sel:[1,1,0] op_sel_hi:[1,0,1] neg_lo:[1,0,0]
	v_pk_mul_f32 v[218:219], v[212:213], v[182:183] op_sel:[0,0] op_sel_hi:[0,1]
	s_nop 0
	v_pk_add_f32 v[148:149], v[146:147], v[144:145] op_sel:[0,1] op_sel_hi:[1,0]
	v_pk_fma_f32 v[214:215], v[212:213], v[160:161], v[214:215] op_sel:[1,1,0] op_sel_hi:[1,0,1] neg_lo:[1,0,0]
	v_pk_mul_f32 v[216:217], v[186:187], v[186:187] op_sel:[0,0] op_sel_hi:[0,1]
	v_pk_fma_f32 v[156:157], v[164:165], v[212:213], v[156:157] op_sel:[1,1,0] op_sel_hi:[1,0,1] neg_lo:[1,0,0]
	v_pk_add_f32 v[144:145], v[146:147], v[144:145] op_sel:[0,1] op_sel_hi:[1,0] neg_lo:[0,1] neg_hi:[0,1]
	v_pk_mul_f32 v[164:165], v[138:139], v[214:215] op_sel:[0,0] op_sel_hi:[0,1]
	v_pk_fma_f32 v[216:217], v[186:187], v[186:187], v[216:217] op_sel:[1,1,0] op_sel_hi:[1,0,1] neg_lo:[1,0,0]
	v_pk_fma_f32 v[218:219], v[212:213], v[182:183], v[218:219] op_sel:[1,1,0] op_sel_hi:[1,0,1] neg_lo:[1,0,0]
	v_pk_mul_f32 v[220:221], v[188:189], v[188:189] op_sel:[0,0] op_sel_hi:[0,1]
	v_mov_b32_e32 v147, v149
	v_pk_fma_f32 v[138:139], v[138:139], v[214:215], v[164:165] op_sel:[1,1,0] op_sel_hi:[1,0,1] neg_lo:[1,0,0]
	v_pk_mul_f32 v[164:165], v[140:141], v[216:217] op_sel:[0,0] op_sel_hi:[0,1]
	v_mov_b32_e32 v146, v144
	v_pk_fma_f32 v[140:141], v[140:141], v[216:217], v[164:165] op_sel:[1,1,0] op_sel_hi:[1,0,1] neg_lo:[1,0,0]
	v_pk_mul_f32 v[164:165], v[142:143], v[218:219] op_sel:[0,0] op_sel_hi:[0,1]
	v_pk_fma_f32 v[220:221], v[188:189], v[188:189], v[220:221] op_sel:[1,1,0] op_sel_hi:[1,0,1] neg_lo:[1,0,0]
	v_pk_mul_f32 v[222:223], v[212:213], v[186:187] op_sel:[0,0] op_sel_hi:[0,1]
	v_mov_b32_e32 v149, v145
	v_pk_mul_f32 v[144:145], v[148:149], v[184:185] op_sel:[0,0] op_sel_hi:[0,1]
	v_pk_fma_f32 v[142:143], v[142:143], v[218:219], v[164:165] op_sel:[1,1,0] op_sel_hi:[1,0,1] neg_lo:[1,0,0]
	v_pk_mul_f32 v[164:165], v[146:147], v[220:221] op_sel:[0,0] op_sel_hi:[0,1]
	v_add_u32_e32 v85, 0x200, v85
	v_pk_fma_f32 v[222:223], v[212:213], v[186:187], v[222:223] op_sel:[1,1,0] op_sel_hi:[1,0,1] neg_lo:[1,0,0]
	v_pk_mul_f32 v[224:225], v[210:211], v[210:211] op_sel:[0,0] op_sel_hi:[0,1]
	v_pk_mul_f32 v[226:227], v[212:213], v[210:211] op_sel:[0,0] op_sel_hi:[0,1]
	v_pk_fma_f32 v[144:145], v[148:149], v[184:185], v[144:145] op_sel:[1,1,0] op_sel_hi:[1,0,1] neg_lo:[1,0,0]
	v_pk_mul_f32 v[148:149], v[166:167], v[186:187] op_sel:[0,0] op_sel_hi:[0,1]
	v_pk_fma_f32 v[146:147], v[146:147], v[220:221], v[164:165] op_sel:[1,1,0] op_sel_hi:[1,0,1] neg_lo:[1,0,0]
	s_nop 0
	v_pk_mul_f32 v[164:165], v[162:163], v[222:223] op_sel:[0,0] op_sel_hi:[0,1]
	v_and_b32_e32 v98, 0x3ff, v85
	v_lshlrev_b32_e32 v85, 4, v85
	v_mov_b32_e32 v176, v168
	v_mov_b32_e32 v178, v174
	v_pk_fma_f32 v[224:225], v[210:211], v[210:211], v[224:225] op_sel:[1,1,0] op_sel_hi:[1,0,1] neg_lo:[1,0,0]
	v_pk_fma_f32 v[226:227], v[212:213], v[210:211], v[226:227] op_sel:[1,1,0] op_sel_hi:[1,0,1] neg_lo:[1,0,0]
	v_pk_mul_f32 v[228:229], v[170:171], v[160:161] op_sel:[0,0] op_sel_hi:[0,1]
	v_pk_fma_f32 v[148:149], v[166:167], v[186:187], v[148:149] op_sel:[1,1,0] op_sel_hi:[1,0,1] neg_lo:[1,0,0]
	v_pk_fma_f32 v[162:163], v[162:163], v[222:223], v[164:165] op_sel:[1,1,0] op_sel_hi:[1,0,1] neg_lo:[1,0,0]
	v_and_or_b32 v85, v85, s31, v98
	v_pk_fma_f32 v[160:161], v[170:171], v[160:161], v[228:229] op_sel:[1,1,0] op_sel_hi:[1,0,1] neg_lo:[1,0,0]
	v_pk_mul_f32 v[170:171], v[154:155], v[180:181] op_sel:[0,0] op_sel_hi:[0,1]
	v_pk_mul_f32 v[164:165], v[176:177], v[224:225] op_sel:[0,0] op_sel_hi:[0,1]
	v_pk_mul_f32 v[166:167], v[178:179], v[226:227] op_sel:[0,0] op_sel_hi:[0,1]
	v_cvt_f32_u32_e32 v98, v98
	v_pk_fma_f32 v[154:155], v[154:155], v[180:181], v[170:171] op_sel:[1,1,0] op_sel_hi:[1,0,1] neg_lo:[1,0,0]
	v_pk_mul_f32 v[170:171], v[158:159], v[182:183] op_sel:[0,0] op_sel_hi:[0,1]
	v_pk_fma_f32 v[164:165], v[176:177], v[224:225], v[164:165] op_sel:[1,1,0] op_sel_hi:[1,0,1] neg_lo:[1,0,0]
	v_pk_fma_f32 v[166:167], v[178:179], v[226:227], v[166:167] op_sel:[1,1,0] op_sel_hi:[1,0,1] neg_lo:[1,0,0]
	v_mul_f32_e32 v98, 0x38800000, v98
	v_pk_fma_f32 v[158:159], v[158:159], v[182:183], v[170:171] op_sel:[1,1,0] op_sel_hi:[1,0,1] neg_lo:[1,0,0]
	ds_write2st64_b64 v100, v[172:173], v[160:161] offset1:17
	ds_write2st64_b64 v100, v[154:155], v[158:159] offset0:34 offset1:51
	ds_write2st64_b64 v100, v[144:145], v[148:149] offset0:68 offset1:85
	ds_write2st64_b64 v100, v[150:151], v[152:153] offset0:102 offset1:119
	ds_write_b64 v190, v[156:157]
	ds_write_b64 v193, v[138:139]
	ds_write_b64 v195, v[140:141]
	ds_write_b64 v197, v[142:143]
	ds_write_b64 v230, v[146:147]
	ds_write_b64 v231, v[162:163]
	ds_write_b64 v232, v[164:165]
	ds_write_b64 v233, v[166:167]
	v_ashrrev_i32_e32 v100, 4, v85
	v_lshlrev_b32_e32 v100, 3, v100
	v_lshlrev_b32_e32 v85, 3, v85
	v_add3_u32 v85, 0, v100, v85
	ds_read2st64_b64 v[138:141], v85 offset1:17
	ds_read2st64_b64 v[142:145], v85 offset0:34 offset1:51
	ds_read2st64_b64 v[146:149], v85 offset0:68 offset1:85
	ds_read2st64_b64 v[150:153], v85 offset0:102 offset1:119
	v_add_u32_e32 v100, 0x11000, v85
	v_add_u32_e32 v190, 0x13200, v85
	v_add_u32_e32 v193, 0x15400, v85
	v_add_u32_e32 v195, 0x17600, v85
	ds_read_b64 v[154:155], v100
	ds_read_b64 v[156:157], v190
	ds_read_b64 v[158:159], v193
	ds_read_b64 v[160:161], v195
	v_add_u32_e32 v230, 0x1ba00, v85
	v_add_u32_e32 v197, 0x19800, v85
	v_add_u32_e32 v231, 0x1dc00, v85
	v_add_u32_e32 v232, 0x1fe00, v85
	ds_read_b64 v[162:163], v230
	ds_read_b64 v[164:165], v231
	ds_read_b64 v[166:167], v232
	ds_read_b64 v[168:169], v197
	s_waitcnt lgkmcnt(6)
	v_pk_add_f32 v[170:171], v[140:141], v[156:157] neg_lo:[0,1] neg_hi:[0,1]
	s_waitcnt lgkmcnt(3)
	v_pk_add_f32 v[172:173], v[148:149], v[162:163] neg_lo:[0,1] neg_hi:[0,1]
	s_waitcnt lgkmcnt(2)
	v_pk_add_f32 v[176:177], v[150:151], v[164:165] neg_lo:[0,1] neg_hi:[0,1]
	v_pk_add_f32 v[174:175], v[170:171], v[172:173] op_sel:[0,1] op_sel_hi:[1,0]
	v_pk_add_f32 v[170:171], v[170:171], v[172:173] op_sel:[0,1] op_sel_hi:[1,0] neg_lo:[0,1] neg_hi:[0,1]
	v_mov_b32_e32 v172, v174
	v_mov_b32_e32 v173, v171
	v_mov_b32_e32 v171, v175
	v_pk_add_f32 v[174:175], v[142:143], v[158:159] neg_lo:[0,1] neg_hi:[0,1]
	v_pk_add_f32 v[140:141], v[140:141], v[156:157]
	v_pk_add_f32 v[178:179], v[174:175], v[176:177] op_sel:[0,1] op_sel_hi:[1,0]
	v_pk_add_f32 v[174:175], v[174:175], v[176:177] op_sel:[0,1] op_sel_hi:[1,0] neg_lo:[0,1] neg_hi:[0,1]
	v_pk_add_f32 v[148:149], v[148:149], v[162:163]
	v_mov_b32_e32 v176, v178
	v_mov_b32_e32 v177, v175
	v_mov_b32_e32 v175, v179
	v_pk_add_f32 v[178:179], v[144:145], v[160:161] neg_lo:[0,1] neg_hi:[0,1]
	s_waitcnt lgkmcnt(1)
	v_pk_add_f32 v[180:181], v[152:153], v[166:167] neg_lo:[0,1] neg_hi:[0,1]
	v_pk_add_f32 v[156:157], v[140:141], v[148:149]
	v_pk_add_f32 v[140:141], v[140:141], v[148:149] neg_lo:[0,1] neg_hi:[0,1]
	v_pk_add_f32 v[142:143], v[142:143], v[158:159]
	v_pk_add_f32 v[148:149], v[150:151], v[164:165]
	v_pk_add_f32 v[182:183], v[178:179], v[180:181] op_sel:[0,1] op_sel_hi:[1,0]
	v_pk_add_f32 v[178:179], v[178:179], v[180:181] op_sel:[0,1] op_sel_hi:[1,0] neg_lo:[0,1] neg_hi:[0,1]
	v_pk_add_f32 v[150:151], v[142:143], v[148:149]
	v_pk_add_f32 v[142:143], v[142:143], v[148:149] neg_lo:[0,1] neg_hi:[0,1]
	v_pk_add_f32 v[144:145], v[144:145], v[160:161]
	v_pk_add_f32 v[148:149], v[152:153], v[166:167]
	v_mov_b32_e32 v180, v182
	v_mov_b32_e32 v181, v179
	v_mov_b32_e32 v179, v183
	v_pk_mul_f32 v[182:183], v[172:173], v[90:91] op_sel:[0,0] op_sel_hi:[0,1]
	v_pk_add_f32 v[152:153], v[144:145], v[148:149]
	v_pk_add_f32 v[144:145], v[144:145], v[148:149] neg_lo:[0,1] neg_hi:[0,1]
	v_pk_mul_f32 v[148:149], v[140:141], v[88:89] op_sel:[0,0] op_sel_hi:[0,1]
	v_pk_fma_f32 v[172:173], v[172:173], v[90:91], v[182:183] op_sel:[1,1,0] op_sel_hi:[1,0,1] neg_lo:[1,0,0]
	v_pk_mul_f32 v[182:183], v[176:177], v[88:89] op_sel:[0,0] op_sel_hi:[0,1]
	s_waitcnt lgkmcnt(0)
	v_pk_add_f32 v[184:185], v[146:147], v[168:169]
	v_pk_fma_f32 v[140:141], v[140:141], v[88:89], v[148:149] op_sel:[1,1,0] op_sel_hi:[1,0,1] neg_lo:[1,0,0]
	v_pk_mul_f32 v[148:149], v[142:143], v[94:95] op_sel:[0,0] op_sel_hi:[0,1]
	v_pk_fma_f32 v[176:177], v[176:177], v[88:89], v[182:183] op_sel:[1,1,0] op_sel_hi:[1,0,1] neg_lo:[1,0,0]
	v_pk_mul_f32 v[182:183], v[180:181], v[86:87] op_sel:[0,0] op_sel_hi:[0,1]
	v_pk_mul_f32 v[160:161], v[178:179], v[96:97] op_sel:[0,0] op_sel_hi:[0,1]
	v_pk_add_f32 v[164:165], v[156:157], v[152:153]
	v_pk_fma_f32 v[142:143], v[142:143], v[94:95], v[148:149] op_sel:[1,1,0] op_sel_hi:[1,0,1] neg_lo:[1,0,0]
	v_pk_mul_f32 v[148:149], v[144:145], v[92:93] op_sel:[0,0] op_sel_hi:[0,1]
	v_pk_fma_f32 v[180:181], v[180:181], v[86:87], v[182:183] op_sel:[1,1,0] op_sel_hi:[1,0,1] neg_lo:[1,0,0]
	v_pk_add_f32 v[182:183], v[138:139], v[154:155]
	v_pk_fma_f32 v[144:145], v[144:145], v[92:93], v[148:149] op_sel:[1,1,0] op_sel_hi:[1,0,1] neg_lo:[1,0,0]
	v_pk_mul_f32 v[148:149], v[170:171], v[86:87] op_sel:[0,0] op_sel_hi:[0,1]
	v_pk_fma_f32 v[160:161], v[178:179], v[96:97], v[160:161] op_sel:[1,1,0] op_sel_hi:[1,0,1] neg_lo:[1,0,0]
	v_pk_add_f32 v[138:139], v[138:139], v[154:155] neg_lo:[0,1] neg_hi:[0,1]
	v_pk_add_f32 v[186:187], v[182:183], v[184:185]
	v_pk_fma_f32 v[148:149], v[170:171], v[86:87], v[148:149] op_sel:[1,1,0] op_sel_hi:[1,0,1] neg_lo:[1,0,0]
	v_pk_add_f32 v[146:147], v[146:147], v[168:169] neg_lo:[0,1] neg_hi:[0,1]
	v_pk_add_f32 v[162:163], v[186:187], v[150:151]
	v_pk_add_f32 v[178:179], v[148:149], v[160:161] neg_lo:[0,1] neg_hi:[0,1]
	v_pk_add_f32 v[148:149], v[148:149], v[160:161]
	v_cos_f32_e32 v160, v98
	v_sin_f32_e32 v98, v98
	v_pk_mul_f32 v[158:159], v[174:175], v[92:93] op_sel:[0,0] op_sel_hi:[0,1]
	v_pk_add_f32 v[166:167], v[162:163], v[164:165]
	v_pk_add_f32 v[162:163], v[162:163], v[164:165] neg_lo:[0,1] neg_hi:[0,1]
	v_pk_add_f32 v[150:151], v[186:187], v[150:151] neg_lo:[0,1] neg_hi:[0,1]
	v_pk_add_f32 v[152:153], v[156:157], v[152:153] neg_lo:[0,1] neg_hi:[0,1]
	v_pk_add_f32 v[164:165], v[182:183], v[184:185] neg_lo:[0,1] neg_hi:[0,1]
	v_pk_add_f32 v[154:155], v[138:139], v[146:147] op_sel:[0,1] op_sel_hi:[1,0] neg_lo:[0,1] neg_hi:[0,1]
	v_pk_add_f32 v[138:139], v[138:139], v[146:147] op_sel:[0,1] op_sel_hi:[1,0]
	v_pk_add_f32 v[168:169], v[172:173], v[180:181] neg_lo:[0,1] neg_hi:[0,1]
	v_pk_add_f32 v[172:173], v[172:173], v[180:181]
	s_nop 1
	v_pk_fma_f32 v[158:159], v[174:175], v[92:93], v[158:159] op_sel:[1,1,0] op_sel_hi:[1,0,1] neg_lo:[1,0,0]
	v_pk_add_f32 v[156:157], v[150:151], v[152:153] op_sel:[0,1] op_sel_hi:[1,0]
	v_xor_b32_e32 v161, 0x80000000, v98
	v_pk_mul_f32 v[180:181], v[160:161], v[160:161] op_sel:[0,0] op_sel_hi:[0,1]
	v_pk_add_f32 v[150:151], v[150:151], v[152:153] op_sel:[0,1] op_sel_hi:[1,0] neg_lo:[0,1] neg_hi:[0,1]
	v_pk_add_f32 v[170:171], v[164:165], v[142:143] neg_lo:[0,1] neg_hi:[0,1]
	v_pk_add_f32 v[174:175], v[140:141], v[144:145] neg_lo:[0,1] neg_hi:[0,1]
	v_pk_add_f32 v[140:141], v[140:141], v[144:145]
	v_pk_add_f32 v[142:143], v[164:165], v[142:143]
	v_mov_b32_e32 v146, v154
	v_mov_b32_e32 v147, v139
	v_mov_b32_e32 v139, v155
	v_pk_fma_f32 v[180:181], v[160:161], v[160:161], v[180:181] op_sel:[1,1,0] op_sel_hi:[1,0,1] neg_lo:[1,0,0]
	v_mov_b32_e32 v152, v150
	v_pk_mul_f32 v[182:183], v[180:181], v[160:161] op_sel:[0,0] op_sel_hi:[0,1]
	v_pk_mul_f32 v[184:185], v[180:181], v[180:181] op_sel:[0,0] op_sel_hi:[0,1]
	v_mov_b32_e32 v153, v157
	v_pk_add_f32 v[144:145], v[142:143], v[140:141]
	v_pk_add_f32 v[140:141], v[142:143], v[140:141] neg_lo:[0,1] neg_hi:[0,1]
	v_pk_add_f32 v[142:143], v[170:171], v[174:175] op_sel:[0,1] op_sel_hi:[1,0]
	v_pk_add_f32 v[164:165], v[170:171], v[174:175] op_sel:[0,1] op_sel_hi:[1,0] neg_lo:[0,1] neg_hi:[0,1]
	v_pk_add_f32 v[154:155], v[138:139], v[176:177] neg_lo:[0,1] neg_hi:[0,1]
	v_pk_add_f32 v[138:139], v[138:139], v[176:177]
	v_pk_add_f32 v[176:177], v[146:147], v[158:159] neg_lo:[0,1] neg_hi:[0,1]
	v_pk_add_f32 v[146:147], v[146:147], v[158:159]
	v_pk_fma_f32 v[182:183], v[180:181], v[160:161], v[182:183] op_sel:[1,1,0] op_sel_hi:[1,0,1] neg_lo:[1,0,0]
	v_pk_fma_f32 v[184:185], v[180:181], v[180:181], v[184:185] op_sel:[1,1,0] op_sel_hi:[1,0,1] neg_lo:[1,0,0]
	v_mov_b32_e32 v157, v151
	v_pk_mul_f32 v[188:189], v[182:183], v[182:183] op_sel:[0,0] op_sel_hi:[0,1]
	v_pk_mul_f32 v[150:151], v[156:157], v[184:185] op_sel:[0,0] op_sel_hi:[0,1]
	v_mov_b32_e32 v171, v143
	v_pk_add_f32 v[158:159], v[146:147], v[148:149]
	v_pk_add_f32 v[146:147], v[146:147], v[148:149] neg_lo:[0,1] neg_hi:[0,1]
	v_pk_add_f32 v[148:149], v[176:177], v[178:179] op_sel:[0,1] op_sel_hi:[1,0]
	v_pk_add_f32 v[176:177], v[176:177], v[178:179] op_sel:[0,1] op_sel_hi:[1,0] neg_lo:[0,1] neg_hi:[0,1]
	v_pk_fma_f32 v[188:189], v[182:183], v[182:183], v[188:189] op_sel:[1,1,0] op_sel_hi:[1,0,1] neg_lo:[1,0,0]
	v_pk_mul_f32 v[210:211], v[184:185], v[182:183] op_sel:[0,0] op_sel_hi:[0,1]
	v_pk_fma_f32 v[150:151], v[156:157], v[184:185], v[150:151] op_sel:[1,1,0] op_sel_hi:[1,0,1] neg_lo:[1,0,0]
	v_mov_b32_e32 v143, v165
	v_pk_mul_f32 v[156:157], v[142:143], v[188:189] op_sel:[0,0] op_sel_hi:[0,1]
	v_mov_b32_e32 v179, v149
	v_pk_fma_f32 v[210:211], v[184:185], v[182:183], v[210:211] op_sel:[1,1,0] op_sel_hi:[1,0,1] neg_lo:[1,0,0]
	v_pk_mul_f32 v[212:213], v[184:185], v[184:185] op_sel:[0,0] op_sel_hi:[0,1]
	v_pk_fma_f32 v[142:143], v[142:143], v[188:189], v[156:157] op_sel:[1,1,0] op_sel_hi:[1,0,1] neg_lo:[1,0,0]
	v_mov_b32_e32 v149, v177
	v_pk_mul_f32 v[156:157], v[148:149], v[210:211] op_sel:[0,0] op_sel_hi:[0,1]
	v_pk_mul_f32 v[186:187], v[184:185], v[160:161] op_sel:[0,0] op_sel_hi:[0,1]
	v_pk_fma_f32 v[212:213], v[184:185], v[184:185], v[212:213] op_sel:[1,1,0] op_sel_hi:[1,0,1] neg_lo:[1,0,0]
	v_pk_add_f32 v[174:175], v[138:139], v[172:173]
	v_pk_mul_f32 v[214:215], v[212:213], v[160:161] op_sel:[0,0] op_sel_hi:[0,1]
	v_pk_fma_f32 v[148:149], v[148:149], v[210:211], v[156:157] op_sel:[1,1,0] op_sel_hi:[1,0,1] neg_lo:[1,0,0]
	v_pk_mul_f32 v[156:157], v[162:163], v[212:213] op_sel:[0,0] op_sel_hi:[0,1]
	v_pk_add_f32 v[138:139], v[138:139], v[172:173] neg_lo:[0,1] neg_hi:[0,1]
	v_pk_fma_f32 v[186:187], v[184:185], v[160:161], v[186:187] op_sel:[1,1,0] op_sel_hi:[1,0,1] neg_lo:[1,0,0]
	v_pk_fma_f32 v[214:215], v[212:213], v[160:161], v[214:215] op_sel:[1,1,0] op_sel_hi:[1,0,1] neg_lo:[1,0,0]
	v_pk_fma_f32 v[156:157], v[162:163], v[212:213], v[156:157] op_sel:[1,1,0] op_sel_hi:[1,0,1] neg_lo:[1,0,0]
	v_pk_mul_f32 v[218:219], v[212:213], v[182:183] op_sel:[0,0] op_sel_hi:[0,1]
	v_pk_mul_f32 v[220:221], v[188:189], v[188:189] op_sel:[0,0] op_sel_hi:[0,1]
	v_pk_add_f32 v[172:173], v[154:155], v[168:169] op_sel:[0,1] op_sel_hi:[1,0]
	v_pk_mul_f32 v[216:217], v[186:187], v[186:187] op_sel:[0,0] op_sel_hi:[0,1]
	v_pk_mul_f32 v[162:163], v[138:139], v[214:215] op_sel:[0,0] op_sel_hi:[0,1]
	v_pk_fma_f32 v[218:219], v[212:213], v[182:183], v[218:219] op_sel:[1,1,0] op_sel_hi:[1,0,1] neg_lo:[1,0,0]
	v_pk_add_f32 v[154:155], v[154:155], v[168:169] op_sel:[0,1] op_sel_hi:[1,0] neg_lo:[0,1] neg_hi:[0,1]
	v_pk_fma_f32 v[216:217], v[186:187], v[186:187], v[216:217] op_sel:[1,1,0] op_sel_hi:[1,0,1] neg_lo:[1,0,0]
	v_pk_fma_f32 v[138:139], v[138:139], v[214:215], v[162:163] op_sel:[1,1,0] op_sel_hi:[1,0,1] neg_lo:[1,0,0]
	v_pk_fma_f32 v[220:221], v[188:189], v[188:189], v[220:221] op_sel:[1,1,0] op_sel_hi:[1,0,1] neg_lo:[1,0,0]
	v_pk_mul_f32 v[222:223], v[212:213], v[186:187] op_sel:[0,0] op_sel_hi:[0,1]
	v_mov_b32_e32 v169, v173
	v_pk_mul_f32 v[162:163], v[140:141], v[216:217] op_sel:[0,0] op_sel_hi:[0,1]
	v_mov_b32_e32 v168, v154
	v_pk_fma_f32 v[140:141], v[140:141], v[216:217], v[162:163] op_sel:[1,1,0] op_sel_hi:[1,0,1] neg_lo:[1,0,0]
	v_pk_mul_f32 v[162:163], v[146:147], v[218:219] op_sel:[0,0] op_sel_hi:[0,1]
	v_pk_fma_f32 v[222:223], v[212:213], v[186:187], v[222:223] op_sel:[1,1,0] op_sel_hi:[1,0,1] neg_lo:[1,0,0]
	v_pk_mul_f32 v[224:225], v[210:211], v[210:211] op_sel:[0,0] op_sel_hi:[0,1]
	v_pk_mul_f32 v[226:227], v[212:213], v[210:211] op_sel:[0,0] op_sel_hi:[0,1]
	v_mov_b32_e32 v170, v164
	v_pk_fma_f32 v[146:147], v[146:147], v[218:219], v[162:163] op_sel:[1,1,0] op_sel_hi:[1,0,1] neg_lo:[1,0,0]
	v_pk_mul_f32 v[162:163], v[152:153], v[220:221] op_sel:[0,0] op_sel_hi:[0,1]
	v_mov_b32_e32 v178, v176
	v_pk_fma_f32 v[152:153], v[152:153], v[220:221], v[162:163] op_sel:[1,1,0] op_sel_hi:[1,0,1] neg_lo:[1,0,0]
	v_pk_mul_f32 v[162:163], v[168:169], v[222:223] op_sel:[0,0] op_sel_hi:[0,1]
	v_pk_fma_f32 v[224:225], v[210:211], v[210:211], v[224:225] op_sel:[1,1,0] op_sel_hi:[1,0,1] neg_lo:[1,0,0]
	v_pk_fma_f32 v[226:227], v[212:213], v[210:211], v[226:227] op_sel:[1,1,0] op_sel_hi:[1,0,1] neg_lo:[1,0,0]
	v_pk_mul_f32 v[228:229], v[174:175], v[160:161] op_sel:[0,0] op_sel_hi:[0,1]
	v_mov_b32_e32 v173, v155
	v_pk_fma_f32 v[160:161], v[174:175], v[160:161], v[228:229] op_sel:[1,1,0] op_sel_hi:[1,0,1] neg_lo:[1,0,0]
	v_pk_mul_f32 v[174:175], v[144:145], v[180:181] op_sel:[0,0] op_sel_hi:[0,1]
	v_pk_mul_f32 v[154:155], v[172:173], v[186:187] op_sel:[0,0] op_sel_hi:[0,1]
	v_pk_fma_f32 v[162:163], v[168:169], v[222:223], v[162:163] op_sel:[1,1,0] op_sel_hi:[1,0,1] neg_lo:[1,0,0]
	v_pk_mul_f32 v[164:165], v[170:171], v[224:225] op_sel:[0,0] op_sel_hi:[0,1]
	v_pk_mul_f32 v[168:169], v[178:179], v[226:227] op_sel:[0,0] op_sel_hi:[0,1]
	s_movk_i32 s12, 0xfc00
	v_pk_fma_f32 v[144:145], v[144:145], v[180:181], v[174:175] op_sel:[1,1,0] op_sel_hi:[1,0,1] neg_lo:[1,0,0]
	v_pk_mul_f32 v[174:175], v[158:159], v[182:183] op_sel:[0,0] op_sel_hi:[0,1]
	v_pk_fma_f32 v[154:155], v[172:173], v[186:187], v[154:155] op_sel:[1,1,0] op_sel_hi:[1,0,1] neg_lo:[1,0,0]
	v_pk_fma_f32 v[164:165], v[170:171], v[224:225], v[164:165] op_sel:[1,1,0] op_sel_hi:[1,0,1] neg_lo:[1,0,0]
	v_pk_fma_f32 v[168:169], v[178:179], v[226:227], v[168:169] op_sel:[1,1,0] op_sel_hi:[1,0,1] neg_lo:[1,0,0]
	s_mov_b32 s10, 0x3f6c835e
	v_pk_fma_f32 v[158:159], v[158:159], v[182:183], v[174:175] op_sel:[1,1,0] op_sel_hi:[1,0,1] neg_lo:[1,0,0]
	ds_write2st64_b64 v85, v[166:167], v[160:161] offset1:17
	ds_write2st64_b64 v85, v[144:145], v[158:159] offset0:34 offset1:51
	ds_write2st64_b64 v85, v[150:151], v[154:155] offset0:68 offset1:85
	ds_write2st64_b64 v85, v[142:143], v[148:149] offset0:102 offset1:119
	ds_write_b64 v100, v[156:157]
	ds_write_b64 v190, v[138:139]
	ds_write_b64 v193, v[140:141]
	ds_write_b64 v195, v[146:147]
	ds_write_b64 v197, v[152:153]
	ds_write_b64 v230, v[162:163]
	ds_write_b64 v231, v[164:165]
	ds_write_b64 v232, v[168:169]
	v_mov_b32_e32 v85, v0
	s_waitcnt lgkmcnt(0)
	s_barrier
	s_mov_b32 s11, 0x3ec3ef15
	v_and_b32_e32 v98, 63, v85
	v_lshlrev_b32_e32 v85, 4, v85
	v_and_or_b32 v85, v85, s12, v98
	v_cvt_f32_ubyte0_e32 v100, v98
	v_ashrrev_i32_e32 v98, 4, v85
	v_lshlrev_b32_e32 v98, 3, v98
	v_lshlrev_b32_e32 v139, 3, v85
	v_add3_u32 v98, 0, v98, v139
	v_add_u32_e32 v139, 0x800, v98
	v_add_u32_e32 v190, 0x1000, v98
	ds_read2_b64 v[140:143], v98 offset1:68
	ds_read2_b64 v[144:147], v98 offset0:136 offset1:204
	ds_read2_b64 v[148:151], v139 offset0:16 offset1:84
	ds_read2_b64 v[152:155], v190 offset0:32 offset1:100
	v_add_u32_e32 v193, 0x1800, v98
	ds_read2_b64 v[156:159], v193 offset0:48 offset1:116
	ds_read2_b64 v[160:163], v139 offset0:152 offset1:220
	ds_read2_b64 v[164:167], v190 offset0:168 offset1:236
	ds_read2_b64 v[168:171], v193 offset0:184 offset1:252
	v_mul_f32_e32 v100, 0x3a800000, v100
	s_waitcnt lgkmcnt(3)
	v_pk_add_f32 v[174:175], v[150:151], v[158:159] neg_lo:[0,1] neg_hi:[0,1]
	v_pk_add_f32 v[172:173], v[142:143], v[154:155] neg_lo:[0,1] neg_hi:[0,1]
	v_pk_add_f32 v[142:143], v[142:143], v[154:155]
	v_pk_add_f32 v[176:177], v[172:173], v[174:175] op_sel:[0,1] op_sel_hi:[1,0]
	v_pk_add_f32 v[172:173], v[172:173], v[174:175] op_sel:[0,1] op_sel_hi:[1,0] neg_lo:[0,1] neg_hi:[0,1]
	v_mov_b32_e32 v174, v176
	v_mov_b32_e32 v175, v173
	v_mov_b32_e32 v173, v177
	s_waitcnt lgkmcnt(1)
	v_pk_add_f32 v[176:177], v[144:145], v[164:165] neg_lo:[0,1] neg_hi:[0,1]
	s_waitcnt lgkmcnt(0)
	v_pk_add_f32 v[178:179], v[160:161], v[168:169] neg_lo:[0,1] neg_hi:[0,1]
	v_pk_add_f32 v[182:183], v[162:163], v[170:171] neg_lo:[0,1] neg_hi:[0,1]
	v_pk_add_f32 v[180:181], v[176:177], v[178:179] op_sel:[0,1] op_sel_hi:[1,0]
	v_pk_add_f32 v[176:177], v[176:177], v[178:179] op_sel:[0,1] op_sel_hi:[1,0] neg_lo:[0,1] neg_hi:[0,1]
	v_mov_b32_e32 v178, v180
	v_mov_b32_e32 v179, v177
	v_mov_b32_e32 v177, v181
	v_pk_add_f32 v[180:181], v[146:147], v[166:167] neg_lo:[0,1] neg_hi:[0,1]
	v_pk_add_f32 v[150:151], v[150:151], v[158:159]
	v_pk_add_f32 v[184:185], v[180:181], v[182:183] op_sel:[0,1] op_sel_hi:[1,0]
	v_pk_add_f32 v[180:181], v[180:181], v[182:183] op_sel:[0,1] op_sel_hi:[1,0] neg_lo:[0,1] neg_hi:[0,1]
	v_mov_b32_e32 v182, v184
	v_mov_b32_e32 v183, v181
	v_mov_b32_e32 v181, v185
	v_pk_mul_f32 v[184:185], v[174:175], v[90:91] op_sel:[0,0] op_sel_hi:[0,1]
	v_pk_add_f32 v[154:155], v[142:143], v[150:151]
	v_pk_fma_f32 v[174:175], v[174:175], v[90:91], v[184:185] op_sel:[1,1,0] op_sel_hi:[1,0,1] neg_lo:[1,0,0]
	v_pk_mul_f32 v[184:185], v[178:179], v[88:89] op_sel:[0,0] op_sel_hi:[0,1]
	v_pk_add_f32 v[142:143], v[142:143], v[150:151] neg_lo:[0,1] neg_hi:[0,1]
	v_pk_add_f32 v[144:145], v[144:145], v[164:165]
	v_pk_add_f32 v[150:151], v[160:161], v[168:169]
	v_pk_fma_f32 v[178:179], v[178:179], v[88:89], v[184:185] op_sel:[1,1,0] op_sel_hi:[1,0,1] neg_lo:[1,0,0]
	v_pk_mul_f32 v[184:185], v[182:183], v[86:87] op_sel:[0,0] op_sel_hi:[0,1]
	v_pk_add_f32 v[146:147], v[146:147], v[166:167]
	v_pk_add_f32 v[158:159], v[144:145], v[150:151]
	v_pk_add_f32 v[144:145], v[144:145], v[150:151] neg_lo:[0,1] neg_hi:[0,1]
	v_pk_add_f32 v[150:151], v[162:163], v[170:171]
	v_pk_fma_f32 v[182:183], v[182:183], v[86:87], v[184:185] op_sel:[1,1,0] op_sel_hi:[1,0,1] neg_lo:[1,0,0]
	v_pk_add_f32 v[184:185], v[140:141], v[152:153]
	v_pk_add_f32 v[186:187], v[148:149], v[156:157]
	v_pk_add_f32 v[160:161], v[146:147], v[150:151]
	v_pk_add_f32 v[146:147], v[146:147], v[150:151] neg_lo:[0,1] neg_hi:[0,1]
	v_pk_mul_f32 v[150:151], v[142:143], v[88:89] op_sel:[0,0] op_sel_hi:[0,1]
	v_pk_add_f32 v[188:189], v[184:185], v[186:187]
	v_pk_fma_f32 v[142:143], v[142:143], v[88:89], v[150:151] op_sel:[1,1,0] op_sel_hi:[1,0,1] neg_lo:[1,0,0]
	v_pk_mul_f32 v[150:151], v[144:145], v[94:95] op_sel:[0,0] op_sel_hi:[0,1]
	v_cos_f32_e32 v138, v100
	v_sin_f32_e32 v100, v100
	v_pk_fma_f32 v[144:145], v[144:145], v[94:95], v[150:151] op_sel:[1,1,0] op_sel_hi:[1,0,1] neg_lo:[1,0,0]
	v_pk_mul_f32 v[150:151], v[146:147], v[92:93] op_sel:[0,0] op_sel_hi:[0,1]
	v_pk_add_f32 v[166:167], v[188:189], v[158:159]
	v_pk_add_f32 v[168:169], v[154:155], v[160:161]
	v_pk_add_f32 v[140:141], v[140:141], v[152:153] neg_lo:[0,1] neg_hi:[0,1]
	v_pk_add_f32 v[148:149], v[148:149], v[156:157] neg_lo:[0,1] neg_hi:[0,1]
	v_pk_fma_f32 v[146:147], v[146:147], v[92:93], v[150:151] op_sel:[1,1,0] op_sel_hi:[1,0,1] neg_lo:[1,0,0]
	v_pk_mul_f32 v[150:151], v[172:173], v[86:87] op_sel:[0,0] op_sel_hi:[0,1]
	v_pk_mul_f32 v[162:163], v[176:177], v[92:93] op_sel:[0,0] op_sel_hi:[0,1]
	v_pk_add_f32 v[170:171], v[166:167], v[168:169]
	v_pk_add_f32 v[166:167], v[166:167], v[168:169] neg_lo:[0,1] neg_hi:[0,1]
	v_pk_add_f32 v[168:169], v[184:185], v[186:187] neg_lo:[0,1] neg_hi:[0,1]
	v_pk_add_f32 v[152:153], v[140:141], v[148:149] op_sel:[0,1] op_sel_hi:[1,0] neg_lo:[0,1] neg_hi:[0,1]
	v_pk_add_f32 v[140:141], v[140:141], v[148:149] op_sel:[0,1] op_sel_hi:[1,0]
	v_pk_fma_f32 v[150:151], v[172:173], v[86:87], v[150:151] op_sel:[1,1,0] op_sel_hi:[1,0,1] neg_lo:[1,0,0]
	v_pk_fma_f32 v[162:163], v[176:177], v[92:93], v[162:163] op_sel:[1,1,0] op_sel_hi:[1,0,1] neg_lo:[1,0,0]
	v_pk_mul_f32 v[164:165], v[180:181], v[96:97] op_sel:[0,0] op_sel_hi:[0,1]
	v_pk_add_f32 v[172:173], v[168:169], v[144:145] neg_lo:[0,1] neg_hi:[0,1]
	v_pk_add_f32 v[176:177], v[142:143], v[146:147] neg_lo:[0,1] neg_hi:[0,1]
	v_pk_add_f32 v[142:143], v[142:143], v[146:147]
	v_pk_add_f32 v[144:145], v[168:169], v[144:145]
	v_mov_b32_e32 v148, v152
	v_mov_b32_e32 v149, v141
	v_mov_b32_e32 v141, v153
	v_pk_fma_f32 v[164:165], v[180:181], v[96:97], v[164:165] op_sel:[1,1,0] op_sel_hi:[1,0,1] neg_lo:[1,0,0]
	v_pk_add_f32 v[146:147], v[144:145], v[142:143]
	v_pk_add_f32 v[142:143], v[144:145], v[142:143] neg_lo:[0,1] neg_hi:[0,1]
	v_pk_add_f32 v[144:145], v[172:173], v[176:177] op_sel:[0,1] op_sel_hi:[1,0]
	v_pk_add_f32 v[152:153], v[140:141], v[178:179] neg_lo:[0,1] neg_hi:[0,1]
	v_pk_add_f32 v[140:141], v[140:141], v[178:179]
	v_pk_add_f32 v[178:179], v[148:149], v[162:163] neg_lo:[0,1] neg_hi:[0,1]
	v_pk_add_f32 v[180:181], v[150:151], v[164:165] neg_lo:[0,1] neg_hi:[0,1]
	v_pk_add_f32 v[150:151], v[150:151], v[164:165]
	v_pk_add_f32 v[148:149], v[148:149], v[162:163]
	v_pk_add_f32 v[168:169], v[172:173], v[176:177] op_sel:[0,1] op_sel_hi:[1,0] neg_lo:[0,1] neg_hi:[0,1]
	v_mov_b32_e32 v173, v145
	v_pk_add_f32 v[162:163], v[148:149], v[150:151]
	v_pk_add_f32 v[148:149], v[148:149], v[150:151] neg_lo:[0,1] neg_hi:[0,1]
	v_pk_add_f32 v[150:151], v[178:179], v[180:181] op_sel:[0,1] op_sel_hi:[1,0]
	v_pk_add_f32 v[164:165], v[178:179], v[180:181] op_sel:[0,1] op_sel_hi:[1,0] neg_lo:[0,1] neg_hi:[0,1]
	v_mov_b32_e32 v145, v100
	v_mov_b32_e32 v180, v138
	v_pk_add_f32 v[156:157], v[174:175], v[182:183] neg_lo:[0,1] neg_hi:[0,1]
	v_pk_add_f32 v[174:175], v[174:175], v[182:183]
	s_nop 1
	v_pk_add_f32 v[158:159], v[188:189], v[158:159] neg_lo:[0,1] neg_hi:[0,1]
	v_xor_b32_e32 v181, 0x80000000, v145
	v_pk_mul_f32 v[182:183], v[180:181], v[180:181] op_sel:[0,0] op_sel_hi:[0,1]
	v_pk_add_f32 v[154:155], v[154:155], v[160:161] neg_lo:[0,1] neg_hi:[0,1]
	v_pk_fma_f32 v[182:183], v[180:181], v[180:181], v[182:183] op_sel:[1,1,0] op_sel_hi:[1,0,1] neg_lo:[1,0,0]
	v_pk_add_f32 v[176:177], v[140:141], v[174:175]
	v_pk_mul_f32 v[186:187], v[182:183], v[182:183] op_sel:[0,0] op_sel_hi:[0,1]
	v_pk_add_f32 v[160:161], v[158:159], v[154:155] op_sel:[0,1] op_sel_hi:[1,0]
	v_pk_fma_f32 v[186:187], v[182:183], v[182:183], v[186:187] op_sel:[1,1,0] op_sel_hi:[1,0,1] neg_lo:[1,0,0]
	v_pk_add_f32 v[154:155], v[158:159], v[154:155] op_sel:[0,1] op_sel_hi:[1,0] neg_lo:[0,1] neg_hi:[0,1]
	v_pk_mul_f32 v[214:215], v[186:187], v[186:187] op_sel:[0,0] op_sel_hi:[0,1]
	v_pk_mul_f32 v[188:189], v[186:187], v[180:181] op_sel:[0,0] op_sel_hi:[0,1]
	v_pk_add_f32 v[140:141], v[140:141], v[174:175] neg_lo:[0,1] neg_hi:[0,1]
	v_pk_fma_f32 v[214:215], v[186:187], v[186:187], v[214:215] op_sel:[1,1,0] op_sel_hi:[1,0,1] neg_lo:[1,0,0]
	v_mov_b32_e32 v178, v164
	v_pk_mul_f32 v[216:217], v[214:215], v[180:181] op_sel:[0,0] op_sel_hi:[0,1]
	v_mov_b32_e32 v179, v151
	v_pk_mul_f32 v[184:185], v[182:183], v[180:181] op_sel:[0,0] op_sel_hi:[0,1]
	v_pk_fma_f32 v[188:189], v[186:187], v[180:181], v[188:189] op_sel:[1,1,0] op_sel_hi:[1,0,1] neg_lo:[1,0,0]
	v_pk_fma_f32 v[216:217], v[214:215], v[180:181], v[216:217] op_sel:[1,1,0] op_sel_hi:[1,0,1] neg_lo:[1,0,0]
	v_mov_b32_e32 v151, v165
	v_pk_mul_f32 v[218:219], v[188:189], v[188:189] op_sel:[0,0] op_sel_hi:[0,1]
	v_pk_mul_f32 v[164:165], v[140:141], v[216:217] op_sel:[0,0] op_sel_hi:[0,1]
	v_mov_b32_e32 v158, v154
	v_mov_b32_e32 v159, v161
	v_pk_fma_f32 v[184:185], v[182:183], v[180:181], v[184:185] op_sel:[1,1,0] op_sel_hi:[1,0,1] neg_lo:[1,0,0]
	v_pk_fma_f32 v[218:219], v[188:189], v[188:189], v[218:219] op_sel:[1,1,0] op_sel_hi:[1,0,1] neg_lo:[1,0,0]
	v_mov_b32_e32 v161, v155
	v_pk_mul_f32 v[210:211], v[184:185], v[184:185] op_sel:[0,0] op_sel_hi:[0,1]
	v_pk_mul_f32 v[220:221], v[214:215], v[184:185] op_sel:[0,0] op_sel_hi:[0,1]
	v_pk_mul_f32 v[154:155], v[160:161], v[186:187] op_sel:[0,0] op_sel_hi:[0,1]
	v_pk_fma_f32 v[140:141], v[140:141], v[216:217], v[164:165] op_sel:[1,1,0] op_sel_hi:[1,0,1] neg_lo:[1,0,0]
	v_pk_mul_f32 v[164:165], v[142:143], v[218:219] op_sel:[0,0] op_sel_hi:[0,1]
	v_pk_mul_f32 v[212:213], v[186:187], v[184:185] op_sel:[0,0] op_sel_hi:[0,1]
	s_nop 0
	v_pk_fma_f32 v[210:211], v[184:185], v[184:185], v[210:211] op_sel:[1,1,0] op_sel_hi:[1,0,1] neg_lo:[1,0,0]
	v_pk_fma_f32 v[220:221], v[214:215], v[184:185], v[220:221] op_sel:[1,1,0] op_sel_hi:[1,0,1] neg_lo:[1,0,0]
	v_pk_fma_f32 v[154:155], v[160:161], v[186:187], v[154:155] op_sel:[1,1,0] op_sel_hi:[1,0,1] neg_lo:[1,0,0]
	v_mov_b32_e32 v145, v169
	v_pk_mul_f32 v[222:223], v[210:211], v[210:211] op_sel:[0,0] op_sel_hi:[0,1]
	v_pk_mul_f32 v[160:161], v[144:145], v[210:211] op_sel:[0,0] op_sel_hi:[0,1]
	v_pk_fma_f32 v[142:143], v[142:143], v[218:219], v[164:165] op_sel:[1,1,0] op_sel_hi:[1,0,1] neg_lo:[1,0,0]
	v_pk_mul_f32 v[164:165], v[148:149], v[220:221] op_sel:[0,0] op_sel_hi:[0,1]
	v_pk_add_f32 v[174:175], v[152:153], v[156:157] op_sel:[0,1] op_sel_hi:[1,0]
	v_pk_add_f32 v[152:153], v[152:153], v[156:157] op_sel:[0,1] op_sel_hi:[1,0] neg_lo:[0,1] neg_hi:[0,1]
	v_pk_fma_f32 v[212:213], v[186:187], v[184:185], v[212:213] op_sel:[1,1,0] op_sel_hi:[1,0,1] neg_lo:[1,0,0]
	v_pk_fma_f32 v[222:223], v[210:211], v[210:211], v[222:223] op_sel:[1,1,0] op_sel_hi:[1,0,1] neg_lo:[1,0,0]
	v_pk_mul_f32 v[224:225], v[214:215], v[188:189] op_sel:[0,0] op_sel_hi:[0,1]
	v_pk_fma_f32 v[144:145], v[144:145], v[210:211], v[160:161] op_sel:[1,1,0] op_sel_hi:[1,0,1] neg_lo:[1,0,0]
	v_pk_fma_f32 v[148:149], v[148:149], v[220:221], v[164:165] op_sel:[1,1,0] op_sel_hi:[1,0,1] neg_lo:[1,0,0]
	s_nop 0
	v_mov_b32_e32 v156, v152
	v_pk_mul_f32 v[160:161], v[150:151], v[212:213] op_sel:[0,0] op_sel_hi:[0,1]
	v_pk_mul_f32 v[164:165], v[158:159], v[222:223] op_sel:[0,0] op_sel_hi:[0,1]
	v_mov_b32_e32 v157, v175
	v_pk_fma_f32 v[224:225], v[214:215], v[188:189], v[224:225] op_sel:[1,1,0] op_sel_hi:[1,0,1] neg_lo:[1,0,0]
	v_pk_mul_f32 v[226:227], v[212:213], v[212:213] op_sel:[0,0] op_sel_hi:[0,1]
	v_pk_mul_f32 v[228:229], v[214:215], v[212:213] op_sel:[0,0] op_sel_hi:[0,1]
	v_pk_fma_f32 v[150:151], v[150:151], v[212:213], v[160:161] op_sel:[1,1,0] op_sel_hi:[1,0,1] neg_lo:[1,0,0]
	v_pk_mul_f32 v[160:161], v[166:167], v[214:215] op_sel:[0,0] op_sel_hi:[0,1]
	v_pk_fma_f32 v[158:159], v[158:159], v[222:223], v[164:165] op_sel:[1,1,0] op_sel_hi:[1,0,1] neg_lo:[1,0,0]
	s_nop 0
	v_pk_mul_f32 v[164:165], v[156:157], v[224:225] op_sel:[0,0] op_sel_hi:[0,1]
	v_mov_b32_e32 v172, v168
	v_pk_fma_f32 v[226:227], v[212:213], v[212:213], v[226:227] op_sel:[1,1,0] op_sel_hi:[1,0,1] neg_lo:[1,0,0]
	v_pk_fma_f32 v[228:229], v[214:215], v[212:213], v[228:229] op_sel:[1,1,0] op_sel_hi:[1,0,1] neg_lo:[1,0,0]
	v_pk_mul_f32 v[230:231], v[176:177], v[180:181] op_sel:[0,0] op_sel_hi:[0,1]
	v_mov_b32_e32 v175, v153
	v_pk_fma_f32 v[176:177], v[176:177], v[180:181], v[230:231] op_sel:[1,1,0] op_sel_hi:[1,0,1] neg_lo:[1,0,0]
	v_pk_mul_f32 v[180:181], v[146:147], v[182:183] op_sel:[0,0] op_sel_hi:[0,1]
	v_pk_mul_f32 v[152:153], v[174:175], v[188:189] op_sel:[0,0] op_sel_hi:[0,1]
	v_pk_fma_f32 v[160:161], v[166:167], v[214:215], v[160:161] op_sel:[1,1,0] op_sel_hi:[1,0,1] neg_lo:[1,0,0]
	v_pk_fma_f32 v[156:157], v[156:157], v[224:225], v[164:165] op_sel:[1,1,0] op_sel_hi:[1,0,1] neg_lo:[1,0,0]
	v_pk_mul_f32 v[164:165], v[172:173], v[226:227] op_sel:[0,0] op_sel_hi:[0,1]
	v_pk_mul_f32 v[166:167], v[178:179], v[228:229] op_sel:[0,0] op_sel_hi:[0,1]
	v_add_u32_e32 v85, 0x2000, v85
	v_pk_fma_f32 v[146:147], v[146:147], v[182:183], v[180:181] op_sel:[1,1,0] op_sel_hi:[1,0,1] neg_lo:[1,0,0]
	v_pk_mul_f32 v[180:181], v[162:163], v[184:185] op_sel:[0,0] op_sel_hi:[0,1]
	v_pk_fma_f32 v[152:153], v[174:175], v[188:189], v[152:153] op_sel:[1,1,0] op_sel_hi:[1,0,1] neg_lo:[1,0,0]
	v_pk_fma_f32 v[164:165], v[172:173], v[226:227], v[164:165] op_sel:[1,1,0] op_sel_hi:[1,0,1] neg_lo:[1,0,0]
	v_pk_fma_f32 v[166:167], v[178:179], v[228:229], v[166:167] op_sel:[1,1,0] op_sel_hi:[1,0,1] neg_lo:[1,0,0]
	v_readlane_b32 s4, v255, 27
	v_pk_fma_f32 v[162:163], v[162:163], v[184:185], v[180:181] op_sel:[1,1,0] op_sel_hi:[1,0,1] neg_lo:[1,0,0]
	ds_write2_b64 v98, v[170:171], v[176:177] offset1:68
	ds_write2_b64 v98, v[146:147], v[162:163] offset0:136 offset1:204
	ds_write2_b64 v139, v[154:155], v[152:153] offset0:16 offset1:84
	ds_write2_b64 v139, v[144:145], v[150:151] offset0:152 offset1:220
	ds_write2_b64 v190, v[160:161], v[140:141] offset0:32 offset1:100
	ds_write2_b64 v190, v[142:143], v[148:149] offset0:168 offset1:236
	ds_write2_b64 v193, v[158:159], v[156:157] offset0:48 offset1:116
	ds_write2_b64 v193, v[164:165], v[166:167] offset0:184 offset1:252
	v_ashrrev_i32_e32 v98, 4, v85
	v_lshlrev_b32_e32 v98, 3, v98
	v_lshlrev_b32_e32 v85, 3, v85
	v_add3_u32 v85, 0, v98, v85
	v_add_u32_e32 v98, 0x800, v85
	v_add_u32_e32 v190, 0x1000, v85
	ds_read2_b64 v[140:143], v85 offset1:68
	ds_read2_b64 v[144:147], v85 offset0:136 offset1:204
	ds_read2_b64 v[148:151], v98 offset0:16 offset1:84
	ds_read2_b64 v[152:155], v190 offset0:32 offset1:100
	v_add_u32_e32 v193, 0x1800, v85
	ds_read2_b64 v[156:159], v193 offset0:48 offset1:116
	ds_read2_b64 v[160:163], v98 offset0:152 offset1:220
	ds_read2_b64 v[164:167], v190 offset0:168 offset1:236
	ds_read2_b64 v[168:171], v193 offset0:184 offset1:252
	s_nop 1
	s_waitcnt lgkmcnt(3)
	v_pk_add_f32 v[174:175], v[150:151], v[158:159] neg_lo:[0,1] neg_hi:[0,1]
	v_pk_add_f32 v[172:173], v[142:143], v[154:155] neg_lo:[0,1] neg_hi:[0,1]
	v_pk_add_f32 v[142:143], v[142:143], v[154:155]
	v_pk_add_f32 v[176:177], v[172:173], v[174:175] op_sel:[0,1] op_sel_hi:[1,0]
	v_pk_add_f32 v[172:173], v[172:173], v[174:175] op_sel:[0,1] op_sel_hi:[1,0] neg_lo:[0,1] neg_hi:[0,1]
	v_mov_b32_e32 v174, v176
	v_mov_b32_e32 v175, v173
	v_mov_b32_e32 v173, v177
	s_waitcnt lgkmcnt(1)
	v_pk_add_f32 v[176:177], v[144:145], v[164:165] neg_lo:[0,1] neg_hi:[0,1]
	s_waitcnt lgkmcnt(0)
	v_pk_add_f32 v[178:179], v[160:161], v[168:169] neg_lo:[0,1] neg_hi:[0,1]
	v_pk_add_f32 v[182:183], v[162:163], v[170:171] neg_lo:[0,1] neg_hi:[0,1]
	v_pk_add_f32 v[180:181], v[176:177], v[178:179] op_sel:[0,1] op_sel_hi:[1,0]
	v_pk_add_f32 v[176:177], v[176:177], v[178:179] op_sel:[0,1] op_sel_hi:[1,0] neg_lo:[0,1] neg_hi:[0,1]
	v_mov_b32_e32 v178, v180
	v_mov_b32_e32 v179, v177
	v_mov_b32_e32 v177, v181
	v_pk_add_f32 v[180:181], v[146:147], v[166:167] neg_lo:[0,1] neg_hi:[0,1]
	v_pk_add_f32 v[150:151], v[150:151], v[158:159]
	v_pk_add_f32 v[184:185], v[180:181], v[182:183] op_sel:[0,1] op_sel_hi:[1,0]
	v_pk_add_f32 v[180:181], v[180:181], v[182:183] op_sel:[0,1] op_sel_hi:[1,0] neg_lo:[0,1] neg_hi:[0,1]
	v_pk_add_f32 v[154:155], v[142:143], v[150:151]
	v_pk_add_f32 v[142:143], v[142:143], v[150:151] neg_lo:[0,1] neg_hi:[0,1]
	v_pk_add_f32 v[144:145], v[144:145], v[164:165]
	v_pk_add_f32 v[150:151], v[160:161], v[168:169]
	v_mov_b32_e32 v182, v184
	v_mov_b32_e32 v183, v181
	v_mov_b32_e32 v181, v185
	v_pk_mul_f32 v[184:185], v[174:175], v[90:91] op_sel:[0,0] op_sel_hi:[0,1]
	v_pk_add_f32 v[158:159], v[144:145], v[150:151]
	v_pk_add_f32 v[144:145], v[144:145], v[150:151] neg_lo:[0,1] neg_hi:[0,1]
	v_pk_add_f32 v[146:147], v[146:147], v[166:167]
	v_pk_add_f32 v[150:151], v[162:163], v[170:171]
	v_pk_fma_f32 v[174:175], v[174:175], v[90:91], v[184:185] op_sel:[1,1,0] op_sel_hi:[1,0,1] neg_lo:[1,0,0]
	v_pk_mul_f32 v[184:185], v[178:179], v[88:89] op_sel:[0,0] op_sel_hi:[0,1]
	v_pk_add_f32 v[186:187], v[148:149], v[156:157]
	v_pk_add_f32 v[160:161], v[146:147], v[150:151]
	v_pk_add_f32 v[146:147], v[146:147], v[150:151] neg_lo:[0,1] neg_hi:[0,1]
	v_pk_mul_f32 v[150:151], v[142:143], v[88:89] op_sel:[0,0] op_sel_hi:[0,1]
	v_pk_fma_f32 v[178:179], v[178:179], v[88:89], v[184:185] op_sel:[1,1,0] op_sel_hi:[1,0,1] neg_lo:[1,0,0]
	v_pk_mul_f32 v[184:185], v[182:183], v[86:87] op_sel:[0,0] op_sel_hi:[0,1]
	v_pk_add_f32 v[148:149], v[148:149], v[156:157] neg_lo:[0,1] neg_hi:[0,1]
	v_pk_fma_f32 v[142:143], v[142:143], v[88:89], v[150:151] op_sel:[1,1,0] op_sel_hi:[1,0,1] neg_lo:[1,0,0]
	v_pk_mul_f32 v[150:151], v[144:145], v[94:95] op_sel:[0,0] op_sel_hi:[0,1]
	v_pk_fma_f32 v[182:183], v[182:183], v[86:87], v[184:185] op_sel:[1,1,0] op_sel_hi:[1,0,1] neg_lo:[1,0,0]
	v_pk_add_f32 v[184:185], v[140:141], v[152:153]
	v_pk_fma_f32 v[144:145], v[144:145], v[94:95], v[150:151] op_sel:[1,1,0] op_sel_hi:[1,0,1] neg_lo:[1,0,0]
	v_pk_mul_f32 v[150:151], v[146:147], v[92:93] op_sel:[0,0] op_sel_hi:[0,1]
	v_pk_add_f32 v[140:141], v[140:141], v[152:153] neg_lo:[0,1] neg_hi:[0,1]
	v_pk_fma_f32 v[146:147], v[146:147], v[92:93], v[150:151] op_sel:[1,1,0] op_sel_hi:[1,0,1] neg_lo:[1,0,0]
	v_pk_mul_f32 v[150:151], v[172:173], v[86:87] op_sel:[0,0] op_sel_hi:[0,1]
	v_pk_mul_f32 v[162:163], v[176:177], v[92:93] op_sel:[0,0] op_sel_hi:[0,1]
	v_pk_mul_f32 v[164:165], v[180:181], v[96:97] op_sel:[0,0] op_sel_hi:[0,1]
	v_pk_add_f32 v[188:189], v[184:185], v[186:187]
	v_pk_add_f32 v[152:153], v[140:141], v[148:149] op_sel:[0,1] op_sel_hi:[1,0] neg_lo:[0,1] neg_hi:[0,1]
	v_pk_add_f32 v[140:141], v[140:141], v[148:149] op_sel:[0,1] op_sel_hi:[1,0]
	v_pk_fma_f32 v[150:151], v[172:173], v[86:87], v[150:151] op_sel:[1,1,0] op_sel_hi:[1,0,1] neg_lo:[1,0,0]
	v_mov_b32_e32 v148, v152
	v_mov_b32_e32 v149, v141
	v_mov_b32_e32 v141, v153
	v_pk_fma_f32 v[162:163], v[176:177], v[92:93], v[162:163] op_sel:[1,1,0] op_sel_hi:[1,0,1] neg_lo:[1,0,0]
	v_pk_fma_f32 v[164:165], v[180:181], v[96:97], v[164:165] op_sel:[1,1,0] op_sel_hi:[1,0,1] neg_lo:[1,0,0]
	v_pk_add_f32 v[152:153], v[140:141], v[178:179] neg_lo:[0,1] neg_hi:[0,1]
	v_pk_add_f32 v[140:141], v[140:141], v[178:179]
	v_pk_add_f32 v[178:179], v[148:149], v[162:163] neg_lo:[0,1] neg_hi:[0,1]
	v_pk_add_f32 v[180:181], v[150:151], v[164:165] neg_lo:[0,1] neg_hi:[0,1]
	v_pk_add_f32 v[150:151], v[150:151], v[164:165]
	v_pk_add_f32 v[148:149], v[148:149], v[162:163]
	v_pk_add_f32 v[166:167], v[188:189], v[158:159]
	v_pk_add_f32 v[168:169], v[154:155], v[160:161]
	v_pk_add_f32 v[162:163], v[148:149], v[150:151]
	v_pk_add_f32 v[148:149], v[148:149], v[150:151] neg_lo:[0,1] neg_hi:[0,1]
	v_pk_add_f32 v[150:151], v[178:179], v[180:181] op_sel:[0,1] op_sel_hi:[1,0]
	v_pk_add_f32 v[164:165], v[178:179], v[180:181] op_sel:[0,1] op_sel_hi:[1,0] neg_lo:[0,1] neg_hi:[0,1]
	v_xor_b32_e32 v139, 0x80000000, v100
	v_pk_mul_f32 v[180:181], v[138:139], v[138:139] op_sel:[0,0] op_sel_hi:[0,1]
	v_pk_add_f32 v[170:171], v[166:167], v[168:169]
	v_pk_add_f32 v[166:167], v[166:167], v[168:169] neg_lo:[0,1] neg_hi:[0,1]
	v_pk_add_f32 v[168:169], v[184:185], v[186:187] neg_lo:[0,1] neg_hi:[0,1]
	v_pk_fma_f32 v[180:181], v[138:139], v[138:139], v[180:181] op_sel:[1,1,0] op_sel_hi:[1,0,1] neg_lo:[1,0,0]
	v_pk_add_f32 v[158:159], v[188:189], v[158:159] neg_lo:[0,1] neg_hi:[0,1]
	v_pk_mul_f32 v[184:185], v[180:181], v[180:181] op_sel:[0,0] op_sel_hi:[0,1]
	v_pk_add_f32 v[154:155], v[154:155], v[160:161] neg_lo:[0,1] neg_hi:[0,1]
	v_pk_fma_f32 v[184:185], v[180:181], v[180:181], v[184:185] op_sel:[1,1,0] op_sel_hi:[1,0,1] neg_lo:[1,0,0]
	v_pk_add_f32 v[172:173], v[168:169], v[144:145] neg_lo:[0,1] neg_hi:[0,1]
	v_pk_mul_f32 v[212:213], v[184:185], v[184:185] op_sel:[0,0] op_sel_hi:[0,1]
	v_pk_add_f32 v[176:177], v[142:143], v[146:147] neg_lo:[0,1] neg_hi:[0,1]
	v_pk_add_f32 v[142:143], v[142:143], v[146:147]
	v_pk_add_f32 v[144:145], v[168:169], v[144:145]
	v_pk_add_f32 v[156:157], v[174:175], v[182:183] neg_lo:[0,1] neg_hi:[0,1]
	v_pk_add_f32 v[174:175], v[174:175], v[182:183]
	v_pk_mul_f32 v[186:187], v[184:185], v[138:139] op_sel:[0,0] op_sel_hi:[0,1]
	v_pk_fma_f32 v[212:213], v[184:185], v[184:185], v[212:213] op_sel:[1,1,0] op_sel_hi:[1,0,1] neg_lo:[1,0,0]
	v_pk_add_f32 v[160:161], v[158:159], v[154:155] op_sel:[0,1] op_sel_hi:[1,0]
	v_pk_mul_f32 v[214:215], v[212:213], v[138:139] op_sel:[0,0] op_sel_hi:[0,1]
	v_pk_add_f32 v[154:155], v[158:159], v[154:155] op_sel:[0,1] op_sel_hi:[1,0] neg_lo:[0,1] neg_hi:[0,1]
	v_pk_add_f32 v[146:147], v[144:145], v[142:143]
	v_pk_add_f32 v[142:143], v[144:145], v[142:143] neg_lo:[0,1] neg_hi:[0,1]
	v_pk_add_f32 v[144:145], v[172:173], v[176:177] op_sel:[0,1] op_sel_hi:[1,0]
	v_pk_add_f32 v[168:169], v[172:173], v[176:177] op_sel:[0,1] op_sel_hi:[1,0] neg_lo:[0,1] neg_hi:[0,1]
	v_pk_add_f32 v[176:177], v[140:141], v[174:175]
	v_pk_add_f32 v[140:141], v[140:141], v[174:175] neg_lo:[0,1] neg_hi:[0,1]
	v_mov_b32_e32 v178, v164
	v_mov_b32_e32 v179, v151
	v_pk_mul_f32 v[182:183], v[180:181], v[138:139] op_sel:[0,0] op_sel_hi:[0,1]
	v_pk_fma_f32 v[186:187], v[184:185], v[138:139], v[186:187] op_sel:[1,1,0] op_sel_hi:[1,0,1] neg_lo:[1,0,0]
	v_pk_fma_f32 v[214:215], v[212:213], v[138:139], v[214:215] op_sel:[1,1,0] op_sel_hi:[1,0,1] neg_lo:[1,0,0]
	v_mov_b32_e32 v151, v165
	v_pk_mul_f32 v[216:217], v[186:187], v[186:187] op_sel:[0,0] op_sel_hi:[0,1]
	v_pk_mul_f32 v[164:165], v[140:141], v[214:215] op_sel:[0,0] op_sel_hi:[0,1]
	v_mov_b32_e32 v158, v154
	v_mov_b32_e32 v159, v161
	v_pk_fma_f32 v[182:183], v[180:181], v[138:139], v[182:183] op_sel:[1,1,0] op_sel_hi:[1,0,1] neg_lo:[1,0,0]
	v_pk_fma_f32 v[216:217], v[186:187], v[186:187], v[216:217] op_sel:[1,1,0] op_sel_hi:[1,0,1] neg_lo:[1,0,0]
	v_mov_b32_e32 v161, v155
	v_pk_mul_f32 v[188:189], v[182:183], v[182:183] op_sel:[0,0] op_sel_hi:[0,1]
	v_pk_mul_f32 v[218:219], v[212:213], v[182:183] op_sel:[0,0] op_sel_hi:[0,1]
	v_pk_mul_f32 v[154:155], v[160:161], v[184:185] op_sel:[0,0] op_sel_hi:[0,1]
	v_pk_fma_f32 v[140:141], v[140:141], v[214:215], v[164:165] op_sel:[1,1,0] op_sel_hi:[1,0,1] neg_lo:[1,0,0]
	v_pk_mul_f32 v[164:165], v[142:143], v[216:217] op_sel:[0,0] op_sel_hi:[0,1]
	v_mov_b32_e32 v173, v145
	v_pk_fma_f32 v[188:189], v[182:183], v[182:183], v[188:189] op_sel:[1,1,0] op_sel_hi:[1,0,1] neg_lo:[1,0,0]
	v_pk_mul_f32 v[210:211], v[184:185], v[182:183] op_sel:[0,0] op_sel_hi:[0,1]
	v_pk_fma_f32 v[218:219], v[212:213], v[182:183], v[218:219] op_sel:[1,1,0] op_sel_hi:[1,0,1] neg_lo:[1,0,0]
	v_pk_fma_f32 v[154:155], v[160:161], v[184:185], v[154:155] op_sel:[1,1,0] op_sel_hi:[1,0,1] neg_lo:[1,0,0]
	v_mov_b32_e32 v145, v169
	v_pk_mul_f32 v[220:221], v[188:189], v[188:189] op_sel:[0,0] op_sel_hi:[0,1]
	v_pk_mul_f32 v[160:161], v[144:145], v[188:189] op_sel:[0,0] op_sel_hi:[0,1]
	v_pk_fma_f32 v[142:143], v[142:143], v[216:217], v[164:165] op_sel:[1,1,0] op_sel_hi:[1,0,1] neg_lo:[1,0,0]
	v_pk_mul_f32 v[164:165], v[148:149], v[218:219] op_sel:[0,0] op_sel_hi:[0,1]
	v_pk_add_f32 v[174:175], v[152:153], v[156:157] op_sel:[0,1] op_sel_hi:[1,0]
	v_pk_add_f32 v[152:153], v[152:153], v[156:157] op_sel:[0,1] op_sel_hi:[1,0] neg_lo:[0,1] neg_hi:[0,1]
	v_pk_fma_f32 v[210:211], v[184:185], v[182:183], v[210:211] op_sel:[1,1,0] op_sel_hi:[1,0,1] neg_lo:[1,0,0]
	v_pk_fma_f32 v[220:221], v[188:189], v[188:189], v[220:221] op_sel:[1,1,0] op_sel_hi:[1,0,1] neg_lo:[1,0,0]
	v_pk_mul_f32 v[222:223], v[212:213], v[186:187] op_sel:[0,0] op_sel_hi:[0,1]
	v_pk_fma_f32 v[144:145], v[144:145], v[188:189], v[160:161] op_sel:[1,1,0] op_sel_hi:[1,0,1] neg_lo:[1,0,0]
	v_pk_fma_f32 v[148:149], v[148:149], v[218:219], v[164:165] op_sel:[1,1,0] op_sel_hi:[1,0,1] neg_lo:[1,0,0]
	s_nop 0
	v_mov_b32_e32 v156, v152
	v_pk_mul_f32 v[160:161], v[150:151], v[210:211] op_sel:[0,0] op_sel_hi:[0,1]
	v_pk_mul_f32 v[164:165], v[158:159], v[220:221] op_sel:[0,0] op_sel_hi:[0,1]
	v_mov_b32_e32 v157, v175
	v_pk_fma_f32 v[222:223], v[212:213], v[186:187], v[222:223] op_sel:[1,1,0] op_sel_hi:[1,0,1] neg_lo:[1,0,0]
	v_pk_mul_f32 v[224:225], v[210:211], v[210:211] op_sel:[0,0] op_sel_hi:[0,1]
	v_pk_mul_f32 v[226:227], v[212:213], v[210:211] op_sel:[0,0] op_sel_hi:[0,1]
	v_pk_fma_f32 v[150:151], v[150:151], v[210:211], v[160:161] op_sel:[1,1,0] op_sel_hi:[1,0,1] neg_lo:[1,0,0]
	v_pk_mul_f32 v[160:161], v[166:167], v[212:213] op_sel:[0,0] op_sel_hi:[0,1]
	v_pk_fma_f32 v[158:159], v[158:159], v[220:221], v[164:165] op_sel:[1,1,0] op_sel_hi:[1,0,1] neg_lo:[1,0,0]
	s_nop 0
	v_pk_mul_f32 v[164:165], v[156:157], v[222:223] op_sel:[0,0] op_sel_hi:[0,1]
	v_mov_b32_e32 v172, v168
	v_pk_fma_f32 v[224:225], v[210:211], v[210:211], v[224:225] op_sel:[1,1,0] op_sel_hi:[1,0,1] neg_lo:[1,0,0]
	v_pk_fma_f32 v[226:227], v[212:213], v[210:211], v[226:227] op_sel:[1,1,0] op_sel_hi:[1,0,1] neg_lo:[1,0,0]
	v_pk_mul_f32 v[228:229], v[176:177], v[138:139] op_sel:[0,0] op_sel_hi:[0,1]
	v_mov_b32_e32 v175, v153
	v_pk_fma_f32 v[138:139], v[176:177], v[138:139], v[228:229] op_sel:[1,1,0] op_sel_hi:[1,0,1] neg_lo:[1,0,0]
	v_pk_mul_f32 v[176:177], v[146:147], v[180:181] op_sel:[0,0] op_sel_hi:[0,1]
	v_pk_mul_f32 v[152:153], v[174:175], v[186:187] op_sel:[0,0] op_sel_hi:[0,1]
	v_pk_fma_f32 v[160:161], v[166:167], v[212:213], v[160:161] op_sel:[1,1,0] op_sel_hi:[1,0,1] neg_lo:[1,0,0]
	v_pk_fma_f32 v[156:157], v[156:157], v[222:223], v[164:165] op_sel:[1,1,0] op_sel_hi:[1,0,1] neg_lo:[1,0,0]
	v_pk_mul_f32 v[164:165], v[172:173], v[224:225] op_sel:[0,0] op_sel_hi:[0,1]
	v_pk_mul_f32 v[166:167], v[178:179], v[226:227] op_sel:[0,0] op_sel_hi:[0,1]
	s_nop 0
	v_pk_fma_f32 v[146:147], v[146:147], v[180:181], v[176:177] op_sel:[1,1,0] op_sel_hi:[1,0,1] neg_lo:[1,0,0]
	v_pk_mul_f32 v[176:177], v[162:163], v[182:183] op_sel:[0,0] op_sel_hi:[0,1]
	v_pk_fma_f32 v[152:153], v[174:175], v[186:187], v[152:153] op_sel:[1,1,0] op_sel_hi:[1,0,1] neg_lo:[1,0,0]
	v_readlane_b32 s5, v255, 28
	v_pk_fma_f32 v[162:163], v[162:163], v[182:183], v[176:177] op_sel:[1,1,0] op_sel_hi:[1,0,1] neg_lo:[1,0,0]
	v_pk_fma_f32 v[164:165], v[172:173], v[224:225], v[164:165] op_sel:[1,1,0] op_sel_hi:[1,0,1] neg_lo:[1,0,0]
	v_pk_fma_f32 v[166:167], v[178:179], v[226:227], v[166:167] op_sel:[1,1,0] op_sel_hi:[1,0,1] neg_lo:[1,0,0]
	ds_write2_b64 v85, v[170:171], v[138:139] offset1:68
	ds_write2_b64 v85, v[146:147], v[162:163] offset0:136 offset1:204
	ds_write2_b64 v98, v[154:155], v[152:153] offset0:16 offset1:84
	ds_write2_b64 v98, v[144:145], v[150:151] offset0:152 offset1:220
	ds_write2_b64 v190, v[160:161], v[140:141] offset0:32 offset1:100
	ds_write2_b64 v190, v[142:143], v[148:149] offset0:168 offset1:236
	ds_write2_b64 v193, v[158:159], v[156:157] offset0:48 offset1:116
	ds_write2_b64 v193, v[164:165], v[166:167] offset0:184 offset1:252
	v_mov_b32_e32 v85, v0
	s_waitcnt lgkmcnt(0)
	s_barrier
	s_mov_b32 s38, s4
	v_and_b32_e32 v98, 3, v85
	v_lshlrev_b32_e32 v85, 4, v85
	v_and_b32_e32 v85, 0xffffffc0, v85
	v_ashrrev_i32_e32 v139, 1, v85
	v_cvt_f32_ubyte0_e32 v100, v98
	v_add_u32_e32 v139, 0, v139
	v_lshlrev_b32_e32 v140, 3, v85
	v_lshlrev_b32_e32 v98, 3, v98
	v_add3_u32 v139, v139, v140, v98
	ds_read2_b64 v[140:143], v139 offset1:4
	ds_read2_b64 v[144:147], v139 offset0:8 offset1:12
	ds_read2_b64 v[148:151], v139 offset0:17 offset1:21
	ds_read2_b64 v[152:155], v139 offset0:34 offset1:38
	ds_read2_b64 v[156:159], v139 offset0:51 offset1:55
	ds_read2_b64 v[160:163], v139 offset0:25 offset1:29
	ds_read2_b64 v[164:167], v139 offset0:42 offset1:46
	ds_read2_b64 v[168:171], v139 offset0:59 offset1:63
	s_waitcnt lgkmcnt(4)
	v_pk_add_f32 v[172:173], v[142:143], v[154:155] neg_lo:[0,1] neg_hi:[0,1]
	s_waitcnt lgkmcnt(3)
	v_pk_add_f32 v[174:175], v[150:151], v[158:159] neg_lo:[0,1] neg_hi:[0,1]
	v_pk_add_f32 v[142:143], v[142:143], v[154:155]
	v_pk_add_f32 v[176:177], v[172:173], v[174:175] op_sel:[0,1] op_sel_hi:[1,0]
	v_pk_add_f32 v[172:173], v[172:173], v[174:175] op_sel:[0,1] op_sel_hi:[1,0] neg_lo:[0,1] neg_hi:[0,1]
	v_mov_b32_e32 v174, v176
	v_mov_b32_e32 v175, v173
	v_mov_b32_e32 v173, v177
	s_waitcnt lgkmcnt(1)
	v_pk_add_f32 v[176:177], v[144:145], v[164:165] neg_lo:[0,1] neg_hi:[0,1]
	s_waitcnt lgkmcnt(0)
	v_pk_add_f32 v[178:179], v[160:161], v[168:169] neg_lo:[0,1] neg_hi:[0,1]
	v_pk_add_f32 v[182:183], v[162:163], v[170:171] neg_lo:[0,1] neg_hi:[0,1]
	v_pk_add_f32 v[180:181], v[176:177], v[178:179] op_sel:[0,1] op_sel_hi:[1,0]
	v_pk_add_f32 v[176:177], v[176:177], v[178:179] op_sel:[0,1] op_sel_hi:[1,0] neg_lo:[0,1] neg_hi:[0,1]
	v_mov_b32_e32 v178, v180
	v_mov_b32_e32 v179, v177
	v_mov_b32_e32 v177, v181
	v_pk_add_f32 v[180:181], v[146:147], v[166:167] neg_lo:[0,1] neg_hi:[0,1]
	v_pk_add_f32 v[150:151], v[150:151], v[158:159]
	v_pk_add_f32 v[184:185], v[180:181], v[182:183] op_sel:[0,1] op_sel_hi:[1,0]
	v_pk_add_f32 v[180:181], v[180:181], v[182:183] op_sel:[0,1] op_sel_hi:[1,0] neg_lo:[0,1] neg_hi:[0,1]
	v_mov_b32_e32 v182, v184
	v_mov_b32_e32 v183, v181
	v_mov_b32_e32 v181, v185
	v_pk_mul_f32 v[184:185], v[174:175], v[90:91] op_sel:[0,0] op_sel_hi:[0,1]
	v_pk_add_f32 v[154:155], v[142:143], v[150:151]
	v_pk_fma_f32 v[174:175], v[174:175], v[90:91], v[184:185] op_sel:[1,1,0] op_sel_hi:[1,0,1] neg_lo:[1,0,0]
	v_pk_mul_f32 v[184:185], v[178:179], v[88:89] op_sel:[0,0] op_sel_hi:[0,1]
	v_pk_add_f32 v[142:143], v[142:143], v[150:151] neg_lo:[0,1] neg_hi:[0,1]
	v_pk_add_f32 v[144:145], v[144:145], v[164:165]
	v_pk_add_f32 v[150:151], v[160:161], v[168:169]
	v_pk_fma_f32 v[178:179], v[178:179], v[88:89], v[184:185] op_sel:[1,1,0] op_sel_hi:[1,0,1] neg_lo:[1,0,0]
	v_pk_mul_f32 v[184:185], v[182:183], v[86:87] op_sel:[0,0] op_sel_hi:[0,1]
	v_pk_add_f32 v[146:147], v[146:147], v[166:167]
	v_pk_add_f32 v[158:159], v[144:145], v[150:151]
	v_pk_add_f32 v[144:145], v[144:145], v[150:151] neg_lo:[0,1] neg_hi:[0,1]
	v_pk_add_f32 v[150:151], v[162:163], v[170:171]
	v_pk_fma_f32 v[182:183], v[182:183], v[86:87], v[184:185] op_sel:[1,1,0] op_sel_hi:[1,0,1] neg_lo:[1,0,0]
	v_pk_add_f32 v[184:185], v[140:141], v[152:153]
	v_pk_add_f32 v[186:187], v[148:149], v[156:157]
	v_pk_add_f32 v[160:161], v[146:147], v[150:151]
	v_pk_add_f32 v[146:147], v[146:147], v[150:151] neg_lo:[0,1] neg_hi:[0,1]
	v_pk_mul_f32 v[150:151], v[142:143], v[88:89] op_sel:[0,0] op_sel_hi:[0,1]
	v_mul_f32_e32 v100, 0x3c800000, v100
	v_pk_add_f32 v[188:189], v[184:185], v[186:187]
	v_pk_fma_f32 v[142:143], v[142:143], v[88:89], v[150:151] op_sel:[1,1,0] op_sel_hi:[1,0,1] neg_lo:[1,0,0]
	v_pk_mul_f32 v[150:151], v[144:145], v[94:95] op_sel:[0,0] op_sel_hi:[0,1]
	v_cos_f32_e32 v138, v100
	v_sin_f32_e32 v100, v100
	v_pk_fma_f32 v[144:145], v[144:145], v[94:95], v[150:151] op_sel:[1,1,0] op_sel_hi:[1,0,1] neg_lo:[1,0,0]
	v_pk_mul_f32 v[150:151], v[146:147], v[92:93] op_sel:[0,0] op_sel_hi:[0,1]
	v_pk_add_f32 v[166:167], v[188:189], v[158:159]
	v_pk_add_f32 v[168:169], v[154:155], v[160:161]
	v_pk_add_f32 v[140:141], v[140:141], v[152:153] neg_lo:[0,1] neg_hi:[0,1]
	v_pk_add_f32 v[148:149], v[148:149], v[156:157] neg_lo:[0,1] neg_hi:[0,1]
	v_pk_fma_f32 v[146:147], v[146:147], v[92:93], v[150:151] op_sel:[1,1,0] op_sel_hi:[1,0,1] neg_lo:[1,0,0]
	v_pk_mul_f32 v[150:151], v[172:173], v[86:87] op_sel:[0,0] op_sel_hi:[0,1]
	v_pk_mul_f32 v[162:163], v[176:177], v[92:93] op_sel:[0,0] op_sel_hi:[0,1]
	v_pk_add_f32 v[170:171], v[166:167], v[168:169]
	v_pk_add_f32 v[166:167], v[166:167], v[168:169] neg_lo:[0,1] neg_hi:[0,1]
	v_pk_add_f32 v[168:169], v[184:185], v[186:187] neg_lo:[0,1] neg_hi:[0,1]
	v_pk_add_f32 v[152:153], v[140:141], v[148:149] op_sel:[0,1] op_sel_hi:[1,0] neg_lo:[0,1] neg_hi:[0,1]
	v_pk_add_f32 v[140:141], v[140:141], v[148:149] op_sel:[0,1] op_sel_hi:[1,0]
	v_pk_fma_f32 v[150:151], v[172:173], v[86:87], v[150:151] op_sel:[1,1,0] op_sel_hi:[1,0,1] neg_lo:[1,0,0]
	v_pk_fma_f32 v[162:163], v[176:177], v[92:93], v[162:163] op_sel:[1,1,0] op_sel_hi:[1,0,1] neg_lo:[1,0,0]
	v_pk_mul_f32 v[164:165], v[180:181], v[96:97] op_sel:[0,0] op_sel_hi:[0,1]
	v_pk_add_f32 v[172:173], v[168:169], v[144:145] neg_lo:[0,1] neg_hi:[0,1]
	v_pk_add_f32 v[176:177], v[142:143], v[146:147] neg_lo:[0,1] neg_hi:[0,1]
	v_pk_add_f32 v[142:143], v[142:143], v[146:147]
	v_pk_add_f32 v[144:145], v[168:169], v[144:145]
	v_mov_b32_e32 v148, v152
	v_mov_b32_e32 v149, v141
	v_mov_b32_e32 v141, v153
	v_pk_fma_f32 v[164:165], v[180:181], v[96:97], v[164:165] op_sel:[1,1,0] op_sel_hi:[1,0,1] neg_lo:[1,0,0]
	v_pk_add_f32 v[146:147], v[144:145], v[142:143]
	v_pk_add_f32 v[142:143], v[144:145], v[142:143] neg_lo:[0,1] neg_hi:[0,1]
	v_pk_add_f32 v[144:145], v[172:173], v[176:177] op_sel:[0,1] op_sel_hi:[1,0]
	v_pk_add_f32 v[152:153], v[140:141], v[178:179] neg_lo:[0,1] neg_hi:[0,1]
	v_pk_add_f32 v[140:141], v[140:141], v[178:179]
	v_pk_add_f32 v[178:179], v[148:149], v[162:163] neg_lo:[0,1] neg_hi:[0,1]
	v_pk_add_f32 v[180:181], v[150:151], v[164:165] neg_lo:[0,1] neg_hi:[0,1]
	v_pk_add_f32 v[150:151], v[150:151], v[164:165]
	v_pk_add_f32 v[148:149], v[148:149], v[162:163]
	v_pk_add_f32 v[168:169], v[172:173], v[176:177] op_sel:[0,1] op_sel_hi:[1,0] neg_lo:[0,1] neg_hi:[0,1]
	v_mov_b32_e32 v173, v145
	v_pk_add_f32 v[162:163], v[148:149], v[150:151]
	v_pk_add_f32 v[148:149], v[148:149], v[150:151] neg_lo:[0,1] neg_hi:[0,1]
	v_pk_add_f32 v[150:151], v[178:179], v[180:181] op_sel:[0,1] op_sel_hi:[1,0]
	v_pk_add_f32 v[164:165], v[178:179], v[180:181] op_sel:[0,1] op_sel_hi:[1,0] neg_lo:[0,1] neg_hi:[0,1]
	v_mov_b32_e32 v180, v138
	v_mov_b32_e32 v145, v100
	v_pk_add_f32 v[156:157], v[174:175], v[182:183] neg_lo:[0,1] neg_hi:[0,1]
	v_pk_add_f32 v[174:175], v[174:175], v[182:183]
	s_nop 1
	v_pk_add_f32 v[158:159], v[188:189], v[158:159] neg_lo:[0,1] neg_hi:[0,1]
	v_xor_b32_e32 v181, 0x80000000, v145
	v_pk_mul_f32 v[182:183], v[180:181], v[180:181] op_sel:[0,0] op_sel_hi:[0,1]
	v_pk_add_f32 v[154:155], v[154:155], v[160:161] neg_lo:[0,1] neg_hi:[0,1]
	v_pk_fma_f32 v[182:183], v[180:181], v[180:181], v[182:183] op_sel:[1,1,0] op_sel_hi:[1,0,1] neg_lo:[1,0,0]
	v_pk_add_f32 v[176:177], v[140:141], v[174:175]
	v_pk_mul_f32 v[186:187], v[182:183], v[182:183] op_sel:[0,0] op_sel_hi:[0,1]
	v_pk_add_f32 v[160:161], v[158:159], v[154:155] op_sel:[0,1] op_sel_hi:[1,0]
	v_pk_fma_f32 v[186:187], v[182:183], v[182:183], v[186:187] op_sel:[1,1,0] op_sel_hi:[1,0,1] neg_lo:[1,0,0]
	v_pk_add_f32 v[154:155], v[158:159], v[154:155] op_sel:[0,1] op_sel_hi:[1,0] neg_lo:[0,1] neg_hi:[0,1]
	v_pk_mul_f32 v[214:215], v[186:187], v[186:187] op_sel:[0,0] op_sel_hi:[0,1]
	v_pk_mul_f32 v[188:189], v[186:187], v[180:181] op_sel:[0,0] op_sel_hi:[0,1]
	v_pk_add_f32 v[140:141], v[140:141], v[174:175] neg_lo:[0,1] neg_hi:[0,1]
	v_pk_fma_f32 v[214:215], v[186:187], v[186:187], v[214:215] op_sel:[1,1,0] op_sel_hi:[1,0,1] neg_lo:[1,0,0]
	v_mov_b32_e32 v178, v164
	v_pk_mul_f32 v[216:217], v[214:215], v[180:181] op_sel:[0,0] op_sel_hi:[0,1]
	v_mov_b32_e32 v179, v151
	v_pk_mul_f32 v[184:185], v[182:183], v[180:181] op_sel:[0,0] op_sel_hi:[0,1]
	v_pk_fma_f32 v[188:189], v[186:187], v[180:181], v[188:189] op_sel:[1,1,0] op_sel_hi:[1,0,1] neg_lo:[1,0,0]
	v_pk_fma_f32 v[216:217], v[214:215], v[180:181], v[216:217] op_sel:[1,1,0] op_sel_hi:[1,0,1] neg_lo:[1,0,0]
	v_mov_b32_e32 v151, v165
	v_pk_mul_f32 v[218:219], v[188:189], v[188:189] op_sel:[0,0] op_sel_hi:[0,1]
	v_pk_mul_f32 v[164:165], v[140:141], v[216:217] op_sel:[0,0] op_sel_hi:[0,1]
	v_mov_b32_e32 v158, v154
	v_mov_b32_e32 v159, v161
	v_pk_fma_f32 v[184:185], v[182:183], v[180:181], v[184:185] op_sel:[1,1,0] op_sel_hi:[1,0,1] neg_lo:[1,0,0]
	v_pk_fma_f32 v[218:219], v[188:189], v[188:189], v[218:219] op_sel:[1,1,0] op_sel_hi:[1,0,1] neg_lo:[1,0,0]
	v_mov_b32_e32 v161, v155
	v_pk_mul_f32 v[210:211], v[184:185], v[184:185] op_sel:[0,0] op_sel_hi:[0,1]
	v_pk_mul_f32 v[220:221], v[214:215], v[184:185] op_sel:[0,0] op_sel_hi:[0,1]
	v_pk_mul_f32 v[154:155], v[160:161], v[186:187] op_sel:[0,0] op_sel_hi:[0,1]
	v_pk_fma_f32 v[140:141], v[140:141], v[216:217], v[164:165] op_sel:[1,1,0] op_sel_hi:[1,0,1] neg_lo:[1,0,0]
	v_pk_mul_f32 v[164:165], v[142:143], v[218:219] op_sel:[0,0] op_sel_hi:[0,1]
	v_pk_mul_f32 v[212:213], v[186:187], v[184:185] op_sel:[0,0] op_sel_hi:[0,1]
	s_nop 0
	v_pk_fma_f32 v[210:211], v[184:185], v[184:185], v[210:211] op_sel:[1,1,0] op_sel_hi:[1,0,1] neg_lo:[1,0,0]
	v_pk_fma_f32 v[220:221], v[214:215], v[184:185], v[220:221] op_sel:[1,1,0] op_sel_hi:[1,0,1] neg_lo:[1,0,0]
	v_pk_fma_f32 v[154:155], v[160:161], v[186:187], v[154:155] op_sel:[1,1,0] op_sel_hi:[1,0,1] neg_lo:[1,0,0]
	v_mov_b32_e32 v145, v169
	v_pk_mul_f32 v[222:223], v[210:211], v[210:211] op_sel:[0,0] op_sel_hi:[0,1]
	v_pk_mul_f32 v[160:161], v[144:145], v[210:211] op_sel:[0,0] op_sel_hi:[0,1]
	v_pk_fma_f32 v[142:143], v[142:143], v[218:219], v[164:165] op_sel:[1,1,0] op_sel_hi:[1,0,1] neg_lo:[1,0,0]
	v_pk_mul_f32 v[164:165], v[148:149], v[220:221] op_sel:[0,0] op_sel_hi:[0,1]
	v_pk_add_f32 v[174:175], v[152:153], v[156:157] op_sel:[0,1] op_sel_hi:[1,0]
	v_pk_add_f32 v[152:153], v[152:153], v[156:157] op_sel:[0,1] op_sel_hi:[1,0] neg_lo:[0,1] neg_hi:[0,1]
	v_pk_fma_f32 v[212:213], v[186:187], v[184:185], v[212:213] op_sel:[1,1,0] op_sel_hi:[1,0,1] neg_lo:[1,0,0]
	v_pk_fma_f32 v[222:223], v[210:211], v[210:211], v[222:223] op_sel:[1,1,0] op_sel_hi:[1,0,1] neg_lo:[1,0,0]
	v_pk_mul_f32 v[224:225], v[214:215], v[188:189] op_sel:[0,0] op_sel_hi:[0,1]
	v_pk_fma_f32 v[144:145], v[144:145], v[210:211], v[160:161] op_sel:[1,1,0] op_sel_hi:[1,0,1] neg_lo:[1,0,0]
	v_pk_fma_f32 v[148:149], v[148:149], v[220:221], v[164:165] op_sel:[1,1,0] op_sel_hi:[1,0,1] neg_lo:[1,0,0]
	s_nop 0
	v_mov_b32_e32 v156, v152
	v_pk_mul_f32 v[160:161], v[150:151], v[212:213] op_sel:[0,0] op_sel_hi:[0,1]
	v_pk_mul_f32 v[164:165], v[158:159], v[222:223] op_sel:[0,0] op_sel_hi:[0,1]
	v_mov_b32_e32 v157, v175
	v_pk_fma_f32 v[224:225], v[214:215], v[188:189], v[224:225] op_sel:[1,1,0] op_sel_hi:[1,0,1] neg_lo:[1,0,0]
	v_pk_mul_f32 v[226:227], v[212:213], v[212:213] op_sel:[0,0] op_sel_hi:[0,1]
	v_pk_mul_f32 v[228:229], v[214:215], v[212:213] op_sel:[0,0] op_sel_hi:[0,1]
	v_pk_fma_f32 v[150:151], v[150:151], v[212:213], v[160:161] op_sel:[1,1,0] op_sel_hi:[1,0,1] neg_lo:[1,0,0]
	v_pk_mul_f32 v[160:161], v[166:167], v[214:215] op_sel:[0,0] op_sel_hi:[0,1]
	v_pk_fma_f32 v[158:159], v[158:159], v[222:223], v[164:165] op_sel:[1,1,0] op_sel_hi:[1,0,1] neg_lo:[1,0,0]
	s_nop 0
	v_pk_mul_f32 v[164:165], v[156:157], v[224:225] op_sel:[0,0] op_sel_hi:[0,1]
	v_mov_b32_e32 v172, v168
	v_pk_fma_f32 v[226:227], v[212:213], v[212:213], v[226:227] op_sel:[1,1,0] op_sel_hi:[1,0,1] neg_lo:[1,0,0]
	v_pk_fma_f32 v[228:229], v[214:215], v[212:213], v[228:229] op_sel:[1,1,0] op_sel_hi:[1,0,1] neg_lo:[1,0,0]
	v_pk_mul_f32 v[230:231], v[176:177], v[180:181] op_sel:[0,0] op_sel_hi:[0,1]
	v_mov_b32_e32 v175, v153
	v_pk_fma_f32 v[176:177], v[176:177], v[180:181], v[230:231] op_sel:[1,1,0] op_sel_hi:[1,0,1] neg_lo:[1,0,0]
	v_pk_mul_f32 v[180:181], v[146:147], v[182:183] op_sel:[0,0] op_sel_hi:[0,1]
	v_pk_mul_f32 v[152:153], v[174:175], v[188:189] op_sel:[0,0] op_sel_hi:[0,1]
	v_pk_fma_f32 v[160:161], v[166:167], v[214:215], v[160:161] op_sel:[1,1,0] op_sel_hi:[1,0,1] neg_lo:[1,0,0]
	v_pk_fma_f32 v[156:157], v[156:157], v[224:225], v[164:165] op_sel:[1,1,0] op_sel_hi:[1,0,1] neg_lo:[1,0,0]
	v_pk_mul_f32 v[164:165], v[172:173], v[226:227] op_sel:[0,0] op_sel_hi:[0,1]
	v_pk_mul_f32 v[166:167], v[178:179], v[228:229] op_sel:[0,0] op_sel_hi:[0,1]
	v_add_u32_e32 v85, 0x2000, v85
	v_pk_fma_f32 v[146:147], v[146:147], v[182:183], v[180:181] op_sel:[1,1,0] op_sel_hi:[1,0,1] neg_lo:[1,0,0]
	v_pk_mul_f32 v[180:181], v[162:163], v[184:185] op_sel:[0,0] op_sel_hi:[0,1]
	v_pk_fma_f32 v[152:153], v[174:175], v[188:189], v[152:153] op_sel:[1,1,0] op_sel_hi:[1,0,1] neg_lo:[1,0,0]
	v_pk_fma_f32 v[164:165], v[172:173], v[226:227], v[164:165] op_sel:[1,1,0] op_sel_hi:[1,0,1] neg_lo:[1,0,0]
	v_pk_fma_f32 v[166:167], v[178:179], v[228:229], v[166:167] op_sel:[1,1,0] op_sel_hi:[1,0,1] neg_lo:[1,0,0]
	s_mov_b32 s39, s4
	v_pk_fma_f32 v[162:163], v[162:163], v[184:185], v[180:181] op_sel:[1,1,0] op_sel_hi:[1,0,1] neg_lo:[1,0,0]
	ds_write2_b64 v139, v[170:171], v[176:177] offset1:4
	ds_write2_b64 v139, v[146:147], v[162:163] offset0:8 offset1:12
	ds_write2_b64 v139, v[154:155], v[152:153] offset0:17 offset1:21
	ds_write2_b64 v139, v[144:145], v[150:151] offset0:25 offset1:29
	ds_write2_b64 v139, v[160:161], v[140:141] offset0:34 offset1:38
	ds_write2_b64 v139, v[142:143], v[148:149] offset0:42 offset1:46
	ds_write2_b64 v139, v[158:159], v[156:157] offset0:51 offset1:55
	ds_write2_b64 v139, v[164:165], v[166:167] offset0:59 offset1:63
	v_ashrrev_i32_e32 v139, 1, v85
	v_add_u32_e32 v139, 0, v139
	v_lshlrev_b32_e32 v85, 3, v85
	v_add3_u32 v85, v139, v85, v98
	ds_read2_b64 v[140:143], v85 offset1:4
	ds_read2_b64 v[144:147], v85 offset0:8 offset1:12
	ds_read2_b64 v[148:151], v85 offset0:17 offset1:21
	ds_read2_b64 v[152:155], v85 offset0:34 offset1:38
	ds_read2_b64 v[156:159], v85 offset0:51 offset1:55
	ds_read2_b64 v[160:163], v85 offset0:25 offset1:29
	ds_read2_b64 v[164:167], v85 offset0:42 offset1:46
	ds_read2_b64 v[168:171], v85 offset0:59 offset1:63
	s_waitcnt lgkmcnt(4)
	v_pk_add_f32 v[172:173], v[142:143], v[154:155] neg_lo:[0,1] neg_hi:[0,1]
	s_waitcnt lgkmcnt(3)
	v_pk_add_f32 v[174:175], v[150:151], v[158:159] neg_lo:[0,1] neg_hi:[0,1]
	v_pk_add_f32 v[142:143], v[142:143], v[154:155]
	v_pk_add_f32 v[176:177], v[172:173], v[174:175] op_sel:[0,1] op_sel_hi:[1,0]
	v_pk_add_f32 v[172:173], v[172:173], v[174:175] op_sel:[0,1] op_sel_hi:[1,0] neg_lo:[0,1] neg_hi:[0,1]
	v_mov_b32_e32 v174, v176
	v_mov_b32_e32 v175, v173
	v_mov_b32_e32 v173, v177
	s_waitcnt lgkmcnt(1)
	v_pk_add_f32 v[176:177], v[144:145], v[164:165] neg_lo:[0,1] neg_hi:[0,1]
	s_waitcnt lgkmcnt(0)
	v_pk_add_f32 v[178:179], v[160:161], v[168:169] neg_lo:[0,1] neg_hi:[0,1]
	v_pk_add_f32 v[182:183], v[162:163], v[170:171] neg_lo:[0,1] neg_hi:[0,1]
	v_pk_add_f32 v[180:181], v[176:177], v[178:179] op_sel:[0,1] op_sel_hi:[1,0]
	v_pk_add_f32 v[176:177], v[176:177], v[178:179] op_sel:[0,1] op_sel_hi:[1,0] neg_lo:[0,1] neg_hi:[0,1]
	v_mov_b32_e32 v178, v180
	v_mov_b32_e32 v179, v177
	v_mov_b32_e32 v177, v181
	v_pk_add_f32 v[180:181], v[146:147], v[166:167] neg_lo:[0,1] neg_hi:[0,1]
	v_pk_add_f32 v[150:151], v[150:151], v[158:159]
	v_pk_add_f32 v[184:185], v[180:181], v[182:183] op_sel:[0,1] op_sel_hi:[1,0]
	v_pk_add_f32 v[180:181], v[180:181], v[182:183] op_sel:[0,1] op_sel_hi:[1,0] neg_lo:[0,1] neg_hi:[0,1]
	v_pk_add_f32 v[154:155], v[142:143], v[150:151]
	v_pk_add_f32 v[142:143], v[142:143], v[150:151] neg_lo:[0,1] neg_hi:[0,1]
	v_pk_add_f32 v[144:145], v[144:145], v[164:165]
	v_pk_add_f32 v[150:151], v[160:161], v[168:169]
	v_mov_b32_e32 v182, v184
	v_mov_b32_e32 v183, v181
	v_mov_b32_e32 v181, v185
	v_pk_mul_f32 v[184:185], v[174:175], v[90:91] op_sel:[0,0] op_sel_hi:[0,1]
	v_pk_add_f32 v[158:159], v[144:145], v[150:151]
	v_pk_add_f32 v[144:145], v[144:145], v[150:151] neg_lo:[0,1] neg_hi:[0,1]
	v_pk_add_f32 v[146:147], v[146:147], v[166:167]
	v_pk_add_f32 v[150:151], v[162:163], v[170:171]
	v_pk_fma_f32 v[174:175], v[174:175], v[90:91], v[184:185] op_sel:[1,1,0] op_sel_hi:[1,0,1] neg_lo:[1,0,0]
	v_pk_mul_f32 v[184:185], v[178:179], v[88:89] op_sel:[0,0] op_sel_hi:[0,1]
	v_pk_add_f32 v[186:187], v[148:149], v[156:157]
	v_pk_add_f32 v[160:161], v[146:147], v[150:151]
	v_pk_add_f32 v[146:147], v[146:147], v[150:151] neg_lo:[0,1] neg_hi:[0,1]
	v_pk_mul_f32 v[150:151], v[142:143], v[88:89] op_sel:[0,0] op_sel_hi:[0,1]
	v_pk_fma_f32 v[178:179], v[178:179], v[88:89], v[184:185] op_sel:[1,1,0] op_sel_hi:[1,0,1] neg_lo:[1,0,0]
	v_pk_mul_f32 v[184:185], v[182:183], v[86:87] op_sel:[0,0] op_sel_hi:[0,1]
	v_pk_add_f32 v[148:149], v[148:149], v[156:157] neg_lo:[0,1] neg_hi:[0,1]
	v_pk_fma_f32 v[142:143], v[142:143], v[88:89], v[150:151] op_sel:[1,1,0] op_sel_hi:[1,0,1] neg_lo:[1,0,0]
	v_pk_mul_f32 v[150:151], v[144:145], v[94:95] op_sel:[0,0] op_sel_hi:[0,1]
	v_pk_fma_f32 v[182:183], v[182:183], v[86:87], v[184:185] op_sel:[1,1,0] op_sel_hi:[1,0,1] neg_lo:[1,0,0]
	v_pk_add_f32 v[184:185], v[140:141], v[152:153]
	v_pk_fma_f32 v[144:145], v[144:145], v[94:95], v[150:151] op_sel:[1,1,0] op_sel_hi:[1,0,1] neg_lo:[1,0,0]
	v_pk_mul_f32 v[150:151], v[146:147], v[92:93] op_sel:[0,0] op_sel_hi:[0,1]
	v_pk_add_f32 v[140:141], v[140:141], v[152:153] neg_lo:[0,1] neg_hi:[0,1]
	v_pk_fma_f32 v[146:147], v[146:147], v[92:93], v[150:151] op_sel:[1,1,0] op_sel_hi:[1,0,1] neg_lo:[1,0,0]
	v_pk_mul_f32 v[150:151], v[172:173], v[86:87] op_sel:[0,0] op_sel_hi:[0,1]
	v_pk_mul_f32 v[162:163], v[176:177], v[92:93] op_sel:[0,0] op_sel_hi:[0,1]
	v_pk_mul_f32 v[164:165], v[180:181], v[96:97] op_sel:[0,0] op_sel_hi:[0,1]
	v_pk_add_f32 v[188:189], v[184:185], v[186:187]
	v_pk_add_f32 v[152:153], v[140:141], v[148:149] op_sel:[0,1] op_sel_hi:[1,0] neg_lo:[0,1] neg_hi:[0,1]
	v_pk_add_f32 v[140:141], v[140:141], v[148:149] op_sel:[0,1] op_sel_hi:[1,0]
	v_pk_fma_f32 v[150:151], v[172:173], v[86:87], v[150:151] op_sel:[1,1,0] op_sel_hi:[1,0,1] neg_lo:[1,0,0]
	v_mov_b32_e32 v148, v152
	v_mov_b32_e32 v149, v141
	v_mov_b32_e32 v141, v153
	v_pk_fma_f32 v[162:163], v[176:177], v[92:93], v[162:163] op_sel:[1,1,0] op_sel_hi:[1,0,1] neg_lo:[1,0,0]
	v_pk_fma_f32 v[164:165], v[180:181], v[96:97], v[164:165] op_sel:[1,1,0] op_sel_hi:[1,0,1] neg_lo:[1,0,0]
	v_pk_add_f32 v[152:153], v[140:141], v[178:179] neg_lo:[0,1] neg_hi:[0,1]
	v_pk_add_f32 v[140:141], v[140:141], v[178:179]
	v_pk_add_f32 v[178:179], v[148:149], v[162:163] neg_lo:[0,1] neg_hi:[0,1]
	v_pk_add_f32 v[180:181], v[150:151], v[164:165] neg_lo:[0,1] neg_hi:[0,1]
	v_pk_add_f32 v[150:151], v[150:151], v[164:165]
	v_pk_add_f32 v[148:149], v[148:149], v[162:163]
	v_pk_add_f32 v[166:167], v[188:189], v[158:159]
	v_pk_add_f32 v[168:169], v[154:155], v[160:161]
	v_pk_add_f32 v[162:163], v[148:149], v[150:151]
	v_pk_add_f32 v[148:149], v[148:149], v[150:151] neg_lo:[0,1] neg_hi:[0,1]
	v_pk_add_f32 v[150:151], v[178:179], v[180:181] op_sel:[0,1] op_sel_hi:[1,0]
	v_pk_add_f32 v[164:165], v[178:179], v[180:181] op_sel:[0,1] op_sel_hi:[1,0] neg_lo:[0,1] neg_hi:[0,1]
	s_nop 1
	v_pk_add_f32 v[170:171], v[166:167], v[168:169]
	v_xor_b32_e32 v139, 0x80000000, v100
	v_pk_mul_f32 v[180:181], v[138:139], v[138:139] op_sel:[0,0] op_sel_hi:[0,1]
	v_pk_add_f32 v[166:167], v[166:167], v[168:169] neg_lo:[0,1] neg_hi:[0,1]
	v_pk_add_f32 v[168:169], v[184:185], v[186:187] neg_lo:[0,1] neg_hi:[0,1]
	v_pk_fma_f32 v[180:181], v[138:139], v[138:139], v[180:181] op_sel:[1,1,0] op_sel_hi:[1,0,1] neg_lo:[1,0,0]
	v_pk_add_f32 v[158:159], v[188:189], v[158:159] neg_lo:[0,1] neg_hi:[0,1]
	v_pk_mul_f32 v[184:185], v[180:181], v[180:181] op_sel:[0,0] op_sel_hi:[0,1]
	v_pk_add_f32 v[154:155], v[154:155], v[160:161] neg_lo:[0,1] neg_hi:[0,1]
	v_pk_fma_f32 v[184:185], v[180:181], v[180:181], v[184:185] op_sel:[1,1,0] op_sel_hi:[1,0,1] neg_lo:[1,0,0]
	v_pk_add_f32 v[172:173], v[168:169], v[144:145] neg_lo:[0,1] neg_hi:[0,1]
	v_pk_mul_f32 v[212:213], v[184:185], v[184:185] op_sel:[0,0] op_sel_hi:[0,1]
	v_pk_add_f32 v[176:177], v[142:143], v[146:147] neg_lo:[0,1] neg_hi:[0,1]
	v_pk_add_f32 v[142:143], v[142:143], v[146:147]
	v_pk_add_f32 v[144:145], v[168:169], v[144:145]
	v_pk_add_f32 v[156:157], v[174:175], v[182:183] neg_lo:[0,1] neg_hi:[0,1]
	v_pk_add_f32 v[174:175], v[174:175], v[182:183]
	v_pk_mul_f32 v[186:187], v[184:185], v[138:139] op_sel:[0,0] op_sel_hi:[0,1]
	v_pk_fma_f32 v[212:213], v[184:185], v[184:185], v[212:213] op_sel:[1,1,0] op_sel_hi:[1,0,1] neg_lo:[1,0,0]
	v_pk_add_f32 v[160:161], v[158:159], v[154:155] op_sel:[0,1] op_sel_hi:[1,0]
	v_pk_mul_f32 v[214:215], v[212:213], v[138:139] op_sel:[0,0] op_sel_hi:[0,1]
	v_pk_add_f32 v[154:155], v[158:159], v[154:155] op_sel:[0,1] op_sel_hi:[1,0] neg_lo:[0,1] neg_hi:[0,1]
	v_pk_add_f32 v[146:147], v[144:145], v[142:143]
	v_pk_add_f32 v[142:143], v[144:145], v[142:143] neg_lo:[0,1] neg_hi:[0,1]
	v_pk_add_f32 v[144:145], v[172:173], v[176:177] op_sel:[0,1] op_sel_hi:[1,0]
	v_pk_add_f32 v[168:169], v[172:173], v[176:177] op_sel:[0,1] op_sel_hi:[1,0] neg_lo:[0,1] neg_hi:[0,1]
	v_pk_add_f32 v[176:177], v[140:141], v[174:175]
	v_pk_add_f32 v[140:141], v[140:141], v[174:175] neg_lo:[0,1] neg_hi:[0,1]
	v_mov_b32_e32 v178, v164
	v_mov_b32_e32 v179, v151
	v_pk_mul_f32 v[182:183], v[180:181], v[138:139] op_sel:[0,0] op_sel_hi:[0,1]
	v_pk_fma_f32 v[186:187], v[184:185], v[138:139], v[186:187] op_sel:[1,1,0] op_sel_hi:[1,0,1] neg_lo:[1,0,0]
	v_pk_fma_f32 v[214:215], v[212:213], v[138:139], v[214:215] op_sel:[1,1,0] op_sel_hi:[1,0,1] neg_lo:[1,0,0]
	v_mov_b32_e32 v151, v165
	v_pk_mul_f32 v[216:217], v[186:187], v[186:187] op_sel:[0,0] op_sel_hi:[0,1]
	v_pk_mul_f32 v[164:165], v[140:141], v[214:215] op_sel:[0,0] op_sel_hi:[0,1]
	v_mov_b32_e32 v158, v154
	v_mov_b32_e32 v159, v161
	v_pk_fma_f32 v[182:183], v[180:181], v[138:139], v[182:183] op_sel:[1,1,0] op_sel_hi:[1,0,1] neg_lo:[1,0,0]
	v_pk_fma_f32 v[216:217], v[186:187], v[186:187], v[216:217] op_sel:[1,1,0] op_sel_hi:[1,0,1] neg_lo:[1,0,0]
	v_mov_b32_e32 v161, v155
	v_pk_mul_f32 v[188:189], v[182:183], v[182:183] op_sel:[0,0] op_sel_hi:[0,1]
	v_pk_mul_f32 v[218:219], v[212:213], v[182:183] op_sel:[0,0] op_sel_hi:[0,1]
	v_pk_mul_f32 v[154:155], v[160:161], v[184:185] op_sel:[0,0] op_sel_hi:[0,1]
	v_pk_fma_f32 v[140:141], v[140:141], v[214:215], v[164:165] op_sel:[1,1,0] op_sel_hi:[1,0,1] neg_lo:[1,0,0]
	v_pk_mul_f32 v[164:165], v[142:143], v[216:217] op_sel:[0,0] op_sel_hi:[0,1]
	v_mov_b32_e32 v173, v145
	v_pk_fma_f32 v[188:189], v[182:183], v[182:183], v[188:189] op_sel:[1,1,0] op_sel_hi:[1,0,1] neg_lo:[1,0,0]
	v_pk_mul_f32 v[210:211], v[184:185], v[182:183] op_sel:[0,0] op_sel_hi:[0,1]
	v_pk_fma_f32 v[218:219], v[212:213], v[182:183], v[218:219] op_sel:[1,1,0] op_sel_hi:[1,0,1] neg_lo:[1,0,0]
	v_pk_fma_f32 v[154:155], v[160:161], v[184:185], v[154:155] op_sel:[1,1,0] op_sel_hi:[1,0,1] neg_lo:[1,0,0]
	v_mov_b32_e32 v145, v169
	v_pk_mul_f32 v[220:221], v[188:189], v[188:189] op_sel:[0,0] op_sel_hi:[0,1]
	v_pk_mul_f32 v[160:161], v[144:145], v[188:189] op_sel:[0,0] op_sel_hi:[0,1]
	v_pk_fma_f32 v[142:143], v[142:143], v[216:217], v[164:165] op_sel:[1,1,0] op_sel_hi:[1,0,1] neg_lo:[1,0,0]
	v_pk_mul_f32 v[164:165], v[148:149], v[218:219] op_sel:[0,0] op_sel_hi:[0,1]
	v_pk_add_f32 v[174:175], v[152:153], v[156:157] op_sel:[0,1] op_sel_hi:[1,0]
	v_pk_add_f32 v[152:153], v[152:153], v[156:157] op_sel:[0,1] op_sel_hi:[1,0] neg_lo:[0,1] neg_hi:[0,1]
	v_pk_fma_f32 v[210:211], v[184:185], v[182:183], v[210:211] op_sel:[1,1,0] op_sel_hi:[1,0,1] neg_lo:[1,0,0]
	v_pk_fma_f32 v[220:221], v[188:189], v[188:189], v[220:221] op_sel:[1,1,0] op_sel_hi:[1,0,1] neg_lo:[1,0,0]
	v_pk_mul_f32 v[222:223], v[212:213], v[186:187] op_sel:[0,0] op_sel_hi:[0,1]
	v_pk_fma_f32 v[144:145], v[144:145], v[188:189], v[160:161] op_sel:[1,1,0] op_sel_hi:[1,0,1] neg_lo:[1,0,0]
	v_pk_fma_f32 v[148:149], v[148:149], v[218:219], v[164:165] op_sel:[1,1,0] op_sel_hi:[1,0,1] neg_lo:[1,0,0]
	s_nop 0
	v_mov_b32_e32 v156, v152
	v_pk_mul_f32 v[160:161], v[150:151], v[210:211] op_sel:[0,0] op_sel_hi:[0,1]
	v_pk_mul_f32 v[164:165], v[158:159], v[220:221] op_sel:[0,0] op_sel_hi:[0,1]
	v_mov_b32_e32 v157, v175
	v_pk_fma_f32 v[222:223], v[212:213], v[186:187], v[222:223] op_sel:[1,1,0] op_sel_hi:[1,0,1] neg_lo:[1,0,0]
	v_pk_mul_f32 v[224:225], v[210:211], v[210:211] op_sel:[0,0] op_sel_hi:[0,1]
	v_pk_mul_f32 v[226:227], v[212:213], v[210:211] op_sel:[0,0] op_sel_hi:[0,1]
	v_pk_fma_f32 v[150:151], v[150:151], v[210:211], v[160:161] op_sel:[1,1,0] op_sel_hi:[1,0,1] neg_lo:[1,0,0]
	v_pk_mul_f32 v[160:161], v[166:167], v[212:213] op_sel:[0,0] op_sel_hi:[0,1]
	v_pk_fma_f32 v[158:159], v[158:159], v[220:221], v[164:165] op_sel:[1,1,0] op_sel_hi:[1,0,1] neg_lo:[1,0,0]
	s_nop 0
	v_pk_mul_f32 v[164:165], v[156:157], v[222:223] op_sel:[0,0] op_sel_hi:[0,1]
	v_mov_b32_e32 v172, v168
	v_pk_fma_f32 v[224:225], v[210:211], v[210:211], v[224:225] op_sel:[1,1,0] op_sel_hi:[1,0,1] neg_lo:[1,0,0]
	v_pk_fma_f32 v[226:227], v[212:213], v[210:211], v[226:227] op_sel:[1,1,0] op_sel_hi:[1,0,1] neg_lo:[1,0,0]
	v_pk_mul_f32 v[228:229], v[176:177], v[138:139] op_sel:[0,0] op_sel_hi:[0,1]
	v_mov_b32_e32 v175, v153
	v_pk_fma_f32 v[138:139], v[176:177], v[138:139], v[228:229] op_sel:[1,1,0] op_sel_hi:[1,0,1] neg_lo:[1,0,0]
	v_pk_mul_f32 v[176:177], v[146:147], v[180:181] op_sel:[0,0] op_sel_hi:[0,1]
	v_pk_mul_f32 v[152:153], v[174:175], v[186:187] op_sel:[0,0] op_sel_hi:[0,1]
	v_pk_fma_f32 v[160:161], v[166:167], v[212:213], v[160:161] op_sel:[1,1,0] op_sel_hi:[1,0,1] neg_lo:[1,0,0]
	v_pk_fma_f32 v[156:157], v[156:157], v[222:223], v[164:165] op_sel:[1,1,0] op_sel_hi:[1,0,1] neg_lo:[1,0,0]
	v_pk_mul_f32 v[164:165], v[172:173], v[224:225] op_sel:[0,0] op_sel_hi:[0,1]
	v_pk_mul_f32 v[166:167], v[178:179], v[226:227] op_sel:[0,0] op_sel_hi:[0,1]
	s_nop 0
	v_pk_fma_f32 v[146:147], v[146:147], v[180:181], v[176:177] op_sel:[1,1,0] op_sel_hi:[1,0,1] neg_lo:[1,0,0]
	v_pk_mul_f32 v[176:177], v[162:163], v[182:183] op_sel:[0,0] op_sel_hi:[0,1]
	v_pk_fma_f32 v[152:153], v[174:175], v[186:187], v[152:153] op_sel:[1,1,0] op_sel_hi:[1,0,1] neg_lo:[1,0,0]
	s_mov_b32 s4, s11
	v_pk_fma_f32 v[162:163], v[162:163], v[182:183], v[176:177] op_sel:[1,1,0] op_sel_hi:[1,0,1] neg_lo:[1,0,0]
	v_pk_fma_f32 v[164:165], v[172:173], v[224:225], v[164:165] op_sel:[1,1,0] op_sel_hi:[1,0,1] neg_lo:[1,0,0]
	v_pk_fma_f32 v[166:167], v[178:179], v[226:227], v[166:167] op_sel:[1,1,0] op_sel_hi:[1,0,1] neg_lo:[1,0,0]
	ds_write2_b64 v85, v[170:171], v[138:139] offset1:4
	ds_write2_b64 v85, v[146:147], v[162:163] offset0:8 offset1:12
	ds_write2_b64 v85, v[154:155], v[152:153] offset0:17 offset1:21
	ds_write2_b64 v85, v[144:145], v[150:151] offset0:25 offset1:29
	ds_write2_b64 v85, v[160:161], v[140:141] offset0:34 offset1:38
	ds_write2_b64 v85, v[142:143], v[148:149] offset0:42 offset1:46
	ds_write2_b64 v85, v[158:159], v[156:157] offset0:51 offset1:55
	ds_write2_b64 v85, v[164:165], v[166:167] offset0:59 offset1:63
	v_mov_b32_e32 v85, v0
	s_waitcnt lgkmcnt(0)
	s_barrier
	s_waitcnt vmcnt(7)
	v_lshlrev_b32_e32 v146, 16, v62
	v_lshlrev_b32_e32 v98, 1, v85
	v_and_b32_e32 v98, -8, v98
	v_lshlrev_b32_e32 v100, 5, v85
	v_add3_u32 v98, 0, v98, v100
	ds_read2_b64 v[138:141], v98 offset1:1
	ds_read2_b64 v[142:145], v98 offset0:2 offset1:3
	v_and_b32_e32 v147, 0xffff0000, v62
	v_lshlrev_b32_e32 v62, 16, v63
	v_and_b32_e32 v63, 0xffff0000, v63
	v_lshlrev_b32_e32 v148, 16, v64
	s_waitcnt lgkmcnt(0)
	v_pk_add_f32 v[150:151], v[138:139], v[142:143]
	v_pk_add_f32 v[152:153], v[140:141], v[144:145]
	v_pk_add_f32 v[138:139], v[138:139], v[142:143] neg_lo:[0,1] neg_hi:[0,1]
	v_pk_add_f32 v[140:141], v[140:141], v[144:145] neg_lo:[0,1] neg_hi:[0,1]
	v_and_b32_e32 v149, 0xffff0000, v64
	v_pk_add_f32 v[142:143], v[138:139], v[140:141] op_sel:[0,1] op_sel_hi:[1,0]
	v_pk_add_f32 v[138:139], v[138:139], v[140:141] op_sel:[0,1] op_sel_hi:[1,0] neg_lo:[0,1] neg_hi:[0,1]
	v_mov_b32_e32 v141, v143
	v_mov_b32_e32 v140, v138
	v_mov_b32_e32 v143, v139
	v_pk_mul_f32 v[138:139], v[142:143], v[62:63] op_sel:[0,0] op_sel_hi:[0,1]
	v_pk_add_f32 v[154:155], v[150:151], v[152:153]
	v_pk_add_f32 v[150:151], v[150:151], v[152:153] neg_lo:[0,1] neg_hi:[0,1]
	v_pk_fma_f32 v[62:63], v[142:143], v[62:63], v[138:139] op_sel:[1,1,0] op_sel_hi:[1,0,1] neg_lo:[1,0,0]
	v_lshlrev_b32_e32 v64, 16, v65
	v_pk_mul_f32 v[138:139], v[150:151], v[148:149] op_sel:[0,0] op_sel_hi:[0,1]
	v_and_b32_e32 v65, 0xffff0000, v65
	v_pk_mul_f32 v[144:145], v[154:155], v[146:147] op_sel:[0,0] op_sel_hi:[0,1]
	v_pk_fma_f32 v[138:139], v[150:151], v[148:149], v[138:139] op_sel:[1,1,0] op_sel_hi:[1,0,1] neg_lo:[1,0,0]
	v_pk_mul_f32 v[142:143], v[140:141], v[64:65] op_sel:[0,0] op_sel_hi:[0,1]
	s_mov_b32 s5, s10
	v_pk_fma_f32 v[144:145], v[154:155], v[146:147], v[144:145] op_sel:[1,1,0] op_sel_hi:[1,0,1] neg_lo:[1,0,0]
	v_pk_fma_f32 v[64:65], v[140:141], v[64:65], v[142:143] op_sel:[1,1,0] op_sel_hi:[1,0,1] neg_lo:[1,0,0]
	s_nop 0
	v_pk_add_f32 v[140:141], v[144:145], v[138:139]
	v_pk_add_f32 v[142:143], v[62:63], v[64:65]
	v_pk_add_f32 v[138:139], v[144:145], v[138:139] neg_lo:[0,1] neg_hi:[0,1]
	v_pk_add_f32 v[62:63], v[62:63], v[64:65] neg_lo:[0,1] neg_hi:[0,1]
	v_pk_add_f32 v[146:147], v[140:141], v[142:143]
	v_pk_add_f32 v[64:65], v[138:139], v[62:63] op_sel:[0,1] op_sel_hi:[1,0] neg_lo:[0,1] neg_hi:[0,1]
	v_pk_add_f32 v[62:63], v[138:139], v[62:63] op_sel:[0,1] op_sel_hi:[1,0]
	v_pk_add_f32 v[140:141], v[140:141], v[142:143] neg_lo:[0,1] neg_hi:[0,1]
	v_mov_b32_e32 v139, v63
	v_mov_b32_e32 v63, v65
	ds_write2_b64 v98, v[140:141], v[62:63] offset0:2 offset1:3
	v_add_u32_e32 v62, 0x200, v85
	v_lshlrev_b32_e32 v63, 1, v62
	v_mov_b32_e32 v138, v64
	v_and_b32_e32 v63, -8, v63
	v_lshlrev_b32_e32 v62, 5, v62
	ds_write2_b64 v98, v[146:147], v[138:139] offset1:1
	v_add3_u32 v98, 0, v63, v62
	ds_read2_b64 v[62:65], v98 offset1:1
	ds_read2_b64 v[138:141], v98 offset0:2 offset1:3
	s_waitcnt vmcnt(6)
	v_lshlrev_b32_e32 v142, 16, v58
	v_and_b32_e32 v143, 0xffff0000, v58
	v_lshlrev_b32_e32 v58, 16, v59
	v_and_b32_e32 v59, 0xffff0000, v59
	s_waitcnt lgkmcnt(0)
	v_pk_add_f32 v[146:147], v[62:63], v[138:139]
	v_pk_add_f32 v[148:149], v[64:65], v[140:141]
	v_pk_add_f32 v[62:63], v[62:63], v[138:139] neg_lo:[0,1] neg_hi:[0,1]
	v_pk_add_f32 v[64:65], v[64:65], v[140:141] neg_lo:[0,1] neg_hi:[0,1]
	v_lshlrev_b32_e32 v144, 16, v60
	v_pk_add_f32 v[138:139], v[62:63], v[64:65] op_sel:[0,1] op_sel_hi:[1,0]
	v_pk_add_f32 v[62:63], v[62:63], v[64:65] op_sel:[0,1] op_sel_hi:[1,0] neg_lo:[0,1] neg_hi:[0,1]
	v_mov_b32_e32 v65, v139
	v_mov_b32_e32 v64, v62
	v_mov_b32_e32 v139, v63
	v_pk_mul_f32 v[62:63], v[138:139], v[58:59] op_sel:[0,0] op_sel_hi:[0,1]
	v_and_b32_e32 v145, 0xffff0000, v60
	v_pk_add_f32 v[150:151], v[146:147], v[148:149]
	v_pk_add_f32 v[146:147], v[146:147], v[148:149] neg_lo:[0,1] neg_hi:[0,1]
	v_pk_fma_f32 v[58:59], v[138:139], v[58:59], v[62:63] op_sel:[1,1,0] op_sel_hi:[1,0,1] neg_lo:[1,0,0]
	v_lshlrev_b32_e32 v60, 16, v61
	v_pk_mul_f32 v[62:63], v[146:147], v[144:145] op_sel:[0,0] op_sel_hi:[0,1]
	v_and_b32_e32 v61, 0xffff0000, v61
	v_pk_mul_f32 v[140:141], v[150:151], v[142:143] op_sel:[0,0] op_sel_hi:[0,1]
	v_pk_fma_f32 v[62:63], v[146:147], v[144:145], v[62:63] op_sel:[1,1,0] op_sel_hi:[1,0,1] neg_lo:[1,0,0]
	v_pk_mul_f32 v[138:139], v[64:65], v[60:61] op_sel:[0,0] op_sel_hi:[0,1]
	s_nop 0
	v_pk_fma_f32 v[140:141], v[150:151], v[142:143], v[140:141] op_sel:[1,1,0] op_sel_hi:[1,0,1] neg_lo:[1,0,0]
	v_pk_fma_f32 v[60:61], v[64:65], v[60:61], v[138:139] op_sel:[1,1,0] op_sel_hi:[1,0,1] neg_lo:[1,0,0]
	s_nop 0
	v_pk_add_f32 v[64:65], v[140:141], v[62:63]
	v_pk_add_f32 v[138:139], v[58:59], v[60:61]
	v_pk_add_f32 v[62:63], v[140:141], v[62:63] neg_lo:[0,1] neg_hi:[0,1]
	v_pk_add_f32 v[58:59], v[58:59], v[60:61] neg_lo:[0,1] neg_hi:[0,1]
	v_pk_add_f32 v[142:143], v[64:65], v[138:139]
	v_pk_add_f32 v[60:61], v[62:63], v[58:59] op_sel:[0,1] op_sel_hi:[1,0] neg_lo:[0,1] neg_hi:[0,1]
	v_pk_add_f32 v[58:59], v[62:63], v[58:59] op_sel:[0,1] op_sel_hi:[1,0]
	v_pk_add_f32 v[64:65], v[64:65], v[138:139] neg_lo:[0,1] neg_hi:[0,1]
	v_mov_b32_e32 v63, v59
	v_mov_b32_e32 v59, v61
	ds_write2_b64 v98, v[64:65], v[58:59] offset0:2 offset1:3
	v_add_u32_e32 v58, 0x400, v85
	v_lshlrev_b32_e32 v59, 1, v58
	v_mov_b32_e32 v62, v60
	v_and_b32_e32 v59, -8, v59
	v_lshlrev_b32_e32 v58, 5, v58
	ds_write2_b64 v98, v[142:143], v[62:63] offset1:1
	v_add3_u32 v98, 0, v59, v58
	ds_read2_b64 v[58:61], v98 offset1:1
	ds_read2_b64 v[62:65], v98 offset0:2 offset1:3
	s_waitcnt vmcnt(5)
	v_lshlrev_b32_e32 v138, 16, v54
	v_and_b32_e32 v139, 0xffff0000, v54
	v_lshlrev_b32_e32 v54, 16, v55
	v_and_b32_e32 v55, 0xffff0000, v55
	s_waitcnt lgkmcnt(0)
	v_pk_add_f32 v[142:143], v[58:59], v[62:63]
	v_pk_add_f32 v[144:145], v[60:61], v[64:65]
	v_pk_add_f32 v[58:59], v[58:59], v[62:63] neg_lo:[0,1] neg_hi:[0,1]
	v_pk_add_f32 v[60:61], v[60:61], v[64:65] neg_lo:[0,1] neg_hi:[0,1]
	v_lshlrev_b32_e32 v140, 16, v56
	v_pk_add_f32 v[62:63], v[58:59], v[60:61] op_sel:[0,1] op_sel_hi:[1,0]
	v_pk_add_f32 v[58:59], v[58:59], v[60:61] op_sel:[0,1] op_sel_hi:[1,0] neg_lo:[0,1] neg_hi:[0,1]
	v_mov_b32_e32 v61, v63
	v_mov_b32_e32 v60, v58
	v_mov_b32_e32 v63, v59
	v_pk_mul_f32 v[58:59], v[62:63], v[54:55] op_sel:[0,0] op_sel_hi:[0,1]
	v_and_b32_e32 v141, 0xffff0000, v56
	v_pk_add_f32 v[146:147], v[142:143], v[144:145]
	v_pk_add_f32 v[142:143], v[142:143], v[144:145] neg_lo:[0,1] neg_hi:[0,1]
	v_pk_fma_f32 v[54:55], v[62:63], v[54:55], v[58:59] op_sel:[1,1,0] op_sel_hi:[1,0,1] neg_lo:[1,0,0]
	v_lshlrev_b32_e32 v56, 16, v57
	v_pk_mul_f32 v[58:59], v[142:143], v[140:141] op_sel:[0,0] op_sel_hi:[0,1]
	v_and_b32_e32 v57, 0xffff0000, v57
	v_pk_mul_f32 v[64:65], v[146:147], v[138:139] op_sel:[0,0] op_sel_hi:[0,1]
	v_pk_fma_f32 v[58:59], v[142:143], v[140:141], v[58:59] op_sel:[1,1,0] op_sel_hi:[1,0,1] neg_lo:[1,0,0]
	v_pk_mul_f32 v[62:63], v[60:61], v[56:57] op_sel:[0,0] op_sel_hi:[0,1]
	s_nop 0
	v_pk_fma_f32 v[64:65], v[146:147], v[138:139], v[64:65] op_sel:[1,1,0] op_sel_hi:[1,0,1] neg_lo:[1,0,0]
	v_pk_fma_f32 v[56:57], v[60:61], v[56:57], v[62:63] op_sel:[1,1,0] op_sel_hi:[1,0,1] neg_lo:[1,0,0]
	s_nop 0
	v_pk_add_f32 v[60:61], v[64:65], v[58:59]
	v_pk_add_f32 v[62:63], v[54:55], v[56:57]
	v_pk_add_f32 v[58:59], v[64:65], v[58:59] neg_lo:[0,1] neg_hi:[0,1]
	v_pk_add_f32 v[54:55], v[54:55], v[56:57] neg_lo:[0,1] neg_hi:[0,1]
	v_pk_add_f32 v[138:139], v[60:61], v[62:63]
	v_pk_add_f32 v[56:57], v[58:59], v[54:55] op_sel:[0,1] op_sel_hi:[1,0] neg_lo:[0,1] neg_hi:[0,1]
	v_pk_add_f32 v[54:55], v[58:59], v[54:55] op_sel:[0,1] op_sel_hi:[1,0]
	v_pk_add_f32 v[60:61], v[60:61], v[62:63] neg_lo:[0,1] neg_hi:[0,1]
	v_mov_b32_e32 v59, v55
	v_mov_b32_e32 v55, v57
	ds_write2_b64 v98, v[60:61], v[54:55] offset0:2 offset1:3
	v_add_u32_e32 v54, 0x600, v85
	v_lshlrev_b32_e32 v55, 1, v54
	v_mov_b32_e32 v58, v56
	v_and_b32_e32 v55, -8, v55
	v_lshlrev_b32_e32 v54, 5, v54
	ds_write2_b64 v98, v[138:139], v[58:59] offset1:1
	v_add3_u32 v98, 0, v55, v54
	ds_read2_b64 v[54:57], v98 offset1:1
	ds_read2_b64 v[58:61], v98 offset0:2 offset1:3
	s_waitcnt vmcnt(4)
	v_lshlrev_b32_e32 v62, 16, v50
	v_and_b32_e32 v63, 0xffff0000, v50
	v_lshlrev_b32_e32 v50, 16, v51
	v_and_b32_e32 v51, 0xffff0000, v51
	s_waitcnt lgkmcnt(0)
	v_pk_add_f32 v[138:139], v[54:55], v[58:59]
	v_pk_add_f32 v[140:141], v[56:57], v[60:61]
	v_pk_add_f32 v[54:55], v[54:55], v[58:59] neg_lo:[0,1] neg_hi:[0,1]
	v_pk_add_f32 v[56:57], v[56:57], v[60:61] neg_lo:[0,1] neg_hi:[0,1]
	v_lshlrev_b32_e32 v64, 16, v52
	v_pk_add_f32 v[58:59], v[54:55], v[56:57] op_sel:[0,1] op_sel_hi:[1,0]
	v_pk_add_f32 v[54:55], v[54:55], v[56:57] op_sel:[0,1] op_sel_hi:[1,0] neg_lo:[0,1] neg_hi:[0,1]
	v_mov_b32_e32 v57, v59
	v_mov_b32_e32 v56, v54
	v_mov_b32_e32 v59, v55
	v_pk_mul_f32 v[54:55], v[58:59], v[50:51] op_sel:[0,0] op_sel_hi:[0,1]
	v_and_b32_e32 v65, 0xffff0000, v52
	v_pk_add_f32 v[142:143], v[138:139], v[140:141]
	v_pk_add_f32 v[138:139], v[138:139], v[140:141] neg_lo:[0,1] neg_hi:[0,1]
	v_pk_fma_f32 v[50:51], v[58:59], v[50:51], v[54:55] op_sel:[1,1,0] op_sel_hi:[1,0,1] neg_lo:[1,0,0]
	v_lshlrev_b32_e32 v52, 16, v53
	v_pk_mul_f32 v[54:55], v[138:139], v[64:65] op_sel:[0,0] op_sel_hi:[0,1]
	v_and_b32_e32 v53, 0xffff0000, v53
	v_pk_mul_f32 v[60:61], v[142:143], v[62:63] op_sel:[0,0] op_sel_hi:[0,1]
	v_pk_fma_f32 v[54:55], v[138:139], v[64:65], v[54:55] op_sel:[1,1,0] op_sel_hi:[1,0,1] neg_lo:[1,0,0]
	v_pk_mul_f32 v[58:59], v[56:57], v[52:53] op_sel:[0,0] op_sel_hi:[0,1]
	s_nop 0
	v_pk_fma_f32 v[60:61], v[142:143], v[62:63], v[60:61] op_sel:[1,1,0] op_sel_hi:[1,0,1] neg_lo:[1,0,0]
	v_pk_fma_f32 v[52:53], v[56:57], v[52:53], v[58:59] op_sel:[1,1,0] op_sel_hi:[1,0,1] neg_lo:[1,0,0]
	s_nop 0
	v_pk_add_f32 v[56:57], v[60:61], v[54:55]
	v_pk_add_f32 v[58:59], v[50:51], v[52:53]
	v_pk_add_f32 v[54:55], v[60:61], v[54:55] neg_lo:[0,1] neg_hi:[0,1]
	v_pk_add_f32 v[50:51], v[50:51], v[52:53] neg_lo:[0,1] neg_hi:[0,1]
	v_pk_add_f32 v[62:63], v[56:57], v[58:59]
	v_pk_add_f32 v[52:53], v[54:55], v[50:51] op_sel:[0,1] op_sel_hi:[1,0] neg_lo:[0,1] neg_hi:[0,1]
	v_pk_add_f32 v[50:51], v[54:55], v[50:51] op_sel:[0,1] op_sel_hi:[1,0]
	v_pk_add_f32 v[56:57], v[56:57], v[58:59] neg_lo:[0,1] neg_hi:[0,1]
	v_mov_b32_e32 v55, v51
	v_mov_b32_e32 v51, v53
	ds_write2_b64 v98, v[56:57], v[50:51] offset0:2 offset1:3
	v_add_u32_e32 v50, 0x800, v85
	v_lshlrev_b32_e32 v51, 1, v50
	v_mov_b32_e32 v54, v52
	v_and_b32_e32 v51, -8, v51
	v_lshlrev_b32_e32 v50, 5, v50
	ds_write2_b64 v98, v[62:63], v[54:55] offset1:1
	v_add3_u32 v98, 0, v51, v50
	ds_read2_b64 v[50:53], v98 offset1:1
	ds_read2_b64 v[54:57], v98 offset0:2 offset1:3
	s_waitcnt vmcnt(3)
	v_lshlrev_b32_e32 v58, 16, v46
	v_and_b32_e32 v59, 0xffff0000, v46
	v_lshlrev_b32_e32 v46, 16, v47
	v_and_b32_e32 v47, 0xffff0000, v47
	s_waitcnt lgkmcnt(0)
	v_pk_add_f32 v[62:63], v[50:51], v[54:55]
	v_pk_add_f32 v[64:65], v[52:53], v[56:57]
	v_pk_add_f32 v[50:51], v[50:51], v[54:55] neg_lo:[0,1] neg_hi:[0,1]
	v_pk_add_f32 v[52:53], v[52:53], v[56:57] neg_lo:[0,1] neg_hi:[0,1]
	v_lshlrev_b32_e32 v60, 16, v48
	v_pk_add_f32 v[54:55], v[50:51], v[52:53] op_sel:[0,1] op_sel_hi:[1,0]
	v_pk_add_f32 v[50:51], v[50:51], v[52:53] op_sel:[0,1] op_sel_hi:[1,0] neg_lo:[0,1] neg_hi:[0,1]
	v_mov_b32_e32 v53, v55
	v_mov_b32_e32 v52, v50
	v_mov_b32_e32 v55, v51
	v_pk_mul_f32 v[50:51], v[54:55], v[46:47] op_sel:[0,0] op_sel_hi:[0,1]
	v_and_b32_e32 v61, 0xffff0000, v48
	v_pk_add_f32 v[138:139], v[62:63], v[64:65]
	v_pk_add_f32 v[62:63], v[62:63], v[64:65] neg_lo:[0,1] neg_hi:[0,1]
	v_pk_fma_f32 v[46:47], v[54:55], v[46:47], v[50:51] op_sel:[1,1,0] op_sel_hi:[1,0,1] neg_lo:[1,0,0]
	v_lshlrev_b32_e32 v48, 16, v49
	v_pk_mul_f32 v[50:51], v[62:63], v[60:61] op_sel:[0,0] op_sel_hi:[0,1]
	v_and_b32_e32 v49, 0xffff0000, v49
	v_pk_mul_f32 v[56:57], v[138:139], v[58:59] op_sel:[0,0] op_sel_hi:[0,1]
	v_pk_fma_f32 v[50:51], v[62:63], v[60:61], v[50:51] op_sel:[1,1,0] op_sel_hi:[1,0,1] neg_lo:[1,0,0]
	v_pk_mul_f32 v[54:55], v[52:53], v[48:49] op_sel:[0,0] op_sel_hi:[0,1]
	s_nop 0
	v_pk_fma_f32 v[56:57], v[138:139], v[58:59], v[56:57] op_sel:[1,1,0] op_sel_hi:[1,0,1] neg_lo:[1,0,0]
	v_pk_fma_f32 v[48:49], v[52:53], v[48:49], v[54:55] op_sel:[1,1,0] op_sel_hi:[1,0,1] neg_lo:[1,0,0]
	s_nop 0
	v_pk_add_f32 v[52:53], v[56:57], v[50:51]
	v_pk_add_f32 v[54:55], v[46:47], v[48:49]
	v_pk_add_f32 v[50:51], v[56:57], v[50:51] neg_lo:[0,1] neg_hi:[0,1]
	v_pk_add_f32 v[46:47], v[46:47], v[48:49] neg_lo:[0,1] neg_hi:[0,1]
	v_pk_add_f32 v[58:59], v[52:53], v[54:55]
	v_pk_add_f32 v[48:49], v[50:51], v[46:47] op_sel:[0,1] op_sel_hi:[1,0] neg_lo:[0,1] neg_hi:[0,1]
	v_pk_add_f32 v[46:47], v[50:51], v[46:47] op_sel:[0,1] op_sel_hi:[1,0]
	v_pk_add_f32 v[52:53], v[52:53], v[54:55] neg_lo:[0,1] neg_hi:[0,1]
	v_mov_b32_e32 v51, v47
	v_mov_b32_e32 v47, v49
	ds_write2_b64 v98, v[52:53], v[46:47] offset0:2 offset1:3
	v_add_u32_e32 v46, 0xa00, v85
	v_lshlrev_b32_e32 v47, 1, v46
	v_mov_b32_e32 v50, v48
	v_and_b32_e32 v47, -8, v47
	v_lshlrev_b32_e32 v46, 5, v46
	ds_write2_b64 v98, v[58:59], v[50:51] offset1:1
	v_add3_u32 v64, 0, v47, v46
	ds_read2_b64 v[46:49], v64 offset1:1
	ds_read2_b64 v[50:53], v64 offset0:2 offset1:3
	s_waitcnt vmcnt(2)
	v_lshlrev_b32_e32 v54, 16, v42
	v_and_b32_e32 v55, 0xffff0000, v42
	v_lshlrev_b32_e32 v42, 16, v43
	v_and_b32_e32 v43, 0xffff0000, v43
	s_waitcnt lgkmcnt(0)
	v_pk_add_f32 v[58:59], v[46:47], v[50:51]
	v_pk_add_f32 v[60:61], v[48:49], v[52:53]
	v_pk_add_f32 v[46:47], v[46:47], v[50:51] neg_lo:[0,1] neg_hi:[0,1]
	v_pk_add_f32 v[48:49], v[48:49], v[52:53] neg_lo:[0,1] neg_hi:[0,1]
	v_lshlrev_b32_e32 v56, 16, v44
	v_pk_add_f32 v[50:51], v[46:47], v[48:49] op_sel:[0,1] op_sel_hi:[1,0]
	v_pk_add_f32 v[46:47], v[46:47], v[48:49] op_sel:[0,1] op_sel_hi:[1,0] neg_lo:[0,1] neg_hi:[0,1]
	v_mov_b32_e32 v49, v51
	v_mov_b32_e32 v48, v46
	v_mov_b32_e32 v51, v47
	v_pk_mul_f32 v[46:47], v[50:51], v[42:43] op_sel:[0,0] op_sel_hi:[0,1]
	v_and_b32_e32 v57, 0xffff0000, v44
	v_pk_add_f32 v[62:63], v[58:59], v[60:61]
	v_pk_add_f32 v[58:59], v[58:59], v[60:61] neg_lo:[0,1] neg_hi:[0,1]
	v_pk_fma_f32 v[42:43], v[50:51], v[42:43], v[46:47] op_sel:[1,1,0] op_sel_hi:[1,0,1] neg_lo:[1,0,0]
	v_lshlrev_b32_e32 v44, 16, v45
	v_pk_mul_f32 v[46:47], v[58:59], v[56:57] op_sel:[0,0] op_sel_hi:[0,1]
	v_and_b32_e32 v45, 0xffff0000, v45
	v_pk_mul_f32 v[52:53], v[62:63], v[54:55] op_sel:[0,0] op_sel_hi:[0,1]
	v_pk_fma_f32 v[46:47], v[58:59], v[56:57], v[46:47] op_sel:[1,1,0] op_sel_hi:[1,0,1] neg_lo:[1,0,0]
	v_pk_mul_f32 v[50:51], v[48:49], v[44:45] op_sel:[0,0] op_sel_hi:[0,1]
	s_nop 0
	v_pk_fma_f32 v[52:53], v[62:63], v[54:55], v[52:53] op_sel:[1,1,0] op_sel_hi:[1,0,1] neg_lo:[1,0,0]
	v_pk_fma_f32 v[44:45], v[48:49], v[44:45], v[50:51] op_sel:[1,1,0] op_sel_hi:[1,0,1] neg_lo:[1,0,0]
	s_nop 0
	v_pk_add_f32 v[48:49], v[52:53], v[46:47]
	v_pk_add_f32 v[50:51], v[42:43], v[44:45]
	v_pk_add_f32 v[46:47], v[52:53], v[46:47] neg_lo:[0,1] neg_hi:[0,1]
	v_pk_add_f32 v[42:43], v[42:43], v[44:45] neg_lo:[0,1] neg_hi:[0,1]
	v_pk_add_f32 v[54:55], v[48:49], v[50:51]
	v_pk_add_f32 v[44:45], v[46:47], v[42:43] op_sel:[0,1] op_sel_hi:[1,0] neg_lo:[0,1] neg_hi:[0,1]
	v_pk_add_f32 v[42:43], v[46:47], v[42:43] op_sel:[0,1] op_sel_hi:[1,0]
	v_pk_add_f32 v[48:49], v[48:49], v[50:51] neg_lo:[0,1] neg_hi:[0,1]
	v_mov_b32_e32 v47, v43
	v_mov_b32_e32 v43, v45
	ds_write2_b64 v64, v[48:49], v[42:43] offset0:2 offset1:3
	v_add_u32_e32 v42, 0xc00, v85
	v_lshlrev_b32_e32 v43, 1, v42
	v_mov_b32_e32 v46, v44
	v_and_b32_e32 v43, -8, v43
	v_lshlrev_b32_e32 v42, 5, v42
	ds_write2_b64 v64, v[54:55], v[46:47] offset1:1
	v_add3_u32 v60, 0, v43, v42
	ds_read2_b64 v[42:45], v60 offset1:1
	ds_read2_b64 v[46:49], v60 offset0:2 offset1:3
	s_waitcnt vmcnt(1)
	v_lshlrev_b32_e32 v50, 16, v38
	v_and_b32_e32 v51, 0xffff0000, v38
	v_lshlrev_b32_e32 v38, 16, v39
	v_and_b32_e32 v39, 0xffff0000, v39
	s_waitcnt lgkmcnt(0)
	v_pk_add_f32 v[54:55], v[42:43], v[46:47]
	v_pk_add_f32 v[56:57], v[44:45], v[48:49]
	v_pk_add_f32 v[42:43], v[42:43], v[46:47] neg_lo:[0,1] neg_hi:[0,1]
	v_pk_add_f32 v[44:45], v[44:45], v[48:49] neg_lo:[0,1] neg_hi:[0,1]
	v_lshlrev_b32_e32 v52, 16, v40
	v_pk_add_f32 v[46:47], v[42:43], v[44:45] op_sel:[0,1] op_sel_hi:[1,0]
	v_pk_add_f32 v[42:43], v[42:43], v[44:45] op_sel:[0,1] op_sel_hi:[1,0] neg_lo:[0,1] neg_hi:[0,1]
	v_mov_b32_e32 v45, v47
	v_mov_b32_e32 v44, v42
	v_mov_b32_e32 v47, v43
	v_pk_mul_f32 v[42:43], v[46:47], v[38:39] op_sel:[0,0] op_sel_hi:[0,1]
	v_and_b32_e32 v53, 0xffff0000, v40
	v_pk_add_f32 v[58:59], v[54:55], v[56:57]
	v_pk_add_f32 v[54:55], v[54:55], v[56:57] neg_lo:[0,1] neg_hi:[0,1]
	v_pk_fma_f32 v[38:39], v[46:47], v[38:39], v[42:43] op_sel:[1,1,0] op_sel_hi:[1,0,1] neg_lo:[1,0,0]
	v_lshlrev_b32_e32 v40, 16, v41
	v_pk_mul_f32 v[42:43], v[54:55], v[52:53] op_sel:[0,0] op_sel_hi:[0,1]
	v_and_b32_e32 v41, 0xffff0000, v41
	v_pk_mul_f32 v[48:49], v[58:59], v[50:51] op_sel:[0,0] op_sel_hi:[0,1]
	v_pk_fma_f32 v[42:43], v[54:55], v[52:53], v[42:43] op_sel:[1,1,0] op_sel_hi:[1,0,1] neg_lo:[1,0,0]
	v_pk_mul_f32 v[46:47], v[44:45], v[40:41] op_sel:[0,0] op_sel_hi:[0,1]
	s_nop 0
	v_pk_fma_f32 v[48:49], v[58:59], v[50:51], v[48:49] op_sel:[1,1,0] op_sel_hi:[1,0,1] neg_lo:[1,0,0]
	v_pk_fma_f32 v[40:41], v[44:45], v[40:41], v[46:47] op_sel:[1,1,0] op_sel_hi:[1,0,1] neg_lo:[1,0,0]
	s_nop 0
	v_pk_add_f32 v[44:45], v[48:49], v[42:43]
	v_pk_add_f32 v[46:47], v[38:39], v[40:41]
	v_pk_add_f32 v[42:43], v[48:49], v[42:43] neg_lo:[0,1] neg_hi:[0,1]
	v_pk_add_f32 v[38:39], v[38:39], v[40:41] neg_lo:[0,1] neg_hi:[0,1]
	v_pk_add_f32 v[50:51], v[44:45], v[46:47]
	v_pk_add_f32 v[40:41], v[42:43], v[38:39] op_sel:[0,1] op_sel_hi:[1,0] neg_lo:[0,1] neg_hi:[0,1]
	v_pk_add_f32 v[38:39], v[42:43], v[38:39] op_sel:[0,1] op_sel_hi:[1,0]
	v_pk_add_f32 v[44:45], v[44:45], v[46:47] neg_lo:[0,1] neg_hi:[0,1]
	v_mov_b32_e32 v43, v39
	v_mov_b32_e32 v39, v41
	ds_write2_b64 v60, v[44:45], v[38:39] offset0:2 offset1:3
	v_add_u32_e32 v38, 0xe00, v85
	v_lshlrev_b32_e32 v39, 1, v38
	v_mov_b32_e32 v42, v40
	v_and_b32_e32 v39, -8, v39
	v_lshlrev_b32_e32 v38, 5, v38
	ds_write2_b64 v60, v[50:51], v[42:43] offset1:1
	v_add3_u32 v56, 0, v39, v38
	ds_read2_b64 v[38:41], v56 offset1:1
	ds_read2_b64 v[42:45], v56 offset0:2 offset1:3
	s_waitcnt vmcnt(0)
	v_lshlrev_b32_e32 v46, 16, v34
	v_and_b32_e32 v47, 0xffff0000, v34
	v_lshlrev_b32_e32 v34, 16, v35
	v_and_b32_e32 v35, 0xffff0000, v35
	s_waitcnt lgkmcnt(0)
	v_pk_add_f32 v[50:51], v[38:39], v[42:43]
	v_pk_add_f32 v[52:53], v[40:41], v[44:45]
	v_pk_add_f32 v[38:39], v[38:39], v[42:43] neg_lo:[0,1] neg_hi:[0,1]
	v_pk_add_f32 v[40:41], v[40:41], v[44:45] neg_lo:[0,1] neg_hi:[0,1]
	v_lshlrev_b32_e32 v48, 16, v36
	v_pk_add_f32 v[42:43], v[38:39], v[40:41] op_sel:[0,1] op_sel_hi:[1,0]
	v_pk_add_f32 v[38:39], v[38:39], v[40:41] op_sel:[0,1] op_sel_hi:[1,0] neg_lo:[0,1] neg_hi:[0,1]
	v_mov_b32_e32 v41, v43
	v_mov_b32_e32 v40, v38
	v_mov_b32_e32 v43, v39
	v_pk_mul_f32 v[38:39], v[42:43], v[34:35] op_sel:[0,0] op_sel_hi:[0,1]
	v_and_b32_e32 v49, 0xffff0000, v36
	v_pk_add_f32 v[54:55], v[50:51], v[52:53]
	v_pk_add_f32 v[50:51], v[50:51], v[52:53] neg_lo:[0,1] neg_hi:[0,1]
	v_pk_fma_f32 v[34:35], v[42:43], v[34:35], v[38:39] op_sel:[1,1,0] op_sel_hi:[1,0,1] neg_lo:[1,0,0]
	v_lshlrev_b32_e32 v36, 16, v37
	v_pk_mul_f32 v[38:39], v[50:51], v[48:49] op_sel:[0,0] op_sel_hi:[0,1]
	v_and_b32_e32 v37, 0xffff0000, v37
	v_pk_mul_f32 v[44:45], v[54:55], v[46:47] op_sel:[0,0] op_sel_hi:[0,1]
	v_pk_fma_f32 v[38:39], v[50:51], v[48:49], v[38:39] op_sel:[1,1,0] op_sel_hi:[1,0,1] neg_lo:[1,0,0]
	v_pk_mul_f32 v[42:43], v[40:41], v[36:37] op_sel:[0,0] op_sel_hi:[0,1]
	s_nop 0
	v_pk_fma_f32 v[44:45], v[54:55], v[46:47], v[44:45] op_sel:[1,1,0] op_sel_hi:[1,0,1] neg_lo:[1,0,0]
	v_pk_fma_f32 v[36:37], v[40:41], v[36:37], v[42:43] op_sel:[1,1,0] op_sel_hi:[1,0,1] neg_lo:[1,0,0]
	s_nop 0
	v_pk_add_f32 v[40:41], v[44:45], v[38:39]
	v_pk_add_f32 v[42:43], v[34:35], v[36:37]
	v_pk_add_f32 v[38:39], v[44:45], v[38:39] neg_lo:[0,1] neg_hi:[0,1]
	v_pk_add_f32 v[34:35], v[34:35], v[36:37] neg_lo:[0,1] neg_hi:[0,1]
	v_pk_add_f32 v[46:47], v[40:41], v[42:43]
	v_pk_add_f32 v[36:37], v[38:39], v[34:35] op_sel:[0,1] op_sel_hi:[1,0] neg_lo:[0,1] neg_hi:[0,1]
	v_pk_add_f32 v[34:35], v[38:39], v[34:35] op_sel:[0,1] op_sel_hi:[1,0]
	v_pk_add_f32 v[40:41], v[40:41], v[42:43] neg_lo:[0,1] neg_hi:[0,1]
	v_mov_b32_e32 v39, v35
	v_mov_b32_e32 v35, v37
	v_mov_b32_e32 v38, v36
	ds_write2_b64 v56, v[40:41], v[34:35] offset0:2 offset1:3
	v_mov_b32_e32 v34, v0
	ds_write2_b64 v56, v[46:47], v[38:39] offset1:1
	s_waitcnt lgkmcnt(0)
	s_barrier
	s_nop 0
	v_and_b32_e32 v36, 3, v34
	v_lshlrev_b32_e32 v37, 4, v34
	v_cvt_f32_ubyte0_e32 v34, v36
	v_mul_f32_e32 v35, 0x3c800000, v34
	v_cos_f32_e32 v34, v35
	v_sin_f32_e32 v35, v35
	v_and_b32_e32 v85, 0xffffffc0, v37
	v_ashrrev_i32_e32 v37, 1, v85
	v_add_u32_e32 v37, 0, v37
	v_lshlrev_b32_e32 v38, 3, v85
	v_lshlrev_b32_e32 v98, 3, v36
	v_add3_u32 v100, v37, v38, v98
	v_mov_b32_e32 v64, v34
	v_mov_b32_e32 v65, v35
	ds_read2_b64 v[36:39], v100 offset1:4
	ds_read2_b64 v[40:43], v100 offset0:8 offset1:12
	ds_read2_b64 v[44:47], v100 offset0:17 offset1:21
	ds_read2_b64 v[48:51], v100 offset0:25 offset1:29
	ds_read2_b64 v[52:55], v100 offset0:34 offset1:38
	ds_read2_b64 v[56:59], v100 offset0:42 offset1:46
	ds_read2_b64 v[60:63], v100 offset0:51 offset1:55
	ds_read2_b64 v[138:141], v100 offset0:59 offset1:63
	s_nop 1
	s_nop 0
	v_pk_mul_f32 v[142:143], v[64:65], v[64:65] op_sel:[0,0] op_sel_hi:[0,1]
	s_waitcnt lgkmcnt(7)
	v_pk_mul_f32 v[170:171], v[38:39], v[64:65] op_sel:[0,0] op_sel_hi:[0,1]
	v_pk_fma_f32 v[142:143], v[64:65], v[64:65], v[142:143] op_sel:[1,1,0] op_sel_hi:[1,0,1] neg_lo:[1,0,0]
	s_nop 0
	v_pk_fma_f32 v[38:39], v[38:39], v[64:65], v[170:171] op_sel:[1,1,0] op_sel_hi:[1,0,1] neg_lo:[1,0,0]
	v_pk_mul_f32 v[146:147], v[142:143], v[142:143] op_sel:[0,0] op_sel_hi:[0,1]
	v_pk_mul_f32 v[144:145], v[142:143], v[64:65] op_sel:[0,0] op_sel_hi:[0,1]
	s_nop 0
	v_pk_fma_f32 v[146:147], v[142:143], v[142:143], v[146:147] op_sel:[1,1,0] op_sel_hi:[1,0,1] neg_lo:[1,0,0]
	v_pk_fma_f32 v[144:145], v[142:143], v[64:65], v[144:145] op_sel:[1,1,0] op_sel_hi:[1,0,1] neg_lo:[1,0,0]
	s_nop 0
	v_pk_mul_f32 v[154:155], v[146:147], v[146:147] op_sel:[0,0] op_sel_hi:[0,1]
	v_pk_mul_f32 v[148:149], v[146:147], v[64:65] op_sel:[0,0] op_sel_hi:[0,1]
	v_pk_mul_f32 v[150:151], v[144:145], v[144:145] op_sel:[0,0] op_sel_hi:[0,1]
	v_pk_mul_f32 v[152:153], v[146:147], v[144:145] op_sel:[0,0] op_sel_hi:[0,1]
	s_nop 0
	v_pk_fma_f32 v[154:155], v[146:147], v[146:147], v[154:155] op_sel:[1,1,0] op_sel_hi:[1,0,1] neg_lo:[1,0,0]
	v_pk_fma_f32 v[148:149], v[146:147], v[64:65], v[148:149] op_sel:[1,1,0] op_sel_hi:[1,0,1] neg_lo:[1,0,0]
	v_pk_fma_f32 v[150:151], v[144:145], v[144:145], v[150:151] op_sel:[1,1,0] op_sel_hi:[1,0,1] neg_lo:[1,0,0]
	v_pk_fma_f32 v[152:153], v[146:147], v[144:145], v[152:153] op_sel:[1,1,0] op_sel_hi:[1,0,1] neg_lo:[1,0,0]
	s_nop 0
	v_pk_mul_f32 v[156:157], v[154:155], v[64:65] op_sel:[0,0] op_sel_hi:[0,1]
	v_pk_mul_f32 v[158:159], v[148:149], v[148:149] op_sel:[0,0] op_sel_hi:[0,1]
	v_pk_mul_f32 v[160:161], v[154:155], v[144:145] op_sel:[0,0] op_sel_hi:[0,1]
	v_pk_mul_f32 v[162:163], v[150:151], v[150:151] op_sel:[0,0] op_sel_hi:[0,1]
	v_pk_mul_f32 v[164:165], v[154:155], v[148:149] op_sel:[0,0] op_sel_hi:[0,1]
	v_pk_mul_f32 v[166:167], v[152:153], v[152:153] op_sel:[0,0] op_sel_hi:[0,1]
	s_nop 0
	v_pk_fma_f32 v[156:157], v[154:155], v[64:65], v[156:157] op_sel:[1,1,0] op_sel_hi:[1,0,1] neg_lo:[1,0,0]
	s_waitcnt lgkmcnt(6)
	v_pk_mul_f32 v[64:65], v[40:41], v[142:143] op_sel:[0,0] op_sel_hi:[0,1]
	v_pk_fma_f32 v[158:159], v[148:149], v[148:149], v[158:159] op_sel:[1,1,0] op_sel_hi:[1,0,1] neg_lo:[1,0,0]
	v_pk_fma_f32 v[160:161], v[154:155], v[144:145], v[160:161] op_sel:[1,1,0] op_sel_hi:[1,0,1] neg_lo:[1,0,0]
	v_pk_fma_f32 v[162:163], v[150:151], v[150:151], v[162:163] op_sel:[1,1,0] op_sel_hi:[1,0,1] neg_lo:[1,0,0]
	v_pk_fma_f32 v[164:165], v[154:155], v[148:149], v[164:165] op_sel:[1,1,0] op_sel_hi:[1,0,1] neg_lo:[1,0,0]
	v_pk_fma_f32 v[166:167], v[152:153], v[152:153], v[166:167] op_sel:[1,1,0] op_sel_hi:[1,0,1] neg_lo:[1,0,0]
	s_nop 0
	v_pk_fma_f32 v[40:41], v[40:41], v[142:143], v[64:65] op_sel:[1,1,0] op_sel_hi:[1,0,1] neg_lo:[1,0,0]
	v_pk_mul_f32 v[64:65], v[42:43], v[144:145] op_sel:[0,0] op_sel_hi:[0,1]
	v_pk_mul_f32 v[168:169], v[154:155], v[152:153] op_sel:[0,0] op_sel_hi:[0,1]
	s_nop 0
	v_pk_fma_f32 v[42:43], v[42:43], v[144:145], v[64:65] op_sel:[1,1,0] op_sel_hi:[1,0,1] neg_lo:[1,0,0]
	s_waitcnt lgkmcnt(5)
	v_pk_mul_f32 v[64:65], v[44:45], v[146:147] op_sel:[0,0] op_sel_hi:[0,1]
	v_pk_fma_f32 v[168:169], v[154:155], v[152:153], v[168:169] op_sel:[1,1,0] op_sel_hi:[1,0,1] neg_lo:[1,0,0]
	v_mov_b32_e32 v144, v37
	v_pk_fma_f32 v[44:45], v[44:45], v[146:147], v[64:65] op_sel:[1,1,0] op_sel_hi:[1,0,1] neg_lo:[1,0,0]
	v_pk_mul_f32 v[64:65], v[46:47], v[148:149] op_sel:[0,0] op_sel_hi:[0,1]
	s_nop 0
	v_pk_fma_f32 v[46:47], v[46:47], v[148:149], v[64:65] op_sel:[1,1,0] op_sel_hi:[1,0,1] neg_lo:[1,0,0]
	s_waitcnt lgkmcnt(4)
	v_pk_mul_f32 v[64:65], v[48:49], v[150:151] op_sel:[0,0] op_sel_hi:[0,1]
	v_mov_b32_e32 v145, v45
	v_pk_fma_f32 v[48:49], v[48:49], v[150:151], v[64:65] op_sel:[1,1,0] op_sel_hi:[1,0,1] neg_lo:[1,0,0]
	v_pk_mul_f32 v[64:65], v[50:51], v[152:153] op_sel:[0,0] op_sel_hi:[0,1]
	s_nop 0
	v_pk_fma_f32 v[50:51], v[50:51], v[152:153], v[64:65] op_sel:[1,1,0] op_sel_hi:[1,0,1] neg_lo:[1,0,0]
	s_waitcnt lgkmcnt(3)
	v_pk_mul_f32 v[64:65], v[52:53], v[154:155] op_sel:[0,0] op_sel_hi:[0,1]
	s_nop 0
	v_pk_fma_f32 v[52:53], v[52:53], v[154:155], v[64:65] op_sel:[1,1,0] op_sel_hi:[1,0,1] neg_lo:[1,0,0]
	v_pk_mul_f32 v[64:65], v[54:55], v[156:157] op_sel:[0,0] op_sel_hi:[0,1]
	s_nop 0
	v_pk_fma_f32 v[54:55], v[54:55], v[156:157], v[64:65] op_sel:[1,1,0] op_sel_hi:[1,0,1] neg_lo:[1,0,0]
	s_waitcnt lgkmcnt(2)
	v_pk_mul_f32 v[64:65], v[56:57], v[158:159] op_sel:[0,0] op_sel_hi:[0,1]
	v_mov_b32_e32 v146, v53
	v_pk_fma_f32 v[56:57], v[56:57], v[158:159], v[64:65] op_sel:[1,1,0] op_sel_hi:[1,0,1] neg_lo:[1,0,0]
	v_pk_mul_f32 v[64:65], v[58:59], v[160:161] op_sel:[0,0] op_sel_hi:[0,1]
	s_nop 0
	v_pk_fma_f32 v[58:59], v[58:59], v[160:161], v[64:65] op_sel:[1,1,0] op_sel_hi:[1,0,1] neg_lo:[1,0,0]
	s_waitcnt lgkmcnt(1)
	v_pk_mul_f32 v[64:65], v[60:61], v[162:163] op_sel:[0,0] op_sel_hi:[0,1]
	s_nop 0
	v_pk_fma_f32 v[60:61], v[60:61], v[162:163], v[64:65] op_sel:[1,1,0] op_sel_hi:[1,0,1] neg_lo:[1,0,0]
	v_pk_mul_f32 v[64:65], v[62:63], v[164:165] op_sel:[0,0] op_sel_hi:[0,1]
	s_nop 0
	v_pk_fma_f32 v[62:63], v[62:63], v[164:165], v[64:65] op_sel:[1,1,0] op_sel_hi:[1,0,1] neg_lo:[1,0,0]
	s_waitcnt lgkmcnt(0)
	v_pk_mul_f32 v[64:65], v[138:139], v[166:167] op_sel:[0,0] op_sel_hi:[0,1]
	v_mov_b32_e32 v147, v61
	v_pk_fma_f32 v[64:65], v[138:139], v[166:167], v[64:65] op_sel:[1,1,0] op_sel_hi:[1,0,1] neg_lo:[1,0,0]
	v_pk_mul_f32 v[138:139], v[140:141], v[168:169] op_sel:[0,0] op_sel_hi:[0,1]
	v_pk_add_f32 v[144:145], v[144:145], v[146:147]
	v_pk_fma_f32 v[138:139], v[140:141], v[168:169], v[138:139] op_sel:[1,1,0] op_sel_hi:[1,0,1] neg_lo:[1,0,0]
	v_pk_add_f32 v[140:141], v[36:37], v[52:53]
	v_pk_mov_b32 v[146:147], v[36:37], v[44:45] op_sel:[1,0]
	v_pk_mov_b32 v[148:149], v[52:53], v[60:61] op_sel:[1,0]
	v_mov_b32_e32 v37, v45
	v_mov_b32_e32 v53, v61
	v_pk_add_f32 v[142:143], v[44:45], v[60:61]
	v_pk_add_f32 v[36:37], v[36:37], v[52:53] neg_lo:[0,1] neg_hi:[0,1]
	v_pk_add_f32 v[52:53], v[38:39], v[54:55]
	v_pk_add_f32 v[60:61], v[46:47], v[62:63]
	v_pk_add_f32 v[38:39], v[38:39], v[54:55] neg_lo:[0,1] neg_hi:[0,1]
	v_pk_add_f32 v[46:47], v[46:47], v[62:63] neg_lo:[0,1] neg_hi:[0,1]
	v_pk_add_f32 v[146:147], v[146:147], v[148:149] neg_lo:[0,1] neg_hi:[0,1]
	v_pk_add_f32 v[148:149], v[52:53], v[60:61]
	v_pk_add_f32 v[60:61], v[52:53], v[60:61] neg_lo:[0,1] neg_hi:[0,1]
	v_pk_add_f32 v[52:53], v[38:39], v[46:47] op_sel:[0,1] op_sel_hi:[1,0] neg_lo:[0,1] neg_hi:[0,1]
	v_pk_add_f32 v[38:39], v[38:39], v[46:47] op_sel:[0,1] op_sel_hi:[1,0]
	v_mov_b32_e32 v46, v52
	v_mov_b32_e32 v47, v39
	v_mov_b32_e32 v39, v53
	v_pk_add_f32 v[52:53], v[40:41], v[56:57]
	v_pk_add_f32 v[54:55], v[48:49], v[64:65]
	v_pk_add_f32 v[40:41], v[40:41], v[56:57] neg_lo:[0,1] neg_hi:[0,1]
	v_pk_add_f32 v[48:49], v[48:49], v[64:65] neg_lo:[0,1] neg_hi:[0,1]
	v_pk_add_f32 v[62:63], v[52:53], v[54:55]
	v_pk_add_f32 v[150:151], v[52:53], v[54:55] neg_lo:[0,1] neg_hi:[0,1]
	v_pk_add_f32 v[52:53], v[40:41], v[48:49] op_sel:[0,1] op_sel_hi:[1,0] neg_lo:[0,1] neg_hi:[0,1]
	v_pk_add_f32 v[40:41], v[40:41], v[48:49] op_sel:[0,1] op_sel_hi:[1,0]
	v_mov_b32_e32 v48, v52
	v_mov_b32_e32 v49, v41
	v_mov_b32_e32 v41, v53
	v_pk_add_f32 v[52:53], v[42:43], v[58:59]
	v_pk_add_f32 v[54:55], v[50:51], v[138:139]
	v_pk_add_f32 v[42:43], v[42:43], v[58:59] neg_lo:[0,1] neg_hi:[0,1]
	v_pk_add_f32 v[50:51], v[50:51], v[138:139] neg_lo:[0,1] neg_hi:[0,1]
	v_pk_add_f32 v[64:65], v[52:53], v[54:55]
	v_pk_add_f32 v[152:153], v[52:53], v[54:55] neg_lo:[0,1] neg_hi:[0,1]
	v_pk_add_f32 v[52:53], v[42:43], v[50:51] op_sel:[0,1] op_sel_hi:[1,0] neg_lo:[0,1] neg_hi:[0,1]
	v_pk_add_f32 v[42:43], v[42:43], v[50:51] op_sel:[0,1] op_sel_hi:[1,0]
	v_mov_b64_e32 v[54:55], s[10:11]
	v_pk_mul_f32 v[50:51], v[46:47], v[54:55] op_sel:[0,0] op_sel_hi:[0,1]
	v_mov_b32_e32 v56, v52
	v_mov_b32_e32 v57, v43
	v_mov_b32_e32 v43, v53
	v_pk_fma_f32 v[46:47], v[46:47], v[54:55], v[50:51] op_sel:[1,1,0] op_sel_hi:[1,0,1] neg_lo:[1,0,0]
	v_mov_b64_e32 v[52:53], s[38:39]
	v_pk_mul_f32 v[50:51], v[48:49], v[52:53] op_sel:[0,0] op_sel_hi:[0,1]
	s_mov_b32 s10, s67
	v_pk_fma_f32 v[48:49], v[48:49], v[52:53], v[50:51] op_sel:[1,1,0] op_sel_hi:[1,0,1] neg_lo:[1,0,0]
	v_mov_b64_e32 v[50:51], s[4:5]
	v_readlane_b32 s4, v255, 29
	v_readlane_b32 s5, v255, 30
	s_mov_b32 s11, s5
	v_writelane_b32 v255, s4, 29
	v_pk_mul_f32 v[58:59], v[56:57], v[50:51] op_sel:[0,0] op_sel_hi:[0,1]
	v_mov_b32_e32 v141, v144
	v_pk_fma_f32 v[138:139], v[56:57], v[50:51], v[58:59] op_sel:[1,1,0] op_sel_hi:[1,0,1] neg_lo:[1,0,0]
	v_pk_mul_f32 v[56:57], v[60:61], v[52:53] op_sel:[0,0] op_sel_hi:[0,1]
	v_mov_b32_e32 v143, v145
	v_writelane_b32 v255, s5, 30
	v_pk_fma_f32 v[154:155], v[60:61], v[52:53], v[56:57] op_sel:[1,1,0] op_sel_hi:[1,0,1] neg_lo:[1,0,0]
	v_mov_b64_e32 v[56:57], s[10:11]
	v_readlane_b32 s4, v255, 19
	v_readlane_b32 s5, v255, 20
	s_mov_b32 s10, s4
	s_mov_b32 s4, s38
	v_writelane_b32 v255, s4, 27
	v_pk_mul_f32 v[58:59], v[150:151], v[56:57] op_sel:[0,0] op_sel_hi:[0,1]
	s_mov_b32 s11, s38
	v_pk_fma_f32 v[150:151], v[150:151], v[56:57], v[58:59] op_sel:[1,1,0] op_sel_hi:[1,0,1] neg_lo:[1,0,0]
	v_mov_b64_e32 v[58:59], s[10:11]
	v_writelane_b32 v255, s5, 28
	s_mov_b32 s4, s10
	v_writelane_b32 v255, s4, 19
	v_pk_mul_f32 v[60:61], v[152:153], v[58:59] op_sel:[0,0] op_sel_hi:[0,1]
	v_pk_add_f32 v[44:45], v[140:141], v[142:143]
	v_pk_fma_f32 v[152:153], v[152:153], v[58:59], v[60:61] op_sel:[1,1,0] op_sel_hi:[1,0,1] neg_lo:[1,0,0]
	v_pk_mul_f32 v[60:61], v[38:39], v[50:51] op_sel:[0,0] op_sel_hi:[0,1]
	v_pk_add_f32 v[140:141], v[140:141], v[142:143] neg_lo:[0,1] neg_hi:[0,1]
	v_writelane_b32 v255, s5, 20
	s_mov_b32 s4, 0xbf6c835e
	v_pk_fma_f32 v[38:39], v[38:39], v[50:51], v[60:61] op_sel:[1,1,0] op_sel_hi:[1,0,1] neg_lo:[1,0,0]
	v_pk_mul_f32 v[60:61], v[40:41], v[58:59] op_sel:[0,0] op_sel_hi:[0,1]
	s_mov_b32 s5, 0xbec3ef15
	v_pk_add_f32 v[142:143], v[36:37], v[36:37] op_sel:[0,1] op_sel_hi:[1,0] neg_lo:[0,1] neg_hi:[0,1]
	v_pk_fma_f32 v[40:41], v[40:41], v[58:59], v[60:61] op_sel:[1,1,0] op_sel_hi:[1,0,1] neg_lo:[1,0,0]
	v_mov_b64_e32 v[60:61], s[4:5]
	v_pk_mul_f32 v[156:157], v[42:43], v[60:61] op_sel:[0,0] op_sel_hi:[0,1]
	v_pk_add_f32 v[144:145], v[146:147], v[146:147] op_sel:[0,1] op_sel_hi:[1,0]
	v_pk_fma_f32 v[42:43], v[42:43], v[60:61], v[156:157] op_sel:[1,1,0] op_sel_hi:[1,0,1] neg_lo:[1,0,0]
	v_pk_mov_b32 v[156:157], v[44:45], v[148:149] op_sel:[1,0]
	v_pk_mov_b32 v[158:159], v[62:63], v[64:65] op_sel:[1,0]
	v_mov_b32_e32 v143, v47
	v_mov_b32_e32 v162, v48
	v_mov_b32_e32 v163, v139
	v_pk_add_f32 v[36:37], v[36:37], v[36:37] op_sel:[0,1] op_sel_hi:[1,0]
	v_pk_add_f32 v[146:147], v[146:147], v[146:147] op_sel_hi:[0,1] neg_lo:[0,1] neg_hi:[0,1]
	v_pk_add_f32 v[156:157], v[156:157], v[158:159] neg_lo:[0,1] neg_hi:[0,1]
	v_mov_b32_e32 v158, v44
	v_mov_b32_e32 v159, v149
	v_mov_b32_e32 v160, v62
	v_mov_b32_e32 v161, v65
	v_pk_add_f32 v[162:163], v[142:143], v[162:163] neg_lo:[0,1] neg_hi:[0,1]
	v_mov_b32_e32 v143, v144
	v_pk_add_f32 v[158:159], v[158:159], v[160:161] neg_lo:[0,1] neg_hi:[0,1]
	v_mov_b32_e32 v145, v46
	v_pk_mov_b32 v[160:161], v[48:49], v[138:139] op_sel:[1,0]
	v_pk_add_f32 v[48:49], v[142:143], v[48:49]
	v_pk_add_f32 v[46:47], v[46:47], v[138:139]
	v_mov_b32_e32 v37, v147
	v_pk_add_f32 v[44:45], v[44:45], v[62:63]
	v_pk_add_f32 v[62:63], v[148:149], v[64:65]
	v_pk_add_f32 v[160:161], v[144:145], v[160:161] neg_lo:[0,1] neg_hi:[0,1]
	v_pk_add_f32 v[138:139], v[48:49], v[46:47]
	v_pk_add_f32 v[46:47], v[48:49], v[46:47] neg_lo:[0,1] neg_hi:[0,1]
	v_pk_add_f32 v[48:49], v[162:163], v[162:163] op_sel:[0,1] op_sel_hi:[1,0] neg_lo:[0,1] neg_hi:[0,1]
	v_pk_add_f32 v[144:145], v[162:163], v[162:163] op_sel:[0,1] op_sel_hi:[1,0]
	v_pk_add_f32 v[162:163], v[140:141], v[150:151]
	v_pk_add_f32 v[164:165], v[154:155], v[152:153]
	v_pk_add_f32 v[140:141], v[140:141], v[150:151] neg_lo:[0,1] neg_hi:[0,1]
	v_pk_add_f32 v[150:151], v[154:155], v[152:153] neg_lo:[0,1] neg_hi:[0,1]
	v_pk_add_f32 v[146:147], v[36:37], v[40:41]
	v_pk_add_f32 v[154:155], v[38:39], v[42:43]
	v_pk_add_f32 v[36:37], v[36:37], v[40:41] neg_lo:[0,1] neg_hi:[0,1]
	v_pk_add_f32 v[38:39], v[38:39], v[42:43] neg_lo:[0,1] neg_hi:[0,1]
	v_pk_add_f32 v[64:65], v[44:45], v[62:63]
	v_pk_add_f32 v[44:45], v[44:45], v[62:63] neg_lo:[0,1] neg_hi:[0,1]
	v_pk_add_f32 v[62:63], v[158:159], v[158:159] op_sel:[0,1] op_sel_hi:[1,0] neg_lo:[0,1] neg_hi:[0,1]
	v_pk_add_f32 v[148:149], v[156:157], v[156:157] op_sel_hi:[0,1]
	v_pk_add_f32 v[142:143], v[160:161], v[160:161] op_sel_hi:[0,1]
	v_pk_add_f32 v[152:153], v[140:141], v[150:151] op_sel:[0,1] op_sel_hi:[1,0] neg_lo:[0,1] neg_hi:[0,1]
	v_pk_add_f32 v[140:141], v[140:141], v[150:151] op_sel:[0,1] op_sel_hi:[1,0]
	v_pk_add_f32 v[40:41], v[36:37], v[38:39] op_sel:[0,1] op_sel_hi:[1,0] neg_lo:[0,1] neg_hi:[0,1]
	v_pk_add_f32 v[36:37], v[36:37], v[38:39] op_sel:[0,1] op_sel_hi:[1,0]
	v_mov_b32_e32 v151, v141
	v_mov_b32_e32 v39, v37
	v_mov_b32_e32 v63, v149
	v_mov_b32_e32 v49, v143
	v_mov_b32_e32 v141, v153
	v_mov_b32_e32 v37, v41
	v_pk_add_f32 v[166:167], v[162:163], v[164:165]
	v_pk_add_f32 v[162:163], v[162:163], v[164:165] neg_lo:[0,1] neg_hi:[0,1]
	v_mov_b32_e32 v150, v152
	v_pk_add_f32 v[164:165], v[146:147], v[154:155]
	v_pk_add_f32 v[146:147], v[146:147], v[154:155] neg_lo:[0,1] neg_hi:[0,1]
	v_mov_b32_e32 v38, v40
	ds_write2_b64 v100, v[64:65], v[138:139] offset1:4
	ds_write2_b64 v100, v[166:167], v[164:165] offset0:8 offset1:12
	ds_write2_b64 v100, v[62:63], v[48:49] offset0:17 offset1:21
	ds_write2_b64 v100, v[150:151], v[38:39] offset0:25 offset1:29
	ds_write2_b64 v100, v[44:45], v[46:47] offset0:34 offset1:38
	ds_write2_b64 v100, v[162:163], v[146:147] offset0:42 offset1:46
	ds_write2_b64 v100, v[140:141], v[36:37] offset0:59 offset1:63
	v_add_u32_e32 v36, 0x2000, v85
	v_pk_add_f32 v[158:159], v[158:159], v[158:159] op_sel:[0,1] op_sel_hi:[1,0]
	v_pk_add_f32 v[156:157], v[156:157], v[156:157] op_sel_hi:[0,1] neg_lo:[0,1] neg_hi:[0,1]
	v_pk_add_f32 v[160:161], v[160:161], v[160:161] op_sel_hi:[0,1] neg_lo:[0,1] neg_hi:[0,1]
	v_ashrrev_i32_e32 v37, 1, v36
	v_mov_b32_e32 v159, v157
	v_mov_b32_e32 v145, v161
	v_add_u32_e32 v37, 0, v37
	v_lshlrev_b32_e32 v36, 3, v36
	ds_write2_b64 v100, v[158:159], v[144:145] offset0:51 offset1:55
	v_add3_u32 v85, v37, v36, v98
	ds_read2_b64 v[36:39], v85 offset1:4
	ds_read2_b64 v[40:43], v85 offset0:8 offset1:12
	ds_read2_b64 v[44:47], v85 offset0:17 offset1:21
	ds_read2_b64 v[62:65], v85 offset0:25 offset1:29
	ds_read2_b64 v[138:141], v85 offset0:34 offset1:38
	ds_read2_b64 v[142:145], v85 offset0:42 offset1:46
	ds_read2_b64 v[146:149], v85 offset0:51 offset1:55
	ds_read2_b64 v[150:153], v85 offset0:59 offset1:63
	s_nop 1
	s_mov_b64 s[4:5], 0x4000
	v_pk_mul_f32 v[48:49], v[34:35], v[34:35] op_sel:[0,0] op_sel_hi:[0,1]
	s_waitcnt lgkmcnt(7)
	v_pk_mul_f32 v[180:181], v[38:39], v[34:35] op_sel:[0,0] op_sel_hi:[0,1]
	v_pk_fma_f32 v[48:49], v[34:35], v[34:35], v[48:49] op_sel:[1,1,0] op_sel_hi:[1,0,1] neg_lo:[1,0,0]
	s_nop 0
	v_pk_mul_f32 v[156:157], v[48:49], v[48:49] op_sel:[0,0] op_sel_hi:[0,1]
	v_pk_mul_f32 v[154:155], v[48:49], v[34:35] op_sel:[0,0] op_sel_hi:[0,1]
	s_nop 0
	v_pk_fma_f32 v[156:157], v[48:49], v[48:49], v[156:157] op_sel:[1,1,0] op_sel_hi:[1,0,1] neg_lo:[1,0,0]
	v_pk_fma_f32 v[154:155], v[48:49], v[34:35], v[154:155] op_sel:[1,1,0] op_sel_hi:[1,0,1] neg_lo:[1,0,0]
	s_nop 0
	v_pk_mul_f32 v[164:165], v[156:157], v[156:157] op_sel:[0,0] op_sel_hi:[0,1]
	v_pk_mul_f32 v[158:159], v[156:157], v[34:35] op_sel:[0,0] op_sel_hi:[0,1]
	v_pk_mul_f32 v[160:161], v[154:155], v[154:155] op_sel:[0,0] op_sel_hi:[0,1]
	v_pk_mul_f32 v[162:163], v[156:157], v[154:155] op_sel:[0,0] op_sel_hi:[0,1]
	s_nop 0
	v_pk_fma_f32 v[164:165], v[156:157], v[156:157], v[164:165] op_sel:[1,1,0] op_sel_hi:[1,0,1] neg_lo:[1,0,0]
	v_pk_fma_f32 v[158:159], v[156:157], v[34:35], v[158:159] op_sel:[1,1,0] op_sel_hi:[1,0,1] neg_lo:[1,0,0]
	v_pk_fma_f32 v[160:161], v[154:155], v[154:155], v[160:161] op_sel:[1,1,0] op_sel_hi:[1,0,1] neg_lo:[1,0,0]
	v_pk_fma_f32 v[162:163], v[156:157], v[154:155], v[162:163] op_sel:[1,1,0] op_sel_hi:[1,0,1] neg_lo:[1,0,0]
	s_nop 0
	v_pk_mul_f32 v[166:167], v[164:165], v[34:35] op_sel:[0,0] op_sel_hi:[0,1]
	v_pk_mul_f32 v[168:169], v[158:159], v[158:159] op_sel:[0,0] op_sel_hi:[0,1]
	v_pk_mul_f32 v[170:171], v[164:165], v[154:155] op_sel:[0,0] op_sel_hi:[0,1]
	v_pk_mul_f32 v[172:173], v[160:161], v[160:161] op_sel:[0,0] op_sel_hi:[0,1]
	v_pk_mul_f32 v[174:175], v[164:165], v[158:159] op_sel:[0,0] op_sel_hi:[0,1]
	v_pk_mul_f32 v[176:177], v[162:163], v[162:163] op_sel:[0,0] op_sel_hi:[0,1]
	s_nop 0
	v_pk_fma_f32 v[166:167], v[164:165], v[34:35], v[166:167] op_sel:[1,1,0] op_sel_hi:[1,0,1] neg_lo:[1,0,0]
	v_pk_fma_f32 v[34:35], v[38:39], v[34:35], v[180:181] op_sel:[1,1,0] op_sel_hi:[1,0,1] neg_lo:[1,0,0]
	s_waitcnt lgkmcnt(6)
	v_pk_mul_f32 v[38:39], v[40:41], v[48:49] op_sel:[0,0] op_sel_hi:[0,1]
	v_pk_fma_f32 v[168:169], v[158:159], v[158:159], v[168:169] op_sel:[1,1,0] op_sel_hi:[1,0,1] neg_lo:[1,0,0]
	v_pk_fma_f32 v[170:171], v[164:165], v[154:155], v[170:171] op_sel:[1,1,0] op_sel_hi:[1,0,1] neg_lo:[1,0,0]
	v_pk_fma_f32 v[172:173], v[160:161], v[160:161], v[172:173] op_sel:[1,1,0] op_sel_hi:[1,0,1] neg_lo:[1,0,0]
	v_pk_fma_f32 v[174:175], v[164:165], v[158:159], v[174:175] op_sel:[1,1,0] op_sel_hi:[1,0,1] neg_lo:[1,0,0]
	v_pk_mul_f32 v[178:179], v[164:165], v[162:163] op_sel:[0,0] op_sel_hi:[0,1]
	s_nop 0
	v_pk_fma_f32 v[38:39], v[40:41], v[48:49], v[38:39] op_sel:[1,1,0] op_sel_hi:[1,0,1] neg_lo:[1,0,0]
	v_pk_mul_f32 v[40:41], v[42:43], v[154:155] op_sel:[0,0] op_sel_hi:[0,1]
	s_waitcnt lgkmcnt(4)
	v_pk_mul_f32 v[48:49], v[64:65], v[162:163] op_sel:[0,0] op_sel_hi:[0,1]
	v_pk_fma_f32 v[176:177], v[162:163], v[162:163], v[176:177] op_sel:[1,1,0] op_sel_hi:[1,0,1] neg_lo:[1,0,0]
	v_pk_fma_f32 v[40:41], v[42:43], v[154:155], v[40:41] op_sel:[1,1,0] op_sel_hi:[1,0,1] neg_lo:[1,0,0]
	v_pk_mul_f32 v[42:43], v[44:45], v[156:157] op_sel:[0,0] op_sel_hi:[0,1]
	s_nop 0
	v_pk_fma_f32 v[48:49], v[64:65], v[162:163], v[48:49] op_sel:[1,1,0] op_sel_hi:[1,0,1] neg_lo:[1,0,0]
	s_waitcnt lgkmcnt(3)
	v_pk_mul_f32 v[64:65], v[140:141], v[166:167] op_sel:[0,0] op_sel_hi:[0,1]
	v_pk_fma_f32 v[178:179], v[164:165], v[162:163], v[178:179] op_sel:[1,1,0] op_sel_hi:[1,0,1] neg_lo:[1,0,0]
	v_mov_b32_e32 v154, v37
	v_pk_fma_f32 v[42:43], v[44:45], v[156:157], v[42:43] op_sel:[1,1,0] op_sel_hi:[1,0,1] neg_lo:[1,0,0]
	v_pk_mul_f32 v[44:45], v[46:47], v[158:159] op_sel:[0,0] op_sel_hi:[0,1]
	v_pk_fma_f32 v[64:65], v[140:141], v[166:167], v[64:65] op_sel:[1,1,0] op_sel_hi:[1,0,1] neg_lo:[1,0,0]
	s_waitcnt lgkmcnt(2)
	v_pk_mul_f32 v[140:141], v[144:145], v[170:171] op_sel:[0,0] op_sel_hi:[0,1]
	v_pk_fma_f32 v[44:45], v[46:47], v[158:159], v[44:45] op_sel:[1,1,0] op_sel_hi:[1,0,1] neg_lo:[1,0,0]
	v_pk_mul_f32 v[46:47], v[62:63], v[160:161] op_sel:[0,0] op_sel_hi:[0,1]
	s_nop 0
	v_pk_fma_f32 v[140:141], v[144:145], v[170:171], v[140:141] op_sel:[1,1,0] op_sel_hi:[1,0,1] neg_lo:[1,0,0]
	s_waitcnt lgkmcnt(1)
	v_pk_mul_f32 v[144:145], v[148:149], v[174:175] op_sel:[0,0] op_sel_hi:[0,1]
	v_mov_b32_e32 v155, v43
	v_pk_fma_f32 v[46:47], v[62:63], v[160:161], v[46:47] op_sel:[1,1,0] op_sel_hi:[1,0,1] neg_lo:[1,0,0]
	v_pk_mul_f32 v[62:63], v[138:139], v[164:165] op_sel:[0,0] op_sel_hi:[0,1]
	v_pk_fma_f32 v[144:145], v[148:149], v[174:175], v[144:145] op_sel:[1,1,0] op_sel_hi:[1,0,1] neg_lo:[1,0,0]
	s_waitcnt lgkmcnt(0)
	v_pk_mul_f32 v[148:149], v[152:153], v[178:179] op_sel:[0,0] op_sel_hi:[0,1]
	v_pk_fma_f32 v[62:63], v[138:139], v[164:165], v[62:63] op_sel:[1,1,0] op_sel_hi:[1,0,1] neg_lo:[1,0,0]
	v_pk_mul_f32 v[138:139], v[142:143], v[168:169] op_sel:[0,0] op_sel_hi:[0,1]
	s_nop 0
	v_pk_fma_f32 v[148:149], v[152:153], v[178:179], v[148:149] op_sel:[1,1,0] op_sel_hi:[1,0,1] neg_lo:[1,0,0]
	v_pk_fma_f32 v[138:139], v[142:143], v[168:169], v[138:139] op_sel:[1,1,0] op_sel_hi:[1,0,1] neg_lo:[1,0,0]
	v_pk_mul_f32 v[142:143], v[146:147], v[172:173] op_sel:[0,0] op_sel_hi:[0,1]
	v_mov_b32_e32 v156, v63
	v_pk_fma_f32 v[142:143], v[146:147], v[172:173], v[142:143] op_sel:[1,1,0] op_sel_hi:[1,0,1] neg_lo:[1,0,0]
	v_pk_mul_f32 v[146:147], v[150:151], v[176:177] op_sel:[0,0] op_sel_hi:[0,1]
	s_nop 0
	v_mov_b32_e32 v157, v143
	v_pk_fma_f32 v[146:147], v[150:151], v[176:177], v[146:147] op_sel:[1,1,0] op_sel_hi:[1,0,1] neg_lo:[1,0,0]
	v_pk_add_f32 v[150:151], v[36:37], v[62:63]
	v_pk_add_f32 v[152:153], v[42:43], v[142:143]
	v_pk_add_f32 v[154:155], v[154:155], v[156:157]
	v_pk_mov_b32 v[156:157], v[36:37], v[42:43] op_sel:[1,0]
	v_pk_mov_b32 v[158:159], v[62:63], v[142:143] op_sel:[1,0]
	v_mov_b32_e32 v37, v43
	v_pk_add_f32 v[156:157], v[156:157], v[158:159] neg_lo:[0,1] neg_hi:[0,1]
	v_mov_b32_e32 v63, v143
	v_mov_b32_e32 v151, v154
	v_mov_b32_e32 v153, v155
	v_pk_add_f32 v[36:37], v[36:37], v[62:63] neg_lo:[0,1] neg_hi:[0,1]
	v_pk_add_f32 v[42:43], v[150:151], v[152:153]
	v_pk_add_f32 v[62:63], v[150:151], v[152:153] neg_lo:[0,1] neg_hi:[0,1]
	v_pk_add_f32 v[150:151], v[156:157], v[156:157] op_sel:[0,1] op_sel_hi:[1,0]
	v_pk_add_f32 v[152:153], v[156:157], v[156:157] op_sel_hi:[0,1] neg_lo:[0,1] neg_hi:[0,1]
	v_pk_add_f32 v[154:155], v[34:35], v[64:65]
	v_pk_add_f32 v[156:157], v[44:45], v[144:145]
	v_pk_add_f32 v[34:35], v[34:35], v[64:65] neg_lo:[0,1] neg_hi:[0,1]
	v_pk_add_f32 v[44:45], v[44:45], v[144:145] neg_lo:[0,1] neg_hi:[0,1]
	v_pk_add_f32 v[144:145], v[46:47], v[146:147]
	v_pk_add_f32 v[64:65], v[34:35], v[44:45] op_sel:[0,1] op_sel_hi:[1,0] neg_lo:[0,1] neg_hi:[0,1]
	v_pk_add_f32 v[34:35], v[34:35], v[44:45] op_sel:[0,1] op_sel_hi:[1,0]
	v_mov_b32_e32 v44, v64
	v_mov_b32_e32 v45, v35
	v_mov_b32_e32 v35, v65
	v_pk_add_f32 v[64:65], v[38:39], v[138:139]
	v_pk_add_f32 v[38:39], v[38:39], v[138:139] neg_lo:[0,1] neg_hi:[0,1]
	v_pk_add_f32 v[46:47], v[46:47], v[146:147] neg_lo:[0,1] neg_hi:[0,1]
	v_pk_add_f32 v[158:159], v[154:155], v[156:157]
	v_pk_add_f32 v[138:139], v[38:39], v[46:47] op_sel:[0,1] op_sel_hi:[1,0] neg_lo:[0,1] neg_hi:[0,1]
	v_pk_add_f32 v[38:39], v[38:39], v[46:47] op_sel:[0,1] op_sel_hi:[1,0]
	v_pk_add_f32 v[154:155], v[154:155], v[156:157] neg_lo:[0,1] neg_hi:[0,1]
	v_pk_add_f32 v[156:157], v[64:65], v[144:145]
	v_pk_add_f32 v[64:65], v[64:65], v[144:145] neg_lo:[0,1] neg_hi:[0,1]
	v_mov_b32_e32 v46, v138
	v_mov_b32_e32 v47, v39
	v_mov_b32_e32 v39, v139
	v_pk_add_f32 v[138:139], v[40:41], v[140:141]
	v_pk_add_f32 v[144:145], v[48:49], v[148:149]
	v_pk_add_f32 v[40:41], v[40:41], v[140:141] neg_lo:[0,1] neg_hi:[0,1]
	v_pk_add_f32 v[146:147], v[138:139], v[144:145]
	v_pk_add_f32 v[138:139], v[138:139], v[144:145] neg_lo:[0,1] neg_hi:[0,1]
	v_pk_add_f32 v[48:49], v[48:49], v[148:149] neg_lo:[0,1] neg_hi:[0,1]
	v_pk_mul_f32 v[144:145], v[64:65], v[56:57] op_sel:[0,0] op_sel_hi:[0,1]
	v_pk_add_f32 v[142:143], v[36:37], v[36:37] op_sel:[0,1] op_sel_hi:[1,0] neg_lo:[0,1] neg_hi:[0,1]
	v_pk_add_f32 v[140:141], v[40:41], v[48:49] op_sel:[0,1] op_sel_hi:[1,0] neg_lo:[0,1] neg_hi:[0,1]
	v_pk_add_f32 v[40:41], v[40:41], v[48:49] op_sel:[0,1] op_sel_hi:[1,0]
	v_pk_fma_f32 v[64:65], v[64:65], v[56:57], v[144:145] op_sel:[1,1,0] op_sel_hi:[1,0,1] neg_lo:[1,0,0]
	v_pk_mul_f32 v[144:145], v[138:139], v[58:59] op_sel:[0,0] op_sel_hi:[0,1]
	v_mov_b32_e32 v48, v140
	v_mov_b32_e32 v49, v41
	v_mov_b32_e32 v41, v141
	v_pk_mul_f32 v[140:141], v[44:45], v[54:55] op_sel:[0,0] op_sel_hi:[0,1]
	v_pk_fma_f32 v[138:139], v[138:139], v[58:59], v[144:145] op_sel:[1,1,0] op_sel_hi:[1,0,1] neg_lo:[1,0,0]
	v_pk_mul_f32 v[144:145], v[34:35], v[50:51] op_sel:[0,0] op_sel_hi:[0,1]
	v_pk_add_f32 v[36:37], v[36:37], v[36:37] op_sel:[0,1] op_sel_hi:[1,0]
	v_pk_fma_f32 v[44:45], v[44:45], v[54:55], v[140:141] op_sel:[1,1,0] op_sel_hi:[1,0,1] neg_lo:[1,0,0]
	v_pk_mul_f32 v[140:141], v[46:47], v[52:53] op_sel:[0,0] op_sel_hi:[0,1]
	v_pk_fma_f32 v[34:35], v[34:35], v[50:51], v[144:145] op_sel:[1,1,0] op_sel_hi:[1,0,1] neg_lo:[1,0,0]
	v_pk_mul_f32 v[144:145], v[38:39], v[58:59] op_sel:[0,0] op_sel_hi:[0,1]
	v_pk_mov_b32 v[148:149], v[156:157], v[146:147] op_sel:[1,0]
	v_pk_fma_f32 v[46:47], v[46:47], v[52:53], v[140:141] op_sel:[1,1,0] op_sel_hi:[1,0,1] neg_lo:[1,0,0]
	v_pk_mul_f32 v[140:141], v[48:49], v[50:51] op_sel:[0,0] op_sel_hi:[0,1]
	v_pk_fma_f32 v[38:39], v[38:39], v[58:59], v[144:145] op_sel:[1,1,0] op_sel_hi:[1,0,1] neg_lo:[1,0,0]
	v_pk_mul_f32 v[144:145], v[40:41], v[60:61] op_sel:[0,0] op_sel_hi:[0,1]
	v_mov_b32_e32 v143, v45
	v_pk_fma_f32 v[48:49], v[48:49], v[50:51], v[140:141] op_sel:[1,1,0] op_sel_hi:[1,0,1] neg_lo:[1,0,0]
	v_mov_b32_e32 v160, v46
	v_mov_b32_e32 v161, v49
	v_pk_mul_f32 v[140:141], v[154:155], v[52:53] op_sel:[0,0] op_sel_hi:[0,1]
	v_pk_fma_f32 v[40:41], v[40:41], v[60:61], v[144:145] op_sel:[1,1,0] op_sel_hi:[1,0,1] neg_lo:[1,0,0]
	v_pk_mov_b32 v[144:145], v[42:43], v[158:159] op_sel:[1,0]
	v_pk_add_f32 v[160:161], v[142:143], v[160:161] neg_lo:[0,1] neg_hi:[0,1]
	v_mov_b32_e32 v143, v150
	v_pk_fma_f32 v[140:141], v[154:155], v[52:53], v[140:141] op_sel:[1,1,0] op_sel_hi:[1,0,1] neg_lo:[1,0,0]
	v_pk_add_f32 v[144:145], v[144:145], v[148:149] neg_lo:[0,1] neg_hi:[0,1]
	v_mov_b32_e32 v148, v42
	v_mov_b32_e32 v149, v159
	v_mov_b32_e32 v154, v156
	v_mov_b32_e32 v155, v147
	v_pk_add_f32 v[146:147], v[158:159], v[146:147]
	v_mov_b32_e32 v151, v44
	v_pk_mov_b32 v[158:159], v[46:47], v[48:49] op_sel:[1,0]
	v_pk_add_f32 v[46:47], v[142:143], v[46:47]
	v_pk_add_f32 v[44:45], v[44:45], v[48:49]
	v_mov_b32_e32 v37, v153
	v_pk_add_f32 v[148:149], v[148:149], v[154:155] neg_lo:[0,1] neg_hi:[0,1]
	v_pk_add_f32 v[42:43], v[42:43], v[156:157]
	v_pk_add_f32 v[158:159], v[150:151], v[158:159] neg_lo:[0,1] neg_hi:[0,1]
	v_pk_add_f32 v[48:49], v[46:47], v[44:45]
	v_pk_add_f32 v[44:45], v[46:47], v[44:45] neg_lo:[0,1] neg_hi:[0,1]
	v_pk_add_f32 v[46:47], v[160:161], v[160:161] op_sel:[0,1] op_sel_hi:[1,0] neg_lo:[0,1] neg_hi:[0,1]
	v_pk_add_f32 v[150:151], v[160:161], v[160:161] op_sel:[0,1] op_sel_hi:[1,0]
	v_pk_add_f32 v[160:161], v[62:63], v[64:65]
	v_pk_add_f32 v[162:163], v[140:141], v[138:139]
	v_pk_add_f32 v[62:63], v[62:63], v[64:65] neg_lo:[0,1] neg_hi:[0,1]
	v_pk_add_f32 v[64:65], v[140:141], v[138:139] neg_lo:[0,1] neg_hi:[0,1]
	v_pk_add_f32 v[140:141], v[36:37], v[38:39]
	v_pk_add_f32 v[152:153], v[34:35], v[40:41]
	v_pk_add_f32 v[36:37], v[36:37], v[38:39] neg_lo:[0,1] neg_hi:[0,1]
	v_pk_add_f32 v[34:35], v[34:35], v[40:41] neg_lo:[0,1] neg_hi:[0,1]
	v_pk_add_f32 v[154:155], v[42:43], v[146:147]
	v_pk_add_f32 v[42:43], v[42:43], v[146:147] neg_lo:[0,1] neg_hi:[0,1]
	v_pk_add_f32 v[146:147], v[148:149], v[148:149] op_sel:[0,1] op_sel_hi:[1,0] neg_lo:[0,1] neg_hi:[0,1]
	v_pk_add_f32 v[156:157], v[144:145], v[144:145] op_sel_hi:[0,1]
	v_pk_add_f32 v[142:143], v[158:159], v[158:159] op_sel_hi:[0,1]
	v_pk_add_f32 v[138:139], v[62:63], v[64:65] op_sel:[0,1] op_sel_hi:[1,0] neg_lo:[0,1] neg_hi:[0,1]
	v_pk_add_f32 v[62:63], v[62:63], v[64:65] op_sel:[0,1] op_sel_hi:[1,0]
	v_pk_add_f32 v[38:39], v[36:37], v[34:35] op_sel:[0,1] op_sel_hi:[1,0] neg_lo:[0,1] neg_hi:[0,1]
	v_pk_add_f32 v[34:35], v[36:37], v[34:35] op_sel:[0,1] op_sel_hi:[1,0]
	v_pk_add_f32 v[148:149], v[148:149], v[148:149] op_sel:[0,1] op_sel_hi:[1,0]
	v_pk_add_f32 v[144:145], v[144:145], v[144:145] op_sel_hi:[0,1] neg_lo:[0,1] neg_hi:[0,1]
	v_pk_add_f32 v[158:159], v[158:159], v[158:159] op_sel_hi:[0,1] neg_lo:[0,1] neg_hi:[0,1]
	v_mov_b32_e32 v65, v63
	v_mov_b32_e32 v37, v35
	v_mov_b32_e32 v147, v157
	v_mov_b32_e32 v47, v143
	v_mov_b32_e32 v63, v139
	v_mov_b32_e32 v35, v39
	v_pk_add_f32 v[164:165], v[160:161], v[162:163]
	v_pk_add_f32 v[160:161], v[160:161], v[162:163] neg_lo:[0,1] neg_hi:[0,1]
	v_mov_b32_e32 v64, v138
	v_pk_add_f32 v[162:163], v[140:141], v[152:153]
	v_pk_add_f32 v[140:141], v[140:141], v[152:153] neg_lo:[0,1] neg_hi:[0,1]
	v_mov_b32_e32 v36, v38
	ds_write2_b64 v85, v[154:155], v[48:49] offset1:4
	ds_write2_b64 v85, v[164:165], v[162:163] offset0:8 offset1:12
	ds_write2_b64 v85, v[146:147], v[46:47] offset0:17 offset1:21
	ds_write2_b64 v85, v[64:65], v[36:37] offset0:25 offset1:29
	ds_write2_b64 v85, v[42:43], v[44:45] offset0:34 offset1:38
	ds_write2_b64 v85, v[160:161], v[140:141] offset0:42 offset1:46
	v_mov_b32_e32 v149, v145
	v_mov_b32_e32 v151, v159
	ds_write2_b64 v85, v[62:63], v[34:35] offset0:59 offset1:63
	v_mov_b32_e32 v34, v0
	ds_write2_b64 v85, v[148:149], v[150:151] offset0:51 offset1:55
	s_waitcnt lgkmcnt(0)
	s_barrier
	s_nop 0
	v_and_b32_e32 v36, 63, v34
	v_lshlrev_b32_e32 v37, 4, v34
	v_cvt_f32_ubyte0_e32 v34, v36
	v_mul_f32_e32 v35, 0x3a800000, v34
	v_cos_f32_e32 v34, v35
	v_sin_f32_e32 v35, v35
	v_and_or_b32 v85, v37, s12, v36
	v_ashrrev_i32_e32 v36, 4, v85
	v_lshlrev_b32_e32 v36, 3, v36
	v_lshlrev_b32_e32 v37, 3, v85
	v_add3_u32 v98, 0, v36, v37
	ds_read2_b64 v[36:39], v98 offset1:68
	ds_read2_b64 v[40:43], v98 offset0:136 offset1:204
	v_add_u32_e32 v100, 0x800, v98
	v_add_u32_e32 v184, 0x1000, v98
	v_add_u32_e32 v185, 0x1800, v98
	v_mov_b32_e32 v48, v34
	v_mov_b32_e32 v49, v35
	ds_read2_b64 v[44:47], v100 offset0:16 offset1:84
	ds_read2_b64 v[62:65], v100 offset0:152 offset1:220
	ds_read2_b64 v[138:141], v184 offset0:32 offset1:100
	ds_read2_b64 v[142:145], v184 offset0:168 offset1:236
	ds_read2_b64 v[146:149], v185 offset0:48 offset1:116
	ds_read2_b64 v[150:153], v185 offset0:184 offset1:252
	s_nop 1
	s_nop 0
	v_pk_mul_f32 v[154:155], v[48:49], v[48:49] op_sel:[0,0] op_sel_hi:[0,1]
	s_waitcnt lgkmcnt(7)
	v_pk_mul_f32 v[182:183], v[38:39], v[48:49] op_sel:[0,0] op_sel_hi:[0,1]
	v_pk_fma_f32 v[154:155], v[48:49], v[48:49], v[154:155] op_sel:[1,1,0] op_sel_hi:[1,0,1] neg_lo:[1,0,0]
	s_nop 0
	v_pk_fma_f32 v[38:39], v[38:39], v[48:49], v[182:183] op_sel:[1,1,0] op_sel_hi:[1,0,1] neg_lo:[1,0,0]
	v_pk_mul_f32 v[158:159], v[154:155], v[154:155] op_sel:[0,0] op_sel_hi:[0,1]
	v_pk_mul_f32 v[156:157], v[154:155], v[48:49] op_sel:[0,0] op_sel_hi:[0,1]
	s_nop 0
	v_pk_fma_f32 v[158:159], v[154:155], v[154:155], v[158:159] op_sel:[1,1,0] op_sel_hi:[1,0,1] neg_lo:[1,0,0]
	v_pk_fma_f32 v[156:157], v[154:155], v[48:49], v[156:157] op_sel:[1,1,0] op_sel_hi:[1,0,1] neg_lo:[1,0,0]
	s_nop 0
	v_pk_mul_f32 v[166:167], v[158:159], v[158:159] op_sel:[0,0] op_sel_hi:[0,1]
	v_pk_mul_f32 v[160:161], v[158:159], v[48:49] op_sel:[0,0] op_sel_hi:[0,1]
	v_pk_mul_f32 v[162:163], v[156:157], v[156:157] op_sel:[0,0] op_sel_hi:[0,1]
	v_pk_mul_f32 v[164:165], v[158:159], v[156:157] op_sel:[0,0] op_sel_hi:[0,1]
	s_nop 0
	v_pk_fma_f32 v[166:167], v[158:159], v[158:159], v[166:167] op_sel:[1,1,0] op_sel_hi:[1,0,1] neg_lo:[1,0,0]
	v_pk_fma_f32 v[160:161], v[158:159], v[48:49], v[160:161] op_sel:[1,1,0] op_sel_hi:[1,0,1] neg_lo:[1,0,0]
	v_pk_fma_f32 v[162:163], v[156:157], v[156:157], v[162:163] op_sel:[1,1,0] op_sel_hi:[1,0,1] neg_lo:[1,0,0]
	v_pk_fma_f32 v[164:165], v[158:159], v[156:157], v[164:165] op_sel:[1,1,0] op_sel_hi:[1,0,1] neg_lo:[1,0,0]
	s_nop 0
	v_pk_mul_f32 v[168:169], v[166:167], v[48:49] op_sel:[0,0] op_sel_hi:[0,1]
	v_pk_mul_f32 v[170:171], v[160:161], v[160:161] op_sel:[0,0] op_sel_hi:[0,1]
	v_pk_mul_f32 v[172:173], v[166:167], v[156:157] op_sel:[0,0] op_sel_hi:[0,1]
	v_pk_mul_f32 v[174:175], v[162:163], v[162:163] op_sel:[0,0] op_sel_hi:[0,1]
	v_pk_mul_f32 v[176:177], v[166:167], v[160:161] op_sel:[0,0] op_sel_hi:[0,1]
	v_pk_mul_f32 v[178:179], v[164:165], v[164:165] op_sel:[0,0] op_sel_hi:[0,1]
	s_nop 0
	v_pk_fma_f32 v[168:169], v[166:167], v[48:49], v[168:169] op_sel:[1,1,0] op_sel_hi:[1,0,1] neg_lo:[1,0,0]
	s_waitcnt lgkmcnt(6)
	v_pk_mul_f32 v[48:49], v[40:41], v[154:155] op_sel:[0,0] op_sel_hi:[0,1]
	v_pk_fma_f32 v[170:171], v[160:161], v[160:161], v[170:171] op_sel:[1,1,0] op_sel_hi:[1,0,1] neg_lo:[1,0,0]
	v_pk_fma_f32 v[172:173], v[166:167], v[156:157], v[172:173] op_sel:[1,1,0] op_sel_hi:[1,0,1] neg_lo:[1,0,0]
	v_pk_fma_f32 v[174:175], v[162:163], v[162:163], v[174:175] op_sel:[1,1,0] op_sel_hi:[1,0,1] neg_lo:[1,0,0]
	v_pk_fma_f32 v[176:177], v[166:167], v[160:161], v[176:177] op_sel:[1,1,0] op_sel_hi:[1,0,1] neg_lo:[1,0,0]
	v_pk_fma_f32 v[178:179], v[164:165], v[164:165], v[178:179] op_sel:[1,1,0] op_sel_hi:[1,0,1] neg_lo:[1,0,0]
	s_nop 0
	v_pk_fma_f32 v[40:41], v[40:41], v[154:155], v[48:49] op_sel:[1,1,0] op_sel_hi:[1,0,1] neg_lo:[1,0,0]
	v_pk_mul_f32 v[48:49], v[42:43], v[156:157] op_sel:[0,0] op_sel_hi:[0,1]
	v_pk_mul_f32 v[180:181], v[166:167], v[164:165] op_sel:[0,0] op_sel_hi:[0,1]
	s_nop 0
	v_pk_fma_f32 v[42:43], v[42:43], v[156:157], v[48:49] op_sel:[1,1,0] op_sel_hi:[1,0,1] neg_lo:[1,0,0]
	s_waitcnt lgkmcnt(5)
	v_pk_mul_f32 v[48:49], v[44:45], v[158:159] op_sel:[0,0] op_sel_hi:[0,1]
	v_pk_fma_f32 v[180:181], v[166:167], v[164:165], v[180:181] op_sel:[1,1,0] op_sel_hi:[1,0,1] neg_lo:[1,0,0]
	v_mov_b32_e32 v156, v37
	v_pk_fma_f32 v[44:45], v[44:45], v[158:159], v[48:49] op_sel:[1,1,0] op_sel_hi:[1,0,1] neg_lo:[1,0,0]
	v_pk_mul_f32 v[48:49], v[46:47], v[160:161] op_sel:[0,0] op_sel_hi:[0,1]
	s_nop 0
	v_pk_fma_f32 v[46:47], v[46:47], v[160:161], v[48:49] op_sel:[1,1,0] op_sel_hi:[1,0,1] neg_lo:[1,0,0]
	s_waitcnt lgkmcnt(4)
	v_pk_mul_f32 v[48:49], v[62:63], v[162:163] op_sel:[0,0] op_sel_hi:[0,1]
	v_mov_b32_e32 v157, v45
	v_pk_fma_f32 v[48:49], v[62:63], v[162:163], v[48:49] op_sel:[1,1,0] op_sel_hi:[1,0,1] neg_lo:[1,0,0]
	v_pk_mul_f32 v[62:63], v[64:65], v[164:165] op_sel:[0,0] op_sel_hi:[0,1]
	s_nop 0
	v_pk_fma_f32 v[62:63], v[64:65], v[164:165], v[62:63] op_sel:[1,1,0] op_sel_hi:[1,0,1] neg_lo:[1,0,0]
	s_waitcnt lgkmcnt(3)
	v_pk_mul_f32 v[64:65], v[138:139], v[166:167] op_sel:[0,0] op_sel_hi:[0,1]
	s_nop 0
	v_pk_fma_f32 v[64:65], v[138:139], v[166:167], v[64:65] op_sel:[1,1,0] op_sel_hi:[1,0,1] neg_lo:[1,0,0]
	v_pk_mul_f32 v[138:139], v[140:141], v[168:169] op_sel:[0,0] op_sel_hi:[0,1]
	s_nop 0
	v_pk_fma_f32 v[138:139], v[140:141], v[168:169], v[138:139] op_sel:[1,1,0] op_sel_hi:[1,0,1] neg_lo:[1,0,0]
	s_waitcnt lgkmcnt(2)
	v_pk_mul_f32 v[140:141], v[142:143], v[170:171] op_sel:[0,0] op_sel_hi:[0,1]
	v_mov_b32_e32 v158, v65
	v_pk_fma_f32 v[140:141], v[142:143], v[170:171], v[140:141] op_sel:[1,1,0] op_sel_hi:[1,0,1] neg_lo:[1,0,0]
	v_pk_mul_f32 v[142:143], v[144:145], v[172:173] op_sel:[0,0] op_sel_hi:[0,1]
	s_nop 0
	v_pk_fma_f32 v[142:143], v[144:145], v[172:173], v[142:143] op_sel:[1,1,0] op_sel_hi:[1,0,1] neg_lo:[1,0,0]
	s_waitcnt lgkmcnt(1)
	v_pk_mul_f32 v[144:145], v[146:147], v[174:175] op_sel:[0,0] op_sel_hi:[0,1]
	s_nop 0
	v_pk_fma_f32 v[144:145], v[146:147], v[174:175], v[144:145] op_sel:[1,1,0] op_sel_hi:[1,0,1] neg_lo:[1,0,0]
	v_pk_mul_f32 v[146:147], v[148:149], v[176:177] op_sel:[0,0] op_sel_hi:[0,1]
	s_nop 0
	v_pk_fma_f32 v[146:147], v[148:149], v[176:177], v[146:147] op_sel:[1,1,0] op_sel_hi:[1,0,1] neg_lo:[1,0,0]
	s_waitcnt lgkmcnt(0)
	v_pk_mul_f32 v[148:149], v[150:151], v[178:179] op_sel:[0,0] op_sel_hi:[0,1]
	v_mov_b32_e32 v159, v145
	v_pk_fma_f32 v[148:149], v[150:151], v[178:179], v[148:149] op_sel:[1,1,0] op_sel_hi:[1,0,1] neg_lo:[1,0,0]
	v_pk_mul_f32 v[150:151], v[152:153], v[180:181] op_sel:[0,0] op_sel_hi:[0,1]
	v_pk_add_f32 v[154:155], v[44:45], v[144:145]
	v_pk_fma_f32 v[150:151], v[152:153], v[180:181], v[150:151] op_sel:[1,1,0] op_sel_hi:[1,0,1] neg_lo:[1,0,0]
	v_pk_add_f32 v[152:153], v[36:37], v[64:65]
	v_pk_add_f32 v[156:157], v[156:157], v[158:159]
	v_pk_mov_b32 v[158:159], v[36:37], v[44:45] op_sel:[1,0]
	v_pk_mov_b32 v[160:161], v[64:65], v[144:145] op_sel:[1,0]
	v_mov_b32_e32 v37, v45
	v_pk_add_f32 v[158:159], v[158:159], v[160:161] neg_lo:[0,1] neg_hi:[0,1]
	v_mov_b32_e32 v65, v145
	v_mov_b32_e32 v153, v156
	v_mov_b32_e32 v155, v157
	v_pk_add_f32 v[36:37], v[36:37], v[64:65] neg_lo:[0,1] neg_hi:[0,1]
	v_pk_add_f32 v[44:45], v[152:153], v[154:155]
	v_pk_add_f32 v[64:65], v[152:153], v[154:155] neg_lo:[0,1] neg_hi:[0,1]
	v_pk_add_f32 v[152:153], v[158:159], v[158:159] op_sel:[0,1] op_sel_hi:[1,0]
	v_pk_add_f32 v[154:155], v[158:159], v[158:159] op_sel_hi:[0,1] neg_lo:[0,1] neg_hi:[0,1]
	v_pk_add_f32 v[156:157], v[38:39], v[138:139]
	v_pk_add_f32 v[158:159], v[46:47], v[146:147]
	v_pk_add_f32 v[38:39], v[38:39], v[138:139] neg_lo:[0,1] neg_hi:[0,1]
	v_pk_add_f32 v[46:47], v[46:47], v[146:147] neg_lo:[0,1] neg_hi:[0,1]
	v_pk_add_f32 v[146:147], v[48:49], v[148:149]
	v_pk_add_f32 v[138:139], v[38:39], v[46:47] op_sel:[0,1] op_sel_hi:[1,0] neg_lo:[0,1] neg_hi:[0,1]
	v_pk_add_f32 v[38:39], v[38:39], v[46:47] op_sel:[0,1] op_sel_hi:[1,0]
	v_mov_b32_e32 v46, v138
	v_mov_b32_e32 v47, v39
	v_mov_b32_e32 v39, v139
	v_pk_add_f32 v[138:139], v[40:41], v[140:141]
	v_pk_add_f32 v[40:41], v[40:41], v[140:141] neg_lo:[0,1] neg_hi:[0,1]
	v_pk_add_f32 v[48:49], v[48:49], v[148:149] neg_lo:[0,1] neg_hi:[0,1]
	v_pk_add_f32 v[160:161], v[156:157], v[158:159]
	v_pk_add_f32 v[140:141], v[40:41], v[48:49] op_sel:[0,1] op_sel_hi:[1,0] neg_lo:[0,1] neg_hi:[0,1]
	v_pk_add_f32 v[40:41], v[40:41], v[48:49] op_sel:[0,1] op_sel_hi:[1,0]
	v_pk_add_f32 v[156:157], v[156:157], v[158:159] neg_lo:[0,1] neg_hi:[0,1]
	v_pk_add_f32 v[158:159], v[138:139], v[146:147]
	v_pk_add_f32 v[138:139], v[138:139], v[146:147] neg_lo:[0,1] neg_hi:[0,1]
	v_mov_b32_e32 v48, v140
	v_mov_b32_e32 v49, v41
	v_mov_b32_e32 v41, v141
	v_pk_add_f32 v[140:141], v[42:43], v[142:143]
	v_pk_add_f32 v[146:147], v[62:63], v[150:151]
	v_pk_add_f32 v[42:43], v[42:43], v[142:143] neg_lo:[0,1] neg_hi:[0,1]
	v_pk_add_f32 v[148:149], v[140:141], v[146:147]
	v_pk_add_f32 v[140:141], v[140:141], v[146:147] neg_lo:[0,1] neg_hi:[0,1]
	v_pk_add_f32 v[62:63], v[62:63], v[150:151] neg_lo:[0,1] neg_hi:[0,1]
	v_pk_mul_f32 v[146:147], v[138:139], v[56:57] op_sel:[0,0] op_sel_hi:[0,1]
	v_pk_add_f32 v[144:145], v[36:37], v[36:37] op_sel:[0,1] op_sel_hi:[1,0] neg_lo:[0,1] neg_hi:[0,1]
	v_pk_add_f32 v[142:143], v[42:43], v[62:63] op_sel:[0,1] op_sel_hi:[1,0] neg_lo:[0,1] neg_hi:[0,1]
	v_pk_add_f32 v[42:43], v[42:43], v[62:63] op_sel:[0,1] op_sel_hi:[1,0]
	v_pk_fma_f32 v[138:139], v[138:139], v[56:57], v[146:147] op_sel:[1,1,0] op_sel_hi:[1,0,1] neg_lo:[1,0,0]
	v_pk_mul_f32 v[146:147], v[140:141], v[58:59] op_sel:[0,0] op_sel_hi:[0,1]
	v_mov_b32_e32 v62, v142
	v_mov_b32_e32 v63, v43
	v_mov_b32_e32 v43, v143
	v_pk_mul_f32 v[142:143], v[46:47], v[54:55] op_sel:[0,0] op_sel_hi:[0,1]
	v_pk_fma_f32 v[140:141], v[140:141], v[58:59], v[146:147] op_sel:[1,1,0] op_sel_hi:[1,0,1] neg_lo:[1,0,0]
	v_pk_mul_f32 v[146:147], v[38:39], v[50:51] op_sel:[0,0] op_sel_hi:[0,1]
	v_pk_add_f32 v[36:37], v[36:37], v[36:37] op_sel:[0,1] op_sel_hi:[1,0]
	v_pk_fma_f32 v[46:47], v[46:47], v[54:55], v[142:143] op_sel:[1,1,0] op_sel_hi:[1,0,1] neg_lo:[1,0,0]
	v_pk_mul_f32 v[142:143], v[48:49], v[52:53] op_sel:[0,0] op_sel_hi:[0,1]
	v_pk_fma_f32 v[38:39], v[38:39], v[50:51], v[146:147] op_sel:[1,1,0] op_sel_hi:[1,0,1] neg_lo:[1,0,0]
	v_pk_mul_f32 v[146:147], v[40:41], v[58:59] op_sel:[0,0] op_sel_hi:[0,1]
	v_pk_mov_b32 v[150:151], v[158:159], v[148:149] op_sel:[1,0]
	v_pk_fma_f32 v[48:49], v[48:49], v[52:53], v[142:143] op_sel:[1,1,0] op_sel_hi:[1,0,1] neg_lo:[1,0,0]
	v_pk_mul_f32 v[142:143], v[62:63], v[50:51] op_sel:[0,0] op_sel_hi:[0,1]
	v_pk_fma_f32 v[40:41], v[40:41], v[58:59], v[146:147] op_sel:[1,1,0] op_sel_hi:[1,0,1] neg_lo:[1,0,0]
	v_pk_mul_f32 v[146:147], v[42:43], v[60:61] op_sel:[0,0] op_sel_hi:[0,1]
	v_mov_b32_e32 v145, v47
	v_pk_fma_f32 v[62:63], v[62:63], v[50:51], v[142:143] op_sel:[1,1,0] op_sel_hi:[1,0,1] neg_lo:[1,0,0]
	v_mov_b32_e32 v162, v48
	v_mov_b32_e32 v163, v63
	v_pk_mul_f32 v[142:143], v[156:157], v[52:53] op_sel:[0,0] op_sel_hi:[0,1]
	v_pk_fma_f32 v[42:43], v[42:43], v[60:61], v[146:147] op_sel:[1,1,0] op_sel_hi:[1,0,1] neg_lo:[1,0,0]
	v_pk_mov_b32 v[146:147], v[44:45], v[160:161] op_sel:[1,0]
	v_pk_add_f32 v[162:163], v[144:145], v[162:163] neg_lo:[0,1] neg_hi:[0,1]
	v_mov_b32_e32 v145, v152
	v_pk_fma_f32 v[142:143], v[156:157], v[52:53], v[142:143] op_sel:[1,1,0] op_sel_hi:[1,0,1] neg_lo:[1,0,0]
	v_pk_add_f32 v[146:147], v[146:147], v[150:151] neg_lo:[0,1] neg_hi:[0,1]
	v_mov_b32_e32 v150, v44
	v_mov_b32_e32 v151, v161
	v_mov_b32_e32 v156, v158
	v_mov_b32_e32 v157, v149
	v_pk_add_f32 v[148:149], v[160:161], v[148:149]
	v_mov_b32_e32 v153, v46
	v_pk_mov_b32 v[160:161], v[48:49], v[62:63] op_sel:[1,0]
	v_pk_add_f32 v[48:49], v[144:145], v[48:49]
	v_pk_add_f32 v[46:47], v[46:47], v[62:63]
	v_mov_b32_e32 v37, v155
	v_pk_add_f32 v[150:151], v[150:151], v[156:157] neg_lo:[0,1] neg_hi:[0,1]
	v_pk_add_f32 v[44:45], v[44:45], v[158:159]
	v_pk_add_f32 v[160:161], v[152:153], v[160:161] neg_lo:[0,1] neg_hi:[0,1]
	v_pk_add_f32 v[62:63], v[48:49], v[46:47]
	v_pk_add_f32 v[46:47], v[48:49], v[46:47] neg_lo:[0,1] neg_hi:[0,1]
	v_pk_add_f32 v[48:49], v[162:163], v[162:163] op_sel:[0,1] op_sel_hi:[1,0] neg_lo:[0,1] neg_hi:[0,1]
	v_pk_add_f32 v[152:153], v[162:163], v[162:163] op_sel:[0,1] op_sel_hi:[1,0]
	v_pk_add_f32 v[162:163], v[64:65], v[138:139]
	v_pk_add_f32 v[164:165], v[142:143], v[140:141]
	v_pk_add_f32 v[64:65], v[64:65], v[138:139] neg_lo:[0,1] neg_hi:[0,1]
	v_pk_add_f32 v[138:139], v[142:143], v[140:141] neg_lo:[0,1] neg_hi:[0,1]
	v_pk_add_f32 v[142:143], v[36:37], v[40:41]
	v_pk_add_f32 v[154:155], v[38:39], v[42:43]
	v_pk_add_f32 v[36:37], v[36:37], v[40:41] neg_lo:[0,1] neg_hi:[0,1]
	v_pk_add_f32 v[38:39], v[38:39], v[42:43] neg_lo:[0,1] neg_hi:[0,1]
	v_pk_add_f32 v[156:157], v[44:45], v[148:149]
	v_pk_add_f32 v[44:45], v[44:45], v[148:149] neg_lo:[0,1] neg_hi:[0,1]
	v_pk_add_f32 v[148:149], v[150:151], v[150:151] op_sel:[0,1] op_sel_hi:[1,0] neg_lo:[0,1] neg_hi:[0,1]
	v_pk_add_f32 v[158:159], v[146:147], v[146:147] op_sel_hi:[0,1]
	v_pk_add_f32 v[144:145], v[160:161], v[160:161] op_sel_hi:[0,1]
	v_pk_add_f32 v[140:141], v[64:65], v[138:139] op_sel:[0,1] op_sel_hi:[1,0] neg_lo:[0,1] neg_hi:[0,1]
	v_pk_add_f32 v[64:65], v[64:65], v[138:139] op_sel:[0,1] op_sel_hi:[1,0]
	v_pk_add_f32 v[40:41], v[36:37], v[38:39] op_sel:[0,1] op_sel_hi:[1,0] neg_lo:[0,1] neg_hi:[0,1]
	v_pk_add_f32 v[36:37], v[36:37], v[38:39] op_sel:[0,1] op_sel_hi:[1,0]
	v_mov_b32_e32 v139, v65
	v_mov_b32_e32 v39, v37
	v_mov_b32_e32 v149, v159
	v_mov_b32_e32 v49, v145
	v_mov_b32_e32 v65, v141
	v_mov_b32_e32 v37, v41
	v_pk_add_f32 v[166:167], v[162:163], v[164:165]
	v_pk_add_f32 v[162:163], v[162:163], v[164:165] neg_lo:[0,1] neg_hi:[0,1]
	v_mov_b32_e32 v138, v140
	v_pk_add_f32 v[164:165], v[142:143], v[154:155]
	v_pk_add_f32 v[142:143], v[142:143], v[154:155] neg_lo:[0,1] neg_hi:[0,1]
	v_mov_b32_e32 v38, v40
	ds_write2_b64 v98, v[156:157], v[62:63] offset1:68
	ds_write2_b64 v98, v[166:167], v[164:165] offset0:136 offset1:204
	ds_write2_b64 v100, v[148:149], v[48:49] offset0:16 offset1:84
	ds_write2_b64 v100, v[138:139], v[38:39] offset0:152 offset1:220
	ds_write2_b64 v184, v[44:45], v[46:47] offset0:32 offset1:100
	ds_write2_b64 v184, v[162:163], v[142:143] offset0:168 offset1:236
	ds_write2_b64 v185, v[64:65], v[36:37] offset0:184 offset1:252
	v_add_u32_e32 v36, 0x2000, v85
	v_pk_add_f32 v[150:151], v[150:151], v[150:151] op_sel:[0,1] op_sel_hi:[1,0]
	v_pk_add_f32 v[146:147], v[146:147], v[146:147] op_sel_hi:[0,1] neg_lo:[0,1] neg_hi:[0,1]
	v_pk_add_f32 v[160:161], v[160:161], v[160:161] op_sel_hi:[0,1] neg_lo:[0,1] neg_hi:[0,1]
	v_ashrrev_i32_e32 v37, 4, v36
	v_mov_b32_e32 v151, v147
	v_mov_b32_e32 v153, v161
	v_lshlrev_b32_e32 v37, 3, v37
	v_lshlrev_b32_e32 v36, 3, v36
	ds_write2_b64 v185, v[150:151], v[152:153] offset0:48 offset1:116
	v_add3_u32 v85, 0, v37, v36
	ds_read2_b64 v[36:39], v85 offset1:68
	ds_read2_b64 v[40:43], v85 offset0:136 offset1:204
	v_add_u32_e32 v98, 0x800, v85
	v_add_u32_e32 v100, 0x1000, v85
	v_add_u32_e32 v182, 0x1800, v85
	ds_read2_b64 v[44:47], v98 offset0:16 offset1:84
	ds_read2_b64 v[62:65], v98 offset0:152 offset1:220
	ds_read2_b64 v[138:141], v100 offset0:32 offset1:100
	ds_read2_b64 v[142:145], v100 offset0:168 offset1:236
	ds_read2_b64 v[146:149], v182 offset0:48 offset1:116
	ds_read2_b64 v[150:153], v182 offset0:184 offset1:252
	s_nop 1
	s_nop 0
	v_pk_mul_f32 v[48:49], v[34:35], v[34:35] op_sel:[0,0] op_sel_hi:[0,1]
	s_waitcnt lgkmcnt(7)
	v_pk_mul_f32 v[180:181], v[38:39], v[34:35] op_sel:[0,0] op_sel_hi:[0,1]
	v_pk_fma_f32 v[48:49], v[34:35], v[34:35], v[48:49] op_sel:[1,1,0] op_sel_hi:[1,0,1] neg_lo:[1,0,0]
	s_nop 0
	v_pk_mul_f32 v[156:157], v[48:49], v[48:49] op_sel:[0,0] op_sel_hi:[0,1]
	v_pk_mul_f32 v[154:155], v[48:49], v[34:35] op_sel:[0,0] op_sel_hi:[0,1]
	s_nop 0
	v_pk_fma_f32 v[156:157], v[48:49], v[48:49], v[156:157] op_sel:[1,1,0] op_sel_hi:[1,0,1] neg_lo:[1,0,0]
	v_pk_fma_f32 v[154:155], v[48:49], v[34:35], v[154:155] op_sel:[1,1,0] op_sel_hi:[1,0,1] neg_lo:[1,0,0]
	s_nop 0
	v_pk_mul_f32 v[164:165], v[156:157], v[156:157] op_sel:[0,0] op_sel_hi:[0,1]
	v_pk_mul_f32 v[158:159], v[156:157], v[34:35] op_sel:[0,0] op_sel_hi:[0,1]
	v_pk_mul_f32 v[160:161], v[154:155], v[154:155] op_sel:[0,0] op_sel_hi:[0,1]
	v_pk_mul_f32 v[162:163], v[156:157], v[154:155] op_sel:[0,0] op_sel_hi:[0,1]
	s_nop 0
	v_pk_fma_f32 v[164:165], v[156:157], v[156:157], v[164:165] op_sel:[1,1,0] op_sel_hi:[1,0,1] neg_lo:[1,0,0]
	v_pk_fma_f32 v[158:159], v[156:157], v[34:35], v[158:159] op_sel:[1,1,0] op_sel_hi:[1,0,1] neg_lo:[1,0,0]
	v_pk_fma_f32 v[160:161], v[154:155], v[154:155], v[160:161] op_sel:[1,1,0] op_sel_hi:[1,0,1] neg_lo:[1,0,0]
	v_pk_fma_f32 v[162:163], v[156:157], v[154:155], v[162:163] op_sel:[1,1,0] op_sel_hi:[1,0,1] neg_lo:[1,0,0]
	s_nop 0
	v_pk_mul_f32 v[166:167], v[164:165], v[34:35] op_sel:[0,0] op_sel_hi:[0,1]
	v_pk_mul_f32 v[168:169], v[158:159], v[158:159] op_sel:[0,0] op_sel_hi:[0,1]
	v_pk_mul_f32 v[170:171], v[164:165], v[154:155] op_sel:[0,0] op_sel_hi:[0,1]
	v_pk_mul_f32 v[172:173], v[160:161], v[160:161] op_sel:[0,0] op_sel_hi:[0,1]
	v_pk_mul_f32 v[174:175], v[164:165], v[158:159] op_sel:[0,0] op_sel_hi:[0,1]
	v_pk_mul_f32 v[176:177], v[162:163], v[162:163] op_sel:[0,0] op_sel_hi:[0,1]
	s_nop 0
	v_pk_fma_f32 v[166:167], v[164:165], v[34:35], v[166:167] op_sel:[1,1,0] op_sel_hi:[1,0,1] neg_lo:[1,0,0]
	v_pk_fma_f32 v[34:35], v[38:39], v[34:35], v[180:181] op_sel:[1,1,0] op_sel_hi:[1,0,1] neg_lo:[1,0,0]
	s_waitcnt lgkmcnt(6)
	v_pk_mul_f32 v[38:39], v[40:41], v[48:49] op_sel:[0,0] op_sel_hi:[0,1]
	v_pk_fma_f32 v[168:169], v[158:159], v[158:159], v[168:169] op_sel:[1,1,0] op_sel_hi:[1,0,1] neg_lo:[1,0,0]
	v_pk_fma_f32 v[170:171], v[164:165], v[154:155], v[170:171] op_sel:[1,1,0] op_sel_hi:[1,0,1] neg_lo:[1,0,0]
	v_pk_fma_f32 v[172:173], v[160:161], v[160:161], v[172:173] op_sel:[1,1,0] op_sel_hi:[1,0,1] neg_lo:[1,0,0]
	v_pk_fma_f32 v[174:175], v[164:165], v[158:159], v[174:175] op_sel:[1,1,0] op_sel_hi:[1,0,1] neg_lo:[1,0,0]
	v_pk_mul_f32 v[178:179], v[164:165], v[162:163] op_sel:[0,0] op_sel_hi:[0,1]
	s_nop 0
	v_pk_fma_f32 v[38:39], v[40:41], v[48:49], v[38:39] op_sel:[1,1,0] op_sel_hi:[1,0,1] neg_lo:[1,0,0]
	v_pk_mul_f32 v[40:41], v[42:43], v[154:155] op_sel:[0,0] op_sel_hi:[0,1]
	s_waitcnt lgkmcnt(4)
	v_pk_mul_f32 v[48:49], v[64:65], v[162:163] op_sel:[0,0] op_sel_hi:[0,1]
	v_pk_fma_f32 v[176:177], v[162:163], v[162:163], v[176:177] op_sel:[1,1,0] op_sel_hi:[1,0,1] neg_lo:[1,0,0]
	v_pk_fma_f32 v[40:41], v[42:43], v[154:155], v[40:41] op_sel:[1,1,0] op_sel_hi:[1,0,1] neg_lo:[1,0,0]
	v_pk_mul_f32 v[42:43], v[44:45], v[156:157] op_sel:[0,0] op_sel_hi:[0,1]
	s_nop 0
	v_pk_fma_f32 v[48:49], v[64:65], v[162:163], v[48:49] op_sel:[1,1,0] op_sel_hi:[1,0,1] neg_lo:[1,0,0]
	s_waitcnt lgkmcnt(3)
	v_pk_mul_f32 v[64:65], v[140:141], v[166:167] op_sel:[0,0] op_sel_hi:[0,1]
	v_pk_fma_f32 v[178:179], v[164:165], v[162:163], v[178:179] op_sel:[1,1,0] op_sel_hi:[1,0,1] neg_lo:[1,0,0]
	v_mov_b32_e32 v154, v37
	v_pk_fma_f32 v[42:43], v[44:45], v[156:157], v[42:43] op_sel:[1,1,0] op_sel_hi:[1,0,1] neg_lo:[1,0,0]
	v_pk_mul_f32 v[44:45], v[46:47], v[158:159] op_sel:[0,0] op_sel_hi:[0,1]
	v_pk_fma_f32 v[64:65], v[140:141], v[166:167], v[64:65] op_sel:[1,1,0] op_sel_hi:[1,0,1] neg_lo:[1,0,0]
	s_waitcnt lgkmcnt(2)
	v_pk_mul_f32 v[140:141], v[144:145], v[170:171] op_sel:[0,0] op_sel_hi:[0,1]
	v_pk_fma_f32 v[44:45], v[46:47], v[158:159], v[44:45] op_sel:[1,1,0] op_sel_hi:[1,0,1] neg_lo:[1,0,0]
	v_pk_mul_f32 v[46:47], v[62:63], v[160:161] op_sel:[0,0] op_sel_hi:[0,1]
	s_nop 0
	v_pk_fma_f32 v[140:141], v[144:145], v[170:171], v[140:141] op_sel:[1,1,0] op_sel_hi:[1,0,1] neg_lo:[1,0,0]
	s_waitcnt lgkmcnt(1)
	v_pk_mul_f32 v[144:145], v[148:149], v[174:175] op_sel:[0,0] op_sel_hi:[0,1]
	v_mov_b32_e32 v155, v43
	v_pk_fma_f32 v[46:47], v[62:63], v[160:161], v[46:47] op_sel:[1,1,0] op_sel_hi:[1,0,1] neg_lo:[1,0,0]
	v_pk_mul_f32 v[62:63], v[138:139], v[164:165] op_sel:[0,0] op_sel_hi:[0,1]
	v_pk_fma_f32 v[144:145], v[148:149], v[174:175], v[144:145] op_sel:[1,1,0] op_sel_hi:[1,0,1] neg_lo:[1,0,0]
	s_waitcnt lgkmcnt(0)
	v_pk_mul_f32 v[148:149], v[152:153], v[178:179] op_sel:[0,0] op_sel_hi:[0,1]
	v_pk_fma_f32 v[62:63], v[138:139], v[164:165], v[62:63] op_sel:[1,1,0] op_sel_hi:[1,0,1] neg_lo:[1,0,0]
	v_pk_mul_f32 v[138:139], v[142:143], v[168:169] op_sel:[0,0] op_sel_hi:[0,1]
	s_nop 0
	v_pk_fma_f32 v[148:149], v[152:153], v[178:179], v[148:149] op_sel:[1,1,0] op_sel_hi:[1,0,1] neg_lo:[1,0,0]
	v_pk_fma_f32 v[138:139], v[142:143], v[168:169], v[138:139] op_sel:[1,1,0] op_sel_hi:[1,0,1] neg_lo:[1,0,0]
	v_pk_mul_f32 v[142:143], v[146:147], v[172:173] op_sel:[0,0] op_sel_hi:[0,1]
	v_mov_b32_e32 v156, v63
	v_pk_fma_f32 v[142:143], v[146:147], v[172:173], v[142:143] op_sel:[1,1,0] op_sel_hi:[1,0,1] neg_lo:[1,0,0]
	v_pk_mul_f32 v[146:147], v[150:151], v[176:177] op_sel:[0,0] op_sel_hi:[0,1]
	s_nop 0
	v_mov_b32_e32 v157, v143
	v_pk_fma_f32 v[146:147], v[150:151], v[176:177], v[146:147] op_sel:[1,1,0] op_sel_hi:[1,0,1] neg_lo:[1,0,0]
	v_pk_add_f32 v[150:151], v[36:37], v[62:63]
	v_pk_add_f32 v[152:153], v[42:43], v[142:143]
	v_pk_add_f32 v[154:155], v[154:155], v[156:157]
	v_pk_mov_b32 v[156:157], v[36:37], v[42:43] op_sel:[1,0]
	v_pk_mov_b32 v[158:159], v[62:63], v[142:143] op_sel:[1,0]
	v_mov_b32_e32 v37, v43
	v_pk_add_f32 v[156:157], v[156:157], v[158:159] neg_lo:[0,1] neg_hi:[0,1]
	v_mov_b32_e32 v63, v143
	v_mov_b32_e32 v151, v154
	v_mov_b32_e32 v153, v155
	v_pk_add_f32 v[36:37], v[36:37], v[62:63] neg_lo:[0,1] neg_hi:[0,1]
	v_pk_add_f32 v[42:43], v[150:151], v[152:153]
	v_pk_add_f32 v[62:63], v[150:151], v[152:153] neg_lo:[0,1] neg_hi:[0,1]
	v_pk_add_f32 v[150:151], v[156:157], v[156:157] op_sel:[0,1] op_sel_hi:[1,0]
	v_pk_add_f32 v[152:153], v[156:157], v[156:157] op_sel_hi:[0,1] neg_lo:[0,1] neg_hi:[0,1]
	v_pk_add_f32 v[154:155], v[34:35], v[64:65]
	v_pk_add_f32 v[156:157], v[44:45], v[144:145]
	v_pk_add_f32 v[34:35], v[34:35], v[64:65] neg_lo:[0,1] neg_hi:[0,1]
	v_pk_add_f32 v[44:45], v[44:45], v[144:145] neg_lo:[0,1] neg_hi:[0,1]
	v_pk_add_f32 v[144:145], v[46:47], v[146:147]
	v_pk_add_f32 v[64:65], v[34:35], v[44:45] op_sel:[0,1] op_sel_hi:[1,0] neg_lo:[0,1] neg_hi:[0,1]
	v_pk_add_f32 v[34:35], v[34:35], v[44:45] op_sel:[0,1] op_sel_hi:[1,0]
	v_mov_b32_e32 v44, v64
	v_mov_b32_e32 v45, v35
	v_mov_b32_e32 v35, v65
	v_pk_add_f32 v[64:65], v[38:39], v[138:139]
	v_pk_add_f32 v[38:39], v[38:39], v[138:139] neg_lo:[0,1] neg_hi:[0,1]
	v_pk_add_f32 v[46:47], v[46:47], v[146:147] neg_lo:[0,1] neg_hi:[0,1]
	v_pk_add_f32 v[158:159], v[154:155], v[156:157]
	v_pk_add_f32 v[138:139], v[38:39], v[46:47] op_sel:[0,1] op_sel_hi:[1,0] neg_lo:[0,1] neg_hi:[0,1]
	v_pk_add_f32 v[38:39], v[38:39], v[46:47] op_sel:[0,1] op_sel_hi:[1,0]
	v_pk_add_f32 v[154:155], v[154:155], v[156:157] neg_lo:[0,1] neg_hi:[0,1]
	v_pk_add_f32 v[156:157], v[64:65], v[144:145]
	v_pk_add_f32 v[64:65], v[64:65], v[144:145] neg_lo:[0,1] neg_hi:[0,1]
	v_mov_b32_e32 v46, v138
	v_mov_b32_e32 v47, v39
	v_mov_b32_e32 v39, v139
	v_pk_add_f32 v[138:139], v[40:41], v[140:141]
	v_pk_add_f32 v[144:145], v[48:49], v[148:149]
	v_pk_add_f32 v[40:41], v[40:41], v[140:141] neg_lo:[0,1] neg_hi:[0,1]
	v_pk_add_f32 v[146:147], v[138:139], v[144:145]
	v_pk_add_f32 v[138:139], v[138:139], v[144:145] neg_lo:[0,1] neg_hi:[0,1]
	v_pk_add_f32 v[48:49], v[48:49], v[148:149] neg_lo:[0,1] neg_hi:[0,1]
	v_pk_mul_f32 v[144:145], v[64:65], v[56:57] op_sel:[0,0] op_sel_hi:[0,1]
	v_pk_add_f32 v[142:143], v[36:37], v[36:37] op_sel:[0,1] op_sel_hi:[1,0] neg_lo:[0,1] neg_hi:[0,1]
	v_pk_add_f32 v[140:141], v[40:41], v[48:49] op_sel:[0,1] op_sel_hi:[1,0] neg_lo:[0,1] neg_hi:[0,1]
	v_pk_add_f32 v[40:41], v[40:41], v[48:49] op_sel:[0,1] op_sel_hi:[1,0]
	v_pk_fma_f32 v[64:65], v[64:65], v[56:57], v[144:145] op_sel:[1,1,0] op_sel_hi:[1,0,1] neg_lo:[1,0,0]
	v_pk_mul_f32 v[144:145], v[138:139], v[58:59] op_sel:[0,0] op_sel_hi:[0,1]
	v_mov_b32_e32 v48, v140
	v_mov_b32_e32 v49, v41
	v_mov_b32_e32 v41, v141
	v_pk_mul_f32 v[140:141], v[44:45], v[54:55] op_sel:[0,0] op_sel_hi:[0,1]
	v_pk_fma_f32 v[138:139], v[138:139], v[58:59], v[144:145] op_sel:[1,1,0] op_sel_hi:[1,0,1] neg_lo:[1,0,0]
	v_pk_mul_f32 v[144:145], v[34:35], v[50:51] op_sel:[0,0] op_sel_hi:[0,1]
	v_pk_add_f32 v[36:37], v[36:37], v[36:37] op_sel:[0,1] op_sel_hi:[1,0]
	v_pk_fma_f32 v[44:45], v[44:45], v[54:55], v[140:141] op_sel:[1,1,0] op_sel_hi:[1,0,1] neg_lo:[1,0,0]
	v_pk_mul_f32 v[140:141], v[46:47], v[52:53] op_sel:[0,0] op_sel_hi:[0,1]
	v_pk_fma_f32 v[34:35], v[34:35], v[50:51], v[144:145] op_sel:[1,1,0] op_sel_hi:[1,0,1] neg_lo:[1,0,0]
	v_pk_mul_f32 v[144:145], v[38:39], v[58:59] op_sel:[0,0] op_sel_hi:[0,1]
	v_pk_mov_b32 v[148:149], v[156:157], v[146:147] op_sel:[1,0]
	v_pk_fma_f32 v[46:47], v[46:47], v[52:53], v[140:141] op_sel:[1,1,0] op_sel_hi:[1,0,1] neg_lo:[1,0,0]
	v_pk_mul_f32 v[140:141], v[48:49], v[50:51] op_sel:[0,0] op_sel_hi:[0,1]
	v_pk_fma_f32 v[38:39], v[38:39], v[58:59], v[144:145] op_sel:[1,1,0] op_sel_hi:[1,0,1] neg_lo:[1,0,0]
	v_pk_mul_f32 v[144:145], v[40:41], v[60:61] op_sel:[0,0] op_sel_hi:[0,1]
	v_mov_b32_e32 v143, v45
	v_pk_fma_f32 v[48:49], v[48:49], v[50:51], v[140:141] op_sel:[1,1,0] op_sel_hi:[1,0,1] neg_lo:[1,0,0]
	v_mov_b32_e32 v160, v46
	v_mov_b32_e32 v161, v49
	v_pk_mul_f32 v[140:141], v[154:155], v[52:53] op_sel:[0,0] op_sel_hi:[0,1]
	v_pk_fma_f32 v[40:41], v[40:41], v[60:61], v[144:145] op_sel:[1,1,0] op_sel_hi:[1,0,1] neg_lo:[1,0,0]
	v_pk_mov_b32 v[144:145], v[42:43], v[158:159] op_sel:[1,0]
	v_pk_add_f32 v[160:161], v[142:143], v[160:161] neg_lo:[0,1] neg_hi:[0,1]
	v_mov_b32_e32 v143, v150
	v_pk_fma_f32 v[140:141], v[154:155], v[52:53], v[140:141] op_sel:[1,1,0] op_sel_hi:[1,0,1] neg_lo:[1,0,0]
	v_pk_add_f32 v[144:145], v[144:145], v[148:149] neg_lo:[0,1] neg_hi:[0,1]
	v_mov_b32_e32 v148, v42
	v_mov_b32_e32 v149, v159
	v_mov_b32_e32 v154, v156
	v_mov_b32_e32 v155, v147
	v_pk_add_f32 v[146:147], v[158:159], v[146:147]
	v_mov_b32_e32 v151, v44
	v_pk_mov_b32 v[158:159], v[46:47], v[48:49] op_sel:[1,0]
	v_pk_add_f32 v[46:47], v[142:143], v[46:47]
	v_pk_add_f32 v[44:45], v[44:45], v[48:49]
	v_mov_b32_e32 v37, v153
	v_pk_add_f32 v[148:149], v[148:149], v[154:155] neg_lo:[0,1] neg_hi:[0,1]
	v_pk_add_f32 v[42:43], v[42:43], v[156:157]
	v_pk_add_f32 v[158:159], v[150:151], v[158:159] neg_lo:[0,1] neg_hi:[0,1]
	v_pk_add_f32 v[48:49], v[46:47], v[44:45]
	v_pk_add_f32 v[44:45], v[46:47], v[44:45] neg_lo:[0,1] neg_hi:[0,1]
	v_pk_add_f32 v[46:47], v[160:161], v[160:161] op_sel:[0,1] op_sel_hi:[1,0] neg_lo:[0,1] neg_hi:[0,1]
	v_pk_add_f32 v[150:151], v[160:161], v[160:161] op_sel:[0,1] op_sel_hi:[1,0]
	v_pk_add_f32 v[160:161], v[62:63], v[64:65]
	v_pk_add_f32 v[162:163], v[140:141], v[138:139]
	v_pk_add_f32 v[62:63], v[62:63], v[64:65] neg_lo:[0,1] neg_hi:[0,1]
	v_pk_add_f32 v[64:65], v[140:141], v[138:139] neg_lo:[0,1] neg_hi:[0,1]
	v_pk_add_f32 v[140:141], v[36:37], v[38:39]
	v_pk_add_f32 v[152:153], v[34:35], v[40:41]
	v_pk_add_f32 v[36:37], v[36:37], v[38:39] neg_lo:[0,1] neg_hi:[0,1]
	v_pk_add_f32 v[34:35], v[34:35], v[40:41] neg_lo:[0,1] neg_hi:[0,1]
	v_pk_add_f32 v[154:155], v[42:43], v[146:147]
	v_pk_add_f32 v[42:43], v[42:43], v[146:147] neg_lo:[0,1] neg_hi:[0,1]
	v_pk_add_f32 v[146:147], v[148:149], v[148:149] op_sel:[0,1] op_sel_hi:[1,0] neg_lo:[0,1] neg_hi:[0,1]
	v_pk_add_f32 v[156:157], v[144:145], v[144:145] op_sel_hi:[0,1]
	v_pk_add_f32 v[148:149], v[148:149], v[148:149] op_sel:[0,1] op_sel_hi:[1,0]
	v_pk_add_f32 v[144:145], v[144:145], v[144:145] op_sel_hi:[0,1] neg_lo:[0,1] neg_hi:[0,1]
	v_pk_add_f32 v[142:143], v[158:159], v[158:159] op_sel_hi:[0,1]
	v_pk_add_f32 v[158:159], v[158:159], v[158:159] op_sel_hi:[0,1] neg_lo:[0,1] neg_hi:[0,1]
	v_pk_add_f32 v[138:139], v[62:63], v[64:65] op_sel:[0,1] op_sel_hi:[1,0] neg_lo:[0,1] neg_hi:[0,1]
	v_pk_add_f32 v[62:63], v[62:63], v[64:65] op_sel:[0,1] op_sel_hi:[1,0]
	v_pk_add_f32 v[38:39], v[36:37], v[34:35] op_sel:[0,1] op_sel_hi:[1,0] neg_lo:[0,1] neg_hi:[0,1]
	v_pk_add_f32 v[34:35], v[36:37], v[34:35] op_sel:[0,1] op_sel_hi:[1,0]
	v_pk_add_f32 v[164:165], v[160:161], v[162:163]
	v_pk_add_f32 v[160:161], v[160:161], v[162:163] neg_lo:[0,1] neg_hi:[0,1]
	v_mov_b32_e32 v65, v63
	v_pk_add_f32 v[162:163], v[140:141], v[152:153]
	v_mov_b32_e32 v37, v35
	ds_write2_b64 v85, v[154:155], v[48:49] offset1:68
	ds_write2_b64 v85, v[164:165], v[162:163] offset0:136 offset1:204
	v_mov_b32_e32 v147, v157
	v_mov_b32_e32 v47, v143
	v_mov_b32_e32 v149, v145
	v_mov_b32_e32 v151, v159
	v_mov_b32_e32 v63, v139
	v_mov_b32_e32 v35, v39
	v_mov_b32_e32 v85, v0
	v_mov_b32_e32 v64, v138
	v_pk_add_f32 v[140:141], v[140:141], v[152:153] neg_lo:[0,1] neg_hi:[0,1]
	v_mov_b32_e32 v36, v38
	ds_write2_b64 v98, v[146:147], v[46:47] offset0:16 offset1:84
	ds_write2_b64 v98, v[64:65], v[36:37] offset0:152 offset1:220
	ds_write2_b64 v100, v[42:43], v[44:45] offset0:32 offset1:100
	ds_write2_b64 v100, v[160:161], v[140:141] offset0:168 offset1:236
	ds_write2_b64 v182, v[148:149], v[150:151] offset0:48 offset1:116
	ds_write2_b64 v182, v[62:63], v[34:35] offset0:184 offset1:252
	s_waitcnt lgkmcnt(0)
	s_barrier
	s_nop 0
	v_and_b32_e32 v38, 0x3ff, v85
	v_lshlrev_b32_e32 v34, 4, v85
	v_and_or_b32 v34, v34, s31, v38
	v_cvt_f32_u32_e32 v38, v38
	v_ashrrev_i32_e32 v35, 4, v34
	v_lshlrev_b32_e32 v35, 3, v35
	v_lshlrev_b32_e32 v34, 3, v34
	v_mul_f32_e32 v38, 0x38800000, v38
	v_add3_u32 v98, 0, v35, v34
	v_cos_f32_e32 v62, v38
	v_sin_f32_e32 v63, v38
	ds_read2st64_b64 v[34:37], v98 offset1:17
	v_add_u32_e32 v100, 0x11000, v98
	v_add_u32_e32 v182, 0x13200, v98
	v_add_u32_e32 v183, 0x15400, v98
	v_add_u32_e32 v184, 0x17600, v98
	v_add_u32_e32 v185, 0x19800, v98
	v_add_u32_e32 v186, 0x1ba00, v98
	v_add_u32_e32 v187, 0x1dc00, v98
	v_add_u32_e32 v188, 0x1fe00, v98
	ds_read2st64_b64 v[38:41], v98 offset0:34 offset1:51
	ds_read2st64_b64 v[42:45], v98 offset0:68 offset1:85
	ds_read2st64_b64 v[46:49], v98 offset0:102 offset1:119
	ds_read_b64 v[64:65], v100
	ds_read_b64 v[138:139], v182
	ds_read_b64 v[140:141], v183
	ds_read_b64 v[142:143], v184
	ds_read_b64 v[144:145], v185
	ds_read_b64 v[146:147], v186
	ds_read_b64 v[148:149], v187
	ds_read_b64 v[150:151], v188
	s_nop 1
	s_nop 0
	v_pk_mul_f32 v[152:153], v[62:63], v[62:63] op_sel:[0,0] op_sel_hi:[0,1]
	s_waitcnt lgkmcnt(11)
	v_pk_mul_f32 v[180:181], v[36:37], v[62:63] op_sel:[0,0] op_sel_hi:[0,1]
	v_pk_fma_f32 v[152:153], v[62:63], v[62:63], v[152:153] op_sel:[1,1,0] op_sel_hi:[1,0,1] neg_lo:[1,0,0]
	s_nop 0
	v_pk_fma_f32 v[36:37], v[36:37], v[62:63], v[180:181] op_sel:[1,1,0] op_sel_hi:[1,0,1] neg_lo:[1,0,0]
	v_pk_mul_f32 v[156:157], v[152:153], v[152:153] op_sel:[0,0] op_sel_hi:[0,1]
	v_pk_mul_f32 v[154:155], v[152:153], v[62:63] op_sel:[0,0] op_sel_hi:[0,1]
	s_nop 0
	v_pk_fma_f32 v[156:157], v[152:153], v[152:153], v[156:157] op_sel:[1,1,0] op_sel_hi:[1,0,1] neg_lo:[1,0,0]
	v_pk_fma_f32 v[154:155], v[152:153], v[62:63], v[154:155] op_sel:[1,1,0] op_sel_hi:[1,0,1] neg_lo:[1,0,0]
	s_nop 0
	v_pk_mul_f32 v[164:165], v[156:157], v[156:157] op_sel:[0,0] op_sel_hi:[0,1]
	v_pk_mul_f32 v[158:159], v[156:157], v[62:63] op_sel:[0,0] op_sel_hi:[0,1]
	v_pk_mul_f32 v[160:161], v[154:155], v[154:155] op_sel:[0,0] op_sel_hi:[0,1]
	v_pk_mul_f32 v[162:163], v[156:157], v[154:155] op_sel:[0,0] op_sel_hi:[0,1]
	s_nop 0
	v_pk_fma_f32 v[164:165], v[156:157], v[156:157], v[164:165] op_sel:[1,1,0] op_sel_hi:[1,0,1] neg_lo:[1,0,0]
	v_pk_fma_f32 v[158:159], v[156:157], v[62:63], v[158:159] op_sel:[1,1,0] op_sel_hi:[1,0,1] neg_lo:[1,0,0]
	v_pk_fma_f32 v[160:161], v[154:155], v[154:155], v[160:161] op_sel:[1,1,0] op_sel_hi:[1,0,1] neg_lo:[1,0,0]
	v_pk_fma_f32 v[162:163], v[156:157], v[154:155], v[162:163] op_sel:[1,1,0] op_sel_hi:[1,0,1] neg_lo:[1,0,0]
	s_nop 0
	v_pk_mul_f32 v[166:167], v[164:165], v[62:63] op_sel:[0,0] op_sel_hi:[0,1]
	v_pk_mul_f32 v[168:169], v[158:159], v[158:159] op_sel:[0,0] op_sel_hi:[0,1]
	v_pk_mul_f32 v[170:171], v[164:165], v[154:155] op_sel:[0,0] op_sel_hi:[0,1]
	v_pk_mul_f32 v[172:173], v[160:161], v[160:161] op_sel:[0,0] op_sel_hi:[0,1]
	v_pk_mul_f32 v[174:175], v[164:165], v[158:159] op_sel:[0,0] op_sel_hi:[0,1]
	v_pk_mul_f32 v[176:177], v[162:163], v[162:163] op_sel:[0,0] op_sel_hi:[0,1]
	s_nop 0
	v_pk_fma_f32 v[166:167], v[164:165], v[62:63], v[166:167] op_sel:[1,1,0] op_sel_hi:[1,0,1] neg_lo:[1,0,0]
	s_waitcnt lgkmcnt(10)
	v_pk_mul_f32 v[62:63], v[38:39], v[152:153] op_sel:[0,0] op_sel_hi:[0,1]
	v_pk_fma_f32 v[168:169], v[158:159], v[158:159], v[168:169] op_sel:[1,1,0] op_sel_hi:[1,0,1] neg_lo:[1,0,0]
	v_pk_fma_f32 v[170:171], v[164:165], v[154:155], v[170:171] op_sel:[1,1,0] op_sel_hi:[1,0,1] neg_lo:[1,0,0]
	v_pk_fma_f32 v[172:173], v[160:161], v[160:161], v[172:173] op_sel:[1,1,0] op_sel_hi:[1,0,1] neg_lo:[1,0,0]
	v_pk_fma_f32 v[174:175], v[164:165], v[158:159], v[174:175] op_sel:[1,1,0] op_sel_hi:[1,0,1] neg_lo:[1,0,0]
	v_pk_fma_f32 v[176:177], v[162:163], v[162:163], v[176:177] op_sel:[1,1,0] op_sel_hi:[1,0,1] neg_lo:[1,0,0]
	s_nop 0
	v_pk_fma_f32 v[38:39], v[38:39], v[152:153], v[62:63] op_sel:[1,1,0] op_sel_hi:[1,0,1] neg_lo:[1,0,0]
	v_pk_mul_f32 v[62:63], v[40:41], v[154:155] op_sel:[0,0] op_sel_hi:[0,1]
	v_pk_mul_f32 v[178:179], v[164:165], v[162:163] op_sel:[0,0] op_sel_hi:[0,1]
	s_nop 0
	v_pk_fma_f32 v[40:41], v[40:41], v[154:155], v[62:63] op_sel:[1,1,0] op_sel_hi:[1,0,1] neg_lo:[1,0,0]
	s_waitcnt lgkmcnt(9)
	v_pk_mul_f32 v[62:63], v[42:43], v[156:157] op_sel:[0,0] op_sel_hi:[0,1]
	v_pk_fma_f32 v[178:179], v[164:165], v[162:163], v[178:179] op_sel:[1,1,0] op_sel_hi:[1,0,1] neg_lo:[1,0,0]
	v_mov_b32_e32 v154, v35
	v_pk_fma_f32 v[42:43], v[42:43], v[156:157], v[62:63] op_sel:[1,1,0] op_sel_hi:[1,0,1] neg_lo:[1,0,0]
	v_pk_mul_f32 v[62:63], v[44:45], v[158:159] op_sel:[0,0] op_sel_hi:[0,1]
	s_nop 0
	v_pk_fma_f32 v[44:45], v[44:45], v[158:159], v[62:63] op_sel:[1,1,0] op_sel_hi:[1,0,1] neg_lo:[1,0,0]
	s_waitcnt lgkmcnt(8)
	v_pk_mul_f32 v[62:63], v[46:47], v[160:161] op_sel:[0,0] op_sel_hi:[0,1]
	v_mov_b32_e32 v155, v43
	v_pk_fma_f32 v[46:47], v[46:47], v[160:161], v[62:63] op_sel:[1,1,0] op_sel_hi:[1,0,1] neg_lo:[1,0,0]
	v_pk_mul_f32 v[62:63], v[48:49], v[162:163] op_sel:[0,0] op_sel_hi:[0,1]
	s_nop 0
	v_pk_fma_f32 v[48:49], v[48:49], v[162:163], v[62:63] op_sel:[1,1,0] op_sel_hi:[1,0,1] neg_lo:[1,0,0]
	s_waitcnt lgkmcnt(7)
	v_pk_mul_f32 v[62:63], v[64:65], v[164:165] op_sel:[0,0] op_sel_hi:[0,1]
	s_nop 0
	v_pk_fma_f32 v[62:63], v[64:65], v[164:165], v[62:63] op_sel:[1,1,0] op_sel_hi:[1,0,1] neg_lo:[1,0,0]
	s_waitcnt lgkmcnt(6)
	v_pk_mul_f32 v[64:65], v[138:139], v[166:167] op_sel:[0,0] op_sel_hi:[0,1]
	s_nop 0
	v_pk_fma_f32 v[64:65], v[138:139], v[166:167], v[64:65] op_sel:[1,1,0] op_sel_hi:[1,0,1] neg_lo:[1,0,0]
	s_waitcnt lgkmcnt(5)
	v_pk_mul_f32 v[138:139], v[140:141], v[168:169] op_sel:[0,0] op_sel_hi:[0,1]
	v_mov_b32_e32 v156, v63
	v_pk_fma_f32 v[138:139], v[140:141], v[168:169], v[138:139] op_sel:[1,1,0] op_sel_hi:[1,0,1] neg_lo:[1,0,0]
	s_waitcnt lgkmcnt(4)
	v_pk_mul_f32 v[140:141], v[142:143], v[170:171] op_sel:[0,0] op_sel_hi:[0,1]
	s_nop 0
	v_pk_fma_f32 v[140:141], v[142:143], v[170:171], v[140:141] op_sel:[1,1,0] op_sel_hi:[1,0,1] neg_lo:[1,0,0]
	s_waitcnt lgkmcnt(3)
	v_pk_mul_f32 v[142:143], v[144:145], v[172:173] op_sel:[0,0] op_sel_hi:[0,1]
	s_nop 0
	v_pk_fma_f32 v[142:143], v[144:145], v[172:173], v[142:143] op_sel:[1,1,0] op_sel_hi:[1,0,1] neg_lo:[1,0,0]
	s_waitcnt lgkmcnt(2)
	v_pk_mul_f32 v[144:145], v[146:147], v[174:175] op_sel:[0,0] op_sel_hi:[0,1]
	s_nop 0
	v_pk_fma_f32 v[144:145], v[146:147], v[174:175], v[144:145] op_sel:[1,1,0] op_sel_hi:[1,0,1] neg_lo:[1,0,0]
	s_waitcnt lgkmcnt(1)
	v_pk_mul_f32 v[146:147], v[148:149], v[176:177] op_sel:[0,0] op_sel_hi:[0,1]
	v_mov_b32_e32 v157, v143
	v_pk_fma_f32 v[146:147], v[148:149], v[176:177], v[146:147] op_sel:[1,1,0] op_sel_hi:[1,0,1] neg_lo:[1,0,0]
	s_waitcnt lgkmcnt(0)
	v_pk_mul_f32 v[148:149], v[150:151], v[178:179] op_sel:[0,0] op_sel_hi:[0,1]
	v_pk_add_f32 v[152:153], v[42:43], v[142:143]
	v_pk_fma_f32 v[148:149], v[150:151], v[178:179], v[148:149] op_sel:[1,1,0] op_sel_hi:[1,0,1] neg_lo:[1,0,0]
	v_pk_add_f32 v[150:151], v[34:35], v[62:63]
	v_pk_add_f32 v[154:155], v[154:155], v[156:157]
	v_pk_mov_b32 v[156:157], v[34:35], v[42:43] op_sel:[1,0]
	v_pk_mov_b32 v[158:159], v[62:63], v[142:143] op_sel:[1,0]
	v_mov_b32_e32 v35, v43
	v_pk_add_f32 v[156:157], v[156:157], v[158:159] neg_lo:[0,1] neg_hi:[0,1]
	v_mov_b32_e32 v63, v143
	v_mov_b32_e32 v151, v154
	v_mov_b32_e32 v153, v155
	v_pk_add_f32 v[34:35], v[34:35], v[62:63] neg_lo:[0,1] neg_hi:[0,1]
	v_pk_add_f32 v[42:43], v[150:151], v[152:153]
	v_pk_add_f32 v[62:63], v[150:151], v[152:153] neg_lo:[0,1] neg_hi:[0,1]
	v_pk_add_f32 v[150:151], v[156:157], v[156:157] op_sel:[0,1] op_sel_hi:[1,0]
	v_pk_add_f32 v[152:153], v[156:157], v[156:157] op_sel_hi:[0,1] neg_lo:[0,1] neg_hi:[0,1]
	v_pk_add_f32 v[154:155], v[36:37], v[64:65]
	v_pk_add_f32 v[156:157], v[44:45], v[144:145]
	v_pk_add_f32 v[36:37], v[36:37], v[64:65] neg_lo:[0,1] neg_hi:[0,1]
	v_pk_add_f32 v[44:45], v[44:45], v[144:145] neg_lo:[0,1] neg_hi:[0,1]
	v_pk_add_f32 v[144:145], v[46:47], v[146:147]
	v_pk_add_f32 v[64:65], v[36:37], v[44:45] op_sel:[0,1] op_sel_hi:[1,0] neg_lo:[0,1] neg_hi:[0,1]
	v_pk_add_f32 v[36:37], v[36:37], v[44:45] op_sel:[0,1] op_sel_hi:[1,0]
	v_mov_b32_e32 v44, v64
	v_mov_b32_e32 v45, v37
	v_mov_b32_e32 v37, v65
	v_pk_add_f32 v[64:65], v[38:39], v[138:139]
	v_pk_add_f32 v[38:39], v[38:39], v[138:139] neg_lo:[0,1] neg_hi:[0,1]
	v_pk_add_f32 v[46:47], v[46:47], v[146:147] neg_lo:[0,1] neg_hi:[0,1]
	v_pk_add_f32 v[158:159], v[154:155], v[156:157]
	v_pk_add_f32 v[138:139], v[38:39], v[46:47] op_sel:[0,1] op_sel_hi:[1,0] neg_lo:[0,1] neg_hi:[0,1]
	v_pk_add_f32 v[38:39], v[38:39], v[46:47] op_sel:[0,1] op_sel_hi:[1,0]
	v_pk_add_f32 v[154:155], v[154:155], v[156:157] neg_lo:[0,1] neg_hi:[0,1]
	v_pk_add_f32 v[156:157], v[64:65], v[144:145]
	v_pk_add_f32 v[64:65], v[64:65], v[144:145] neg_lo:[0,1] neg_hi:[0,1]
	v_mov_b32_e32 v46, v138
	v_mov_b32_e32 v47, v39
	v_mov_b32_e32 v39, v139
	v_pk_add_f32 v[138:139], v[40:41], v[140:141]
	v_pk_add_f32 v[144:145], v[48:49], v[148:149]
	v_pk_add_f32 v[40:41], v[40:41], v[140:141] neg_lo:[0,1] neg_hi:[0,1]
	v_pk_add_f32 v[146:147], v[138:139], v[144:145]
	v_pk_add_f32 v[138:139], v[138:139], v[144:145] neg_lo:[0,1] neg_hi:[0,1]
	v_pk_add_f32 v[48:49], v[48:49], v[148:149] neg_lo:[0,1] neg_hi:[0,1]
	v_pk_mul_f32 v[144:145], v[64:65], v[56:57] op_sel:[0,0] op_sel_hi:[0,1]
	v_pk_add_f32 v[142:143], v[34:35], v[34:35] op_sel:[0,1] op_sel_hi:[1,0] neg_lo:[0,1] neg_hi:[0,1]
	v_pk_add_f32 v[140:141], v[40:41], v[48:49] op_sel:[0,1] op_sel_hi:[1,0] neg_lo:[0,1] neg_hi:[0,1]
	v_pk_add_f32 v[40:41], v[40:41], v[48:49] op_sel:[0,1] op_sel_hi:[1,0]
	v_pk_fma_f32 v[64:65], v[64:65], v[56:57], v[144:145] op_sel:[1,1,0] op_sel_hi:[1,0,1] neg_lo:[1,0,0]
	v_pk_mul_f32 v[144:145], v[138:139], v[58:59] op_sel:[0,0] op_sel_hi:[0,1]
	v_mov_b32_e32 v48, v140
	v_mov_b32_e32 v49, v41
	v_mov_b32_e32 v41, v141
	v_pk_mul_f32 v[140:141], v[44:45], v[54:55] op_sel:[0,0] op_sel_hi:[0,1]
	v_pk_fma_f32 v[138:139], v[138:139], v[58:59], v[144:145] op_sel:[1,1,0] op_sel_hi:[1,0,1] neg_lo:[1,0,0]
	v_pk_mul_f32 v[144:145], v[36:37], v[50:51] op_sel:[0,0] op_sel_hi:[0,1]
	v_pk_add_f32 v[34:35], v[34:35], v[34:35] op_sel:[0,1] op_sel_hi:[1,0]
	v_pk_fma_f32 v[44:45], v[44:45], v[54:55], v[140:141] op_sel:[1,1,0] op_sel_hi:[1,0,1] neg_lo:[1,0,0]
	v_pk_mul_f32 v[140:141], v[46:47], v[52:53] op_sel:[0,0] op_sel_hi:[0,1]
	v_pk_fma_f32 v[36:37], v[36:37], v[50:51], v[144:145] op_sel:[1,1,0] op_sel_hi:[1,0,1] neg_lo:[1,0,0]
	v_pk_mul_f32 v[144:145], v[38:39], v[58:59] op_sel:[0,0] op_sel_hi:[0,1]
	v_pk_mov_b32 v[148:149], v[156:157], v[146:147] op_sel:[1,0]
	v_pk_fma_f32 v[46:47], v[46:47], v[52:53], v[140:141] op_sel:[1,1,0] op_sel_hi:[1,0,1] neg_lo:[1,0,0]
	v_pk_mul_f32 v[140:141], v[48:49], v[50:51] op_sel:[0,0] op_sel_hi:[0,1]
	v_pk_fma_f32 v[38:39], v[38:39], v[58:59], v[144:145] op_sel:[1,1,0] op_sel_hi:[1,0,1] neg_lo:[1,0,0]
	v_pk_mul_f32 v[144:145], v[40:41], v[60:61] op_sel:[0,0] op_sel_hi:[0,1]
	v_mov_b32_e32 v143, v45
	v_pk_fma_f32 v[48:49], v[48:49], v[50:51], v[140:141] op_sel:[1,1,0] op_sel_hi:[1,0,1] neg_lo:[1,0,0]
	v_mov_b32_e32 v160, v46
	v_mov_b32_e32 v161, v49
	v_pk_mul_f32 v[140:141], v[154:155], v[52:53] op_sel:[0,0] op_sel_hi:[0,1]
	v_pk_fma_f32 v[40:41], v[40:41], v[60:61], v[144:145] op_sel:[1,1,0] op_sel_hi:[1,0,1] neg_lo:[1,0,0]
	v_pk_mov_b32 v[144:145], v[42:43], v[158:159] op_sel:[1,0]
	v_pk_add_f32 v[160:161], v[142:143], v[160:161] neg_lo:[0,1] neg_hi:[0,1]
	v_mov_b32_e32 v143, v150
	v_pk_fma_f32 v[140:141], v[154:155], v[52:53], v[140:141] op_sel:[1,1,0] op_sel_hi:[1,0,1] neg_lo:[1,0,0]
	v_pk_add_f32 v[144:145], v[144:145], v[148:149] neg_lo:[0,1] neg_hi:[0,1]
	v_mov_b32_e32 v148, v42
	v_mov_b32_e32 v149, v159
	v_mov_b32_e32 v154, v156
	v_mov_b32_e32 v155, v147
	v_pk_add_f32 v[146:147], v[158:159], v[146:147]
	v_mov_b32_e32 v151, v44
	v_pk_mov_b32 v[158:159], v[46:47], v[48:49] op_sel:[1,0]
	v_pk_add_f32 v[46:47], v[142:143], v[46:47]
	v_pk_add_f32 v[44:45], v[44:45], v[48:49]
	v_mov_b32_e32 v35, v153
	v_pk_add_f32 v[148:149], v[148:149], v[154:155] neg_lo:[0,1] neg_hi:[0,1]
	v_pk_add_f32 v[42:43], v[42:43], v[156:157]
	v_pk_add_f32 v[158:159], v[150:151], v[158:159] neg_lo:[0,1] neg_hi:[0,1]
	v_pk_add_f32 v[48:49], v[46:47], v[44:45]
	v_pk_add_f32 v[44:45], v[46:47], v[44:45] neg_lo:[0,1] neg_hi:[0,1]
	v_pk_add_f32 v[46:47], v[160:161], v[160:161] op_sel:[0,1] op_sel_hi:[1,0] neg_lo:[0,1] neg_hi:[0,1]
	v_pk_add_f32 v[150:151], v[160:161], v[160:161] op_sel:[0,1] op_sel_hi:[1,0]
	v_pk_add_f32 v[160:161], v[62:63], v[64:65]
	v_pk_add_f32 v[162:163], v[140:141], v[138:139]
	v_pk_add_f32 v[62:63], v[62:63], v[64:65] neg_lo:[0,1] neg_hi:[0,1]
	v_pk_add_f32 v[64:65], v[140:141], v[138:139] neg_lo:[0,1] neg_hi:[0,1]
	v_pk_add_f32 v[140:141], v[34:35], v[38:39]
	v_pk_add_f32 v[152:153], v[36:37], v[40:41]
	v_pk_add_f32 v[34:35], v[34:35], v[38:39] neg_lo:[0,1] neg_hi:[0,1]
	v_pk_add_f32 v[36:37], v[36:37], v[40:41] neg_lo:[0,1] neg_hi:[0,1]
	v_pk_add_f32 v[154:155], v[42:43], v[146:147]
	v_pk_add_f32 v[42:43], v[42:43], v[146:147] neg_lo:[0,1] neg_hi:[0,1]
	v_pk_add_f32 v[146:147], v[148:149], v[148:149] op_sel:[0,1] op_sel_hi:[1,0] neg_lo:[0,1] neg_hi:[0,1]
	v_pk_add_f32 v[156:157], v[144:145], v[144:145] op_sel_hi:[0,1]
	v_pk_add_f32 v[142:143], v[158:159], v[158:159] op_sel_hi:[0,1]
	v_pk_add_f32 v[38:39], v[34:35], v[36:37] op_sel:[0,1] op_sel_hi:[1,0] neg_lo:[0,1] neg_hi:[0,1]
	v_pk_add_f32 v[34:35], v[34:35], v[36:37] op_sel:[0,1] op_sel_hi:[1,0]
	v_pk_add_f32 v[138:139], v[62:63], v[64:65] op_sel:[0,1] op_sel_hi:[1,0] neg_lo:[0,1] neg_hi:[0,1]
	v_pk_add_f32 v[62:63], v[62:63], v[64:65] op_sel:[0,1] op_sel_hi:[1,0]
	v_mov_b32_e32 v37, v35
	v_mov_b32_e32 v147, v157
	v_mov_b32_e32 v47, v143
	v_mov_b32_e32 v35, v39
	v_pk_add_f32 v[164:165], v[160:161], v[162:163]
	v_pk_add_f32 v[160:161], v[160:161], v[162:163] neg_lo:[0,1] neg_hi:[0,1]
	v_mov_b32_e32 v64, v138
	v_mov_b32_e32 v65, v63
	v_pk_add_f32 v[162:163], v[140:141], v[152:153]
	v_pk_add_f32 v[140:141], v[140:141], v[152:153] neg_lo:[0,1] neg_hi:[0,1]
	v_mov_b32_e32 v36, v38
	ds_write2st64_b64 v98, v[154:155], v[48:49] offset1:17
	ds_write2st64_b64 v98, v[164:165], v[162:163] offset0:34 offset1:51
	ds_write2st64_b64 v98, v[146:147], v[46:47] offset0:68 offset1:85
	ds_write2st64_b64 v98, v[64:65], v[36:37] offset0:102 offset1:119
	ds_write_b64 v100, v[42:43]
	ds_write_b64 v182, v[44:45]
	ds_write_b64 v183, v[160:161]
	ds_write_b64 v184, v[140:141]
	ds_write_b64 v188, v[34:35]
	v_add_u32_e32 v34, 0x200, v85
	v_and_b32_e32 v38, 0x3ff, v34
	v_lshlrev_b32_e32 v34, 4, v34
	v_and_or_b32 v34, v34, s31, v38
	v_cvt_f32_u32_e32 v38, v38
	v_pk_add_f32 v[148:149], v[148:149], v[148:149] op_sel:[0,1] op_sel_hi:[1,0]
	v_pk_add_f32 v[144:145], v[144:145], v[144:145] op_sel_hi:[0,1] neg_lo:[0,1] neg_hi:[0,1]
	v_pk_add_f32 v[158:159], v[158:159], v[158:159] op_sel_hi:[0,1] neg_lo:[0,1] neg_hi:[0,1]
	v_ashrrev_i32_e32 v35, 4, v34
	v_mov_b32_e32 v149, v145
	v_mov_b32_e32 v151, v159
	v_mov_b32_e32 v63, v139
	v_lshlrev_b32_e32 v35, 3, v35
	v_lshlrev_b32_e32 v34, 3, v34
	v_mul_f32_e32 v38, 0x38800000, v38
	ds_write_b64 v185, v[148:149]
	ds_write_b64 v186, v[150:151]
	ds_write_b64 v187, v[62:63]
	v_add3_u32 v85, 0, v35, v34
	v_cos_f32_e32 v62, v38
	v_sin_f32_e32 v63, v38
	ds_read2st64_b64 v[34:37], v85 offset1:17
	v_add_u32_e32 v98, 0x11000, v85
	v_add_u32_e32 v100, 0x13200, v85
	v_add_u32_e32 v182, 0x15400, v85
	v_add_u32_e32 v183, 0x17600, v85
	v_add_u32_e32 v184, 0x19800, v85
	v_add_u32_e32 v185, 0x1ba00, v85
	v_add_u32_e32 v186, 0x1dc00, v85
	v_add_u32_e32 v187, 0x1fe00, v85
	ds_read2st64_b64 v[38:41], v85 offset0:34 offset1:51
	ds_read2st64_b64 v[42:45], v85 offset0:68 offset1:85
	ds_read2st64_b64 v[46:49], v85 offset0:102 offset1:119
	ds_read_b64 v[64:65], v98
	ds_read_b64 v[138:139], v100
	ds_read_b64 v[140:141], v182
	ds_read_b64 v[142:143], v183
	ds_read_b64 v[144:145], v184
	ds_read_b64 v[146:147], v185
	ds_read_b64 v[148:149], v186
	ds_read_b64 v[150:151], v187
	s_nop 1
	s_nop 0
	v_pk_mul_f32 v[152:153], v[62:63], v[62:63] op_sel:[0,0] op_sel_hi:[0,1]
	s_waitcnt lgkmcnt(11)
	v_pk_mul_f32 v[180:181], v[36:37], v[62:63] op_sel:[0,0] op_sel_hi:[0,1]
	v_pk_fma_f32 v[152:153], v[62:63], v[62:63], v[152:153] op_sel:[1,1,0] op_sel_hi:[1,0,1] neg_lo:[1,0,0]
	s_nop 0
	v_pk_fma_f32 v[36:37], v[36:37], v[62:63], v[180:181] op_sel:[1,1,0] op_sel_hi:[1,0,1] neg_lo:[1,0,0]
	v_pk_mul_f32 v[156:157], v[152:153], v[152:153] op_sel:[0,0] op_sel_hi:[0,1]
	v_pk_mul_f32 v[154:155], v[152:153], v[62:63] op_sel:[0,0] op_sel_hi:[0,1]
	s_nop 0
	v_pk_fma_f32 v[156:157], v[152:153], v[152:153], v[156:157] op_sel:[1,1,0] op_sel_hi:[1,0,1] neg_lo:[1,0,0]
	v_pk_fma_f32 v[154:155], v[152:153], v[62:63], v[154:155] op_sel:[1,1,0] op_sel_hi:[1,0,1] neg_lo:[1,0,0]
	s_nop 0
	v_pk_mul_f32 v[164:165], v[156:157], v[156:157] op_sel:[0,0] op_sel_hi:[0,1]
	v_pk_mul_f32 v[158:159], v[156:157], v[62:63] op_sel:[0,0] op_sel_hi:[0,1]
	v_pk_mul_f32 v[160:161], v[154:155], v[154:155] op_sel:[0,0] op_sel_hi:[0,1]
	v_pk_mul_f32 v[162:163], v[156:157], v[154:155] op_sel:[0,0] op_sel_hi:[0,1]
	s_nop 0
	v_pk_fma_f32 v[164:165], v[156:157], v[156:157], v[164:165] op_sel:[1,1,0] op_sel_hi:[1,0,1] neg_lo:[1,0,0]
	v_pk_fma_f32 v[158:159], v[156:157], v[62:63], v[158:159] op_sel:[1,1,0] op_sel_hi:[1,0,1] neg_lo:[1,0,0]
	v_pk_fma_f32 v[160:161], v[154:155], v[154:155], v[160:161] op_sel:[1,1,0] op_sel_hi:[1,0,1] neg_lo:[1,0,0]
	v_pk_fma_f32 v[162:163], v[156:157], v[154:155], v[162:163] op_sel:[1,1,0] op_sel_hi:[1,0,1] neg_lo:[1,0,0]
	s_nop 0
	v_pk_mul_f32 v[166:167], v[164:165], v[62:63] op_sel:[0,0] op_sel_hi:[0,1]
	v_pk_mul_f32 v[168:169], v[158:159], v[158:159] op_sel:[0,0] op_sel_hi:[0,1]
	v_pk_mul_f32 v[170:171], v[164:165], v[154:155] op_sel:[0,0] op_sel_hi:[0,1]
	v_pk_mul_f32 v[172:173], v[160:161], v[160:161] op_sel:[0,0] op_sel_hi:[0,1]
	v_pk_mul_f32 v[174:175], v[164:165], v[158:159] op_sel:[0,0] op_sel_hi:[0,1]
	v_pk_mul_f32 v[176:177], v[162:163], v[162:163] op_sel:[0,0] op_sel_hi:[0,1]
	s_nop 0
	v_pk_fma_f32 v[166:167], v[164:165], v[62:63], v[166:167] op_sel:[1,1,0] op_sel_hi:[1,0,1] neg_lo:[1,0,0]
	s_waitcnt lgkmcnt(10)
	v_pk_mul_f32 v[62:63], v[38:39], v[152:153] op_sel:[0,0] op_sel_hi:[0,1]
	v_pk_fma_f32 v[168:169], v[158:159], v[158:159], v[168:169] op_sel:[1,1,0] op_sel_hi:[1,0,1] neg_lo:[1,0,0]
	v_pk_fma_f32 v[170:171], v[164:165], v[154:155], v[170:171] op_sel:[1,1,0] op_sel_hi:[1,0,1] neg_lo:[1,0,0]
	v_pk_fma_f32 v[172:173], v[160:161], v[160:161], v[172:173] op_sel:[1,1,0] op_sel_hi:[1,0,1] neg_lo:[1,0,0]
	v_pk_fma_f32 v[174:175], v[164:165], v[158:159], v[174:175] op_sel:[1,1,0] op_sel_hi:[1,0,1] neg_lo:[1,0,0]
	v_pk_fma_f32 v[176:177], v[162:163], v[162:163], v[176:177] op_sel:[1,1,0] op_sel_hi:[1,0,1] neg_lo:[1,0,0]
	s_nop 0
	v_pk_fma_f32 v[38:39], v[38:39], v[152:153], v[62:63] op_sel:[1,1,0] op_sel_hi:[1,0,1] neg_lo:[1,0,0]
	v_pk_mul_f32 v[62:63], v[40:41], v[154:155] op_sel:[0,0] op_sel_hi:[0,1]
	v_pk_mul_f32 v[178:179], v[164:165], v[162:163] op_sel:[0,0] op_sel_hi:[0,1]
	s_nop 0
	v_pk_fma_f32 v[40:41], v[40:41], v[154:155], v[62:63] op_sel:[1,1,0] op_sel_hi:[1,0,1] neg_lo:[1,0,0]
	s_waitcnt lgkmcnt(9)
	v_pk_mul_f32 v[62:63], v[42:43], v[156:157] op_sel:[0,0] op_sel_hi:[0,1]
	v_pk_fma_f32 v[178:179], v[164:165], v[162:163], v[178:179] op_sel:[1,1,0] op_sel_hi:[1,0,1] neg_lo:[1,0,0]
	v_mov_b32_e32 v154, v35
	v_pk_fma_f32 v[42:43], v[42:43], v[156:157], v[62:63] op_sel:[1,1,0] op_sel_hi:[1,0,1] neg_lo:[1,0,0]
	v_pk_mul_f32 v[62:63], v[44:45], v[158:159] op_sel:[0,0] op_sel_hi:[0,1]
	s_nop 0
	v_pk_fma_f32 v[44:45], v[44:45], v[158:159], v[62:63] op_sel:[1,1,0] op_sel_hi:[1,0,1] neg_lo:[1,0,0]
	s_waitcnt lgkmcnt(8)
	v_pk_mul_f32 v[62:63], v[46:47], v[160:161] op_sel:[0,0] op_sel_hi:[0,1]
	v_mov_b32_e32 v155, v43
	v_pk_fma_f32 v[46:47], v[46:47], v[160:161], v[62:63] op_sel:[1,1,0] op_sel_hi:[1,0,1] neg_lo:[1,0,0]
	v_pk_mul_f32 v[62:63], v[48:49], v[162:163] op_sel:[0,0] op_sel_hi:[0,1]
	s_nop 0
	v_pk_fma_f32 v[48:49], v[48:49], v[162:163], v[62:63] op_sel:[1,1,0] op_sel_hi:[1,0,1] neg_lo:[1,0,0]
	s_waitcnt lgkmcnt(7)
	v_pk_mul_f32 v[62:63], v[64:65], v[164:165] op_sel:[0,0] op_sel_hi:[0,1]
	s_nop 0
	v_pk_fma_f32 v[62:63], v[64:65], v[164:165], v[62:63] op_sel:[1,1,0] op_sel_hi:[1,0,1] neg_lo:[1,0,0]
	s_waitcnt lgkmcnt(6)
	v_pk_mul_f32 v[64:65], v[138:139], v[166:167] op_sel:[0,0] op_sel_hi:[0,1]
	s_nop 0
	v_pk_fma_f32 v[64:65], v[138:139], v[166:167], v[64:65] op_sel:[1,1,0] op_sel_hi:[1,0,1] neg_lo:[1,0,0]
	s_waitcnt lgkmcnt(5)
	v_pk_mul_f32 v[138:139], v[140:141], v[168:169] op_sel:[0,0] op_sel_hi:[0,1]
	v_mov_b32_e32 v156, v63
	v_pk_fma_f32 v[138:139], v[140:141], v[168:169], v[138:139] op_sel:[1,1,0] op_sel_hi:[1,0,1] neg_lo:[1,0,0]
	s_waitcnt lgkmcnt(4)
	v_pk_mul_f32 v[140:141], v[142:143], v[170:171] op_sel:[0,0] op_sel_hi:[0,1]
	s_nop 0
	v_pk_fma_f32 v[140:141], v[142:143], v[170:171], v[140:141] op_sel:[1,1,0] op_sel_hi:[1,0,1] neg_lo:[1,0,0]
	s_waitcnt lgkmcnt(3)
	v_pk_mul_f32 v[142:143], v[144:145], v[172:173] op_sel:[0,0] op_sel_hi:[0,1]
	s_nop 0
	v_pk_fma_f32 v[142:143], v[144:145], v[172:173], v[142:143] op_sel:[1,1,0] op_sel_hi:[1,0,1] neg_lo:[1,0,0]
	s_waitcnt lgkmcnt(2)
	v_pk_mul_f32 v[144:145], v[146:147], v[174:175] op_sel:[0,0] op_sel_hi:[0,1]
	s_nop 0
	v_pk_fma_f32 v[144:145], v[146:147], v[174:175], v[144:145] op_sel:[1,1,0] op_sel_hi:[1,0,1] neg_lo:[1,0,0]
	s_waitcnt lgkmcnt(1)
	v_pk_mul_f32 v[146:147], v[148:149], v[176:177] op_sel:[0,0] op_sel_hi:[0,1]
	v_mov_b32_e32 v157, v143
	v_pk_fma_f32 v[146:147], v[148:149], v[176:177], v[146:147] op_sel:[1,1,0] op_sel_hi:[1,0,1] neg_lo:[1,0,0]
	s_waitcnt lgkmcnt(0)
	v_pk_mul_f32 v[148:149], v[150:151], v[178:179] op_sel:[0,0] op_sel_hi:[0,1]
	v_pk_add_f32 v[152:153], v[42:43], v[142:143]
	v_pk_fma_f32 v[148:149], v[150:151], v[178:179], v[148:149] op_sel:[1,1,0] op_sel_hi:[1,0,1] neg_lo:[1,0,0]
	v_pk_add_f32 v[150:151], v[34:35], v[62:63]
	v_pk_add_f32 v[154:155], v[154:155], v[156:157]
	v_pk_mov_b32 v[156:157], v[34:35], v[42:43] op_sel:[1,0]
	v_pk_mov_b32 v[158:159], v[62:63], v[142:143] op_sel:[1,0]
	v_mov_b32_e32 v35, v43
	v_pk_add_f32 v[156:157], v[156:157], v[158:159] neg_lo:[0,1] neg_hi:[0,1]
	v_mov_b32_e32 v63, v143
	v_mov_b32_e32 v151, v154
	v_mov_b32_e32 v153, v155
	v_pk_add_f32 v[34:35], v[34:35], v[62:63] neg_lo:[0,1] neg_hi:[0,1]
	v_pk_add_f32 v[42:43], v[150:151], v[152:153]
	v_pk_add_f32 v[62:63], v[150:151], v[152:153] neg_lo:[0,1] neg_hi:[0,1]
	v_pk_add_f32 v[150:151], v[156:157], v[156:157] op_sel:[0,1] op_sel_hi:[1,0]
	v_pk_add_f32 v[152:153], v[156:157], v[156:157] op_sel_hi:[0,1] neg_lo:[0,1] neg_hi:[0,1]
	v_pk_add_f32 v[154:155], v[36:37], v[64:65]
	v_pk_add_f32 v[156:157], v[44:45], v[144:145]
	v_pk_add_f32 v[36:37], v[36:37], v[64:65] neg_lo:[0,1] neg_hi:[0,1]
	v_pk_add_f32 v[44:45], v[44:45], v[144:145] neg_lo:[0,1] neg_hi:[0,1]
	v_pk_add_f32 v[144:145], v[46:47], v[146:147]
	v_pk_add_f32 v[64:65], v[36:37], v[44:45] op_sel:[0,1] op_sel_hi:[1,0] neg_lo:[0,1] neg_hi:[0,1]
	v_pk_add_f32 v[36:37], v[36:37], v[44:45] op_sel:[0,1] op_sel_hi:[1,0]
	v_mov_b32_e32 v44, v64
	v_mov_b32_e32 v45, v37
	v_mov_b32_e32 v37, v65
	v_pk_add_f32 v[64:65], v[38:39], v[138:139]
	v_pk_add_f32 v[38:39], v[38:39], v[138:139] neg_lo:[0,1] neg_hi:[0,1]
	v_pk_add_f32 v[46:47], v[46:47], v[146:147] neg_lo:[0,1] neg_hi:[0,1]
	v_pk_add_f32 v[158:159], v[154:155], v[156:157]
	v_pk_add_f32 v[138:139], v[38:39], v[46:47] op_sel:[0,1] op_sel_hi:[1,0] neg_lo:[0,1] neg_hi:[0,1]
	v_pk_add_f32 v[38:39], v[38:39], v[46:47] op_sel:[0,1] op_sel_hi:[1,0]
	v_pk_add_f32 v[154:155], v[154:155], v[156:157] neg_lo:[0,1] neg_hi:[0,1]
	v_pk_add_f32 v[156:157], v[64:65], v[144:145]
	v_pk_add_f32 v[64:65], v[64:65], v[144:145] neg_lo:[0,1] neg_hi:[0,1]
	v_mov_b32_e32 v46, v138
	v_mov_b32_e32 v47, v39
	v_mov_b32_e32 v39, v139
	v_pk_add_f32 v[138:139], v[40:41], v[140:141]
	v_pk_add_f32 v[144:145], v[48:49], v[148:149]
	v_pk_add_f32 v[40:41], v[40:41], v[140:141] neg_lo:[0,1] neg_hi:[0,1]
	v_pk_add_f32 v[146:147], v[138:139], v[144:145]
	v_pk_add_f32 v[138:139], v[138:139], v[144:145] neg_lo:[0,1] neg_hi:[0,1]
	v_pk_add_f32 v[48:49], v[48:49], v[148:149] neg_lo:[0,1] neg_hi:[0,1]
	v_pk_mul_f32 v[144:145], v[64:65], v[56:57] op_sel:[0,0] op_sel_hi:[0,1]
	v_pk_add_f32 v[142:143], v[34:35], v[34:35] op_sel:[0,1] op_sel_hi:[1,0] neg_lo:[0,1] neg_hi:[0,1]
	v_pk_add_f32 v[140:141], v[40:41], v[48:49] op_sel:[0,1] op_sel_hi:[1,0] neg_lo:[0,1] neg_hi:[0,1]
	v_pk_add_f32 v[40:41], v[40:41], v[48:49] op_sel:[0,1] op_sel_hi:[1,0]
	v_pk_fma_f32 v[64:65], v[64:65], v[56:57], v[144:145] op_sel:[1,1,0] op_sel_hi:[1,0,1] neg_lo:[1,0,0]
	v_pk_mul_f32 v[144:145], v[138:139], v[58:59] op_sel:[0,0] op_sel_hi:[0,1]
	v_mov_b32_e32 v48, v140
	v_mov_b32_e32 v49, v41
	v_mov_b32_e32 v41, v141
	v_pk_mul_f32 v[140:141], v[44:45], v[54:55] op_sel:[0,0] op_sel_hi:[0,1]
	v_pk_fma_f32 v[138:139], v[138:139], v[58:59], v[144:145] op_sel:[1,1,0] op_sel_hi:[1,0,1] neg_lo:[1,0,0]
	v_pk_mul_f32 v[144:145], v[36:37], v[50:51] op_sel:[0,0] op_sel_hi:[0,1]
	v_pk_add_f32 v[34:35], v[34:35], v[34:35] op_sel:[0,1] op_sel_hi:[1,0]
	v_pk_fma_f32 v[44:45], v[44:45], v[54:55], v[140:141] op_sel:[1,1,0] op_sel_hi:[1,0,1] neg_lo:[1,0,0]
	v_pk_mul_f32 v[140:141], v[46:47], v[52:53] op_sel:[0,0] op_sel_hi:[0,1]
	v_pk_fma_f32 v[36:37], v[36:37], v[50:51], v[144:145] op_sel:[1,1,0] op_sel_hi:[1,0,1] neg_lo:[1,0,0]
	v_pk_mul_f32 v[144:145], v[38:39], v[58:59] op_sel:[0,0] op_sel_hi:[0,1]
	v_pk_mov_b32 v[148:149], v[156:157], v[146:147] op_sel:[1,0]
	v_pk_fma_f32 v[46:47], v[46:47], v[52:53], v[140:141] op_sel:[1,1,0] op_sel_hi:[1,0,1] neg_lo:[1,0,0]
	v_pk_mul_f32 v[140:141], v[48:49], v[50:51] op_sel:[0,0] op_sel_hi:[0,1]
	v_pk_fma_f32 v[38:39], v[38:39], v[58:59], v[144:145] op_sel:[1,1,0] op_sel_hi:[1,0,1] neg_lo:[1,0,0]
	v_pk_mul_f32 v[144:145], v[40:41], v[60:61] op_sel:[0,0] op_sel_hi:[0,1]
	v_mov_b32_e32 v143, v45
	v_pk_fma_f32 v[48:49], v[48:49], v[50:51], v[140:141] op_sel:[1,1,0] op_sel_hi:[1,0,1] neg_lo:[1,0,0]
	v_mov_b32_e32 v160, v46
	v_mov_b32_e32 v161, v49
	v_pk_mul_f32 v[140:141], v[154:155], v[52:53] op_sel:[0,0] op_sel_hi:[0,1]
	v_pk_fma_f32 v[40:41], v[40:41], v[60:61], v[144:145] op_sel:[1,1,0] op_sel_hi:[1,0,1] neg_lo:[1,0,0]
	v_pk_mov_b32 v[144:145], v[42:43], v[158:159] op_sel:[1,0]
	v_pk_add_f32 v[160:161], v[142:143], v[160:161] neg_lo:[0,1] neg_hi:[0,1]
	v_mov_b32_e32 v143, v150
	v_pk_fma_f32 v[140:141], v[154:155], v[52:53], v[140:141] op_sel:[1,1,0] op_sel_hi:[1,0,1] neg_lo:[1,0,0]
	v_pk_add_f32 v[144:145], v[144:145], v[148:149] neg_lo:[0,1] neg_hi:[0,1]
	v_mov_b32_e32 v148, v42
	v_mov_b32_e32 v149, v159
	v_mov_b32_e32 v154, v156
	v_mov_b32_e32 v155, v147
	v_pk_add_f32 v[146:147], v[158:159], v[146:147]
	v_mov_b32_e32 v151, v44
	v_pk_mov_b32 v[158:159], v[46:47], v[48:49] op_sel:[1,0]
	v_pk_add_f32 v[46:47], v[142:143], v[46:47]
	v_pk_add_f32 v[44:45], v[44:45], v[48:49]
	v_mov_b32_e32 v35, v153
	v_pk_add_f32 v[148:149], v[148:149], v[154:155] neg_lo:[0,1] neg_hi:[0,1]
	v_pk_add_f32 v[42:43], v[42:43], v[156:157]
	v_pk_add_f32 v[158:159], v[150:151], v[158:159] neg_lo:[0,1] neg_hi:[0,1]
	v_pk_add_f32 v[48:49], v[46:47], v[44:45]
	v_pk_add_f32 v[44:45], v[46:47], v[44:45] neg_lo:[0,1] neg_hi:[0,1]
	v_pk_add_f32 v[46:47], v[160:161], v[160:161] op_sel:[0,1] op_sel_hi:[1,0] neg_lo:[0,1] neg_hi:[0,1]
	v_pk_add_f32 v[150:151], v[160:161], v[160:161] op_sel:[0,1] op_sel_hi:[1,0]
	v_pk_add_f32 v[160:161], v[62:63], v[64:65]
	v_pk_add_f32 v[162:163], v[140:141], v[138:139]
	v_pk_add_f32 v[62:63], v[62:63], v[64:65] neg_lo:[0,1] neg_hi:[0,1]
	v_pk_add_f32 v[64:65], v[140:141], v[138:139] neg_lo:[0,1] neg_hi:[0,1]
	v_pk_add_f32 v[140:141], v[34:35], v[38:39]
	v_pk_add_f32 v[152:153], v[36:37], v[40:41]
	v_pk_add_f32 v[34:35], v[34:35], v[38:39] neg_lo:[0,1] neg_hi:[0,1]
	v_pk_add_f32 v[36:37], v[36:37], v[40:41] neg_lo:[0,1] neg_hi:[0,1]
	v_pk_add_f32 v[154:155], v[42:43], v[146:147]
	v_pk_add_f32 v[42:43], v[42:43], v[146:147] neg_lo:[0,1] neg_hi:[0,1]
	v_pk_add_f32 v[146:147], v[148:149], v[148:149] op_sel:[0,1] op_sel_hi:[1,0] neg_lo:[0,1] neg_hi:[0,1]
	v_pk_add_f32 v[156:157], v[144:145], v[144:145] op_sel_hi:[0,1]
	v_pk_add_f32 v[142:143], v[158:159], v[158:159] op_sel_hi:[0,1]
	v_pk_add_f32 v[38:39], v[34:35], v[36:37] op_sel:[0,1] op_sel_hi:[1,0] neg_lo:[0,1] neg_hi:[0,1]
	v_pk_add_f32 v[34:35], v[34:35], v[36:37] op_sel:[0,1] op_sel_hi:[1,0]
	v_pk_add_f32 v[138:139], v[62:63], v[64:65] op_sel:[0,1] op_sel_hi:[1,0] neg_lo:[0,1] neg_hi:[0,1]
	v_pk_add_f32 v[62:63], v[62:63], v[64:65] op_sel:[0,1] op_sel_hi:[1,0]
	v_mov_b32_e32 v37, v35
	v_mov_b32_e32 v147, v157
	v_mov_b32_e32 v47, v143
	v_mov_b32_e32 v35, v39
	v_pk_add_f32 v[164:165], v[160:161], v[162:163]
	v_pk_add_f32 v[160:161], v[160:161], v[162:163] neg_lo:[0,1] neg_hi:[0,1]
	v_mov_b32_e32 v64, v138
	v_mov_b32_e32 v65, v63
	v_pk_add_f32 v[162:163], v[140:141], v[152:153]
	v_pk_add_f32 v[140:141], v[140:141], v[152:153] neg_lo:[0,1] neg_hi:[0,1]
	v_mov_b32_e32 v36, v38
	ds_write2st64_b64 v85, v[154:155], v[48:49] offset1:17
	ds_write2st64_b64 v85, v[164:165], v[162:163] offset0:34 offset1:51
	ds_write2st64_b64 v85, v[146:147], v[46:47] offset0:68 offset1:85
	ds_write2st64_b64 v85, v[64:65], v[36:37] offset0:102 offset1:119
	ds_write_b64 v98, v[42:43]
	ds_write_b64 v100, v[44:45]
	ds_write_b64 v182, v[160:161]
	ds_write_b64 v183, v[140:141]
	ds_write_b64 v187, v[34:35]
	v_lshlrev_b32_e32 v35, 16, v30
	v_and_b32_e32 v34, 0xffff0000, v30
	v_lshlrev_b32_e32 v37, 16, v31
	v_and_b32_e32 v36, 0xffff0000, v31
	v_lshlrev_b32_e32 v31, 16, v32
	v_and_b32_e32 v30, 0xffff0000, v32
	v_lshlrev_b32_e32 v39, 16, v33
	v_and_b32_e32 v38, 0xffff0000, v33
	v_pk_mul_f32 v[32:33], v[82:83], v[34:35]
	v_mov_b32_e32 v63, v139
	v_fma_f32 v33, v84, v75, v33
	v_add_f32_e32 v32, v32, v33
	ds_write_b64 v186, v[62:63]
	v_add_f32_e32 v62, v80, v32
	v_mov_b32_e32 v85, v82
	v_mov_b32_e32 v32, v35
	v_mov_b32_e32 v33, v37
	v_pk_mul_f32 v[32:33], v[84:85], v[32:33]
	v_lshlrev_b32_e32 v65, 16, v29
	v_fma_f32 v32, v83, v34, v32
	v_add_f32_e32 v32, v32, v33
	v_add_f32_e32 v138, v80, v32
	v_pk_mul_f32 v[32:33], v[82:83], v[36:37]
	v_and_b32_e32 v64, 0xffff0000, v29
	v_fma_f32 v33, v84, v34, v33
	v_add_f32_e32 v32, v32, v33
	v_add_f32_e32 v140, v80, v32
	v_mov_b32_e32 v32, v37
	v_mov_b32_e32 v33, v31
	v_pk_mul_f32 v[32:33], v[84:85], v[32:33]
	v_mov_b32_e32 v100, v65
	v_fma_f32 v32, v83, v36, v32
	v_add_f32_e32 v32, v32, v33
	v_add_f32_e32 v142, v80, v32
	v_pk_mul_f32 v[32:33], v[82:83], v[30:31]
	v_pk_add_f32 v[148:149], v[148:149], v[148:149] op_sel:[0,1] op_sel_hi:[1,0]
	v_fma_f32 v33, v84, v36, v33
	v_add_f32_e32 v32, v32, v33
	v_add_f32_e32 v44, v80, v32
	v_mov_b32_e32 v32, v31
	v_mov_b32_e32 v33, v39
	v_pk_mul_f32 v[32:33], v[84:85], v[32:33]
	v_pk_add_f32 v[144:145], v[144:145], v[144:145] op_sel_hi:[0,1] neg_lo:[0,1] neg_hi:[0,1]
	v_fma_f32 v31, v83, v30, v32
	v_add_f32_e32 v31, v31, v33
	v_pk_mul_f32 v[32:33], v[82:83], v[38:39]
	v_add_f32_e32 v46, v80, v31
	v_fma_f32 v30, v84, v30, v33
	v_add_f32_e32 v30, v32, v30
	v_lshlrev_b32_e32 v31, 16, v26
	v_add_f32_e32 v42, v80, v30
	v_and_b32_e32 v30, 0xffff0000, v26
	v_lshlrev_b32_e32 v33, 16, v27
	v_and_b32_e32 v32, 0xffff0000, v27
	v_lshlrev_b32_e32 v27, 16, v28
	v_and_b32_e32 v26, 0xffff0000, v28
	v_mov_b32_e32 v28, v39
	v_mov_b32_e32 v29, v31
	v_pk_mul_f32 v[28:29], v[84:85], v[28:29]
	v_mov_b32_e32 v149, v145
	v_fma_f32 v28, v83, v38, v28
	v_add_f32_e32 v28, v28, v29
	v_add_f32_e32 v48, v80, v28
	v_pk_mul_f32 v[28:29], v[82:83], v[30:31]
	v_lshlrev_b32_e32 v145, 16, v25
	v_fma_f32 v29, v84, v38, v29
	v_add_f32_e32 v28, v28, v29
	v_add_f32_e32 v38, v80, v28
	v_mov_b32_e32 v28, v31
	v_mov_b32_e32 v29, v33
	v_pk_mul_f32 v[28:29], v[84:85], v[28:29]
	v_and_b32_e32 v144, 0xffff0000, v25
	v_fma_f32 v28, v83, v30, v28
	v_add_f32_e32 v28, v28, v29
	v_add_f32_e32 v40, v80, v28
	v_pk_mul_f32 v[28:29], v[82:83], v[32:33]
	v_pk_add_f32 v[158:159], v[158:159], v[158:159] op_sel_hi:[0,1] neg_lo:[0,1] neg_hi:[0,1]
	v_fma_f32 v29, v84, v30, v29
	v_add_f32_e32 v28, v28, v29
	v_add_f32_e32 v36, v80, v28
	v_mov_b32_e32 v28, v33
	v_mov_b32_e32 v29, v27
	v_pk_mul_f32 v[28:29], v[84:85], v[28:29]
	v_mov_b32_e32 v151, v159
	v_fma_f32 v28, v83, v32, v28
	v_add_f32_e32 v28, v28, v29
	v_add_f32_e32 v34, v80, v28
	v_pk_mul_f32 v[28:29], v[82:83], v[26:27]
	v_mov_b32_e32 v146, v0
	v_fma_f32 v29, v84, v32, v29
	v_add_f32_e32 v28, v28, v29
	v_add_f32_e32 v30, v80, v28
	v_mov_b32_e32 v28, v27
	v_mov_b32_e32 v29, v65
	v_pk_mul_f32 v[28:29], v[84:85], v[28:29]
	ds_write_b64 v184, v[148:149]
	v_fma_f32 v27, v83, v26, v28
	v_add_f32_e32 v27, v27, v29
	v_pk_mul_f32 v[28:29], v[82:83], v[64:65]
	v_add_f32_e32 v32, v80, v27
	v_fma_f32 v26, v84, v26, v29
	v_add_f32_e32 v26, v28, v26
	v_add_f32_e32 v28, v80, v26
	v_pk_mul_f32 v[26:27], v[84:85], v[100:101]
	v_lshlrev_b32_e32 v65, 16, v22
	v_fma_f32 v26, v83, v64, v26
	v_and_b32_e32 v64, 0xffff0000, v22
	v_lshlrev_b32_e32 v101, 16, v23
	v_and_b32_e32 v100, 0xffff0000, v23
	v_lshlrev_b32_e32 v23, 16, v24
	v_and_b32_e32 v22, 0xffff0000, v24
	v_pk_mul_f32 v[24:25], v[82:83], v[64:65]
	ds_write_b64 v185, v[150:151]
	v_fma_f32 v25, v84, v73, v25
	v_add_f32_e32 v24, v24, v25
	v_add_f32_e32 v63, v80, v24
	v_mov_b32_e32 v24, v65
	v_mov_b32_e32 v25, v101
	v_pk_mul_f32 v[24:25], v[84:85], v[24:25]
	v_lshlrev_b32_e32 v65, 16, v21
	v_fma_f32 v24, v83, v64, v24
	v_add_f32_e32 v24, v24, v25
	v_add_f32_e32 v139, v80, v24
	v_pk_mul_f32 v[24:25], v[82:83], v[100:101]
	s_waitcnt lgkmcnt(0)
	v_fma_f32 v25, v84, v64, v25
	v_add_f32_e32 v24, v24, v25
	v_add_f32_e32 v141, v80, v24
	v_mov_b32_e32 v24, v101
	v_mov_b32_e32 v25, v23
	v_pk_mul_f32 v[24:25], v[84:85], v[24:25]
	v_and_b32_e32 v64, 0xffff0000, v21
	v_fma_f32 v24, v83, v100, v24
	v_add_f32_e32 v24, v24, v25
	v_add_f32_e32 v143, v80, v24
	v_pk_mul_f32 v[24:25], v[82:83], v[22:23]
	s_barrier
	v_fma_f32 v25, v84, v100, v25
	v_add_f32_e32 v24, v24, v25
	v_add_f32_e32 v45, v80, v24
	v_mov_b32_e32 v24, v23
	v_mov_b32_e32 v25, v145
	v_pk_mul_f32 v[24:25], v[84:85], v[24:25]
	s_nop 0
	v_fma_f32 v23, v83, v22, v24
	v_add_f32_e32 v23, v23, v25
	v_pk_mul_f32 v[24:25], v[82:83], v[144:145]
	v_add_f32_e32 v47, v80, v23
	v_fma_f32 v22, v84, v22, v25
	v_add_f32_e32 v22, v24, v22
	v_lshlrev_b32_e32 v23, 16, v18
	v_add_f32_e32 v43, v80, v22
	v_and_b32_e32 v22, 0xffff0000, v18
	v_lshlrev_b32_e32 v25, 16, v19
	v_and_b32_e32 v24, 0xffff0000, v19
	v_lshlrev_b32_e32 v19, 16, v20
	v_and_b32_e32 v18, 0xffff0000, v20
	v_mov_b32_e32 v20, v145
	v_mov_b32_e32 v21, v23
	v_pk_mul_f32 v[20:21], v[84:85], v[20:21]
	v_mov_b32_e32 v98, v65
	v_fma_f32 v20, v83, v144, v20
	v_add_f32_e32 v20, v20, v21
	v_add_f32_e32 v49, v80, v20
	v_pk_mul_f32 v[20:21], v[82:83], v[22:23]
	v_add_f32_e32 v26, v26, v27
	v_fma_f32 v21, v84, v144, v21
	v_add_f32_e32 v20, v20, v21
	v_add_f32_e32 v39, v80, v20
	v_mov_b32_e32 v20, v23
	v_mov_b32_e32 v21, v25
	v_pk_mul_f32 v[20:21], v[84:85], v[20:21]
	v_add_f32_e32 v26, v80, v26
	v_fma_f32 v20, v83, v22, v20
	v_add_f32_e32 v20, v20, v21
	v_add_f32_e32 v41, v80, v20
	v_pk_mul_f32 v[20:21], v[82:83], v[24:25]
	s_nop 0
	v_fma_f32 v21, v84, v22, v21
	v_add_f32_e32 v20, v20, v21
	v_add_f32_e32 v37, v80, v20
	v_mov_b32_e32 v20, v25
	v_mov_b32_e32 v21, v19
	v_pk_mul_f32 v[20:21], v[84:85], v[20:21]
	v_pk_mul_f32 v[22:23], v[84:85], v[98:99]
	v_fma_f32 v20, v83, v24, v20
	v_add_f32_e32 v20, v20, v21
	v_add_f32_e32 v35, v80, v20
	v_pk_mul_f32 v[20:21], v[82:83], v[18:19]
	v_fma_f32 v22, v83, v64, v22
	v_fma_f32 v21, v84, v24, v21
	v_add_f32_e32 v20, v20, v21
	v_add_f32_e32 v31, v80, v20
	v_mov_b32_e32 v20, v19
	v_mov_b32_e32 v21, v65
	v_pk_mul_f32 v[20:21], v[84:85], v[20:21]
	v_add_f32_e32 v22, v22, v23
	v_fma_f32 v19, v83, v18, v20
	v_add_f32_e32 v19, v19, v21
	v_pk_mul_f32 v[20:21], v[82:83], v[64:65]
	v_add_f32_e32 v33, v80, v19
	v_fma_f32 v18, v84, v18, v21
	v_add_f32_e32 v18, v20, v18
	v_add_f32_e32 v29, v80, v18
	v_mul_lo_u32 v18, v146, s33
	v_add_u32_e32 v73, 0, v18
	ds_read2_b64 v[18:21], v73 offset1:1
	v_add_f32_e32 v27, v80, v22
	ds_read2_b64 v[22:25], v73 offset0:2 offset1:3
	v_add_u32_e32 v75, 0x11000, v73
	s_waitcnt lgkmcnt(1)
	v_pk_fma_f32 v[18:19], v[78:79], v[130:131], v[18:19] op_sel_hi:[0,1,1]
	v_pk_mul_f32 v[64:65], v[62:63], v[18:19]
	v_pk_fma_f32 v[18:19], v[78:79], v[136:137], v[20:21] op_sel_hi:[0,1,1]
	v_pk_mul_f32 v[82:83], v[138:139], v[18:19]
	ds_write2_b64 v73, v[64:65], v[82:83] offset1:1
	ds_write2_b64 v75, v[124:125], v[126:127] offset1:1
	s_waitcnt lgkmcnt(2)
	v_pk_fma_f32 v[18:19], v[78:79], v[132:133], v[22:23] op_sel_hi:[0,1,1]
	v_pk_mul_f32 v[62:63], v[140:141], v[18:19]
	v_pk_fma_f32 v[22:23], v[78:79], v[134:135], v[24:25] op_sel_hi:[0,1,1]
	ds_read2_b64 v[18:21], v73 offset0:4 offset1:5
	v_pk_mul_f32 v[98:99], v[142:143], v[22:23]
	v_add_u32_e32 v75, 0x11010, v73
	ds_write2_b64 v73, v[62:63], v[98:99] offset0:2 offset1:3
	ds_write2_b64 v75, v[124:125], v[126:127] offset1:1
	ds_read2_b64 v[22:25], v73 offset0:6 offset1:7
	s_waitcnt lgkmcnt(3)
	v_pk_fma_f32 v[18:19], v[78:79], v[102:103], v[18:19] op_sel_hi:[0,1,1]
	v_pk_mul_f32 v[100:101], v[44:45], v[18:19]
	v_pk_fma_f32 v[18:19], v[78:79], v[128:129], v[20:21] op_sel_hi:[0,1,1]
	v_pk_mul_f32 v[102:103], v[46:47], v[18:19]
	v_add_u32_e32 v44, 0x11020, v73
	ds_write2_b64 v73, v[100:101], v[102:103] offset0:4 offset1:5
	ds_write2_b64 v44, v[124:125], v[126:127] offset1:1
	s_waitcnt lgkmcnt(2)
	v_pk_fma_f32 v[18:19], v[78:79], v[106:107], v[22:23] op_sel_hi:[0,1,1]
	v_pk_mul_f32 v[84:85], v[42:43], v[18:19]
	v_pk_fma_f32 v[22:23], v[78:79], v[110:111], v[24:25] op_sel_hi:[0,1,1]
	ds_read2_b64 v[18:21], v73 offset0:8 offset1:9
	v_pk_mul_f32 v[110:111], v[48:49], v[22:23]
	v_add_u32_e32 v42, 0x11030, v73
	ds_write2_b64 v73, v[84:85], v[110:111] offset0:6 offset1:7
	ds_write2_b64 v42, v[124:125], v[126:127] offset1:1
	ds_read2_b64 v[22:25], v73 offset0:10 offset1:11
	s_waitcnt lgkmcnt(3)
	v_pk_fma_f32 v[18:19], v[78:79], v[104:105], v[18:19] op_sel_hi:[0,1,1]
	v_pk_mul_f32 v[106:107], v[38:39], v[18:19]
	v_pk_fma_f32 v[18:19], v[78:79], v[108:109], v[20:21] op_sel_hi:[0,1,1]
	v_pk_mul_f32 v[108:109], v[40:41], v[18:19]
	v_add_u32_e32 v38, 0x11040, v73
	ds_write2_b64 v73, v[106:107], v[108:109] offset0:8 offset1:9
	ds_write2_b64 v38, v[124:125], v[126:127] offset1:1
	s_waitcnt lgkmcnt(2)
	v_pk_fma_f32 v[18:19], v[78:79], v[112:113], v[22:23] op_sel_hi:[0,1,1]
	v_pk_fma_f32 v[22:23], v[78:79], v[116:117], v[24:25] op_sel_hi:[0,1,1]
	v_pk_mul_f32 v[104:105], v[36:37], v[18:19]
	ds_read2_b64 v[18:21], v73 offset0:12 offset1:13
	v_pk_mul_f32 v[112:113], v[34:35], v[22:23]
	v_add_u32_e32 v36, 0x11050, v73
	ds_write2_b64 v73, v[104:105], v[112:113] offset0:10 offset1:11
	ds_write2_b64 v36, v[124:125], v[126:127] offset1:1
	ds_read2_b64 v[22:25], v73 offset0:14 offset1:15
	s_waitcnt lgkmcnt(3)
	v_pk_fma_f32 v[18:19], v[78:79], v[114:115], v[18:19] op_sel_hi:[0,1,1]
	v_pk_mul_f32 v[116:117], v[30:31], v[18:19]
	v_pk_fma_f32 v[18:19], v[78:79], v[120:121], v[20:21] op_sel_hi:[0,1,1]
	v_pk_mul_f32 v[120:121], v[32:33], v[18:19]
	s_waitcnt lgkmcnt(0)
	v_pk_fma_f32 v[18:19], v[78:79], v[122:123], v[22:23] op_sel_hi:[0,1,1]
	v_pk_mul_f32 v[114:115], v[28:29], v[18:19]
	v_pk_fma_f32 v[18:19], v[78:79], v[118:119], v[24:25] op_sel_hi:[0,1,1]
	v_add_u32_e32 v20, 0x11070, v73
	v_pk_mul_f32 v[118:119], v[26:27], v[18:19]
	v_lshl_add_u64 v[18:19], v[68:69], 0, s[44:45]
	v_add_u32_e32 v30, 0x11060, v73
	ds_write2_b64 v73, v[116:117], v[120:121] offset0:12 offset1:13
	ds_write2_b64 v30, v[124:125], v[126:127] offset1:1
	ds_write2_b64 v73, v[114:115], v[118:119] offset0:14 offset1:15
	ds_write2_b64 v20, v[124:125], v[126:127] offset1:1
	v_add_co_u32_e32 v20, vcc, s13, v18
	s_waitcnt lgkmcnt(0)
	s_nop 0
	v_addc_co_u32_e32 v21, vcc, 0, v19, vcc
	s_barrier
	global_load_dwordx4 v[46:49], v[18:19], off
	global_load_dwordx4 v[42:45], v[20:21], off
	v_add_co_u32_e32 v20, vcc, s22, v18
	v_mov_b32_e32 v73, v0
	s_nop 0
	v_addc_co_u32_e32 v21, vcc, 0, v19, vcc
	v_add_co_u32_e32 v22, vcc, s23, v18
	s_nop 1
	v_addc_co_u32_e32 v23, vcc, 0, v19, vcc
	global_load_dwordx4 v[38:41], v[20:21], off
	global_load_dwordx4 v[34:37], v[22:23], off
	v_add_co_u32_e32 v20, vcc, s3, v18
	s_nop 1
	v_addc_co_u32_e32 v21, vcc, 0, v19, vcc
	v_add_co_u32_e32 v22, vcc, s25, v18
	s_nop 1
	v_addc_co_u32_e32 v23, vcc, 0, v19, vcc
	global_load_dwordx4 v[30:33], v[20:21], off
	global_load_dwordx4 v[26:29], v[22:23], off
	v_add_co_u32_e32 v20, vcc, s29, v18
	s_nop 1
	v_addc_co_u32_e32 v21, vcc, 0, v19, vcc
	v_add_co_u32_e32 v18, vcc, s30, v18
	s_nop 1
	v_addc_co_u32_e32 v19, vcc, 0, v19, vcc
	global_load_dwordx4 v[22:25], v[20:21], off
	s_nop 0
	global_load_dwordx4 v[18:21], v[18:19], off
	s_nop 0
	v_and_b32_e32 v75, 0x3ff, v73
	v_lshlrev_b32_e32 v78, 4, v73
	v_and_or_b32 v78, v78, s31, v75
	v_ashrrev_i32_e32 v80, 4, v78
	v_lshlrev_b32_e32 v80, 3, v80
	v_lshlrev_b32_e32 v78, 3, v78
	v_add3_u32 v78, 0, v80, v78
	ds_read2st64_b64 v[122:125], v78 offset1:17
	ds_read2st64_b64 v[126:129], v78 offset0:34 offset1:51
	ds_read2st64_b64 v[130:133], v78 offset0:68 offset1:85
	ds_read2st64_b64 v[134:137], v78 offset0:102 offset1:119
	v_add_u32_e32 v80, 0x11000, v78
	v_add_u32_e32 v197, 0x19800, v78
	v_add_u32_e32 v190, 0x13200, v78
	v_add_u32_e32 v193, 0x15400, v78
	v_add_u32_e32 v195, 0x17600, v78
	ds_read_b64 v[138:139], v80
	ds_read_b64 v[140:141], v190
	ds_read_b64 v[142:143], v193
	ds_read_b64 v[144:145], v195
	v_add_u32_e32 v214, 0x1ba00, v78
	v_add_u32_e32 v215, 0x1dc00, v78
	v_add_u32_e32 v216, 0x1fe00, v78
	ds_read_b64 v[146:147], v197
	ds_read_b64 v[148:149], v214
	ds_read_b64 v[150:151], v215
	ds_read_b64 v[152:153], v216
	s_waitcnt lgkmcnt(11)
	v_mov_b32_e32 v154, v122
	s_waitcnt lgkmcnt(9)
	v_mov_b32_e32 v155, v130
	s_waitcnt lgkmcnt(7)
	v_mov_b32_e32 v156, v138
	s_waitcnt lgkmcnt(3)
	v_mov_b32_e32 v157, v146
	v_pk_add_f32 v[154:155], v[154:155], v[156:157]
	v_mov_b32_e32 v156, v123
	v_mov_b32_e32 v157, v131
	v_mov_b32_e32 v158, v139
	v_mov_b32_e32 v159, v147
	v_pk_add_f32 v[156:157], v[156:157], v[158:159]
	v_pk_mov_b32 v[158:159], v[122:123], v[130:131] op_sel:[1,0]
	v_pk_mov_b32 v[160:161], v[138:139], v[146:147] op_sel:[1,0]
	v_mov_b32_e32 v123, v131
	v_pk_add_f32 v[158:159], v[158:159], v[160:161] neg_lo:[0,1] neg_hi:[0,1]
	v_mov_b32_e32 v139, v147
	v_mov_b32_e32 v130, v154
	v_mov_b32_e32 v131, v156
	v_mov_b32_e32 v156, v155
	v_pk_add_f32 v[122:123], v[122:123], v[138:139] neg_lo:[0,1] neg_hi:[0,1]
	v_pk_add_f32 v[138:139], v[130:131], v[156:157]
	v_pk_add_f32 v[130:131], v[130:131], v[156:157] neg_lo:[0,1] neg_hi:[0,1]
	v_pk_add_f32 v[154:155], v[158:159], v[158:159] op_sel_hi:[0,1] neg_lo:[0,1] neg_hi:[0,1]
	v_pk_add_f32 v[156:157], v[158:159], v[158:159] op_sel_hi:[0,1]
	v_pk_add_f32 v[158:159], v[124:125], v[140:141]
	s_waitcnt lgkmcnt(2)
	v_pk_add_f32 v[160:161], v[132:133], v[148:149]
	v_pk_add_f32 v[124:125], v[124:125], v[140:141] neg_lo:[0,1] neg_hi:[0,1]
	v_pk_add_f32 v[132:133], v[132:133], v[148:149] neg_lo:[0,1] neg_hi:[0,1]
	s_waitcnt lgkmcnt(1)
	v_pk_add_f32 v[148:149], v[134:135], v[150:151]
	v_pk_add_f32 v[140:141], v[124:125], v[132:133] op_sel:[0,1] op_sel_hi:[1,0]
	v_pk_add_f32 v[124:125], v[124:125], v[132:133] op_sel:[0,1] op_sel_hi:[1,0] neg_lo:[0,1] neg_hi:[0,1]
	v_mov_b32_e32 v132, v140
	v_mov_b32_e32 v133, v125
	v_mov_b32_e32 v125, v141
	v_pk_add_f32 v[140:141], v[126:127], v[142:143]
	v_pk_add_f32 v[126:127], v[126:127], v[142:143] neg_lo:[0,1] neg_hi:[0,1]
	v_pk_add_f32 v[134:135], v[134:135], v[150:151] neg_lo:[0,1] neg_hi:[0,1]
	v_pk_add_f32 v[162:163], v[158:159], v[160:161]
	v_pk_add_f32 v[142:143], v[126:127], v[134:135] op_sel:[0,1] op_sel_hi:[1,0]
	v_pk_add_f32 v[126:127], v[126:127], v[134:135] op_sel:[0,1] op_sel_hi:[1,0] neg_lo:[0,1] neg_hi:[0,1]
	v_pk_add_f32 v[158:159], v[158:159], v[160:161] neg_lo:[0,1] neg_hi:[0,1]
	v_pk_add_f32 v[160:161], v[140:141], v[148:149]
	v_pk_add_f32 v[140:141], v[140:141], v[148:149] neg_lo:[0,1] neg_hi:[0,1]
	v_mov_b32_e32 v134, v142
	v_mov_b32_e32 v135, v127
	v_mov_b32_e32 v127, v143
	v_pk_add_f32 v[142:143], v[128:129], v[144:145]
	s_waitcnt lgkmcnt(0)
	v_pk_add_f32 v[148:149], v[136:137], v[152:153]
	v_pk_add_f32 v[128:129], v[128:129], v[144:145] neg_lo:[0,1] neg_hi:[0,1]
	v_pk_add_f32 v[136:137], v[136:137], v[152:153] neg_lo:[0,1] neg_hi:[0,1]
	v_pk_add_f32 v[150:151], v[142:143], v[148:149]
	v_pk_add_f32 v[142:143], v[142:143], v[148:149] neg_lo:[0,1] neg_hi:[0,1]
	v_pk_add_f32 v[144:145], v[128:129], v[136:137] op_sel:[0,1] op_sel_hi:[1,0]
	v_pk_add_f32 v[128:129], v[128:129], v[136:137] op_sel:[0,1] op_sel_hi:[1,0] neg_lo:[0,1] neg_hi:[0,1]
	v_pk_mul_f32 v[148:149], v[140:141], v[94:95] op_sel:[0,0] op_sel_hi:[0,1]
	v_mov_b32_e32 v136, v144
	v_mov_b32_e32 v137, v129
	v_mov_b32_e32 v129, v145
	v_pk_mul_f32 v[144:145], v[132:133], v[90:91] op_sel:[0,0] op_sel_hi:[0,1]
	v_pk_fma_f32 v[140:141], v[140:141], v[94:95], v[148:149] op_sel:[1,1,0] op_sel_hi:[1,0,1] neg_lo:[1,0,0]
	v_pk_mul_f32 v[148:149], v[142:143], v[92:93] op_sel:[0,0] op_sel_hi:[0,1]
	v_cvt_f32_u32_e32 v75, v75
	v_pk_fma_f32 v[132:133], v[132:133], v[90:91], v[144:145] op_sel:[1,1,0] op_sel_hi:[1,0,1] neg_lo:[1,0,0]
	v_pk_mul_f32 v[144:145], v[134:135], v[88:89] op_sel:[0,0] op_sel_hi:[0,1]
	v_pk_fma_f32 v[142:143], v[142:143], v[92:93], v[148:149] op_sel:[1,1,0] op_sel_hi:[1,0,1] neg_lo:[1,0,0]
	v_pk_mul_f32 v[148:149], v[124:125], v[86:87] op_sel:[0,0] op_sel_hi:[0,1]
	v_pk_add_f32 v[146:147], v[122:123], v[122:123] op_sel:[0,1] op_sel_hi:[1,0]
	v_pk_fma_f32 v[134:135], v[134:135], v[88:89], v[144:145] op_sel:[1,1,0] op_sel_hi:[1,0,1] neg_lo:[1,0,0]
	v_pk_mul_f32 v[144:145], v[136:137], v[86:87] op_sel:[0,0] op_sel_hi:[0,1]
	v_pk_fma_f32 v[124:125], v[124:125], v[86:87], v[148:149] op_sel:[1,1,0] op_sel_hi:[1,0,1] neg_lo:[1,0,0]
	v_pk_mul_f32 v[148:149], v[126:127], v[92:93] op_sel:[0,0] op_sel_hi:[0,1]
	v_pk_add_f32 v[122:123], v[122:123], v[122:123] op_sel:[0,1] op_sel_hi:[1,0] neg_lo:[0,1] neg_hi:[0,1]
	v_pk_fma_f32 v[136:137], v[136:137], v[86:87], v[144:145] op_sel:[1,1,0] op_sel_hi:[1,0,1] neg_lo:[1,0,0]
	v_pk_mul_f32 v[144:145], v[158:159], v[88:89] op_sel:[0,0] op_sel_hi:[0,1]
	v_pk_fma_f32 v[126:127], v[126:127], v[92:93], v[148:149] op_sel:[1,1,0] op_sel_hi:[1,0,1] neg_lo:[1,0,0]
	v_pk_mul_f32 v[148:149], v[128:129], v[96:97] op_sel:[0,0] op_sel_hi:[0,1]
	v_mov_b32_e32 v147, v155
	v_pk_fma_f32 v[144:145], v[158:159], v[88:89], v[144:145] op_sel:[1,1,0] op_sel_hi:[1,0,1] neg_lo:[1,0,0]
	v_pk_fma_f32 v[128:129], v[128:129], v[96:97], v[148:149] op_sel:[1,1,0] op_sel_hi:[1,0,1] neg_lo:[1,0,0]
	v_pk_add_f32 v[148:149], v[138:139], v[160:161]
	v_pk_add_f32 v[138:139], v[138:139], v[160:161] neg_lo:[0,1] neg_hi:[0,1]
	v_pk_add_f32 v[154:155], v[146:147], v[134:135]
	v_pk_add_f32 v[160:161], v[132:133], v[136:137]
	v_mov_b32_e32 v123, v157
	v_mul_f32_e32 v75, 0x38800000, v75
	v_pk_add_f32 v[152:153], v[162:163], v[150:151]
	v_pk_add_f32 v[150:151], v[162:163], v[150:151] neg_lo:[0,1] neg_hi:[0,1]
	v_pk_add_f32 v[162:163], v[154:155], v[160:161]
	v_pk_add_f32 v[154:155], v[154:155], v[160:161] neg_lo:[0,1] neg_hi:[0,1]
	v_pk_add_f32 v[134:135], v[146:147], v[134:135] neg_lo:[0,1] neg_hi:[0,1]
	v_pk_add_f32 v[146:147], v[130:131], v[140:141]
	v_pk_add_f32 v[160:161], v[144:145], v[142:143]
	v_pk_add_f32 v[130:131], v[130:131], v[140:141] neg_lo:[0,1] neg_hi:[0,1]
	v_pk_add_f32 v[140:141], v[144:145], v[142:143] neg_lo:[0,1] neg_hi:[0,1]
	v_pk_add_f32 v[144:145], v[122:123], v[126:127]
	v_pk_add_f32 v[156:157], v[124:125], v[128:129]
	v_pk_add_f32 v[124:125], v[124:125], v[128:129] neg_lo:[0,1] neg_hi:[0,1]
	v_cos_f32_e32 v128, v75
	v_sin_f32_e32 v75, v75
	v_pk_add_f32 v[164:165], v[146:147], v[160:161]
	v_pk_add_f32 v[146:147], v[146:147], v[160:161] neg_lo:[0,1] neg_hi:[0,1]
	v_pk_add_f32 v[160:161], v[144:145], v[156:157]
	v_pk_add_f32 v[144:145], v[144:145], v[156:157] neg_lo:[0,1] neg_hi:[0,1]
	s_nop 1
	v_pk_add_f32 v[142:143], v[130:131], v[140:141] op_sel:[0,1] op_sel_hi:[1,0]
	v_xor_b32_e32 v129, 0x80000000, v75
	v_pk_mul_f32 v[156:157], v[128:129], v[128:129] op_sel:[0,0] op_sel_hi:[0,1]
	v_pk_add_f32 v[130:131], v[130:131], v[140:141] op_sel:[0,1] op_sel_hi:[1,0] neg_lo:[0,1] neg_hi:[0,1]
	v_pk_fma_f32 v[156:157], v[128:129], v[128:129], v[156:157] op_sel:[1,1,0] op_sel_hi:[1,0,1] neg_lo:[1,0,0]
	v_mov_b32_e32 v141, v143
	v_pk_mul_f32 v[166:167], v[156:157], v[128:129] op_sel:[0,0] op_sel_hi:[0,1]
	v_pk_mul_f32 v[168:169], v[156:157], v[156:157] op_sel:[0,0] op_sel_hi:[0,1]
	v_mov_b32_e32 v140, v130
	v_pk_fma_f32 v[166:167], v[156:157], v[128:129], v[166:167] op_sel:[1,1,0] op_sel_hi:[1,0,1] neg_lo:[1,0,0]
	v_pk_fma_f32 v[168:169], v[156:157], v[156:157], v[168:169] op_sel:[1,1,0] op_sel_hi:[1,0,1] neg_lo:[1,0,0]
	v_mov_b32_e32 v143, v131
	v_pk_mul_f32 v[170:171], v[168:169], v[128:129] op_sel:[0,0] op_sel_hi:[0,1]
	v_pk_mul_f32 v[172:173], v[166:167], v[166:167] op_sel:[0,0] op_sel_hi:[0,1]
	v_pk_mul_f32 v[176:177], v[168:169], v[168:169] op_sel:[0,0] op_sel_hi:[0,1]
	v_pk_add_f32 v[158:159], v[148:149], v[152:153]
	v_pk_fma_f32 v[170:171], v[168:169], v[128:129], v[170:171] op_sel:[1,1,0] op_sel_hi:[1,0,1] neg_lo:[1,0,0]
	v_pk_fma_f32 v[172:173], v[166:167], v[166:167], v[172:173] op_sel:[1,1,0] op_sel_hi:[1,0,1] neg_lo:[1,0,0]
	v_pk_fma_f32 v[176:177], v[168:169], v[168:169], v[176:177] op_sel:[1,1,0] op_sel_hi:[1,0,1] neg_lo:[1,0,0]
	v_pk_add_f32 v[148:149], v[148:149], v[152:153] neg_lo:[0,1] neg_hi:[0,1]
	v_pk_mul_f32 v[180:181], v[170:171], v[170:171] op_sel:[0,0] op_sel_hi:[0,1]
	v_pk_mul_f32 v[130:131], v[142:143], v[172:173] op_sel:[0,0] op_sel_hi:[0,1]
	v_pk_mul_f32 v[182:183], v[176:177], v[166:167] op_sel:[0,0] op_sel_hi:[0,1]
	v_pk_add_f32 v[152:153], v[138:139], v[150:151] op_sel:[0,1] op_sel_hi:[1,0]
	v_pk_fma_f32 v[180:181], v[170:171], v[170:171], v[180:181] op_sel:[1,1,0] op_sel_hi:[1,0,1] neg_lo:[1,0,0]
	v_pk_fma_f32 v[130:131], v[142:143], v[172:173], v[130:131] op_sel:[1,1,0] op_sel_hi:[1,0,1] neg_lo:[1,0,0]
	v_pk_add_f32 v[138:139], v[138:139], v[150:151] op_sel:[0,1] op_sel_hi:[1,0] neg_lo:[0,1] neg_hi:[0,1]
	v_pk_mul_f32 v[142:143], v[146:147], v[180:181] op_sel:[0,0] op_sel_hi:[0,1]
	v_pk_add_f32 v[132:133], v[132:133], v[136:137] neg_lo:[0,1] neg_hi:[0,1]
	v_pk_add_f32 v[122:123], v[122:123], v[126:127] neg_lo:[0,1] neg_hi:[0,1]
	v_pk_fma_f32 v[182:183], v[176:177], v[166:167], v[182:183] op_sel:[1,1,0] op_sel_hi:[1,0,1] neg_lo:[1,0,0]
	v_pk_mul_f32 v[184:185], v[172:173], v[172:173] op_sel:[0,0] op_sel_hi:[0,1]
	v_pk_fma_f32 v[142:143], v[146:147], v[180:181], v[142:143] op_sel:[1,1,0] op_sel_hi:[1,0,1] neg_lo:[1,0,0]
	v_mov_b32_e32 v151, v139
	v_pk_mul_f32 v[146:147], v[144:145], v[182:183] op_sel:[0,0] op_sel_hi:[0,1]
	v_pk_add_f32 v[136:137], v[134:135], v[132:133] op_sel:[0,1] op_sel_hi:[1,0]
	v_pk_add_f32 v[132:133], v[134:135], v[132:133] op_sel:[0,1] op_sel_hi:[1,0] neg_lo:[0,1] neg_hi:[0,1]
	v_pk_add_f32 v[126:127], v[122:123], v[124:125] op_sel:[0,1] op_sel_hi:[1,0]
	v_pk_add_f32 v[122:123], v[122:123], v[124:125] op_sel:[0,1] op_sel_hi:[1,0] neg_lo:[0,1] neg_hi:[0,1]
	v_pk_mul_f32 v[174:175], v[168:169], v[166:167] op_sel:[0,0] op_sel_hi:[0,1]
	v_pk_mul_f32 v[178:179], v[176:177], v[128:129] op_sel:[0,0] op_sel_hi:[0,1]
	v_pk_fma_f32 v[184:185], v[172:173], v[172:173], v[184:185] op_sel:[1,1,0] op_sel_hi:[1,0,1] neg_lo:[1,0,0]
	v_pk_mul_f32 v[186:187], v[176:177], v[170:171] op_sel:[0,0] op_sel_hi:[0,1]
	v_pk_fma_f32 v[144:145], v[144:145], v[182:183], v[146:147] op_sel:[1,1,0] op_sel_hi:[1,0,1] neg_lo:[1,0,0]
	v_mov_b32_e32 v139, v153
	v_pk_mul_f32 v[146:147], v[138:139], v[184:185] op_sel:[0,0] op_sel_hi:[0,1]
	v_add_u32_e32 v73, 0x200, v73
	v_mov_b32_e32 v134, v132
	v_mov_b32_e32 v135, v137
	v_mov_b32_e32 v124, v122
	v_mov_b32_e32 v125, v127
	v_pk_fma_f32 v[174:175], v[168:169], v[166:167], v[174:175] op_sel:[1,1,0] op_sel_hi:[1,0,1] neg_lo:[1,0,0]
	v_pk_fma_f32 v[178:179], v[176:177], v[128:129], v[178:179] op_sel:[1,1,0] op_sel_hi:[1,0,1] neg_lo:[1,0,0]
	v_pk_fma_f32 v[186:187], v[176:177], v[170:171], v[186:187] op_sel:[1,1,0] op_sel_hi:[1,0,1] neg_lo:[1,0,0]
	v_pk_mul_f32 v[212:213], v[162:163], v[128:129] op_sel:[0,0] op_sel_hi:[0,1]
	v_mov_b32_e32 v137, v133
	v_pk_mul_f32 v[188:189], v[174:175], v[174:175] op_sel:[0,0] op_sel_hi:[0,1]
	v_pk_fma_f32 v[128:129], v[162:163], v[128:129], v[212:213] op_sel:[1,1,0] op_sel_hi:[1,0,1] neg_lo:[1,0,0]
	v_pk_mul_f32 v[162:163], v[164:165], v[156:157] op_sel:[0,0] op_sel_hi:[0,1]
	v_pk_mul_f32 v[132:133], v[136:137], v[170:171] op_sel:[0,0] op_sel_hi:[0,1]
	v_mov_b32_e32 v127, v123
	v_pk_mul_f32 v[122:123], v[126:127], v[174:175] op_sel:[0,0] op_sel_hi:[0,1]
	v_pk_fma_f32 v[138:139], v[138:139], v[184:185], v[146:147] op_sel:[1,1,0] op_sel_hi:[1,0,1] neg_lo:[1,0,0]
	v_pk_mul_f32 v[146:147], v[134:135], v[186:187] op_sel:[0,0] op_sel_hi:[0,1]
	v_and_b32_e32 v75, 0x3ff, v73
	v_lshlrev_b32_e32 v73, 4, v73
	v_mov_b32_e32 v150, v152
	v_pk_fma_f32 v[188:189], v[174:175], v[174:175], v[188:189] op_sel:[1,1,0] op_sel_hi:[1,0,1] neg_lo:[1,0,0]
	v_pk_mul_f32 v[210:211], v[176:177], v[174:175] op_sel:[0,0] op_sel_hi:[0,1]
	v_pk_fma_f32 v[156:157], v[164:165], v[156:157], v[162:163] op_sel:[1,1,0] op_sel_hi:[1,0,1] neg_lo:[1,0,0]
	v_pk_mul_f32 v[162:163], v[160:161], v[166:167] op_sel:[0,0] op_sel_hi:[0,1]
	v_pk_fma_f32 v[132:133], v[136:137], v[170:171], v[132:133] op_sel:[1,1,0] op_sel_hi:[1,0,1] neg_lo:[1,0,0]
	v_pk_fma_f32 v[122:123], v[126:127], v[174:175], v[122:123] op_sel:[1,1,0] op_sel_hi:[1,0,1] neg_lo:[1,0,0]
	v_pk_mul_f32 v[126:127], v[148:149], v[176:177] op_sel:[0,0] op_sel_hi:[0,1]
	v_pk_mul_f32 v[136:137], v[154:155], v[178:179] op_sel:[0,0] op_sel_hi:[0,1]
	v_pk_fma_f32 v[134:135], v[134:135], v[186:187], v[146:147] op_sel:[1,1,0] op_sel_hi:[1,0,1] neg_lo:[1,0,0]
	s_nop 0
	v_pk_mul_f32 v[146:147], v[140:141], v[188:189] op_sel:[0,0] op_sel_hi:[0,1]
	v_and_or_b32 v73, v73, s31, v75
	v_pk_fma_f32 v[210:211], v[176:177], v[174:175], v[210:211] op_sel:[1,1,0] op_sel_hi:[1,0,1] neg_lo:[1,0,0]
	v_pk_fma_f32 v[160:161], v[160:161], v[166:167], v[162:163] op_sel:[1,1,0] op_sel_hi:[1,0,1] neg_lo:[1,0,0]
	v_pk_mul_f32 v[162:163], v[150:151], v[168:169] op_sel:[0,0] op_sel_hi:[0,1]
	v_pk_fma_f32 v[126:127], v[148:149], v[176:177], v[126:127] op_sel:[1,1,0] op_sel_hi:[1,0,1] neg_lo:[1,0,0]
	v_pk_fma_f32 v[136:137], v[154:155], v[178:179], v[136:137] op_sel:[1,1,0] op_sel_hi:[1,0,1] neg_lo:[1,0,0]
	v_pk_fma_f32 v[140:141], v[140:141], v[188:189], v[146:147] op_sel:[1,1,0] op_sel_hi:[1,0,1] neg_lo:[1,0,0]
	s_nop 0
	v_pk_mul_f32 v[146:147], v[124:125], v[210:211] op_sel:[0,0] op_sel_hi:[0,1]
	v_cvt_f32_u32_e32 v75, v75
	v_pk_fma_f32 v[150:151], v[150:151], v[168:169], v[162:163] op_sel:[1,1,0] op_sel_hi:[1,0,1] neg_lo:[1,0,0]
	v_pk_fma_f32 v[124:125], v[124:125], v[210:211], v[146:147] op_sel:[1,1,0] op_sel_hi:[1,0,1] neg_lo:[1,0,0]
	ds_write2st64_b64 v78, v[158:159], v[128:129] offset1:17
	ds_write2st64_b64 v78, v[156:157], v[160:161] offset0:34 offset1:51
	ds_write2st64_b64 v78, v[150:151], v[132:133] offset0:68 offset1:85
	ds_write2st64_b64 v78, v[130:131], v[122:123] offset0:102 offset1:119
	ds_write_b64 v80, v[126:127]
	ds_write_b64 v190, v[136:137]
	ds_write_b64 v193, v[142:143]
	ds_write_b64 v195, v[144:145]
	ds_write_b64 v197, v[138:139]
	ds_write_b64 v214, v[134:135]
	ds_write_b64 v215, v[140:141]
	ds_write_b64 v216, v[124:125]
	v_ashrrev_i32_e32 v78, 4, v73
	v_lshlrev_b32_e32 v78, 3, v78
	v_lshlrev_b32_e32 v73, 3, v73
	v_add3_u32 v73, 0, v78, v73
	ds_read2st64_b64 v[122:125], v73 offset1:17
	ds_read2st64_b64 v[126:129], v73 offset0:34 offset1:51
	ds_read2st64_b64 v[130:133], v73 offset0:68 offset1:85
	ds_read2st64_b64 v[134:137], v73 offset0:102 offset1:119
	v_add_u32_e32 v78, 0x11000, v73
	v_add_u32_e32 v195, 0x19800, v73
	v_add_u32_e32 v80, 0x13200, v73
	v_add_u32_e32 v190, 0x15400, v73
	v_add_u32_e32 v193, 0x17600, v73
	ds_read_b64 v[138:139], v78
	ds_read_b64 v[140:141], v80
	ds_read_b64 v[142:143], v190
	ds_read_b64 v[144:145], v193
	v_add_u32_e32 v197, 0x1ba00, v73
	v_add_u32_e32 v214, 0x1dc00, v73
	v_add_u32_e32 v215, 0x1fe00, v73
	ds_read_b64 v[146:147], v195
	ds_read_b64 v[148:149], v197
	ds_read_b64 v[150:151], v214
	ds_read_b64 v[152:153], v215
	s_waitcnt lgkmcnt(11)
	v_mov_b32_e32 v154, v122
	s_waitcnt lgkmcnt(9)
	v_mov_b32_e32 v155, v130
	s_waitcnt lgkmcnt(7)
	v_mov_b32_e32 v156, v138
	s_waitcnt lgkmcnt(3)
	v_mov_b32_e32 v157, v146
	v_pk_add_f32 v[154:155], v[154:155], v[156:157]
	v_mov_b32_e32 v156, v123
	v_mov_b32_e32 v157, v131
	v_mov_b32_e32 v158, v139
	v_mov_b32_e32 v159, v147
	v_pk_add_f32 v[156:157], v[156:157], v[158:159]
	v_pk_mov_b32 v[158:159], v[122:123], v[130:131] op_sel:[1,0]
	v_pk_mov_b32 v[160:161], v[138:139], v[146:147] op_sel:[1,0]
	v_mov_b32_e32 v123, v131
	v_pk_add_f32 v[158:159], v[158:159], v[160:161] neg_lo:[0,1] neg_hi:[0,1]
	v_mov_b32_e32 v139, v147
	v_mov_b32_e32 v130, v154
	v_mov_b32_e32 v131, v156
	v_mov_b32_e32 v156, v155
	v_pk_add_f32 v[122:123], v[122:123], v[138:139] neg_lo:[0,1] neg_hi:[0,1]
	v_pk_add_f32 v[138:139], v[130:131], v[156:157]
	v_pk_add_f32 v[130:131], v[130:131], v[156:157] neg_lo:[0,1] neg_hi:[0,1]
	v_pk_add_f32 v[154:155], v[158:159], v[158:159] op_sel_hi:[0,1] neg_lo:[0,1] neg_hi:[0,1]
	v_pk_add_f32 v[156:157], v[158:159], v[158:159] op_sel_hi:[0,1]
	v_pk_add_f32 v[158:159], v[124:125], v[140:141]
	s_waitcnt lgkmcnt(2)
	v_pk_add_f32 v[160:161], v[132:133], v[148:149]
	v_pk_add_f32 v[124:125], v[124:125], v[140:141] neg_lo:[0,1] neg_hi:[0,1]
	v_pk_add_f32 v[132:133], v[132:133], v[148:149] neg_lo:[0,1] neg_hi:[0,1]
	s_waitcnt lgkmcnt(1)
	v_pk_add_f32 v[148:149], v[134:135], v[150:151]
	v_pk_add_f32 v[140:141], v[124:125], v[132:133] op_sel:[0,1] op_sel_hi:[1,0]
	v_pk_add_f32 v[124:125], v[124:125], v[132:133] op_sel:[0,1] op_sel_hi:[1,0] neg_lo:[0,1] neg_hi:[0,1]
	v_mov_b32_e32 v132, v140
	v_mov_b32_e32 v133, v125
	v_mov_b32_e32 v125, v141
	v_pk_add_f32 v[140:141], v[126:127], v[142:143]
	v_pk_add_f32 v[126:127], v[126:127], v[142:143] neg_lo:[0,1] neg_hi:[0,1]
	v_pk_add_f32 v[134:135], v[134:135], v[150:151] neg_lo:[0,1] neg_hi:[0,1]
	v_pk_add_f32 v[162:163], v[158:159], v[160:161]
	v_pk_add_f32 v[142:143], v[126:127], v[134:135] op_sel:[0,1] op_sel_hi:[1,0]
	v_pk_add_f32 v[126:127], v[126:127], v[134:135] op_sel:[0,1] op_sel_hi:[1,0] neg_lo:[0,1] neg_hi:[0,1]
	v_pk_add_f32 v[158:159], v[158:159], v[160:161] neg_lo:[0,1] neg_hi:[0,1]
	v_pk_add_f32 v[160:161], v[140:141], v[148:149]
	v_pk_add_f32 v[140:141], v[140:141], v[148:149] neg_lo:[0,1] neg_hi:[0,1]
	v_mov_b32_e32 v134, v142
	v_mov_b32_e32 v135, v127
	v_mov_b32_e32 v127, v143
	v_pk_add_f32 v[142:143], v[128:129], v[144:145]
	s_waitcnt lgkmcnt(0)
	v_pk_add_f32 v[148:149], v[136:137], v[152:153]
	v_pk_add_f32 v[128:129], v[128:129], v[144:145] neg_lo:[0,1] neg_hi:[0,1]
	v_pk_add_f32 v[136:137], v[136:137], v[152:153] neg_lo:[0,1] neg_hi:[0,1]
	v_pk_add_f32 v[150:151], v[142:143], v[148:149]
	v_pk_add_f32 v[142:143], v[142:143], v[148:149] neg_lo:[0,1] neg_hi:[0,1]
	v_pk_add_f32 v[144:145], v[128:129], v[136:137] op_sel:[0,1] op_sel_hi:[1,0]
	v_pk_add_f32 v[128:129], v[128:129], v[136:137] op_sel:[0,1] op_sel_hi:[1,0] neg_lo:[0,1] neg_hi:[0,1]
	v_pk_mul_f32 v[148:149], v[140:141], v[94:95] op_sel:[0,0] op_sel_hi:[0,1]
	v_mov_b32_e32 v136, v144
	v_mov_b32_e32 v137, v129
	v_mov_b32_e32 v129, v145
	v_pk_mul_f32 v[144:145], v[132:133], v[90:91] op_sel:[0,0] op_sel_hi:[0,1]
	v_pk_fma_f32 v[140:141], v[140:141], v[94:95], v[148:149] op_sel:[1,1,0] op_sel_hi:[1,0,1] neg_lo:[1,0,0]
	v_pk_mul_f32 v[148:149], v[142:143], v[92:93] op_sel:[0,0] op_sel_hi:[0,1]
	v_pk_add_f32 v[146:147], v[122:123], v[122:123] op_sel:[0,1] op_sel_hi:[1,0]
	v_pk_fma_f32 v[132:133], v[132:133], v[90:91], v[144:145] op_sel:[1,1,0] op_sel_hi:[1,0,1] neg_lo:[1,0,0]
	v_pk_mul_f32 v[144:145], v[134:135], v[88:89] op_sel:[0,0] op_sel_hi:[0,1]
	v_pk_fma_f32 v[142:143], v[142:143], v[92:93], v[148:149] op_sel:[1,1,0] op_sel_hi:[1,0,1] neg_lo:[1,0,0]
	v_pk_mul_f32 v[148:149], v[124:125], v[86:87] op_sel:[0,0] op_sel_hi:[0,1]
	v_pk_add_f32 v[122:123], v[122:123], v[122:123] op_sel:[0,1] op_sel_hi:[1,0] neg_lo:[0,1] neg_hi:[0,1]
	v_pk_fma_f32 v[134:135], v[134:135], v[88:89], v[144:145] op_sel:[1,1,0] op_sel_hi:[1,0,1] neg_lo:[1,0,0]
	v_pk_mul_f32 v[144:145], v[136:137], v[86:87] op_sel:[0,0] op_sel_hi:[0,1]
	v_pk_fma_f32 v[124:125], v[124:125], v[86:87], v[148:149] op_sel:[1,1,0] op_sel_hi:[1,0,1] neg_lo:[1,0,0]
	v_pk_mul_f32 v[148:149], v[126:127], v[92:93] op_sel:[0,0] op_sel_hi:[0,1]
	v_mov_b32_e32 v147, v155
	v_pk_fma_f32 v[136:137], v[136:137], v[86:87], v[144:145] op_sel:[1,1,0] op_sel_hi:[1,0,1] neg_lo:[1,0,0]
	v_pk_mul_f32 v[144:145], v[158:159], v[88:89] op_sel:[0,0] op_sel_hi:[0,1]
	v_pk_fma_f32 v[126:127], v[126:127], v[92:93], v[148:149] op_sel:[1,1,0] op_sel_hi:[1,0,1] neg_lo:[1,0,0]
	v_pk_mul_f32 v[148:149], v[128:129], v[96:97] op_sel:[0,0] op_sel_hi:[0,1]
	v_pk_add_f32 v[154:155], v[146:147], v[134:135]
	v_pk_fma_f32 v[144:145], v[158:159], v[88:89], v[144:145] op_sel:[1,1,0] op_sel_hi:[1,0,1] neg_lo:[1,0,0]
	v_pk_fma_f32 v[128:129], v[128:129], v[96:97], v[148:149] op_sel:[1,1,0] op_sel_hi:[1,0,1] neg_lo:[1,0,0]
	v_pk_add_f32 v[148:149], v[138:139], v[160:161]
	v_pk_add_f32 v[138:139], v[138:139], v[160:161] neg_lo:[0,1] neg_hi:[0,1]
	v_pk_add_f32 v[160:161], v[132:133], v[136:137]
	v_mov_b32_e32 v123, v157
	v_mul_f32_e32 v75, 0x38800000, v75
	v_pk_add_f32 v[152:153], v[162:163], v[150:151]
	v_pk_add_f32 v[150:151], v[162:163], v[150:151] neg_lo:[0,1] neg_hi:[0,1]
	v_pk_add_f32 v[162:163], v[154:155], v[160:161]
	v_pk_add_f32 v[154:155], v[154:155], v[160:161] neg_lo:[0,1] neg_hi:[0,1]
	v_pk_add_f32 v[134:135], v[146:147], v[134:135] neg_lo:[0,1] neg_hi:[0,1]
	v_pk_add_f32 v[146:147], v[130:131], v[140:141]
	v_pk_add_f32 v[160:161], v[144:145], v[142:143]
	v_pk_add_f32 v[130:131], v[130:131], v[140:141] neg_lo:[0,1] neg_hi:[0,1]
	v_pk_add_f32 v[140:141], v[144:145], v[142:143] neg_lo:[0,1] neg_hi:[0,1]
	v_pk_add_f32 v[144:145], v[122:123], v[126:127]
	v_pk_add_f32 v[156:157], v[124:125], v[128:129]
	v_pk_add_f32 v[124:125], v[124:125], v[128:129] neg_lo:[0,1] neg_hi:[0,1]
	v_cos_f32_e32 v128, v75
	v_sin_f32_e32 v75, v75
	v_pk_add_f32 v[164:165], v[146:147], v[160:161]
	v_pk_add_f32 v[146:147], v[146:147], v[160:161] neg_lo:[0,1] neg_hi:[0,1]
	v_pk_add_f32 v[160:161], v[144:145], v[156:157]
	v_pk_add_f32 v[144:145], v[144:145], v[156:157] neg_lo:[0,1] neg_hi:[0,1]
	s_nop 1
	v_pk_add_f32 v[142:143], v[130:131], v[140:141] op_sel:[0,1] op_sel_hi:[1,0]
	v_xor_b32_e32 v129, 0x80000000, v75
	v_pk_mul_f32 v[156:157], v[128:129], v[128:129] op_sel:[0,0] op_sel_hi:[0,1]
	v_pk_add_f32 v[130:131], v[130:131], v[140:141] op_sel:[0,1] op_sel_hi:[1,0] neg_lo:[0,1] neg_hi:[0,1]
	v_pk_fma_f32 v[156:157], v[128:129], v[128:129], v[156:157] op_sel:[1,1,0] op_sel_hi:[1,0,1] neg_lo:[1,0,0]
	v_mov_b32_e32 v141, v143
	v_pk_mul_f32 v[166:167], v[156:157], v[128:129] op_sel:[0,0] op_sel_hi:[0,1]
	v_pk_mul_f32 v[168:169], v[156:157], v[156:157] op_sel:[0,0] op_sel_hi:[0,1]
	v_mov_b32_e32 v140, v130
	v_pk_fma_f32 v[166:167], v[156:157], v[128:129], v[166:167] op_sel:[1,1,0] op_sel_hi:[1,0,1] neg_lo:[1,0,0]
	v_pk_fma_f32 v[168:169], v[156:157], v[156:157], v[168:169] op_sel:[1,1,0] op_sel_hi:[1,0,1] neg_lo:[1,0,0]
	v_mov_b32_e32 v143, v131
	v_pk_mul_f32 v[170:171], v[168:169], v[128:129] op_sel:[0,0] op_sel_hi:[0,1]
	v_pk_mul_f32 v[172:173], v[166:167], v[166:167] op_sel:[0,0] op_sel_hi:[0,1]
	v_pk_mul_f32 v[176:177], v[168:169], v[168:169] op_sel:[0,0] op_sel_hi:[0,1]
	v_pk_add_f32 v[158:159], v[148:149], v[152:153]
	v_pk_fma_f32 v[170:171], v[168:169], v[128:129], v[170:171] op_sel:[1,1,0] op_sel_hi:[1,0,1] neg_lo:[1,0,0]
	v_pk_fma_f32 v[172:173], v[166:167], v[166:167], v[172:173] op_sel:[1,1,0] op_sel_hi:[1,0,1] neg_lo:[1,0,0]
	v_pk_fma_f32 v[176:177], v[168:169], v[168:169], v[176:177] op_sel:[1,1,0] op_sel_hi:[1,0,1] neg_lo:[1,0,0]
	v_pk_add_f32 v[148:149], v[148:149], v[152:153] neg_lo:[0,1] neg_hi:[0,1]
	v_pk_mul_f32 v[180:181], v[170:171], v[170:171] op_sel:[0,0] op_sel_hi:[0,1]
	v_pk_mul_f32 v[130:131], v[142:143], v[172:173] op_sel:[0,0] op_sel_hi:[0,1]
	v_pk_mul_f32 v[182:183], v[176:177], v[166:167] op_sel:[0,0] op_sel_hi:[0,1]
	v_pk_add_f32 v[152:153], v[138:139], v[150:151] op_sel:[0,1] op_sel_hi:[1,0]
	v_pk_fma_f32 v[180:181], v[170:171], v[170:171], v[180:181] op_sel:[1,1,0] op_sel_hi:[1,0,1] neg_lo:[1,0,0]
	v_pk_fma_f32 v[130:131], v[142:143], v[172:173], v[130:131] op_sel:[1,1,0] op_sel_hi:[1,0,1] neg_lo:[1,0,0]
	v_pk_add_f32 v[138:139], v[138:139], v[150:151] op_sel:[0,1] op_sel_hi:[1,0] neg_lo:[0,1] neg_hi:[0,1]
	v_pk_mul_f32 v[142:143], v[146:147], v[180:181] op_sel:[0,0] op_sel_hi:[0,1]
	v_pk_add_f32 v[132:133], v[132:133], v[136:137] neg_lo:[0,1] neg_hi:[0,1]
	v_pk_add_f32 v[122:123], v[122:123], v[126:127] neg_lo:[0,1] neg_hi:[0,1]
	v_pk_fma_f32 v[182:183], v[176:177], v[166:167], v[182:183] op_sel:[1,1,0] op_sel_hi:[1,0,1] neg_lo:[1,0,0]
	v_pk_mul_f32 v[184:185], v[172:173], v[172:173] op_sel:[0,0] op_sel_hi:[0,1]
	v_pk_fma_f32 v[142:143], v[146:147], v[180:181], v[142:143] op_sel:[1,1,0] op_sel_hi:[1,0,1] neg_lo:[1,0,0]
	v_mov_b32_e32 v151, v139
	v_pk_mul_f32 v[146:147], v[144:145], v[182:183] op_sel:[0,0] op_sel_hi:[0,1]
	v_pk_add_f32 v[136:137], v[134:135], v[132:133] op_sel:[0,1] op_sel_hi:[1,0]
	v_pk_add_f32 v[132:133], v[134:135], v[132:133] op_sel:[0,1] op_sel_hi:[1,0] neg_lo:[0,1] neg_hi:[0,1]
	v_pk_add_f32 v[126:127], v[122:123], v[124:125] op_sel:[0,1] op_sel_hi:[1,0]
	v_pk_add_f32 v[122:123], v[122:123], v[124:125] op_sel:[0,1] op_sel_hi:[1,0] neg_lo:[0,1] neg_hi:[0,1]
	v_pk_mul_f32 v[174:175], v[168:169], v[166:167] op_sel:[0,0] op_sel_hi:[0,1]
	v_pk_mul_f32 v[178:179], v[176:177], v[128:129] op_sel:[0,0] op_sel_hi:[0,1]
	v_pk_fma_f32 v[184:185], v[172:173], v[172:173], v[184:185] op_sel:[1,1,0] op_sel_hi:[1,0,1] neg_lo:[1,0,0]
	v_pk_mul_f32 v[186:187], v[176:177], v[170:171] op_sel:[0,0] op_sel_hi:[0,1]
	v_pk_fma_f32 v[144:145], v[144:145], v[182:183], v[146:147] op_sel:[1,1,0] op_sel_hi:[1,0,1] neg_lo:[1,0,0]
	v_mov_b32_e32 v139, v153
	v_pk_mul_f32 v[146:147], v[138:139], v[184:185] op_sel:[0,0] op_sel_hi:[0,1]
	v_mov_b32_e32 v134, v132
	v_mov_b32_e32 v135, v137
	v_mov_b32_e32 v124, v122
	v_mov_b32_e32 v125, v127
	v_pk_fma_f32 v[174:175], v[168:169], v[166:167], v[174:175] op_sel:[1,1,0] op_sel_hi:[1,0,1] neg_lo:[1,0,0]
	v_pk_fma_f32 v[178:179], v[176:177], v[128:129], v[178:179] op_sel:[1,1,0] op_sel_hi:[1,0,1] neg_lo:[1,0,0]
	v_pk_fma_f32 v[186:187], v[176:177], v[170:171], v[186:187] op_sel:[1,1,0] op_sel_hi:[1,0,1] neg_lo:[1,0,0]
	v_pk_mul_f32 v[212:213], v[162:163], v[128:129] op_sel:[0,0] op_sel_hi:[0,1]
	v_mov_b32_e32 v137, v133
	v_pk_mul_f32 v[188:189], v[174:175], v[174:175] op_sel:[0,0] op_sel_hi:[0,1]
	v_pk_fma_f32 v[128:129], v[162:163], v[128:129], v[212:213] op_sel:[1,1,0] op_sel_hi:[1,0,1] neg_lo:[1,0,0]
	v_pk_mul_f32 v[162:163], v[164:165], v[156:157] op_sel:[0,0] op_sel_hi:[0,1]
	v_pk_mul_f32 v[132:133], v[136:137], v[170:171] op_sel:[0,0] op_sel_hi:[0,1]
	v_mov_b32_e32 v127, v123
	v_pk_mul_f32 v[122:123], v[126:127], v[174:175] op_sel:[0,0] op_sel_hi:[0,1]
	v_pk_fma_f32 v[138:139], v[138:139], v[184:185], v[146:147] op_sel:[1,1,0] op_sel_hi:[1,0,1] neg_lo:[1,0,0]
	v_pk_mul_f32 v[146:147], v[134:135], v[186:187] op_sel:[0,0] op_sel_hi:[0,1]
	v_mov_b32_e32 v150, v152
	v_pk_fma_f32 v[188:189], v[174:175], v[174:175], v[188:189] op_sel:[1,1,0] op_sel_hi:[1,0,1] neg_lo:[1,0,0]
	v_pk_mul_f32 v[210:211], v[176:177], v[174:175] op_sel:[0,0] op_sel_hi:[0,1]
	v_pk_fma_f32 v[156:157], v[164:165], v[156:157], v[162:163] op_sel:[1,1,0] op_sel_hi:[1,0,1] neg_lo:[1,0,0]
	v_pk_mul_f32 v[162:163], v[160:161], v[166:167] op_sel:[0,0] op_sel_hi:[0,1]
	v_pk_fma_f32 v[132:133], v[136:137], v[170:171], v[132:133] op_sel:[1,1,0] op_sel_hi:[1,0,1] neg_lo:[1,0,0]
	v_pk_fma_f32 v[122:123], v[126:127], v[174:175], v[122:123] op_sel:[1,1,0] op_sel_hi:[1,0,1] neg_lo:[1,0,0]
	v_pk_mul_f32 v[126:127], v[148:149], v[176:177] op_sel:[0,0] op_sel_hi:[0,1]
	v_pk_mul_f32 v[136:137], v[154:155], v[178:179] op_sel:[0,0] op_sel_hi:[0,1]
	v_pk_fma_f32 v[134:135], v[134:135], v[186:187], v[146:147] op_sel:[1,1,0] op_sel_hi:[1,0,1] neg_lo:[1,0,0]
	s_nop 0
	v_pk_mul_f32 v[146:147], v[140:141], v[188:189] op_sel:[0,0] op_sel_hi:[0,1]
	v_pk_fma_f32 v[210:211], v[176:177], v[174:175], v[210:211] op_sel:[1,1,0] op_sel_hi:[1,0,1] neg_lo:[1,0,0]
	v_pk_fma_f32 v[160:161], v[160:161], v[166:167], v[162:163] op_sel:[1,1,0] op_sel_hi:[1,0,1] neg_lo:[1,0,0]
	v_pk_mul_f32 v[162:163], v[150:151], v[168:169] op_sel:[0,0] op_sel_hi:[0,1]
	v_pk_fma_f32 v[126:127], v[148:149], v[176:177], v[126:127] op_sel:[1,1,0] op_sel_hi:[1,0,1] neg_lo:[1,0,0]
	v_pk_fma_f32 v[136:137], v[154:155], v[178:179], v[136:137] op_sel:[1,1,0] op_sel_hi:[1,0,1] neg_lo:[1,0,0]
	s_nop 0
	v_pk_fma_f32 v[140:141], v[140:141], v[188:189], v[146:147] op_sel:[1,1,0] op_sel_hi:[1,0,1] neg_lo:[1,0,0]
	v_pk_mul_f32 v[146:147], v[124:125], v[210:211] op_sel:[0,0] op_sel_hi:[0,1]
	v_pk_fma_f32 v[150:151], v[150:151], v[168:169], v[162:163] op_sel:[1,1,0] op_sel_hi:[1,0,1] neg_lo:[1,0,0]
	s_nop 0
	v_pk_fma_f32 v[124:125], v[124:125], v[210:211], v[146:147] op_sel:[1,1,0] op_sel_hi:[1,0,1] neg_lo:[1,0,0]
	ds_write2st64_b64 v73, v[158:159], v[128:129] offset1:17
	ds_write2st64_b64 v73, v[156:157], v[160:161] offset0:34 offset1:51
	ds_write2st64_b64 v73, v[150:151], v[132:133] offset0:68 offset1:85
	ds_write2st64_b64 v73, v[130:131], v[122:123] offset0:102 offset1:119
	ds_write_b64 v78, v[126:127]
	ds_write_b64 v80, v[136:137]
	ds_write_b64 v190, v[142:143]
	ds_write_b64 v193, v[144:145]
	ds_write_b64 v195, v[138:139]
	ds_write_b64 v197, v[134:135]
	ds_write_b64 v214, v[140:141]
	ds_write_b64 v215, v[124:125]
	v_mov_b32_e32 v73, v0
	s_waitcnt lgkmcnt(0)
	s_barrier
	s_nop 0
	v_and_b32_e32 v75, 63, v73
	v_lshlrev_b32_e32 v73, 4, v73
	v_and_or_b32 v73, v73, s12, v75
	v_cvt_f32_ubyte0_e32 v78, v75
	v_ashrrev_i32_e32 v75, 4, v73
	v_lshlrev_b32_e32 v75, 3, v75
	v_lshlrev_b32_e32 v80, 3, v73
	v_add3_u32 v75, 0, v75, v80
	v_add_u32_e32 v80, 0x800, v75
	v_add_u32_e32 v123, 0x1000, v75
	v_add_u32_e32 v190, 0x1800, v75
	ds_read2_b64 v[124:127], v75 offset1:68
	ds_read2_b64 v[128:131], v75 offset0:136 offset1:204
	ds_read2_b64 v[132:135], v80 offset0:16 offset1:84
	ds_read2_b64 v[136:139], v80 offset0:152 offset1:220
	ds_read2_b64 v[140:143], v123 offset0:32 offset1:100
	ds_read2_b64 v[144:147], v123 offset0:168 offset1:236
	ds_read2_b64 v[148:151], v190 offset0:48 offset1:116
	ds_read2_b64 v[152:155], v190 offset0:184 offset1:252
	s_waitcnt lgkmcnt(7)
	v_mov_b32_e32 v156, v124
	s_waitcnt lgkmcnt(5)
	v_mov_b32_e32 v157, v132
	s_waitcnt lgkmcnt(3)
	v_mov_b32_e32 v158, v140
	s_waitcnt lgkmcnt(1)
	v_mov_b32_e32 v159, v148
	v_pk_add_f32 v[156:157], v[156:157], v[158:159]
	v_mov_b32_e32 v158, v125
	v_mov_b32_e32 v159, v133
	v_mov_b32_e32 v160, v141
	v_mov_b32_e32 v161, v149
	v_pk_add_f32 v[158:159], v[158:159], v[160:161]
	v_pk_mov_b32 v[160:161], v[124:125], v[132:133] op_sel:[1,0]
	v_pk_mov_b32 v[162:163], v[140:141], v[148:149] op_sel:[1,0]
	v_mov_b32_e32 v125, v133
	v_pk_add_f32 v[160:161], v[160:161], v[162:163] neg_lo:[0,1] neg_hi:[0,1]
	v_mov_b32_e32 v141, v149
	v_mov_b32_e32 v132, v156
	v_mov_b32_e32 v133, v158
	v_mov_b32_e32 v158, v157
	v_pk_add_f32 v[124:125], v[124:125], v[140:141] neg_lo:[0,1] neg_hi:[0,1]
	v_pk_add_f32 v[140:141], v[132:133], v[158:159]
	v_pk_add_f32 v[132:133], v[132:133], v[158:159] neg_lo:[0,1] neg_hi:[0,1]
	v_pk_add_f32 v[156:157], v[160:161], v[160:161] op_sel_hi:[0,1] neg_lo:[0,1] neg_hi:[0,1]
	v_pk_add_f32 v[158:159], v[160:161], v[160:161] op_sel_hi:[0,1]
	v_pk_add_f32 v[160:161], v[126:127], v[142:143]
	v_pk_add_f32 v[162:163], v[134:135], v[150:151]
	v_pk_add_f32 v[126:127], v[126:127], v[142:143] neg_lo:[0,1] neg_hi:[0,1]
	v_pk_add_f32 v[134:135], v[134:135], v[150:151] neg_lo:[0,1] neg_hi:[0,1]
	s_waitcnt lgkmcnt(0)
	v_pk_add_f32 v[150:151], v[136:137], v[152:153]
	v_pk_add_f32 v[142:143], v[126:127], v[134:135] op_sel:[0,1] op_sel_hi:[1,0]
	v_pk_add_f32 v[126:127], v[126:127], v[134:135] op_sel:[0,1] op_sel_hi:[1,0] neg_lo:[0,1] neg_hi:[0,1]
	v_mov_b32_e32 v134, v142
	v_mov_b32_e32 v135, v127
	v_mov_b32_e32 v127, v143
	v_pk_add_f32 v[142:143], v[128:129], v[144:145]
	v_pk_add_f32 v[128:129], v[128:129], v[144:145] neg_lo:[0,1] neg_hi:[0,1]
	v_pk_add_f32 v[136:137], v[136:137], v[152:153] neg_lo:[0,1] neg_hi:[0,1]
	v_pk_add_f32 v[164:165], v[160:161], v[162:163]
	v_pk_add_f32 v[144:145], v[128:129], v[136:137] op_sel:[0,1] op_sel_hi:[1,0]
	v_pk_add_f32 v[128:129], v[128:129], v[136:137] op_sel:[0,1] op_sel_hi:[1,0] neg_lo:[0,1] neg_hi:[0,1]
	v_pk_add_f32 v[160:161], v[160:161], v[162:163] neg_lo:[0,1] neg_hi:[0,1]
	v_pk_add_f32 v[162:163], v[142:143], v[150:151]
	v_pk_add_f32 v[142:143], v[142:143], v[150:151] neg_lo:[0,1] neg_hi:[0,1]
	v_mov_b32_e32 v136, v144
	v_mov_b32_e32 v137, v129
	v_mov_b32_e32 v129, v145
	v_pk_add_f32 v[144:145], v[130:131], v[146:147]
	v_pk_add_f32 v[150:151], v[138:139], v[154:155]
	v_pk_add_f32 v[130:131], v[130:131], v[146:147] neg_lo:[0,1] neg_hi:[0,1]
	v_pk_add_f32 v[138:139], v[138:139], v[154:155] neg_lo:[0,1] neg_hi:[0,1]
	v_pk_add_f32 v[152:153], v[144:145], v[150:151]
	v_pk_add_f32 v[144:145], v[144:145], v[150:151] neg_lo:[0,1] neg_hi:[0,1]
	v_pk_add_f32 v[146:147], v[130:131], v[138:139] op_sel:[0,1] op_sel_hi:[1,0]
	v_pk_add_f32 v[130:131], v[130:131], v[138:139] op_sel:[0,1] op_sel_hi:[1,0] neg_lo:[0,1] neg_hi:[0,1]
	v_pk_mul_f32 v[150:151], v[142:143], v[94:95] op_sel:[0,0] op_sel_hi:[0,1]
	v_mov_b32_e32 v138, v146
	v_mov_b32_e32 v139, v131
	v_mov_b32_e32 v131, v147
	v_pk_mul_f32 v[146:147], v[134:135], v[90:91] op_sel:[0,0] op_sel_hi:[0,1]
	v_pk_fma_f32 v[142:143], v[142:143], v[94:95], v[150:151] op_sel:[1,1,0] op_sel_hi:[1,0,1] neg_lo:[1,0,0]
	v_pk_mul_f32 v[150:151], v[144:145], v[92:93] op_sel:[0,0] op_sel_hi:[0,1]
	v_mul_f32_e32 v78, 0x3a800000, v78
	v_pk_fma_f32 v[134:135], v[134:135], v[90:91], v[146:147] op_sel:[1,1,0] op_sel_hi:[1,0,1] neg_lo:[1,0,0]
	v_pk_mul_f32 v[146:147], v[136:137], v[88:89] op_sel:[0,0] op_sel_hi:[0,1]
	v_pk_fma_f32 v[144:145], v[144:145], v[92:93], v[150:151] op_sel:[1,1,0] op_sel_hi:[1,0,1] neg_lo:[1,0,0]
	v_pk_mul_f32 v[150:151], v[126:127], v[86:87] op_sel:[0,0] op_sel_hi:[0,1]
	v_pk_add_f32 v[148:149], v[124:125], v[124:125] op_sel:[0,1] op_sel_hi:[1,0]
	v_pk_fma_f32 v[136:137], v[136:137], v[88:89], v[146:147] op_sel:[1,1,0] op_sel_hi:[1,0,1] neg_lo:[1,0,0]
	v_pk_mul_f32 v[146:147], v[138:139], v[86:87] op_sel:[0,0] op_sel_hi:[0,1]
	v_pk_fma_f32 v[126:127], v[126:127], v[86:87], v[150:151] op_sel:[1,1,0] op_sel_hi:[1,0,1] neg_lo:[1,0,0]
	v_pk_mul_f32 v[150:151], v[128:129], v[92:93] op_sel:[0,0] op_sel_hi:[0,1]
	v_cos_f32_e32 v122, v78
	v_sin_f32_e32 v78, v78
	v_pk_add_f32 v[124:125], v[124:125], v[124:125] op_sel:[0,1] op_sel_hi:[1,0] neg_lo:[0,1] neg_hi:[0,1]
	v_pk_fma_f32 v[138:139], v[138:139], v[86:87], v[146:147] op_sel:[1,1,0] op_sel_hi:[1,0,1] neg_lo:[1,0,0]
	v_pk_mul_f32 v[146:147], v[160:161], v[88:89] op_sel:[0,0] op_sel_hi:[0,1]
	v_pk_fma_f32 v[128:129], v[128:129], v[92:93], v[150:151] op_sel:[1,1,0] op_sel_hi:[1,0,1] neg_lo:[1,0,0]
	v_pk_mul_f32 v[150:151], v[130:131], v[96:97] op_sel:[0,0] op_sel_hi:[0,1]
	v_mov_b32_e32 v149, v157
	v_pk_fma_f32 v[146:147], v[160:161], v[88:89], v[146:147] op_sel:[1,1,0] op_sel_hi:[1,0,1] neg_lo:[1,0,0]
	v_pk_fma_f32 v[130:131], v[130:131], v[96:97], v[150:151] op_sel:[1,1,0] op_sel_hi:[1,0,1] neg_lo:[1,0,0]
	v_pk_add_f32 v[150:151], v[140:141], v[162:163]
	v_pk_add_f32 v[140:141], v[140:141], v[162:163] neg_lo:[0,1] neg_hi:[0,1]
	v_pk_add_f32 v[156:157], v[148:149], v[136:137]
	v_pk_add_f32 v[162:163], v[134:135], v[138:139]
	v_mov_b32_e32 v125, v159
	v_pk_add_f32 v[154:155], v[164:165], v[152:153]
	v_pk_add_f32 v[152:153], v[164:165], v[152:153] neg_lo:[0,1] neg_hi:[0,1]
	v_pk_add_f32 v[164:165], v[156:157], v[162:163]
	v_pk_add_f32 v[156:157], v[156:157], v[162:163] neg_lo:[0,1] neg_hi:[0,1]
	v_pk_add_f32 v[136:137], v[148:149], v[136:137] neg_lo:[0,1] neg_hi:[0,1]
	v_pk_add_f32 v[148:149], v[132:133], v[142:143]
	v_pk_add_f32 v[162:163], v[146:147], v[144:145]
	v_pk_add_f32 v[132:133], v[132:133], v[142:143] neg_lo:[0,1] neg_hi:[0,1]
	v_pk_add_f32 v[142:143], v[146:147], v[144:145] neg_lo:[0,1] neg_hi:[0,1]
	v_pk_add_f32 v[146:147], v[124:125], v[128:129]
	v_pk_add_f32 v[158:159], v[126:127], v[130:131]
	v_pk_add_f32 v[124:125], v[124:125], v[128:129] neg_lo:[0,1] neg_hi:[0,1]
	v_pk_add_f32 v[126:127], v[126:127], v[130:131] neg_lo:[0,1] neg_hi:[0,1]
	v_mov_b32_e32 v130, v122
	v_pk_add_f32 v[128:129], v[124:125], v[126:127] op_sel:[0,1] op_sel_hi:[1,0]
	v_pk_add_f32 v[124:125], v[124:125], v[126:127] op_sel:[0,1] op_sel_hi:[1,0] neg_lo:[0,1] neg_hi:[0,1]
	v_pk_add_f32 v[166:167], v[148:149], v[162:163]
	v_mov_b32_e32 v126, v124
	v_mov_b32_e32 v124, v78
	v_pk_add_f32 v[148:149], v[148:149], v[162:163] neg_lo:[0,1] neg_hi:[0,1]
	v_pk_add_f32 v[162:163], v[146:147], v[158:159]
	v_pk_add_f32 v[146:147], v[146:147], v[158:159] neg_lo:[0,1] neg_hi:[0,1]
	s_nop 1
	v_pk_add_f32 v[144:145], v[132:133], v[142:143] op_sel:[0,1] op_sel_hi:[1,0]
	v_xor_b32_e32 v131, 0x80000000, v124
	v_pk_mul_f32 v[158:159], v[130:131], v[130:131] op_sel:[0,0] op_sel_hi:[0,1]
	v_pk_add_f32 v[132:133], v[132:133], v[142:143] op_sel:[0,1] op_sel_hi:[1,0] neg_lo:[0,1] neg_hi:[0,1]
	v_pk_fma_f32 v[158:159], v[130:131], v[130:131], v[158:159] op_sel:[1,1,0] op_sel_hi:[1,0,1] neg_lo:[1,0,0]
	v_mov_b32_e32 v143, v145
	v_pk_mul_f32 v[168:169], v[158:159], v[130:131] op_sel:[0,0] op_sel_hi:[0,1]
	v_pk_mul_f32 v[170:171], v[158:159], v[158:159] op_sel:[0,0] op_sel_hi:[0,1]
	v_mov_b32_e32 v142, v132
	v_pk_fma_f32 v[168:169], v[158:159], v[130:131], v[168:169] op_sel:[1,1,0] op_sel_hi:[1,0,1] neg_lo:[1,0,0]
	v_pk_fma_f32 v[170:171], v[158:159], v[158:159], v[170:171] op_sel:[1,1,0] op_sel_hi:[1,0,1] neg_lo:[1,0,0]
	v_mov_b32_e32 v145, v133
	v_pk_mul_f32 v[172:173], v[170:171], v[130:131] op_sel:[0,0] op_sel_hi:[0,1]
	v_pk_mul_f32 v[174:175], v[168:169], v[168:169] op_sel:[0,0] op_sel_hi:[0,1]
	v_pk_mul_f32 v[178:179], v[170:171], v[170:171] op_sel:[0,0] op_sel_hi:[0,1]
	v_pk_add_f32 v[160:161], v[150:151], v[154:155]
	v_pk_fma_f32 v[172:173], v[170:171], v[130:131], v[172:173] op_sel:[1,1,0] op_sel_hi:[1,0,1] neg_lo:[1,0,0]
	v_pk_fma_f32 v[174:175], v[168:169], v[168:169], v[174:175] op_sel:[1,1,0] op_sel_hi:[1,0,1] neg_lo:[1,0,0]
	v_pk_fma_f32 v[178:179], v[170:171], v[170:171], v[178:179] op_sel:[1,1,0] op_sel_hi:[1,0,1] neg_lo:[1,0,0]
	v_pk_add_f32 v[150:151], v[150:151], v[154:155] neg_lo:[0,1] neg_hi:[0,1]
	v_pk_mul_f32 v[182:183], v[172:173], v[172:173] op_sel:[0,0] op_sel_hi:[0,1]
	v_pk_mul_f32 v[132:133], v[144:145], v[174:175] op_sel:[0,0] op_sel_hi:[0,1]
	v_pk_mul_f32 v[184:185], v[178:179], v[168:169] op_sel:[0,0] op_sel_hi:[0,1]
	v_pk_add_f32 v[154:155], v[140:141], v[152:153] op_sel:[0,1] op_sel_hi:[1,0]
	v_pk_fma_f32 v[182:183], v[172:173], v[172:173], v[182:183] op_sel:[1,1,0] op_sel_hi:[1,0,1] neg_lo:[1,0,0]
	v_pk_fma_f32 v[132:133], v[144:145], v[174:175], v[132:133] op_sel:[1,1,0] op_sel_hi:[1,0,1] neg_lo:[1,0,0]
	v_pk_add_f32 v[140:141], v[140:141], v[152:153] op_sel:[0,1] op_sel_hi:[1,0] neg_lo:[0,1] neg_hi:[0,1]
	v_pk_mul_f32 v[144:145], v[148:149], v[182:183] op_sel:[0,0] op_sel_hi:[0,1]
	v_pk_add_f32 v[134:135], v[134:135], v[138:139] neg_lo:[0,1] neg_hi:[0,1]
	v_pk_fma_f32 v[184:185], v[178:179], v[168:169], v[184:185] op_sel:[1,1,0] op_sel_hi:[1,0,1] neg_lo:[1,0,0]
	v_pk_mul_f32 v[186:187], v[174:175], v[174:175] op_sel:[0,0] op_sel_hi:[0,1]
	v_pk_fma_f32 v[144:145], v[148:149], v[182:183], v[144:145] op_sel:[1,1,0] op_sel_hi:[1,0,1] neg_lo:[1,0,0]
	v_mov_b32_e32 v153, v141
	v_pk_mul_f32 v[148:149], v[146:147], v[184:185] op_sel:[0,0] op_sel_hi:[0,1]
	v_pk_add_f32 v[138:139], v[136:137], v[134:135] op_sel:[0,1] op_sel_hi:[1,0]
	v_pk_add_f32 v[134:135], v[136:137], v[134:135] op_sel:[0,1] op_sel_hi:[1,0] neg_lo:[0,1] neg_hi:[0,1]
	v_pk_mul_f32 v[176:177], v[170:171], v[168:169] op_sel:[0,0] op_sel_hi:[0,1]
	v_pk_mul_f32 v[180:181], v[178:179], v[130:131] op_sel:[0,0] op_sel_hi:[0,1]
	v_pk_fma_f32 v[186:187], v[174:175], v[174:175], v[186:187] op_sel:[1,1,0] op_sel_hi:[1,0,1] neg_lo:[1,0,0]
	v_pk_mul_f32 v[188:189], v[178:179], v[172:173] op_sel:[0,0] op_sel_hi:[0,1]
	v_pk_fma_f32 v[146:147], v[146:147], v[184:185], v[148:149] op_sel:[1,1,0] op_sel_hi:[1,0,1] neg_lo:[1,0,0]
	v_mov_b32_e32 v141, v155
	v_pk_mul_f32 v[148:149], v[140:141], v[186:187] op_sel:[0,0] op_sel_hi:[0,1]
	v_mov_b32_e32 v136, v134
	v_mov_b32_e32 v137, v139
	v_mov_b32_e32 v127, v129
	v_pk_fma_f32 v[176:177], v[170:171], v[168:169], v[176:177] op_sel:[1,1,0] op_sel_hi:[1,0,1] neg_lo:[1,0,0]
	v_pk_fma_f32 v[180:181], v[178:179], v[130:131], v[180:181] op_sel:[1,1,0] op_sel_hi:[1,0,1] neg_lo:[1,0,0]
	v_pk_fma_f32 v[188:189], v[178:179], v[172:173], v[188:189] op_sel:[1,1,0] op_sel_hi:[1,0,1] neg_lo:[1,0,0]
	v_pk_mul_f32 v[214:215], v[164:165], v[130:131] op_sel:[0,0] op_sel_hi:[0,1]
	v_mov_b32_e32 v139, v135
	v_pk_mul_f32 v[210:211], v[176:177], v[176:177] op_sel:[0,0] op_sel_hi:[0,1]
	v_pk_fma_f32 v[130:131], v[164:165], v[130:131], v[214:215] op_sel:[1,1,0] op_sel_hi:[1,0,1] neg_lo:[1,0,0]
	v_pk_mul_f32 v[164:165], v[166:167], v[158:159] op_sel:[0,0] op_sel_hi:[0,1]
	v_pk_mul_f32 v[134:135], v[138:139], v[172:173] op_sel:[0,0] op_sel_hi:[0,1]
	v_mov_b32_e32 v129, v125
	v_pk_mul_f32 v[124:125], v[128:129], v[176:177] op_sel:[0,0] op_sel_hi:[0,1]
	v_pk_fma_f32 v[140:141], v[140:141], v[186:187], v[148:149] op_sel:[1,1,0] op_sel_hi:[1,0,1] neg_lo:[1,0,0]
	v_pk_mul_f32 v[148:149], v[136:137], v[188:189] op_sel:[0,0] op_sel_hi:[0,1]
	v_mov_b32_e32 v152, v154
	v_pk_fma_f32 v[210:211], v[176:177], v[176:177], v[210:211] op_sel:[1,1,0] op_sel_hi:[1,0,1] neg_lo:[1,0,0]
	v_pk_mul_f32 v[212:213], v[178:179], v[176:177] op_sel:[0,0] op_sel_hi:[0,1]
	v_pk_fma_f32 v[158:159], v[166:167], v[158:159], v[164:165] op_sel:[1,1,0] op_sel_hi:[1,0,1] neg_lo:[1,0,0]
	v_pk_mul_f32 v[164:165], v[162:163], v[168:169] op_sel:[0,0] op_sel_hi:[0,1]
	v_pk_fma_f32 v[134:135], v[138:139], v[172:173], v[134:135] op_sel:[1,1,0] op_sel_hi:[1,0,1] neg_lo:[1,0,0]
	v_pk_fma_f32 v[124:125], v[128:129], v[176:177], v[124:125] op_sel:[1,1,0] op_sel_hi:[1,0,1] neg_lo:[1,0,0]
	v_pk_mul_f32 v[128:129], v[150:151], v[178:179] op_sel:[0,0] op_sel_hi:[0,1]
	v_pk_mul_f32 v[138:139], v[156:157], v[180:181] op_sel:[0,0] op_sel_hi:[0,1]
	v_pk_fma_f32 v[136:137], v[136:137], v[188:189], v[148:149] op_sel:[1,1,0] op_sel_hi:[1,0,1] neg_lo:[1,0,0]
	s_nop 0
	v_pk_mul_f32 v[148:149], v[142:143], v[210:211] op_sel:[0,0] op_sel_hi:[0,1]
	v_add_u32_e32 v73, 0x2000, v73
	v_pk_fma_f32 v[212:213], v[178:179], v[176:177], v[212:213] op_sel:[1,1,0] op_sel_hi:[1,0,1] neg_lo:[1,0,0]
	v_pk_fma_f32 v[162:163], v[162:163], v[168:169], v[164:165] op_sel:[1,1,0] op_sel_hi:[1,0,1] neg_lo:[1,0,0]
	v_pk_mul_f32 v[164:165], v[152:153], v[170:171] op_sel:[0,0] op_sel_hi:[0,1]
	v_pk_fma_f32 v[128:129], v[150:151], v[178:179], v[128:129] op_sel:[1,1,0] op_sel_hi:[1,0,1] neg_lo:[1,0,0]
	v_pk_fma_f32 v[138:139], v[156:157], v[180:181], v[138:139] op_sel:[1,1,0] op_sel_hi:[1,0,1] neg_lo:[1,0,0]
	v_pk_fma_f32 v[142:143], v[142:143], v[210:211], v[148:149] op_sel:[1,1,0] op_sel_hi:[1,0,1] neg_lo:[1,0,0]
	s_nop 0
	v_pk_mul_f32 v[148:149], v[126:127], v[212:213] op_sel:[0,0] op_sel_hi:[0,1]
	v_pk_fma_f32 v[152:153], v[152:153], v[170:171], v[164:165] op_sel:[1,1,0] op_sel_hi:[1,0,1] neg_lo:[1,0,0]
	s_nop 0
	v_pk_fma_f32 v[126:127], v[126:127], v[212:213], v[148:149] op_sel:[1,1,0] op_sel_hi:[1,0,1] neg_lo:[1,0,0]
	ds_write2_b64 v75, v[160:161], v[130:131] offset1:68
	ds_write2_b64 v75, v[158:159], v[162:163] offset0:136 offset1:204
	ds_write2_b64 v80, v[152:153], v[134:135] offset0:16 offset1:84
	ds_write2_b64 v80, v[132:133], v[124:125] offset0:152 offset1:220
	ds_write2_b64 v123, v[128:129], v[138:139] offset0:32 offset1:100
	ds_write2_b64 v123, v[144:145], v[146:147] offset0:168 offset1:236
	ds_write2_b64 v190, v[140:141], v[136:137] offset0:48 offset1:116
	ds_write2_b64 v190, v[142:143], v[126:127] offset0:184 offset1:252
	v_ashrrev_i32_e32 v75, 4, v73
	v_lshlrev_b32_e32 v75, 3, v75
	v_lshlrev_b32_e32 v73, 3, v73
	v_add3_u32 v73, 0, v75, v73
	v_add_u32_e32 v75, 0x800, v73
	v_add_u32_e32 v80, 0x1000, v73
	v_add_u32_e32 v190, 0x1800, v73
	ds_read2_b64 v[124:127], v73 offset1:68
	ds_read2_b64 v[128:131], v73 offset0:136 offset1:204
	ds_read2_b64 v[132:135], v75 offset0:16 offset1:84
	ds_read2_b64 v[136:139], v75 offset0:152 offset1:220
	ds_read2_b64 v[140:143], v80 offset0:32 offset1:100
	ds_read2_b64 v[144:147], v80 offset0:168 offset1:236
	ds_read2_b64 v[148:151], v190 offset0:48 offset1:116
	ds_read2_b64 v[152:155], v190 offset0:184 offset1:252
	s_waitcnt lgkmcnt(7)
	v_mov_b32_e32 v156, v124
	s_waitcnt lgkmcnt(5)
	v_mov_b32_e32 v157, v132
	s_waitcnt lgkmcnt(3)
	v_mov_b32_e32 v158, v140
	s_waitcnt lgkmcnt(1)
	v_mov_b32_e32 v159, v148
	v_pk_add_f32 v[156:157], v[156:157], v[158:159]
	v_mov_b32_e32 v158, v125
	v_mov_b32_e32 v159, v133
	v_mov_b32_e32 v160, v141
	v_mov_b32_e32 v161, v149
	v_pk_add_f32 v[158:159], v[158:159], v[160:161]
	v_pk_mov_b32 v[160:161], v[124:125], v[132:133] op_sel:[1,0]
	v_pk_mov_b32 v[162:163], v[140:141], v[148:149] op_sel:[1,0]
	v_mov_b32_e32 v125, v133
	v_pk_add_f32 v[160:161], v[160:161], v[162:163] neg_lo:[0,1] neg_hi:[0,1]
	v_mov_b32_e32 v141, v149
	v_mov_b32_e32 v132, v156
	v_mov_b32_e32 v133, v158
	v_mov_b32_e32 v158, v157
	v_pk_add_f32 v[124:125], v[124:125], v[140:141] neg_lo:[0,1] neg_hi:[0,1]
	v_pk_add_f32 v[140:141], v[132:133], v[158:159]
	v_pk_add_f32 v[132:133], v[132:133], v[158:159] neg_lo:[0,1] neg_hi:[0,1]
	v_pk_add_f32 v[156:157], v[160:161], v[160:161] op_sel_hi:[0,1] neg_lo:[0,1] neg_hi:[0,1]
	v_pk_add_f32 v[158:159], v[160:161], v[160:161] op_sel_hi:[0,1]
	v_pk_add_f32 v[160:161], v[126:127], v[142:143]
	v_pk_add_f32 v[162:163], v[134:135], v[150:151]
	v_pk_add_f32 v[126:127], v[126:127], v[142:143] neg_lo:[0,1] neg_hi:[0,1]
	v_pk_add_f32 v[134:135], v[134:135], v[150:151] neg_lo:[0,1] neg_hi:[0,1]
	s_waitcnt lgkmcnt(0)
	v_pk_add_f32 v[150:151], v[136:137], v[152:153]
	v_pk_add_f32 v[142:143], v[126:127], v[134:135] op_sel:[0,1] op_sel_hi:[1,0]
	v_pk_add_f32 v[126:127], v[126:127], v[134:135] op_sel:[0,1] op_sel_hi:[1,0] neg_lo:[0,1] neg_hi:[0,1]
	v_mov_b32_e32 v134, v142
	v_mov_b32_e32 v135, v127
	v_mov_b32_e32 v127, v143
	v_pk_add_f32 v[142:143], v[128:129], v[144:145]
	v_pk_add_f32 v[128:129], v[128:129], v[144:145] neg_lo:[0,1] neg_hi:[0,1]
	v_pk_add_f32 v[136:137], v[136:137], v[152:153] neg_lo:[0,1] neg_hi:[0,1]
	v_pk_add_f32 v[164:165], v[160:161], v[162:163]
	v_pk_add_f32 v[144:145], v[128:129], v[136:137] op_sel:[0,1] op_sel_hi:[1,0]
	v_pk_add_f32 v[128:129], v[128:129], v[136:137] op_sel:[0,1] op_sel_hi:[1,0] neg_lo:[0,1] neg_hi:[0,1]
	v_pk_add_f32 v[160:161], v[160:161], v[162:163] neg_lo:[0,1] neg_hi:[0,1]
	v_pk_add_f32 v[162:163], v[142:143], v[150:151]
	v_pk_add_f32 v[142:143], v[142:143], v[150:151] neg_lo:[0,1] neg_hi:[0,1]
	v_mov_b32_e32 v136, v144
	v_mov_b32_e32 v137, v129
	v_mov_b32_e32 v129, v145
	v_pk_add_f32 v[144:145], v[130:131], v[146:147]
	v_pk_add_f32 v[150:151], v[138:139], v[154:155]
	v_pk_add_f32 v[130:131], v[130:131], v[146:147] neg_lo:[0,1] neg_hi:[0,1]
	v_pk_add_f32 v[138:139], v[138:139], v[154:155] neg_lo:[0,1] neg_hi:[0,1]
	v_pk_add_f32 v[152:153], v[144:145], v[150:151]
	v_pk_add_f32 v[144:145], v[144:145], v[150:151] neg_lo:[0,1] neg_hi:[0,1]
	v_pk_add_f32 v[146:147], v[130:131], v[138:139] op_sel:[0,1] op_sel_hi:[1,0]
	v_pk_add_f32 v[130:131], v[130:131], v[138:139] op_sel:[0,1] op_sel_hi:[1,0] neg_lo:[0,1] neg_hi:[0,1]
	v_pk_mul_f32 v[150:151], v[142:143], v[94:95] op_sel:[0,0] op_sel_hi:[0,1]
	v_mov_b32_e32 v138, v146
	v_mov_b32_e32 v139, v131
	v_mov_b32_e32 v131, v147
	v_pk_mul_f32 v[146:147], v[134:135], v[90:91] op_sel:[0,0] op_sel_hi:[0,1]
	v_pk_fma_f32 v[142:143], v[142:143], v[94:95], v[150:151] op_sel:[1,1,0] op_sel_hi:[1,0,1] neg_lo:[1,0,0]
	v_pk_mul_f32 v[150:151], v[144:145], v[92:93] op_sel:[0,0] op_sel_hi:[0,1]
	v_pk_add_f32 v[148:149], v[124:125], v[124:125] op_sel:[0,1] op_sel_hi:[1,0]
	v_pk_fma_f32 v[134:135], v[134:135], v[90:91], v[146:147] op_sel:[1,1,0] op_sel_hi:[1,0,1] neg_lo:[1,0,0]
	v_pk_mul_f32 v[146:147], v[136:137], v[88:89] op_sel:[0,0] op_sel_hi:[0,1]
	v_pk_fma_f32 v[144:145], v[144:145], v[92:93], v[150:151] op_sel:[1,1,0] op_sel_hi:[1,0,1] neg_lo:[1,0,0]
	v_pk_mul_f32 v[150:151], v[126:127], v[86:87] op_sel:[0,0] op_sel_hi:[0,1]
	v_pk_add_f32 v[124:125], v[124:125], v[124:125] op_sel:[0,1] op_sel_hi:[1,0] neg_lo:[0,1] neg_hi:[0,1]
	v_pk_fma_f32 v[136:137], v[136:137], v[88:89], v[146:147] op_sel:[1,1,0] op_sel_hi:[1,0,1] neg_lo:[1,0,0]
	v_pk_mul_f32 v[146:147], v[138:139], v[86:87] op_sel:[0,0] op_sel_hi:[0,1]
	v_pk_fma_f32 v[126:127], v[126:127], v[86:87], v[150:151] op_sel:[1,1,0] op_sel_hi:[1,0,1] neg_lo:[1,0,0]
	v_pk_mul_f32 v[150:151], v[128:129], v[92:93] op_sel:[0,0] op_sel_hi:[0,1]
	v_mov_b32_e32 v149, v157
	v_pk_fma_f32 v[138:139], v[138:139], v[86:87], v[146:147] op_sel:[1,1,0] op_sel_hi:[1,0,1] neg_lo:[1,0,0]
	v_pk_mul_f32 v[146:147], v[160:161], v[88:89] op_sel:[0,0] op_sel_hi:[0,1]
	v_pk_fma_f32 v[128:129], v[128:129], v[92:93], v[150:151] op_sel:[1,1,0] op_sel_hi:[1,0,1] neg_lo:[1,0,0]
	v_pk_mul_f32 v[150:151], v[130:131], v[96:97] op_sel:[0,0] op_sel_hi:[0,1]
	v_pk_add_f32 v[156:157], v[148:149], v[136:137]
	v_pk_fma_f32 v[146:147], v[160:161], v[88:89], v[146:147] op_sel:[1,1,0] op_sel_hi:[1,0,1] neg_lo:[1,0,0]
	v_pk_fma_f32 v[130:131], v[130:131], v[96:97], v[150:151] op_sel:[1,1,0] op_sel_hi:[1,0,1] neg_lo:[1,0,0]
	v_pk_add_f32 v[150:151], v[140:141], v[162:163]
	v_pk_add_f32 v[140:141], v[140:141], v[162:163] neg_lo:[0,1] neg_hi:[0,1]
	v_pk_add_f32 v[162:163], v[134:135], v[138:139]
	v_mov_b32_e32 v125, v159
	v_pk_add_f32 v[154:155], v[164:165], v[152:153]
	v_pk_add_f32 v[152:153], v[164:165], v[152:153] neg_lo:[0,1] neg_hi:[0,1]
	v_pk_add_f32 v[164:165], v[156:157], v[162:163]
	v_pk_add_f32 v[156:157], v[156:157], v[162:163] neg_lo:[0,1] neg_hi:[0,1]
	v_pk_add_f32 v[136:137], v[148:149], v[136:137] neg_lo:[0,1] neg_hi:[0,1]
	v_pk_add_f32 v[148:149], v[132:133], v[142:143]
	v_pk_add_f32 v[162:163], v[146:147], v[144:145]
	v_pk_add_f32 v[132:133], v[132:133], v[142:143] neg_lo:[0,1] neg_hi:[0,1]
	v_pk_add_f32 v[142:143], v[146:147], v[144:145] neg_lo:[0,1] neg_hi:[0,1]
	v_pk_add_f32 v[146:147], v[124:125], v[128:129]
	v_pk_add_f32 v[158:159], v[126:127], v[130:131]
	v_pk_add_f32 v[126:127], v[126:127], v[130:131] neg_lo:[0,1] neg_hi:[0,1]
	s_nop 1
	v_pk_add_f32 v[166:167], v[148:149], v[162:163]
	v_xor_b32_e32 v123, 0x80000000, v78
	v_pk_mul_f32 v[130:131], v[122:123], v[122:123] op_sel:[0,0] op_sel_hi:[0,1]
	v_pk_add_f32 v[148:149], v[148:149], v[162:163] neg_lo:[0,1] neg_hi:[0,1]
	v_pk_add_f32 v[162:163], v[146:147], v[158:159]
	v_pk_add_f32 v[146:147], v[146:147], v[158:159] neg_lo:[0,1] neg_hi:[0,1]
	v_pk_fma_f32 v[130:131], v[122:123], v[122:123], v[130:131] op_sel:[1,1,0] op_sel_hi:[1,0,1] neg_lo:[1,0,0]
	v_pk_add_f32 v[144:145], v[132:133], v[142:143] op_sel:[0,1] op_sel_hi:[1,0]
	v_pk_mul_f32 v[158:159], v[130:131], v[122:123] op_sel:[0,0] op_sel_hi:[0,1]
	v_pk_mul_f32 v[168:169], v[130:131], v[130:131] op_sel:[0,0] op_sel_hi:[0,1]
	v_pk_add_f32 v[132:133], v[132:133], v[142:143] op_sel:[0,1] op_sel_hi:[1,0] neg_lo:[0,1] neg_hi:[0,1]
	v_pk_fma_f32 v[158:159], v[130:131], v[122:123], v[158:159] op_sel:[1,1,0] op_sel_hi:[1,0,1] neg_lo:[1,0,0]
	v_pk_fma_f32 v[168:169], v[130:131], v[130:131], v[168:169] op_sel:[1,1,0] op_sel_hi:[1,0,1] neg_lo:[1,0,0]
	v_mov_b32_e32 v143, v145
	v_pk_mul_f32 v[170:171], v[168:169], v[122:123] op_sel:[0,0] op_sel_hi:[0,1]
	v_pk_mul_f32 v[172:173], v[158:159], v[158:159] op_sel:[0,0] op_sel_hi:[0,1]
	v_mov_b32_e32 v142, v132
	v_pk_fma_f32 v[170:171], v[168:169], v[122:123], v[170:171] op_sel:[1,1,0] op_sel_hi:[1,0,1] neg_lo:[1,0,0]
	v_pk_fma_f32 v[172:173], v[158:159], v[158:159], v[172:173] op_sel:[1,1,0] op_sel_hi:[1,0,1] neg_lo:[1,0,0]
	v_pk_mul_f32 v[176:177], v[168:169], v[168:169] op_sel:[0,0] op_sel_hi:[0,1]
	v_mov_b32_e32 v145, v133
	v_pk_mul_f32 v[180:181], v[170:171], v[170:171] op_sel:[0,0] op_sel_hi:[0,1]
	v_pk_mul_f32 v[132:133], v[144:145], v[172:173] op_sel:[0,0] op_sel_hi:[0,1]
	v_pk_fma_f32 v[176:177], v[168:169], v[168:169], v[176:177] op_sel:[1,1,0] op_sel_hi:[1,0,1] neg_lo:[1,0,0]
	v_pk_add_f32 v[160:161], v[150:151], v[154:155]
	v_pk_fma_f32 v[180:181], v[170:171], v[170:171], v[180:181] op_sel:[1,1,0] op_sel_hi:[1,0,1] neg_lo:[1,0,0]
	v_pk_mul_f32 v[182:183], v[176:177], v[158:159] op_sel:[0,0] op_sel_hi:[0,1]
	v_pk_fma_f32 v[132:133], v[144:145], v[172:173], v[132:133] op_sel:[1,1,0] op_sel_hi:[1,0,1] neg_lo:[1,0,0]
	v_pk_add_f32 v[150:151], v[150:151], v[154:155] neg_lo:[0,1] neg_hi:[0,1]
	v_pk_mul_f32 v[144:145], v[148:149], v[180:181] op_sel:[0,0] op_sel_hi:[0,1]
	v_pk_add_f32 v[154:155], v[140:141], v[152:153] op_sel:[0,1] op_sel_hi:[1,0]
	v_pk_add_f32 v[140:141], v[140:141], v[152:153] op_sel:[0,1] op_sel_hi:[1,0] neg_lo:[0,1] neg_hi:[0,1]
	v_pk_add_f32 v[134:135], v[134:135], v[138:139] neg_lo:[0,1] neg_hi:[0,1]
	v_pk_add_f32 v[124:125], v[124:125], v[128:129] neg_lo:[0,1] neg_hi:[0,1]
	v_pk_fma_f32 v[182:183], v[176:177], v[158:159], v[182:183] op_sel:[1,1,0] op_sel_hi:[1,0,1] neg_lo:[1,0,0]
	v_pk_mul_f32 v[184:185], v[172:173], v[172:173] op_sel:[0,0] op_sel_hi:[0,1]
	v_pk_fma_f32 v[144:145], v[148:149], v[180:181], v[144:145] op_sel:[1,1,0] op_sel_hi:[1,0,1] neg_lo:[1,0,0]
	v_mov_b32_e32 v153, v141
	v_pk_mul_f32 v[148:149], v[146:147], v[182:183] op_sel:[0,0] op_sel_hi:[0,1]
	v_pk_add_f32 v[138:139], v[136:137], v[134:135] op_sel:[0,1] op_sel_hi:[1,0]
	v_pk_add_f32 v[134:135], v[136:137], v[134:135] op_sel:[0,1] op_sel_hi:[1,0] neg_lo:[0,1] neg_hi:[0,1]
	v_pk_add_f32 v[128:129], v[124:125], v[126:127] op_sel:[0,1] op_sel_hi:[1,0]
	v_pk_add_f32 v[124:125], v[124:125], v[126:127] op_sel:[0,1] op_sel_hi:[1,0] neg_lo:[0,1] neg_hi:[0,1]
	v_pk_mul_f32 v[174:175], v[168:169], v[158:159] op_sel:[0,0] op_sel_hi:[0,1]
	v_pk_fma_f32 v[184:185], v[172:173], v[172:173], v[184:185] op_sel:[1,1,0] op_sel_hi:[1,0,1] neg_lo:[1,0,0]
	v_pk_mul_f32 v[186:187], v[176:177], v[170:171] op_sel:[0,0] op_sel_hi:[0,1]
	v_pk_fma_f32 v[146:147], v[146:147], v[182:183], v[148:149] op_sel:[1,1,0] op_sel_hi:[1,0,1] neg_lo:[1,0,0]
	v_mov_b32_e32 v141, v155
	v_pk_mul_f32 v[148:149], v[140:141], v[184:185] op_sel:[0,0] op_sel_hi:[0,1]
	v_mov_b32_e32 v136, v134
	v_mov_b32_e32 v137, v139
	v_mov_b32_e32 v126, v124
	v_mov_b32_e32 v127, v129
	v_pk_fma_f32 v[174:175], v[168:169], v[158:159], v[174:175] op_sel:[1,1,0] op_sel_hi:[1,0,1] neg_lo:[1,0,0]
	v_pk_mul_f32 v[178:179], v[176:177], v[122:123] op_sel:[0,0] op_sel_hi:[0,1]
	v_pk_fma_f32 v[186:187], v[176:177], v[170:171], v[186:187] op_sel:[1,1,0] op_sel_hi:[1,0,1] neg_lo:[1,0,0]
	v_mov_b32_e32 v139, v135
	v_pk_mul_f32 v[188:189], v[174:175], v[174:175] op_sel:[0,0] op_sel_hi:[0,1]
	v_pk_mul_f32 v[134:135], v[138:139], v[170:171] op_sel:[0,0] op_sel_hi:[0,1]
	v_mov_b32_e32 v129, v125
	v_pk_mul_f32 v[124:125], v[128:129], v[174:175] op_sel:[0,0] op_sel_hi:[0,1]
	v_pk_fma_f32 v[140:141], v[140:141], v[184:185], v[148:149] op_sel:[1,1,0] op_sel_hi:[1,0,1] neg_lo:[1,0,0]
	v_pk_mul_f32 v[148:149], v[136:137], v[186:187] op_sel:[0,0] op_sel_hi:[0,1]
	v_mov_b32_e32 v152, v154
	v_pk_fma_f32 v[178:179], v[176:177], v[122:123], v[178:179] op_sel:[1,1,0] op_sel_hi:[1,0,1] neg_lo:[1,0,0]
	v_pk_fma_f32 v[188:189], v[174:175], v[174:175], v[188:189] op_sel:[1,1,0] op_sel_hi:[1,0,1] neg_lo:[1,0,0]
	v_pk_mul_f32 v[210:211], v[176:177], v[174:175] op_sel:[0,0] op_sel_hi:[0,1]
	v_pk_mul_f32 v[212:213], v[164:165], v[122:123] op_sel:[0,0] op_sel_hi:[0,1]
	v_pk_fma_f32 v[134:135], v[138:139], v[170:171], v[134:135] op_sel:[1,1,0] op_sel_hi:[1,0,1] neg_lo:[1,0,0]
	v_pk_fma_f32 v[124:125], v[128:129], v[174:175], v[124:125] op_sel:[1,1,0] op_sel_hi:[1,0,1] neg_lo:[1,0,0]
	v_pk_mul_f32 v[128:129], v[150:151], v[176:177] op_sel:[0,0] op_sel_hi:[0,1]
	s_nop 0
	v_pk_mul_f32 v[138:139], v[156:157], v[178:179] op_sel:[0,0] op_sel_hi:[0,1]
	v_pk_fma_f32 v[136:137], v[136:137], v[186:187], v[148:149] op_sel:[1,1,0] op_sel_hi:[1,0,1] neg_lo:[1,0,0]
	v_pk_fma_f32 v[122:123], v[164:165], v[122:123], v[212:213] op_sel:[1,1,0] op_sel_hi:[1,0,1] neg_lo:[1,0,0]
	v_pk_mul_f32 v[164:165], v[166:167], v[130:131] op_sel:[0,0] op_sel_hi:[0,1]
	v_pk_mul_f32 v[148:149], v[142:143], v[188:189] op_sel:[0,0] op_sel_hi:[0,1]
	v_pk_fma_f32 v[210:211], v[176:177], v[174:175], v[210:211] op_sel:[1,1,0] op_sel_hi:[1,0,1] neg_lo:[1,0,0]
	v_pk_fma_f32 v[128:129], v[150:151], v[176:177], v[128:129] op_sel:[1,1,0] op_sel_hi:[1,0,1] neg_lo:[1,0,0]
	s_nop 0
	v_pk_fma_f32 v[138:139], v[156:157], v[178:179], v[138:139] op_sel:[1,1,0] op_sel_hi:[1,0,1] neg_lo:[1,0,0]
	v_pk_fma_f32 v[130:131], v[166:167], v[130:131], v[164:165] op_sel:[1,1,0] op_sel_hi:[1,0,1] neg_lo:[1,0,0]
	v_pk_mul_f32 v[164:165], v[162:163], v[158:159] op_sel:[0,0] op_sel_hi:[0,1]
	v_pk_fma_f32 v[142:143], v[142:143], v[188:189], v[148:149] op_sel:[1,1,0] op_sel_hi:[1,0,1] neg_lo:[1,0,0]
	v_pk_mul_f32 v[148:149], v[126:127], v[210:211] op_sel:[0,0] op_sel_hi:[0,1]
	s_nop 0
	v_pk_fma_f32 v[158:159], v[162:163], v[158:159], v[164:165] op_sel:[1,1,0] op_sel_hi:[1,0,1] neg_lo:[1,0,0]
	v_pk_mul_f32 v[162:163], v[152:153], v[168:169] op_sel:[0,0] op_sel_hi:[0,1]
	v_pk_fma_f32 v[126:127], v[126:127], v[210:211], v[148:149] op_sel:[1,1,0] op_sel_hi:[1,0,1] neg_lo:[1,0,0]
	s_nop 0
	v_pk_fma_f32 v[152:153], v[152:153], v[168:169], v[162:163] op_sel:[1,1,0] op_sel_hi:[1,0,1] neg_lo:[1,0,0]
	ds_write2_b64 v73, v[160:161], v[122:123] offset1:68
	ds_write2_b64 v73, v[130:131], v[158:159] offset0:136 offset1:204
	ds_write2_b64 v75, v[152:153], v[134:135] offset0:16 offset1:84
	ds_write2_b64 v75, v[132:133], v[124:125] offset0:152 offset1:220
	ds_write2_b64 v80, v[128:129], v[138:139] offset0:32 offset1:100
	ds_write2_b64 v80, v[144:145], v[146:147] offset0:168 offset1:236
	ds_write2_b64 v190, v[140:141], v[136:137] offset0:48 offset1:116
	ds_write2_b64 v190, v[142:143], v[126:127] offset0:184 offset1:252
	v_mov_b32_e32 v73, v0
	s_waitcnt lgkmcnt(0)
	s_barrier
	s_nop 0
	v_and_b32_e32 v75, 3, v73
	v_lshlrev_b32_e32 v73, 4, v73
	v_and_b32_e32 v73, 0xffffffc0, v73
	v_ashrrev_i32_e32 v80, 1, v73
	v_cvt_f32_ubyte0_e32 v78, v75
	v_add_u32_e32 v80, 0, v80
	v_lshlrev_b32_e32 v123, 3, v73
	v_lshlrev_b32_e32 v75, 3, v75
	v_add3_u32 v80, v80, v123, v75
	ds_read2_b64 v[124:127], v80 offset1:4
	ds_read2_b64 v[128:131], v80 offset0:8 offset1:12
	ds_read2_b64 v[132:135], v80 offset0:17 offset1:21
	ds_read2_b64 v[136:139], v80 offset0:25 offset1:29
	ds_read2_b64 v[140:143], v80 offset0:34 offset1:38
	ds_read2_b64 v[144:147], v80 offset0:42 offset1:46
	ds_read2_b64 v[148:151], v80 offset0:51 offset1:55
	ds_read2_b64 v[152:155], v80 offset0:59 offset1:63
	s_waitcnt lgkmcnt(7)
	v_mov_b32_e32 v156, v124
	s_waitcnt lgkmcnt(5)
	v_mov_b32_e32 v157, v132
	s_waitcnt lgkmcnt(3)
	v_mov_b32_e32 v158, v140
	s_waitcnt lgkmcnt(1)
	v_mov_b32_e32 v159, v148
	v_pk_add_f32 v[156:157], v[156:157], v[158:159]
	v_mov_b32_e32 v158, v125
	v_mov_b32_e32 v159, v133
	v_mov_b32_e32 v160, v141
	v_mov_b32_e32 v161, v149
	v_pk_add_f32 v[158:159], v[158:159], v[160:161]
	v_pk_mov_b32 v[160:161], v[124:125], v[132:133] op_sel:[1,0]
	v_pk_mov_b32 v[162:163], v[140:141], v[148:149] op_sel:[1,0]
	v_mov_b32_e32 v125, v133
	v_pk_add_f32 v[160:161], v[160:161], v[162:163] neg_lo:[0,1] neg_hi:[0,1]
	v_mov_b32_e32 v141, v149
	v_mov_b32_e32 v132, v156
	v_mov_b32_e32 v133, v158
	v_mov_b32_e32 v158, v157
	v_pk_add_f32 v[124:125], v[124:125], v[140:141] neg_lo:[0,1] neg_hi:[0,1]
	v_pk_add_f32 v[140:141], v[132:133], v[158:159]
	v_pk_add_f32 v[132:133], v[132:133], v[158:159] neg_lo:[0,1] neg_hi:[0,1]
	v_pk_add_f32 v[156:157], v[160:161], v[160:161] op_sel_hi:[0,1] neg_lo:[0,1] neg_hi:[0,1]
	v_pk_add_f32 v[158:159], v[160:161], v[160:161] op_sel_hi:[0,1]
	v_pk_add_f32 v[160:161], v[126:127], v[142:143]
	v_pk_add_f32 v[162:163], v[134:135], v[150:151]
	v_pk_add_f32 v[126:127], v[126:127], v[142:143] neg_lo:[0,1] neg_hi:[0,1]
	v_pk_add_f32 v[134:135], v[134:135], v[150:151] neg_lo:[0,1] neg_hi:[0,1]
	s_waitcnt lgkmcnt(0)
	v_pk_add_f32 v[150:151], v[136:137], v[152:153]
	v_pk_add_f32 v[142:143], v[126:127], v[134:135] op_sel:[0,1] op_sel_hi:[1,0]
	v_pk_add_f32 v[126:127], v[126:127], v[134:135] op_sel:[0,1] op_sel_hi:[1,0] neg_lo:[0,1] neg_hi:[0,1]
	v_mov_b32_e32 v134, v142
	v_mov_b32_e32 v135, v127
	v_mov_b32_e32 v127, v143
	v_pk_add_f32 v[142:143], v[128:129], v[144:145]
	v_pk_add_f32 v[128:129], v[128:129], v[144:145] neg_lo:[0,1] neg_hi:[0,1]
	v_pk_add_f32 v[136:137], v[136:137], v[152:153] neg_lo:[0,1] neg_hi:[0,1]
	v_pk_add_f32 v[164:165], v[160:161], v[162:163]
	v_pk_add_f32 v[144:145], v[128:129], v[136:137] op_sel:[0,1] op_sel_hi:[1,0]
	v_pk_add_f32 v[128:129], v[128:129], v[136:137] op_sel:[0,1] op_sel_hi:[1,0] neg_lo:[0,1] neg_hi:[0,1]
	v_pk_add_f32 v[160:161], v[160:161], v[162:163] neg_lo:[0,1] neg_hi:[0,1]
	v_pk_add_f32 v[162:163], v[142:143], v[150:151]
	v_pk_add_f32 v[142:143], v[142:143], v[150:151] neg_lo:[0,1] neg_hi:[0,1]
	v_mov_b32_e32 v136, v144
	v_mov_b32_e32 v137, v129
	v_mov_b32_e32 v129, v145
	v_pk_add_f32 v[144:145], v[130:131], v[146:147]
	v_pk_add_f32 v[150:151], v[138:139], v[154:155]
	v_pk_add_f32 v[130:131], v[130:131], v[146:147] neg_lo:[0,1] neg_hi:[0,1]
	v_pk_add_f32 v[138:139], v[138:139], v[154:155] neg_lo:[0,1] neg_hi:[0,1]
	v_pk_add_f32 v[152:153], v[144:145], v[150:151]
	v_pk_add_f32 v[144:145], v[144:145], v[150:151] neg_lo:[0,1] neg_hi:[0,1]
	v_pk_add_f32 v[146:147], v[130:131], v[138:139] op_sel:[0,1] op_sel_hi:[1,0]
	v_pk_add_f32 v[130:131], v[130:131], v[138:139] op_sel:[0,1] op_sel_hi:[1,0] neg_lo:[0,1] neg_hi:[0,1]
	v_pk_mul_f32 v[150:151], v[142:143], v[94:95] op_sel:[0,0] op_sel_hi:[0,1]
	v_mul_f32_e32 v78, 0x3c800000, v78
	v_mov_b32_e32 v138, v146
	v_mov_b32_e32 v139, v131
	v_mov_b32_e32 v131, v147
	v_pk_mul_f32 v[146:147], v[134:135], v[90:91] op_sel:[0,0] op_sel_hi:[0,1]
	v_pk_fma_f32 v[142:143], v[142:143], v[94:95], v[150:151] op_sel:[1,1,0] op_sel_hi:[1,0,1] neg_lo:[1,0,0]
	v_pk_mul_f32 v[150:151], v[144:145], v[92:93] op_sel:[0,0] op_sel_hi:[0,1]
	v_cos_f32_e32 v122, v78
	v_sin_f32_e32 v78, v78
	v_pk_fma_f32 v[134:135], v[134:135], v[90:91], v[146:147] op_sel:[1,1,0] op_sel_hi:[1,0,1] neg_lo:[1,0,0]
	v_pk_mul_f32 v[146:147], v[136:137], v[88:89] op_sel:[0,0] op_sel_hi:[0,1]
	v_pk_fma_f32 v[144:145], v[144:145], v[92:93], v[150:151] op_sel:[1,1,0] op_sel_hi:[1,0,1] neg_lo:[1,0,0]
	v_pk_mul_f32 v[150:151], v[126:127], v[86:87] op_sel:[0,0] op_sel_hi:[0,1]
	v_pk_add_f32 v[148:149], v[124:125], v[124:125] op_sel:[0,1] op_sel_hi:[1,0]
	v_pk_fma_f32 v[136:137], v[136:137], v[88:89], v[146:147] op_sel:[1,1,0] op_sel_hi:[1,0,1] neg_lo:[1,0,0]
	v_pk_mul_f32 v[146:147], v[138:139], v[86:87] op_sel:[0,0] op_sel_hi:[0,1]
	v_pk_fma_f32 v[126:127], v[126:127], v[86:87], v[150:151] op_sel:[1,1,0] op_sel_hi:[1,0,1] neg_lo:[1,0,0]
	v_pk_mul_f32 v[150:151], v[128:129], v[92:93] op_sel:[0,0] op_sel_hi:[0,1]
	v_pk_add_f32 v[124:125], v[124:125], v[124:125] op_sel:[0,1] op_sel_hi:[1,0] neg_lo:[0,1] neg_hi:[0,1]
	v_pk_fma_f32 v[138:139], v[138:139], v[86:87], v[146:147] op_sel:[1,1,0] op_sel_hi:[1,0,1] neg_lo:[1,0,0]
	v_pk_mul_f32 v[146:147], v[160:161], v[88:89] op_sel:[0,0] op_sel_hi:[0,1]
	v_pk_fma_f32 v[128:129], v[128:129], v[92:93], v[150:151] op_sel:[1,1,0] op_sel_hi:[1,0,1] neg_lo:[1,0,0]
	v_pk_mul_f32 v[150:151], v[130:131], v[96:97] op_sel:[0,0] op_sel_hi:[0,1]
	v_mov_b32_e32 v149, v157
	v_pk_fma_f32 v[146:147], v[160:161], v[88:89], v[146:147] op_sel:[1,1,0] op_sel_hi:[1,0,1] neg_lo:[1,0,0]
	v_pk_fma_f32 v[130:131], v[130:131], v[96:97], v[150:151] op_sel:[1,1,0] op_sel_hi:[1,0,1] neg_lo:[1,0,0]
	v_pk_add_f32 v[150:151], v[140:141], v[162:163]
	v_pk_add_f32 v[140:141], v[140:141], v[162:163] neg_lo:[0,1] neg_hi:[0,1]
	v_pk_add_f32 v[156:157], v[148:149], v[136:137]
	v_pk_add_f32 v[162:163], v[134:135], v[138:139]
	v_mov_b32_e32 v125, v159
	v_pk_add_f32 v[154:155], v[164:165], v[152:153]
	v_pk_add_f32 v[152:153], v[164:165], v[152:153] neg_lo:[0,1] neg_hi:[0,1]
	v_pk_add_f32 v[164:165], v[156:157], v[162:163]
	v_pk_add_f32 v[156:157], v[156:157], v[162:163] neg_lo:[0,1] neg_hi:[0,1]
	v_pk_add_f32 v[136:137], v[148:149], v[136:137] neg_lo:[0,1] neg_hi:[0,1]
	v_pk_add_f32 v[148:149], v[132:133], v[142:143]
	v_pk_add_f32 v[162:163], v[146:147], v[144:145]
	v_pk_add_f32 v[132:133], v[132:133], v[142:143] neg_lo:[0,1] neg_hi:[0,1]
	v_pk_add_f32 v[142:143], v[146:147], v[144:145] neg_lo:[0,1] neg_hi:[0,1]
	v_pk_add_f32 v[146:147], v[124:125], v[128:129]
	v_pk_add_f32 v[158:159], v[126:127], v[130:131]
	v_pk_add_f32 v[126:127], v[126:127], v[130:131] neg_lo:[0,1] neg_hi:[0,1]
	v_mov_b32_e32 v130, v122
	v_mov_b32_e32 v123, v78
	v_pk_add_f32 v[166:167], v[148:149], v[162:163]
	v_pk_add_f32 v[148:149], v[148:149], v[162:163] neg_lo:[0,1] neg_hi:[0,1]
	v_pk_add_f32 v[162:163], v[146:147], v[158:159]
	v_pk_add_f32 v[146:147], v[146:147], v[158:159] neg_lo:[0,1] neg_hi:[0,1]
	s_nop 1
	v_pk_add_f32 v[144:145], v[132:133], v[142:143] op_sel:[0,1] op_sel_hi:[1,0]
	v_xor_b32_e32 v131, 0x80000000, v123
	v_pk_mul_f32 v[158:159], v[130:131], v[130:131] op_sel:[0,0] op_sel_hi:[0,1]
	v_pk_add_f32 v[132:133], v[132:133], v[142:143] op_sel:[0,1] op_sel_hi:[1,0] neg_lo:[0,1] neg_hi:[0,1]
	v_pk_fma_f32 v[158:159], v[130:131], v[130:131], v[158:159] op_sel:[1,1,0] op_sel_hi:[1,0,1] neg_lo:[1,0,0]
	v_mov_b32_e32 v143, v145
	v_pk_mul_f32 v[168:169], v[158:159], v[130:131] op_sel:[0,0] op_sel_hi:[0,1]
	v_pk_mul_f32 v[170:171], v[158:159], v[158:159] op_sel:[0,0] op_sel_hi:[0,1]
	v_mov_b32_e32 v142, v132
	v_pk_fma_f32 v[168:169], v[158:159], v[130:131], v[168:169] op_sel:[1,1,0] op_sel_hi:[1,0,1] neg_lo:[1,0,0]
	v_pk_fma_f32 v[170:171], v[158:159], v[158:159], v[170:171] op_sel:[1,1,0] op_sel_hi:[1,0,1] neg_lo:[1,0,0]
	v_mov_b32_e32 v145, v133
	v_pk_mul_f32 v[172:173], v[170:171], v[130:131] op_sel:[0,0] op_sel_hi:[0,1]
	v_pk_mul_f32 v[174:175], v[168:169], v[168:169] op_sel:[0,0] op_sel_hi:[0,1]
	v_pk_mul_f32 v[178:179], v[170:171], v[170:171] op_sel:[0,0] op_sel_hi:[0,1]
	v_pk_add_f32 v[160:161], v[150:151], v[154:155]
	v_pk_fma_f32 v[172:173], v[170:171], v[130:131], v[172:173] op_sel:[1,1,0] op_sel_hi:[1,0,1] neg_lo:[1,0,0]
	v_pk_fma_f32 v[174:175], v[168:169], v[168:169], v[174:175] op_sel:[1,1,0] op_sel_hi:[1,0,1] neg_lo:[1,0,0]
	v_pk_fma_f32 v[178:179], v[170:171], v[170:171], v[178:179] op_sel:[1,1,0] op_sel_hi:[1,0,1] neg_lo:[1,0,0]
	v_pk_add_f32 v[150:151], v[150:151], v[154:155] neg_lo:[0,1] neg_hi:[0,1]
	v_pk_mul_f32 v[182:183], v[172:173], v[172:173] op_sel:[0,0] op_sel_hi:[0,1]
	v_pk_mul_f32 v[132:133], v[144:145], v[174:175] op_sel:[0,0] op_sel_hi:[0,1]
	v_pk_mul_f32 v[184:185], v[178:179], v[168:169] op_sel:[0,0] op_sel_hi:[0,1]
	v_pk_add_f32 v[154:155], v[140:141], v[152:153] op_sel:[0,1] op_sel_hi:[1,0]
	v_pk_fma_f32 v[182:183], v[172:173], v[172:173], v[182:183] op_sel:[1,1,0] op_sel_hi:[1,0,1] neg_lo:[1,0,0]
	v_pk_fma_f32 v[132:133], v[144:145], v[174:175], v[132:133] op_sel:[1,1,0] op_sel_hi:[1,0,1] neg_lo:[1,0,0]
	v_pk_add_f32 v[140:141], v[140:141], v[152:153] op_sel:[0,1] op_sel_hi:[1,0] neg_lo:[0,1] neg_hi:[0,1]
	v_pk_mul_f32 v[144:145], v[148:149], v[182:183] op_sel:[0,0] op_sel_hi:[0,1]
	v_pk_add_f32 v[134:135], v[134:135], v[138:139] neg_lo:[0,1] neg_hi:[0,1]
	v_pk_add_f32 v[124:125], v[124:125], v[128:129] neg_lo:[0,1] neg_hi:[0,1]
	v_pk_fma_f32 v[184:185], v[178:179], v[168:169], v[184:185] op_sel:[1,1,0] op_sel_hi:[1,0,1] neg_lo:[1,0,0]
	v_pk_mul_f32 v[186:187], v[174:175], v[174:175] op_sel:[0,0] op_sel_hi:[0,1]
	v_pk_fma_f32 v[144:145], v[148:149], v[182:183], v[144:145] op_sel:[1,1,0] op_sel_hi:[1,0,1] neg_lo:[1,0,0]
	v_mov_b32_e32 v153, v141
	v_pk_mul_f32 v[148:149], v[146:147], v[184:185] op_sel:[0,0] op_sel_hi:[0,1]
	v_pk_add_f32 v[138:139], v[136:137], v[134:135] op_sel:[0,1] op_sel_hi:[1,0]
	v_pk_add_f32 v[134:135], v[136:137], v[134:135] op_sel:[0,1] op_sel_hi:[1,0] neg_lo:[0,1] neg_hi:[0,1]
	v_pk_add_f32 v[128:129], v[124:125], v[126:127] op_sel:[0,1] op_sel_hi:[1,0]
	v_pk_add_f32 v[124:125], v[124:125], v[126:127] op_sel:[0,1] op_sel_hi:[1,0] neg_lo:[0,1] neg_hi:[0,1]
	v_pk_mul_f32 v[176:177], v[170:171], v[168:169] op_sel:[0,0] op_sel_hi:[0,1]
	v_pk_mul_f32 v[180:181], v[178:179], v[130:131] op_sel:[0,0] op_sel_hi:[0,1]
	v_pk_fma_f32 v[186:187], v[174:175], v[174:175], v[186:187] op_sel:[1,1,0] op_sel_hi:[1,0,1] neg_lo:[1,0,0]
	v_pk_mul_f32 v[188:189], v[178:179], v[172:173] op_sel:[0,0] op_sel_hi:[0,1]
	v_pk_fma_f32 v[146:147], v[146:147], v[184:185], v[148:149] op_sel:[1,1,0] op_sel_hi:[1,0,1] neg_lo:[1,0,0]
	v_mov_b32_e32 v141, v155
	v_pk_mul_f32 v[148:149], v[140:141], v[186:187] op_sel:[0,0] op_sel_hi:[0,1]
	v_mov_b32_e32 v136, v134
	v_mov_b32_e32 v137, v139
	v_mov_b32_e32 v126, v124
	v_mov_b32_e32 v127, v129
	v_pk_fma_f32 v[176:177], v[170:171], v[168:169], v[176:177] op_sel:[1,1,0] op_sel_hi:[1,0,1] neg_lo:[1,0,0]
	v_pk_fma_f32 v[180:181], v[178:179], v[130:131], v[180:181] op_sel:[1,1,0] op_sel_hi:[1,0,1] neg_lo:[1,0,0]
	v_pk_fma_f32 v[188:189], v[178:179], v[172:173], v[188:189] op_sel:[1,1,0] op_sel_hi:[1,0,1] neg_lo:[1,0,0]
	v_pk_mul_f32 v[214:215], v[164:165], v[130:131] op_sel:[0,0] op_sel_hi:[0,1]
	v_mov_b32_e32 v139, v135
	v_pk_mul_f32 v[210:211], v[176:177], v[176:177] op_sel:[0,0] op_sel_hi:[0,1]
	v_pk_fma_f32 v[130:131], v[164:165], v[130:131], v[214:215] op_sel:[1,1,0] op_sel_hi:[1,0,1] neg_lo:[1,0,0]
	v_pk_mul_f32 v[164:165], v[166:167], v[158:159] op_sel:[0,0] op_sel_hi:[0,1]
	v_pk_mul_f32 v[134:135], v[138:139], v[172:173] op_sel:[0,0] op_sel_hi:[0,1]
	v_mov_b32_e32 v129, v125
	v_pk_mul_f32 v[124:125], v[128:129], v[176:177] op_sel:[0,0] op_sel_hi:[0,1]
	v_pk_fma_f32 v[140:141], v[140:141], v[186:187], v[148:149] op_sel:[1,1,0] op_sel_hi:[1,0,1] neg_lo:[1,0,0]
	v_pk_mul_f32 v[148:149], v[136:137], v[188:189] op_sel:[0,0] op_sel_hi:[0,1]
	v_mov_b32_e32 v152, v154
	v_pk_fma_f32 v[210:211], v[176:177], v[176:177], v[210:211] op_sel:[1,1,0] op_sel_hi:[1,0,1] neg_lo:[1,0,0]
	v_pk_mul_f32 v[212:213], v[178:179], v[176:177] op_sel:[0,0] op_sel_hi:[0,1]
	v_pk_fma_f32 v[158:159], v[166:167], v[158:159], v[164:165] op_sel:[1,1,0] op_sel_hi:[1,0,1] neg_lo:[1,0,0]
	v_pk_mul_f32 v[164:165], v[162:163], v[168:169] op_sel:[0,0] op_sel_hi:[0,1]
	v_pk_fma_f32 v[134:135], v[138:139], v[172:173], v[134:135] op_sel:[1,1,0] op_sel_hi:[1,0,1] neg_lo:[1,0,0]
	v_pk_fma_f32 v[124:125], v[128:129], v[176:177], v[124:125] op_sel:[1,1,0] op_sel_hi:[1,0,1] neg_lo:[1,0,0]
	v_pk_mul_f32 v[128:129], v[150:151], v[178:179] op_sel:[0,0] op_sel_hi:[0,1]
	v_pk_mul_f32 v[138:139], v[156:157], v[180:181] op_sel:[0,0] op_sel_hi:[0,1]
	v_pk_fma_f32 v[136:137], v[136:137], v[188:189], v[148:149] op_sel:[1,1,0] op_sel_hi:[1,0,1] neg_lo:[1,0,0]
	s_nop 0
	v_pk_mul_f32 v[148:149], v[142:143], v[210:211] op_sel:[0,0] op_sel_hi:[0,1]
	v_add_u32_e32 v73, 0x2000, v73
	v_pk_fma_f32 v[212:213], v[178:179], v[176:177], v[212:213] op_sel:[1,1,0] op_sel_hi:[1,0,1] neg_lo:[1,0,0]
	v_pk_fma_f32 v[162:163], v[162:163], v[168:169], v[164:165] op_sel:[1,1,0] op_sel_hi:[1,0,1] neg_lo:[1,0,0]
	v_pk_mul_f32 v[164:165], v[152:153], v[170:171] op_sel:[0,0] op_sel_hi:[0,1]
	v_pk_fma_f32 v[128:129], v[150:151], v[178:179], v[128:129] op_sel:[1,1,0] op_sel_hi:[1,0,1] neg_lo:[1,0,0]
	v_pk_fma_f32 v[138:139], v[156:157], v[180:181], v[138:139] op_sel:[1,1,0] op_sel_hi:[1,0,1] neg_lo:[1,0,0]
	v_pk_fma_f32 v[142:143], v[142:143], v[210:211], v[148:149] op_sel:[1,1,0] op_sel_hi:[1,0,1] neg_lo:[1,0,0]
	s_nop 0
	v_pk_mul_f32 v[148:149], v[126:127], v[212:213] op_sel:[0,0] op_sel_hi:[0,1]
	v_pk_fma_f32 v[152:153], v[152:153], v[170:171], v[164:165] op_sel:[1,1,0] op_sel_hi:[1,0,1] neg_lo:[1,0,0]
	s_nop 0
	v_pk_fma_f32 v[126:127], v[126:127], v[212:213], v[148:149] op_sel:[1,1,0] op_sel_hi:[1,0,1] neg_lo:[1,0,0]
	ds_write2_b64 v80, v[160:161], v[130:131] offset1:4
	ds_write2_b64 v80, v[158:159], v[162:163] offset0:8 offset1:12
	ds_write2_b64 v80, v[152:153], v[134:135] offset0:17 offset1:21
	ds_write2_b64 v80, v[132:133], v[124:125] offset0:25 offset1:29
	ds_write2_b64 v80, v[128:129], v[138:139] offset0:34 offset1:38
	ds_write2_b64 v80, v[144:145], v[146:147] offset0:42 offset1:46
	ds_write2_b64 v80, v[140:141], v[136:137] offset0:51 offset1:55
	ds_write2_b64 v80, v[142:143], v[126:127] offset0:59 offset1:63
	v_ashrrev_i32_e32 v80, 1, v73
	v_add_u32_e32 v80, 0, v80
	v_lshlrev_b32_e32 v73, 3, v73
	v_add3_u32 v73, v80, v73, v75
	ds_read2_b64 v[124:127], v73 offset1:4
	ds_read2_b64 v[128:131], v73 offset0:8 offset1:12
	ds_read2_b64 v[132:135], v73 offset0:17 offset1:21
	ds_read2_b64 v[136:139], v73 offset0:25 offset1:29
	ds_read2_b64 v[140:143], v73 offset0:34 offset1:38
	ds_read2_b64 v[144:147], v73 offset0:42 offset1:46
	ds_read2_b64 v[148:151], v73 offset0:51 offset1:55
	ds_read2_b64 v[152:155], v73 offset0:59 offset1:63
	s_waitcnt lgkmcnt(7)
	v_mov_b32_e32 v156, v124
	s_waitcnt lgkmcnt(5)
	v_mov_b32_e32 v157, v132
	s_waitcnt lgkmcnt(3)
	v_mov_b32_e32 v158, v140
	s_waitcnt lgkmcnt(1)
	v_mov_b32_e32 v159, v148
	v_pk_add_f32 v[156:157], v[156:157], v[158:159]
	v_mov_b32_e32 v158, v125
	v_mov_b32_e32 v159, v133
	v_mov_b32_e32 v160, v141
	v_mov_b32_e32 v161, v149
	v_pk_add_f32 v[158:159], v[158:159], v[160:161]
	v_pk_mov_b32 v[160:161], v[124:125], v[132:133] op_sel:[1,0]
	v_pk_mov_b32 v[162:163], v[140:141], v[148:149] op_sel:[1,0]
	v_mov_b32_e32 v125, v133
	v_pk_add_f32 v[160:161], v[160:161], v[162:163] neg_lo:[0,1] neg_hi:[0,1]
	v_mov_b32_e32 v141, v149
	v_mov_b32_e32 v132, v156
	v_mov_b32_e32 v133, v158
	v_mov_b32_e32 v158, v157
	v_pk_add_f32 v[124:125], v[124:125], v[140:141] neg_lo:[0,1] neg_hi:[0,1]
	v_pk_add_f32 v[140:141], v[132:133], v[158:159]
	v_pk_add_f32 v[132:133], v[132:133], v[158:159] neg_lo:[0,1] neg_hi:[0,1]
	v_pk_add_f32 v[156:157], v[160:161], v[160:161] op_sel_hi:[0,1] neg_lo:[0,1] neg_hi:[0,1]
	v_pk_add_f32 v[158:159], v[160:161], v[160:161] op_sel_hi:[0,1]
	v_pk_add_f32 v[160:161], v[126:127], v[142:143]
	v_pk_add_f32 v[162:163], v[134:135], v[150:151]
	v_pk_add_f32 v[126:127], v[126:127], v[142:143] neg_lo:[0,1] neg_hi:[0,1]
	v_pk_add_f32 v[134:135], v[134:135], v[150:151] neg_lo:[0,1] neg_hi:[0,1]
	s_waitcnt lgkmcnt(0)
	v_pk_add_f32 v[150:151], v[136:137], v[152:153]
	v_pk_add_f32 v[142:143], v[126:127], v[134:135] op_sel:[0,1] op_sel_hi:[1,0]
	v_pk_add_f32 v[126:127], v[126:127], v[134:135] op_sel:[0,1] op_sel_hi:[1,0] neg_lo:[0,1] neg_hi:[0,1]
	v_mov_b32_e32 v134, v142
	v_mov_b32_e32 v135, v127
	v_mov_b32_e32 v127, v143
	v_pk_add_f32 v[142:143], v[128:129], v[144:145]
	v_pk_add_f32 v[128:129], v[128:129], v[144:145] neg_lo:[0,1] neg_hi:[0,1]
	v_pk_add_f32 v[136:137], v[136:137], v[152:153] neg_lo:[0,1] neg_hi:[0,1]
	v_pk_add_f32 v[164:165], v[160:161], v[162:163]
	v_pk_add_f32 v[144:145], v[128:129], v[136:137] op_sel:[0,1] op_sel_hi:[1,0]
	v_pk_add_f32 v[128:129], v[128:129], v[136:137] op_sel:[0,1] op_sel_hi:[1,0] neg_lo:[0,1] neg_hi:[0,1]
	v_pk_add_f32 v[160:161], v[160:161], v[162:163] neg_lo:[0,1] neg_hi:[0,1]
	v_pk_add_f32 v[162:163], v[142:143], v[150:151]
	v_pk_add_f32 v[142:143], v[142:143], v[150:151] neg_lo:[0,1] neg_hi:[0,1]
	v_mov_b32_e32 v136, v144
	v_mov_b32_e32 v137, v129
	v_mov_b32_e32 v129, v145
	v_pk_add_f32 v[144:145], v[130:131], v[146:147]
	v_pk_add_f32 v[150:151], v[138:139], v[154:155]
	v_pk_add_f32 v[130:131], v[130:131], v[146:147] neg_lo:[0,1] neg_hi:[0,1]
	v_pk_add_f32 v[138:139], v[138:139], v[154:155] neg_lo:[0,1] neg_hi:[0,1]
	v_pk_add_f32 v[148:149], v[124:125], v[124:125] op_sel:[0,1] op_sel_hi:[1,0]
	v_pk_add_f32 v[146:147], v[130:131], v[138:139] op_sel:[0,1] op_sel_hi:[1,0]
	v_pk_add_f32 v[130:131], v[130:131], v[138:139] op_sel:[0,1] op_sel_hi:[1,0] neg_lo:[0,1] neg_hi:[0,1]
	v_mov_b32_e32 v138, v146
	v_mov_b32_e32 v139, v131
	v_mov_b32_e32 v131, v147
	v_pk_mul_f32 v[146:147], v[134:135], v[90:91] op_sel:[0,0] op_sel_hi:[0,1]
	v_pk_add_f32 v[124:125], v[124:125], v[124:125] op_sel:[0,1] op_sel_hi:[1,0] neg_lo:[0,1] neg_hi:[0,1]
	v_pk_fma_f32 v[90:91], v[134:135], v[90:91], v[146:147] op_sel:[1,1,0] op_sel_hi:[1,0,1] neg_lo:[1,0,0]
	v_pk_mul_f32 v[134:135], v[136:137], v[88:89] op_sel:[0,0] op_sel_hi:[0,1]
	v_pk_add_f32 v[152:153], v[144:145], v[150:151]
	v_pk_fma_f32 v[134:135], v[136:137], v[88:89], v[134:135] op_sel:[1,1,0] op_sel_hi:[1,0,1] neg_lo:[1,0,0]
	v_pk_mul_f32 v[136:137], v[138:139], v[86:87] op_sel:[0,0] op_sel_hi:[0,1]
	v_pk_add_f32 v[144:145], v[144:145], v[150:151] neg_lo:[0,1] neg_hi:[0,1]
	v_pk_fma_f32 v[136:137], v[138:139], v[86:87], v[136:137] op_sel:[1,1,0] op_sel_hi:[1,0,1] neg_lo:[1,0,0]
	v_pk_mul_f32 v[138:139], v[160:161], v[88:89] op_sel:[0,0] op_sel_hi:[0,1]
	v_mov_b32_e32 v149, v157
	v_pk_fma_f32 v[88:89], v[160:161], v[88:89], v[138:139] op_sel:[1,1,0] op_sel_hi:[1,0,1] neg_lo:[1,0,0]
	v_pk_mul_f32 v[138:139], v[142:143], v[94:95] op_sel:[0,0] op_sel_hi:[0,1]
	v_pk_add_f32 v[146:147], v[90:91], v[136:137]
	v_pk_fma_f32 v[94:95], v[142:143], v[94:95], v[138:139] op_sel:[1,1,0] op_sel_hi:[1,0,1] neg_lo:[1,0,0]
	v_pk_mul_f32 v[138:139], v[144:145], v[92:93] op_sel:[0,0] op_sel_hi:[0,1]
	v_pk_mul_f32 v[142:143], v[126:127], v[86:87] op_sel:[0,0] op_sel_hi:[0,1]
	v_mov_b32_e32 v125, v159
	v_pk_fma_f32 v[86:87], v[126:127], v[86:87], v[142:143] op_sel:[1,1,0] op_sel_hi:[1,0,1] neg_lo:[1,0,0]
	v_pk_mul_f32 v[126:127], v[128:129], v[92:93] op_sel:[0,0] op_sel_hi:[0,1]
	v_pk_fma_f32 v[138:139], v[144:145], v[92:93], v[138:139] op_sel:[1,1,0] op_sel_hi:[1,0,1] neg_lo:[1,0,0]
	v_pk_add_f32 v[144:145], v[148:149], v[134:135]
	v_pk_fma_f32 v[92:93], v[128:129], v[92:93], v[126:127] op_sel:[1,1,0] op_sel_hi:[1,0,1] neg_lo:[1,0,0]
	v_pk_mul_f32 v[126:127], v[130:131], v[96:97] op_sel:[0,0] op_sel_hi:[0,1]
	v_pk_add_f32 v[128:129], v[164:165], v[152:153]
	v_pk_fma_f32 v[96:97], v[130:131], v[96:97], v[126:127] op_sel:[1,1,0] op_sel_hi:[1,0,1] neg_lo:[1,0,0]
	v_pk_add_f32 v[126:127], v[140:141], v[162:163]
	v_pk_add_f32 v[150:151], v[144:145], v[146:147]
	v_pk_add_f32 v[144:145], v[144:145], v[146:147] neg_lo:[0,1] neg_hi:[0,1]
	v_pk_add_f32 v[134:135], v[148:149], v[134:135] neg_lo:[0,1] neg_hi:[0,1]
	v_pk_add_f32 v[146:147], v[132:133], v[94:95]
	v_pk_add_f32 v[148:149], v[88:89], v[138:139]
	v_pk_add_f32 v[88:89], v[88:89], v[138:139] neg_lo:[0,1] neg_hi:[0,1]
	v_pk_add_f32 v[138:139], v[124:125], v[92:93]
	v_pk_add_f32 v[92:93], v[124:125], v[92:93] neg_lo:[0,1] neg_hi:[0,1]
	s_nop 1
	v_pk_add_f32 v[130:131], v[126:127], v[128:129]
	v_xor_b32_e32 v123, 0x80000000, v78
	v_pk_mul_f32 v[124:125], v[122:123], v[122:123] op_sel:[0,0] op_sel_hi:[0,1]
	v_pk_add_f32 v[126:127], v[126:127], v[128:129] neg_lo:[0,1] neg_hi:[0,1]
	v_pk_add_f32 v[128:129], v[140:141], v[162:163] neg_lo:[0,1] neg_hi:[0,1]
	v_pk_add_f32 v[140:141], v[164:165], v[152:153] neg_lo:[0,1] neg_hi:[0,1]
	v_pk_add_f32 v[90:91], v[90:91], v[136:137] neg_lo:[0,1] neg_hi:[0,1]
	v_pk_add_f32 v[152:153], v[146:147], v[148:149]
	v_pk_add_f32 v[146:147], v[146:147], v[148:149] neg_lo:[0,1] neg_hi:[0,1]
	v_pk_add_f32 v[148:149], v[86:87], v[96:97]
	v_pk_fma_f32 v[124:125], v[122:123], v[122:123], v[124:125] op_sel:[1,1,0] op_sel_hi:[1,0,1] neg_lo:[1,0,0]
	v_pk_add_f32 v[136:137], v[134:135], v[90:91] op_sel:[0,1] op_sel_hi:[1,0]
	v_pk_mul_f32 v[156:157], v[124:125], v[124:125] op_sel:[0,0] op_sel_hi:[0,1]
	v_pk_add_f32 v[90:91], v[134:135], v[90:91] op_sel:[0,1] op_sel_hi:[1,0] neg_lo:[0,1] neg_hi:[0,1]
	v_pk_add_f32 v[154:155], v[138:139], v[148:149]
	v_pk_add_f32 v[138:139], v[138:139], v[148:149] neg_lo:[0,1] neg_hi:[0,1]
	v_pk_mul_f32 v[148:149], v[124:125], v[122:123] op_sel:[0,0] op_sel_hi:[0,1]
	v_pk_fma_f32 v[156:157], v[124:125], v[124:125], v[156:157] op_sel:[1,1,0] op_sel_hi:[1,0,1] neg_lo:[1,0,0]
	v_mov_b32_e32 v134, v90
	v_pk_mul_f32 v[158:159], v[156:157], v[122:123] op_sel:[0,0] op_sel_hi:[0,1]
	v_pk_mul_f32 v[164:165], v[156:157], v[156:157] op_sel:[0,0] op_sel_hi:[0,1]
	v_mov_b32_e32 v135, v137
	v_pk_add_f32 v[86:87], v[86:87], v[96:97] neg_lo:[0,1] neg_hi:[0,1]
	v_pk_fma_f32 v[148:149], v[124:125], v[122:123], v[148:149] op_sel:[1,1,0] op_sel_hi:[1,0,1] neg_lo:[1,0,0]
	v_pk_fma_f32 v[158:159], v[156:157], v[122:123], v[158:159] op_sel:[1,1,0] op_sel_hi:[1,0,1] neg_lo:[1,0,0]
	v_pk_fma_f32 v[164:165], v[156:157], v[156:157], v[164:165] op_sel:[1,1,0] op_sel_hi:[1,0,1] neg_lo:[1,0,0]
	v_mov_b32_e32 v137, v91
	v_pk_mul_f32 v[160:161], v[148:149], v[148:149] op_sel:[0,0] op_sel_hi:[0,1]
	v_pk_mul_f32 v[170:171], v[164:165], v[148:149] op_sel:[0,0] op_sel_hi:[0,1]
	v_pk_mul_f32 v[90:91], v[136:137], v[158:159] op_sel:[0,0] op_sel_hi:[0,1]
	v_pk_add_f32 v[142:143], v[128:129], v[140:141] op_sel:[0,1] op_sel_hi:[1,0]
	v_pk_add_f32 v[128:129], v[128:129], v[140:141] op_sel:[0,1] op_sel_hi:[1,0] neg_lo:[0,1] neg_hi:[0,1]
	v_pk_add_f32 v[94:95], v[132:133], v[94:95] neg_lo:[0,1] neg_hi:[0,1]
	v_pk_add_f32 v[96:97], v[92:93], v[86:87] op_sel:[0,1] op_sel_hi:[1,0]
	v_pk_add_f32 v[86:87], v[92:93], v[86:87] op_sel:[0,1] op_sel_hi:[1,0] neg_lo:[0,1] neg_hi:[0,1]
	v_pk_fma_f32 v[160:161], v[148:149], v[148:149], v[160:161] op_sel:[1,1,0] op_sel_hi:[1,0,1] neg_lo:[1,0,0]
	v_pk_mul_f32 v[162:163], v[156:157], v[148:149] op_sel:[0,0] op_sel_hi:[0,1]
	v_pk_fma_f32 v[170:171], v[164:165], v[148:149], v[170:171] op_sel:[1,1,0] op_sel_hi:[1,0,1] neg_lo:[1,0,0]
	v_pk_fma_f32 v[90:91], v[136:137], v[158:159], v[90:91] op_sel:[1,1,0] op_sel_hi:[1,0,1] neg_lo:[1,0,0]
	v_mov_b32_e32 v141, v129
	v_pk_mul_f32 v[172:173], v[160:161], v[160:161] op_sel:[0,0] op_sel_hi:[0,1]
	v_pk_mul_f32 v[136:137], v[138:139], v[170:171] op_sel:[0,0] op_sel_hi:[0,1]
	v_pk_add_f32 v[132:133], v[94:95], v[88:89] op_sel:[0,1] op_sel_hi:[1,0]
	v_pk_add_f32 v[88:89], v[94:95], v[88:89] op_sel:[0,1] op_sel_hi:[1,0] neg_lo:[0,1] neg_hi:[0,1]
	v_mov_b32_e32 v92, v86
	v_mov_b32_e32 v93, v97
	v_pk_fma_f32 v[162:163], v[156:157], v[148:149], v[162:163] op_sel:[1,1,0] op_sel_hi:[1,0,1] neg_lo:[1,0,0]
	v_pk_mul_f32 v[166:167], v[164:165], v[122:123] op_sel:[0,0] op_sel_hi:[0,1]
	v_pk_fma_f32 v[172:173], v[160:161], v[160:161], v[172:173] op_sel:[1,1,0] op_sel_hi:[1,0,1] neg_lo:[1,0,0]
	v_pk_mul_f32 v[174:175], v[164:165], v[158:159] op_sel:[0,0] op_sel_hi:[0,1]
	v_mov_b32_e32 v97, v87
	v_pk_mul_f32 v[86:87], v[96:97], v[162:163] op_sel:[0,0] op_sel_hi:[0,1]
	v_pk_fma_f32 v[136:137], v[138:139], v[170:171], v[136:137] op_sel:[1,1,0] op_sel_hi:[1,0,1] neg_lo:[1,0,0]
	v_mov_b32_e32 v129, v143
	v_pk_mul_f32 v[138:139], v[128:129], v[172:173] op_sel:[0,0] op_sel_hi:[0,1]
	v_mov_b32_e32 v94, v88
	v_mov_b32_e32 v95, v133
	v_pk_fma_f32 v[166:167], v[164:165], v[122:123], v[166:167] op_sel:[1,1,0] op_sel_hi:[1,0,1] neg_lo:[1,0,0]
	v_pk_mul_f32 v[168:169], v[158:159], v[158:159] op_sel:[0,0] op_sel_hi:[0,1]
	v_pk_fma_f32 v[174:175], v[164:165], v[158:159], v[174:175] op_sel:[1,1,0] op_sel_hi:[1,0,1] neg_lo:[1,0,0]
	v_pk_mul_f32 v[176:177], v[162:163], v[162:163] op_sel:[0,0] op_sel_hi:[0,1]
	v_pk_mul_f32 v[180:181], v[150:151], v[122:123] op_sel:[0,0] op_sel_hi:[0,1]
	v_mov_b32_e32 v133, v89
	v_pk_fma_f32 v[122:123], v[150:151], v[122:123], v[180:181] op_sel:[1,1,0] op_sel_hi:[1,0,1] neg_lo:[1,0,0]
	v_pk_mul_f32 v[150:151], v[152:153], v[124:125] op_sel:[0,0] op_sel_hi:[0,1]
	v_pk_mul_f32 v[88:89], v[132:133], v[160:161] op_sel:[0,0] op_sel_hi:[0,1]
	v_pk_fma_f32 v[86:87], v[96:97], v[162:163], v[86:87] op_sel:[1,1,0] op_sel_hi:[1,0,1] neg_lo:[1,0,0]
	v_pk_mul_f32 v[96:97], v[126:127], v[164:165] op_sel:[0,0] op_sel_hi:[0,1]
	v_pk_fma_f32 v[128:129], v[128:129], v[172:173], v[138:139] op_sel:[1,1,0] op_sel_hi:[1,0,1] neg_lo:[1,0,0]
	v_pk_mul_f32 v[138:139], v[134:135], v[174:175] op_sel:[0,0] op_sel_hi:[0,1]
	v_mov_b32_e32 v140, v142
	v_pk_fma_f32 v[168:169], v[158:159], v[158:159], v[168:169] op_sel:[1,1,0] op_sel_hi:[1,0,1] neg_lo:[1,0,0]
	v_pk_fma_f32 v[176:177], v[162:163], v[162:163], v[176:177] op_sel:[1,1,0] op_sel_hi:[1,0,1] neg_lo:[1,0,0]
	v_pk_mul_f32 v[178:179], v[164:165], v[162:163] op_sel:[0,0] op_sel_hi:[0,1]
	v_pk_fma_f32 v[124:125], v[152:153], v[124:125], v[150:151] op_sel:[1,1,0] op_sel_hi:[1,0,1] neg_lo:[1,0,0]
	v_pk_mul_f32 v[150:151], v[154:155], v[148:149] op_sel:[0,0] op_sel_hi:[0,1]
	v_pk_fma_f32 v[88:89], v[132:133], v[160:161], v[88:89] op_sel:[1,1,0] op_sel_hi:[1,0,1] neg_lo:[1,0,0]
	v_pk_fma_f32 v[96:97], v[126:127], v[164:165], v[96:97] op_sel:[1,1,0] op_sel_hi:[1,0,1] neg_lo:[1,0,0]
	v_pk_mul_f32 v[126:127], v[144:145], v[166:167] op_sel:[0,0] op_sel_hi:[0,1]
	s_nop 0
	v_pk_mul_f32 v[132:133], v[146:147], v[168:169] op_sel:[0,0] op_sel_hi:[0,1]
	v_pk_fma_f32 v[134:135], v[134:135], v[174:175], v[138:139] op_sel:[1,1,0] op_sel_hi:[1,0,1] neg_lo:[1,0,0]
	v_pk_mul_f32 v[138:139], v[94:95], v[176:177] op_sel:[0,0] op_sel_hi:[0,1]
	v_pk_fma_f32 v[178:179], v[164:165], v[162:163], v[178:179] op_sel:[1,1,0] op_sel_hi:[1,0,1] neg_lo:[1,0,0]
	v_pk_fma_f32 v[148:149], v[154:155], v[148:149], v[150:151] op_sel:[1,1,0] op_sel_hi:[1,0,1] neg_lo:[1,0,0]
	v_pk_mul_f32 v[150:151], v[140:141], v[156:157] op_sel:[0,0] op_sel_hi:[0,1]
	v_pk_fma_f32 v[126:127], v[144:145], v[166:167], v[126:127] op_sel:[1,1,0] op_sel_hi:[1,0,1] neg_lo:[1,0,0]
	s_nop 0
	v_pk_fma_f32 v[132:133], v[146:147], v[168:169], v[132:133] op_sel:[1,1,0] op_sel_hi:[1,0,1] neg_lo:[1,0,0]
	v_pk_fma_f32 v[94:95], v[94:95], v[176:177], v[138:139] op_sel:[1,1,0] op_sel_hi:[1,0,1] neg_lo:[1,0,0]
	v_pk_mul_f32 v[138:139], v[92:93], v[178:179] op_sel:[0,0] op_sel_hi:[0,1]
	v_pk_fma_f32 v[140:141], v[140:141], v[156:157], v[150:151] op_sel:[1,1,0] op_sel_hi:[1,0,1] neg_lo:[1,0,0]
	s_nop 0
	v_pk_fma_f32 v[92:93], v[92:93], v[178:179], v[138:139] op_sel:[1,1,0] op_sel_hi:[1,0,1] neg_lo:[1,0,0]
	ds_write2_b64 v73, v[130:131], v[122:123] offset1:4
	ds_write2_b64 v73, v[124:125], v[148:149] offset0:8 offset1:12
	ds_write2_b64 v73, v[140:141], v[90:91] offset0:17 offset1:21
	ds_write2_b64 v73, v[88:89], v[86:87] offset0:25 offset1:29
	ds_write2_b64 v73, v[96:97], v[126:127] offset0:34 offset1:38
	ds_write2_b64 v73, v[132:133], v[136:137] offset0:42 offset1:46
	ds_write2_b64 v73, v[128:129], v[134:135] offset0:51 offset1:55
	ds_write2_b64 v73, v[94:95], v[92:93] offset0:59 offset1:63
	v_mov_b32_e32 v73, v0
	s_waitcnt lgkmcnt(0)
	s_barrier
	s_waitcnt vmcnt(7)
	v_lshlrev_b32_e32 v94, 16, v46
	v_lshlrev_b32_e32 v75, 1, v73
	v_and_b32_e32 v75, -8, v75
	v_lshlrev_b32_e32 v78, 5, v73
	v_add3_u32 v75, 0, v75, v78
	ds_read2_b64 v[86:89], v75 offset1:1
	ds_read2_b64 v[90:93], v75 offset0:2 offset1:3
	v_and_b32_e32 v95, 0xffff0000, v46
	v_lshlrev_b32_e32 v46, 16, v47
	v_and_b32_e32 v47, 0xffff0000, v47
	v_lshlrev_b32_e32 v96, 16, v48
	s_waitcnt lgkmcnt(0)
	v_pk_add_f32 v[122:123], v[86:87], v[90:91]
	v_pk_add_f32 v[124:125], v[88:89], v[92:93]
	v_pk_add_f32 v[86:87], v[86:87], v[90:91] neg_lo:[0,1] neg_hi:[0,1]
	v_pk_add_f32 v[88:89], v[88:89], v[92:93] neg_lo:[0,1] neg_hi:[0,1]
	v_and_b32_e32 v97, 0xffff0000, v48
	v_pk_add_f32 v[90:91], v[86:87], v[88:89] op_sel:[0,1] op_sel_hi:[1,0]
	v_pk_add_f32 v[86:87], v[86:87], v[88:89] op_sel:[0,1] op_sel_hi:[1,0] neg_lo:[0,1] neg_hi:[0,1]
	v_mov_b32_e32 v89, v91
	v_mov_b32_e32 v88, v86
	v_mov_b32_e32 v91, v87
	v_pk_mul_f32 v[86:87], v[90:91], v[46:47] op_sel:[0,0] op_sel_hi:[0,1]
	v_pk_add_f32 v[126:127], v[122:123], v[124:125]
	v_pk_add_f32 v[122:123], v[122:123], v[124:125] neg_lo:[0,1] neg_hi:[0,1]
	v_pk_fma_f32 v[46:47], v[90:91], v[46:47], v[86:87] op_sel:[1,1,0] op_sel_hi:[1,0,1] neg_lo:[1,0,0]
	v_lshlrev_b32_e32 v48, 16, v49
	v_pk_mul_f32 v[86:87], v[122:123], v[96:97] op_sel:[0,0] op_sel_hi:[0,1]
	v_and_b32_e32 v49, 0xffff0000, v49
	v_pk_mul_f32 v[92:93], v[126:127], v[94:95] op_sel:[0,0] op_sel_hi:[0,1]
	v_pk_fma_f32 v[86:87], v[122:123], v[96:97], v[86:87] op_sel:[1,1,0] op_sel_hi:[1,0,1] neg_lo:[1,0,0]
	v_pk_mul_f32 v[90:91], v[88:89], v[48:49] op_sel:[0,0] op_sel_hi:[0,1]
	s_nop 0
	v_pk_fma_f32 v[92:93], v[126:127], v[94:95], v[92:93] op_sel:[1,1,0] op_sel_hi:[1,0,1] neg_lo:[1,0,0]
	v_pk_fma_f32 v[48:49], v[88:89], v[48:49], v[90:91] op_sel:[1,1,0] op_sel_hi:[1,0,1] neg_lo:[1,0,0]
	s_nop 0
	v_pk_add_f32 v[88:89], v[92:93], v[86:87]
	v_pk_add_f32 v[90:91], v[46:47], v[48:49]
	v_pk_add_f32 v[86:87], v[92:93], v[86:87] neg_lo:[0,1] neg_hi:[0,1]
	v_pk_add_f32 v[46:47], v[46:47], v[48:49] neg_lo:[0,1] neg_hi:[0,1]
	v_pk_add_f32 v[94:95], v[88:89], v[90:91]
	v_pk_add_f32 v[48:49], v[86:87], v[46:47] op_sel:[0,1] op_sel_hi:[1,0] neg_lo:[0,1] neg_hi:[0,1]
	v_pk_add_f32 v[46:47], v[86:87], v[46:47] op_sel:[0,1] op_sel_hi:[1,0]
	v_pk_add_f32 v[88:89], v[88:89], v[90:91] neg_lo:[0,1] neg_hi:[0,1]
	v_mov_b32_e32 v87, v47
	v_mov_b32_e32 v47, v49
	ds_write2_b64 v75, v[88:89], v[46:47] offset0:2 offset1:3
	v_add_u32_e32 v46, 0x200, v73
	v_lshlrev_b32_e32 v47, 1, v46
	v_mov_b32_e32 v86, v48
	v_and_b32_e32 v47, -8, v47
	v_lshlrev_b32_e32 v46, 5, v46
	ds_write2_b64 v75, v[94:95], v[86:87] offset1:1
	v_add3_u32 v75, 0, v47, v46
	ds_read2_b64 v[46:49], v75 offset1:1
	ds_read2_b64 v[86:89], v75 offset0:2 offset1:3
	s_waitcnt vmcnt(6)
	v_lshlrev_b32_e32 v90, 16, v42
	v_and_b32_e32 v91, 0xffff0000, v42
	v_lshlrev_b32_e32 v42, 16, v43
	v_and_b32_e32 v43, 0xffff0000, v43
	s_waitcnt lgkmcnt(0)
	v_pk_add_f32 v[94:95], v[46:47], v[86:87]
	v_pk_add_f32 v[96:97], v[48:49], v[88:89]
	v_pk_add_f32 v[46:47], v[46:47], v[86:87] neg_lo:[0,1] neg_hi:[0,1]
	v_pk_add_f32 v[48:49], v[48:49], v[88:89] neg_lo:[0,1] neg_hi:[0,1]
	v_lshlrev_b32_e32 v92, 16, v44
	v_pk_add_f32 v[86:87], v[46:47], v[48:49] op_sel:[0,1] op_sel_hi:[1,0]
	v_pk_add_f32 v[46:47], v[46:47], v[48:49] op_sel:[0,1] op_sel_hi:[1,0] neg_lo:[0,1] neg_hi:[0,1]
	v_mov_b32_e32 v49, v87
	v_mov_b32_e32 v48, v46
	v_mov_b32_e32 v87, v47
	v_pk_mul_f32 v[46:47], v[86:87], v[42:43] op_sel:[0,0] op_sel_hi:[0,1]
	v_and_b32_e32 v93, 0xffff0000, v44
	v_pk_add_f32 v[122:123], v[94:95], v[96:97]
	v_pk_add_f32 v[94:95], v[94:95], v[96:97] neg_lo:[0,1] neg_hi:[0,1]
	v_pk_fma_f32 v[42:43], v[86:87], v[42:43], v[46:47] op_sel:[1,1,0] op_sel_hi:[1,0,1] neg_lo:[1,0,0]
	v_lshlrev_b32_e32 v44, 16, v45
	v_pk_mul_f32 v[46:47], v[94:95], v[92:93] op_sel:[0,0] op_sel_hi:[0,1]
	v_and_b32_e32 v45, 0xffff0000, v45
	v_pk_mul_f32 v[88:89], v[122:123], v[90:91] op_sel:[0,0] op_sel_hi:[0,1]
	v_pk_fma_f32 v[46:47], v[94:95], v[92:93], v[46:47] op_sel:[1,1,0] op_sel_hi:[1,0,1] neg_lo:[1,0,0]
	v_pk_mul_f32 v[86:87], v[48:49], v[44:45] op_sel:[0,0] op_sel_hi:[0,1]
	s_nop 0
	v_pk_fma_f32 v[88:89], v[122:123], v[90:91], v[88:89] op_sel:[1,1,0] op_sel_hi:[1,0,1] neg_lo:[1,0,0]
	v_pk_fma_f32 v[44:45], v[48:49], v[44:45], v[86:87] op_sel:[1,1,0] op_sel_hi:[1,0,1] neg_lo:[1,0,0]
	s_nop 0
	v_pk_add_f32 v[48:49], v[88:89], v[46:47]
	v_pk_add_f32 v[86:87], v[42:43], v[44:45]
	v_pk_add_f32 v[46:47], v[88:89], v[46:47] neg_lo:[0,1] neg_hi:[0,1]
	v_pk_add_f32 v[42:43], v[42:43], v[44:45] neg_lo:[0,1] neg_hi:[0,1]
	v_pk_add_f32 v[90:91], v[48:49], v[86:87]
	v_pk_add_f32 v[44:45], v[46:47], v[42:43] op_sel:[0,1] op_sel_hi:[1,0] neg_lo:[0,1] neg_hi:[0,1]
	v_pk_add_f32 v[42:43], v[46:47], v[42:43] op_sel:[0,1] op_sel_hi:[1,0]
	v_pk_add_f32 v[48:49], v[48:49], v[86:87] neg_lo:[0,1] neg_hi:[0,1]
	v_mov_b32_e32 v47, v43
	v_mov_b32_e32 v43, v45
	ds_write2_b64 v75, v[48:49], v[42:43] offset0:2 offset1:3
	v_add_u32_e32 v42, 0x400, v73
	v_lshlrev_b32_e32 v43, 1, v42
	v_mov_b32_e32 v46, v44
	v_and_b32_e32 v43, -8, v43
	v_lshlrev_b32_e32 v42, 5, v42
	ds_write2_b64 v75, v[90:91], v[46:47] offset1:1
	v_add3_u32 v75, 0, v43, v42
	ds_read2_b64 v[42:45], v75 offset1:1
	ds_read2_b64 v[46:49], v75 offset0:2 offset1:3
	s_waitcnt vmcnt(5)
	v_lshlrev_b32_e32 v86, 16, v38
	v_and_b32_e32 v87, 0xffff0000, v38
	v_lshlrev_b32_e32 v38, 16, v39
	v_and_b32_e32 v39, 0xffff0000, v39
	s_waitcnt lgkmcnt(0)
	v_pk_add_f32 v[90:91], v[42:43], v[46:47]
	v_pk_add_f32 v[92:93], v[44:45], v[48:49]
	v_pk_add_f32 v[42:43], v[42:43], v[46:47] neg_lo:[0,1] neg_hi:[0,1]
	v_pk_add_f32 v[44:45], v[44:45], v[48:49] neg_lo:[0,1] neg_hi:[0,1]
	v_lshlrev_b32_e32 v88, 16, v40
	v_pk_add_f32 v[46:47], v[42:43], v[44:45] op_sel:[0,1] op_sel_hi:[1,0]
	v_pk_add_f32 v[42:43], v[42:43], v[44:45] op_sel:[0,1] op_sel_hi:[1,0] neg_lo:[0,1] neg_hi:[0,1]
	v_mov_b32_e32 v45, v47
	v_mov_b32_e32 v44, v42
	v_mov_b32_e32 v47, v43
	v_pk_mul_f32 v[42:43], v[46:47], v[38:39] op_sel:[0,0] op_sel_hi:[0,1]
	v_and_b32_e32 v89, 0xffff0000, v40
	v_pk_add_f32 v[94:95], v[90:91], v[92:93]
	v_pk_add_f32 v[90:91], v[90:91], v[92:93] neg_lo:[0,1] neg_hi:[0,1]
	v_pk_fma_f32 v[38:39], v[46:47], v[38:39], v[42:43] op_sel:[1,1,0] op_sel_hi:[1,0,1] neg_lo:[1,0,0]
	v_lshlrev_b32_e32 v40, 16, v41
	v_pk_mul_f32 v[42:43], v[90:91], v[88:89] op_sel:[0,0] op_sel_hi:[0,1]
	v_and_b32_e32 v41, 0xffff0000, v41
	v_pk_mul_f32 v[48:49], v[94:95], v[86:87] op_sel:[0,0] op_sel_hi:[0,1]
	v_pk_fma_f32 v[42:43], v[90:91], v[88:89], v[42:43] op_sel:[1,1,0] op_sel_hi:[1,0,1] neg_lo:[1,0,0]
	v_pk_mul_f32 v[46:47], v[44:45], v[40:41] op_sel:[0,0] op_sel_hi:[0,1]
	s_nop 0
	v_pk_fma_f32 v[48:49], v[94:95], v[86:87], v[48:49] op_sel:[1,1,0] op_sel_hi:[1,0,1] neg_lo:[1,0,0]
	v_pk_fma_f32 v[40:41], v[44:45], v[40:41], v[46:47] op_sel:[1,1,0] op_sel_hi:[1,0,1] neg_lo:[1,0,0]
	s_nop 0
	v_pk_add_f32 v[44:45], v[48:49], v[42:43]
	v_pk_add_f32 v[46:47], v[38:39], v[40:41]
	v_pk_add_f32 v[42:43], v[48:49], v[42:43] neg_lo:[0,1] neg_hi:[0,1]
	v_pk_add_f32 v[38:39], v[38:39], v[40:41] neg_lo:[0,1] neg_hi:[0,1]
	v_pk_add_f32 v[86:87], v[44:45], v[46:47]
	v_pk_add_f32 v[40:41], v[42:43], v[38:39] op_sel:[0,1] op_sel_hi:[1,0] neg_lo:[0,1] neg_hi:[0,1]
	v_pk_add_f32 v[38:39], v[42:43], v[38:39] op_sel:[0,1] op_sel_hi:[1,0]
	v_pk_add_f32 v[44:45], v[44:45], v[46:47] neg_lo:[0,1] neg_hi:[0,1]
	v_mov_b32_e32 v43, v39
	v_mov_b32_e32 v39, v41
	ds_write2_b64 v75, v[44:45], v[38:39] offset0:2 offset1:3
	v_add_u32_e32 v38, 0x600, v73
	v_lshlrev_b32_e32 v39, 1, v38
	v_mov_b32_e32 v42, v40
	v_and_b32_e32 v39, -8, v39
	v_lshlrev_b32_e32 v38, 5, v38
	ds_write2_b64 v75, v[86:87], v[42:43] offset1:1
	v_add3_u32 v75, 0, v39, v38
	ds_read2_b64 v[38:41], v75 offset1:1
	ds_read2_b64 v[42:45], v75 offset0:2 offset1:3
	s_waitcnt vmcnt(4)
	v_lshlrev_b32_e32 v46, 16, v34
	v_and_b32_e32 v47, 0xffff0000, v34
	v_lshlrev_b32_e32 v34, 16, v35
	v_and_b32_e32 v35, 0xffff0000, v35
	s_waitcnt lgkmcnt(0)
	v_pk_add_f32 v[86:87], v[38:39], v[42:43]
	v_pk_add_f32 v[88:89], v[40:41], v[44:45]
	v_pk_add_f32 v[38:39], v[38:39], v[42:43] neg_lo:[0,1] neg_hi:[0,1]
	v_pk_add_f32 v[40:41], v[40:41], v[44:45] neg_lo:[0,1] neg_hi:[0,1]
	v_lshlrev_b32_e32 v48, 16, v36
	v_pk_add_f32 v[42:43], v[38:39], v[40:41] op_sel:[0,1] op_sel_hi:[1,0]
	v_pk_add_f32 v[38:39], v[38:39], v[40:41] op_sel:[0,1] op_sel_hi:[1,0] neg_lo:[0,1] neg_hi:[0,1]
	v_mov_b32_e32 v41, v43
	v_mov_b32_e32 v40, v38
	v_mov_b32_e32 v43, v39
	v_pk_mul_f32 v[38:39], v[42:43], v[34:35] op_sel:[0,0] op_sel_hi:[0,1]
	v_and_b32_e32 v49, 0xffff0000, v36
	v_pk_add_f32 v[90:91], v[86:87], v[88:89]
	v_pk_add_f32 v[86:87], v[86:87], v[88:89] neg_lo:[0,1] neg_hi:[0,1]
	v_pk_fma_f32 v[34:35], v[42:43], v[34:35], v[38:39] op_sel:[1,1,0] op_sel_hi:[1,0,1] neg_lo:[1,0,0]
	v_lshlrev_b32_e32 v36, 16, v37
	v_pk_mul_f32 v[38:39], v[86:87], v[48:49] op_sel:[0,0] op_sel_hi:[0,1]
	v_and_b32_e32 v37, 0xffff0000, v37
	v_pk_mul_f32 v[44:45], v[90:91], v[46:47] op_sel:[0,0] op_sel_hi:[0,1]
	v_pk_fma_f32 v[38:39], v[86:87], v[48:49], v[38:39] op_sel:[1,1,0] op_sel_hi:[1,0,1] neg_lo:[1,0,0]
	v_pk_mul_f32 v[42:43], v[40:41], v[36:37] op_sel:[0,0] op_sel_hi:[0,1]
	s_nop 0
	v_pk_fma_f32 v[44:45], v[90:91], v[46:47], v[44:45] op_sel:[1,1,0] op_sel_hi:[1,0,1] neg_lo:[1,0,0]
	v_pk_fma_f32 v[36:37], v[40:41], v[36:37], v[42:43] op_sel:[1,1,0] op_sel_hi:[1,0,1] neg_lo:[1,0,0]
	s_nop 0
	v_pk_add_f32 v[40:41], v[44:45], v[38:39]
	v_pk_add_f32 v[42:43], v[34:35], v[36:37]
	v_pk_add_f32 v[38:39], v[44:45], v[38:39] neg_lo:[0,1] neg_hi:[0,1]
	v_pk_add_f32 v[34:35], v[34:35], v[36:37] neg_lo:[0,1] neg_hi:[0,1]
	v_pk_add_f32 v[46:47], v[40:41], v[42:43]
	v_pk_add_f32 v[36:37], v[38:39], v[34:35] op_sel:[0,1] op_sel_hi:[1,0] neg_lo:[0,1] neg_hi:[0,1]
	v_pk_add_f32 v[34:35], v[38:39], v[34:35] op_sel:[0,1] op_sel_hi:[1,0]
	v_pk_add_f32 v[40:41], v[40:41], v[42:43] neg_lo:[0,1] neg_hi:[0,1]
	v_mov_b32_e32 v39, v35
	v_mov_b32_e32 v35, v37
	ds_write2_b64 v75, v[40:41], v[34:35] offset0:2 offset1:3
	v_add_u32_e32 v34, 0x800, v73
	v_lshlrev_b32_e32 v35, 1, v34
	v_mov_b32_e32 v38, v36
	v_and_b32_e32 v35, -8, v35
	v_lshlrev_b32_e32 v34, 5, v34
	ds_write2_b64 v75, v[46:47], v[38:39] offset1:1
	v_add3_u32 v75, 0, v35, v34
	ds_read2_b64 v[34:37], v75 offset1:1
	ds_read2_b64 v[38:41], v75 offset0:2 offset1:3
	s_waitcnt vmcnt(3)
	v_lshlrev_b32_e32 v42, 16, v30
	v_and_b32_e32 v43, 0xffff0000, v30
	v_lshlrev_b32_e32 v30, 16, v31
	v_and_b32_e32 v31, 0xffff0000, v31
	s_waitcnt lgkmcnt(0)
	v_pk_add_f32 v[46:47], v[34:35], v[38:39]
	v_pk_add_f32 v[48:49], v[36:37], v[40:41]
	v_pk_add_f32 v[34:35], v[34:35], v[38:39] neg_lo:[0,1] neg_hi:[0,1]
	v_pk_add_f32 v[36:37], v[36:37], v[40:41] neg_lo:[0,1] neg_hi:[0,1]
	v_lshlrev_b32_e32 v44, 16, v32
	v_pk_add_f32 v[38:39], v[34:35], v[36:37] op_sel:[0,1] op_sel_hi:[1,0]
	v_pk_add_f32 v[34:35], v[34:35], v[36:37] op_sel:[0,1] op_sel_hi:[1,0] neg_lo:[0,1] neg_hi:[0,1]
	v_mov_b32_e32 v37, v39
	v_mov_b32_e32 v36, v34
	v_mov_b32_e32 v39, v35
	v_pk_mul_f32 v[34:35], v[38:39], v[30:31] op_sel:[0,0] op_sel_hi:[0,1]
	v_and_b32_e32 v45, 0xffff0000, v32
	v_pk_add_f32 v[86:87], v[46:47], v[48:49]
	v_pk_add_f32 v[46:47], v[46:47], v[48:49] neg_lo:[0,1] neg_hi:[0,1]
	v_pk_fma_f32 v[30:31], v[38:39], v[30:31], v[34:35] op_sel:[1,1,0] op_sel_hi:[1,0,1] neg_lo:[1,0,0]
	v_lshlrev_b32_e32 v32, 16, v33
	v_pk_mul_f32 v[34:35], v[46:47], v[44:45] op_sel:[0,0] op_sel_hi:[0,1]
	v_and_b32_e32 v33, 0xffff0000, v33
	v_pk_mul_f32 v[40:41], v[86:87], v[42:43] op_sel:[0,0] op_sel_hi:[0,1]
	v_pk_fma_f32 v[34:35], v[46:47], v[44:45], v[34:35] op_sel:[1,1,0] op_sel_hi:[1,0,1] neg_lo:[1,0,0]
	v_pk_mul_f32 v[38:39], v[36:37], v[32:33] op_sel:[0,0] op_sel_hi:[0,1]
	s_nop 0
	v_pk_fma_f32 v[40:41], v[86:87], v[42:43], v[40:41] op_sel:[1,1,0] op_sel_hi:[1,0,1] neg_lo:[1,0,0]
	v_pk_fma_f32 v[32:33], v[36:37], v[32:33], v[38:39] op_sel:[1,1,0] op_sel_hi:[1,0,1] neg_lo:[1,0,0]
	s_nop 0
	v_pk_add_f32 v[36:37], v[40:41], v[34:35]
	v_pk_add_f32 v[38:39], v[30:31], v[32:33]
	v_pk_add_f32 v[34:35], v[40:41], v[34:35] neg_lo:[0,1] neg_hi:[0,1]
	v_pk_add_f32 v[30:31], v[30:31], v[32:33] neg_lo:[0,1] neg_hi:[0,1]
	v_pk_add_f32 v[42:43], v[36:37], v[38:39]
	v_pk_add_f32 v[32:33], v[34:35], v[30:31] op_sel:[0,1] op_sel_hi:[1,0] neg_lo:[0,1] neg_hi:[0,1]
	v_pk_add_f32 v[30:31], v[34:35], v[30:31] op_sel:[0,1] op_sel_hi:[1,0]
	v_pk_add_f32 v[36:37], v[36:37], v[38:39] neg_lo:[0,1] neg_hi:[0,1]
	v_mov_b32_e32 v35, v31
	v_mov_b32_e32 v31, v33
	ds_write2_b64 v75, v[36:37], v[30:31] offset0:2 offset1:3
	v_add_u32_e32 v30, 0xa00, v73
	v_lshlrev_b32_e32 v31, 1, v30
	v_mov_b32_e32 v34, v32
	v_and_b32_e32 v31, -8, v31
	v_lshlrev_b32_e32 v30, 5, v30
	ds_write2_b64 v75, v[42:43], v[34:35] offset1:1
	v_add3_u32 v48, 0, v31, v30
	ds_read2_b64 v[30:33], v48 offset1:1
	ds_read2_b64 v[34:37], v48 offset0:2 offset1:3
	s_waitcnt vmcnt(2)
	v_lshlrev_b32_e32 v38, 16, v26
	v_and_b32_e32 v39, 0xffff0000, v26
	v_lshlrev_b32_e32 v26, 16, v27
	v_and_b32_e32 v27, 0xffff0000, v27
	s_waitcnt lgkmcnt(0)
	v_pk_add_f32 v[42:43], v[30:31], v[34:35]
	v_pk_add_f32 v[44:45], v[32:33], v[36:37]
	v_pk_add_f32 v[30:31], v[30:31], v[34:35] neg_lo:[0,1] neg_hi:[0,1]
	v_pk_add_f32 v[32:33], v[32:33], v[36:37] neg_lo:[0,1] neg_hi:[0,1]
	v_lshlrev_b32_e32 v40, 16, v28
	v_pk_add_f32 v[34:35], v[30:31], v[32:33] op_sel:[0,1] op_sel_hi:[1,0]
	v_pk_add_f32 v[30:31], v[30:31], v[32:33] op_sel:[0,1] op_sel_hi:[1,0] neg_lo:[0,1] neg_hi:[0,1]
	v_mov_b32_e32 v33, v35
	v_mov_b32_e32 v32, v30
	v_mov_b32_e32 v35, v31
	v_pk_mul_f32 v[30:31], v[34:35], v[26:27] op_sel:[0,0] op_sel_hi:[0,1]
	v_and_b32_e32 v41, 0xffff0000, v28
	v_pk_add_f32 v[46:47], v[42:43], v[44:45]
	v_pk_add_f32 v[42:43], v[42:43], v[44:45] neg_lo:[0,1] neg_hi:[0,1]
	v_pk_fma_f32 v[26:27], v[34:35], v[26:27], v[30:31] op_sel:[1,1,0] op_sel_hi:[1,0,1] neg_lo:[1,0,0]
	v_lshlrev_b32_e32 v28, 16, v29
	v_pk_mul_f32 v[30:31], v[42:43], v[40:41] op_sel:[0,0] op_sel_hi:[0,1]
	v_and_b32_e32 v29, 0xffff0000, v29
	v_pk_mul_f32 v[36:37], v[46:47], v[38:39] op_sel:[0,0] op_sel_hi:[0,1]
	v_pk_fma_f32 v[30:31], v[42:43], v[40:41], v[30:31] op_sel:[1,1,0] op_sel_hi:[1,0,1] neg_lo:[1,0,0]
	v_pk_mul_f32 v[34:35], v[32:33], v[28:29] op_sel:[0,0] op_sel_hi:[0,1]
	s_nop 0
	v_pk_fma_f32 v[36:37], v[46:47], v[38:39], v[36:37] op_sel:[1,1,0] op_sel_hi:[1,0,1] neg_lo:[1,0,0]
	v_pk_fma_f32 v[28:29], v[32:33], v[28:29], v[34:35] op_sel:[1,1,0] op_sel_hi:[1,0,1] neg_lo:[1,0,0]
	s_nop 0
	v_pk_add_f32 v[32:33], v[36:37], v[30:31]
	v_pk_add_f32 v[34:35], v[26:27], v[28:29]
	v_pk_add_f32 v[30:31], v[36:37], v[30:31] neg_lo:[0,1] neg_hi:[0,1]
	v_pk_add_f32 v[26:27], v[26:27], v[28:29] neg_lo:[0,1] neg_hi:[0,1]
	v_pk_add_f32 v[38:39], v[32:33], v[34:35]
	v_pk_add_f32 v[28:29], v[30:31], v[26:27] op_sel:[0,1] op_sel_hi:[1,0] neg_lo:[0,1] neg_hi:[0,1]
	v_pk_add_f32 v[26:27], v[30:31], v[26:27] op_sel:[0,1] op_sel_hi:[1,0]
	v_pk_add_f32 v[32:33], v[32:33], v[34:35] neg_lo:[0,1] neg_hi:[0,1]
	v_mov_b32_e32 v31, v27
	v_mov_b32_e32 v27, v29
	ds_write2_b64 v48, v[32:33], v[26:27] offset0:2 offset1:3
	v_add_u32_e32 v26, 0xc00, v73
	v_lshlrev_b32_e32 v27, 1, v26
	v_mov_b32_e32 v30, v28
	v_and_b32_e32 v27, -8, v27
	v_lshlrev_b32_e32 v26, 5, v26
	ds_write2_b64 v48, v[38:39], v[30:31] offset1:1
	v_add3_u32 v44, 0, v27, v26
	ds_read2_b64 v[26:29], v44 offset1:1
	ds_read2_b64 v[30:33], v44 offset0:2 offset1:3
	s_waitcnt vmcnt(1)
	v_lshlrev_b32_e32 v34, 16, v22
	v_and_b32_e32 v35, 0xffff0000, v22
	v_lshlrev_b32_e32 v22, 16, v23
	v_and_b32_e32 v23, 0xffff0000, v23
	s_waitcnt lgkmcnt(0)
	v_pk_add_f32 v[38:39], v[26:27], v[30:31]
	v_pk_add_f32 v[40:41], v[28:29], v[32:33]
	v_pk_add_f32 v[26:27], v[26:27], v[30:31] neg_lo:[0,1] neg_hi:[0,1]
	v_pk_add_f32 v[28:29], v[28:29], v[32:33] neg_lo:[0,1] neg_hi:[0,1]
	v_lshlrev_b32_e32 v36, 16, v24
	v_pk_add_f32 v[30:31], v[26:27], v[28:29] op_sel:[0,1] op_sel_hi:[1,0]
	v_pk_add_f32 v[26:27], v[26:27], v[28:29] op_sel:[0,1] op_sel_hi:[1,0] neg_lo:[0,1] neg_hi:[0,1]
	v_mov_b32_e32 v29, v31
	v_mov_b32_e32 v28, v26
	v_mov_b32_e32 v31, v27
	v_pk_mul_f32 v[26:27], v[30:31], v[22:23] op_sel:[0,0] op_sel_hi:[0,1]
	v_and_b32_e32 v37, 0xffff0000, v24
	v_pk_add_f32 v[42:43], v[38:39], v[40:41]
	v_pk_add_f32 v[38:39], v[38:39], v[40:41] neg_lo:[0,1] neg_hi:[0,1]
	v_pk_fma_f32 v[22:23], v[30:31], v[22:23], v[26:27] op_sel:[1,1,0] op_sel_hi:[1,0,1] neg_lo:[1,0,0]
	v_lshlrev_b32_e32 v24, 16, v25
	v_pk_mul_f32 v[26:27], v[38:39], v[36:37] op_sel:[0,0] op_sel_hi:[0,1]
	v_and_b32_e32 v25, 0xffff0000, v25
	v_pk_mul_f32 v[32:33], v[42:43], v[34:35] op_sel:[0,0] op_sel_hi:[0,1]
	v_pk_fma_f32 v[26:27], v[38:39], v[36:37], v[26:27] op_sel:[1,1,0] op_sel_hi:[1,0,1] neg_lo:[1,0,0]
	v_pk_mul_f32 v[30:31], v[28:29], v[24:25] op_sel:[0,0] op_sel_hi:[0,1]
	s_nop 0
	v_pk_fma_f32 v[32:33], v[42:43], v[34:35], v[32:33] op_sel:[1,1,0] op_sel_hi:[1,0,1] neg_lo:[1,0,0]
	v_pk_fma_f32 v[24:25], v[28:29], v[24:25], v[30:31] op_sel:[1,1,0] op_sel_hi:[1,0,1] neg_lo:[1,0,0]
	s_nop 0
	v_pk_add_f32 v[28:29], v[32:33], v[26:27]
	v_pk_add_f32 v[30:31], v[22:23], v[24:25]
	v_pk_add_f32 v[26:27], v[32:33], v[26:27] neg_lo:[0,1] neg_hi:[0,1]
	v_pk_add_f32 v[22:23], v[22:23], v[24:25] neg_lo:[0,1] neg_hi:[0,1]
	v_pk_add_f32 v[34:35], v[28:29], v[30:31]
	v_pk_add_f32 v[24:25], v[26:27], v[22:23] op_sel:[0,1] op_sel_hi:[1,0] neg_lo:[0,1] neg_hi:[0,1]
	v_pk_add_f32 v[22:23], v[26:27], v[22:23] op_sel:[0,1] op_sel_hi:[1,0]
	v_pk_add_f32 v[28:29], v[28:29], v[30:31] neg_lo:[0,1] neg_hi:[0,1]
	v_mov_b32_e32 v27, v23
	v_mov_b32_e32 v23, v25
	ds_write2_b64 v44, v[28:29], v[22:23] offset0:2 offset1:3
	v_add_u32_e32 v22, 0xe00, v73
	v_lshlrev_b32_e32 v23, 1, v22
	v_mov_b32_e32 v26, v24
	v_and_b32_e32 v23, -8, v23
	v_lshlrev_b32_e32 v22, 5, v22
	ds_write2_b64 v44, v[34:35], v[26:27] offset1:1
	v_add3_u32 v40, 0, v23, v22
	ds_read2_b64 v[22:25], v40 offset1:1
	ds_read2_b64 v[26:29], v40 offset0:2 offset1:3
	s_waitcnt vmcnt(0)
	v_lshlrev_b32_e32 v30, 16, v18
	v_and_b32_e32 v31, 0xffff0000, v18
	v_lshlrev_b32_e32 v18, 16, v19
	v_and_b32_e32 v19, 0xffff0000, v19
	s_waitcnt lgkmcnt(0)
	v_pk_add_f32 v[34:35], v[22:23], v[26:27]
	v_pk_add_f32 v[36:37], v[24:25], v[28:29]
	v_pk_add_f32 v[22:23], v[22:23], v[26:27] neg_lo:[0,1] neg_hi:[0,1]
	v_pk_add_f32 v[24:25], v[24:25], v[28:29] neg_lo:[0,1] neg_hi:[0,1]
	v_lshlrev_b32_e32 v32, 16, v20
	v_pk_add_f32 v[26:27], v[22:23], v[24:25] op_sel:[0,1] op_sel_hi:[1,0]
	v_pk_add_f32 v[22:23], v[22:23], v[24:25] op_sel:[0,1] op_sel_hi:[1,0] neg_lo:[0,1] neg_hi:[0,1]
	v_mov_b32_e32 v25, v27
	v_mov_b32_e32 v24, v22
	v_mov_b32_e32 v27, v23
	v_pk_mul_f32 v[22:23], v[26:27], v[18:19] op_sel:[0,0] op_sel_hi:[0,1]
	v_and_b32_e32 v33, 0xffff0000, v20
	v_pk_add_f32 v[38:39], v[34:35], v[36:37]
	v_pk_add_f32 v[34:35], v[34:35], v[36:37] neg_lo:[0,1] neg_hi:[0,1]
	v_pk_fma_f32 v[18:19], v[26:27], v[18:19], v[22:23] op_sel:[1,1,0] op_sel_hi:[1,0,1] neg_lo:[1,0,0]
	v_lshlrev_b32_e32 v20, 16, v21
	v_pk_mul_f32 v[22:23], v[34:35], v[32:33] op_sel:[0,0] op_sel_hi:[0,1]
	v_and_b32_e32 v21, 0xffff0000, v21
	v_pk_mul_f32 v[28:29], v[38:39], v[30:31] op_sel:[0,0] op_sel_hi:[0,1]
	v_pk_fma_f32 v[22:23], v[34:35], v[32:33], v[22:23] op_sel:[1,1,0] op_sel_hi:[1,0,1] neg_lo:[1,0,0]
	v_pk_mul_f32 v[26:27], v[24:25], v[20:21] op_sel:[0,0] op_sel_hi:[0,1]
	s_nop 0
	v_pk_fma_f32 v[28:29], v[38:39], v[30:31], v[28:29] op_sel:[1,1,0] op_sel_hi:[1,0,1] neg_lo:[1,0,0]
	v_pk_fma_f32 v[20:21], v[24:25], v[20:21], v[26:27] op_sel:[1,1,0] op_sel_hi:[1,0,1] neg_lo:[1,0,0]
	s_nop 0
	v_pk_add_f32 v[24:25], v[28:29], v[22:23]
	v_pk_add_f32 v[26:27], v[18:19], v[20:21]
	v_pk_add_f32 v[22:23], v[28:29], v[22:23] neg_lo:[0,1] neg_hi:[0,1]
	v_pk_add_f32 v[18:19], v[18:19], v[20:21] neg_lo:[0,1] neg_hi:[0,1]
	v_pk_add_f32 v[30:31], v[24:25], v[26:27]
	v_pk_add_f32 v[20:21], v[22:23], v[18:19] op_sel:[0,1] op_sel_hi:[1,0] neg_lo:[0,1] neg_hi:[0,1]
	v_pk_add_f32 v[18:19], v[22:23], v[18:19] op_sel:[0,1] op_sel_hi:[1,0]
	v_pk_add_f32 v[24:25], v[24:25], v[26:27] neg_lo:[0,1] neg_hi:[0,1]
	v_mov_b32_e32 v23, v19
	v_mov_b32_e32 v19, v21
	v_mov_b32_e32 v22, v20
	ds_write2_b64 v40, v[24:25], v[18:19] offset0:2 offset1:3
	v_mov_b32_e32 v18, v0
	ds_write2_b64 v40, v[30:31], v[22:23] offset1:1
	s_waitcnt lgkmcnt(0)
	s_barrier
	s_nop 0
	v_and_b32_e32 v20, 3, v18
	v_lshlrev_b32_e32 v21, 4, v18
	v_cvt_f32_ubyte0_e32 v18, v20
	v_mul_f32_e32 v19, 0x3c800000, v18
	v_cos_f32_e32 v18, v19
	v_sin_f32_e32 v19, v19
	v_and_b32_e32 v73, 0xffffffc0, v21
	v_ashrrev_i32_e32 v21, 1, v73
	v_add_u32_e32 v21, 0, v21
	v_lshlrev_b32_e32 v22, 3, v73
	v_lshlrev_b32_e32 v75, 3, v20
	v_add3_u32 v78, v21, v22, v75
	v_mov_b32_e32 v48, v18
	v_mov_b32_e32 v49, v19
	ds_read2_b64 v[20:23], v78 offset1:4
	ds_read2_b64 v[24:27], v78 offset0:8 offset1:12
	ds_read2_b64 v[28:31], v78 offset0:17 offset1:21
	ds_read2_b64 v[32:35], v78 offset0:25 offset1:29
	ds_read2_b64 v[36:39], v78 offset0:34 offset1:38
	ds_read2_b64 v[40:43], v78 offset0:42 offset1:46
	ds_read2_b64 v[44:47], v78 offset0:51 offset1:55
	ds_read2_b64 v[86:89], v78 offset0:59 offset1:63
	s_nop 1
	s_nop 0
	v_pk_mul_f32 v[90:91], v[48:49], v[48:49] op_sel:[0,0] op_sel_hi:[0,1]
	s_waitcnt lgkmcnt(7)
	v_pk_mul_f32 v[142:143], v[22:23], v[48:49] op_sel:[0,0] op_sel_hi:[0,1]
	v_pk_fma_f32 v[90:91], v[48:49], v[48:49], v[90:91] op_sel:[1,1,0] op_sel_hi:[1,0,1] neg_lo:[1,0,0]
	s_nop 0
	v_pk_fma_f32 v[22:23], v[22:23], v[48:49], v[142:143] op_sel:[1,1,0] op_sel_hi:[1,0,1] neg_lo:[1,0,0]
	v_pk_mul_f32 v[94:95], v[90:91], v[90:91] op_sel:[0,0] op_sel_hi:[0,1]
	v_pk_mul_f32 v[92:93], v[90:91], v[48:49] op_sel:[0,0] op_sel_hi:[0,1]
	s_nop 0
	v_pk_fma_f32 v[94:95], v[90:91], v[90:91], v[94:95] op_sel:[1,1,0] op_sel_hi:[1,0,1] neg_lo:[1,0,0]
	v_pk_fma_f32 v[92:93], v[90:91], v[48:49], v[92:93] op_sel:[1,1,0] op_sel_hi:[1,0,1] neg_lo:[1,0,0]
	s_nop 0
	v_pk_mul_f32 v[126:127], v[94:95], v[94:95] op_sel:[0,0] op_sel_hi:[0,1]
	v_pk_mul_f32 v[96:97], v[94:95], v[48:49] op_sel:[0,0] op_sel_hi:[0,1]
	v_pk_mul_f32 v[122:123], v[92:93], v[92:93] op_sel:[0,0] op_sel_hi:[0,1]
	v_pk_mul_f32 v[124:125], v[94:95], v[92:93] op_sel:[0,0] op_sel_hi:[0,1]
	s_nop 0
	v_pk_fma_f32 v[126:127], v[94:95], v[94:95], v[126:127] op_sel:[1,1,0] op_sel_hi:[1,0,1] neg_lo:[1,0,0]
	v_pk_fma_f32 v[96:97], v[94:95], v[48:49], v[96:97] op_sel:[1,1,0] op_sel_hi:[1,0,1] neg_lo:[1,0,0]
	v_pk_fma_f32 v[122:123], v[92:93], v[92:93], v[122:123] op_sel:[1,1,0] op_sel_hi:[1,0,1] neg_lo:[1,0,0]
	v_pk_fma_f32 v[124:125], v[94:95], v[92:93], v[124:125] op_sel:[1,1,0] op_sel_hi:[1,0,1] neg_lo:[1,0,0]
	s_nop 0
	v_pk_mul_f32 v[128:129], v[126:127], v[48:49] op_sel:[0,0] op_sel_hi:[0,1]
	v_pk_mul_f32 v[130:131], v[96:97], v[96:97] op_sel:[0,0] op_sel_hi:[0,1]
	v_pk_mul_f32 v[132:133], v[126:127], v[92:93] op_sel:[0,0] op_sel_hi:[0,1]
	v_pk_mul_f32 v[134:135], v[122:123], v[122:123] op_sel:[0,0] op_sel_hi:[0,1]
	v_pk_mul_f32 v[136:137], v[126:127], v[96:97] op_sel:[0,0] op_sel_hi:[0,1]
	v_pk_mul_f32 v[138:139], v[124:125], v[124:125] op_sel:[0,0] op_sel_hi:[0,1]
	s_nop 0
	v_pk_fma_f32 v[128:129], v[126:127], v[48:49], v[128:129] op_sel:[1,1,0] op_sel_hi:[1,0,1] neg_lo:[1,0,0]
	s_waitcnt lgkmcnt(6)
	v_pk_mul_f32 v[48:49], v[24:25], v[90:91] op_sel:[0,0] op_sel_hi:[0,1]
	v_pk_fma_f32 v[130:131], v[96:97], v[96:97], v[130:131] op_sel:[1,1,0] op_sel_hi:[1,0,1] neg_lo:[1,0,0]
	v_pk_fma_f32 v[132:133], v[126:127], v[92:93], v[132:133] op_sel:[1,1,0] op_sel_hi:[1,0,1] neg_lo:[1,0,0]
	v_pk_fma_f32 v[134:135], v[122:123], v[122:123], v[134:135] op_sel:[1,1,0] op_sel_hi:[1,0,1] neg_lo:[1,0,0]
	v_pk_fma_f32 v[136:137], v[126:127], v[96:97], v[136:137] op_sel:[1,1,0] op_sel_hi:[1,0,1] neg_lo:[1,0,0]
	v_pk_fma_f32 v[138:139], v[124:125], v[124:125], v[138:139] op_sel:[1,1,0] op_sel_hi:[1,0,1] neg_lo:[1,0,0]
	s_nop 0
	v_pk_fma_f32 v[24:25], v[24:25], v[90:91], v[48:49] op_sel:[1,1,0] op_sel_hi:[1,0,1] neg_lo:[1,0,0]
	v_pk_mul_f32 v[48:49], v[26:27], v[92:93] op_sel:[0,0] op_sel_hi:[0,1]
	v_pk_mul_f32 v[140:141], v[126:127], v[124:125] op_sel:[0,0] op_sel_hi:[0,1]
	s_nop 0
	v_pk_fma_f32 v[26:27], v[26:27], v[92:93], v[48:49] op_sel:[1,1,0] op_sel_hi:[1,0,1] neg_lo:[1,0,0]
	s_waitcnt lgkmcnt(5)
	v_pk_mul_f32 v[48:49], v[28:29], v[94:95] op_sel:[0,0] op_sel_hi:[0,1]
	v_pk_fma_f32 v[140:141], v[126:127], v[124:125], v[140:141] op_sel:[1,1,0] op_sel_hi:[1,0,1] neg_lo:[1,0,0]
	v_mov_b32_e32 v92, v21
	v_pk_fma_f32 v[28:29], v[28:29], v[94:95], v[48:49] op_sel:[1,1,0] op_sel_hi:[1,0,1] neg_lo:[1,0,0]
	v_pk_mul_f32 v[48:49], v[30:31], v[96:97] op_sel:[0,0] op_sel_hi:[0,1]
	s_nop 0
	v_pk_fma_f32 v[30:31], v[30:31], v[96:97], v[48:49] op_sel:[1,1,0] op_sel_hi:[1,0,1] neg_lo:[1,0,0]
	s_waitcnt lgkmcnt(4)
	v_pk_mul_f32 v[48:49], v[32:33], v[122:123] op_sel:[0,0] op_sel_hi:[0,1]
	v_mov_b32_e32 v93, v29
	v_pk_fma_f32 v[32:33], v[32:33], v[122:123], v[48:49] op_sel:[1,1,0] op_sel_hi:[1,0,1] neg_lo:[1,0,0]
	v_pk_mul_f32 v[48:49], v[34:35], v[124:125] op_sel:[0,0] op_sel_hi:[0,1]
	s_nop 0
	v_pk_fma_f32 v[34:35], v[34:35], v[124:125], v[48:49] op_sel:[1,1,0] op_sel_hi:[1,0,1] neg_lo:[1,0,0]
	s_waitcnt lgkmcnt(3)
	v_pk_mul_f32 v[48:49], v[36:37], v[126:127] op_sel:[0,0] op_sel_hi:[0,1]
	s_nop 0
	v_pk_fma_f32 v[36:37], v[36:37], v[126:127], v[48:49] op_sel:[1,1,0] op_sel_hi:[1,0,1] neg_lo:[1,0,0]
	v_pk_mul_f32 v[48:49], v[38:39], v[128:129] op_sel:[0,0] op_sel_hi:[0,1]
	s_nop 0
	v_pk_fma_f32 v[38:39], v[38:39], v[128:129], v[48:49] op_sel:[1,1,0] op_sel_hi:[1,0,1] neg_lo:[1,0,0]
	s_waitcnt lgkmcnt(2)
	v_pk_mul_f32 v[48:49], v[40:41], v[130:131] op_sel:[0,0] op_sel_hi:[0,1]
	v_mov_b32_e32 v94, v37
	v_pk_fma_f32 v[40:41], v[40:41], v[130:131], v[48:49] op_sel:[1,1,0] op_sel_hi:[1,0,1] neg_lo:[1,0,0]
	v_pk_mul_f32 v[48:49], v[42:43], v[132:133] op_sel:[0,0] op_sel_hi:[0,1]
	s_nop 0
	v_pk_fma_f32 v[42:43], v[42:43], v[132:133], v[48:49] op_sel:[1,1,0] op_sel_hi:[1,0,1] neg_lo:[1,0,0]
	s_waitcnt lgkmcnt(1)
	v_pk_mul_f32 v[48:49], v[44:45], v[134:135] op_sel:[0,0] op_sel_hi:[0,1]
	s_nop 0
	v_pk_fma_f32 v[44:45], v[44:45], v[134:135], v[48:49] op_sel:[1,1,0] op_sel_hi:[1,0,1] neg_lo:[1,0,0]
	v_pk_mul_f32 v[48:49], v[46:47], v[136:137] op_sel:[0,0] op_sel_hi:[0,1]
	s_nop 0
	v_pk_fma_f32 v[46:47], v[46:47], v[136:137], v[48:49] op_sel:[1,1,0] op_sel_hi:[1,0,1] neg_lo:[1,0,0]
	s_waitcnt lgkmcnt(0)
	v_pk_mul_f32 v[48:49], v[86:87], v[138:139] op_sel:[0,0] op_sel_hi:[0,1]
	v_mov_b32_e32 v95, v45
	v_pk_fma_f32 v[48:49], v[86:87], v[138:139], v[48:49] op_sel:[1,1,0] op_sel_hi:[1,0,1] neg_lo:[1,0,0]
	v_pk_mul_f32 v[86:87], v[88:89], v[140:141] op_sel:[0,0] op_sel_hi:[0,1]
	v_pk_add_f32 v[90:91], v[28:29], v[44:45]
	v_pk_fma_f32 v[86:87], v[88:89], v[140:141], v[86:87] op_sel:[1,1,0] op_sel_hi:[1,0,1] neg_lo:[1,0,0]
	v_pk_add_f32 v[88:89], v[20:21], v[36:37]
	v_pk_add_f32 v[92:93], v[92:93], v[94:95]
	v_pk_mov_b32 v[94:95], v[20:21], v[28:29] op_sel:[1,0]
	v_pk_mov_b32 v[96:97], v[36:37], v[44:45] op_sel:[1,0]
	v_mov_b32_e32 v21, v29
	v_pk_add_f32 v[94:95], v[94:95], v[96:97] neg_lo:[0,1] neg_hi:[0,1]
	v_mov_b32_e32 v37, v45
	v_mov_b32_e32 v89, v92
	v_mov_b32_e32 v91, v93
	v_pk_add_f32 v[20:21], v[20:21], v[36:37] neg_lo:[0,1] neg_hi:[0,1]
	v_pk_add_f32 v[28:29], v[88:89], v[90:91]
	v_pk_add_f32 v[36:37], v[88:89], v[90:91] neg_lo:[0,1] neg_hi:[0,1]
	v_pk_add_f32 v[88:89], v[94:95], v[94:95] op_sel:[0,1] op_sel_hi:[1,0]
	v_pk_add_f32 v[90:91], v[94:95], v[94:95] op_sel_hi:[0,1] neg_lo:[0,1] neg_hi:[0,1]
	v_pk_add_f32 v[92:93], v[22:23], v[38:39]
	v_pk_add_f32 v[94:95], v[30:31], v[46:47]
	v_pk_add_f32 v[22:23], v[22:23], v[38:39] neg_lo:[0,1] neg_hi:[0,1]
	v_pk_add_f32 v[30:31], v[30:31], v[46:47] neg_lo:[0,1] neg_hi:[0,1]
	v_pk_add_f32 v[46:47], v[32:33], v[48:49]
	v_pk_add_f32 v[38:39], v[22:23], v[30:31] op_sel:[0,1] op_sel_hi:[1,0] neg_lo:[0,1] neg_hi:[0,1]
	v_pk_add_f32 v[22:23], v[22:23], v[30:31] op_sel:[0,1] op_sel_hi:[1,0]
	v_mov_b32_e32 v30, v38
	v_mov_b32_e32 v31, v23
	v_mov_b32_e32 v23, v39
	v_pk_add_f32 v[38:39], v[24:25], v[40:41]
	v_pk_add_f32 v[24:25], v[24:25], v[40:41] neg_lo:[0,1] neg_hi:[0,1]
	v_pk_add_f32 v[32:33], v[32:33], v[48:49] neg_lo:[0,1] neg_hi:[0,1]
	v_pk_add_f32 v[96:97], v[92:93], v[94:95]
	v_pk_add_f32 v[40:41], v[24:25], v[32:33] op_sel:[0,1] op_sel_hi:[1,0] neg_lo:[0,1] neg_hi:[0,1]
	v_pk_add_f32 v[24:25], v[24:25], v[32:33] op_sel:[0,1] op_sel_hi:[1,0]
	v_pk_add_f32 v[92:93], v[92:93], v[94:95] neg_lo:[0,1] neg_hi:[0,1]
	v_pk_add_f32 v[94:95], v[38:39], v[46:47]
	v_pk_add_f32 v[38:39], v[38:39], v[46:47] neg_lo:[0,1] neg_hi:[0,1]
	v_mov_b32_e32 v32, v40
	v_mov_b32_e32 v33, v25
	v_mov_b32_e32 v25, v41
	v_pk_add_f32 v[40:41], v[26:27], v[42:43]
	v_pk_add_f32 v[46:47], v[34:35], v[86:87]
	v_pk_add_f32 v[26:27], v[26:27], v[42:43] neg_lo:[0,1] neg_hi:[0,1]
	v_pk_add_f32 v[48:49], v[40:41], v[46:47]
	v_pk_add_f32 v[40:41], v[40:41], v[46:47] neg_lo:[0,1] neg_hi:[0,1]
	v_pk_add_f32 v[34:35], v[34:35], v[86:87] neg_lo:[0,1] neg_hi:[0,1]
	v_pk_mul_f32 v[46:47], v[38:39], v[56:57] op_sel:[0,0] op_sel_hi:[0,1]
	v_pk_add_f32 v[44:45], v[20:21], v[20:21] op_sel:[0,1] op_sel_hi:[1,0] neg_lo:[0,1] neg_hi:[0,1]
	v_pk_add_f32 v[42:43], v[26:27], v[34:35] op_sel:[0,1] op_sel_hi:[1,0] neg_lo:[0,1] neg_hi:[0,1]
	v_pk_add_f32 v[26:27], v[26:27], v[34:35] op_sel:[0,1] op_sel_hi:[1,0]
	v_pk_fma_f32 v[38:39], v[38:39], v[56:57], v[46:47] op_sel:[1,1,0] op_sel_hi:[1,0,1] neg_lo:[1,0,0]
	v_pk_mul_f32 v[46:47], v[40:41], v[58:59] op_sel:[0,0] op_sel_hi:[0,1]
	v_mov_b32_e32 v34, v42
	v_mov_b32_e32 v35, v27
	v_mov_b32_e32 v27, v43
	v_pk_mul_f32 v[42:43], v[30:31], v[54:55] op_sel:[0,0] op_sel_hi:[0,1]
	v_pk_fma_f32 v[40:41], v[40:41], v[58:59], v[46:47] op_sel:[1,1,0] op_sel_hi:[1,0,1] neg_lo:[1,0,0]
	v_pk_mul_f32 v[46:47], v[22:23], v[50:51] op_sel:[0,0] op_sel_hi:[0,1]
	v_pk_add_f32 v[20:21], v[20:21], v[20:21] op_sel:[0,1] op_sel_hi:[1,0]
	v_pk_fma_f32 v[30:31], v[30:31], v[54:55], v[42:43] op_sel:[1,1,0] op_sel_hi:[1,0,1] neg_lo:[1,0,0]
	v_pk_mul_f32 v[42:43], v[32:33], v[52:53] op_sel:[0,0] op_sel_hi:[0,1]
	v_pk_fma_f32 v[22:23], v[22:23], v[50:51], v[46:47] op_sel:[1,1,0] op_sel_hi:[1,0,1] neg_lo:[1,0,0]
	v_pk_mul_f32 v[46:47], v[24:25], v[58:59] op_sel:[0,0] op_sel_hi:[0,1]
	v_pk_mov_b32 v[86:87], v[94:95], v[48:49] op_sel:[1,0]
	v_pk_fma_f32 v[32:33], v[32:33], v[52:53], v[42:43] op_sel:[1,1,0] op_sel_hi:[1,0,1] neg_lo:[1,0,0]
	v_pk_mul_f32 v[42:43], v[34:35], v[50:51] op_sel:[0,0] op_sel_hi:[0,1]
	v_pk_fma_f32 v[24:25], v[24:25], v[58:59], v[46:47] op_sel:[1,1,0] op_sel_hi:[1,0,1] neg_lo:[1,0,0]
	v_pk_mul_f32 v[46:47], v[26:27], v[60:61] op_sel:[0,0] op_sel_hi:[0,1]
	v_mov_b32_e32 v45, v31
	v_pk_fma_f32 v[34:35], v[34:35], v[50:51], v[42:43] op_sel:[1,1,0] op_sel_hi:[1,0,1] neg_lo:[1,0,0]
	v_mov_b32_e32 v122, v32
	v_mov_b32_e32 v123, v35
	v_pk_mul_f32 v[42:43], v[92:93], v[52:53] op_sel:[0,0] op_sel_hi:[0,1]
	v_pk_fma_f32 v[26:27], v[26:27], v[60:61], v[46:47] op_sel:[1,1,0] op_sel_hi:[1,0,1] neg_lo:[1,0,0]
	v_pk_mov_b32 v[46:47], v[28:29], v[96:97] op_sel:[1,0]
	v_pk_add_f32 v[122:123], v[44:45], v[122:123] neg_lo:[0,1] neg_hi:[0,1]
	v_mov_b32_e32 v45, v88
	v_pk_fma_f32 v[42:43], v[92:93], v[52:53], v[42:43] op_sel:[1,1,0] op_sel_hi:[1,0,1] neg_lo:[1,0,0]
	v_pk_add_f32 v[46:47], v[46:47], v[86:87] neg_lo:[0,1] neg_hi:[0,1]
	v_mov_b32_e32 v86, v28
	v_mov_b32_e32 v87, v97
	v_mov_b32_e32 v92, v94
	v_mov_b32_e32 v93, v49
	v_pk_add_f32 v[48:49], v[96:97], v[48:49]
	v_mov_b32_e32 v89, v30
	v_pk_mov_b32 v[96:97], v[32:33], v[34:35] op_sel:[1,0]
	v_pk_add_f32 v[32:33], v[44:45], v[32:33]
	v_pk_add_f32 v[30:31], v[30:31], v[34:35]
	v_mov_b32_e32 v21, v91
	v_pk_add_f32 v[86:87], v[86:87], v[92:93] neg_lo:[0,1] neg_hi:[0,1]
	v_pk_add_f32 v[28:29], v[28:29], v[94:95]
	v_pk_add_f32 v[96:97], v[88:89], v[96:97] neg_lo:[0,1] neg_hi:[0,1]
	v_pk_add_f32 v[34:35], v[32:33], v[30:31]
	v_pk_add_f32 v[30:31], v[32:33], v[30:31] neg_lo:[0,1] neg_hi:[0,1]
	v_pk_add_f32 v[32:33], v[122:123], v[122:123] op_sel:[0,1] op_sel_hi:[1,0] neg_lo:[0,1] neg_hi:[0,1]
	v_pk_add_f32 v[88:89], v[122:123], v[122:123] op_sel:[0,1] op_sel_hi:[1,0]
	v_pk_add_f32 v[122:123], v[36:37], v[38:39]
	v_pk_add_f32 v[124:125], v[42:43], v[40:41]
	v_pk_add_f32 v[36:37], v[36:37], v[38:39] neg_lo:[0,1] neg_hi:[0,1]
	v_pk_add_f32 v[38:39], v[42:43], v[40:41] neg_lo:[0,1] neg_hi:[0,1]
	v_pk_add_f32 v[42:43], v[20:21], v[24:25]
	v_pk_add_f32 v[90:91], v[22:23], v[26:27]
	v_pk_add_f32 v[20:21], v[20:21], v[24:25] neg_lo:[0,1] neg_hi:[0,1]
	v_pk_add_f32 v[22:23], v[22:23], v[26:27] neg_lo:[0,1] neg_hi:[0,1]
	v_pk_add_f32 v[92:93], v[28:29], v[48:49]
	v_pk_add_f32 v[28:29], v[28:29], v[48:49] neg_lo:[0,1] neg_hi:[0,1]
	v_pk_add_f32 v[48:49], v[86:87], v[86:87] op_sel:[0,1] op_sel_hi:[1,0] neg_lo:[0,1] neg_hi:[0,1]
	v_pk_add_f32 v[94:95], v[46:47], v[46:47] op_sel_hi:[0,1]
	v_pk_add_f32 v[44:45], v[96:97], v[96:97] op_sel_hi:[0,1]
	v_pk_add_f32 v[40:41], v[36:37], v[38:39] op_sel:[0,1] op_sel_hi:[1,0] neg_lo:[0,1] neg_hi:[0,1]
	v_pk_add_f32 v[36:37], v[36:37], v[38:39] op_sel:[0,1] op_sel_hi:[1,0]
	v_pk_add_f32 v[24:25], v[20:21], v[22:23] op_sel:[0,1] op_sel_hi:[1,0] neg_lo:[0,1] neg_hi:[0,1]
	v_pk_add_f32 v[20:21], v[20:21], v[22:23] op_sel:[0,1] op_sel_hi:[1,0]
	v_mov_b32_e32 v39, v37
	v_mov_b32_e32 v23, v21
	v_mov_b32_e32 v49, v95
	v_mov_b32_e32 v33, v45
	v_mov_b32_e32 v37, v41
	v_mov_b32_e32 v21, v25
	v_pk_add_f32 v[126:127], v[122:123], v[124:125]
	v_pk_add_f32 v[122:123], v[122:123], v[124:125] neg_lo:[0,1] neg_hi:[0,1]
	v_mov_b32_e32 v38, v40
	v_pk_add_f32 v[124:125], v[42:43], v[90:91]
	v_pk_add_f32 v[42:43], v[42:43], v[90:91] neg_lo:[0,1] neg_hi:[0,1]
	v_mov_b32_e32 v22, v24
	ds_write2_b64 v78, v[92:93], v[34:35] offset1:4
	ds_write2_b64 v78, v[126:127], v[124:125] offset0:8 offset1:12
	ds_write2_b64 v78, v[48:49], v[32:33] offset0:17 offset1:21
	ds_write2_b64 v78, v[38:39], v[22:23] offset0:25 offset1:29
	ds_write2_b64 v78, v[28:29], v[30:31] offset0:34 offset1:38
	ds_write2_b64 v78, v[122:123], v[42:43] offset0:42 offset1:46
	ds_write2_b64 v78, v[36:37], v[20:21] offset0:59 offset1:63
	v_add_u32_e32 v20, 0x2000, v73
	v_pk_add_f32 v[86:87], v[86:87], v[86:87] op_sel:[0,1] op_sel_hi:[1,0]
	v_pk_add_f32 v[46:47], v[46:47], v[46:47] op_sel_hi:[0,1] neg_lo:[0,1] neg_hi:[0,1]
	v_pk_add_f32 v[96:97], v[96:97], v[96:97] op_sel_hi:[0,1] neg_lo:[0,1] neg_hi:[0,1]
	v_ashrrev_i32_e32 v21, 1, v20
	v_mov_b32_e32 v87, v47
	v_mov_b32_e32 v89, v97
	v_add_u32_e32 v21, 0, v21
	v_lshlrev_b32_e32 v20, 3, v20
	ds_write2_b64 v78, v[86:87], v[88:89] offset0:51 offset1:55
	v_add3_u32 v73, v21, v20, v75
	ds_read2_b64 v[20:23], v73 offset1:4
	ds_read2_b64 v[24:27], v73 offset0:8 offset1:12
	ds_read2_b64 v[28:31], v73 offset0:17 offset1:21
	ds_read2_b64 v[32:35], v73 offset0:25 offset1:29
	ds_read2_b64 v[36:39], v73 offset0:34 offset1:38
	ds_read2_b64 v[40:43], v73 offset0:42 offset1:46
	ds_read2_b64 v[44:47], v73 offset0:51 offset1:55
	ds_read2_b64 v[86:89], v73 offset0:59 offset1:63
	s_nop 1
	s_nop 0
	v_pk_mul_f32 v[48:49], v[18:19], v[18:19] op_sel:[0,0] op_sel_hi:[0,1]
	s_waitcnt lgkmcnt(7)
	v_pk_mul_f32 v[140:141], v[22:23], v[18:19] op_sel:[0,0] op_sel_hi:[0,1]
	v_pk_fma_f32 v[48:49], v[18:19], v[18:19], v[48:49] op_sel:[1,1,0] op_sel_hi:[1,0,1] neg_lo:[1,0,0]
	s_nop 0
	v_pk_mul_f32 v[92:93], v[48:49], v[48:49] op_sel:[0,0] op_sel_hi:[0,1]
	v_pk_mul_f32 v[90:91], v[48:49], v[18:19] op_sel:[0,0] op_sel_hi:[0,1]
	s_nop 0
	v_pk_fma_f32 v[92:93], v[48:49], v[48:49], v[92:93] op_sel:[1,1,0] op_sel_hi:[1,0,1] neg_lo:[1,0,0]
	v_pk_fma_f32 v[90:91], v[48:49], v[18:19], v[90:91] op_sel:[1,1,0] op_sel_hi:[1,0,1] neg_lo:[1,0,0]
	s_nop 0
	v_pk_mul_f32 v[124:125], v[92:93], v[92:93] op_sel:[0,0] op_sel_hi:[0,1]
	v_pk_mul_f32 v[94:95], v[92:93], v[18:19] op_sel:[0,0] op_sel_hi:[0,1]
	v_pk_mul_f32 v[96:97], v[90:91], v[90:91] op_sel:[0,0] op_sel_hi:[0,1]
	v_pk_mul_f32 v[122:123], v[92:93], v[90:91] op_sel:[0,0] op_sel_hi:[0,1]
	s_nop 0
	v_pk_fma_f32 v[124:125], v[92:93], v[92:93], v[124:125] op_sel:[1,1,0] op_sel_hi:[1,0,1] neg_lo:[1,0,0]
	v_pk_fma_f32 v[94:95], v[92:93], v[18:19], v[94:95] op_sel:[1,1,0] op_sel_hi:[1,0,1] neg_lo:[1,0,0]
	v_pk_fma_f32 v[96:97], v[90:91], v[90:91], v[96:97] op_sel:[1,1,0] op_sel_hi:[1,0,1] neg_lo:[1,0,0]
	v_pk_fma_f32 v[122:123], v[92:93], v[90:91], v[122:123] op_sel:[1,1,0] op_sel_hi:[1,0,1] neg_lo:[1,0,0]
	s_nop 0
	v_pk_mul_f32 v[126:127], v[124:125], v[18:19] op_sel:[0,0] op_sel_hi:[0,1]
	v_pk_mul_f32 v[128:129], v[94:95], v[94:95] op_sel:[0,0] op_sel_hi:[0,1]
	v_pk_mul_f32 v[130:131], v[124:125], v[90:91] op_sel:[0,0] op_sel_hi:[0,1]
	v_pk_mul_f32 v[132:133], v[96:97], v[96:97] op_sel:[0,0] op_sel_hi:[0,1]
	v_pk_mul_f32 v[134:135], v[124:125], v[94:95] op_sel:[0,0] op_sel_hi:[0,1]
	v_pk_mul_f32 v[136:137], v[122:123], v[122:123] op_sel:[0,0] op_sel_hi:[0,1]
	s_nop 0
	v_pk_fma_f32 v[126:127], v[124:125], v[18:19], v[126:127] op_sel:[1,1,0] op_sel_hi:[1,0,1] neg_lo:[1,0,0]
	v_pk_fma_f32 v[18:19], v[22:23], v[18:19], v[140:141] op_sel:[1,1,0] op_sel_hi:[1,0,1] neg_lo:[1,0,0]
	s_waitcnt lgkmcnt(6)
	v_pk_mul_f32 v[22:23], v[24:25], v[48:49] op_sel:[0,0] op_sel_hi:[0,1]
	v_pk_fma_f32 v[128:129], v[94:95], v[94:95], v[128:129] op_sel:[1,1,0] op_sel_hi:[1,0,1] neg_lo:[1,0,0]
	v_pk_fma_f32 v[130:131], v[124:125], v[90:91], v[130:131] op_sel:[1,1,0] op_sel_hi:[1,0,1] neg_lo:[1,0,0]
	v_pk_fma_f32 v[132:133], v[96:97], v[96:97], v[132:133] op_sel:[1,1,0] op_sel_hi:[1,0,1] neg_lo:[1,0,0]
	v_pk_fma_f32 v[134:135], v[124:125], v[94:95], v[134:135] op_sel:[1,1,0] op_sel_hi:[1,0,1] neg_lo:[1,0,0]
	v_pk_mul_f32 v[138:139], v[124:125], v[122:123] op_sel:[0,0] op_sel_hi:[0,1]
	s_nop 0
	v_pk_fma_f32 v[22:23], v[24:25], v[48:49], v[22:23] op_sel:[1,1,0] op_sel_hi:[1,0,1] neg_lo:[1,0,0]
	v_pk_mul_f32 v[24:25], v[26:27], v[90:91] op_sel:[0,0] op_sel_hi:[0,1]
	v_pk_fma_f32 v[136:137], v[122:123], v[122:123], v[136:137] op_sel:[1,1,0] op_sel_hi:[1,0,1] neg_lo:[1,0,0]
	s_nop 0
	v_pk_fma_f32 v[24:25], v[26:27], v[90:91], v[24:25] op_sel:[1,1,0] op_sel_hi:[1,0,1] neg_lo:[1,0,0]
	s_waitcnt lgkmcnt(5)
	v_pk_mul_f32 v[26:27], v[28:29], v[92:93] op_sel:[0,0] op_sel_hi:[0,1]
	v_pk_fma_f32 v[138:139], v[124:125], v[122:123], v[138:139] op_sel:[1,1,0] op_sel_hi:[1,0,1] neg_lo:[1,0,0]
	v_mov_b32_e32 v90, v21
	v_pk_fma_f32 v[26:27], v[28:29], v[92:93], v[26:27] op_sel:[1,1,0] op_sel_hi:[1,0,1] neg_lo:[1,0,0]
	v_pk_mul_f32 v[28:29], v[30:31], v[94:95] op_sel:[0,0] op_sel_hi:[0,1]
	s_waitcnt lgkmcnt(0)
	v_pk_mul_f32 v[48:49], v[88:89], v[138:139] op_sel:[0,0] op_sel_hi:[0,1]
	v_pk_fma_f32 v[28:29], v[30:31], v[94:95], v[28:29] op_sel:[1,1,0] op_sel_hi:[1,0,1] neg_lo:[1,0,0]
	v_pk_mul_f32 v[30:31], v[32:33], v[96:97] op_sel:[0,0] op_sel_hi:[0,1]
	v_mov_b32_e32 v91, v27
	v_pk_fma_f32 v[30:31], v[32:33], v[96:97], v[30:31] op_sel:[1,1,0] op_sel_hi:[1,0,1] neg_lo:[1,0,0]
	v_pk_mul_f32 v[32:33], v[34:35], v[122:123] op_sel:[0,0] op_sel_hi:[0,1]
	v_pk_fma_f32 v[48:49], v[88:89], v[138:139], v[48:49] op_sel:[1,1,0] op_sel_hi:[1,0,1] neg_lo:[1,0,0]
	s_nop 0
	v_pk_fma_f32 v[32:33], v[34:35], v[122:123], v[32:33] op_sel:[1,1,0] op_sel_hi:[1,0,1] neg_lo:[1,0,0]
	v_pk_mul_f32 v[34:35], v[36:37], v[124:125] op_sel:[0,0] op_sel_hi:[0,1]
	s_nop 0
	v_pk_fma_f32 v[34:35], v[36:37], v[124:125], v[34:35] op_sel:[1,1,0] op_sel_hi:[1,0,1] neg_lo:[1,0,0]
	v_pk_mul_f32 v[36:37], v[38:39], v[126:127] op_sel:[0,0] op_sel_hi:[0,1]
	s_nop 0
	v_pk_fma_f32 v[36:37], v[38:39], v[126:127], v[36:37] op_sel:[1,1,0] op_sel_hi:[1,0,1] neg_lo:[1,0,0]
	v_pk_mul_f32 v[38:39], v[40:41], v[128:129] op_sel:[0,0] op_sel_hi:[0,1]
	v_mov_b32_e32 v92, v35
	v_pk_fma_f32 v[38:39], v[40:41], v[128:129], v[38:39] op_sel:[1,1,0] op_sel_hi:[1,0,1] neg_lo:[1,0,0]
	v_pk_mul_f32 v[40:41], v[42:43], v[130:131] op_sel:[0,0] op_sel_hi:[0,1]
	s_nop 0
	v_pk_fma_f32 v[40:41], v[42:43], v[130:131], v[40:41] op_sel:[1,1,0] op_sel_hi:[1,0,1] neg_lo:[1,0,0]
	v_pk_mul_f32 v[42:43], v[44:45], v[132:133] op_sel:[0,0] op_sel_hi:[0,1]
	s_nop 0
	v_pk_fma_f32 v[42:43], v[44:45], v[132:133], v[42:43] op_sel:[1,1,0] op_sel_hi:[1,0,1] neg_lo:[1,0,0]
	v_pk_mul_f32 v[44:45], v[46:47], v[134:135] op_sel:[0,0] op_sel_hi:[0,1]
	s_nop 0
	v_pk_fma_f32 v[44:45], v[46:47], v[134:135], v[44:45] op_sel:[1,1,0] op_sel_hi:[1,0,1] neg_lo:[1,0,0]
	v_pk_mul_f32 v[46:47], v[86:87], v[136:137] op_sel:[0,0] op_sel_hi:[0,1]
	v_mov_b32_e32 v93, v43
	v_pk_fma_f32 v[46:47], v[86:87], v[136:137], v[46:47] op_sel:[1,1,0] op_sel_hi:[1,0,1] neg_lo:[1,0,0]
	v_pk_add_f32 v[86:87], v[20:21], v[34:35]
	v_pk_add_f32 v[88:89], v[26:27], v[42:43]
	v_pk_add_f32 v[90:91], v[90:91], v[92:93]
	v_pk_mov_b32 v[92:93], v[20:21], v[26:27] op_sel:[1,0]
	v_pk_mov_b32 v[94:95], v[34:35], v[42:43] op_sel:[1,0]
	v_mov_b32_e32 v21, v27
	v_pk_add_f32 v[92:93], v[92:93], v[94:95] neg_lo:[0,1] neg_hi:[0,1]
	v_mov_b32_e32 v35, v43
	v_mov_b32_e32 v87, v90
	v_mov_b32_e32 v89, v91
	v_pk_add_f32 v[20:21], v[20:21], v[34:35] neg_lo:[0,1] neg_hi:[0,1]
	v_pk_add_f32 v[26:27], v[86:87], v[88:89]
	v_pk_add_f32 v[34:35], v[86:87], v[88:89] neg_lo:[0,1] neg_hi:[0,1]
	v_pk_add_f32 v[86:87], v[92:93], v[92:93] op_sel:[0,1] op_sel_hi:[1,0]
	v_pk_add_f32 v[88:89], v[92:93], v[92:93] op_sel_hi:[0,1] neg_lo:[0,1] neg_hi:[0,1]
	v_pk_add_f32 v[90:91], v[18:19], v[36:37]
	v_pk_add_f32 v[92:93], v[28:29], v[44:45]
	v_pk_add_f32 v[18:19], v[18:19], v[36:37] neg_lo:[0,1] neg_hi:[0,1]
	v_pk_add_f32 v[28:29], v[28:29], v[44:45] neg_lo:[0,1] neg_hi:[0,1]
	v_pk_add_f32 v[44:45], v[30:31], v[46:47]
	v_pk_add_f32 v[36:37], v[18:19], v[28:29] op_sel:[0,1] op_sel_hi:[1,0] neg_lo:[0,1] neg_hi:[0,1]
	v_pk_add_f32 v[18:19], v[18:19], v[28:29] op_sel:[0,1] op_sel_hi:[1,0]
	v_mov_b32_e32 v28, v36
	v_mov_b32_e32 v29, v19
	v_mov_b32_e32 v19, v37
	v_pk_add_f32 v[36:37], v[22:23], v[38:39]
	v_pk_add_f32 v[22:23], v[22:23], v[38:39] neg_lo:[0,1] neg_hi:[0,1]
	v_pk_add_f32 v[30:31], v[30:31], v[46:47] neg_lo:[0,1] neg_hi:[0,1]
	v_pk_add_f32 v[94:95], v[90:91], v[92:93]
	v_pk_add_f32 v[38:39], v[22:23], v[30:31] op_sel:[0,1] op_sel_hi:[1,0] neg_lo:[0,1] neg_hi:[0,1]
	v_pk_add_f32 v[22:23], v[22:23], v[30:31] op_sel:[0,1] op_sel_hi:[1,0]
	v_pk_add_f32 v[90:91], v[90:91], v[92:93] neg_lo:[0,1] neg_hi:[0,1]
	v_pk_add_f32 v[92:93], v[36:37], v[44:45]
	v_pk_add_f32 v[36:37], v[36:37], v[44:45] neg_lo:[0,1] neg_hi:[0,1]
	v_mov_b32_e32 v30, v38
	v_mov_b32_e32 v31, v23
	v_mov_b32_e32 v23, v39
	v_pk_add_f32 v[38:39], v[24:25], v[40:41]
	v_pk_add_f32 v[44:45], v[32:33], v[48:49]
	v_pk_add_f32 v[24:25], v[24:25], v[40:41] neg_lo:[0,1] neg_hi:[0,1]
	v_pk_add_f32 v[46:47], v[38:39], v[44:45]
	v_pk_add_f32 v[38:39], v[38:39], v[44:45] neg_lo:[0,1] neg_hi:[0,1]
	v_pk_add_f32 v[32:33], v[32:33], v[48:49] neg_lo:[0,1] neg_hi:[0,1]
	v_pk_mul_f32 v[44:45], v[36:37], v[56:57] op_sel:[0,0] op_sel_hi:[0,1]
	v_pk_add_f32 v[42:43], v[20:21], v[20:21] op_sel:[0,1] op_sel_hi:[1,0] neg_lo:[0,1] neg_hi:[0,1]
	v_pk_add_f32 v[40:41], v[24:25], v[32:33] op_sel:[0,1] op_sel_hi:[1,0] neg_lo:[0,1] neg_hi:[0,1]
	v_pk_add_f32 v[24:25], v[24:25], v[32:33] op_sel:[0,1] op_sel_hi:[1,0]
	v_pk_fma_f32 v[36:37], v[36:37], v[56:57], v[44:45] op_sel:[1,1,0] op_sel_hi:[1,0,1] neg_lo:[1,0,0]
	v_pk_mul_f32 v[44:45], v[38:39], v[58:59] op_sel:[0,0] op_sel_hi:[0,1]
	v_mov_b32_e32 v32, v40
	v_mov_b32_e32 v33, v25
	v_mov_b32_e32 v25, v41
	v_pk_mul_f32 v[40:41], v[28:29], v[54:55] op_sel:[0,0] op_sel_hi:[0,1]
	v_pk_fma_f32 v[38:39], v[38:39], v[58:59], v[44:45] op_sel:[1,1,0] op_sel_hi:[1,0,1] neg_lo:[1,0,0]
	v_pk_mul_f32 v[44:45], v[18:19], v[50:51] op_sel:[0,0] op_sel_hi:[0,1]
	v_pk_add_f32 v[20:21], v[20:21], v[20:21] op_sel:[0,1] op_sel_hi:[1,0]
	v_pk_fma_f32 v[28:29], v[28:29], v[54:55], v[40:41] op_sel:[1,1,0] op_sel_hi:[1,0,1] neg_lo:[1,0,0]
	v_pk_mul_f32 v[40:41], v[30:31], v[52:53] op_sel:[0,0] op_sel_hi:[0,1]
	v_pk_fma_f32 v[18:19], v[18:19], v[50:51], v[44:45] op_sel:[1,1,0] op_sel_hi:[1,0,1] neg_lo:[1,0,0]
	v_pk_mul_f32 v[44:45], v[22:23], v[58:59] op_sel:[0,0] op_sel_hi:[0,1]
	v_pk_mov_b32 v[48:49], v[92:93], v[46:47] op_sel:[1,0]
	v_pk_fma_f32 v[30:31], v[30:31], v[52:53], v[40:41] op_sel:[1,1,0] op_sel_hi:[1,0,1] neg_lo:[1,0,0]
	v_pk_mul_f32 v[40:41], v[32:33], v[50:51] op_sel:[0,0] op_sel_hi:[0,1]
	v_pk_fma_f32 v[22:23], v[22:23], v[58:59], v[44:45] op_sel:[1,1,0] op_sel_hi:[1,0,1] neg_lo:[1,0,0]
	v_pk_mul_f32 v[44:45], v[24:25], v[60:61] op_sel:[0,0] op_sel_hi:[0,1]
	v_mov_b32_e32 v43, v29
	v_pk_fma_f32 v[32:33], v[32:33], v[50:51], v[40:41] op_sel:[1,1,0] op_sel_hi:[1,0,1] neg_lo:[1,0,0]
	v_mov_b32_e32 v96, v30
	v_mov_b32_e32 v97, v33
	v_pk_mul_f32 v[40:41], v[90:91], v[52:53] op_sel:[0,0] op_sel_hi:[0,1]
	v_pk_fma_f32 v[24:25], v[24:25], v[60:61], v[44:45] op_sel:[1,1,0] op_sel_hi:[1,0,1] neg_lo:[1,0,0]
	v_pk_mov_b32 v[44:45], v[26:27], v[94:95] op_sel:[1,0]
	v_pk_add_f32 v[96:97], v[42:43], v[96:97] neg_lo:[0,1] neg_hi:[0,1]
	v_mov_b32_e32 v43, v86
	v_pk_fma_f32 v[40:41], v[90:91], v[52:53], v[40:41] op_sel:[1,1,0] op_sel_hi:[1,0,1] neg_lo:[1,0,0]
	v_pk_add_f32 v[44:45], v[44:45], v[48:49] neg_lo:[0,1] neg_hi:[0,1]
	v_mov_b32_e32 v48, v26
	v_mov_b32_e32 v49, v95
	v_mov_b32_e32 v90, v92
	v_mov_b32_e32 v91, v47
	v_pk_add_f32 v[46:47], v[94:95], v[46:47]
	v_mov_b32_e32 v87, v28
	v_pk_mov_b32 v[94:95], v[30:31], v[32:33] op_sel:[1,0]
	v_pk_add_f32 v[30:31], v[42:43], v[30:31]
	v_pk_add_f32 v[28:29], v[28:29], v[32:33]
	v_mov_b32_e32 v21, v89
	v_pk_add_f32 v[48:49], v[48:49], v[90:91] neg_lo:[0,1] neg_hi:[0,1]
	v_pk_add_f32 v[26:27], v[26:27], v[92:93]
	v_pk_add_f32 v[94:95], v[86:87], v[94:95] neg_lo:[0,1] neg_hi:[0,1]
	v_pk_add_f32 v[32:33], v[30:31], v[28:29]
	v_pk_add_f32 v[28:29], v[30:31], v[28:29] neg_lo:[0,1] neg_hi:[0,1]
	v_pk_add_f32 v[30:31], v[96:97], v[96:97] op_sel:[0,1] op_sel_hi:[1,0] neg_lo:[0,1] neg_hi:[0,1]
	v_pk_add_f32 v[86:87], v[96:97], v[96:97] op_sel:[0,1] op_sel_hi:[1,0]
	v_pk_add_f32 v[96:97], v[34:35], v[36:37]
	v_pk_add_f32 v[122:123], v[40:41], v[38:39]
	v_pk_add_f32 v[34:35], v[34:35], v[36:37] neg_lo:[0,1] neg_hi:[0,1]
	v_pk_add_f32 v[36:37], v[40:41], v[38:39] neg_lo:[0,1] neg_hi:[0,1]
	v_pk_add_f32 v[40:41], v[20:21], v[22:23]
	v_pk_add_f32 v[88:89], v[18:19], v[24:25]
	v_pk_add_f32 v[20:21], v[20:21], v[22:23] neg_lo:[0,1] neg_hi:[0,1]
	v_pk_add_f32 v[18:19], v[18:19], v[24:25] neg_lo:[0,1] neg_hi:[0,1]
	v_pk_add_f32 v[90:91], v[26:27], v[46:47]
	v_pk_add_f32 v[26:27], v[26:27], v[46:47] neg_lo:[0,1] neg_hi:[0,1]
	v_pk_add_f32 v[46:47], v[48:49], v[48:49] op_sel:[0,1] op_sel_hi:[1,0] neg_lo:[0,1] neg_hi:[0,1]
	v_pk_add_f32 v[92:93], v[44:45], v[44:45] op_sel_hi:[0,1]
	v_pk_add_f32 v[42:43], v[94:95], v[94:95] op_sel_hi:[0,1]
	v_pk_add_f32 v[38:39], v[34:35], v[36:37] op_sel:[0,1] op_sel_hi:[1,0] neg_lo:[0,1] neg_hi:[0,1]
	v_pk_add_f32 v[34:35], v[34:35], v[36:37] op_sel:[0,1] op_sel_hi:[1,0]
	v_pk_add_f32 v[22:23], v[20:21], v[18:19] op_sel:[0,1] op_sel_hi:[1,0] neg_lo:[0,1] neg_hi:[0,1]
	v_pk_add_f32 v[18:19], v[20:21], v[18:19] op_sel:[0,1] op_sel_hi:[1,0]
	v_pk_add_f32 v[48:49], v[48:49], v[48:49] op_sel:[0,1] op_sel_hi:[1,0]
	v_pk_add_f32 v[44:45], v[44:45], v[44:45] op_sel_hi:[0,1] neg_lo:[0,1] neg_hi:[0,1]
	v_pk_add_f32 v[94:95], v[94:95], v[94:95] op_sel_hi:[0,1] neg_lo:[0,1] neg_hi:[0,1]
	v_mov_b32_e32 v37, v35
	v_mov_b32_e32 v21, v19
	v_mov_b32_e32 v47, v93
	v_mov_b32_e32 v31, v43
	v_mov_b32_e32 v35, v39
	v_mov_b32_e32 v19, v23
	v_pk_add_f32 v[124:125], v[96:97], v[122:123]
	v_pk_add_f32 v[96:97], v[96:97], v[122:123] neg_lo:[0,1] neg_hi:[0,1]
	v_mov_b32_e32 v36, v38
	v_pk_add_f32 v[122:123], v[40:41], v[88:89]
	v_pk_add_f32 v[40:41], v[40:41], v[88:89] neg_lo:[0,1] neg_hi:[0,1]
	v_mov_b32_e32 v20, v22
	ds_write2_b64 v73, v[90:91], v[32:33] offset1:4
	ds_write2_b64 v73, v[124:125], v[122:123] offset0:8 offset1:12
	ds_write2_b64 v73, v[46:47], v[30:31] offset0:17 offset1:21
	ds_write2_b64 v73, v[36:37], v[20:21] offset0:25 offset1:29
	ds_write2_b64 v73, v[26:27], v[28:29] offset0:34 offset1:38
	ds_write2_b64 v73, v[96:97], v[40:41] offset0:42 offset1:46
	v_mov_b32_e32 v49, v45
	v_mov_b32_e32 v87, v95
	ds_write2_b64 v73, v[34:35], v[18:19] offset0:59 offset1:63
	v_mov_b32_e32 v18, v0
	ds_write2_b64 v73, v[48:49], v[86:87] offset0:51 offset1:55
	s_waitcnt lgkmcnt(0)
	s_barrier
	s_nop 0
	v_and_b32_e32 v20, 63, v18
	v_lshlrev_b32_e32 v21, 4, v18
	v_cvt_f32_ubyte0_e32 v18, v20
	v_mul_f32_e32 v19, 0x3a800000, v18
	v_cos_f32_e32 v18, v19
	v_sin_f32_e32 v19, v19
	v_and_or_b32 v73, v21, s12, v20
	v_ashrrev_i32_e32 v20, 4, v73
	v_lshlrev_b32_e32 v20, 3, v20
	v_lshlrev_b32_e32 v21, 3, v73
	v_add3_u32 v75, 0, v20, v21
	ds_read2_b64 v[20:23], v75 offset1:68
	ds_read2_b64 v[24:27], v75 offset0:136 offset1:204
	v_add_u32_e32 v78, 0x800, v75
	v_add_u32_e32 v80, 0x1000, v75
	v_add_u32_e32 v144, 0x1800, v75
	v_mov_b32_e32 v48, v18
	v_mov_b32_e32 v49, v19
	ds_read2_b64 v[28:31], v78 offset0:16 offset1:84
	ds_read2_b64 v[32:35], v78 offset0:152 offset1:220
	ds_read2_b64 v[36:39], v80 offset0:32 offset1:100
	ds_read2_b64 v[40:43], v80 offset0:168 offset1:236
	ds_read2_b64 v[44:47], v144 offset0:48 offset1:116
	ds_read2_b64 v[86:89], v144 offset0:184 offset1:252
	s_nop 1
	s_nop 0
	v_pk_mul_f32 v[90:91], v[48:49], v[48:49] op_sel:[0,0] op_sel_hi:[0,1]
	s_waitcnt lgkmcnt(7)
	v_pk_mul_f32 v[142:143], v[22:23], v[48:49] op_sel:[0,0] op_sel_hi:[0,1]
	v_pk_fma_f32 v[90:91], v[48:49], v[48:49], v[90:91] op_sel:[1,1,0] op_sel_hi:[1,0,1] neg_lo:[1,0,0]
	s_nop 0
	v_pk_fma_f32 v[22:23], v[22:23], v[48:49], v[142:143] op_sel:[1,1,0] op_sel_hi:[1,0,1] neg_lo:[1,0,0]
	v_pk_mul_f32 v[94:95], v[90:91], v[90:91] op_sel:[0,0] op_sel_hi:[0,1]
	v_pk_mul_f32 v[92:93], v[90:91], v[48:49] op_sel:[0,0] op_sel_hi:[0,1]
	s_nop 0
	v_pk_fma_f32 v[94:95], v[90:91], v[90:91], v[94:95] op_sel:[1,1,0] op_sel_hi:[1,0,1] neg_lo:[1,0,0]
	v_pk_fma_f32 v[92:93], v[90:91], v[48:49], v[92:93] op_sel:[1,1,0] op_sel_hi:[1,0,1] neg_lo:[1,0,0]
	s_nop 0
	v_pk_mul_f32 v[126:127], v[94:95], v[94:95] op_sel:[0,0] op_sel_hi:[0,1]
	v_pk_mul_f32 v[96:97], v[94:95], v[48:49] op_sel:[0,0] op_sel_hi:[0,1]
	v_pk_mul_f32 v[122:123], v[92:93], v[92:93] op_sel:[0,0] op_sel_hi:[0,1]
	v_pk_mul_f32 v[124:125], v[94:95], v[92:93] op_sel:[0,0] op_sel_hi:[0,1]
	s_nop 0
	v_pk_fma_f32 v[126:127], v[94:95], v[94:95], v[126:127] op_sel:[1,1,0] op_sel_hi:[1,0,1] neg_lo:[1,0,0]
	v_pk_fma_f32 v[96:97], v[94:95], v[48:49], v[96:97] op_sel:[1,1,0] op_sel_hi:[1,0,1] neg_lo:[1,0,0]
	v_pk_fma_f32 v[122:123], v[92:93], v[92:93], v[122:123] op_sel:[1,1,0] op_sel_hi:[1,0,1] neg_lo:[1,0,0]
	v_pk_fma_f32 v[124:125], v[94:95], v[92:93], v[124:125] op_sel:[1,1,0] op_sel_hi:[1,0,1] neg_lo:[1,0,0]
	s_nop 0
	v_pk_mul_f32 v[128:129], v[126:127], v[48:49] op_sel:[0,0] op_sel_hi:[0,1]
	v_pk_mul_f32 v[130:131], v[96:97], v[96:97] op_sel:[0,0] op_sel_hi:[0,1]
	v_pk_mul_f32 v[132:133], v[126:127], v[92:93] op_sel:[0,0] op_sel_hi:[0,1]
	v_pk_mul_f32 v[134:135], v[122:123], v[122:123] op_sel:[0,0] op_sel_hi:[0,1]
	v_pk_mul_f32 v[136:137], v[126:127], v[96:97] op_sel:[0,0] op_sel_hi:[0,1]
	v_pk_mul_f32 v[138:139], v[124:125], v[124:125] op_sel:[0,0] op_sel_hi:[0,1]
	s_nop 0
	v_pk_fma_f32 v[128:129], v[126:127], v[48:49], v[128:129] op_sel:[1,1,0] op_sel_hi:[1,0,1] neg_lo:[1,0,0]
	s_waitcnt lgkmcnt(6)
	v_pk_mul_f32 v[48:49], v[24:25], v[90:91] op_sel:[0,0] op_sel_hi:[0,1]
	v_pk_fma_f32 v[130:131], v[96:97], v[96:97], v[130:131] op_sel:[1,1,0] op_sel_hi:[1,0,1] neg_lo:[1,0,0]
	v_pk_fma_f32 v[132:133], v[126:127], v[92:93], v[132:133] op_sel:[1,1,0] op_sel_hi:[1,0,1] neg_lo:[1,0,0]
	v_pk_fma_f32 v[134:135], v[122:123], v[122:123], v[134:135] op_sel:[1,1,0] op_sel_hi:[1,0,1] neg_lo:[1,0,0]
	v_pk_fma_f32 v[136:137], v[126:127], v[96:97], v[136:137] op_sel:[1,1,0] op_sel_hi:[1,0,1] neg_lo:[1,0,0]
	v_pk_fma_f32 v[138:139], v[124:125], v[124:125], v[138:139] op_sel:[1,1,0] op_sel_hi:[1,0,1] neg_lo:[1,0,0]
	s_nop 0
	v_pk_fma_f32 v[24:25], v[24:25], v[90:91], v[48:49] op_sel:[1,1,0] op_sel_hi:[1,0,1] neg_lo:[1,0,0]
	v_pk_mul_f32 v[48:49], v[26:27], v[92:93] op_sel:[0,0] op_sel_hi:[0,1]
	v_pk_mul_f32 v[140:141], v[126:127], v[124:125] op_sel:[0,0] op_sel_hi:[0,1]
	s_nop 0
	v_pk_fma_f32 v[26:27], v[26:27], v[92:93], v[48:49] op_sel:[1,1,0] op_sel_hi:[1,0,1] neg_lo:[1,0,0]
	s_waitcnt lgkmcnt(5)
	v_pk_mul_f32 v[48:49], v[28:29], v[94:95] op_sel:[0,0] op_sel_hi:[0,1]
	v_pk_fma_f32 v[140:141], v[126:127], v[124:125], v[140:141] op_sel:[1,1,0] op_sel_hi:[1,0,1] neg_lo:[1,0,0]
	v_mov_b32_e32 v92, v21
	v_pk_fma_f32 v[28:29], v[28:29], v[94:95], v[48:49] op_sel:[1,1,0] op_sel_hi:[1,0,1] neg_lo:[1,0,0]
	v_pk_mul_f32 v[48:49], v[30:31], v[96:97] op_sel:[0,0] op_sel_hi:[0,1]
	s_nop 0
	v_pk_fma_f32 v[30:31], v[30:31], v[96:97], v[48:49] op_sel:[1,1,0] op_sel_hi:[1,0,1] neg_lo:[1,0,0]
	s_waitcnt lgkmcnt(4)
	v_pk_mul_f32 v[48:49], v[32:33], v[122:123] op_sel:[0,0] op_sel_hi:[0,1]
	v_mov_b32_e32 v93, v29
	v_pk_fma_f32 v[32:33], v[32:33], v[122:123], v[48:49] op_sel:[1,1,0] op_sel_hi:[1,0,1] neg_lo:[1,0,0]
	v_pk_mul_f32 v[48:49], v[34:35], v[124:125] op_sel:[0,0] op_sel_hi:[0,1]
	s_nop 0
	v_pk_fma_f32 v[34:35], v[34:35], v[124:125], v[48:49] op_sel:[1,1,0] op_sel_hi:[1,0,1] neg_lo:[1,0,0]
	s_waitcnt lgkmcnt(3)
	v_pk_mul_f32 v[48:49], v[36:37], v[126:127] op_sel:[0,0] op_sel_hi:[0,1]
	s_nop 0
	v_pk_fma_f32 v[36:37], v[36:37], v[126:127], v[48:49] op_sel:[1,1,0] op_sel_hi:[1,0,1] neg_lo:[1,0,0]
	v_pk_mul_f32 v[48:49], v[38:39], v[128:129] op_sel:[0,0] op_sel_hi:[0,1]
	s_nop 0
	v_pk_fma_f32 v[38:39], v[38:39], v[128:129], v[48:49] op_sel:[1,1,0] op_sel_hi:[1,0,1] neg_lo:[1,0,0]
	s_waitcnt lgkmcnt(2)
	v_pk_mul_f32 v[48:49], v[40:41], v[130:131] op_sel:[0,0] op_sel_hi:[0,1]
	v_mov_b32_e32 v94, v37
	v_pk_fma_f32 v[40:41], v[40:41], v[130:131], v[48:49] op_sel:[1,1,0] op_sel_hi:[1,0,1] neg_lo:[1,0,0]
	v_pk_mul_f32 v[48:49], v[42:43], v[132:133] op_sel:[0,0] op_sel_hi:[0,1]
	s_nop 0
	v_pk_fma_f32 v[42:43], v[42:43], v[132:133], v[48:49] op_sel:[1,1,0] op_sel_hi:[1,0,1] neg_lo:[1,0,0]
	s_waitcnt lgkmcnt(1)
	v_pk_mul_f32 v[48:49], v[44:45], v[134:135] op_sel:[0,0] op_sel_hi:[0,1]
	s_nop 0
	v_pk_fma_f32 v[44:45], v[44:45], v[134:135], v[48:49] op_sel:[1,1,0] op_sel_hi:[1,0,1] neg_lo:[1,0,0]
	v_pk_mul_f32 v[48:49], v[46:47], v[136:137] op_sel:[0,0] op_sel_hi:[0,1]
	s_nop 0
	v_pk_fma_f32 v[46:47], v[46:47], v[136:137], v[48:49] op_sel:[1,1,0] op_sel_hi:[1,0,1] neg_lo:[1,0,0]
	s_waitcnt lgkmcnt(0)
	v_pk_mul_f32 v[48:49], v[86:87], v[138:139] op_sel:[0,0] op_sel_hi:[0,1]
	v_mov_b32_e32 v95, v45
	v_pk_fma_f32 v[48:49], v[86:87], v[138:139], v[48:49] op_sel:[1,1,0] op_sel_hi:[1,0,1] neg_lo:[1,0,0]
	v_pk_mul_f32 v[86:87], v[88:89], v[140:141] op_sel:[0,0] op_sel_hi:[0,1]
	v_pk_add_f32 v[90:91], v[28:29], v[44:45]
	v_pk_fma_f32 v[86:87], v[88:89], v[140:141], v[86:87] op_sel:[1,1,0] op_sel_hi:[1,0,1] neg_lo:[1,0,0]
	v_pk_add_f32 v[88:89], v[20:21], v[36:37]
	v_pk_add_f32 v[92:93], v[92:93], v[94:95]
	v_pk_mov_b32 v[94:95], v[20:21], v[28:29] op_sel:[1,0]
	v_pk_mov_b32 v[96:97], v[36:37], v[44:45] op_sel:[1,0]
	v_mov_b32_e32 v21, v29
	v_pk_add_f32 v[94:95], v[94:95], v[96:97] neg_lo:[0,1] neg_hi:[0,1]
	v_mov_b32_e32 v37, v45
	v_mov_b32_e32 v89, v92
	v_mov_b32_e32 v91, v93
	v_pk_add_f32 v[20:21], v[20:21], v[36:37] neg_lo:[0,1] neg_hi:[0,1]
	v_pk_add_f32 v[28:29], v[88:89], v[90:91]
	v_pk_add_f32 v[36:37], v[88:89], v[90:91] neg_lo:[0,1] neg_hi:[0,1]
	v_pk_add_f32 v[88:89], v[94:95], v[94:95] op_sel:[0,1] op_sel_hi:[1,0]
	v_pk_add_f32 v[90:91], v[94:95], v[94:95] op_sel_hi:[0,1] neg_lo:[0,1] neg_hi:[0,1]
	v_pk_add_f32 v[92:93], v[22:23], v[38:39]
	v_pk_add_f32 v[94:95], v[30:31], v[46:47]
	v_pk_add_f32 v[22:23], v[22:23], v[38:39] neg_lo:[0,1] neg_hi:[0,1]
	v_pk_add_f32 v[30:31], v[30:31], v[46:47] neg_lo:[0,1] neg_hi:[0,1]
	v_pk_add_f32 v[46:47], v[32:33], v[48:49]
	v_pk_add_f32 v[38:39], v[22:23], v[30:31] op_sel:[0,1] op_sel_hi:[1,0] neg_lo:[0,1] neg_hi:[0,1]
	v_pk_add_f32 v[22:23], v[22:23], v[30:31] op_sel:[0,1] op_sel_hi:[1,0]
	v_mov_b32_e32 v30, v38
	v_mov_b32_e32 v31, v23
	v_mov_b32_e32 v23, v39
	v_pk_add_f32 v[38:39], v[24:25], v[40:41]
	v_pk_add_f32 v[24:25], v[24:25], v[40:41] neg_lo:[0,1] neg_hi:[0,1]
	v_pk_add_f32 v[32:33], v[32:33], v[48:49] neg_lo:[0,1] neg_hi:[0,1]
	v_pk_add_f32 v[96:97], v[92:93], v[94:95]
	v_pk_add_f32 v[40:41], v[24:25], v[32:33] op_sel:[0,1] op_sel_hi:[1,0] neg_lo:[0,1] neg_hi:[0,1]
	v_pk_add_f32 v[24:25], v[24:25], v[32:33] op_sel:[0,1] op_sel_hi:[1,0]
	v_pk_add_f32 v[92:93], v[92:93], v[94:95] neg_lo:[0,1] neg_hi:[0,1]
	v_pk_add_f32 v[94:95], v[38:39], v[46:47]
	v_pk_add_f32 v[38:39], v[38:39], v[46:47] neg_lo:[0,1] neg_hi:[0,1]
	v_mov_b32_e32 v32, v40
	v_mov_b32_e32 v33, v25
	v_mov_b32_e32 v25, v41
	v_pk_add_f32 v[40:41], v[26:27], v[42:43]
	v_pk_add_f32 v[46:47], v[34:35], v[86:87]
	v_pk_add_f32 v[26:27], v[26:27], v[42:43] neg_lo:[0,1] neg_hi:[0,1]
	v_pk_add_f32 v[48:49], v[40:41], v[46:47]
	v_pk_add_f32 v[40:41], v[40:41], v[46:47] neg_lo:[0,1] neg_hi:[0,1]
	v_pk_add_f32 v[34:35], v[34:35], v[86:87] neg_lo:[0,1] neg_hi:[0,1]
	v_pk_mul_f32 v[46:47], v[38:39], v[56:57] op_sel:[0,0] op_sel_hi:[0,1]
	v_pk_add_f32 v[44:45], v[20:21], v[20:21] op_sel:[0,1] op_sel_hi:[1,0] neg_lo:[0,1] neg_hi:[0,1]
	v_pk_add_f32 v[42:43], v[26:27], v[34:35] op_sel:[0,1] op_sel_hi:[1,0] neg_lo:[0,1] neg_hi:[0,1]
	v_pk_add_f32 v[26:27], v[26:27], v[34:35] op_sel:[0,1] op_sel_hi:[1,0]
	v_pk_fma_f32 v[38:39], v[38:39], v[56:57], v[46:47] op_sel:[1,1,0] op_sel_hi:[1,0,1] neg_lo:[1,0,0]
	v_pk_mul_f32 v[46:47], v[40:41], v[58:59] op_sel:[0,0] op_sel_hi:[0,1]
	v_mov_b32_e32 v34, v42
	v_mov_b32_e32 v35, v27
	v_mov_b32_e32 v27, v43
	v_pk_mul_f32 v[42:43], v[30:31], v[54:55] op_sel:[0,0] op_sel_hi:[0,1]
	v_pk_fma_f32 v[40:41], v[40:41], v[58:59], v[46:47] op_sel:[1,1,0] op_sel_hi:[1,0,1] neg_lo:[1,0,0]
	v_pk_mul_f32 v[46:47], v[22:23], v[50:51] op_sel:[0,0] op_sel_hi:[0,1]
	v_pk_add_f32 v[20:21], v[20:21], v[20:21] op_sel:[0,1] op_sel_hi:[1,0]
	v_pk_fma_f32 v[30:31], v[30:31], v[54:55], v[42:43] op_sel:[1,1,0] op_sel_hi:[1,0,1] neg_lo:[1,0,0]
	v_pk_mul_f32 v[42:43], v[32:33], v[52:53] op_sel:[0,0] op_sel_hi:[0,1]
	v_pk_fma_f32 v[22:23], v[22:23], v[50:51], v[46:47] op_sel:[1,1,0] op_sel_hi:[1,0,1] neg_lo:[1,0,0]
	v_pk_mul_f32 v[46:47], v[24:25], v[58:59] op_sel:[0,0] op_sel_hi:[0,1]
	v_pk_mov_b32 v[86:87], v[94:95], v[48:49] op_sel:[1,0]
	v_pk_fma_f32 v[32:33], v[32:33], v[52:53], v[42:43] op_sel:[1,1,0] op_sel_hi:[1,0,1] neg_lo:[1,0,0]
	v_pk_mul_f32 v[42:43], v[34:35], v[50:51] op_sel:[0,0] op_sel_hi:[0,1]
	v_pk_fma_f32 v[24:25], v[24:25], v[58:59], v[46:47] op_sel:[1,1,0] op_sel_hi:[1,0,1] neg_lo:[1,0,0]
	v_pk_mul_f32 v[46:47], v[26:27], v[60:61] op_sel:[0,0] op_sel_hi:[0,1]
	v_mov_b32_e32 v45, v31
	v_pk_fma_f32 v[34:35], v[34:35], v[50:51], v[42:43] op_sel:[1,1,0] op_sel_hi:[1,0,1] neg_lo:[1,0,0]
	v_mov_b32_e32 v122, v32
	v_mov_b32_e32 v123, v35
	v_pk_mul_f32 v[42:43], v[92:93], v[52:53] op_sel:[0,0] op_sel_hi:[0,1]
	v_pk_fma_f32 v[26:27], v[26:27], v[60:61], v[46:47] op_sel:[1,1,0] op_sel_hi:[1,0,1] neg_lo:[1,0,0]
	v_pk_mov_b32 v[46:47], v[28:29], v[96:97] op_sel:[1,0]
	v_pk_add_f32 v[122:123], v[44:45], v[122:123] neg_lo:[0,1] neg_hi:[0,1]
	v_mov_b32_e32 v45, v88
	v_pk_fma_f32 v[42:43], v[92:93], v[52:53], v[42:43] op_sel:[1,1,0] op_sel_hi:[1,0,1] neg_lo:[1,0,0]
	v_pk_add_f32 v[46:47], v[46:47], v[86:87] neg_lo:[0,1] neg_hi:[0,1]
	v_mov_b32_e32 v86, v28
	v_mov_b32_e32 v87, v97
	v_mov_b32_e32 v92, v94
	v_mov_b32_e32 v93, v49
	v_pk_add_f32 v[48:49], v[96:97], v[48:49]
	v_mov_b32_e32 v89, v30
	v_pk_mov_b32 v[96:97], v[32:33], v[34:35] op_sel:[1,0]
	v_pk_add_f32 v[32:33], v[44:45], v[32:33]
	v_pk_add_f32 v[30:31], v[30:31], v[34:35]
	v_mov_b32_e32 v21, v91
	v_pk_add_f32 v[86:87], v[86:87], v[92:93] neg_lo:[0,1] neg_hi:[0,1]
	v_pk_add_f32 v[28:29], v[28:29], v[94:95]
	v_pk_add_f32 v[96:97], v[88:89], v[96:97] neg_lo:[0,1] neg_hi:[0,1]
	v_pk_add_f32 v[34:35], v[32:33], v[30:31]
	v_pk_add_f32 v[30:31], v[32:33], v[30:31] neg_lo:[0,1] neg_hi:[0,1]
	v_pk_add_f32 v[32:33], v[122:123], v[122:123] op_sel:[0,1] op_sel_hi:[1,0] neg_lo:[0,1] neg_hi:[0,1]
	v_pk_add_f32 v[88:89], v[122:123], v[122:123] op_sel:[0,1] op_sel_hi:[1,0]
	v_pk_add_f32 v[122:123], v[36:37], v[38:39]
	v_pk_add_f32 v[124:125], v[42:43], v[40:41]
	v_pk_add_f32 v[36:37], v[36:37], v[38:39] neg_lo:[0,1] neg_hi:[0,1]
	v_pk_add_f32 v[38:39], v[42:43], v[40:41] neg_lo:[0,1] neg_hi:[0,1]
	v_pk_add_f32 v[42:43], v[20:21], v[24:25]
	v_pk_add_f32 v[90:91], v[22:23], v[26:27]
	v_pk_add_f32 v[20:21], v[20:21], v[24:25] neg_lo:[0,1] neg_hi:[0,1]
	v_pk_add_f32 v[22:23], v[22:23], v[26:27] neg_lo:[0,1] neg_hi:[0,1]
	v_pk_add_f32 v[92:93], v[28:29], v[48:49]
	v_pk_add_f32 v[28:29], v[28:29], v[48:49] neg_lo:[0,1] neg_hi:[0,1]
	v_pk_add_f32 v[48:49], v[86:87], v[86:87] op_sel:[0,1] op_sel_hi:[1,0] neg_lo:[0,1] neg_hi:[0,1]
	v_pk_add_f32 v[94:95], v[46:47], v[46:47] op_sel_hi:[0,1]
	v_pk_add_f32 v[44:45], v[96:97], v[96:97] op_sel_hi:[0,1]
	v_pk_add_f32 v[40:41], v[36:37], v[38:39] op_sel:[0,1] op_sel_hi:[1,0] neg_lo:[0,1] neg_hi:[0,1]
	v_pk_add_f32 v[36:37], v[36:37], v[38:39] op_sel:[0,1] op_sel_hi:[1,0]
	v_pk_add_f32 v[24:25], v[20:21], v[22:23] op_sel:[0,1] op_sel_hi:[1,0] neg_lo:[0,1] neg_hi:[0,1]
	v_pk_add_f32 v[20:21], v[20:21], v[22:23] op_sel:[0,1] op_sel_hi:[1,0]
	v_mov_b32_e32 v39, v37
	v_mov_b32_e32 v23, v21
	v_mov_b32_e32 v49, v95
	v_mov_b32_e32 v33, v45
	v_mov_b32_e32 v37, v41
	v_mov_b32_e32 v21, v25
	v_pk_add_f32 v[126:127], v[122:123], v[124:125]
	v_pk_add_f32 v[122:123], v[122:123], v[124:125] neg_lo:[0,1] neg_hi:[0,1]
	v_mov_b32_e32 v38, v40
	v_pk_add_f32 v[124:125], v[42:43], v[90:91]
	v_pk_add_f32 v[42:43], v[42:43], v[90:91] neg_lo:[0,1] neg_hi:[0,1]
	v_mov_b32_e32 v22, v24
	ds_write2_b64 v75, v[92:93], v[34:35] offset1:68
	ds_write2_b64 v75, v[126:127], v[124:125] offset0:136 offset1:204
	ds_write2_b64 v78, v[48:49], v[32:33] offset0:16 offset1:84
	ds_write2_b64 v78, v[38:39], v[22:23] offset0:152 offset1:220
	ds_write2_b64 v80, v[28:29], v[30:31] offset0:32 offset1:100
	ds_write2_b64 v80, v[122:123], v[42:43] offset0:168 offset1:236
	ds_write2_b64 v144, v[36:37], v[20:21] offset0:184 offset1:252
	v_add_u32_e32 v20, 0x2000, v73
	v_pk_add_f32 v[86:87], v[86:87], v[86:87] op_sel:[0,1] op_sel_hi:[1,0]
	v_pk_add_f32 v[46:47], v[46:47], v[46:47] op_sel_hi:[0,1] neg_lo:[0,1] neg_hi:[0,1]
	v_pk_add_f32 v[96:97], v[96:97], v[96:97] op_sel_hi:[0,1] neg_lo:[0,1] neg_hi:[0,1]
	v_ashrrev_i32_e32 v21, 4, v20
	v_mov_b32_e32 v87, v47
	v_mov_b32_e32 v89, v97
	v_lshlrev_b32_e32 v21, 3, v21
	v_lshlrev_b32_e32 v20, 3, v20
	ds_write2_b64 v144, v[86:87], v[88:89] offset0:48 offset1:116
	v_add3_u32 v73, 0, v21, v20
	ds_read2_b64 v[20:23], v73 offset1:68
	ds_read2_b64 v[24:27], v73 offset0:136 offset1:204
	v_add_u32_e32 v75, 0x800, v73
	v_add_u32_e32 v78, 0x1000, v73
	v_add_u32_e32 v80, 0x1800, v73
	ds_read2_b64 v[28:31], v75 offset0:16 offset1:84
	ds_read2_b64 v[32:35], v75 offset0:152 offset1:220
	ds_read2_b64 v[36:39], v78 offset0:32 offset1:100
	ds_read2_b64 v[40:43], v78 offset0:168 offset1:236
	ds_read2_b64 v[44:47], v80 offset0:48 offset1:116
	ds_read2_b64 v[86:89], v80 offset0:184 offset1:252
	s_nop 1
	s_nop 0
	v_pk_mul_f32 v[48:49], v[18:19], v[18:19] op_sel:[0,0] op_sel_hi:[0,1]
	s_waitcnt lgkmcnt(7)
	v_pk_mul_f32 v[140:141], v[22:23], v[18:19] op_sel:[0,0] op_sel_hi:[0,1]
	v_pk_fma_f32 v[48:49], v[18:19], v[18:19], v[48:49] op_sel:[1,1,0] op_sel_hi:[1,0,1] neg_lo:[1,0,0]
	s_nop 0
	v_pk_mul_f32 v[92:93], v[48:49], v[48:49] op_sel:[0,0] op_sel_hi:[0,1]
	v_pk_mul_f32 v[90:91], v[48:49], v[18:19] op_sel:[0,0] op_sel_hi:[0,1]
	s_nop 0
	v_pk_fma_f32 v[92:93], v[48:49], v[48:49], v[92:93] op_sel:[1,1,0] op_sel_hi:[1,0,1] neg_lo:[1,0,0]
	v_pk_fma_f32 v[90:91], v[48:49], v[18:19], v[90:91] op_sel:[1,1,0] op_sel_hi:[1,0,1] neg_lo:[1,0,0]
	s_nop 0
	v_pk_mul_f32 v[124:125], v[92:93], v[92:93] op_sel:[0,0] op_sel_hi:[0,1]
	v_pk_mul_f32 v[94:95], v[92:93], v[18:19] op_sel:[0,0] op_sel_hi:[0,1]
	v_pk_mul_f32 v[96:97], v[90:91], v[90:91] op_sel:[0,0] op_sel_hi:[0,1]
	v_pk_mul_f32 v[122:123], v[92:93], v[90:91] op_sel:[0,0] op_sel_hi:[0,1]
	s_nop 0
	v_pk_fma_f32 v[124:125], v[92:93], v[92:93], v[124:125] op_sel:[1,1,0] op_sel_hi:[1,0,1] neg_lo:[1,0,0]
	v_pk_fma_f32 v[94:95], v[92:93], v[18:19], v[94:95] op_sel:[1,1,0] op_sel_hi:[1,0,1] neg_lo:[1,0,0]
	v_pk_fma_f32 v[96:97], v[90:91], v[90:91], v[96:97] op_sel:[1,1,0] op_sel_hi:[1,0,1] neg_lo:[1,0,0]
	v_pk_fma_f32 v[122:123], v[92:93], v[90:91], v[122:123] op_sel:[1,1,0] op_sel_hi:[1,0,1] neg_lo:[1,0,0]
	s_nop 0
	v_pk_mul_f32 v[126:127], v[124:125], v[18:19] op_sel:[0,0] op_sel_hi:[0,1]
	v_pk_mul_f32 v[128:129], v[94:95], v[94:95] op_sel:[0,0] op_sel_hi:[0,1]
	v_pk_mul_f32 v[130:131], v[124:125], v[90:91] op_sel:[0,0] op_sel_hi:[0,1]
	v_pk_mul_f32 v[132:133], v[96:97], v[96:97] op_sel:[0,0] op_sel_hi:[0,1]
	v_pk_mul_f32 v[134:135], v[124:125], v[94:95] op_sel:[0,0] op_sel_hi:[0,1]
	v_pk_mul_f32 v[136:137], v[122:123], v[122:123] op_sel:[0,0] op_sel_hi:[0,1]
	s_nop 0
	v_pk_fma_f32 v[126:127], v[124:125], v[18:19], v[126:127] op_sel:[1,1,0] op_sel_hi:[1,0,1] neg_lo:[1,0,0]
	v_pk_fma_f32 v[18:19], v[22:23], v[18:19], v[140:141] op_sel:[1,1,0] op_sel_hi:[1,0,1] neg_lo:[1,0,0]
	s_waitcnt lgkmcnt(6)
	v_pk_mul_f32 v[22:23], v[24:25], v[48:49] op_sel:[0,0] op_sel_hi:[0,1]
	v_pk_fma_f32 v[128:129], v[94:95], v[94:95], v[128:129] op_sel:[1,1,0] op_sel_hi:[1,0,1] neg_lo:[1,0,0]
	v_pk_fma_f32 v[130:131], v[124:125], v[90:91], v[130:131] op_sel:[1,1,0] op_sel_hi:[1,0,1] neg_lo:[1,0,0]
	v_pk_fma_f32 v[132:133], v[96:97], v[96:97], v[132:133] op_sel:[1,1,0] op_sel_hi:[1,0,1] neg_lo:[1,0,0]
	v_pk_fma_f32 v[134:135], v[124:125], v[94:95], v[134:135] op_sel:[1,1,0] op_sel_hi:[1,0,1] neg_lo:[1,0,0]
	v_pk_mul_f32 v[138:139], v[124:125], v[122:123] op_sel:[0,0] op_sel_hi:[0,1]
	s_nop 0
	v_pk_fma_f32 v[22:23], v[24:25], v[48:49], v[22:23] op_sel:[1,1,0] op_sel_hi:[1,0,1] neg_lo:[1,0,0]
	v_pk_mul_f32 v[24:25], v[26:27], v[90:91] op_sel:[0,0] op_sel_hi:[0,1]
	v_pk_fma_f32 v[136:137], v[122:123], v[122:123], v[136:137] op_sel:[1,1,0] op_sel_hi:[1,0,1] neg_lo:[1,0,0]
	s_nop 0
	v_pk_fma_f32 v[24:25], v[26:27], v[90:91], v[24:25] op_sel:[1,1,0] op_sel_hi:[1,0,1] neg_lo:[1,0,0]
	s_waitcnt lgkmcnt(5)
	v_pk_mul_f32 v[26:27], v[28:29], v[92:93] op_sel:[0,0] op_sel_hi:[0,1]
	v_pk_fma_f32 v[138:139], v[124:125], v[122:123], v[138:139] op_sel:[1,1,0] op_sel_hi:[1,0,1] neg_lo:[1,0,0]
	v_mov_b32_e32 v90, v21
	v_pk_fma_f32 v[26:27], v[28:29], v[92:93], v[26:27] op_sel:[1,1,0] op_sel_hi:[1,0,1] neg_lo:[1,0,0]
	v_pk_mul_f32 v[28:29], v[30:31], v[94:95] op_sel:[0,0] op_sel_hi:[0,1]
	s_waitcnt lgkmcnt(0)
	v_pk_mul_f32 v[48:49], v[88:89], v[138:139] op_sel:[0,0] op_sel_hi:[0,1]
	v_pk_fma_f32 v[28:29], v[30:31], v[94:95], v[28:29] op_sel:[1,1,0] op_sel_hi:[1,0,1] neg_lo:[1,0,0]
	v_pk_mul_f32 v[30:31], v[32:33], v[96:97] op_sel:[0,0] op_sel_hi:[0,1]
	v_mov_b32_e32 v91, v27
	v_pk_fma_f32 v[30:31], v[32:33], v[96:97], v[30:31] op_sel:[1,1,0] op_sel_hi:[1,0,1] neg_lo:[1,0,0]
	v_pk_mul_f32 v[32:33], v[34:35], v[122:123] op_sel:[0,0] op_sel_hi:[0,1]
	v_pk_fma_f32 v[48:49], v[88:89], v[138:139], v[48:49] op_sel:[1,1,0] op_sel_hi:[1,0,1] neg_lo:[1,0,0]
	s_nop 0
	v_pk_fma_f32 v[32:33], v[34:35], v[122:123], v[32:33] op_sel:[1,1,0] op_sel_hi:[1,0,1] neg_lo:[1,0,0]
	v_pk_mul_f32 v[34:35], v[36:37], v[124:125] op_sel:[0,0] op_sel_hi:[0,1]
	s_nop 0
	v_pk_fma_f32 v[34:35], v[36:37], v[124:125], v[34:35] op_sel:[1,1,0] op_sel_hi:[1,0,1] neg_lo:[1,0,0]
	v_pk_mul_f32 v[36:37], v[38:39], v[126:127] op_sel:[0,0] op_sel_hi:[0,1]
	s_nop 0
	v_pk_fma_f32 v[36:37], v[38:39], v[126:127], v[36:37] op_sel:[1,1,0] op_sel_hi:[1,0,1] neg_lo:[1,0,0]
	v_pk_mul_f32 v[38:39], v[40:41], v[128:129] op_sel:[0,0] op_sel_hi:[0,1]
	v_mov_b32_e32 v92, v35
	v_pk_fma_f32 v[38:39], v[40:41], v[128:129], v[38:39] op_sel:[1,1,0] op_sel_hi:[1,0,1] neg_lo:[1,0,0]
	v_pk_mul_f32 v[40:41], v[42:43], v[130:131] op_sel:[0,0] op_sel_hi:[0,1]
	s_nop 0
	v_pk_fma_f32 v[40:41], v[42:43], v[130:131], v[40:41] op_sel:[1,1,0] op_sel_hi:[1,0,1] neg_lo:[1,0,0]
	v_pk_mul_f32 v[42:43], v[44:45], v[132:133] op_sel:[0,0] op_sel_hi:[0,1]
	s_nop 0
	v_pk_fma_f32 v[42:43], v[44:45], v[132:133], v[42:43] op_sel:[1,1,0] op_sel_hi:[1,0,1] neg_lo:[1,0,0]
	v_pk_mul_f32 v[44:45], v[46:47], v[134:135] op_sel:[0,0] op_sel_hi:[0,1]
	s_nop 0
	v_pk_fma_f32 v[44:45], v[46:47], v[134:135], v[44:45] op_sel:[1,1,0] op_sel_hi:[1,0,1] neg_lo:[1,0,0]
	v_pk_mul_f32 v[46:47], v[86:87], v[136:137] op_sel:[0,0] op_sel_hi:[0,1]
	v_mov_b32_e32 v93, v43
	v_pk_fma_f32 v[46:47], v[86:87], v[136:137], v[46:47] op_sel:[1,1,0] op_sel_hi:[1,0,1] neg_lo:[1,0,0]
	v_pk_add_f32 v[86:87], v[20:21], v[34:35]
	v_pk_add_f32 v[88:89], v[26:27], v[42:43]
	v_pk_add_f32 v[90:91], v[90:91], v[92:93]
	v_pk_mov_b32 v[92:93], v[20:21], v[26:27] op_sel:[1,0]
	v_pk_mov_b32 v[94:95], v[34:35], v[42:43] op_sel:[1,0]
	v_mov_b32_e32 v21, v27
	v_pk_add_f32 v[92:93], v[92:93], v[94:95] neg_lo:[0,1] neg_hi:[0,1]
	v_mov_b32_e32 v35, v43
	v_mov_b32_e32 v87, v90
	v_mov_b32_e32 v89, v91
	v_pk_add_f32 v[20:21], v[20:21], v[34:35] neg_lo:[0,1] neg_hi:[0,1]
	v_pk_add_f32 v[26:27], v[86:87], v[88:89]
	v_pk_add_f32 v[34:35], v[86:87], v[88:89] neg_lo:[0,1] neg_hi:[0,1]
	v_pk_add_f32 v[86:87], v[92:93], v[92:93] op_sel:[0,1] op_sel_hi:[1,0]
	v_pk_add_f32 v[88:89], v[92:93], v[92:93] op_sel_hi:[0,1] neg_lo:[0,1] neg_hi:[0,1]
	v_pk_add_f32 v[90:91], v[18:19], v[36:37]
	v_pk_add_f32 v[92:93], v[28:29], v[44:45]
	v_pk_add_f32 v[18:19], v[18:19], v[36:37] neg_lo:[0,1] neg_hi:[0,1]
	v_pk_add_f32 v[28:29], v[28:29], v[44:45] neg_lo:[0,1] neg_hi:[0,1]
	v_pk_add_f32 v[44:45], v[30:31], v[46:47]
	v_pk_add_f32 v[36:37], v[18:19], v[28:29] op_sel:[0,1] op_sel_hi:[1,0] neg_lo:[0,1] neg_hi:[0,1]
	v_pk_add_f32 v[18:19], v[18:19], v[28:29] op_sel:[0,1] op_sel_hi:[1,0]
	v_mov_b32_e32 v28, v36
	v_mov_b32_e32 v29, v19
	v_mov_b32_e32 v19, v37
	v_pk_add_f32 v[36:37], v[22:23], v[38:39]
	v_pk_add_f32 v[22:23], v[22:23], v[38:39] neg_lo:[0,1] neg_hi:[0,1]
	v_pk_add_f32 v[30:31], v[30:31], v[46:47] neg_lo:[0,1] neg_hi:[0,1]
	v_pk_add_f32 v[94:95], v[90:91], v[92:93]
	v_pk_add_f32 v[38:39], v[22:23], v[30:31] op_sel:[0,1] op_sel_hi:[1,0] neg_lo:[0,1] neg_hi:[0,1]
	v_pk_add_f32 v[22:23], v[22:23], v[30:31] op_sel:[0,1] op_sel_hi:[1,0]
	v_pk_add_f32 v[90:91], v[90:91], v[92:93] neg_lo:[0,1] neg_hi:[0,1]
	v_pk_add_f32 v[92:93], v[36:37], v[44:45]
	v_pk_add_f32 v[36:37], v[36:37], v[44:45] neg_lo:[0,1] neg_hi:[0,1]
	v_mov_b32_e32 v30, v38
	v_mov_b32_e32 v31, v23
	v_mov_b32_e32 v23, v39
	v_pk_add_f32 v[38:39], v[24:25], v[40:41]
	v_pk_add_f32 v[44:45], v[32:33], v[48:49]
	v_pk_add_f32 v[24:25], v[24:25], v[40:41] neg_lo:[0,1] neg_hi:[0,1]
	v_pk_add_f32 v[46:47], v[38:39], v[44:45]
	v_pk_add_f32 v[38:39], v[38:39], v[44:45] neg_lo:[0,1] neg_hi:[0,1]
	v_pk_add_f32 v[32:33], v[32:33], v[48:49] neg_lo:[0,1] neg_hi:[0,1]
	v_pk_mul_f32 v[44:45], v[36:37], v[56:57] op_sel:[0,0] op_sel_hi:[0,1]
	v_pk_add_f32 v[42:43], v[20:21], v[20:21] op_sel:[0,1] op_sel_hi:[1,0] neg_lo:[0,1] neg_hi:[0,1]
	v_pk_add_f32 v[40:41], v[24:25], v[32:33] op_sel:[0,1] op_sel_hi:[1,0] neg_lo:[0,1] neg_hi:[0,1]
	v_pk_add_f32 v[24:25], v[24:25], v[32:33] op_sel:[0,1] op_sel_hi:[1,0]
	v_pk_fma_f32 v[36:37], v[36:37], v[56:57], v[44:45] op_sel:[1,1,0] op_sel_hi:[1,0,1] neg_lo:[1,0,0]
	v_pk_mul_f32 v[44:45], v[38:39], v[58:59] op_sel:[0,0] op_sel_hi:[0,1]
	v_mov_b32_e32 v32, v40
	v_mov_b32_e32 v33, v25
	v_mov_b32_e32 v25, v41
	v_pk_mul_f32 v[40:41], v[28:29], v[54:55] op_sel:[0,0] op_sel_hi:[0,1]
	v_pk_fma_f32 v[38:39], v[38:39], v[58:59], v[44:45] op_sel:[1,1,0] op_sel_hi:[1,0,1] neg_lo:[1,0,0]
	v_pk_mul_f32 v[44:45], v[18:19], v[50:51] op_sel:[0,0] op_sel_hi:[0,1]
	v_pk_add_f32 v[20:21], v[20:21], v[20:21] op_sel:[0,1] op_sel_hi:[1,0]
	v_pk_fma_f32 v[28:29], v[28:29], v[54:55], v[40:41] op_sel:[1,1,0] op_sel_hi:[1,0,1] neg_lo:[1,0,0]
	v_pk_mul_f32 v[40:41], v[30:31], v[52:53] op_sel:[0,0] op_sel_hi:[0,1]
	v_pk_fma_f32 v[18:19], v[18:19], v[50:51], v[44:45] op_sel:[1,1,0] op_sel_hi:[1,0,1] neg_lo:[1,0,0]
	v_pk_mul_f32 v[44:45], v[22:23], v[58:59] op_sel:[0,0] op_sel_hi:[0,1]
	v_pk_mov_b32 v[48:49], v[92:93], v[46:47] op_sel:[1,0]
	v_pk_fma_f32 v[30:31], v[30:31], v[52:53], v[40:41] op_sel:[1,1,0] op_sel_hi:[1,0,1] neg_lo:[1,0,0]
	v_pk_mul_f32 v[40:41], v[32:33], v[50:51] op_sel:[0,0] op_sel_hi:[0,1]
	v_pk_fma_f32 v[22:23], v[22:23], v[58:59], v[44:45] op_sel:[1,1,0] op_sel_hi:[1,0,1] neg_lo:[1,0,0]
	v_pk_mul_f32 v[44:45], v[24:25], v[60:61] op_sel:[0,0] op_sel_hi:[0,1]
	v_mov_b32_e32 v43, v29
	v_pk_fma_f32 v[32:33], v[32:33], v[50:51], v[40:41] op_sel:[1,1,0] op_sel_hi:[1,0,1] neg_lo:[1,0,0]
	v_mov_b32_e32 v96, v30
	v_mov_b32_e32 v97, v33
	v_pk_mul_f32 v[40:41], v[90:91], v[52:53] op_sel:[0,0] op_sel_hi:[0,1]
	v_pk_fma_f32 v[24:25], v[24:25], v[60:61], v[44:45] op_sel:[1,1,0] op_sel_hi:[1,0,1] neg_lo:[1,0,0]
	v_pk_mov_b32 v[44:45], v[26:27], v[94:95] op_sel:[1,0]
	v_pk_add_f32 v[96:97], v[42:43], v[96:97] neg_lo:[0,1] neg_hi:[0,1]
	v_mov_b32_e32 v43, v86
	v_pk_fma_f32 v[40:41], v[90:91], v[52:53], v[40:41] op_sel:[1,1,0] op_sel_hi:[1,0,1] neg_lo:[1,0,0]
	v_pk_add_f32 v[44:45], v[44:45], v[48:49] neg_lo:[0,1] neg_hi:[0,1]
	v_mov_b32_e32 v48, v26
	v_mov_b32_e32 v49, v95
	v_mov_b32_e32 v90, v92
	v_mov_b32_e32 v91, v47
	v_pk_add_f32 v[46:47], v[94:95], v[46:47]
	v_mov_b32_e32 v87, v28
	v_pk_mov_b32 v[94:95], v[30:31], v[32:33] op_sel:[1,0]
	v_pk_add_f32 v[30:31], v[42:43], v[30:31]
	v_pk_add_f32 v[28:29], v[28:29], v[32:33]
	v_mov_b32_e32 v21, v89
	v_pk_add_f32 v[48:49], v[48:49], v[90:91] neg_lo:[0,1] neg_hi:[0,1]
	v_pk_add_f32 v[26:27], v[26:27], v[92:93]
	v_pk_add_f32 v[94:95], v[86:87], v[94:95] neg_lo:[0,1] neg_hi:[0,1]
	v_pk_add_f32 v[32:33], v[30:31], v[28:29]
	v_pk_add_f32 v[28:29], v[30:31], v[28:29] neg_lo:[0,1] neg_hi:[0,1]
	v_pk_add_f32 v[30:31], v[96:97], v[96:97] op_sel:[0,1] op_sel_hi:[1,0] neg_lo:[0,1] neg_hi:[0,1]
	v_pk_add_f32 v[86:87], v[96:97], v[96:97] op_sel:[0,1] op_sel_hi:[1,0]
	v_pk_add_f32 v[96:97], v[34:35], v[36:37]
	v_pk_add_f32 v[122:123], v[40:41], v[38:39]
	v_pk_add_f32 v[34:35], v[34:35], v[36:37] neg_lo:[0,1] neg_hi:[0,1]
	v_pk_add_f32 v[36:37], v[40:41], v[38:39] neg_lo:[0,1] neg_hi:[0,1]
	v_pk_add_f32 v[40:41], v[20:21], v[22:23]
	v_pk_add_f32 v[88:89], v[18:19], v[24:25]
	v_pk_add_f32 v[20:21], v[20:21], v[22:23] neg_lo:[0,1] neg_hi:[0,1]
	v_pk_add_f32 v[18:19], v[18:19], v[24:25] neg_lo:[0,1] neg_hi:[0,1]
	v_pk_add_f32 v[90:91], v[26:27], v[46:47]
	v_pk_add_f32 v[26:27], v[26:27], v[46:47] neg_lo:[0,1] neg_hi:[0,1]
	v_pk_add_f32 v[46:47], v[48:49], v[48:49] op_sel:[0,1] op_sel_hi:[1,0] neg_lo:[0,1] neg_hi:[0,1]
	v_pk_add_f32 v[92:93], v[44:45], v[44:45] op_sel_hi:[0,1]
	v_pk_add_f32 v[48:49], v[48:49], v[48:49] op_sel:[0,1] op_sel_hi:[1,0]
	v_pk_add_f32 v[44:45], v[44:45], v[44:45] op_sel_hi:[0,1] neg_lo:[0,1] neg_hi:[0,1]
	v_pk_add_f32 v[42:43], v[94:95], v[94:95] op_sel_hi:[0,1]
	v_pk_add_f32 v[94:95], v[94:95], v[94:95] op_sel_hi:[0,1] neg_lo:[0,1] neg_hi:[0,1]
	v_pk_add_f32 v[38:39], v[34:35], v[36:37] op_sel:[0,1] op_sel_hi:[1,0] neg_lo:[0,1] neg_hi:[0,1]
	v_pk_add_f32 v[34:35], v[34:35], v[36:37] op_sel:[0,1] op_sel_hi:[1,0]
	v_pk_add_f32 v[22:23], v[20:21], v[18:19] op_sel:[0,1] op_sel_hi:[1,0] neg_lo:[0,1] neg_hi:[0,1]
	v_pk_add_f32 v[18:19], v[20:21], v[18:19] op_sel:[0,1] op_sel_hi:[1,0]
	v_pk_add_f32 v[124:125], v[96:97], v[122:123]
	v_pk_add_f32 v[96:97], v[96:97], v[122:123] neg_lo:[0,1] neg_hi:[0,1]
	v_mov_b32_e32 v37, v35
	v_pk_add_f32 v[122:123], v[40:41], v[88:89]
	v_mov_b32_e32 v21, v19
	ds_write2_b64 v73, v[90:91], v[32:33] offset1:68
	ds_write2_b64 v73, v[124:125], v[122:123] offset0:136 offset1:204
	v_mov_b32_e32 v47, v93
	v_mov_b32_e32 v31, v43
	v_mov_b32_e32 v49, v45
	v_mov_b32_e32 v87, v95
	v_mov_b32_e32 v35, v39
	v_mov_b32_e32 v19, v23
	v_mov_b32_e32 v73, v0
	v_mov_b32_e32 v36, v38
	v_pk_add_f32 v[40:41], v[40:41], v[88:89] neg_lo:[0,1] neg_hi:[0,1]
	v_mov_b32_e32 v20, v22
	ds_write2_b64 v75, v[46:47], v[30:31] offset0:16 offset1:84
	ds_write2_b64 v75, v[36:37], v[20:21] offset0:152 offset1:220
	ds_write2_b64 v78, v[26:27], v[28:29] offset0:32 offset1:100
	ds_write2_b64 v78, v[96:97], v[40:41] offset0:168 offset1:236
	ds_write2_b64 v80, v[48:49], v[86:87] offset0:48 offset1:116
	ds_write2_b64 v80, v[34:35], v[18:19] offset0:184 offset1:252
	s_waitcnt lgkmcnt(0)
	s_barrier
	s_nop 0
	v_and_b32_e32 v22, 0x3ff, v73
	v_lshlrev_b32_e32 v18, 4, v73
	v_and_or_b32 v18, v18, s31, v22
	v_cvt_f32_u32_e32 v22, v22
	v_ashrrev_i32_e32 v19, 4, v18
	v_lshlrev_b32_e32 v19, 3, v19
	v_lshlrev_b32_e32 v18, 3, v18
	v_mul_f32_e32 v22, 0x38800000, v22
	v_add3_u32 v75, 0, v19, v18
	v_cos_f32_e32 v34, v22
	v_sin_f32_e32 v35, v22
	ds_read2st64_b64 v[18:21], v75 offset1:17
	v_add_u32_e32 v78, 0x11000, v75
	v_add_u32_e32 v80, 0x13200, v75
	v_add_u32_e32 v142, 0x15400, v75
	v_add_u32_e32 v143, 0x17600, v75
	v_add_u32_e32 v144, 0x19800, v75
	v_add_u32_e32 v145, 0x1ba00, v75
	v_add_u32_e32 v146, 0x1dc00, v75
	v_add_u32_e32 v147, 0x1fe00, v75
	ds_read2st64_b64 v[22:25], v75 offset0:34 offset1:51
	ds_read2st64_b64 v[26:29], v75 offset0:68 offset1:85
	ds_read2st64_b64 v[30:33], v75 offset0:102 offset1:119
	ds_read_b64 v[36:37], v78
	ds_read_b64 v[38:39], v80
	ds_read_b64 v[40:41], v142
	ds_read_b64 v[42:43], v143
	ds_read_b64 v[44:45], v144
	ds_read_b64 v[46:47], v145
	ds_read_b64 v[48:49], v146
	ds_read_b64 v[86:87], v147
	s_nop 1
	s_nop 0
	v_pk_mul_f32 v[88:89], v[34:35], v[34:35] op_sel:[0,0] op_sel_hi:[0,1]
	s_waitcnt lgkmcnt(11)
	v_pk_mul_f32 v[140:141], v[20:21], v[34:35] op_sel:[0,0] op_sel_hi:[0,1]
	v_pk_fma_f32 v[88:89], v[34:35], v[34:35], v[88:89] op_sel:[1,1,0] op_sel_hi:[1,0,1] neg_lo:[1,0,0]
	s_nop 0
	v_pk_fma_f32 v[20:21], v[20:21], v[34:35], v[140:141] op_sel:[1,1,0] op_sel_hi:[1,0,1] neg_lo:[1,0,0]
	v_pk_mul_f32 v[92:93], v[88:89], v[88:89] op_sel:[0,0] op_sel_hi:[0,1]
	v_pk_mul_f32 v[90:91], v[88:89], v[34:35] op_sel:[0,0] op_sel_hi:[0,1]
	s_nop 0
	v_pk_fma_f32 v[92:93], v[88:89], v[88:89], v[92:93] op_sel:[1,1,0] op_sel_hi:[1,0,1] neg_lo:[1,0,0]
	v_pk_fma_f32 v[90:91], v[88:89], v[34:35], v[90:91] op_sel:[1,1,0] op_sel_hi:[1,0,1] neg_lo:[1,0,0]
	s_nop 0
	v_pk_mul_f32 v[124:125], v[92:93], v[92:93] op_sel:[0,0] op_sel_hi:[0,1]
	v_pk_mul_f32 v[94:95], v[92:93], v[34:35] op_sel:[0,0] op_sel_hi:[0,1]
	v_pk_mul_f32 v[96:97], v[90:91], v[90:91] op_sel:[0,0] op_sel_hi:[0,1]
	v_pk_mul_f32 v[122:123], v[92:93], v[90:91] op_sel:[0,0] op_sel_hi:[0,1]
	s_nop 0
	v_pk_fma_f32 v[124:125], v[92:93], v[92:93], v[124:125] op_sel:[1,1,0] op_sel_hi:[1,0,1] neg_lo:[1,0,0]
	v_pk_fma_f32 v[94:95], v[92:93], v[34:35], v[94:95] op_sel:[1,1,0] op_sel_hi:[1,0,1] neg_lo:[1,0,0]
	v_pk_fma_f32 v[96:97], v[90:91], v[90:91], v[96:97] op_sel:[1,1,0] op_sel_hi:[1,0,1] neg_lo:[1,0,0]
	v_pk_fma_f32 v[122:123], v[92:93], v[90:91], v[122:123] op_sel:[1,1,0] op_sel_hi:[1,0,1] neg_lo:[1,0,0]
	s_nop 0
	v_pk_mul_f32 v[126:127], v[124:125], v[34:35] op_sel:[0,0] op_sel_hi:[0,1]
	v_pk_mul_f32 v[128:129], v[94:95], v[94:95] op_sel:[0,0] op_sel_hi:[0,1]
	v_pk_mul_f32 v[130:131], v[124:125], v[90:91] op_sel:[0,0] op_sel_hi:[0,1]
	v_pk_mul_f32 v[132:133], v[96:97], v[96:97] op_sel:[0,0] op_sel_hi:[0,1]
	v_pk_mul_f32 v[134:135], v[124:125], v[94:95] op_sel:[0,0] op_sel_hi:[0,1]
	v_pk_mul_f32 v[136:137], v[122:123], v[122:123] op_sel:[0,0] op_sel_hi:[0,1]
	s_nop 0
	v_pk_fma_f32 v[126:127], v[124:125], v[34:35], v[126:127] op_sel:[1,1,0] op_sel_hi:[1,0,1] neg_lo:[1,0,0]
	s_waitcnt lgkmcnt(10)
	v_pk_mul_f32 v[34:35], v[22:23], v[88:89] op_sel:[0,0] op_sel_hi:[0,1]
	v_pk_fma_f32 v[128:129], v[94:95], v[94:95], v[128:129] op_sel:[1,1,0] op_sel_hi:[1,0,1] neg_lo:[1,0,0]
	v_pk_fma_f32 v[130:131], v[124:125], v[90:91], v[130:131] op_sel:[1,1,0] op_sel_hi:[1,0,1] neg_lo:[1,0,0]
	v_pk_fma_f32 v[132:133], v[96:97], v[96:97], v[132:133] op_sel:[1,1,0] op_sel_hi:[1,0,1] neg_lo:[1,0,0]
	v_pk_fma_f32 v[134:135], v[124:125], v[94:95], v[134:135] op_sel:[1,1,0] op_sel_hi:[1,0,1] neg_lo:[1,0,0]
	v_pk_fma_f32 v[136:137], v[122:123], v[122:123], v[136:137] op_sel:[1,1,0] op_sel_hi:[1,0,1] neg_lo:[1,0,0]
	s_nop 0
	v_pk_fma_f32 v[22:23], v[22:23], v[88:89], v[34:35] op_sel:[1,1,0] op_sel_hi:[1,0,1] neg_lo:[1,0,0]
	v_pk_mul_f32 v[34:35], v[24:25], v[90:91] op_sel:[0,0] op_sel_hi:[0,1]
	v_pk_mul_f32 v[138:139], v[124:125], v[122:123] op_sel:[0,0] op_sel_hi:[0,1]
	s_nop 0
	v_pk_fma_f32 v[24:25], v[24:25], v[90:91], v[34:35] op_sel:[1,1,0] op_sel_hi:[1,0,1] neg_lo:[1,0,0]
	s_waitcnt lgkmcnt(9)
	v_pk_mul_f32 v[34:35], v[26:27], v[92:93] op_sel:[0,0] op_sel_hi:[0,1]
	v_pk_fma_f32 v[138:139], v[124:125], v[122:123], v[138:139] op_sel:[1,1,0] op_sel_hi:[1,0,1] neg_lo:[1,0,0]
	v_mov_b32_e32 v90, v19
	v_pk_fma_f32 v[26:27], v[26:27], v[92:93], v[34:35] op_sel:[1,1,0] op_sel_hi:[1,0,1] neg_lo:[1,0,0]
	v_pk_mul_f32 v[34:35], v[28:29], v[94:95] op_sel:[0,0] op_sel_hi:[0,1]
	s_nop 0
	v_pk_fma_f32 v[28:29], v[28:29], v[94:95], v[34:35] op_sel:[1,1,0] op_sel_hi:[1,0,1] neg_lo:[1,0,0]
	s_waitcnt lgkmcnt(8)
	v_pk_mul_f32 v[34:35], v[30:31], v[96:97] op_sel:[0,0] op_sel_hi:[0,1]
	v_mov_b32_e32 v91, v27
	v_pk_fma_f32 v[30:31], v[30:31], v[96:97], v[34:35] op_sel:[1,1,0] op_sel_hi:[1,0,1] neg_lo:[1,0,0]
	v_pk_mul_f32 v[34:35], v[32:33], v[122:123] op_sel:[0,0] op_sel_hi:[0,1]
	s_nop 0
	v_pk_fma_f32 v[32:33], v[32:33], v[122:123], v[34:35] op_sel:[1,1,0] op_sel_hi:[1,0,1] neg_lo:[1,0,0]
	s_waitcnt lgkmcnt(7)
	v_pk_mul_f32 v[34:35], v[36:37], v[124:125] op_sel:[0,0] op_sel_hi:[0,1]
	s_nop 0
	v_pk_fma_f32 v[34:35], v[36:37], v[124:125], v[34:35] op_sel:[1,1,0] op_sel_hi:[1,0,1] neg_lo:[1,0,0]
	s_waitcnt lgkmcnt(6)
	v_pk_mul_f32 v[36:37], v[38:39], v[126:127] op_sel:[0,0] op_sel_hi:[0,1]
	s_nop 0
	v_pk_fma_f32 v[36:37], v[38:39], v[126:127], v[36:37] op_sel:[1,1,0] op_sel_hi:[1,0,1] neg_lo:[1,0,0]
	s_waitcnt lgkmcnt(5)
	v_pk_mul_f32 v[38:39], v[40:41], v[128:129] op_sel:[0,0] op_sel_hi:[0,1]
	v_mov_b32_e32 v92, v35
	v_pk_fma_f32 v[38:39], v[40:41], v[128:129], v[38:39] op_sel:[1,1,0] op_sel_hi:[1,0,1] neg_lo:[1,0,0]
	s_waitcnt lgkmcnt(4)
	v_pk_mul_f32 v[40:41], v[42:43], v[130:131] op_sel:[0,0] op_sel_hi:[0,1]
	s_nop 0
	v_pk_fma_f32 v[40:41], v[42:43], v[130:131], v[40:41] op_sel:[1,1,0] op_sel_hi:[1,0,1] neg_lo:[1,0,0]
	s_waitcnt lgkmcnt(3)
	v_pk_mul_f32 v[42:43], v[44:45], v[132:133] op_sel:[0,0] op_sel_hi:[0,1]
	s_nop 0
	v_pk_fma_f32 v[42:43], v[44:45], v[132:133], v[42:43] op_sel:[1,1,0] op_sel_hi:[1,0,1] neg_lo:[1,0,0]
	s_waitcnt lgkmcnt(2)
	v_pk_mul_f32 v[44:45], v[46:47], v[134:135] op_sel:[0,0] op_sel_hi:[0,1]
	s_nop 0
	v_pk_fma_f32 v[44:45], v[46:47], v[134:135], v[44:45] op_sel:[1,1,0] op_sel_hi:[1,0,1] neg_lo:[1,0,0]
	s_waitcnt lgkmcnt(1)
	v_pk_mul_f32 v[46:47], v[48:49], v[136:137] op_sel:[0,0] op_sel_hi:[0,1]
	v_mov_b32_e32 v93, v43
	v_pk_fma_f32 v[46:47], v[48:49], v[136:137], v[46:47] op_sel:[1,1,0] op_sel_hi:[1,0,1] neg_lo:[1,0,0]
	s_waitcnt lgkmcnt(0)
	v_pk_mul_f32 v[48:49], v[86:87], v[138:139] op_sel:[0,0] op_sel_hi:[0,1]
	v_pk_add_f32 v[88:89], v[26:27], v[42:43]
	v_pk_fma_f32 v[48:49], v[86:87], v[138:139], v[48:49] op_sel:[1,1,0] op_sel_hi:[1,0,1] neg_lo:[1,0,0]
	v_pk_add_f32 v[86:87], v[18:19], v[34:35]
	v_pk_add_f32 v[90:91], v[90:91], v[92:93]
	v_pk_mov_b32 v[92:93], v[18:19], v[26:27] op_sel:[1,0]
	v_pk_mov_b32 v[94:95], v[34:35], v[42:43] op_sel:[1,0]
	v_mov_b32_e32 v19, v27
	v_pk_add_f32 v[92:93], v[92:93], v[94:95] neg_lo:[0,1] neg_hi:[0,1]
	v_mov_b32_e32 v35, v43
	v_mov_b32_e32 v87, v90
	v_mov_b32_e32 v89, v91
	v_pk_add_f32 v[18:19], v[18:19], v[34:35] neg_lo:[0,1] neg_hi:[0,1]
	v_pk_add_f32 v[26:27], v[86:87], v[88:89]
	v_pk_add_f32 v[34:35], v[86:87], v[88:89] neg_lo:[0,1] neg_hi:[0,1]
	v_pk_add_f32 v[86:87], v[92:93], v[92:93] op_sel:[0,1] op_sel_hi:[1,0]
	v_pk_add_f32 v[88:89], v[92:93], v[92:93] op_sel_hi:[0,1] neg_lo:[0,1] neg_hi:[0,1]
	v_pk_add_f32 v[90:91], v[20:21], v[36:37]
	v_pk_add_f32 v[92:93], v[28:29], v[44:45]
	v_pk_add_f32 v[20:21], v[20:21], v[36:37] neg_lo:[0,1] neg_hi:[0,1]
	v_pk_add_f32 v[28:29], v[28:29], v[44:45] neg_lo:[0,1] neg_hi:[0,1]
	v_pk_add_f32 v[44:45], v[30:31], v[46:47]
	v_pk_add_f32 v[36:37], v[20:21], v[28:29] op_sel:[0,1] op_sel_hi:[1,0] neg_lo:[0,1] neg_hi:[0,1]
	v_pk_add_f32 v[20:21], v[20:21], v[28:29] op_sel:[0,1] op_sel_hi:[1,0]
	v_mov_b32_e32 v28, v36
	v_mov_b32_e32 v29, v21
	v_mov_b32_e32 v21, v37
	v_pk_add_f32 v[36:37], v[22:23], v[38:39]
	v_pk_add_f32 v[22:23], v[22:23], v[38:39] neg_lo:[0,1] neg_hi:[0,1]
	v_pk_add_f32 v[30:31], v[30:31], v[46:47] neg_lo:[0,1] neg_hi:[0,1]
	v_pk_add_f32 v[94:95], v[90:91], v[92:93]
	v_pk_add_f32 v[38:39], v[22:23], v[30:31] op_sel:[0,1] op_sel_hi:[1,0] neg_lo:[0,1] neg_hi:[0,1]
	v_pk_add_f32 v[22:23], v[22:23], v[30:31] op_sel:[0,1] op_sel_hi:[1,0]
	v_pk_add_f32 v[90:91], v[90:91], v[92:93] neg_lo:[0,1] neg_hi:[0,1]
	v_pk_add_f32 v[92:93], v[36:37], v[44:45]
	v_pk_add_f32 v[36:37], v[36:37], v[44:45] neg_lo:[0,1] neg_hi:[0,1]
	v_mov_b32_e32 v30, v38
	v_mov_b32_e32 v31, v23
	v_mov_b32_e32 v23, v39
	v_pk_add_f32 v[38:39], v[24:25], v[40:41]
	v_pk_add_f32 v[44:45], v[32:33], v[48:49]
	v_pk_add_f32 v[24:25], v[24:25], v[40:41] neg_lo:[0,1] neg_hi:[0,1]
	v_pk_add_f32 v[46:47], v[38:39], v[44:45]
	v_pk_add_f32 v[38:39], v[38:39], v[44:45] neg_lo:[0,1] neg_hi:[0,1]
	v_pk_add_f32 v[32:33], v[32:33], v[48:49] neg_lo:[0,1] neg_hi:[0,1]
	v_pk_mul_f32 v[44:45], v[36:37], v[56:57] op_sel:[0,0] op_sel_hi:[0,1]
	v_pk_add_f32 v[42:43], v[18:19], v[18:19] op_sel:[0,1] op_sel_hi:[1,0] neg_lo:[0,1] neg_hi:[0,1]
	v_pk_add_f32 v[40:41], v[24:25], v[32:33] op_sel:[0,1] op_sel_hi:[1,0] neg_lo:[0,1] neg_hi:[0,1]
	v_pk_add_f32 v[24:25], v[24:25], v[32:33] op_sel:[0,1] op_sel_hi:[1,0]
	v_pk_fma_f32 v[36:37], v[36:37], v[56:57], v[44:45] op_sel:[1,1,0] op_sel_hi:[1,0,1] neg_lo:[1,0,0]
	v_pk_mul_f32 v[44:45], v[38:39], v[58:59] op_sel:[0,0] op_sel_hi:[0,1]
	v_mov_b32_e32 v32, v40
	v_mov_b32_e32 v33, v25
	v_mov_b32_e32 v25, v41
	v_pk_mul_f32 v[40:41], v[28:29], v[54:55] op_sel:[0,0] op_sel_hi:[0,1]
	v_pk_fma_f32 v[38:39], v[38:39], v[58:59], v[44:45] op_sel:[1,1,0] op_sel_hi:[1,0,1] neg_lo:[1,0,0]
	v_pk_mul_f32 v[44:45], v[20:21], v[50:51] op_sel:[0,0] op_sel_hi:[0,1]
	v_pk_add_f32 v[18:19], v[18:19], v[18:19] op_sel:[0,1] op_sel_hi:[1,0]
	v_pk_fma_f32 v[28:29], v[28:29], v[54:55], v[40:41] op_sel:[1,1,0] op_sel_hi:[1,0,1] neg_lo:[1,0,0]
	v_pk_mul_f32 v[40:41], v[30:31], v[52:53] op_sel:[0,0] op_sel_hi:[0,1]
	v_pk_fma_f32 v[20:21], v[20:21], v[50:51], v[44:45] op_sel:[1,1,0] op_sel_hi:[1,0,1] neg_lo:[1,0,0]
	v_pk_mul_f32 v[44:45], v[22:23], v[58:59] op_sel:[0,0] op_sel_hi:[0,1]
	v_pk_mov_b32 v[48:49], v[92:93], v[46:47] op_sel:[1,0]
	v_pk_fma_f32 v[30:31], v[30:31], v[52:53], v[40:41] op_sel:[1,1,0] op_sel_hi:[1,0,1] neg_lo:[1,0,0]
	v_pk_mul_f32 v[40:41], v[32:33], v[50:51] op_sel:[0,0] op_sel_hi:[0,1]
	v_pk_fma_f32 v[22:23], v[22:23], v[58:59], v[44:45] op_sel:[1,1,0] op_sel_hi:[1,0,1] neg_lo:[1,0,0]
	v_pk_mul_f32 v[44:45], v[24:25], v[60:61] op_sel:[0,0] op_sel_hi:[0,1]
	v_mov_b32_e32 v43, v29
	v_pk_fma_f32 v[32:33], v[32:33], v[50:51], v[40:41] op_sel:[1,1,0] op_sel_hi:[1,0,1] neg_lo:[1,0,0]
	v_mov_b32_e32 v96, v30
	v_mov_b32_e32 v97, v33
	v_pk_mul_f32 v[40:41], v[90:91], v[52:53] op_sel:[0,0] op_sel_hi:[0,1]
	v_pk_fma_f32 v[24:25], v[24:25], v[60:61], v[44:45] op_sel:[1,1,0] op_sel_hi:[1,0,1] neg_lo:[1,0,0]
	v_pk_mov_b32 v[44:45], v[26:27], v[94:95] op_sel:[1,0]
	v_pk_add_f32 v[96:97], v[42:43], v[96:97] neg_lo:[0,1] neg_hi:[0,1]
	v_mov_b32_e32 v43, v86
	v_pk_fma_f32 v[40:41], v[90:91], v[52:53], v[40:41] op_sel:[1,1,0] op_sel_hi:[1,0,1] neg_lo:[1,0,0]
	v_pk_add_f32 v[44:45], v[44:45], v[48:49] neg_lo:[0,1] neg_hi:[0,1]
	v_mov_b32_e32 v48, v26
	v_mov_b32_e32 v49, v95
	v_mov_b32_e32 v90, v92
	v_mov_b32_e32 v91, v47
	v_pk_add_f32 v[46:47], v[94:95], v[46:47]
	v_mov_b32_e32 v87, v28
	v_pk_mov_b32 v[94:95], v[30:31], v[32:33] op_sel:[1,0]
	v_pk_add_f32 v[30:31], v[42:43], v[30:31]
	v_pk_add_f32 v[28:29], v[28:29], v[32:33]
	v_mov_b32_e32 v19, v89
	v_pk_add_f32 v[48:49], v[48:49], v[90:91] neg_lo:[0,1] neg_hi:[0,1]
	v_pk_add_f32 v[26:27], v[26:27], v[92:93]
	v_pk_add_f32 v[94:95], v[86:87], v[94:95] neg_lo:[0,1] neg_hi:[0,1]
	v_pk_add_f32 v[32:33], v[30:31], v[28:29]
	v_pk_add_f32 v[28:29], v[30:31], v[28:29] neg_lo:[0,1] neg_hi:[0,1]
	v_pk_add_f32 v[30:31], v[96:97], v[96:97] op_sel:[0,1] op_sel_hi:[1,0] neg_lo:[0,1] neg_hi:[0,1]
	v_pk_add_f32 v[86:87], v[96:97], v[96:97] op_sel:[0,1] op_sel_hi:[1,0]
	v_pk_add_f32 v[96:97], v[34:35], v[36:37]
	v_pk_add_f32 v[122:123], v[40:41], v[38:39]
	v_pk_add_f32 v[34:35], v[34:35], v[36:37] neg_lo:[0,1] neg_hi:[0,1]
	v_pk_add_f32 v[36:37], v[40:41], v[38:39] neg_lo:[0,1] neg_hi:[0,1]
	v_pk_add_f32 v[40:41], v[18:19], v[22:23]
	v_pk_add_f32 v[88:89], v[20:21], v[24:25]
	v_pk_add_f32 v[18:19], v[18:19], v[22:23] neg_lo:[0,1] neg_hi:[0,1]
	v_pk_add_f32 v[20:21], v[20:21], v[24:25] neg_lo:[0,1] neg_hi:[0,1]
	v_pk_add_f32 v[90:91], v[26:27], v[46:47]
	v_pk_add_f32 v[26:27], v[26:27], v[46:47] neg_lo:[0,1] neg_hi:[0,1]
	v_pk_add_f32 v[46:47], v[48:49], v[48:49] op_sel:[0,1] op_sel_hi:[1,0] neg_lo:[0,1] neg_hi:[0,1]
	v_pk_add_f32 v[92:93], v[44:45], v[44:45] op_sel_hi:[0,1]
	v_pk_add_f32 v[42:43], v[94:95], v[94:95] op_sel_hi:[0,1]
	v_pk_add_f32 v[22:23], v[18:19], v[20:21] op_sel:[0,1] op_sel_hi:[1,0] neg_lo:[0,1] neg_hi:[0,1]
	v_pk_add_f32 v[18:19], v[18:19], v[20:21] op_sel:[0,1] op_sel_hi:[1,0]
	v_pk_add_f32 v[38:39], v[34:35], v[36:37] op_sel:[0,1] op_sel_hi:[1,0] neg_lo:[0,1] neg_hi:[0,1]
	v_pk_add_f32 v[34:35], v[34:35], v[36:37] op_sel:[0,1] op_sel_hi:[1,0]
	v_mov_b32_e32 v21, v19
	v_mov_b32_e32 v47, v93
	v_mov_b32_e32 v31, v43
	v_mov_b32_e32 v19, v23
	v_pk_add_f32 v[124:125], v[96:97], v[122:123]
	v_pk_add_f32 v[96:97], v[96:97], v[122:123] neg_lo:[0,1] neg_hi:[0,1]
	v_mov_b32_e32 v36, v38
	v_mov_b32_e32 v37, v35
	v_pk_add_f32 v[122:123], v[40:41], v[88:89]
	v_pk_add_f32 v[40:41], v[40:41], v[88:89] neg_lo:[0,1] neg_hi:[0,1]
	v_mov_b32_e32 v20, v22
	ds_write2st64_b64 v75, v[90:91], v[32:33] offset1:17
	ds_write2st64_b64 v75, v[124:125], v[122:123] offset0:34 offset1:51
	ds_write2st64_b64 v75, v[46:47], v[30:31] offset0:68 offset1:85
	ds_write2st64_b64 v75, v[36:37], v[20:21] offset0:102 offset1:119
	ds_write_b64 v78, v[26:27]
	ds_write_b64 v80, v[28:29]
	ds_write_b64 v142, v[96:97]
	ds_write_b64 v143, v[40:41]
	ds_write_b64 v147, v[18:19]
	v_add_u32_e32 v18, 0x200, v73
	v_and_b32_e32 v22, 0x3ff, v18
	v_lshlrev_b32_e32 v18, 4, v18
	v_and_or_b32 v18, v18, s31, v22
	v_cvt_f32_u32_e32 v22, v22
	v_pk_add_f32 v[48:49], v[48:49], v[48:49] op_sel:[0,1] op_sel_hi:[1,0]
	v_pk_add_f32 v[44:45], v[44:45], v[44:45] op_sel_hi:[0,1] neg_lo:[0,1] neg_hi:[0,1]
	v_pk_add_f32 v[94:95], v[94:95], v[94:95] op_sel_hi:[0,1] neg_lo:[0,1] neg_hi:[0,1]
	v_ashrrev_i32_e32 v19, 4, v18
	v_mov_b32_e32 v49, v45
	v_mov_b32_e32 v87, v95
	v_mov_b32_e32 v35, v39
	v_lshlrev_b32_e32 v19, 3, v19
	v_lshlrev_b32_e32 v18, 3, v18
	v_mul_f32_e32 v22, 0x38800000, v22
	ds_write_b64 v144, v[48:49]
	ds_write_b64 v145, v[86:87]
	ds_write_b64 v146, v[34:35]
	v_add3_u32 v73, 0, v19, v18
	v_cos_f32_e32 v34, v22
	v_sin_f32_e32 v35, v22
	ds_read2st64_b64 v[18:21], v73 offset1:17
	v_add_u32_e32 v75, 0x11000, v73
	v_add_u32_e32 v78, 0x13200, v73
	v_add_u32_e32 v80, 0x15400, v73
	v_add_u32_e32 v142, 0x17600, v73
	v_add_u32_e32 v143, 0x19800, v73
	v_add_u32_e32 v144, 0x1ba00, v73
	v_add_u32_e32 v145, 0x1dc00, v73
	v_add_u32_e32 v146, 0x1fe00, v73
	ds_read2st64_b64 v[22:25], v73 offset0:34 offset1:51
	ds_read2st64_b64 v[26:29], v73 offset0:68 offset1:85
	ds_read2st64_b64 v[30:33], v73 offset0:102 offset1:119
	ds_read_b64 v[36:37], v75
	ds_read_b64 v[38:39], v78
	ds_read_b64 v[40:41], v80
	ds_read_b64 v[42:43], v142
	ds_read_b64 v[44:45], v143
	ds_read_b64 v[46:47], v144
	ds_read_b64 v[48:49], v145
	ds_read_b64 v[86:87], v146
	s_nop 1
	s_nop 0
	v_pk_mul_f32 v[88:89], v[34:35], v[34:35] op_sel:[0,0] op_sel_hi:[0,1]
	s_waitcnt lgkmcnt(11)
	v_pk_mul_f32 v[140:141], v[20:21], v[34:35] op_sel:[0,0] op_sel_hi:[0,1]
	v_pk_fma_f32 v[88:89], v[34:35], v[34:35], v[88:89] op_sel:[1,1,0] op_sel_hi:[1,0,1] neg_lo:[1,0,0]
	s_nop 0
	v_pk_fma_f32 v[20:21], v[20:21], v[34:35], v[140:141] op_sel:[1,1,0] op_sel_hi:[1,0,1] neg_lo:[1,0,0]
	v_pk_mul_f32 v[92:93], v[88:89], v[88:89] op_sel:[0,0] op_sel_hi:[0,1]
	v_pk_mul_f32 v[90:91], v[88:89], v[34:35] op_sel:[0,0] op_sel_hi:[0,1]
	s_nop 0
	v_pk_fma_f32 v[92:93], v[88:89], v[88:89], v[92:93] op_sel:[1,1,0] op_sel_hi:[1,0,1] neg_lo:[1,0,0]
	v_pk_fma_f32 v[90:91], v[88:89], v[34:35], v[90:91] op_sel:[1,1,0] op_sel_hi:[1,0,1] neg_lo:[1,0,0]
	s_nop 0
	v_pk_mul_f32 v[124:125], v[92:93], v[92:93] op_sel:[0,0] op_sel_hi:[0,1]
	v_pk_mul_f32 v[94:95], v[92:93], v[34:35] op_sel:[0,0] op_sel_hi:[0,1]
	v_pk_mul_f32 v[96:97], v[90:91], v[90:91] op_sel:[0,0] op_sel_hi:[0,1]
	v_pk_mul_f32 v[122:123], v[92:93], v[90:91] op_sel:[0,0] op_sel_hi:[0,1]
	s_nop 0
	v_pk_fma_f32 v[124:125], v[92:93], v[92:93], v[124:125] op_sel:[1,1,0] op_sel_hi:[1,0,1] neg_lo:[1,0,0]
	v_pk_fma_f32 v[94:95], v[92:93], v[34:35], v[94:95] op_sel:[1,1,0] op_sel_hi:[1,0,1] neg_lo:[1,0,0]
	v_pk_fma_f32 v[96:97], v[90:91], v[90:91], v[96:97] op_sel:[1,1,0] op_sel_hi:[1,0,1] neg_lo:[1,0,0]
	v_pk_fma_f32 v[122:123], v[92:93], v[90:91], v[122:123] op_sel:[1,1,0] op_sel_hi:[1,0,1] neg_lo:[1,0,0]
	s_nop 0
	v_pk_mul_f32 v[126:127], v[124:125], v[34:35] op_sel:[0,0] op_sel_hi:[0,1]
	v_pk_mul_f32 v[128:129], v[94:95], v[94:95] op_sel:[0,0] op_sel_hi:[0,1]
	v_pk_mul_f32 v[130:131], v[124:125], v[90:91] op_sel:[0,0] op_sel_hi:[0,1]
	v_pk_mul_f32 v[132:133], v[96:97], v[96:97] op_sel:[0,0] op_sel_hi:[0,1]
	v_pk_mul_f32 v[134:135], v[124:125], v[94:95] op_sel:[0,0] op_sel_hi:[0,1]
	v_pk_mul_f32 v[136:137], v[122:123], v[122:123] op_sel:[0,0] op_sel_hi:[0,1]
	s_nop 0
	v_pk_fma_f32 v[126:127], v[124:125], v[34:35], v[126:127] op_sel:[1,1,0] op_sel_hi:[1,0,1] neg_lo:[1,0,0]
	s_waitcnt lgkmcnt(10)
	v_pk_mul_f32 v[34:35], v[22:23], v[88:89] op_sel:[0,0] op_sel_hi:[0,1]
	v_pk_fma_f32 v[128:129], v[94:95], v[94:95], v[128:129] op_sel:[1,1,0] op_sel_hi:[1,0,1] neg_lo:[1,0,0]
	v_pk_fma_f32 v[130:131], v[124:125], v[90:91], v[130:131] op_sel:[1,1,0] op_sel_hi:[1,0,1] neg_lo:[1,0,0]
	v_pk_fma_f32 v[132:133], v[96:97], v[96:97], v[132:133] op_sel:[1,1,0] op_sel_hi:[1,0,1] neg_lo:[1,0,0]
	v_pk_fma_f32 v[134:135], v[124:125], v[94:95], v[134:135] op_sel:[1,1,0] op_sel_hi:[1,0,1] neg_lo:[1,0,0]
	v_pk_fma_f32 v[136:137], v[122:123], v[122:123], v[136:137] op_sel:[1,1,0] op_sel_hi:[1,0,1] neg_lo:[1,0,0]
	s_nop 0
	v_pk_fma_f32 v[22:23], v[22:23], v[88:89], v[34:35] op_sel:[1,1,0] op_sel_hi:[1,0,1] neg_lo:[1,0,0]
	v_pk_mul_f32 v[34:35], v[24:25], v[90:91] op_sel:[0,0] op_sel_hi:[0,1]
	v_pk_mul_f32 v[138:139], v[124:125], v[122:123] op_sel:[0,0] op_sel_hi:[0,1]
	s_nop 0
	v_pk_fma_f32 v[24:25], v[24:25], v[90:91], v[34:35] op_sel:[1,1,0] op_sel_hi:[1,0,1] neg_lo:[1,0,0]
	s_waitcnt lgkmcnt(9)
	v_pk_mul_f32 v[34:35], v[26:27], v[92:93] op_sel:[0,0] op_sel_hi:[0,1]
	v_pk_fma_f32 v[138:139], v[124:125], v[122:123], v[138:139] op_sel:[1,1,0] op_sel_hi:[1,0,1] neg_lo:[1,0,0]
	v_mov_b32_e32 v90, v19
	v_pk_fma_f32 v[26:27], v[26:27], v[92:93], v[34:35] op_sel:[1,1,0] op_sel_hi:[1,0,1] neg_lo:[1,0,0]
	v_pk_mul_f32 v[34:35], v[28:29], v[94:95] op_sel:[0,0] op_sel_hi:[0,1]
	s_nop 0
	v_pk_fma_f32 v[28:29], v[28:29], v[94:95], v[34:35] op_sel:[1,1,0] op_sel_hi:[1,0,1] neg_lo:[1,0,0]
	s_waitcnt lgkmcnt(8)
	v_pk_mul_f32 v[34:35], v[30:31], v[96:97] op_sel:[0,0] op_sel_hi:[0,1]
	v_mov_b32_e32 v91, v27
	v_pk_fma_f32 v[30:31], v[30:31], v[96:97], v[34:35] op_sel:[1,1,0] op_sel_hi:[1,0,1] neg_lo:[1,0,0]
	v_pk_mul_f32 v[34:35], v[32:33], v[122:123] op_sel:[0,0] op_sel_hi:[0,1]
	s_nop 0
	v_pk_fma_f32 v[32:33], v[32:33], v[122:123], v[34:35] op_sel:[1,1,0] op_sel_hi:[1,0,1] neg_lo:[1,0,0]
	s_waitcnt lgkmcnt(7)
	v_pk_mul_f32 v[34:35], v[36:37], v[124:125] op_sel:[0,0] op_sel_hi:[0,1]
	s_nop 0
	v_pk_fma_f32 v[34:35], v[36:37], v[124:125], v[34:35] op_sel:[1,1,0] op_sel_hi:[1,0,1] neg_lo:[1,0,0]
	s_waitcnt lgkmcnt(6)
	v_pk_mul_f32 v[36:37], v[38:39], v[126:127] op_sel:[0,0] op_sel_hi:[0,1]
	s_nop 0
	v_pk_fma_f32 v[36:37], v[38:39], v[126:127], v[36:37] op_sel:[1,1,0] op_sel_hi:[1,0,1] neg_lo:[1,0,0]
	s_waitcnt lgkmcnt(5)
	v_pk_mul_f32 v[38:39], v[40:41], v[128:129] op_sel:[0,0] op_sel_hi:[0,1]
	v_mov_b32_e32 v92, v35
	v_pk_fma_f32 v[38:39], v[40:41], v[128:129], v[38:39] op_sel:[1,1,0] op_sel_hi:[1,0,1] neg_lo:[1,0,0]
	s_waitcnt lgkmcnt(4)
	v_pk_mul_f32 v[40:41], v[42:43], v[130:131] op_sel:[0,0] op_sel_hi:[0,1]
	s_nop 0
	v_pk_fma_f32 v[40:41], v[42:43], v[130:131], v[40:41] op_sel:[1,1,0] op_sel_hi:[1,0,1] neg_lo:[1,0,0]
	s_waitcnt lgkmcnt(3)
	v_pk_mul_f32 v[42:43], v[44:45], v[132:133] op_sel:[0,0] op_sel_hi:[0,1]
	s_nop 0
	v_pk_fma_f32 v[42:43], v[44:45], v[132:133], v[42:43] op_sel:[1,1,0] op_sel_hi:[1,0,1] neg_lo:[1,0,0]
	s_waitcnt lgkmcnt(2)
	v_pk_mul_f32 v[44:45], v[46:47], v[134:135] op_sel:[0,0] op_sel_hi:[0,1]
	s_nop 0
	v_pk_fma_f32 v[44:45], v[46:47], v[134:135], v[44:45] op_sel:[1,1,0] op_sel_hi:[1,0,1] neg_lo:[1,0,0]
	s_waitcnt lgkmcnt(1)
	v_pk_mul_f32 v[46:47], v[48:49], v[136:137] op_sel:[0,0] op_sel_hi:[0,1]
	v_mov_b32_e32 v93, v43
	v_pk_fma_f32 v[46:47], v[48:49], v[136:137], v[46:47] op_sel:[1,1,0] op_sel_hi:[1,0,1] neg_lo:[1,0,0]
	s_waitcnt lgkmcnt(0)
	v_pk_mul_f32 v[48:49], v[86:87], v[138:139] op_sel:[0,0] op_sel_hi:[0,1]
	v_pk_add_f32 v[88:89], v[26:27], v[42:43]
	v_pk_fma_f32 v[48:49], v[86:87], v[138:139], v[48:49] op_sel:[1,1,0] op_sel_hi:[1,0,1] neg_lo:[1,0,0]
	v_pk_add_f32 v[86:87], v[18:19], v[34:35]
	v_pk_add_f32 v[90:91], v[90:91], v[92:93]
	v_pk_mov_b32 v[92:93], v[18:19], v[26:27] op_sel:[1,0]
	v_pk_mov_b32 v[94:95], v[34:35], v[42:43] op_sel:[1,0]
	v_mov_b32_e32 v19, v27
	v_pk_add_f32 v[92:93], v[92:93], v[94:95] neg_lo:[0,1] neg_hi:[0,1]
	v_mov_b32_e32 v35, v43
	v_mov_b32_e32 v87, v90
	v_mov_b32_e32 v89, v91
	v_pk_add_f32 v[18:19], v[18:19], v[34:35] neg_lo:[0,1] neg_hi:[0,1]
	v_pk_add_f32 v[26:27], v[86:87], v[88:89]
	v_pk_add_f32 v[34:35], v[86:87], v[88:89] neg_lo:[0,1] neg_hi:[0,1]
	v_pk_add_f32 v[86:87], v[92:93], v[92:93] op_sel:[0,1] op_sel_hi:[1,0]
	v_pk_add_f32 v[88:89], v[92:93], v[92:93] op_sel_hi:[0,1] neg_lo:[0,1] neg_hi:[0,1]
	v_pk_add_f32 v[90:91], v[20:21], v[36:37]
	v_pk_add_f32 v[92:93], v[28:29], v[44:45]
	v_pk_add_f32 v[20:21], v[20:21], v[36:37] neg_lo:[0,1] neg_hi:[0,1]
	v_pk_add_f32 v[28:29], v[28:29], v[44:45] neg_lo:[0,1] neg_hi:[0,1]
	v_pk_add_f32 v[44:45], v[30:31], v[46:47]
	v_pk_add_f32 v[36:37], v[20:21], v[28:29] op_sel:[0,1] op_sel_hi:[1,0] neg_lo:[0,1] neg_hi:[0,1]
	v_pk_add_f32 v[20:21], v[20:21], v[28:29] op_sel:[0,1] op_sel_hi:[1,0]
	v_mov_b32_e32 v28, v36
	v_mov_b32_e32 v29, v21
	v_mov_b32_e32 v21, v37
	v_pk_add_f32 v[36:37], v[22:23], v[38:39]
	v_pk_add_f32 v[22:23], v[22:23], v[38:39] neg_lo:[0,1] neg_hi:[0,1]
	v_pk_add_f32 v[30:31], v[30:31], v[46:47] neg_lo:[0,1] neg_hi:[0,1]
	v_pk_add_f32 v[94:95], v[90:91], v[92:93]
	v_pk_add_f32 v[38:39], v[22:23], v[30:31] op_sel:[0,1] op_sel_hi:[1,0] neg_lo:[0,1] neg_hi:[0,1]
	v_pk_add_f32 v[22:23], v[22:23], v[30:31] op_sel:[0,1] op_sel_hi:[1,0]
	v_pk_add_f32 v[90:91], v[90:91], v[92:93] neg_lo:[0,1] neg_hi:[0,1]
	v_pk_add_f32 v[92:93], v[36:37], v[44:45]
	v_pk_add_f32 v[36:37], v[36:37], v[44:45] neg_lo:[0,1] neg_hi:[0,1]
	v_mov_b32_e32 v30, v38
	v_mov_b32_e32 v31, v23
	v_mov_b32_e32 v23, v39
	v_pk_add_f32 v[38:39], v[24:25], v[40:41]
	v_pk_add_f32 v[44:45], v[32:33], v[48:49]
	v_pk_add_f32 v[24:25], v[24:25], v[40:41] neg_lo:[0,1] neg_hi:[0,1]
	v_pk_add_f32 v[46:47], v[38:39], v[44:45]
	v_pk_add_f32 v[38:39], v[38:39], v[44:45] neg_lo:[0,1] neg_hi:[0,1]
	v_pk_add_f32 v[32:33], v[32:33], v[48:49] neg_lo:[0,1] neg_hi:[0,1]
	v_pk_mul_f32 v[44:45], v[36:37], v[56:57] op_sel:[0,0] op_sel_hi:[0,1]
	v_pk_add_f32 v[42:43], v[18:19], v[18:19] op_sel:[0,1] op_sel_hi:[1,0] neg_lo:[0,1] neg_hi:[0,1]
	v_pk_add_f32 v[40:41], v[24:25], v[32:33] op_sel:[0,1] op_sel_hi:[1,0] neg_lo:[0,1] neg_hi:[0,1]
	v_pk_add_f32 v[24:25], v[24:25], v[32:33] op_sel:[0,1] op_sel_hi:[1,0]
	v_pk_fma_f32 v[36:37], v[36:37], v[56:57], v[44:45] op_sel:[1,1,0] op_sel_hi:[1,0,1] neg_lo:[1,0,0]
	v_pk_mul_f32 v[44:45], v[38:39], v[58:59] op_sel:[0,0] op_sel_hi:[0,1]
	v_mov_b32_e32 v32, v40
	v_mov_b32_e32 v33, v25
	v_mov_b32_e32 v25, v41
	v_pk_mul_f32 v[40:41], v[28:29], v[54:55] op_sel:[0,0] op_sel_hi:[0,1]
	v_pk_fma_f32 v[38:39], v[38:39], v[58:59], v[44:45] op_sel:[1,1,0] op_sel_hi:[1,0,1] neg_lo:[1,0,0]
	v_pk_mul_f32 v[44:45], v[20:21], v[50:51] op_sel:[0,0] op_sel_hi:[0,1]
	v_pk_add_f32 v[18:19], v[18:19], v[18:19] op_sel:[0,1] op_sel_hi:[1,0]
	v_pk_fma_f32 v[28:29], v[28:29], v[54:55], v[40:41] op_sel:[1,1,0] op_sel_hi:[1,0,1] neg_lo:[1,0,0]
	v_pk_mul_f32 v[40:41], v[30:31], v[52:53] op_sel:[0,0] op_sel_hi:[0,1]
	v_pk_fma_f32 v[20:21], v[20:21], v[50:51], v[44:45] op_sel:[1,1,0] op_sel_hi:[1,0,1] neg_lo:[1,0,0]
	v_pk_mul_f32 v[44:45], v[22:23], v[58:59] op_sel:[0,0] op_sel_hi:[0,1]
	v_pk_mov_b32 v[48:49], v[92:93], v[46:47] op_sel:[1,0]
	v_pk_fma_f32 v[30:31], v[30:31], v[52:53], v[40:41] op_sel:[1,1,0] op_sel_hi:[1,0,1] neg_lo:[1,0,0]
	v_pk_mul_f32 v[40:41], v[32:33], v[50:51] op_sel:[0,0] op_sel_hi:[0,1]
	v_pk_fma_f32 v[22:23], v[22:23], v[58:59], v[44:45] op_sel:[1,1,0] op_sel_hi:[1,0,1] neg_lo:[1,0,0]
	v_pk_mul_f32 v[44:45], v[24:25], v[60:61] op_sel:[0,0] op_sel_hi:[0,1]
	v_mov_b32_e32 v43, v29
	v_pk_fma_f32 v[32:33], v[32:33], v[50:51], v[40:41] op_sel:[1,1,0] op_sel_hi:[1,0,1] neg_lo:[1,0,0]
	v_pk_mul_f32 v[40:41], v[90:91], v[52:53] op_sel:[0,0] op_sel_hi:[0,1]
	v_pk_fma_f32 v[24:25], v[24:25], v[60:61], v[44:45] op_sel:[1,1,0] op_sel_hi:[1,0,1] neg_lo:[1,0,0]
	v_pk_mov_b32 v[44:45], v[26:27], v[94:95] op_sel:[1,0]
	v_mov_b32_e32 v56, v30
	v_mov_b32_e32 v57, v33
	v_pk_fma_f32 v[40:41], v[90:91], v[52:53], v[40:41] op_sel:[1,1,0] op_sel_hi:[1,0,1] neg_lo:[1,0,0]
	v_pk_add_f32 v[44:45], v[44:45], v[48:49] neg_lo:[0,1] neg_hi:[0,1]
	v_mov_b32_e32 v48, v26
	v_mov_b32_e32 v49, v95
	v_mov_b32_e32 v50, v92
	v_mov_b32_e32 v51, v47
	v_mov_b32_e32 v87, v28
	v_pk_mov_b32 v[54:55], v[30:31], v[32:33] op_sel:[1,0]
	v_pk_add_f32 v[56:57], v[42:43], v[56:57] neg_lo:[0,1] neg_hi:[0,1]
	v_mov_b32_e32 v43, v86
	v_pk_add_f32 v[58:59], v[34:35], v[36:37]
	v_pk_add_f32 v[60:61], v[40:41], v[38:39]
	v_mov_b32_e32 v19, v89
	v_pk_add_f32 v[48:49], v[48:49], v[50:51] neg_lo:[0,1] neg_hi:[0,1]
	v_pk_add_f32 v[26:27], v[26:27], v[92:93]
	v_pk_add_f32 v[46:47], v[94:95], v[46:47]
	v_pk_add_f32 v[54:55], v[86:87], v[54:55] neg_lo:[0,1] neg_hi:[0,1]
	v_pk_add_f32 v[30:31], v[42:43], v[30:31]
	v_pk_add_f32 v[28:29], v[28:29], v[32:33]
	v_pk_add_f32 v[86:87], v[58:59], v[60:61]
	v_pk_add_f32 v[58:59], v[58:59], v[60:61] neg_lo:[0,1] neg_hi:[0,1]
	v_pk_add_f32 v[34:35], v[34:35], v[36:37] neg_lo:[0,1] neg_hi:[0,1]
	v_pk_add_f32 v[36:37], v[40:41], v[38:39] neg_lo:[0,1] neg_hi:[0,1]
	v_pk_add_f32 v[40:41], v[18:19], v[22:23]
	v_pk_add_f32 v[60:61], v[20:21], v[24:25]
	v_pk_add_f32 v[18:19], v[18:19], v[22:23] neg_lo:[0,1] neg_hi:[0,1]
	v_pk_add_f32 v[20:21], v[20:21], v[24:25] neg_lo:[0,1] neg_hi:[0,1]
	v_pk_add_f32 v[50:51], v[26:27], v[46:47]
	v_pk_add_f32 v[26:27], v[26:27], v[46:47] neg_lo:[0,1] neg_hi:[0,1]
	v_pk_add_f32 v[46:47], v[48:49], v[48:49] op_sel:[0,1] op_sel_hi:[1,0] neg_lo:[0,1] neg_hi:[0,1]
	v_pk_add_f32 v[52:53], v[44:45], v[44:45] op_sel_hi:[0,1]
	v_pk_add_f32 v[32:33], v[30:31], v[28:29]
	v_pk_add_f32 v[28:29], v[30:31], v[28:29] neg_lo:[0,1] neg_hi:[0,1]
	v_pk_add_f32 v[30:31], v[56:57], v[56:57] op_sel:[0,1] op_sel_hi:[1,0] neg_lo:[0,1] neg_hi:[0,1]
	v_pk_add_f32 v[42:43], v[54:55], v[54:55] op_sel_hi:[0,1]
	v_pk_add_f32 v[22:23], v[18:19], v[20:21] op_sel:[0,1] op_sel_hi:[1,0] neg_lo:[0,1] neg_hi:[0,1]
	v_pk_add_f32 v[18:19], v[18:19], v[20:21] op_sel:[0,1] op_sel_hi:[1,0]
	v_pk_add_f32 v[38:39], v[34:35], v[36:37] op_sel:[0,1] op_sel_hi:[1,0] neg_lo:[0,1] neg_hi:[0,1]
	v_pk_add_f32 v[34:35], v[34:35], v[36:37] op_sel:[0,1] op_sel_hi:[1,0]
	v_mov_b32_e32 v21, v19
	v_mov_b32_e32 v47, v53
	v_mov_b32_e32 v31, v43
	v_mov_b32_e32 v19, v23
	v_mov_b32_e32 v36, v38
	v_mov_b32_e32 v37, v35
	v_pk_add_f32 v[88:89], v[40:41], v[60:61]
	v_pk_add_f32 v[40:41], v[40:41], v[60:61] neg_lo:[0,1] neg_hi:[0,1]
	v_mov_b32_e32 v20, v22
	ds_write2st64_b64 v73, v[50:51], v[32:33] offset1:17
	ds_write2st64_b64 v73, v[86:87], v[88:89] offset0:34 offset1:51
	ds_write2st64_b64 v73, v[46:47], v[30:31] offset0:68 offset1:85
	ds_write2st64_b64 v73, v[36:37], v[20:21] offset0:102 offset1:119
	ds_write_b64 v75, v[26:27]
	ds_write_b64 v78, v[28:29]
	ds_write_b64 v80, v[58:59]
	ds_write_b64 v142, v[40:41]
	ds_write_b64 v146, v[18:19]
	v_lshlrev_b32_e32 v19, 16, v15
	v_lshlrev_b32_e32 v18, 16, v14
	v_pk_mul_f32 v[28:29], v[76:77], v[18:19]
	v_and_b32_e32 v21, 0xffff0000, v14
	v_mul_f32_e32 v22, v76, v71
	v_mov_b32_e32 v20, v18
	v_mov_b32_e32 v23, v28
	v_lshlrev_b32_e32 v27, 16, v17
	v_lshlrev_b32_e32 v26, 16, v16
	v_mul_f32_e32 v24, v77, v21
	v_pk_fma_f32 v[22:23], v[74:75], v[20:21], v[22:23] op_sel_hi:[0,1,1]
	v_mov_b32_e32 v25, v29
	v_mul_f32_e32 v18, v76, v21
	v_pk_add_f32 v[22:23], v[22:23], v[24:25]
	v_pk_mov_b32 v[24:25], v[18:19], v[26:27] op_sel:[1,0]
	v_and_b32_e32 v15, 0xffff0000, v15
	v_pk_mul_f32 v[24:25], v[76:77], v[24:25]
	v_mov_b32_e32 v14, v19
	v_mov_b32_e32 v19, v24
	v_mul_f32_e32 v20, v77, v15
	v_pk_fma_f32 v[18:19], v[74:75], v[14:15], v[18:19] op_sel_hi:[0,1,1]
	v_mov_b32_e32 v21, v25
	v_and_b32_e32 v16, 0xffff0000, v16
	v_pk_add_f32 v[18:19], v[18:19], v[20:21]
	v_pk_mul_f32 v[20:21], v[76:77], v[26:27]
	v_mul_f32_e32 v14, v76, v15
	v_mov_b32_e32 v28, v26
	v_mov_b32_e32 v29, v16
	v_mov_b32_e32 v15, v20
	v_pk_add_f32 v[24:25], v[72:73], v[18:19] op_sel_hi:[0,1]
	v_mul_f32_e32 v18, v77, v16
	v_pk_fma_f32 v[14:15], v[74:75], v[28:29], v[14:15] op_sel_hi:[0,1,1]
	v_mov_b32_e32 v19, v21
	v_and_b32_e32 v17, 0xffff0000, v17
	v_pk_add_f32 v[14:15], v[14:15], v[18:19]
	v_mov_b32_e32 v28, v77
	v_mov_b32_e32 v29, v76
	v_pk_add_f32 v[20:21], v[72:73], v[14:15] op_sel_hi:[0,1]
	v_pk_mul_f32 v[14:15], v[28:29], v[16:17] op_sel:[0,1] op_sel_hi:[1,0]
	v_lshlrev_b32_e32 v19, 16, v11
	v_lshlrev_b32_e32 v18, 16, v10
	v_fma_f32 v15, v74, v27, v15
	v_pk_mov_b32 v[26:27], v[26:27], v[18:19] op_sel:[1,0]
	v_and_b32_e32 v31, 0xffff0000, v10
	v_pk_mul_f32 v[26:27], v[76:77], v[26:27]
	v_lshlrev_b32_e32 v32, 16, v12
	v_lshlrev_b32_e32 v33, 16, v13
	v_fma_f32 v10, v74, v17, v26
	v_pk_mul_f32 v[36:37], v[76:77], v[18:19]
	v_add_f32_e32 v10, v10, v27
	v_mul_f32_e32 v16, v76, v17
	v_mov_b32_e32 v30, v18
	v_mov_b32_e32 v17, v36
	v_mov_b32_e32 v27, v37
	v_pk_mov_b32 v[36:37], v[18:19], v[32:33] op_sel:[1,0]
	v_mul_f32_e32 v26, v77, v31
	v_pk_fma_f32 v[16:17], v[74:75], v[30:31], v[16:17] op_sel_hi:[0,1,1]
	v_pk_mul_f32 v[36:37], v[76:77], v[36:37]
	v_add_f32_e32 v14, v14, v15
	v_and_b32_e32 v11, 0xffff0000, v11
	v_add_f32_e32 v15, v72, v10
	v_pk_add_f32 v[16:17], v[16:17], v[26:27]
	v_mul_f32_e32 v26, v76, v31
	v_mov_b32_e32 v10, v19
	v_mov_b32_e32 v27, v36
	v_mul_f32_e32 v30, v77, v11
	v_pk_fma_f32 v[18:19], v[74:75], v[10:11], v[26:27] op_sel_hi:[0,1,1]
	v_mov_b32_e32 v31, v37
	v_mov_b32_e32 v35, v39
	v_pk_add_f32 v[18:19], v[18:19], v[30:31]
	v_pk_mul_f32 v[30:31], v[76:77], v[32:33]
	ds_write_b64 v145, v[34:35]
	v_and_b32_e32 v35, 0xffff0000, v12
	v_mul_f32_e32 v10, v76, v11
	v_mov_b32_e32 v34, v32
	v_mov_b32_e32 v11, v30
	v_mul_f32_e32 v26, v77, v35
	v_pk_fma_f32 v[10:11], v[74:75], v[34:35], v[10:11] op_sel_hi:[0,1,1]
	v_mov_b32_e32 v27, v31
	v_mov_b32_e32 v80, v33
	v_pk_add_f32 v[10:11], v[10:11], v[26:27]
	v_mul_f32_e32 v26, v76, v35
	v_pk_mul_f32 v[34:35], v[76:77], v[80:81]
	v_and_b32_e32 v13, 0xffff0000, v13
	v_mov_b32_e32 v12, v33
	v_mov_b32_e32 v27, v34
	v_mul_f32_e32 v30, v77, v13
	v_pk_fma_f32 v[12:13], v[74:75], v[12:13], v[26:27] op_sel_hi:[0,1,1]
	v_lshlrev_b32_e32 v27, 16, v7
	v_lshlrev_b32_e32 v26, 16, v6
	v_mov_b32_e32 v31, v35
	v_pk_mul_f32 v[38:39], v[76:77], v[26:27]
	v_pk_add_f32 v[12:13], v[12:13], v[30:31]
	v_and_b32_e32 v31, 0xffff0000, v6
	v_mul_f32_e32 v34, v76, v1
	v_mov_b32_e32 v30, v26
	v_mov_b32_e32 v35, v38
	v_lshlrev_b32_e32 v33, 16, v9
	v_lshlrev_b32_e32 v32, 16, v8
	v_mul_f32_e32 v36, v77, v31
	v_pk_fma_f32 v[34:35], v[74:75], v[30:31], v[34:35] op_sel_hi:[0,1,1]
	v_mov_b32_e32 v37, v39
	v_mul_f32_e32 v26, v76, v31
	v_pk_add_f32 v[34:35], v[34:35], v[36:37]
	v_pk_mov_b32 v[36:37], v[26:27], v[32:33] op_sel:[1,0]
	v_and_b32_e32 v7, 0xffff0000, v7
	v_pk_mul_f32 v[36:37], v[76:77], v[36:37]
	v_and_b32_e32 v8, 0xffff0000, v8
	v_mov_b32_e32 v6, v27
	v_mov_b32_e32 v27, v36
	v_mov_b32_e32 v31, v37
	v_pk_mul_f32 v[36:37], v[76:77], v[32:33]
	v_mul_f32_e32 v30, v77, v7
	v_pk_fma_f32 v[26:27], v[74:75], v[6:7], v[26:27] op_sel_hi:[0,1,1]
	v_mul_f32_e32 v6, v76, v7
	v_mov_b32_e32 v38, v32
	v_mov_b32_e32 v39, v8
	v_mov_b32_e32 v7, v36
	v_pk_add_f32 v[26:27], v[26:27], v[30:31]
	v_mul_f32_e32 v30, v77, v8
	v_pk_fma_f32 v[6:7], v[74:75], v[38:39], v[6:7] op_sel_hi:[0,1,1]
	v_mov_b32_e32 v31, v37
	v_and_b32_e32 v9, 0xffff0000, v9
	v_pk_add_f32 v[6:7], v[6:7], v[30:31]
	v_and_b32_e32 v37, 0xffff0000, v2
	v_pk_add_f32 v[30:31], v[72:73], v[6:7] op_sel_hi:[0,1]
	v_pk_mul_f32 v[6:7], v[28:29], v[8:9] op_sel:[0,1] op_sel_hi:[1,0]
	v_lshlrev_b32_e32 v38, 16, v4
	v_fma_f32 v1, v74, v33, v7
	v_add_f32_e32 v1, v6, v1
	v_lshlrev_b32_e32 v7, 16, v3
	v_lshlrev_b32_e32 v6, 16, v2
	v_pk_mov_b32 v[32:33], v[32:33], v[6:7] op_sel:[1,0]
	v_pk_mul_f32 v[42:43], v[76:77], v[6:7]
	v_pk_mul_f32 v[32:33], v[76:77], v[32:33]
	v_add_f32_e32 v28, v72, v1
	v_lshlrev_b32_e32 v39, 16, v5
	v_fma_f32 v1, v74, v9, v32
	v_mul_f32_e32 v8, v76, v9
	v_mov_b32_e32 v36, v6
	v_mov_b32_e32 v9, v42
	v_add_f32_e32 v1, v1, v33
	v_mul_f32_e32 v32, v77, v37
	v_pk_fma_f32 v[8:9], v[74:75], v[36:37], v[8:9] op_sel_hi:[0,1,1]
	v_mov_b32_e32 v33, v43
	v_pk_mov_b32 v[42:43], v[6:7], v[38:39] op_sel:[1,0]
	v_pk_add_f32 v[8:9], v[8:9], v[32:33]
	v_pk_mul_f32 v[42:43], v[76:77], v[42:43]
	v_and_b32_e32 v3, 0xffff0000, v3
	v_pk_add_f32 v[32:33], v[72:73], v[8:9] op_sel_hi:[0,1]
	v_mul_f32_e32 v8, v76, v37
	v_mov_b32_e32 v2, v7
	v_mov_b32_e32 v9, v42
	v_mul_f32_e32 v36, v77, v3
	v_pk_fma_f32 v[6:7], v[74:75], v[2:3], v[8:9] op_sel_hi:[0,1,1]
	v_mov_b32_e32 v37, v43
	v_pk_mul_f32 v[8:9], v[76:77], v[38:39]
	v_and_b32_e32 v41, 0xffff0000, v4
	v_pk_add_f32 v[6:7], v[6:7], v[36:37]
	v_mul_f32_e32 v2, v76, v3
	v_mov_b32_e32 v40, v38
	v_mov_b32_e32 v3, v8
	v_pk_add_f32 v[48:49], v[48:49], v[48:49] op_sel:[0,1] op_sel_hi:[1,0]
	v_pk_add_f32 v[44:45], v[44:45], v[44:45] op_sel_hi:[0,1] neg_lo:[0,1] neg_hi:[0,1]
	v_pk_add_f32 v[56:57], v[56:57], v[56:57] op_sel:[0,1] op_sel_hi:[1,0]
	v_pk_add_f32 v[54:55], v[54:55], v[54:55] op_sel_hi:[0,1] neg_lo:[0,1] neg_hi:[0,1]
	v_pk_add_f32 v[36:37], v[72:73], v[6:7] op_sel_hi:[0,1]
	v_mul_f32_e32 v6, v77, v41
	v_pk_fma_f32 v[2:3], v[74:75], v[40:41], v[2:3] op_sel_hi:[0,1,1]
	v_mov_b32_e32 v7, v9
	v_mov_b32_e32 v78, v39
	v_mov_b32_e32 v49, v45
	v_mov_b32_e32 v57, v55
	v_mov_b32_e32 v46, v0
	v_pk_add_f32 v[2:3], v[2:3], v[6:7]
	v_pk_mul_f32 v[8:9], v[76:77], v[78:79]
	ds_write_b64 v143, v[48:49]
	ds_write_b64 v144, v[56:57]
	s_waitcnt lgkmcnt(0)
	s_barrier
	v_and_b32_e32 v5, 0xffff0000, v5
	v_add_f32_e32 v29, v72, v1
	v_pk_add_f32 v[42:43], v[72:73], v[2:3] op_sel_hi:[0,1]
	v_mul_f32_e32 v2, v76, v41
	v_mov_b32_e32 v4, v39
	v_mov_b32_e32 v3, v8
	v_mul_lo_u32 v1, v46, s33
	v_mul_f32_e32 v6, v77, v5
	v_pk_fma_f32 v[2:3], v[74:75], v[4:5], v[2:3] op_sel_hi:[0,1,1]
	v_mov_b32_e32 v7, v9
	v_add_u32_e32 v1, 0, v1
	v_pk_add_f32 v[6:7], v[2:3], v[6:7]
	ds_read2_b64 v[2:5], v1 offset1:1
	v_pk_add_f32 v[38:39], v[72:73], v[6:7] op_sel_hi:[0,1]
	ds_read2_b64 v[6:9], v1 offset0:2 offset1:3
	v_mov_b32_e32 v41, v82
	v_mov_b32_e32 v82, v65
	s_waitcnt lgkmcnt(1)
	v_mov_b32_e32 v45, v4
	v_mov_b32_e32 v4, v3
	v_pk_add_f32 v[34:35], v[72:73], v[34:35] op_sel_hi:[0,1]
	v_mov_b32_e32 v44, v2
	v_pk_fma_f32 v[2:3], v[70:71], v[82:83], v[4:5] op_sel_hi:[0,1,1]
	v_pk_mul_f32 v[34:35], v[34:35], v[2:3]
	v_mov_b32_e32 v2, v62
	v_mov_b32_e32 v3, v98
	s_waitcnt lgkmcnt(0)
	v_mov_b32_e32 v4, v6
	v_mov_b32_e32 v5, v8
	v_pk_fma_f32 v[2:3], v[70:71], v[2:3], v[4:5] op_sel_hi:[0,1,1]
	v_pk_mul_f32 v[24:25], v[24:25], v[2:3]
	v_mov_b32_e32 v98, v63
	v_mov_b32_e32 v8, v7
	ds_read2_b64 v[2:5], v1 offset0:4 offset1:5
	v_pk_add_f32 v[26:27], v[72:73], v[26:27] op_sel_hi:[0,1]
	v_pk_fma_f32 v[6:7], v[70:71], v[98:99], v[8:9] op_sel_hi:[0,1,1]
	v_pk_mul_f32 v[26:27], v[26:27], v[6:7]
	ds_read2_b64 v[6:9], v1 offset0:6 offset1:7
	v_mov_b32_e32 v40, v64
	v_pk_add_f32 v[22:23], v[72:73], v[22:23] op_sel_hi:[0,1]
	v_pk_fma_f32 v[40:41], v[70:71], v[40:41], v[44:45] op_sel_hi:[0,1,1]
	v_pk_mul_f32 v[22:23], v[22:23], v[40:41]
	v_mov_b32_e32 v41, v102
	s_waitcnt lgkmcnt(1)
	v_mov_b32_e32 v45, v4
	v_mov_b32_e32 v102, v101
	v_mov_b32_e32 v4, v3
	v_mov_b32_e32 v44, v2
	v_pk_fma_f32 v[2:3], v[70:71], v[102:103], v[4:5] op_sel_hi:[0,1,1]
	v_pk_mul_f32 v[30:31], v[30:31], v[2:3]
	v_mov_b32_e32 v2, v84
	v_mov_b32_e32 v3, v110
	s_waitcnt lgkmcnt(0)
	v_mov_b32_e32 v4, v6
	v_mov_b32_e32 v5, v8
	v_add_f32_e32 v14, v72, v14
	v_pk_fma_f32 v[2:3], v[70:71], v[2:3], v[4:5] op_sel_hi:[0,1,1]
	v_pk_mul_f32 v[14:15], v[14:15], v[2:3]
	v_mov_b32_e32 v110, v85
	v_mov_b32_e32 v8, v7
	ds_read2_b64 v[2:5], v1 offset0:8 offset1:9
	v_pk_fma_f32 v[6:7], v[70:71], v[110:111], v[8:9] op_sel_hi:[0,1,1]
	v_pk_mul_f32 v[28:29], v[28:29], v[6:7]
	ds_read2_b64 v[6:9], v1 offset0:10 offset1:11
	v_mov_b32_e32 v40, v100
	v_pk_fma_f32 v[40:41], v[70:71], v[40:41], v[44:45] op_sel_hi:[0,1,1]
	v_pk_mul_f32 v[20:21], v[20:21], v[40:41]
	v_mov_b32_e32 v41, v108
	s_waitcnt lgkmcnt(1)
	v_mov_b32_e32 v45, v4
	v_mov_b32_e32 v108, v107
	v_mov_b32_e32 v4, v3
	v_mov_b32_e32 v44, v2
	v_pk_fma_f32 v[2:3], v[70:71], v[108:109], v[4:5] op_sel_hi:[0,1,1]
	v_pk_mul_f32 v[32:33], v[32:33], v[2:3]
	v_mov_b32_e32 v2, v104
	v_mov_b32_e32 v3, v112
	s_waitcnt lgkmcnt(0)
	v_mov_b32_e32 v4, v6
	v_mov_b32_e32 v5, v8
	v_pk_add_f32 v[18:19], v[72:73], v[18:19] op_sel_hi:[0,1]
	v_pk_fma_f32 v[2:3], v[70:71], v[2:3], v[4:5] op_sel_hi:[0,1,1]
	v_pk_mul_f32 v[18:19], v[18:19], v[2:3]
	v_mov_b32_e32 v112, v105
	v_mov_b32_e32 v8, v7
	ds_read2_b64 v[2:5], v1 offset0:12 offset1:13
	v_pk_fma_f32 v[6:7], v[70:71], v[112:113], v[8:9] op_sel_hi:[0,1,1]
	v_pk_mul_f32 v[36:37], v[36:37], v[6:7]
	ds_read2_b64 v[6:9], v1 offset0:14 offset1:15
	v_mov_b32_e32 v40, v106
	v_pk_add_f32 v[16:17], v[72:73], v[16:17] op_sel_hi:[0,1]
	v_pk_fma_f32 v[40:41], v[70:71], v[40:41], v[44:45] op_sel_hi:[0,1,1]
	v_pk_mul_f32 v[16:17], v[16:17], v[40:41]
	v_mov_b32_e32 v40, v116
	v_mov_b32_e32 v41, v120
	s_waitcnt lgkmcnt(1)
	v_mov_b32_e32 v44, v2
	v_mov_b32_e32 v45, v4
	v_mov_b32_e32 v120, v117
	v_mov_b32_e32 v4, v3
	v_pk_add_f32 v[10:11], v[72:73], v[10:11] op_sel_hi:[0,1]
	v_pk_fma_f32 v[40:41], v[70:71], v[40:41], v[44:45] op_sel_hi:[0,1,1]
	v_pk_fma_f32 v[2:3], v[70:71], v[120:121], v[4:5] op_sel_hi:[0,1,1]
	v_pk_mul_f32 v[10:11], v[10:11], v[40:41]
	v_pk_mul_f32 v[40:41], v[42:43], v[2:3]
	v_mov_b32_e32 v2, v114
	v_mov_b32_e32 v3, v118
	s_waitcnt lgkmcnt(0)
	v_mov_b32_e32 v4, v6
	v_mov_b32_e32 v5, v8
	v_pk_add_f32 v[12:13], v[72:73], v[12:13] op_sel_hi:[0,1]
	v_pk_fma_f32 v[2:3], v[70:71], v[2:3], v[4:5] op_sel_hi:[0,1,1]
	v_mov_b32_e32 v118, v115
	v_mov_b32_e32 v8, v7
	v_pk_mul_f32 v[12:13], v[12:13], v[2:3]
	v_pk_fma_f32 v[2:3], v[70:71], v[118:119], v[8:9] op_sel_hi:[0,1,1]
	v_pk_mul_f32 v[6:7], v[38:39], v[2:3]
	v_lshlrev_b32_e32 v2, 4, v46
	v_ashrrev_i32_e32 v3, 31, v2
	v_lshl_add_u64 v[8:9], v[2:3], 1, s[42:43]
	v_cvt_pk_bf16_f32 v2, v22, v23
	v_cvt_pk_bf16_f32 v3, v24, v25
	v_cvt_pk_bf16_f32 v4, v20, v21
	v_cvt_pk_bf16_f32 v5, v14, v15
	global_store_dwordx4 v[8:9], v[2:5], off
	s_nop 1
	v_cvt_pk_bf16_f32 v2, v16, v17
	v_cvt_pk_bf16_f32 v3, v18, v19
	v_cvt_pk_bf16_f32 v4, v10, v11
	v_cvt_pk_bf16_f32 v5, v12, v13
	global_store_dwordx4 v[8:9], v[2:5], off offset:16
	v_lshl_add_u64 v[10:11], v[8:9], 0, s[4:5]
	v_add_co_u32_e32 v8, vcc, s22, v8
	v_cvt_pk_bf16_f32 v2, v34, v35
	v_cvt_pk_bf16_f32 v3, v26, v27
	v_cvt_pk_bf16_f32 v4, v30, v31
	v_cvt_pk_bf16_f32 v5, v28, v29
	v_addc_co_u32_e32 v9, vcc, 0, v9, vcc
	global_store_dwordx4 v[8:9], v[2:5], off
	s_nop 1
	v_cvt_pk_bf16_f32 v2, v32, v33
	v_cvt_pk_bf16_f32 v3, v36, v37
	v_cvt_pk_bf16_f32 v4, v40, v41
	v_cvt_pk_bf16_f32 v5, v6, v7
	global_store_dwordx4 v[10:11], v[2:5], off offset:16
	s_barrier

.LBB0_383:
	s_add_i32 s73, s71, 3
	s_and_b64 s[4:5], s[22:23], exec
	s_cselect_b32 s3, s73, s3
	s_mul_i32 s3, s3, s58
	s_add_i32 s4, s3, s97
	s_and_b32 s3, s72, 0x2000
	s_ashr_i32 s5, s4, 31
	s_bitset1_b32 s3, 14
	s_lshl_b64 s[46:47], s[4:5], 16
	s_add_u32 s12, s0, s46
	s_addc_u32 s13, s1, s47
	s_and_b64 s[10:11], s[22:23], exec
	s_cselect_b32 s3, 0, s3
	s_lshl_b32 s3, s3, 1
	s_add_u32 s50, s12, s3
	v_cndmask_b32_e64 v1, 0, 1, s[22:23]
	s_addc_u32 s51, s13, 0
	s_add_i32 s22, s4, 0x400
	s_ashr_i32 s23, s22, 31
	s_lshl_b64 s[44:45], s[22:23], 16
	s_add_u32 s10, s0, s44
	s_addc_u32 s11, s1, s45
	s_add_u32 s48, s10, s3
	s_addc_u32 s49, s11, 0
	s_add_i32 s10, s4, 0x800
	s_ashr_i32 s11, s10, 31
	s_lshl_b64 s[12:13], s[10:11], 16
	s_add_u32 s12, s0, s12
	s_addc_u32 s13, s1, s13
	s_add_u32 s52, s12, s3
	s_addc_u32 s53, s13, 0
	s_add_u32 s12, s54, s46
	s_addc_u32 s13, s55, s47
	s_add_u32 s42, s12, s3
	s_addc_u32 s43, s13, 0
	s_lshl_b64 s[12:13], s[4:5], 2
	s_add_u32 s30, s59, s12
	s_addc_u32 s31, s64, s13
	s_add_i32 s38, s4, 0xc00
	s_ashr_i32 s39, s38, 31
	s_lshl_b64 s[38:39], s[38:39], 2
	s_add_u32 s38, s59, s38
	s_addc_u32 s39, s64, s39
	s_add_i32 s60, s4, 0x1800
	s_ashr_i32 s61, s60, 31
	s_lshl_b64 s[60:61], s[60:61], 2
	s_add_u32 s60, s59, s60
	s_addc_u32 s61, s64, s61
	s_add_u32 s74, s65, s12
	s_addc_u32 s75, s68, s13
	s_lshl_b64 s[76:77], s[22:23], 2
	s_add_u32 s78, s59, s76
	s_addc_u32 s79, s64, s77
	s_add_i32 s80, s4, 0x1000
	s_ashr_i32 s81, s80, 31
	s_lshl_b64 s[80:81], s[80:81], 2
	s_add_u32 s80, s59, s80
	s_addc_u32 s81, s64, s81
	s_add_i32 s82, s4, 0x1c00
	s_ashr_i32 s83, s82, 31
	s_lshl_b64 s[82:83], s[82:83], 2
	s_add_u32 s82, s59, s82
	s_addc_u32 s83, s64, s83
	s_add_u32 s84, s65, s76
	s_addc_u32 s85, s68, s77
	s_lshl_b64 s[10:11], s[10:11], 2
	s_add_u32 s86, s59, s10
	s_addc_u32 s87, s64, s11
	s_add_i32 vcc_lo, s4, 0x1400
	s_ashr_i32 vcc_hi, vcc_lo, 31
	s_lshl_b64 vcc, vcc, 2
	s_add_u32 s40, s59, vcc_lo
	s_addc_u32 s41, s64, vcc_hi
	s_add_i32 vcc_lo, s4, 0x2000
	s_ashr_i32 vcc_hi, vcc_lo, 31
	s_lshl_b64 vcc, vcc, 2
	s_add_u32 s62, s59, vcc_lo
	s_addc_u32 s63, s64, vcc_hi
	s_add_u32 s10, s65, s10
	s_addc_u32 s11, s68, s11
	s_add_u32 s12, s69, s12
	s_addc_u32 s13, s70, s13
	s_add_u32 s76, s69, s76
	s_addc_u32 s77, s70, s77
	global_load_dword v84, v191, s[30:31]
	global_load_dword v83, v191, s[38:39]
	global_load_dword v82, v191, s[60:61]
	global_load_dword v80, v191, s[74:75]
	global_load_dword v76, v191, s[78:79]
	global_load_dword v74, v191, s[80:81]
	global_load_dword v77, v191, s[82:83]
	global_load_dword v72, v191, s[84:85]
	global_load_dword v50, v191, s[86:87]
	global_load_dword v56, v191, s[40:41]
	global_load_dword v54, v191, s[62:63]
	global_load_dword v52, v191, s[10:11]
	global_load_dword v78, v191, s[12:13]
	global_load_dword v70, v191, s[76:77]
	v_cmp_ne_u32_e32 vcc, 1, v1
	v_readlane_b32 s60, v255, 33
	v_readlane_b32 s61, v255, 34
	s_mov_b64 s[30:31], -1
	s_cbranch_vccz .LBB0_409
	v_mov_b32_e32 v1, v0
	v_mov_b32_e32 v34, 0
	v_lshlrev_b32_e32 v26, 3, v1
	v_ashrrev_i32_e32 v27, 31, v26
	v_lshl_add_u64 v[2:3], v[26:27], 1, s[52:53]
	global_load_dwordx4 v[18:21], v[2:3], off
	v_cmp_lt_i32_e32 vcc, 0, v1
	v_mov_b32_e32 v36, 0
	v_mov_b32_e32 v234, 0
	s_and_saveexec_b64 s[30:31], vcc
	s_cbranch_execz .LBB0_386
	global_load_ushort v234, v[2:3], off offset:-2
.LBB0_386:
	s_or_b64 exec, exec, s[30:31]
	s_movk_i32 s3, 0x1ff
	v_cmp_gt_i32_e64 s[38:39], s3, v1
	v_mov_b32_e32 v235, 0
	s_and_saveexec_b64 s[30:31], s[38:39]
	s_cbranch_execz .LBB0_388
	global_load_ushort v235, v[2:3], off offset:16
.LBB0_388:
	s_or_b64 exec, exec, s[30:31]
	s_add_u32 s10, s52, 0x2000
	s_addc_u32 s11, s53, 0
	v_lshl_add_u64 v[2:3], v[26:27], 1, s[10:11]
	global_load_dwordx4 v[22:25], v[2:3], off
	v_mov_b32_e32 v35, 0
	v_mov_b32_e32 v37, 0
	v_mov_b32_e32 v243, 0
	s_and_saveexec_b64 s[30:31], vcc
	s_cbranch_execz .LBB0_390
	global_load_ushort v243, v[2:3], off offset:-2
.LBB0_390:
	s_or_b64 exec, exec, s[30:31]
	v_mov_b32_e32 v244, 0
	s_and_saveexec_b64 s[30:31], s[38:39]
	s_cbranch_execz .LBB0_392
	global_load_ushort v244, v[2:3], off offset:16
.LBB0_392:
	s_or_b64 exec, exec, s[30:31]
	v_lshl_add_u64 v[2:3], v[26:27], 1, s[50:51]
	global_load_dwordx4 v[10:13], v[2:3], off
	v_mov_b32_e32 v60, 0
	v_mov_b32_e32 v62, 0
	v_mov_b32_e32 v245, 0
	s_and_saveexec_b64 s[30:31], vcc
	s_cbranch_execz .LBB0_394
	global_load_ushort v245, v[2:3], off offset:-2
.LBB0_394:
	s_or_b64 exec, exec, s[30:31]
	v_mov_b32_e32 v246, 0
	s_and_saveexec_b64 s[30:31], s[38:39]
	s_cbranch_execz .LBB0_396
	global_load_ushort v246, v[2:3], off offset:16
.LBB0_396:
	s_or_b64 exec, exec, s[30:31]
	s_add_u32 s10, s50, 0x2000
	s_addc_u32 s11, s51, 0
	v_lshl_add_u64 v[2:3], v[26:27], 1, s[10:11]
	global_load_dwordx4 v[14:17], v[2:3], off
	v_mov_b32_e32 v61, 0
	v_mov_b32_e32 v63, 0
	v_mov_b32_e32 v247, 0
	s_and_saveexec_b64 s[30:31], vcc
	s_cbranch_execz .LBB0_398
	global_load_ushort v247, v[2:3], off offset:-2
.LBB0_398:
	s_or_b64 exec, exec, s[30:31]
	v_mov_b32_e32 v248, 0
	s_and_saveexec_b64 s[30:31], s[38:39]
	s_cbranch_execz .LBB0_400
	global_load_ushort v248, v[2:3], off offset:16
.LBB0_400:
	s_or_b64 exec, exec, s[30:31]
	v_lshl_add_u64 v[2:3], v[26:27], 1, s[48:49]
	global_load_dwordx4 v[6:9], v[2:3], off
	v_mov_b32_e32 v33, 0
	v_mov_b32_e32 v31, 0
	v_mov_b32_e32 v249, 0
	s_and_saveexec_b64 s[30:31], vcc
	s_cbranch_execz .LBB0_402
	global_load_ushort v249, v[2:3], off offset:-2
.LBB0_402:
	s_or_b64 exec, exec, s[30:31]
	v_mov_b32_e32 v250, 0
	s_and_saveexec_b64 s[30:31], s[38:39]
	s_cbranch_execz .LBB0_404
	global_load_ushort v250, v[2:3], off offset:16
.LBB0_404:
	s_or_b64 exec, exec, s[30:31]
	s_add_u32 s10, s48, 0x2000
	s_addc_u32 s11, s49, 0
	v_lshl_add_u64 v[38:39], v[26:27], 1, s[10:11]
	global_load_dwordx4 v[2:5], v[38:39], off
	v_mov_b32_e32 v29, 0
	v_mov_b32_e32 v27, 0
	v_mov_b32_e32 v251, 0
	s_and_saveexec_b64 s[30:31], vcc
	s_cbranch_execz .LBB0_406
	global_load_ushort v251, v[38:39], off offset:-2
.LBB0_406:
	s_or_b64 exec, exec, s[30:31]
	s_lshl_b64 s[30:31], s[4:5], 15
	v_mov_b32_e32 v252, 0
	s_and_saveexec_b64 s[4:5], s[38:39]
	s_cbranch_execz .LBB0_408
	global_load_ushort v252, v[38:39], off offset:16
.LBB0_408:
	s_or_b64 exec, exec, s[4:5]
	s_waitcnt vmcnt(0)
	v_lshlrev_b32_e32 v36, 16, v234
	v_lshlrev_b32_e32 v34, 16, v235
	v_lshlrev_b32_e32 v37, 16, v243
	v_lshlrev_b32_e32 v35, 16, v244
	v_lshlrev_b32_e32 v62, 16, v245
	v_lshlrev_b32_e32 v60, 16, v246
	v_lshlrev_b32_e32 v63, 16, v247
	v_lshlrev_b32_e32 v61, 16, v248
	v_lshlrev_b32_e32 v31, 16, v249
	v_lshlrev_b32_e32 v33, 16, v250
	v_lshlrev_b32_e32 v27, 16, v251
	v_lshlrev_b32_e32 v29, 16, v252
	v_pk_mul_f32 v[36:37], v[50:51], v[36:37] op_sel_hi:[0,1]
	v_lshlrev_b32_e32 v39, 16, v22
	v_lshlrev_b32_e32 v38, 16, v18
	v_and_b32_e32 v41, 0xffff0000, v22
	v_and_b32_e32 v40, 0xffff0000, v18
	v_pk_fma_f32 v[36:37], v[56:57], v[38:39], v[36:37] op_sel_hi:[0,1,1]
	v_pk_fma_f32 v[36:37], v[54:55], v[40:41], v[36:37] op_sel_hi:[0,1,1]
	v_pk_add_f32 v[100:101], v[52:53], v[36:37] op_sel_hi:[0,1]
	v_lshlrev_b32_e32 v37, 16, v23
	v_lshlrev_b32_e32 v36, 16, v19
	v_pk_mul_f32 v[42:43], v[56:57], v[40:41] op_sel_hi:[0,1]
	v_pk_fma_f32 v[38:39], v[50:51], v[38:39], v[42:43] op_sel_hi:[0,1,1]
	v_and_b32_e32 v22, 0xffff0000, v19
	v_pk_mul_f32 v[18:19], v[56:57], v[36:37] op_sel_hi:[0,1]
	v_pk_fma_f32 v[38:39], v[54:55], v[36:37], v[38:39] op_sel_hi:[0,1,1]
	v_and_b32_e32 v23, 0xffff0000, v23
	v_pk_fma_f32 v[18:19], v[50:51], v[40:41], v[18:19] op_sel_hi:[0,1,1]
	v_pk_add_f32 v[102:103], v[52:53], v[38:39] op_sel_hi:[0,1]
	v_pk_fma_f32 v[18:19], v[54:55], v[22:23], v[18:19] op_sel_hi:[0,1,1]
	v_pk_mul_f32 v[38:39], v[56:57], v[22:23] op_sel_hi:[0,1]
	v_pk_add_f32 v[98:99], v[52:53], v[18:19] op_sel_hi:[0,1]
	v_lshlrev_b32_e32 v19, 16, v24
	v_lshlrev_b32_e32 v18, 16, v20
	v_pk_fma_f32 v[36:37], v[50:51], v[36:37], v[38:39] op_sel_hi:[0,1,1]
	v_pk_fma_f32 v[36:37], v[54:55], v[18:19], v[36:37] op_sel_hi:[0,1,1]
	v_pk_mul_f32 v[38:39], v[56:57], v[18:19] op_sel_hi:[0,1]
	v_pk_add_f32 v[96:97], v[52:53], v[36:37] op_sel_hi:[0,1]
	v_and_b32_e32 v37, 0xffff0000, v24
	v_and_b32_e32 v36, 0xffff0000, v20
	v_pk_fma_f32 v[22:23], v[50:51], v[22:23], v[38:39] op_sel_hi:[0,1,1]
	v_pk_fma_f32 v[22:23], v[54:55], v[36:37], v[22:23] op_sel_hi:[0,1,1]
	v_pk_mul_f32 v[38:39], v[56:57], v[36:37] op_sel_hi:[0,1]
	v_pk_add_f32 v[94:95], v[52:53], v[22:23] op_sel_hi:[0,1]
	v_lshlrev_b32_e32 v23, 16, v25
	v_lshlrev_b32_e32 v22, 16, v21
	v_pk_fma_f32 v[18:19], v[50:51], v[18:19], v[38:39] op_sel_hi:[0,1,1]
	v_pk_fma_f32 v[18:19], v[54:55], v[22:23], v[18:19] op_sel_hi:[0,1,1]
	v_pk_add_f32 v[92:93], v[52:53], v[18:19] op_sel_hi:[0,1]
	v_and_b32_e32 v18, 0xffff0000, v21
	v_pk_mul_f32 v[20:21], v[56:57], v[22:23] op_sel_hi:[0,1]
	v_and_b32_e32 v19, 0xffff0000, v25
	v_pk_fma_f32 v[20:21], v[50:51], v[36:37], v[20:21] op_sel_hi:[0,1,1]
	v_pk_fma_f32 v[20:21], v[54:55], v[18:19], v[20:21] op_sel_hi:[0,1,1]
	v_pk_mul_f32 v[18:19], v[56:57], v[18:19] op_sel_hi:[0,1]
	v_pk_fma_f32 v[18:19], v[50:51], v[22:23], v[18:19] op_sel_hi:[0,1,1]
	v_pk_fma_f32 v[18:19], v[54:55], v[34:35], v[18:19] op_sel_hi:[0,1,1]
	v_lshlrev_b32_e32 v1, 2, v1
	v_pk_add_f32 v[64:65], v[52:53], v[18:19] op_sel_hi:[0,1]
	v_and_b32_e32 v1, -8, v1
	v_lshlrev_b32_e32 v18, 3, v26
	v_add3_u32 v1, 0, v1, v18
	s_mov_b32 s66, s67
	s_mov_b32 s10, s67
	s_mov_b32 s11, s67
	v_add_u32_e32 v18, 0x8800, v1
	v_mov_b64_e32 v[88:89], s[66:67]
	v_mov_b64_e32 v[90:91], s[10:11]
	ds_write2_b64 v18, v[88:89], v[90:91] offset1:1
	v_add_u32_e32 v18, 0x8810, v1
	ds_write2_b64 v1, v[100:101], v[102:103] offset1:1
	ds_write2_b64 v1, v[98:99], v[96:97] offset0:2 offset1:3
	ds_write2_b64 v18, v[88:89], v[90:91] offset1:1
	v_add_u32_e32 v18, 0x8820, v1
	v_pk_add_f32 v[86:87], v[52:53], v[20:21] op_sel_hi:[0,1]
	ds_write2_b64 v1, v[94:95], v[92:93] offset0:4 offset1:5
	ds_write2_b64 v18, v[88:89], v[90:91] offset1:1
	v_add_u32_e32 v18, 0x8830, v1
	ds_write2_b64 v1, v[86:87], v[64:65] offset0:6 offset1:7
	ds_write2_b64 v18, v[88:89], v[90:91] offset1:1
	v_lshl_add_u64 v[18:19], v[66:67], 0, s[30:31]
	s_movk_i32 s3, 0x2000
	v_add_co_u32_e32 v22, vcc, s3, v18
	s_lshl_b64 s[4:5], s[22:23], 15
	s_nop 0
	v_addc_co_u32_e32 v23, vcc, 0, v19, vcc
	s_movk_i32 s22, 0x4000
	v_add_co_u32_e32 v20, vcc, s22, v18
	s_movk_i32 s23, 0x6000
	s_nop 0
	v_addc_co_u32_e32 v21, vcc, 0, v19, vcc
	v_add_co_u32_e32 v24, vcc, s23, v18
	s_waitcnt lgkmcnt(0)
	s_nop 0
	v_addc_co_u32_e32 v25, vcc, 0, v19, vcc
	s_barrier
	global_load_dwordx2 v[46:47], v[20:21], off offset:-4096
	global_load_dwordx2 v[38:39], v[20:21], off
	global_load_dwordx2 v[34:35], v[24:25], off offset:-4096
	s_nop 0
	global_load_dwordx2 v[20:21], v[24:25], off
	v_add_co_u32_e32 v24, vcc, s89, v18
	v_mov_b32_e32 v1, v0
	s_nop 0
	v_addc_co_u32_e32 v25, vcc, 0, v19, vcc
	global_load_dwordx2 v[104:105], v[18:19], off
	global_load_dwordx2 v[58:59], v[22:23], off offset:-4096
	global_load_dwordx2 v[48:49], v[22:23], off
	s_nop 0
	global_load_dwordx2 v[18:19], v[24:25], off
	s_movk_i32 s29, 0xe000
	v_and_b32_e32 v22, 0x1ff, v1
	v_lshlrev_b32_e32 v1, 4, v1
	v_and_or_b32 v1, v1, s29, v22
	v_ashrrev_i32_e32 v23, 4, v1
	v_cvt_f32_u32_e32 v22, v22
	v_lshlrev_b32_e32 v23, 3, v23
	v_lshlrev_b32_e32 v1, 3, v1
	v_add3_u32 v1, 0, v23, v1
	ds_read_b64 v[108:109], v1
	ds_read_b64 v[36:37], v1 offset:4352
	ds_read_b64 v[42:43], v1 offset:8704
	ds_read_b64 v[44:45], v1 offset:13056
	ds_read_b64 v[110:111], v1 offset:17408
	ds_read_b64 v[112:113], v1 offset:21760
	ds_read_b64 v[114:115], v1 offset:26112
	ds_read_b64 v[116:117], v1 offset:30464
	ds_read_b64 v[118:119], v1 offset:34816
	ds_read_b64 v[120:121], v1 offset:39168
	ds_read_b64 v[122:123], v1 offset:43520
	ds_read_b64 v[124:125], v1 offset:47872
	ds_read_b64 v[126:127], v1 offset:56576
	ds_read_b64 v[128:129], v1 offset:60928
	ds_read_b64 v[130:131], v1 offset:65280
	ds_read_b64 v[132:133], v1 offset:52224
	v_mul_f32_e32 v22, 0x39000000, v22
	v_cos_f32_e32 v106, v22
	v_sin_f32_e32 v26, v22
	s_waitcnt lgkmcnt(6)
	v_pk_add_f32 v[22:23], v[36:37], v[120:121] neg_lo:[0,1] neg_hi:[0,1]
	s_waitcnt lgkmcnt(3)
	v_pk_add_f32 v[24:25], v[112:113], v[126:127] neg_lo:[0,1] neg_hi:[0,1]
	v_pk_add_f32 v[36:37], v[36:37], v[120:121]
	v_pk_add_f32 v[40:41], v[22:23], v[24:25] op_sel:[0,1] op_sel_hi:[1,0]
	v_pk_add_f32 v[134:135], v[22:23], v[24:25] op_sel:[0,1] op_sel_hi:[1,0] neg_lo:[0,1] neg_hi:[0,1]
	v_mov_b32_e32 v22, v40
	v_mov_b32_e32 v23, v135
	v_mov_b32_e32 v135, v41
	v_pk_add_f32 v[24:25], v[42:43], v[122:123] neg_lo:[0,1] neg_hi:[0,1]
	s_waitcnt lgkmcnt(2)
	v_pk_add_f32 v[40:41], v[114:115], v[128:129] neg_lo:[0,1] neg_hi:[0,1]
	v_pk_add_f32 v[112:113], v[112:113], v[126:127]
	v_pk_add_f32 v[136:137], v[24:25], v[40:41] op_sel:[0,1] op_sel_hi:[1,0]
	v_pk_add_f32 v[138:139], v[24:25], v[40:41] op_sel:[0,1] op_sel_hi:[1,0] neg_lo:[0,1] neg_hi:[0,1]
	v_pk_add_f32 v[24:25], v[44:45], v[124:125] neg_lo:[0,1] neg_hi:[0,1]
	s_waitcnt lgkmcnt(1)
	v_pk_add_f32 v[40:41], v[116:117], v[130:131] neg_lo:[0,1] neg_hi:[0,1]
	v_pk_add_f32 v[120:121], v[36:37], v[112:113]
	v_pk_add_f32 v[36:37], v[36:37], v[112:113] neg_lo:[0,1] neg_hi:[0,1]
	v_pk_add_f32 v[42:43], v[42:43], v[122:123]
	v_pk_add_f32 v[112:113], v[114:115], v[128:129]
	v_mov_b32_e32 v140, v136
	v_mov_b32_e32 v141, v139
	v_mov_b32_e32 v139, v137
	v_pk_add_f32 v[136:137], v[24:25], v[40:41] op_sel:[0,1] op_sel_hi:[1,0]
	v_pk_add_f32 v[142:143], v[24:25], v[40:41] op_sel:[0,1] op_sel_hi:[1,0] neg_lo:[0,1] neg_hi:[0,1]
	v_mov_b64_e32 v[40:41], s[6:7]
	v_pk_mul_f32 v[24:25], v[22:23], v[40:41] op_sel:[0,0] op_sel_hi:[0,1]
	v_pk_add_f32 v[114:115], v[42:43], v[112:113]
	v_pk_add_f32 v[112:113], v[42:43], v[112:113] neg_lo:[0,1] neg_hi:[0,1]
	v_pk_add_f32 v[42:43], v[44:45], v[124:125]
	v_pk_add_f32 v[44:45], v[116:117], v[130:131]
	v_mov_b32_e32 v144, v136
	v_mov_b32_e32 v145, v143
	v_mov_b32_e32 v143, v137
	v_pk_fma_f32 v[136:137], v[22:23], v[40:41], v[24:25] op_sel:[1,1,0] op_sel_hi:[1,0,1] neg_lo:[1,0,0]
	v_mov_b64_e32 v[24:25], s[16:17]
	v_pk_add_f32 v[116:117], v[42:43], v[44:45]
	v_pk_add_f32 v[44:45], v[42:43], v[44:45] neg_lo:[0,1] neg_hi:[0,1]
	v_pk_mul_f32 v[42:43], v[36:37], v[24:25] op_sel:[0,0] op_sel_hi:[0,1]
	v_pk_mul_f32 v[22:23], v[140:141], v[24:25] op_sel:[0,0] op_sel_hi:[0,1]
	s_waitcnt lgkmcnt(0)
	v_pk_add_f32 v[148:149], v[110:111], v[132:133]
	v_pk_fma_f32 v[122:123], v[36:37], v[24:25], v[42:43] op_sel:[1,1,0] op_sel_hi:[1,0,1] neg_lo:[1,0,0]
	v_mov_b64_e32 v[42:43], s[60:61]
	v_pk_mul_f32 v[36:37], v[112:113], v[42:43] op_sel:[0,0] op_sel_hi:[0,1]
	v_pk_fma_f32 v[140:141], v[140:141], v[24:25], v[22:23] op_sel:[1,1,0] op_sel_hi:[1,0,1] neg_lo:[1,0,0]
	v_mov_b64_e32 v[22:23], s[18:19]
	v_pk_mul_f32 v[146:147], v[144:145], v[22:23] op_sel:[0,0] op_sel_hi:[0,1]
	v_pk_fma_f32 v[112:113], v[112:113], v[42:43], v[36:37] op_sel:[1,1,0] op_sel_hi:[1,0,1] neg_lo:[1,0,0]
	v_mov_b64_e32 v[36:37], s[20:21]
	v_pk_mul_f32 v[124:125], v[44:45], v[36:37] op_sel:[0,0] op_sel_hi:[0,1]
	v_pk_fma_f32 v[144:145], v[144:145], v[22:23], v[146:147] op_sel:[1,1,0] op_sel_hi:[1,0,1] neg_lo:[1,0,0]
	v_pk_add_f32 v[146:147], v[108:109], v[118:119]
	v_pk_fma_f32 v[124:125], v[44:45], v[36:37], v[124:125] op_sel:[1,1,0] op_sel_hi:[1,0,1] neg_lo:[1,0,0]
	v_pk_mul_f32 v[44:45], v[134:135], v[22:23] op_sel:[0,0] op_sel_hi:[0,1]
	v_pk_add_f32 v[108:109], v[108:109], v[118:119] neg_lo:[0,1] neg_hi:[0,1]
	v_pk_add_f32 v[150:151], v[146:147], v[148:149]
	v_pk_fma_f32 v[126:127], v[134:135], v[22:23], v[44:45] op_sel:[1,1,0] op_sel_hi:[1,0,1] neg_lo:[1,0,0]
	v_pk_mul_f32 v[44:45], v[138:139], v[36:37] op_sel:[0,0] op_sel_hi:[0,1]
	v_pk_add_f32 v[110:111], v[110:111], v[132:133] neg_lo:[0,1] neg_hi:[0,1]
	v_pk_fma_f32 v[128:129], v[138:139], v[36:37], v[44:45] op_sel:[1,1,0] op_sel_hi:[1,0,1] neg_lo:[1,0,0]
	v_mov_b64_e32 v[44:45], s[8:9]
	v_pk_mul_f32 v[130:131], v[142:143], v[44:45] op_sel:[0,0] op_sel_hi:[0,1]
	v_pk_add_f32 v[134:135], v[150:151], v[114:115]
	v_pk_add_f32 v[138:139], v[120:121], v[116:117]
	v_pk_fma_f32 v[130:131], v[142:143], v[44:45], v[130:131] op_sel:[1,1,0] op_sel_hi:[1,0,1] neg_lo:[1,0,0]
	v_pk_add_f32 v[118:119], v[108:109], v[110:111] op_sel:[0,1] op_sel_hi:[1,0] neg_lo:[0,1] neg_hi:[0,1]
	v_pk_add_f32 v[142:143], v[134:135], v[138:139]
	v_pk_add_f32 v[134:135], v[134:135], v[138:139] neg_lo:[0,1] neg_hi:[0,1]
	v_pk_add_f32 v[138:139], v[146:147], v[148:149] neg_lo:[0,1] neg_hi:[0,1]
	v_pk_add_f32 v[108:109], v[108:109], v[110:111] op_sel:[0,1] op_sel_hi:[1,0]
	v_pk_add_f32 v[146:147], v[138:139], v[112:113] neg_lo:[0,1] neg_hi:[0,1]
	v_pk_add_f32 v[148:149], v[122:123], v[124:125] neg_lo:[0,1] neg_hi:[0,1]
	v_pk_add_f32 v[122:123], v[122:123], v[124:125]
	v_pk_add_f32 v[112:113], v[138:139], v[112:113]
	v_mov_b32_e32 v110, v118
	v_mov_b32_e32 v111, v109
	v_pk_add_f32 v[124:125], v[112:113], v[122:123]
	v_pk_add_f32 v[112:113], v[112:113], v[122:123] neg_lo:[0,1] neg_hi:[0,1]
	v_pk_add_f32 v[122:123], v[146:147], v[148:149] op_sel:[0,1] op_sel_hi:[1,0]
	v_pk_add_f32 v[138:139], v[146:147], v[148:149] op_sel:[0,1] op_sel_hi:[1,0] neg_lo:[0,1] neg_hi:[0,1]
	v_pk_add_f32 v[132:133], v[136:137], v[144:145] neg_lo:[0,1] neg_hi:[0,1]
	v_pk_add_f32 v[136:137], v[136:137], v[144:145]
	v_pk_add_f32 v[144:145], v[110:111], v[128:129] neg_lo:[0,1] neg_hi:[0,1]
	v_pk_add_f32 v[148:149], v[126:127], v[130:131] neg_lo:[0,1] neg_hi:[0,1]
	v_pk_add_f32 v[126:127], v[126:127], v[130:131]
	v_pk_add_f32 v[110:111], v[110:111], v[128:129]
	v_pk_add_f32 v[130:131], v[144:145], v[148:149] op_sel:[0,1] op_sel_hi:[1,0] neg_lo:[0,1] neg_hi:[0,1]
	v_pk_add_f32 v[128:129], v[110:111], v[126:127]
	v_pk_add_f32 v[110:111], v[110:111], v[126:127] neg_lo:[0,1] neg_hi:[0,1]
	v_pk_add_f32 v[126:127], v[144:145], v[148:149] op_sel:[0,1] op_sel_hi:[1,0]
	s_nop 1
	v_mov_b32_e32 v109, v119
	v_xor_b32_e32 v107, 0x80000000, v26
	v_pk_mul_f32 v[148:149], v[106:107], v[106:107] op_sel:[0,0] op_sel_hi:[0,1]
	v_pk_add_f32 v[114:115], v[150:151], v[114:115] neg_lo:[0,1] neg_hi:[0,1]
	v_pk_fma_f32 v[148:149], v[106:107], v[106:107], v[148:149] op_sel:[1,1,0] op_sel_hi:[1,0,1] neg_lo:[1,0,0]
	v_pk_add_f32 v[116:117], v[120:121], v[116:117] neg_lo:[0,1] neg_hi:[0,1]
	v_pk_mul_f32 v[152:153], v[148:149], v[148:149] op_sel:[0,0] op_sel_hi:[0,1]
	v_pk_add_f32 v[118:119], v[108:109], v[140:141] neg_lo:[0,1] neg_hi:[0,1]
	v_pk_fma_f32 v[152:153], v[148:149], v[148:149], v[152:153] op_sel:[1,1,0] op_sel_hi:[1,0,1] neg_lo:[1,0,0]
	v_pk_add_f32 v[108:109], v[108:109], v[140:141]
	v_pk_mul_f32 v[160:161], v[152:153], v[152:153] op_sel:[0,0] op_sel_hi:[0,1]
	v_pk_mul_f32 v[154:155], v[152:153], v[106:107] op_sel:[0,0] op_sel_hi:[0,1]
	v_pk_add_f32 v[120:121], v[114:115], v[116:117] op_sel:[0,1] op_sel_hi:[1,0]
	v_pk_fma_f32 v[160:161], v[152:153], v[152:153], v[160:161] op_sel:[1,1,0] op_sel_hi:[1,0,1] neg_lo:[1,0,0]
	v_pk_add_f32 v[114:115], v[114:115], v[116:117] op_sel:[0,1] op_sel_hi:[1,0] neg_lo:[0,1] neg_hi:[0,1]
	v_pk_mul_f32 v[162:163], v[160:161], v[106:107] op_sel:[0,0] op_sel_hi:[0,1]
	v_pk_add_f32 v[140:141], v[108:109], v[136:137]
	v_pk_add_f32 v[108:109], v[108:109], v[136:137] neg_lo:[0,1] neg_hi:[0,1]
	v_mov_b32_e32 v144, v130
	v_mov_b32_e32 v145, v127
	v_pk_mul_f32 v[150:151], v[148:149], v[106:107] op_sel:[0,0] op_sel_hi:[0,1]
	v_pk_fma_f32 v[154:155], v[152:153], v[106:107], v[154:155] op_sel:[1,1,0] op_sel_hi:[1,0,1] neg_lo:[1,0,0]
	v_pk_fma_f32 v[162:163], v[160:161], v[106:107], v[162:163] op_sel:[1,1,0] op_sel_hi:[1,0,1] neg_lo:[1,0,0]
	v_mov_b32_e32 v127, v131
	v_pk_mul_f32 v[164:165], v[154:155], v[154:155] op_sel:[0,0] op_sel_hi:[0,1]
	v_pk_mul_f32 v[130:131], v[108:109], v[162:163] op_sel:[0,0] op_sel_hi:[0,1]
	v_mov_b32_e32 v116, v114
	v_mov_b32_e32 v117, v121
	v_pk_fma_f32 v[150:151], v[148:149], v[106:107], v[150:151] op_sel:[1,1,0] op_sel_hi:[1,0,1] neg_lo:[1,0,0]
	v_pk_fma_f32 v[164:165], v[154:155], v[154:155], v[164:165] op_sel:[1,1,0] op_sel_hi:[1,0,1] neg_lo:[1,0,0]
	v_mov_b32_e32 v121, v115
	v_pk_mul_f32 v[156:157], v[150:151], v[150:151] op_sel:[0,0] op_sel_hi:[0,1]
	v_pk_mul_f32 v[166:167], v[160:161], v[150:151] op_sel:[0,0] op_sel_hi:[0,1]
	v_pk_mul_f32 v[114:115], v[120:121], v[152:153] op_sel:[0,0] op_sel_hi:[0,1]
	v_pk_fma_f32 v[108:109], v[108:109], v[162:163], v[130:131] op_sel:[1,1,0] op_sel_hi:[1,0,1] neg_lo:[1,0,0]
	v_pk_mul_f32 v[130:131], v[112:113], v[164:165] op_sel:[0,0] op_sel_hi:[0,1]
	v_mov_b32_e32 v147, v123
	v_pk_fma_f32 v[156:157], v[150:151], v[150:151], v[156:157] op_sel:[1,1,0] op_sel_hi:[1,0,1] neg_lo:[1,0,0]
	v_pk_mul_f32 v[158:159], v[152:153], v[150:151] op_sel:[0,0] op_sel_hi:[0,1]
	v_pk_fma_f32 v[166:167], v[160:161], v[150:151], v[166:167] op_sel:[1,1,0] op_sel_hi:[1,0,1] neg_lo:[1,0,0]
	v_pk_fma_f32 v[114:115], v[120:121], v[152:153], v[114:115] op_sel:[1,1,0] op_sel_hi:[1,0,1] neg_lo:[1,0,0]
	v_mov_b32_e32 v123, v139
	v_pk_mul_f32 v[168:169], v[156:157], v[156:157] op_sel:[0,0] op_sel_hi:[0,1]
	v_pk_mul_f32 v[120:121], v[122:123], v[156:157] op_sel:[0,0] op_sel_hi:[0,1]
	v_pk_fma_f32 v[112:113], v[112:113], v[164:165], v[130:131] op_sel:[1,1,0] op_sel_hi:[1,0,1] neg_lo:[1,0,0]
	v_pk_mul_f32 v[130:131], v[110:111], v[166:167] op_sel:[0,0] op_sel_hi:[0,1]
	v_pk_add_f32 v[136:137], v[118:119], v[132:133] op_sel:[0,1] op_sel_hi:[1,0]
	v_pk_add_f32 v[118:119], v[118:119], v[132:133] op_sel:[0,1] op_sel_hi:[1,0] neg_lo:[0,1] neg_hi:[0,1]
	v_pk_fma_f32 v[158:159], v[152:153], v[150:151], v[158:159] op_sel:[1,1,0] op_sel_hi:[1,0,1] neg_lo:[1,0,0]
	v_pk_fma_f32 v[168:169], v[156:157], v[156:157], v[168:169] op_sel:[1,1,0] op_sel_hi:[1,0,1] neg_lo:[1,0,0]
	v_pk_mul_f32 v[170:171], v[160:161], v[154:155] op_sel:[0,0] op_sel_hi:[0,1]
	v_pk_fma_f32 v[120:121], v[122:123], v[156:157], v[120:121] op_sel:[1,1,0] op_sel_hi:[1,0,1] neg_lo:[1,0,0]
	v_pk_fma_f32 v[110:111], v[110:111], v[166:167], v[130:131] op_sel:[1,1,0] op_sel_hi:[1,0,1] neg_lo:[1,0,0]
	s_nop 0
	v_mov_b32_e32 v132, v118
	v_pk_mul_f32 v[122:123], v[126:127], v[158:159] op_sel:[0,0] op_sel_hi:[0,1]
	v_pk_mul_f32 v[130:131], v[116:117], v[168:169] op_sel:[0,0] op_sel_hi:[0,1]
	v_mov_b32_e32 v133, v137
	v_pk_fma_f32 v[170:171], v[160:161], v[154:155], v[170:171] op_sel:[1,1,0] op_sel_hi:[1,0,1] neg_lo:[1,0,0]
	v_pk_mul_f32 v[172:173], v[158:159], v[158:159] op_sel:[0,0] op_sel_hi:[0,1]
	v_pk_mul_f32 v[174:175], v[160:161], v[158:159] op_sel:[0,0] op_sel_hi:[0,1]
	v_pk_fma_f32 v[122:123], v[126:127], v[158:159], v[122:123] op_sel:[1,1,0] op_sel_hi:[1,0,1] neg_lo:[1,0,0]
	v_pk_mul_f32 v[126:127], v[134:135], v[160:161] op_sel:[0,0] op_sel_hi:[0,1]
	v_pk_fma_f32 v[116:117], v[116:117], v[168:169], v[130:131] op_sel:[1,1,0] op_sel_hi:[1,0,1] neg_lo:[1,0,0]
	s_nop 0
	v_pk_mul_f32 v[130:131], v[132:133], v[170:171] op_sel:[0,0] op_sel_hi:[0,1]
	v_mov_b32_e32 v146, v138
	v_pk_fma_f32 v[172:173], v[158:159], v[158:159], v[172:173] op_sel:[1,1,0] op_sel_hi:[1,0,1] neg_lo:[1,0,0]
	v_pk_fma_f32 v[174:175], v[160:161], v[158:159], v[174:175] op_sel:[1,1,0] op_sel_hi:[1,0,1] neg_lo:[1,0,0]
	v_pk_mul_f32 v[176:177], v[140:141], v[106:107] op_sel:[0,0] op_sel_hi:[0,1]
	v_mov_b32_e32 v137, v119
	v_pk_fma_f32 v[106:107], v[140:141], v[106:107], v[176:177] op_sel:[1,1,0] op_sel_hi:[1,0,1] neg_lo:[1,0,0]
	v_pk_mul_f32 v[140:141], v[124:125], v[148:149] op_sel:[0,0] op_sel_hi:[0,1]
	v_pk_mul_f32 v[118:119], v[136:137], v[154:155] op_sel:[0,0] op_sel_hi:[0,1]
	v_pk_fma_f32 v[126:127], v[134:135], v[160:161], v[126:127] op_sel:[1,1,0] op_sel_hi:[1,0,1] neg_lo:[1,0,0]
	v_pk_fma_f32 v[130:131], v[132:133], v[170:171], v[130:131] op_sel:[1,1,0] op_sel_hi:[1,0,1] neg_lo:[1,0,0]
	v_pk_mul_f32 v[132:133], v[146:147], v[172:173] op_sel:[0,0] op_sel_hi:[0,1]
	v_pk_mul_f32 v[134:135], v[144:145], v[174:175] op_sel:[0,0] op_sel_hi:[0,1]
	s_nop 0
	v_pk_fma_f32 v[124:125], v[124:125], v[148:149], v[140:141] op_sel:[1,1,0] op_sel_hi:[1,0,1] neg_lo:[1,0,0]
	v_pk_mul_f32 v[140:141], v[128:129], v[150:151] op_sel:[0,0] op_sel_hi:[0,1]
	v_pk_fma_f32 v[118:119], v[136:137], v[154:155], v[118:119] op_sel:[1,1,0] op_sel_hi:[1,0,1] neg_lo:[1,0,0]
	s_movk_i32 s25, 0xfe00
	v_pk_fma_f32 v[128:129], v[128:129], v[150:151], v[140:141] op_sel:[1,1,0] op_sel_hi:[1,0,1] neg_lo:[1,0,0]
	v_pk_fma_f32 v[132:133], v[146:147], v[172:173], v[132:133] op_sel:[1,1,0] op_sel_hi:[1,0,1] neg_lo:[1,0,0]
	v_pk_fma_f32 v[134:135], v[144:145], v[174:175], v[134:135] op_sel:[1,1,0] op_sel_hi:[1,0,1] neg_lo:[1,0,0]
	ds_write_b64 v1, v[142:143]
	ds_write_b64 v1, v[106:107] offset:4352
	ds_write_b64 v1, v[124:125] offset:8704
	ds_write_b64 v1, v[128:129] offset:13056
	ds_write_b64 v1, v[114:115] offset:17408
	ds_write_b64 v1, v[118:119] offset:21760
	ds_write_b64 v1, v[120:121] offset:26112
	ds_write_b64 v1, v[122:123] offset:30464
	ds_write_b64 v1, v[126:127] offset:34816
	ds_write_b64 v1, v[108:109] offset:39168
	ds_write_b64 v1, v[112:113] offset:43520
	ds_write_b64 v1, v[110:111] offset:47872
	ds_write_b64 v1, v[116:117] offset:52224
	ds_write_b64 v1, v[130:131] offset:56576
	ds_write_b64 v1, v[132:133] offset:60928
	ds_write_b64 v1, v[134:135] offset:65280
	v_mov_b32_e32 v1, v0
	s_waitcnt lgkmcnt(0)
	s_barrier
	s_mov_b32 s12, 0x3f6c835e
	v_and_b32_e32 v26, 31, v1
	v_lshlrev_b32_e32 v1, 4, v1
	v_and_or_b32 v1, v1, s25, v26
	v_ashrrev_i32_e32 v28, 4, v1
	v_lshlrev_b32_e32 v28, 3, v28
	v_lshlrev_b32_e32 v1, 3, v1
	v_add3_u32 v1, 0, v28, v1
	ds_read2_b64 v[106:109], v1 offset1:34
	ds_read2_b64 v[110:113], v1 offset0:68 offset1:102
	ds_read2_b64 v[114:117], v1 offset0:136 offset1:170
	v_add_u32_e32 v28, 0x800, v1
	ds_read2_b64 v[118:121], v28 offset0:16 offset1:50
	ds_read2_b64 v[122:125], v28 offset0:152 offset1:186
	ds_read2_b64 v[126:129], v1 offset0:204 offset1:238
	ds_read2_b64 v[130:133], v28 offset0:84 offset1:118
	ds_read2_b64 v[134:137], v28 offset0:220 offset1:254
	s_waitcnt lgkmcnt(4)
	v_pk_add_f32 v[140:141], v[108:109], v[120:121] neg_lo:[0,1] neg_hi:[0,1]
	v_pk_add_f32 v[108:109], v[108:109], v[120:121]
	s_waitcnt lgkmcnt(3)
	v_pk_add_f32 v[142:143], v[116:117], v[124:125] neg_lo:[0,1] neg_hi:[0,1]
	v_pk_add_f32 v[116:117], v[116:117], v[124:125]
	v_pk_add_f32 v[144:145], v[140:141], v[142:143] op_sel:[0,1] op_sel_hi:[1,0]
	v_pk_add_f32 v[140:141], v[140:141], v[142:143] op_sel:[0,1] op_sel_hi:[1,0] neg_lo:[0,1] neg_hi:[0,1]
	v_mov_b32_e32 v142, v144
	v_mov_b32_e32 v143, v141
	v_mov_b32_e32 v141, v145
	s_waitcnt lgkmcnt(1)
	v_pk_add_f32 v[144:145], v[110:111], v[130:131] neg_lo:[0,1] neg_hi:[0,1]
	s_waitcnt lgkmcnt(0)
	v_pk_add_f32 v[146:147], v[126:127], v[134:135] neg_lo:[0,1] neg_hi:[0,1]
	v_pk_add_f32 v[150:151], v[128:129], v[136:137] neg_lo:[0,1] neg_hi:[0,1]
	v_pk_add_f32 v[148:149], v[144:145], v[146:147] op_sel:[0,1] op_sel_hi:[1,0]
	v_pk_add_f32 v[144:145], v[144:145], v[146:147] op_sel:[0,1] op_sel_hi:[1,0] neg_lo:[0,1] neg_hi:[0,1]
	v_mov_b32_e32 v146, v148
	v_mov_b32_e32 v147, v145
	v_mov_b32_e32 v145, v149
	v_pk_add_f32 v[148:149], v[112:113], v[132:133] neg_lo:[0,1] neg_hi:[0,1]
	v_pk_add_f32 v[120:121], v[108:109], v[116:117]
	v_pk_add_f32 v[152:153], v[148:149], v[150:151] op_sel:[0,1] op_sel_hi:[1,0]
	v_pk_add_f32 v[148:149], v[148:149], v[150:151] op_sel:[0,1] op_sel_hi:[1,0] neg_lo:[0,1] neg_hi:[0,1]
	v_pk_add_f32 v[108:109], v[108:109], v[116:117] neg_lo:[0,1] neg_hi:[0,1]
	v_pk_add_f32 v[110:111], v[110:111], v[130:131]
	v_pk_add_f32 v[116:117], v[126:127], v[134:135]
	v_mov_b32_e32 v150, v152
	v_mov_b32_e32 v151, v149
	v_mov_b32_e32 v149, v153
	v_pk_mul_f32 v[152:153], v[142:143], v[40:41] op_sel:[0,0] op_sel_hi:[0,1]
	v_pk_add_f32 v[124:125], v[110:111], v[116:117]
	v_pk_add_f32 v[110:111], v[110:111], v[116:117] neg_lo:[0,1] neg_hi:[0,1]
	v_pk_add_f32 v[112:113], v[112:113], v[132:133]
	v_pk_add_f32 v[116:117], v[128:129], v[136:137]
	v_pk_fma_f32 v[142:143], v[142:143], v[40:41], v[152:153] op_sel:[1,1,0] op_sel_hi:[1,0,1] neg_lo:[1,0,0]
	v_pk_mul_f32 v[152:153], v[146:147], v[24:25] op_sel:[0,0] op_sel_hi:[0,1]
	v_pk_add_f32 v[154:155], v[114:115], v[122:123]
	v_pk_add_f32 v[126:127], v[112:113], v[116:117]
	v_pk_add_f32 v[112:113], v[112:113], v[116:117] neg_lo:[0,1] neg_hi:[0,1]
	v_pk_mul_f32 v[116:117], v[108:109], v[24:25] op_sel:[0,0] op_sel_hi:[0,1]
	v_pk_fma_f32 v[146:147], v[146:147], v[24:25], v[152:153] op_sel:[1,1,0] op_sel_hi:[1,0,1] neg_lo:[1,0,0]
	v_pk_mul_f32 v[152:153], v[150:151], v[22:23] op_sel:[0,0] op_sel_hi:[0,1]
	v_pk_add_f32 v[114:115], v[114:115], v[122:123] neg_lo:[0,1] neg_hi:[0,1]
	v_pk_fma_f32 v[108:109], v[108:109], v[24:25], v[116:117] op_sel:[1,1,0] op_sel_hi:[1,0,1] neg_lo:[1,0,0]
	v_pk_mul_f32 v[116:117], v[110:111], v[42:43] op_sel:[0,0] op_sel_hi:[0,1]
	v_pk_fma_f32 v[150:151], v[150:151], v[22:23], v[152:153] op_sel:[1,1,0] op_sel_hi:[1,0,1] neg_lo:[1,0,0]
	v_pk_add_f32 v[152:153], v[106:107], v[118:119]
	v_pk_fma_f32 v[110:111], v[110:111], v[42:43], v[116:117] op_sel:[1,1,0] op_sel_hi:[1,0,1] neg_lo:[1,0,0]
	v_pk_mul_f32 v[116:117], v[112:113], v[36:37] op_sel:[0,0] op_sel_hi:[0,1]
	v_pk_add_f32 v[106:107], v[106:107], v[118:119] neg_lo:[0,1] neg_hi:[0,1]
	v_cvt_f32_ubyte0_e32 v26, v26
	v_pk_fma_f32 v[112:113], v[112:113], v[36:37], v[116:117] op_sel:[1,1,0] op_sel_hi:[1,0,1] neg_lo:[1,0,0]
	v_pk_mul_f32 v[116:117], v[140:141], v[22:23] op_sel:[0,0] op_sel_hi:[0,1]
	v_pk_add_f32 v[118:119], v[106:107], v[114:115] op_sel:[0,1] op_sel_hi:[1,0] neg_lo:[0,1] neg_hi:[0,1]
	v_pk_add_f32 v[106:107], v[106:107], v[114:115] op_sel:[0,1] op_sel_hi:[1,0]
	v_mul_f32_e32 v26, 0x3b000000, v26
	v_pk_fma_f32 v[116:117], v[140:141], v[22:23], v[116:117] op_sel:[1,1,0] op_sel_hi:[1,0,1] neg_lo:[1,0,0]
	v_pk_mul_f32 v[128:129], v[144:145], v[36:37] op_sel:[0,0] op_sel_hi:[0,1]
	v_pk_mul_f32 v[130:131], v[148:149], v[44:45] op_sel:[0,0] op_sel_hi:[0,1]
	v_mov_b32_e32 v114, v118
	v_mov_b32_e32 v115, v107
	v_mov_b32_e32 v107, v119
	v_cos_f32_e32 v138, v26
	v_sin_f32_e32 v26, v26
	v_pk_add_f32 v[156:157], v[152:153], v[154:155]
	v_pk_fma_f32 v[128:129], v[144:145], v[36:37], v[128:129] op_sel:[1,1,0] op_sel_hi:[1,0,1] neg_lo:[1,0,0]
	v_pk_fma_f32 v[130:131], v[148:149], v[44:45], v[130:131] op_sel:[1,1,0] op_sel_hi:[1,0,1] neg_lo:[1,0,0]
	v_pk_add_f32 v[118:119], v[106:107], v[146:147] neg_lo:[0,1] neg_hi:[0,1]
	v_pk_add_f32 v[106:107], v[106:107], v[146:147]
	v_pk_add_f32 v[146:147], v[114:115], v[128:129] neg_lo:[0,1] neg_hi:[0,1]
	v_pk_add_f32 v[148:149], v[116:117], v[130:131] neg_lo:[0,1] neg_hi:[0,1]
	v_pk_add_f32 v[116:117], v[116:117], v[130:131]
	v_pk_add_f32 v[114:115], v[114:115], v[128:129]
	v_pk_add_f32 v[132:133], v[156:157], v[124:125]
	v_pk_add_f32 v[134:135], v[120:121], v[126:127]
	v_pk_add_f32 v[128:129], v[114:115], v[116:117]
	v_pk_add_f32 v[114:115], v[114:115], v[116:117] neg_lo:[0,1] neg_hi:[0,1]
	v_pk_add_f32 v[116:117], v[146:147], v[148:149] op_sel:[0,1] op_sel_hi:[1,0]
	v_pk_add_f32 v[130:131], v[146:147], v[148:149] op_sel:[0,1] op_sel_hi:[1,0] neg_lo:[0,1] neg_hi:[0,1]
	s_nop 1
	v_pk_add_f32 v[136:137], v[132:133], v[134:135]
	v_xor_b32_e32 v139, 0x80000000, v26
	v_pk_mul_f32 v[148:149], v[138:139], v[138:139] op_sel:[0,0] op_sel_hi:[0,1]
	v_pk_add_f32 v[132:133], v[132:133], v[134:135] neg_lo:[0,1] neg_hi:[0,1]
	v_pk_add_f32 v[134:135], v[152:153], v[154:155] neg_lo:[0,1] neg_hi:[0,1]
	v_pk_fma_f32 v[148:149], v[138:139], v[138:139], v[148:149] op_sel:[1,1,0] op_sel_hi:[1,0,1] neg_lo:[1,0,0]
	v_pk_add_f32 v[124:125], v[156:157], v[124:125] neg_lo:[0,1] neg_hi:[0,1]
	v_pk_mul_f32 v[152:153], v[148:149], v[148:149] op_sel:[0,0] op_sel_hi:[0,1]
	v_pk_add_f32 v[120:121], v[120:121], v[126:127] neg_lo:[0,1] neg_hi:[0,1]
	v_pk_fma_f32 v[152:153], v[148:149], v[148:149], v[152:153] op_sel:[1,1,0] op_sel_hi:[1,0,1] neg_lo:[1,0,0]
	v_pk_add_f32 v[140:141], v[134:135], v[110:111] neg_lo:[0,1] neg_hi:[0,1]
	v_pk_mul_f32 v[160:161], v[152:153], v[152:153] op_sel:[0,0] op_sel_hi:[0,1]
	v_pk_add_f32 v[144:145], v[108:109], v[112:113] neg_lo:[0,1] neg_hi:[0,1]
	v_pk_add_f32 v[108:109], v[108:109], v[112:113]
	v_pk_add_f32 v[110:111], v[134:135], v[110:111]
	v_pk_add_f32 v[122:123], v[142:143], v[150:151] neg_lo:[0,1] neg_hi:[0,1]
	v_pk_add_f32 v[142:143], v[142:143], v[150:151]
	v_pk_mul_f32 v[154:155], v[152:153], v[138:139] op_sel:[0,0] op_sel_hi:[0,1]
	v_pk_fma_f32 v[160:161], v[152:153], v[152:153], v[160:161] op_sel:[1,1,0] op_sel_hi:[1,0,1] neg_lo:[1,0,0]
	v_pk_add_f32 v[126:127], v[124:125], v[120:121] op_sel:[0,1] op_sel_hi:[1,0]
	v_pk_mul_f32 v[162:163], v[160:161], v[138:139] op_sel:[0,0] op_sel_hi:[0,1]
	v_pk_add_f32 v[120:121], v[124:125], v[120:121] op_sel:[0,1] op_sel_hi:[1,0] neg_lo:[0,1] neg_hi:[0,1]
	v_pk_add_f32 v[112:113], v[110:111], v[108:109]
	v_pk_add_f32 v[108:109], v[110:111], v[108:109] neg_lo:[0,1] neg_hi:[0,1]
	v_pk_add_f32 v[110:111], v[140:141], v[144:145] op_sel:[0,1] op_sel_hi:[1,0]
	v_pk_add_f32 v[134:135], v[140:141], v[144:145] op_sel:[0,1] op_sel_hi:[1,0] neg_lo:[0,1] neg_hi:[0,1]
	v_pk_add_f32 v[144:145], v[106:107], v[142:143]
	v_pk_add_f32 v[106:107], v[106:107], v[142:143] neg_lo:[0,1] neg_hi:[0,1]
	v_mov_b32_e32 v146, v130
	v_mov_b32_e32 v147, v117
	v_pk_mul_f32 v[150:151], v[148:149], v[138:139] op_sel:[0,0] op_sel_hi:[0,1]
	v_pk_fma_f32 v[154:155], v[152:153], v[138:139], v[154:155] op_sel:[1,1,0] op_sel_hi:[1,0,1] neg_lo:[1,0,0]
	v_pk_fma_f32 v[162:163], v[160:161], v[138:139], v[162:163] op_sel:[1,1,0] op_sel_hi:[1,0,1] neg_lo:[1,0,0]
	v_mov_b32_e32 v117, v131
	v_pk_mul_f32 v[164:165], v[154:155], v[154:155] op_sel:[0,0] op_sel_hi:[0,1]
	v_pk_mul_f32 v[130:131], v[106:107], v[162:163] op_sel:[0,0] op_sel_hi:[0,1]
	v_mov_b32_e32 v124, v120
	v_mov_b32_e32 v125, v127
	v_pk_fma_f32 v[150:151], v[148:149], v[138:139], v[150:151] op_sel:[1,1,0] op_sel_hi:[1,0,1] neg_lo:[1,0,0]
	v_pk_fma_f32 v[164:165], v[154:155], v[154:155], v[164:165] op_sel:[1,1,0] op_sel_hi:[1,0,1] neg_lo:[1,0,0]
	v_mov_b32_e32 v127, v121
	v_pk_mul_f32 v[156:157], v[150:151], v[150:151] op_sel:[0,0] op_sel_hi:[0,1]
	v_pk_mul_f32 v[166:167], v[160:161], v[150:151] op_sel:[0,0] op_sel_hi:[0,1]
	v_pk_mul_f32 v[120:121], v[126:127], v[152:153] op_sel:[0,0] op_sel_hi:[0,1]
	v_pk_fma_f32 v[106:107], v[106:107], v[162:163], v[130:131] op_sel:[1,1,0] op_sel_hi:[1,0,1] neg_lo:[1,0,0]
	v_pk_mul_f32 v[130:131], v[108:109], v[164:165] op_sel:[0,0] op_sel_hi:[0,1]
	v_mov_b32_e32 v141, v111
	v_pk_fma_f32 v[156:157], v[150:151], v[150:151], v[156:157] op_sel:[1,1,0] op_sel_hi:[1,0,1] neg_lo:[1,0,0]
	v_pk_mul_f32 v[158:159], v[152:153], v[150:151] op_sel:[0,0] op_sel_hi:[0,1]
	v_pk_fma_f32 v[166:167], v[160:161], v[150:151], v[166:167] op_sel:[1,1,0] op_sel_hi:[1,0,1] neg_lo:[1,0,0]
	v_pk_fma_f32 v[120:121], v[126:127], v[152:153], v[120:121] op_sel:[1,1,0] op_sel_hi:[1,0,1] neg_lo:[1,0,0]
	v_mov_b32_e32 v111, v135
	v_pk_mul_f32 v[168:169], v[156:157], v[156:157] op_sel:[0,0] op_sel_hi:[0,1]
	v_pk_mul_f32 v[126:127], v[110:111], v[156:157] op_sel:[0,0] op_sel_hi:[0,1]
	v_pk_fma_f32 v[108:109], v[108:109], v[164:165], v[130:131] op_sel:[1,1,0] op_sel_hi:[1,0,1] neg_lo:[1,0,0]
	v_pk_mul_f32 v[130:131], v[114:115], v[166:167] op_sel:[0,0] op_sel_hi:[0,1]
	v_pk_add_f32 v[142:143], v[118:119], v[122:123] op_sel:[0,1] op_sel_hi:[1,0]
	v_pk_add_f32 v[118:119], v[118:119], v[122:123] op_sel:[0,1] op_sel_hi:[1,0] neg_lo:[0,1] neg_hi:[0,1]
	v_pk_fma_f32 v[158:159], v[152:153], v[150:151], v[158:159] op_sel:[1,1,0] op_sel_hi:[1,0,1] neg_lo:[1,0,0]
	v_pk_fma_f32 v[168:169], v[156:157], v[156:157], v[168:169] op_sel:[1,1,0] op_sel_hi:[1,0,1] neg_lo:[1,0,0]
	v_pk_mul_f32 v[170:171], v[160:161], v[154:155] op_sel:[0,0] op_sel_hi:[0,1]
	v_pk_fma_f32 v[110:111], v[110:111], v[156:157], v[126:127] op_sel:[1,1,0] op_sel_hi:[1,0,1] neg_lo:[1,0,0]
	v_pk_fma_f32 v[114:115], v[114:115], v[166:167], v[130:131] op_sel:[1,1,0] op_sel_hi:[1,0,1] neg_lo:[1,0,0]
	s_nop 0
	v_mov_b32_e32 v122, v118
	v_pk_mul_f32 v[126:127], v[116:117], v[158:159] op_sel:[0,0] op_sel_hi:[0,1]
	v_pk_mul_f32 v[130:131], v[124:125], v[168:169] op_sel:[0,0] op_sel_hi:[0,1]
	v_mov_b32_e32 v123, v143
	v_pk_fma_f32 v[170:171], v[160:161], v[154:155], v[170:171] op_sel:[1,1,0] op_sel_hi:[1,0,1] neg_lo:[1,0,0]
	v_pk_mul_f32 v[172:173], v[158:159], v[158:159] op_sel:[0,0] op_sel_hi:[0,1]
	v_pk_mul_f32 v[174:175], v[160:161], v[158:159] op_sel:[0,0] op_sel_hi:[0,1]
	v_pk_fma_f32 v[116:117], v[116:117], v[158:159], v[126:127] op_sel:[1,1,0] op_sel_hi:[1,0,1] neg_lo:[1,0,0]
	v_pk_mul_f32 v[126:127], v[132:133], v[160:161] op_sel:[0,0] op_sel_hi:[0,1]
	v_pk_fma_f32 v[124:125], v[124:125], v[168:169], v[130:131] op_sel:[1,1,0] op_sel_hi:[1,0,1] neg_lo:[1,0,0]
	s_nop 0
	v_pk_mul_f32 v[130:131], v[122:123], v[170:171] op_sel:[0,0] op_sel_hi:[0,1]
	v_mov_b32_e32 v140, v134
	v_pk_fma_f32 v[172:173], v[158:159], v[158:159], v[172:173] op_sel:[1,1,0] op_sel_hi:[1,0,1] neg_lo:[1,0,0]
	v_pk_fma_f32 v[174:175], v[160:161], v[158:159], v[174:175] op_sel:[1,1,0] op_sel_hi:[1,0,1] neg_lo:[1,0,0]
	v_pk_mul_f32 v[176:177], v[144:145], v[138:139] op_sel:[0,0] op_sel_hi:[0,1]
	v_mov_b32_e32 v143, v119
	v_pk_fma_f32 v[138:139], v[144:145], v[138:139], v[176:177] op_sel:[1,1,0] op_sel_hi:[1,0,1] neg_lo:[1,0,0]
	v_pk_mul_f32 v[144:145], v[112:113], v[148:149] op_sel:[0,0] op_sel_hi:[0,1]
	v_pk_mul_f32 v[118:119], v[142:143], v[154:155] op_sel:[0,0] op_sel_hi:[0,1]
	v_pk_fma_f32 v[126:127], v[132:133], v[160:161], v[126:127] op_sel:[1,1,0] op_sel_hi:[1,0,1] neg_lo:[1,0,0]
	v_pk_fma_f32 v[122:123], v[122:123], v[170:171], v[130:131] op_sel:[1,1,0] op_sel_hi:[1,0,1] neg_lo:[1,0,0]
	v_pk_mul_f32 v[130:131], v[140:141], v[172:173] op_sel:[0,0] op_sel_hi:[0,1]
	v_pk_mul_f32 v[132:133], v[146:147], v[174:175] op_sel:[0,0] op_sel_hi:[0,1]
	s_nop 0
	v_pk_fma_f32 v[112:113], v[112:113], v[148:149], v[144:145] op_sel:[1,1,0] op_sel_hi:[1,0,1] neg_lo:[1,0,0]
	v_pk_mul_f32 v[144:145], v[128:129], v[150:151] op_sel:[0,0] op_sel_hi:[0,1]
	v_pk_fma_f32 v[118:119], v[142:143], v[154:155], v[118:119] op_sel:[1,1,0] op_sel_hi:[1,0,1] neg_lo:[1,0,0]
	s_mov_b32 s13, 0x3ec3ef15
	v_pk_fma_f32 v[128:129], v[128:129], v[150:151], v[144:145] op_sel:[1,1,0] op_sel_hi:[1,0,1] neg_lo:[1,0,0]
	v_pk_fma_f32 v[130:131], v[140:141], v[172:173], v[130:131] op_sel:[1,1,0] op_sel_hi:[1,0,1] neg_lo:[1,0,0]
	v_pk_fma_f32 v[132:133], v[146:147], v[174:175], v[132:133] op_sel:[1,1,0] op_sel_hi:[1,0,1] neg_lo:[1,0,0]
	ds_write2_b64 v1, v[136:137], v[138:139] offset1:34
	ds_write2_b64 v1, v[112:113], v[128:129] offset0:68 offset1:102
	ds_write2_b64 v1, v[120:121], v[118:119] offset0:136 offset1:170
	ds_write2_b64 v1, v[110:111], v[116:117] offset0:204 offset1:238
	ds_write2_b64 v28, v[126:127], v[106:107] offset0:16 offset1:50
	ds_write2_b64 v28, v[108:109], v[114:115] offset0:84 offset1:118
	ds_write2_b64 v28, v[124:125], v[122:123] offset0:152 offset1:186
	ds_write2_b64 v28, v[130:131], v[132:133] offset0:220 offset1:254
	v_mov_b32_e32 v1, v0
	s_waitcnt lgkmcnt(0)
	s_barrier
	v_readlane_b32 s10, v255, 27
	v_and_b32_e32 v26, 1, v1
	v_lshlrev_b32_e32 v1, 4, v1
	v_and_b32_e32 v1, 0xffffffe0, v1
	v_ashrrev_i32_e32 v28, 1, v1
	v_add_u32_e32 v28, 0, v28
	v_lshlrev_b32_e32 v1, 3, v1
	v_lshlrev_b32_e32 v30, 3, v26
	v_add3_u32 v1, v28, v1, v30
	ds_read2_b64 v[106:109], v1 offset1:2
	ds_read2_b64 v[110:113], v1 offset0:4 offset1:6
	ds_read2_b64 v[114:117], v1 offset0:8 offset1:10
	ds_read2_b64 v[118:121], v1 offset0:17 offset1:19
	ds_read2_b64 v[122:125], v1 offset0:25 offset1:27
	ds_read2_b64 v[126:129], v1 offset0:12 offset1:14
	ds_read2_b64 v[130:133], v1 offset0:21 offset1:23
	ds_read2_b64 v[134:137], v1 offset0:29 offset1:31
	s_waitcnt lgkmcnt(4)
	v_pk_add_f32 v[140:141], v[108:109], v[120:121] neg_lo:[0,1] neg_hi:[0,1]
	s_waitcnt lgkmcnt(3)
	v_pk_add_f32 v[142:143], v[116:117], v[124:125] neg_lo:[0,1] neg_hi:[0,1]
	v_pk_add_f32 v[108:109], v[108:109], v[120:121]
	v_pk_add_f32 v[144:145], v[140:141], v[142:143] op_sel:[0,1] op_sel_hi:[1,0]
	v_pk_add_f32 v[140:141], v[140:141], v[142:143] op_sel:[0,1] op_sel_hi:[1,0] neg_lo:[0,1] neg_hi:[0,1]
	v_mov_b32_e32 v142, v144
	v_mov_b32_e32 v143, v141
	v_mov_b32_e32 v141, v145
	s_waitcnt lgkmcnt(1)
	v_pk_add_f32 v[144:145], v[110:111], v[130:131] neg_lo:[0,1] neg_hi:[0,1]
	s_waitcnt lgkmcnt(0)
	v_pk_add_f32 v[146:147], v[126:127], v[134:135] neg_lo:[0,1] neg_hi:[0,1]
	v_pk_add_f32 v[150:151], v[128:129], v[136:137] neg_lo:[0,1] neg_hi:[0,1]
	v_pk_add_f32 v[148:149], v[144:145], v[146:147] op_sel:[0,1] op_sel_hi:[1,0]
	v_pk_add_f32 v[144:145], v[144:145], v[146:147] op_sel:[0,1] op_sel_hi:[1,0] neg_lo:[0,1] neg_hi:[0,1]
	v_mov_b32_e32 v146, v148
	v_mov_b32_e32 v147, v145
	v_mov_b32_e32 v145, v149
	v_pk_add_f32 v[148:149], v[112:113], v[132:133] neg_lo:[0,1] neg_hi:[0,1]
	v_pk_add_f32 v[116:117], v[116:117], v[124:125]
	v_pk_add_f32 v[152:153], v[148:149], v[150:151] op_sel:[0,1] op_sel_hi:[1,0]
	v_pk_add_f32 v[148:149], v[148:149], v[150:151] op_sel:[0,1] op_sel_hi:[1,0] neg_lo:[0,1] neg_hi:[0,1]
	v_pk_add_f32 v[120:121], v[108:109], v[116:117]
	v_pk_add_f32 v[108:109], v[108:109], v[116:117] neg_lo:[0,1] neg_hi:[0,1]
	v_pk_add_f32 v[110:111], v[110:111], v[130:131]
	v_pk_add_f32 v[116:117], v[126:127], v[134:135]
	v_mov_b32_e32 v150, v152
	v_mov_b32_e32 v151, v149
	v_mov_b32_e32 v149, v153
	v_pk_mul_f32 v[152:153], v[142:143], v[40:41] op_sel:[0,0] op_sel_hi:[0,1]
	v_pk_add_f32 v[124:125], v[110:111], v[116:117]
	v_pk_add_f32 v[110:111], v[110:111], v[116:117] neg_lo:[0,1] neg_hi:[0,1]
	v_pk_add_f32 v[112:113], v[112:113], v[132:133]
	v_pk_add_f32 v[116:117], v[128:129], v[136:137]
	v_pk_fma_f32 v[142:143], v[142:143], v[40:41], v[152:153] op_sel:[1,1,0] op_sel_hi:[1,0,1] neg_lo:[1,0,0]
	v_pk_mul_f32 v[152:153], v[146:147], v[24:25] op_sel:[0,0] op_sel_hi:[0,1]
	v_pk_add_f32 v[154:155], v[114:115], v[122:123]
	v_pk_add_f32 v[126:127], v[112:113], v[116:117]
	v_pk_add_f32 v[112:113], v[112:113], v[116:117] neg_lo:[0,1] neg_hi:[0,1]
	v_pk_mul_f32 v[116:117], v[108:109], v[24:25] op_sel:[0,0] op_sel_hi:[0,1]
	v_pk_fma_f32 v[146:147], v[146:147], v[24:25], v[152:153] op_sel:[1,1,0] op_sel_hi:[1,0,1] neg_lo:[1,0,0]
	v_pk_mul_f32 v[152:153], v[150:151], v[22:23] op_sel:[0,0] op_sel_hi:[0,1]
	v_pk_add_f32 v[114:115], v[114:115], v[122:123] neg_lo:[0,1] neg_hi:[0,1]
	v_pk_fma_f32 v[108:109], v[108:109], v[24:25], v[116:117] op_sel:[1,1,0] op_sel_hi:[1,0,1] neg_lo:[1,0,0]
	v_pk_mul_f32 v[116:117], v[110:111], v[42:43] op_sel:[0,0] op_sel_hi:[0,1]
	v_pk_fma_f32 v[150:151], v[150:151], v[22:23], v[152:153] op_sel:[1,1,0] op_sel_hi:[1,0,1] neg_lo:[1,0,0]
	v_pk_add_f32 v[152:153], v[106:107], v[118:119]
	v_pk_fma_f32 v[110:111], v[110:111], v[42:43], v[116:117] op_sel:[1,1,0] op_sel_hi:[1,0,1] neg_lo:[1,0,0]
	v_pk_mul_f32 v[116:117], v[112:113], v[36:37] op_sel:[0,0] op_sel_hi:[0,1]
	v_pk_add_f32 v[106:107], v[106:107], v[118:119] neg_lo:[0,1] neg_hi:[0,1]
	v_cvt_f32_ubyte0_e32 v26, v26
	v_pk_fma_f32 v[112:113], v[112:113], v[36:37], v[116:117] op_sel:[1,1,0] op_sel_hi:[1,0,1] neg_lo:[1,0,0]
	v_pk_mul_f32 v[116:117], v[140:141], v[22:23] op_sel:[0,0] op_sel_hi:[0,1]
	v_pk_add_f32 v[118:119], v[106:107], v[114:115] op_sel:[0,1] op_sel_hi:[1,0] neg_lo:[0,1] neg_hi:[0,1]
	v_pk_add_f32 v[106:107], v[106:107], v[114:115] op_sel:[0,1] op_sel_hi:[1,0]
	v_mul_f32_e32 v26, 0x3d000000, v26
	v_pk_fma_f32 v[116:117], v[140:141], v[22:23], v[116:117] op_sel:[1,1,0] op_sel_hi:[1,0,1] neg_lo:[1,0,0]
	v_pk_mul_f32 v[128:129], v[144:145], v[36:37] op_sel:[0,0] op_sel_hi:[0,1]
	v_pk_mul_f32 v[130:131], v[148:149], v[44:45] op_sel:[0,0] op_sel_hi:[0,1]
	v_mov_b32_e32 v114, v118
	v_mov_b32_e32 v115, v107
	v_mov_b32_e32 v107, v119
	v_cos_f32_e32 v138, v26
	v_sin_f32_e32 v26, v26
	v_pk_add_f32 v[156:157], v[152:153], v[154:155]
	v_pk_fma_f32 v[128:129], v[144:145], v[36:37], v[128:129] op_sel:[1,1,0] op_sel_hi:[1,0,1] neg_lo:[1,0,0]
	v_pk_fma_f32 v[130:131], v[148:149], v[44:45], v[130:131] op_sel:[1,1,0] op_sel_hi:[1,0,1] neg_lo:[1,0,0]
	v_pk_add_f32 v[118:119], v[106:107], v[146:147] neg_lo:[0,1] neg_hi:[0,1]
	v_pk_add_f32 v[106:107], v[106:107], v[146:147]
	v_pk_add_f32 v[146:147], v[114:115], v[128:129] neg_lo:[0,1] neg_hi:[0,1]
	v_pk_add_f32 v[148:149], v[116:117], v[130:131] neg_lo:[0,1] neg_hi:[0,1]
	v_pk_add_f32 v[116:117], v[116:117], v[130:131]
	v_pk_add_f32 v[114:115], v[114:115], v[128:129]
	v_pk_add_f32 v[132:133], v[156:157], v[124:125]
	v_pk_add_f32 v[134:135], v[120:121], v[126:127]
	v_pk_add_f32 v[128:129], v[114:115], v[116:117]
	v_pk_add_f32 v[114:115], v[114:115], v[116:117] neg_lo:[0,1] neg_hi:[0,1]
	v_pk_add_f32 v[116:117], v[146:147], v[148:149] op_sel:[0,1] op_sel_hi:[1,0]
	v_pk_add_f32 v[130:131], v[146:147], v[148:149] op_sel:[0,1] op_sel_hi:[1,0] neg_lo:[0,1] neg_hi:[0,1]
	s_nop 1
	v_pk_add_f32 v[136:137], v[132:133], v[134:135]
	v_xor_b32_e32 v139, 0x80000000, v26
	v_pk_mul_f32 v[148:149], v[138:139], v[138:139] op_sel:[0,0] op_sel_hi:[0,1]
	v_pk_add_f32 v[132:133], v[132:133], v[134:135] neg_lo:[0,1] neg_hi:[0,1]
	v_pk_add_f32 v[134:135], v[152:153], v[154:155] neg_lo:[0,1] neg_hi:[0,1]
	v_pk_fma_f32 v[148:149], v[138:139], v[138:139], v[148:149] op_sel:[1,1,0] op_sel_hi:[1,0,1] neg_lo:[1,0,0]
	v_pk_add_f32 v[124:125], v[156:157], v[124:125] neg_lo:[0,1] neg_hi:[0,1]
	v_pk_mul_f32 v[152:153], v[148:149], v[148:149] op_sel:[0,0] op_sel_hi:[0,1]
	v_pk_add_f32 v[120:121], v[120:121], v[126:127] neg_lo:[0,1] neg_hi:[0,1]
	v_pk_fma_f32 v[152:153], v[148:149], v[148:149], v[152:153] op_sel:[1,1,0] op_sel_hi:[1,0,1] neg_lo:[1,0,0]
	v_pk_add_f32 v[140:141], v[134:135], v[110:111] neg_lo:[0,1] neg_hi:[0,1]
	v_pk_mul_f32 v[160:161], v[152:153], v[152:153] op_sel:[0,0] op_sel_hi:[0,1]
	v_pk_add_f32 v[144:145], v[108:109], v[112:113] neg_lo:[0,1] neg_hi:[0,1]
	v_pk_add_f32 v[108:109], v[108:109], v[112:113]
	v_pk_add_f32 v[110:111], v[134:135], v[110:111]
	v_pk_add_f32 v[122:123], v[142:143], v[150:151] neg_lo:[0,1] neg_hi:[0,1]
	v_pk_add_f32 v[142:143], v[142:143], v[150:151]
	v_pk_mul_f32 v[154:155], v[152:153], v[138:139] op_sel:[0,0] op_sel_hi:[0,1]
	v_pk_fma_f32 v[160:161], v[152:153], v[152:153], v[160:161] op_sel:[1,1,0] op_sel_hi:[1,0,1] neg_lo:[1,0,0]
	v_pk_add_f32 v[126:127], v[124:125], v[120:121] op_sel:[0,1] op_sel_hi:[1,0]
	v_pk_mul_f32 v[162:163], v[160:161], v[138:139] op_sel:[0,0] op_sel_hi:[0,1]
	v_pk_add_f32 v[120:121], v[124:125], v[120:121] op_sel:[0,1] op_sel_hi:[1,0] neg_lo:[0,1] neg_hi:[0,1]
	v_pk_add_f32 v[112:113], v[110:111], v[108:109]
	v_pk_add_f32 v[108:109], v[110:111], v[108:109] neg_lo:[0,1] neg_hi:[0,1]
	v_pk_add_f32 v[110:111], v[140:141], v[144:145] op_sel:[0,1] op_sel_hi:[1,0]
	v_pk_add_f32 v[134:135], v[140:141], v[144:145] op_sel:[0,1] op_sel_hi:[1,0] neg_lo:[0,1] neg_hi:[0,1]
	v_pk_add_f32 v[144:145], v[106:107], v[142:143]
	v_pk_add_f32 v[106:107], v[106:107], v[142:143] neg_lo:[0,1] neg_hi:[0,1]
	v_mov_b32_e32 v146, v130
	v_mov_b32_e32 v147, v117
	v_pk_mul_f32 v[150:151], v[148:149], v[138:139] op_sel:[0,0] op_sel_hi:[0,1]
	v_pk_fma_f32 v[154:155], v[152:153], v[138:139], v[154:155] op_sel:[1,1,0] op_sel_hi:[1,0,1] neg_lo:[1,0,0]
	v_pk_fma_f32 v[162:163], v[160:161], v[138:139], v[162:163] op_sel:[1,1,0] op_sel_hi:[1,0,1] neg_lo:[1,0,0]
	v_mov_b32_e32 v117, v131
	v_pk_mul_f32 v[164:165], v[154:155], v[154:155] op_sel:[0,0] op_sel_hi:[0,1]
	v_pk_mul_f32 v[130:131], v[106:107], v[162:163] op_sel:[0,0] op_sel_hi:[0,1]
	v_mov_b32_e32 v124, v120
	v_mov_b32_e32 v125, v127
	v_pk_fma_f32 v[150:151], v[148:149], v[138:139], v[150:151] op_sel:[1,1,0] op_sel_hi:[1,0,1] neg_lo:[1,0,0]
	v_pk_fma_f32 v[164:165], v[154:155], v[154:155], v[164:165] op_sel:[1,1,0] op_sel_hi:[1,0,1] neg_lo:[1,0,0]
	v_mov_b32_e32 v127, v121
	v_pk_mul_f32 v[156:157], v[150:151], v[150:151] op_sel:[0,0] op_sel_hi:[0,1]
	v_pk_mul_f32 v[166:167], v[160:161], v[150:151] op_sel:[0,0] op_sel_hi:[0,1]
	v_pk_mul_f32 v[120:121], v[126:127], v[152:153] op_sel:[0,0] op_sel_hi:[0,1]
	v_pk_fma_f32 v[106:107], v[106:107], v[162:163], v[130:131] op_sel:[1,1,0] op_sel_hi:[1,0,1] neg_lo:[1,0,0]
	v_pk_mul_f32 v[130:131], v[108:109], v[164:165] op_sel:[0,0] op_sel_hi:[0,1]
	v_mov_b32_e32 v141, v111
	v_pk_fma_f32 v[156:157], v[150:151], v[150:151], v[156:157] op_sel:[1,1,0] op_sel_hi:[1,0,1] neg_lo:[1,0,0]
	v_pk_mul_f32 v[158:159], v[152:153], v[150:151] op_sel:[0,0] op_sel_hi:[0,1]
	v_pk_fma_f32 v[166:167], v[160:161], v[150:151], v[166:167] op_sel:[1,1,0] op_sel_hi:[1,0,1] neg_lo:[1,0,0]
	v_pk_fma_f32 v[120:121], v[126:127], v[152:153], v[120:121] op_sel:[1,1,0] op_sel_hi:[1,0,1] neg_lo:[1,0,0]
	v_mov_b32_e32 v111, v135
	v_pk_mul_f32 v[168:169], v[156:157], v[156:157] op_sel:[0,0] op_sel_hi:[0,1]
	v_pk_mul_f32 v[126:127], v[110:111], v[156:157] op_sel:[0,0] op_sel_hi:[0,1]
	v_pk_fma_f32 v[108:109], v[108:109], v[164:165], v[130:131] op_sel:[1,1,0] op_sel_hi:[1,0,1] neg_lo:[1,0,0]
	v_pk_mul_f32 v[130:131], v[114:115], v[166:167] op_sel:[0,0] op_sel_hi:[0,1]
	v_pk_add_f32 v[142:143], v[118:119], v[122:123] op_sel:[0,1] op_sel_hi:[1,0]
	v_pk_add_f32 v[118:119], v[118:119], v[122:123] op_sel:[0,1] op_sel_hi:[1,0] neg_lo:[0,1] neg_hi:[0,1]
	v_pk_fma_f32 v[158:159], v[152:153], v[150:151], v[158:159] op_sel:[1,1,0] op_sel_hi:[1,0,1] neg_lo:[1,0,0]
	v_pk_fma_f32 v[168:169], v[156:157], v[156:157], v[168:169] op_sel:[1,1,0] op_sel_hi:[1,0,1] neg_lo:[1,0,0]
	v_pk_mul_f32 v[170:171], v[160:161], v[154:155] op_sel:[0,0] op_sel_hi:[0,1]
	v_pk_fma_f32 v[110:111], v[110:111], v[156:157], v[126:127] op_sel:[1,1,0] op_sel_hi:[1,0,1] neg_lo:[1,0,0]
	v_pk_fma_f32 v[114:115], v[114:115], v[166:167], v[130:131] op_sel:[1,1,0] op_sel_hi:[1,0,1] neg_lo:[1,0,0]
	s_nop 0
	v_mov_b32_e32 v122, v118
	v_pk_mul_f32 v[126:127], v[116:117], v[158:159] op_sel:[0,0] op_sel_hi:[0,1]
	v_pk_mul_f32 v[130:131], v[124:125], v[168:169] op_sel:[0,0] op_sel_hi:[0,1]
	v_mov_b32_e32 v123, v143
	v_pk_fma_f32 v[170:171], v[160:161], v[154:155], v[170:171] op_sel:[1,1,0] op_sel_hi:[1,0,1] neg_lo:[1,0,0]
	v_pk_mul_f32 v[172:173], v[158:159], v[158:159] op_sel:[0,0] op_sel_hi:[0,1]
	v_pk_mul_f32 v[174:175], v[160:161], v[158:159] op_sel:[0,0] op_sel_hi:[0,1]
	v_pk_fma_f32 v[116:117], v[116:117], v[158:159], v[126:127] op_sel:[1,1,0] op_sel_hi:[1,0,1] neg_lo:[1,0,0]
	v_pk_mul_f32 v[126:127], v[132:133], v[160:161] op_sel:[0,0] op_sel_hi:[0,1]
	v_pk_fma_f32 v[124:125], v[124:125], v[168:169], v[130:131] op_sel:[1,1,0] op_sel_hi:[1,0,1] neg_lo:[1,0,0]
	s_nop 0
	v_pk_mul_f32 v[130:131], v[122:123], v[170:171] op_sel:[0,0] op_sel_hi:[0,1]
	v_mov_b32_e32 v140, v134
	v_pk_fma_f32 v[172:173], v[158:159], v[158:159], v[172:173] op_sel:[1,1,0] op_sel_hi:[1,0,1] neg_lo:[1,0,0]
	v_pk_fma_f32 v[174:175], v[160:161], v[158:159], v[174:175] op_sel:[1,1,0] op_sel_hi:[1,0,1] neg_lo:[1,0,0]
	v_pk_mul_f32 v[176:177], v[144:145], v[138:139] op_sel:[0,0] op_sel_hi:[0,1]
	v_mov_b32_e32 v143, v119
	v_pk_fma_f32 v[138:139], v[144:145], v[138:139], v[176:177] op_sel:[1,1,0] op_sel_hi:[1,0,1] neg_lo:[1,0,0]
	v_pk_mul_f32 v[144:145], v[112:113], v[148:149] op_sel:[0,0] op_sel_hi:[0,1]
	v_pk_mul_f32 v[118:119], v[142:143], v[154:155] op_sel:[0,0] op_sel_hi:[0,1]
	v_pk_fma_f32 v[126:127], v[132:133], v[160:161], v[126:127] op_sel:[1,1,0] op_sel_hi:[1,0,1] neg_lo:[1,0,0]
	v_pk_fma_f32 v[122:123], v[122:123], v[170:171], v[130:131] op_sel:[1,1,0] op_sel_hi:[1,0,1] neg_lo:[1,0,0]
	v_pk_mul_f32 v[130:131], v[140:141], v[172:173] op_sel:[0,0] op_sel_hi:[0,1]
	v_pk_mul_f32 v[132:133], v[146:147], v[174:175] op_sel:[0,0] op_sel_hi:[0,1]
	s_nop 0
	v_pk_fma_f32 v[112:113], v[112:113], v[148:149], v[144:145] op_sel:[1,1,0] op_sel_hi:[1,0,1] neg_lo:[1,0,0]
	v_pk_mul_f32 v[144:145], v[128:129], v[150:151] op_sel:[0,0] op_sel_hi:[0,1]
	v_pk_fma_f32 v[118:119], v[142:143], v[154:155], v[118:119] op_sel:[1,1,0] op_sel_hi:[1,0,1] neg_lo:[1,0,0]
	v_readlane_b32 s11, v255, 28
	v_pk_fma_f32 v[128:129], v[128:129], v[150:151], v[144:145] op_sel:[1,1,0] op_sel_hi:[1,0,1] neg_lo:[1,0,0]
	v_pk_fma_f32 v[130:131], v[140:141], v[172:173], v[130:131] op_sel:[1,1,0] op_sel_hi:[1,0,1] neg_lo:[1,0,0]
	v_pk_fma_f32 v[132:133], v[146:147], v[174:175], v[132:133] op_sel:[1,1,0] op_sel_hi:[1,0,1] neg_lo:[1,0,0]
	ds_write2_b64 v1, v[136:137], v[138:139] offset1:2
	ds_write2_b64 v1, v[112:113], v[128:129] offset0:4 offset1:6
	ds_write2_b64 v1, v[120:121], v[118:119] offset0:8 offset1:10
	ds_write2_b64 v1, v[110:111], v[116:117] offset0:12 offset1:14
	ds_write2_b64 v1, v[126:127], v[106:107] offset0:17 offset1:19
	ds_write2_b64 v1, v[108:109], v[114:115] offset0:21 offset1:23
	ds_write2_b64 v1, v[124:125], v[122:123] offset0:25 offset1:27
	ds_write2_b64 v1, v[130:131], v[132:133] offset0:29 offset1:31
	v_mov_b32_e32 v1, v0
	s_waitcnt lgkmcnt(0)
	s_barrier
	s_waitcnt vmcnt(3)
	v_lshlrev_b32_e32 v110, 16, v104
	v_and_b32_e32 v26, -8, v1
	v_lshlrev_b32_e32 v28, 4, v1
	v_add3_u32 v26, 0, v26, v28
	ds_read2_b64 v[106:109], v26 offset1:1
	v_and_b32_e32 v111, 0xffff0000, v104
	v_lshlrev_b32_e32 v104, 16, v105
	v_and_b32_e32 v105, 0xffff0000, v105
	s_mov_b32 s30, s10
	s_waitcnt lgkmcnt(0)
	v_pk_add_f32 v[112:113], v[106:107], v[108:109]
	v_pk_add_f32 v[106:107], v[106:107], v[108:109] neg_lo:[0,1] neg_hi:[0,1]
	v_pk_mul_f32 v[108:109], v[112:113], v[110:111] op_sel:[0,0] op_sel_hi:[0,1]
	s_mov_b32 s31, s10
	v_pk_fma_f32 v[108:109], v[112:113], v[110:111], v[108:109] op_sel:[1,1,0] op_sel_hi:[1,0,1] neg_lo:[1,0,0]
	v_pk_mul_f32 v[110:111], v[106:107], v[104:105] op_sel:[0,0] op_sel_hi:[0,1]
	s_mov_b32 s10, s13
	v_pk_fma_f32 v[104:105], v[106:107], v[104:105], v[110:111] op_sel:[1,1,0] op_sel_hi:[1,0,1] neg_lo:[1,0,0]
	s_mov_b32 s11, s12
	v_pk_add_f32 v[106:107], v[108:109], v[104:105]
	v_pk_add_f32 v[104:105], v[108:109], v[104:105] neg_lo:[0,1] neg_hi:[0,1]
	ds_write2_b64 v26, v[106:107], v[104:105] offset1:1
	v_add_u32_e32 v26, 0x200, v1
	v_and_b32_e32 v28, -8, v26
	v_lshlrev_b32_e32 v26, 4, v26
	v_add3_u32 v26, 0, v28, v26
	ds_read2_b64 v[104:107], v26 offset1:1
	s_waitcnt vmcnt(2)
	v_lshlrev_b32_e32 v108, 16, v58
	v_and_b32_e32 v109, 0xffff0000, v58
	v_lshlrev_b32_e32 v58, 16, v59
	v_and_b32_e32 v59, 0xffff0000, v59
	s_waitcnt lgkmcnt(0)
	v_pk_add_f32 v[110:111], v[104:105], v[106:107]
	v_pk_add_f32 v[104:105], v[104:105], v[106:107] neg_lo:[0,1] neg_hi:[0,1]
	v_pk_mul_f32 v[106:107], v[110:111], v[108:109] op_sel:[0,0] op_sel_hi:[0,1]
	s_nop 0
	v_pk_fma_f32 v[106:107], v[110:111], v[108:109], v[106:107] op_sel:[1,1,0] op_sel_hi:[1,0,1] neg_lo:[1,0,0]
	v_pk_mul_f32 v[108:109], v[104:105], v[58:59] op_sel:[0,0] op_sel_hi:[0,1]
	s_nop 0
	v_pk_fma_f32 v[58:59], v[104:105], v[58:59], v[108:109] op_sel:[1,1,0] op_sel_hi:[1,0,1] neg_lo:[1,0,0]
	s_nop 0
	v_pk_add_f32 v[104:105], v[106:107], v[58:59]
	v_pk_add_f32 v[58:59], v[106:107], v[58:59] neg_lo:[0,1] neg_hi:[0,1]
	ds_write2_b64 v26, v[104:105], v[58:59] offset1:1
	v_add_u32_e32 v26, 0x400, v1
	v_and_b32_e32 v28, -8, v26
	v_lshlrev_b32_e32 v26, 4, v26
	v_add3_u32 v26, 0, v28, v26
	ds_read2_b64 v[104:107], v26 offset1:1
	s_waitcnt vmcnt(1)
	v_lshlrev_b32_e32 v58, 16, v48
	v_and_b32_e32 v59, 0xffff0000, v48
	v_lshlrev_b32_e32 v48, 16, v49
	v_and_b32_e32 v49, 0xffff0000, v49
	s_waitcnt lgkmcnt(0)
	v_pk_add_f32 v[108:109], v[104:105], v[106:107]
	v_pk_add_f32 v[104:105], v[104:105], v[106:107] neg_lo:[0,1] neg_hi:[0,1]
	v_pk_mul_f32 v[106:107], v[108:109], v[58:59] op_sel:[0,0] op_sel_hi:[0,1]
	s_nop 0
	v_pk_fma_f32 v[58:59], v[108:109], v[58:59], v[106:107] op_sel:[1,1,0] op_sel_hi:[1,0,1] neg_lo:[1,0,0]
	v_pk_mul_f32 v[106:107], v[104:105], v[48:49] op_sel:[0,0] op_sel_hi:[0,1]
	s_nop 0
	v_pk_fma_f32 v[48:49], v[104:105], v[48:49], v[106:107] op_sel:[1,1,0] op_sel_hi:[1,0,1] neg_lo:[1,0,0]
	s_nop 0
	v_pk_add_f32 v[104:105], v[58:59], v[48:49]
	v_pk_add_f32 v[48:49], v[58:59], v[48:49] neg_lo:[0,1] neg_hi:[0,1]
	ds_write2_b64 v26, v[104:105], v[48:49] offset1:1
	v_add_u32_e32 v26, 0x600, v1
	v_and_b32_e32 v28, -8, v26
	v_lshlrev_b32_e32 v26, 4, v26
	v_add3_u32 v26, 0, v28, v26
	ds_read2_b64 v[104:107], v26 offset1:1
	v_lshlrev_b32_e32 v48, 16, v46
	v_and_b32_e32 v49, 0xffff0000, v46
	v_lshlrev_b32_e32 v46, 16, v47
	v_and_b32_e32 v47, 0xffff0000, v47
	s_waitcnt lgkmcnt(0)
	v_pk_add_f32 v[58:59], v[104:105], v[106:107]
	v_pk_add_f32 v[104:105], v[104:105], v[106:107] neg_lo:[0,1] neg_hi:[0,1]
	v_pk_mul_f32 v[106:107], v[58:59], v[48:49] op_sel:[0,0] op_sel_hi:[0,1]
	s_nop 0
	v_pk_fma_f32 v[48:49], v[58:59], v[48:49], v[106:107] op_sel:[1,1,0] op_sel_hi:[1,0,1] neg_lo:[1,0,0]
	v_pk_mul_f32 v[58:59], v[104:105], v[46:47] op_sel:[0,0] op_sel_hi:[0,1]
	s_nop 0
	v_pk_fma_f32 v[46:47], v[104:105], v[46:47], v[58:59] op_sel:[1,1,0] op_sel_hi:[1,0,1] neg_lo:[1,0,0]
	s_nop 0
	v_pk_add_f32 v[58:59], v[48:49], v[46:47]
	v_pk_add_f32 v[46:47], v[48:49], v[46:47] neg_lo:[0,1] neg_hi:[0,1]
	ds_write2_b64 v26, v[58:59], v[46:47] offset1:1
	v_add_u32_e32 v26, 0x800, v1
	v_and_b32_e32 v28, -8, v26
	v_lshlrev_b32_e32 v26, 4, v26
	v_add3_u32 v26, 0, v28, v26
	ds_read2_b64 v[46:49], v26 offset1:1
	v_lshlrev_b32_e32 v58, 16, v38
	v_and_b32_e32 v59, 0xffff0000, v38
	v_lshlrev_b32_e32 v38, 16, v39
	v_and_b32_e32 v39, 0xffff0000, v39
	s_waitcnt lgkmcnt(0)
	v_pk_add_f32 v[104:105], v[46:47], v[48:49]
	v_pk_add_f32 v[46:47], v[46:47], v[48:49] neg_lo:[0,1] neg_hi:[0,1]
	v_pk_mul_f32 v[48:49], v[104:105], v[58:59] op_sel:[0,0] op_sel_hi:[0,1]
	s_nop 0
	v_pk_fma_f32 v[48:49], v[104:105], v[58:59], v[48:49] op_sel:[1,1,0] op_sel_hi:[1,0,1] neg_lo:[1,0,0]
	v_pk_mul_f32 v[58:59], v[46:47], v[38:39] op_sel:[0,0] op_sel_hi:[0,1]
	s_nop 0
	v_pk_fma_f32 v[38:39], v[46:47], v[38:39], v[58:59] op_sel:[1,1,0] op_sel_hi:[1,0,1] neg_lo:[1,0,0]
	s_nop 0
	v_pk_add_f32 v[46:47], v[48:49], v[38:39]
	v_pk_add_f32 v[38:39], v[48:49], v[38:39] neg_lo:[0,1] neg_hi:[0,1]
	ds_write2_b64 v26, v[46:47], v[38:39] offset1:1
	v_add_u32_e32 v26, 0xa00, v1
	v_and_b32_e32 v28, -8, v26
	v_lshlrev_b32_e32 v26, 4, v26
	v_add3_u32 v26, 0, v28, v26
	ds_read2_b64 v[46:49], v26 offset1:1
	v_lshlrev_b32_e32 v38, 16, v34
	v_and_b32_e32 v39, 0xffff0000, v34
	v_lshlrev_b32_e32 v34, 16, v35
	v_and_b32_e32 v35, 0xffff0000, v35
	s_waitcnt lgkmcnt(0)
	v_pk_add_f32 v[58:59], v[46:47], v[48:49]
	v_pk_add_f32 v[46:47], v[46:47], v[48:49] neg_lo:[0,1] neg_hi:[0,1]
	v_pk_mul_f32 v[48:49], v[58:59], v[38:39] op_sel:[0,0] op_sel_hi:[0,1]
	s_nop 0
	v_pk_fma_f32 v[38:39], v[58:59], v[38:39], v[48:49] op_sel:[1,1,0] op_sel_hi:[1,0,1] neg_lo:[1,0,0]
	v_pk_mul_f32 v[48:49], v[46:47], v[34:35] op_sel:[0,0] op_sel_hi:[0,1]
	s_nop 0
	v_pk_fma_f32 v[34:35], v[46:47], v[34:35], v[48:49] op_sel:[1,1,0] op_sel_hi:[1,0,1] neg_lo:[1,0,0]
	s_nop 0
	v_pk_add_f32 v[46:47], v[38:39], v[34:35]
	v_pk_add_f32 v[34:35], v[38:39], v[34:35] neg_lo:[0,1] neg_hi:[0,1]
	ds_write2_b64 v26, v[46:47], v[34:35] offset1:1
	v_add_u32_e32 v26, 0xc00, v1
	v_and_b32_e32 v28, -8, v26
	v_lshlrev_b32_e32 v26, 4, v26
	v_add3_u32 v26, 0, v28, v26
	ds_read2_b64 v[46:49], v26 offset1:1
	v_lshlrev_b32_e32 v34, 16, v20
	v_and_b32_e32 v35, 0xffff0000, v20
	v_lshlrev_b32_e32 v20, 16, v21
	v_and_b32_e32 v21, 0xffff0000, v21
	s_waitcnt lgkmcnt(0)
	v_pk_add_f32 v[38:39], v[46:47], v[48:49]
	v_pk_add_f32 v[46:47], v[46:47], v[48:49] neg_lo:[0,1] neg_hi:[0,1]
	v_pk_mul_f32 v[48:49], v[38:39], v[34:35] op_sel:[0,0] op_sel_hi:[0,1]
	v_add_u32_e32 v1, 0xe00, v1
	v_pk_fma_f32 v[34:35], v[38:39], v[34:35], v[48:49] op_sel:[1,1,0] op_sel_hi:[1,0,1] neg_lo:[1,0,0]
	v_pk_mul_f32 v[38:39], v[46:47], v[20:21] op_sel:[0,0] op_sel_hi:[0,1]
	s_nop 0
	v_pk_fma_f32 v[20:21], v[46:47], v[20:21], v[38:39] op_sel:[1,1,0] op_sel_hi:[1,0,1] neg_lo:[1,0,0]
	s_nop 0
	v_pk_add_f32 v[38:39], v[34:35], v[20:21]
	v_pk_add_f32 v[20:21], v[34:35], v[20:21] neg_lo:[0,1] neg_hi:[0,1]
	ds_write2_b64 v26, v[38:39], v[20:21] offset1:1
	v_and_b32_e32 v20, -8, v1
	v_lshlrev_b32_e32 v1, 4, v1
	v_add3_u32 v1, 0, v20, v1
	ds_read2_b64 v[46:49], v1 offset1:1
	s_waitcnt vmcnt(0)
	v_lshlrev_b32_e32 v20, 16, v18
	v_and_b32_e32 v21, 0xffff0000, v18
	v_lshlrev_b32_e32 v18, 16, v19
	v_and_b32_e32 v19, 0xffff0000, v19
	s_waitcnt lgkmcnt(0)
	v_pk_add_f32 v[34:35], v[46:47], v[48:49]
	v_pk_add_f32 v[38:39], v[46:47], v[48:49] neg_lo:[0,1] neg_hi:[0,1]
	v_pk_mul_f32 v[46:47], v[34:35], v[20:21] op_sel:[0,0] op_sel_hi:[0,1]
	s_nop 0
	v_pk_fma_f32 v[20:21], v[34:35], v[20:21], v[46:47] op_sel:[1,1,0] op_sel_hi:[1,0,1] neg_lo:[1,0,0]
	v_pk_mul_f32 v[34:35], v[38:39], v[18:19] op_sel:[0,0] op_sel_hi:[0,1]
	s_nop 0
	v_pk_fma_f32 v[18:19], v[38:39], v[18:19], v[34:35] op_sel:[1,1,0] op_sel_hi:[1,0,1] neg_lo:[1,0,0]
	s_nop 0
	v_pk_add_f32 v[34:35], v[20:21], v[18:19]
	v_pk_add_f32 v[18:19], v[20:21], v[18:19] neg_lo:[0,1] neg_hi:[0,1]
	ds_write2_b64 v1, v[34:35], v[18:19] offset1:1
	v_mov_b32_e32 v1, v0
	s_waitcnt lgkmcnt(0)
	s_barrier
	s_nop 0
	v_and_b32_e32 v18, 1, v1
	v_lshlrev_b32_e32 v1, 4, v1
	v_and_b32_e32 v1, 0xffffffe0, v1
	v_ashrrev_i32_e32 v19, 1, v1
	v_lshlrev_b32_e32 v20, 3, v18
	v_cvt_f32_ubyte0_e32 v18, v18
	v_add_u32_e32 v19, 0, v19
	v_lshlrev_b32_e32 v1, 3, v1
	v_mul_f32_e32 v18, 0x3d000000, v18
	v_add3_u32 v1, v19, v1, v20
	v_cos_f32_e32 v34, v18
	v_sin_f32_e32 v35, v18
	ds_read2_b64 v[18:21], v1 offset1:2
	ds_read2_b64 v[46:49], v1 offset0:4 offset1:6
	ds_read2_b64 v[104:107], v1 offset0:8 offset1:10
	ds_read2_b64 v[108:111], v1 offset0:12 offset1:14
	ds_read2_b64 v[112:115], v1 offset0:17 offset1:19
	ds_read2_b64 v[116:119], v1 offset0:21 offset1:23
	ds_read2_b64 v[120:123], v1 offset0:25 offset1:27
	ds_read2_b64 v[124:127], v1 offset0:29 offset1:31
	s_nop 1
	s_nop 0
	v_pk_mul_f32 v[38:39], v[34:35], v[34:35] op_sel:[0,0] op_sel_hi:[0,1]
	s_waitcnt lgkmcnt(7)
	v_pk_mul_f32 v[152:153], v[20:21], v[34:35] op_sel:[0,0] op_sel_hi:[0,1]
	v_pk_fma_f32 v[38:39], v[34:35], v[34:35], v[38:39] op_sel:[1,1,0] op_sel_hi:[1,0,1] neg_lo:[1,0,0]
	s_nop 0
	v_pk_fma_f32 v[152:153], v[20:21], v[34:35], v[152:153] op_sel:[1,1,0] op_sel_hi:[1,0,1] neg_lo:[1,0,0]
	v_pk_mul_f32 v[58:59], v[38:39], v[34:35] op_sel:[0,0] op_sel_hi:[0,1]
	s_waitcnt lgkmcnt(6)
	v_pk_mul_f32 v[20:21], v[46:47], v[38:39] op_sel:[0,0] op_sel_hi:[0,1]
	v_pk_mul_f32 v[128:129], v[38:39], v[38:39] op_sel:[0,0] op_sel_hi:[0,1]
	v_pk_fma_f32 v[58:59], v[38:39], v[34:35], v[58:59] op_sel:[1,1,0] op_sel_hi:[1,0,1] neg_lo:[1,0,0]
	s_nop 0
	v_pk_fma_f32 v[46:47], v[46:47], v[38:39], v[20:21] op_sel:[1,1,0] op_sel_hi:[1,0,1] neg_lo:[1,0,0]
	v_pk_fma_f32 v[128:129], v[38:39], v[38:39], v[128:129] op_sel:[1,1,0] op_sel_hi:[1,0,1] neg_lo:[1,0,0]
	v_pk_mul_f32 v[20:21], v[48:49], v[58:59] op_sel:[0,0] op_sel_hi:[0,1]
	s_nop 0
	v_pk_mul_f32 v[130:131], v[128:129], v[34:35] op_sel:[0,0] op_sel_hi:[0,1]
	v_pk_mul_f32 v[136:137], v[128:129], v[128:129] op_sel:[0,0] op_sel_hi:[0,1]
	v_pk_mul_f32 v[132:133], v[58:59], v[58:59] op_sel:[0,0] op_sel_hi:[0,1]
	v_pk_mul_f32 v[134:135], v[128:129], v[58:59] op_sel:[0,0] op_sel_hi:[0,1]
	v_pk_fma_f32 v[48:49], v[48:49], v[58:59], v[20:21] op_sel:[1,1,0] op_sel_hi:[1,0,1] neg_lo:[1,0,0]
	s_waitcnt lgkmcnt(5)
	v_pk_mul_f32 v[20:21], v[104:105], v[128:129] op_sel:[0,0] op_sel_hi:[0,1]
	v_pk_fma_f32 v[130:131], v[128:129], v[34:35], v[130:131] op_sel:[1,1,0] op_sel_hi:[1,0,1] neg_lo:[1,0,0]
	v_pk_fma_f32 v[136:137], v[128:129], v[128:129], v[136:137] op_sel:[1,1,0] op_sel_hi:[1,0,1] neg_lo:[1,0,0]
	v_pk_fma_f32 v[132:133], v[58:59], v[58:59], v[132:133] op_sel:[1,1,0] op_sel_hi:[1,0,1] neg_lo:[1,0,0]
	v_pk_fma_f32 v[134:135], v[128:129], v[58:59], v[134:135] op_sel:[1,1,0] op_sel_hi:[1,0,1] neg_lo:[1,0,0]
	s_nop 0
	v_pk_mul_f32 v[142:143], v[136:137], v[58:59] op_sel:[0,0] op_sel_hi:[0,1]
	v_pk_fma_f32 v[104:105], v[104:105], v[128:129], v[20:21] op_sel:[1,1,0] op_sel_hi:[1,0,1] neg_lo:[1,0,0]
	v_pk_mul_f32 v[20:21], v[106:107], v[130:131] op_sel:[0,0] op_sel_hi:[0,1]
	v_pk_mul_f32 v[138:139], v[136:137], v[34:35] op_sel:[0,0] op_sel_hi:[0,1]
	v_pk_mul_f32 v[140:141], v[130:131], v[130:131] op_sel:[0,0] op_sel_hi:[0,1]
	v_pk_mul_f32 v[144:145], v[132:133], v[132:133] op_sel:[0,0] op_sel_hi:[0,1]
	s_nop 0
	v_pk_fma_f32 v[142:143], v[136:137], v[58:59], v[142:143] op_sel:[1,1,0] op_sel_hi:[1,0,1] neg_lo:[1,0,0]
	v_pk_mul_f32 v[146:147], v[136:137], v[130:131] op_sel:[0,0] op_sel_hi:[0,1]
	v_pk_fma_f32 v[58:59], v[106:107], v[130:131], v[20:21] op_sel:[1,1,0] op_sel_hi:[1,0,1] neg_lo:[1,0,0]
	s_waitcnt lgkmcnt(4)
	v_pk_mul_f32 v[20:21], v[108:109], v[132:133] op_sel:[0,0] op_sel_hi:[0,1]
	v_pk_fma_f32 v[138:139], v[136:137], v[34:35], v[138:139] op_sel:[1,1,0] op_sel_hi:[1,0,1] neg_lo:[1,0,0]
	v_pk_fma_f32 v[140:141], v[130:131], v[130:131], v[140:141] op_sel:[1,1,0] op_sel_hi:[1,0,1] neg_lo:[1,0,0]
	v_pk_fma_f32 v[144:145], v[132:133], v[132:133], v[144:145] op_sel:[1,1,0] op_sel_hi:[1,0,1] neg_lo:[1,0,0]
	v_pk_fma_f32 v[146:147], v[136:137], v[130:131], v[146:147] op_sel:[1,1,0] op_sel_hi:[1,0,1] neg_lo:[1,0,0]
	v_pk_mul_f32 v[148:149], v[134:135], v[134:135] op_sel:[0,0] op_sel_hi:[0,1]
	s_nop 0
	v_pk_fma_f32 v[106:107], v[108:109], v[132:133], v[20:21] op_sel:[1,1,0] op_sel_hi:[1,0,1] neg_lo:[1,0,0]
	v_pk_mul_f32 v[20:21], v[110:111], v[134:135] op_sel:[0,0] op_sel_hi:[0,1]
	v_pk_mul_f32 v[150:151], v[136:137], v[134:135] op_sel:[0,0] op_sel_hi:[0,1]
	s_nop 0
	v_pk_fma_f32 v[108:109], v[110:111], v[134:135], v[20:21] op_sel:[1,1,0] op_sel_hi:[1,0,1] neg_lo:[1,0,0]
	s_waitcnt lgkmcnt(3)
	v_pk_mul_f32 v[20:21], v[112:113], v[136:137] op_sel:[0,0] op_sel_hi:[0,1]
	v_pk_fma_f32 v[148:149], v[134:135], v[134:135], v[148:149] op_sel:[1,1,0] op_sel_hi:[1,0,1] neg_lo:[1,0,0]
	v_pk_fma_f32 v[150:151], v[136:137], v[134:135], v[150:151] op_sel:[1,1,0] op_sel_hi:[1,0,1] neg_lo:[1,0,0]
	s_nop 0
	v_pk_fma_f32 v[110:111], v[112:113], v[136:137], v[20:21] op_sel:[1,1,0] op_sel_hi:[1,0,1] neg_lo:[1,0,0]
	v_pk_mul_f32 v[20:21], v[114:115], v[138:139] op_sel:[0,0] op_sel_hi:[0,1]
	s_nop 0
	v_pk_fma_f32 v[112:113], v[114:115], v[138:139], v[20:21] op_sel:[1,1,0] op_sel_hi:[1,0,1] neg_lo:[1,0,0]
	s_waitcnt lgkmcnt(2)
	v_pk_mul_f32 v[20:21], v[116:117], v[140:141] op_sel:[0,0] op_sel_hi:[0,1]
	s_nop 0
	v_pk_fma_f32 v[114:115], v[116:117], v[140:141], v[20:21] op_sel:[1,1,0] op_sel_hi:[1,0,1] neg_lo:[1,0,0]
	v_pk_mul_f32 v[20:21], v[118:119], v[142:143] op_sel:[0,0] op_sel_hi:[0,1]
	s_nop 0
	v_pk_fma_f32 v[116:117], v[118:119], v[142:143], v[20:21] op_sel:[1,1,0] op_sel_hi:[1,0,1] neg_lo:[1,0,0]
	s_waitcnt lgkmcnt(1)
	v_pk_mul_f32 v[20:21], v[120:121], v[144:145] op_sel:[0,0] op_sel_hi:[0,1]
	s_nop 0
	v_pk_fma_f32 v[118:119], v[120:121], v[144:145], v[20:21] op_sel:[1,1,0] op_sel_hi:[1,0,1] neg_lo:[1,0,0]
	v_pk_mul_f32 v[20:21], v[122:123], v[146:147] op_sel:[0,0] op_sel_hi:[0,1]
	s_nop 0
	v_pk_fma_f32 v[120:121], v[122:123], v[146:147], v[20:21] op_sel:[1,1,0] op_sel_hi:[1,0,1] neg_lo:[1,0,0]
	s_waitcnt lgkmcnt(0)
	v_pk_mul_f32 v[20:21], v[124:125], v[148:149] op_sel:[0,0] op_sel_hi:[0,1]
	v_pk_add_f32 v[140:141], v[104:105], v[118:119]
	v_pk_fma_f32 v[122:123], v[124:125], v[148:149], v[20:21] op_sel:[1,1,0] op_sel_hi:[1,0,1] neg_lo:[1,0,0]
	v_pk_mul_f32 v[20:21], v[126:127], v[150:151] op_sel:[0,0] op_sel_hi:[0,1]
	v_pk_add_f32 v[34:35], v[58:59], v[120:121] neg_lo:[0,1] neg_hi:[0,1]
	v_pk_fma_f32 v[124:125], v[126:127], v[150:151], v[20:21] op_sel:[1,1,0] op_sel_hi:[1,0,1] neg_lo:[1,0,0]
	v_pk_add_f32 v[20:21], v[152:153], v[112:113] neg_lo:[0,1] neg_hi:[0,1]
	v_pk_add_f32 v[112:113], v[152:153], v[112:113]
	v_pk_add_f32 v[38:39], v[20:21], v[34:35] op_sel:[0,1] op_sel_hi:[1,0] neg_lo:[0,1] neg_hi:[0,1]
	v_pk_add_f32 v[126:127], v[20:21], v[34:35] op_sel:[0,1] op_sel_hi:[1,0]
	v_mov_b32_e32 v20, v38
	v_mov_b32_e32 v21, v127
	v_mov_b32_e32 v127, v39
	v_pk_add_f32 v[34:35], v[46:47], v[114:115] neg_lo:[0,1] neg_hi:[0,1]
	v_pk_add_f32 v[38:39], v[106:107], v[122:123] neg_lo:[0,1] neg_hi:[0,1]
	v_pk_add_f32 v[58:59], v[58:59], v[120:121]
	v_pk_add_f32 v[128:129], v[34:35], v[38:39] op_sel:[0,1] op_sel_hi:[1,0] neg_lo:[0,1] neg_hi:[0,1]
	v_pk_add_f32 v[130:131], v[34:35], v[38:39] op_sel:[0,1] op_sel_hi:[1,0]
	v_pk_add_f32 v[34:35], v[48:49], v[116:117] neg_lo:[0,1] neg_hi:[0,1]
	v_pk_add_f32 v[38:39], v[108:109], v[124:125] neg_lo:[0,1] neg_hi:[0,1]
	v_mov_b32_e32 v132, v128
	v_mov_b32_e32 v133, v131
	v_mov_b32_e32 v131, v129
	v_pk_add_f32 v[128:129], v[34:35], v[38:39] op_sel:[0,1] op_sel_hi:[1,0] neg_lo:[0,1] neg_hi:[0,1]
	v_pk_add_f32 v[134:135], v[34:35], v[38:39] op_sel:[0,1] op_sel_hi:[1,0]
	v_mov_b64_e32 v[38:39], s[12:13]
	v_pk_mul_f32 v[34:35], v[20:21], v[38:39] op_sel:[0,0] op_sel_hi:[0,1]
	v_mov_b32_e32 v136, v128
	v_mov_b32_e32 v137, v135
	v_mov_b32_e32 v135, v129
	v_pk_fma_f32 v[128:129], v[20:21], v[38:39], v[34:35] op_sel:[1,1,0] op_sel_hi:[1,0,1] neg_lo:[1,0,0]
	v_mov_b64_e32 v[34:35], s[30:31]
	v_pk_mul_f32 v[20:21], v[132:133], v[34:35] op_sel:[0,0] op_sel_hi:[0,1]
	v_pk_add_f32 v[46:47], v[46:47], v[114:115]
	v_pk_fma_f32 v[132:133], v[132:133], v[34:35], v[20:21] op_sel:[1,1,0] op_sel_hi:[1,0,1] neg_lo:[1,0,0]
	v_mov_b64_e32 v[20:21], s[10:11]
	v_readlane_b32 s10, v255, 29
	v_readlane_b32 s11, v255, 30
	v_pk_add_f32 v[106:107], v[106:107], v[122:123]
	s_mov_b32 s13, s11
	v_writelane_b32 v255, s10, 29
	v_pk_add_f32 v[120:121], v[112:113], v[58:59]
	v_pk_add_f32 v[58:59], v[112:113], v[58:59] neg_lo:[0,1] neg_hi:[0,1]
	v_pk_add_f32 v[112:113], v[46:47], v[106:107]
	v_pk_add_f32 v[106:107], v[46:47], v[106:107] neg_lo:[0,1] neg_hi:[0,1]
	v_pk_add_f32 v[46:47], v[48:49], v[116:117]
	v_pk_add_f32 v[48:49], v[108:109], v[124:125]
	v_writelane_b32 v255, s11, 30
	v_pk_add_f32 v[108:109], v[46:47], v[48:49]
	v_pk_add_f32 v[114:115], v[46:47], v[48:49] neg_lo:[0,1] neg_hi:[0,1]
	v_pk_mul_f32 v[46:47], v[58:59], v[34:35] op_sel:[0,0] op_sel_hi:[0,1]
	s_mov_b32 s12, s67
	v_readlane_b32 s10, v255, 19
	v_pk_fma_f32 v[116:117], v[58:59], v[34:35], v[46:47] op_sel:[1,1,0] op_sel_hi:[1,0,1] neg_lo:[1,0,0]
	v_mov_b64_e32 v[46:47], s[12:13]
	v_readlane_b32 s11, v255, 20
	s_mov_b32 s12, s10
	s_mov_b32 s10, s30
	v_writelane_b32 v255, s10, 27
	v_pk_mul_f32 v[48:49], v[106:107], v[46:47] op_sel:[0,0] op_sel_hi:[0,1]
	s_mov_b32 s13, s30
	v_pk_fma_f32 v[106:107], v[106:107], v[46:47], v[48:49] op_sel:[1,1,0] op_sel_hi:[1,0,1] neg_lo:[1,0,0]
	v_mov_b64_e32 v[48:49], s[12:13]
	v_writelane_b32 v255, s11, 28
	s_mov_b32 s10, s12
	v_writelane_b32 v255, s10, 19
	v_pk_mul_f32 v[58:59], v[114:115], v[48:49] op_sel:[0,0] op_sel_hi:[0,1]
	v_pk_mul_f32 v[138:139], v[136:137], v[20:21] op_sel:[0,0] op_sel_hi:[0,1]
	v_pk_add_f32 v[104:105], v[104:105], v[118:119] neg_lo:[0,1] neg_hi:[0,1]
	v_pk_fma_f32 v[114:115], v[114:115], v[48:49], v[58:59] op_sel:[1,1,0] op_sel_hi:[1,0,1] neg_lo:[1,0,0]
	v_pk_mul_f32 v[58:59], v[126:127], v[20:21] op_sel:[0,0] op_sel_hi:[0,1]
	s_nop 0
	v_writelane_b32 v255, s11, 20
	s_mov_b32 s10, 0xbf6c835e
	v_pk_fma_f32 v[136:137], v[136:137], v[20:21], v[138:139] op_sel:[1,1,0] op_sel_hi:[1,0,1] neg_lo:[1,0,0]
	v_pk_add_f32 v[138:139], v[18:19], v[110:111]
	v_pk_fma_f32 v[122:123], v[126:127], v[20:21], v[58:59] op_sel:[1,1,0] op_sel_hi:[1,0,1] neg_lo:[1,0,0]
	v_pk_mul_f32 v[58:59], v[130:131], v[48:49] op_sel:[0,0] op_sel_hi:[0,1]
	s_mov_b32 s11, 0xbec3ef15
	v_pk_add_f32 v[18:19], v[18:19], v[110:111] neg_lo:[0,1] neg_hi:[0,1]
	v_pk_add_f32 v[142:143], v[138:139], v[140:141]
	v_pk_fma_f32 v[124:125], v[130:131], v[48:49], v[58:59] op_sel:[1,1,0] op_sel_hi:[1,0,1] neg_lo:[1,0,0]
	v_mov_b64_e32 v[58:59], s[10:11]
	v_pk_mul_f32 v[126:127], v[134:135], v[58:59] op_sel:[0,0] op_sel_hi:[0,1]
	v_pk_add_f32 v[110:111], v[18:19], v[104:105] op_sel:[0,1] op_sel_hi:[1,0] neg_lo:[0,1] neg_hi:[0,1]
	v_pk_add_f32 v[18:19], v[18:19], v[104:105] op_sel:[0,1] op_sel_hi:[1,0]
	v_pk_fma_f32 v[126:127], v[134:135], v[58:59], v[126:127] op_sel:[1,1,0] op_sel_hi:[1,0,1] neg_lo:[1,0,0]
	v_pk_add_f32 v[130:131], v[142:143], v[112:113]
	v_pk_add_f32 v[134:135], v[120:121], v[108:109]
	v_mov_b32_e32 v104, v110
	v_mov_b32_e32 v105, v19
	v_pk_add_f32 v[144:145], v[130:131], v[134:135]
	v_pk_add_f32 v[130:131], v[130:131], v[134:135] neg_lo:[0,1] neg_hi:[0,1]
	v_pk_add_f32 v[118:119], v[104:105], v[132:133]
	v_pk_add_f32 v[134:135], v[128:129], v[136:137]
	v_pk_add_f32 v[112:113], v[142:143], v[112:113] neg_lo:[0,1] neg_hi:[0,1]
	v_pk_add_f32 v[142:143], v[118:119], v[134:135]
	v_pk_add_f32 v[118:119], v[118:119], v[134:135] neg_lo:[0,1] neg_hi:[0,1]
	v_pk_add_f32 v[134:135], v[138:139], v[140:141] neg_lo:[0,1] neg_hi:[0,1]
	v_mov_b32_e32 v19, v111
	v_pk_add_f32 v[108:109], v[120:121], v[108:109] neg_lo:[0,1] neg_hi:[0,1]
	v_pk_add_f32 v[128:129], v[128:129], v[136:137] neg_lo:[0,1] neg_hi:[0,1]
	v_pk_add_f32 v[104:105], v[104:105], v[132:133] neg_lo:[0,1] neg_hi:[0,1]
	v_pk_add_f32 v[136:137], v[134:135], v[106:107]
	v_pk_add_f32 v[138:139], v[116:117], v[114:115]
	v_pk_add_f32 v[114:115], v[116:117], v[114:115] neg_lo:[0,1] neg_hi:[0,1]
	v_pk_add_f32 v[106:107], v[134:135], v[106:107] neg_lo:[0,1] neg_hi:[0,1]
	v_pk_add_f32 v[110:111], v[18:19], v[124:125]
	v_pk_add_f32 v[134:135], v[122:123], v[126:127]
	v_pk_add_f32 v[122:123], v[122:123], v[126:127] neg_lo:[0,1] neg_hi:[0,1]
	v_pk_add_f32 v[18:19], v[18:19], v[124:125] neg_lo:[0,1] neg_hi:[0,1]
	v_pk_add_f32 v[120:121], v[112:113], v[108:109] op_sel:[0,1] op_sel_hi:[1,0] neg_lo:[0,1] neg_hi:[0,1]
	v_pk_add_f32 v[108:109], v[112:113], v[108:109] op_sel:[0,1] op_sel_hi:[1,0]
	v_pk_add_f32 v[132:133], v[104:105], v[128:129] op_sel:[0,1] op_sel_hi:[1,0] neg_lo:[0,1] neg_hi:[0,1]
	v_pk_add_f32 v[104:105], v[104:105], v[128:129] op_sel:[0,1] op_sel_hi:[1,0]
	v_pk_add_f32 v[116:117], v[106:107], v[114:115] op_sel:[0,1] op_sel_hi:[1,0] neg_lo:[0,1] neg_hi:[0,1]
	v_pk_add_f32 v[106:107], v[106:107], v[114:115] op_sel:[0,1] op_sel_hi:[1,0]
	v_pk_add_f32 v[124:125], v[18:19], v[122:123] op_sel:[0,1] op_sel_hi:[1,0] neg_lo:[0,1] neg_hi:[0,1]
	v_pk_add_f32 v[18:19], v[18:19], v[122:123] op_sel:[0,1] op_sel_hi:[1,0]
	v_mov_b32_e32 v113, v109
	v_mov_b32_e32 v129, v105
	v_mov_b32_e32 v115, v107
	v_mov_b32_e32 v123, v19
	v_mov_b32_e32 v109, v121
	v_mov_b32_e32 v105, v133
	v_mov_b32_e32 v107, v117
	v_mov_b32_e32 v19, v125
	v_mov_b32_e32 v112, v120
	v_mov_b32_e32 v128, v132
	v_pk_add_f32 v[140:141], v[136:137], v[138:139]
	v_pk_add_f32 v[136:137], v[136:137], v[138:139] neg_lo:[0,1] neg_hi:[0,1]
	v_mov_b32_e32 v114, v116
	v_pk_add_f32 v[138:139], v[110:111], v[134:135]
	v_pk_add_f32 v[110:111], v[110:111], v[134:135] neg_lo:[0,1] neg_hi:[0,1]
	v_mov_b32_e32 v122, v124
	ds_write2_b64 v1, v[144:145], v[142:143] offset1:2
	ds_write2_b64 v1, v[140:141], v[138:139] offset0:4 offset1:6
	ds_write2_b64 v1, v[112:113], v[128:129] offset0:8 offset1:10
	ds_write2_b64 v1, v[114:115], v[122:123] offset0:12 offset1:14
	ds_write2_b64 v1, v[130:131], v[118:119] offset0:17 offset1:19
	ds_write2_b64 v1, v[136:137], v[110:111] offset0:21 offset1:23
	ds_write2_b64 v1, v[108:109], v[104:105] offset0:25 offset1:27
	ds_write2_b64 v1, v[106:107], v[18:19] offset0:29 offset1:31
	v_mov_b32_e32 v1, v0
	s_waitcnt lgkmcnt(0)
	s_barrier
	s_mov_b64 s[30:31], 0
	v_and_b32_e32 v18, 31, v1
	v_lshlrev_b32_e32 v1, 4, v1
	v_and_or_b32 v1, v1, s25, v18
	v_ashrrev_i32_e32 v19, 4, v1
	v_lshlrev_b32_e32 v19, 3, v19
	v_lshlrev_b32_e32 v1, 3, v1
	v_cvt_f32_ubyte0_e32 v18, v18
	v_add3_u32 v1, 0, v19, v1
	v_mul_f32_e32 v19, 0x3b000000, v18
	v_cos_f32_e32 v18, v19
	v_sin_f32_e32 v19, v19
	v_add_u32_e32 v26, 0x800, v1
	ds_read2_b64 v[104:107], v1 offset1:34
	ds_read2_b64 v[108:111], v1 offset0:68 offset1:102
	ds_read2_b64 v[112:115], v1 offset0:136 offset1:170
	ds_read2_b64 v[116:119], v1 offset0:204 offset1:238
	ds_read2_b64 v[120:123], v26 offset0:16 offset1:50
	ds_read2_b64 v[124:127], v26 offset0:84 offset1:118
	ds_read2_b64 v[128:131], v26 offset0:152 offset1:186
	ds_read2_b64 v[132:135], v26 offset0:220 offset1:254
	s_nop 1
	s_nop 0
	v_pk_mul_f32 v[136:137], v[18:19], v[18:19] op_sel:[0,0] op_sel_hi:[0,1]
	s_waitcnt lgkmcnt(7)
	v_pk_mul_f32 v[164:165], v[106:107], v[18:19] op_sel:[0,0] op_sel_hi:[0,1]
	v_pk_fma_f32 v[136:137], v[18:19], v[18:19], v[136:137] op_sel:[1,1,0] op_sel_hi:[1,0,1] neg_lo:[1,0,0]
	s_nop 0
	v_pk_mul_f32 v[140:141], v[136:137], v[136:137] op_sel:[0,0] op_sel_hi:[0,1]
	v_pk_mul_f32 v[138:139], v[136:137], v[18:19] op_sel:[0,0] op_sel_hi:[0,1]
	s_nop 0
	v_pk_fma_f32 v[140:141], v[136:137], v[136:137], v[140:141] op_sel:[1,1,0] op_sel_hi:[1,0,1] neg_lo:[1,0,0]
	v_pk_fma_f32 v[138:139], v[136:137], v[18:19], v[138:139] op_sel:[1,1,0] op_sel_hi:[1,0,1] neg_lo:[1,0,0]
	s_nop 0
	v_pk_mul_f32 v[148:149], v[140:141], v[140:141] op_sel:[0,0] op_sel_hi:[0,1]
	v_pk_mul_f32 v[142:143], v[140:141], v[18:19] op_sel:[0,0] op_sel_hi:[0,1]
	v_pk_mul_f32 v[144:145], v[138:139], v[138:139] op_sel:[0,0] op_sel_hi:[0,1]
	v_pk_mul_f32 v[146:147], v[140:141], v[138:139] op_sel:[0,0] op_sel_hi:[0,1]
	s_nop 0
	v_pk_fma_f32 v[148:149], v[140:141], v[140:141], v[148:149] op_sel:[1,1,0] op_sel_hi:[1,0,1] neg_lo:[1,0,0]
	v_pk_fma_f32 v[142:143], v[140:141], v[18:19], v[142:143] op_sel:[1,1,0] op_sel_hi:[1,0,1] neg_lo:[1,0,0]
	v_pk_fma_f32 v[144:145], v[138:139], v[138:139], v[144:145] op_sel:[1,1,0] op_sel_hi:[1,0,1] neg_lo:[1,0,0]
	v_pk_fma_f32 v[146:147], v[140:141], v[138:139], v[146:147] op_sel:[1,1,0] op_sel_hi:[1,0,1] neg_lo:[1,0,0]
	s_nop 0
	v_pk_mul_f32 v[150:151], v[148:149], v[18:19] op_sel:[0,0] op_sel_hi:[0,1]
	v_pk_mul_f32 v[152:153], v[142:143], v[142:143] op_sel:[0,0] op_sel_hi:[0,1]
	v_pk_mul_f32 v[154:155], v[148:149], v[138:139] op_sel:[0,0] op_sel_hi:[0,1]
	v_pk_mul_f32 v[156:157], v[144:145], v[144:145] op_sel:[0,0] op_sel_hi:[0,1]
	v_pk_mul_f32 v[158:159], v[148:149], v[142:143] op_sel:[0,0] op_sel_hi:[0,1]
	v_pk_mul_f32 v[160:161], v[146:147], v[146:147] op_sel:[0,0] op_sel_hi:[0,1]
	s_nop 0
	v_pk_fma_f32 v[150:151], v[148:149], v[18:19], v[150:151] op_sel:[1,1,0] op_sel_hi:[1,0,1] neg_lo:[1,0,0]
	v_pk_fma_f32 v[18:19], v[106:107], v[18:19], v[164:165] op_sel:[1,1,0] op_sel_hi:[1,0,1] neg_lo:[1,0,0]
	s_waitcnt lgkmcnt(6)
	v_pk_mul_f32 v[106:107], v[108:109], v[136:137] op_sel:[0,0] op_sel_hi:[0,1]
	v_pk_fma_f32 v[152:153], v[142:143], v[142:143], v[152:153] op_sel:[1,1,0] op_sel_hi:[1,0,1] neg_lo:[1,0,0]
	v_pk_fma_f32 v[154:155], v[148:149], v[138:139], v[154:155] op_sel:[1,1,0] op_sel_hi:[1,0,1] neg_lo:[1,0,0]
	v_pk_fma_f32 v[156:157], v[144:145], v[144:145], v[156:157] op_sel:[1,1,0] op_sel_hi:[1,0,1] neg_lo:[1,0,0]
	v_pk_fma_f32 v[158:159], v[148:149], v[142:143], v[158:159] op_sel:[1,1,0] op_sel_hi:[1,0,1] neg_lo:[1,0,0]
	v_pk_fma_f32 v[160:161], v[146:147], v[146:147], v[160:161] op_sel:[1,1,0] op_sel_hi:[1,0,1] neg_lo:[1,0,0]
	s_nop 0
	v_pk_fma_f32 v[106:107], v[108:109], v[136:137], v[106:107] op_sel:[1,1,0] op_sel_hi:[1,0,1] neg_lo:[1,0,0]
	v_pk_mul_f32 v[108:109], v[110:111], v[138:139] op_sel:[0,0] op_sel_hi:[0,1]
	v_pk_mul_f32 v[162:163], v[148:149], v[146:147] op_sel:[0,0] op_sel_hi:[0,1]
	s_nop 0
	v_pk_fma_f32 v[108:109], v[110:111], v[138:139], v[108:109] op_sel:[1,1,0] op_sel_hi:[1,0,1] neg_lo:[1,0,0]
	s_waitcnt lgkmcnt(5)
	v_pk_mul_f32 v[110:111], v[112:113], v[140:141] op_sel:[0,0] op_sel_hi:[0,1]
	v_pk_fma_f32 v[162:163], v[148:149], v[146:147], v[162:163] op_sel:[1,1,0] op_sel_hi:[1,0,1] neg_lo:[1,0,0]
	s_nop 0
	v_pk_fma_f32 v[110:111], v[112:113], v[140:141], v[110:111] op_sel:[1,1,0] op_sel_hi:[1,0,1] neg_lo:[1,0,0]
	v_pk_mul_f32 v[112:113], v[114:115], v[142:143] op_sel:[0,0] op_sel_hi:[0,1]
	s_nop 0
	v_pk_fma_f32 v[112:113], v[114:115], v[142:143], v[112:113] op_sel:[1,1,0] op_sel_hi:[1,0,1] neg_lo:[1,0,0]
	s_waitcnt lgkmcnt(4)
	v_pk_mul_f32 v[114:115], v[116:117], v[144:145] op_sel:[0,0] op_sel_hi:[0,1]
	s_nop 0
	v_pk_fma_f32 v[114:115], v[116:117], v[144:145], v[114:115] op_sel:[1,1,0] op_sel_hi:[1,0,1] neg_lo:[1,0,0]
	v_pk_mul_f32 v[116:117], v[118:119], v[146:147] op_sel:[0,0] op_sel_hi:[0,1]
	s_nop 0
	v_pk_fma_f32 v[116:117], v[118:119], v[146:147], v[116:117] op_sel:[1,1,0] op_sel_hi:[1,0,1] neg_lo:[1,0,0]
	s_waitcnt lgkmcnt(3)
	v_pk_mul_f32 v[118:119], v[120:121], v[148:149] op_sel:[0,0] op_sel_hi:[0,1]
	s_nop 0
	v_pk_fma_f32 v[118:119], v[120:121], v[148:149], v[118:119] op_sel:[1,1,0] op_sel_hi:[1,0,1] neg_lo:[1,0,0]
	v_pk_mul_f32 v[120:121], v[122:123], v[150:151] op_sel:[0,0] op_sel_hi:[0,1]
	s_nop 0
	v_pk_fma_f32 v[120:121], v[122:123], v[150:151], v[120:121] op_sel:[1,1,0] op_sel_hi:[1,0,1] neg_lo:[1,0,0]
	s_waitcnt lgkmcnt(2)
	v_pk_mul_f32 v[122:123], v[124:125], v[152:153] op_sel:[0,0] op_sel_hi:[0,1]
	s_nop 0
	v_pk_fma_f32 v[122:123], v[124:125], v[152:153], v[122:123] op_sel:[1,1,0] op_sel_hi:[1,0,1] neg_lo:[1,0,0]
	v_pk_mul_f32 v[124:125], v[126:127], v[154:155] op_sel:[0,0] op_sel_hi:[0,1]
	s_nop 0
	v_pk_fma_f32 v[124:125], v[126:127], v[154:155], v[124:125] op_sel:[1,1,0] op_sel_hi:[1,0,1] neg_lo:[1,0,0]
	s_waitcnt lgkmcnt(1)
	v_pk_mul_f32 v[126:127], v[128:129], v[156:157] op_sel:[0,0] op_sel_hi:[0,1]
	s_nop 0
	v_pk_fma_f32 v[126:127], v[128:129], v[156:157], v[126:127] op_sel:[1,1,0] op_sel_hi:[1,0,1] neg_lo:[1,0,0]
	v_pk_mul_f32 v[128:129], v[130:131], v[158:159] op_sel:[0,0] op_sel_hi:[0,1]
	s_nop 0
	v_pk_fma_f32 v[128:129], v[130:131], v[158:159], v[128:129] op_sel:[1,1,0] op_sel_hi:[1,0,1] neg_lo:[1,0,0]
	s_waitcnt lgkmcnt(0)
	v_pk_mul_f32 v[130:131], v[132:133], v[160:161] op_sel:[0,0] op_sel_hi:[0,1]
	v_pk_add_f32 v[148:149], v[110:111], v[126:127]
	v_pk_fma_f32 v[130:131], v[132:133], v[160:161], v[130:131] op_sel:[1,1,0] op_sel_hi:[1,0,1] neg_lo:[1,0,0]
	v_pk_mul_f32 v[132:133], v[134:135], v[162:163] op_sel:[0,0] op_sel_hi:[0,1]
	v_pk_add_f32 v[136:137], v[112:113], v[128:129] neg_lo:[0,1] neg_hi:[0,1]
	v_pk_fma_f32 v[132:133], v[134:135], v[162:163], v[132:133] op_sel:[1,1,0] op_sel_hi:[1,0,1] neg_lo:[1,0,0]
	v_pk_add_f32 v[134:135], v[18:19], v[120:121] neg_lo:[0,1] neg_hi:[0,1]
	v_pk_add_f32 v[140:141], v[114:115], v[130:131] neg_lo:[0,1] neg_hi:[0,1]
	v_pk_add_f32 v[138:139], v[134:135], v[136:137] op_sel:[0,1] op_sel_hi:[1,0] neg_lo:[0,1] neg_hi:[0,1]
	v_pk_add_f32 v[134:135], v[134:135], v[136:137] op_sel:[0,1] op_sel_hi:[1,0]
	v_mov_b32_e32 v136, v138
	v_mov_b32_e32 v137, v135
	v_mov_b32_e32 v135, v139
	v_pk_add_f32 v[138:139], v[106:107], v[122:123] neg_lo:[0,1] neg_hi:[0,1]
	v_pk_add_f32 v[144:145], v[116:117], v[132:133] neg_lo:[0,1] neg_hi:[0,1]
	v_pk_add_f32 v[142:143], v[138:139], v[140:141] op_sel:[0,1] op_sel_hi:[1,0] neg_lo:[0,1] neg_hi:[0,1]
	v_pk_add_f32 v[138:139], v[138:139], v[140:141] op_sel:[0,1] op_sel_hi:[1,0]
	v_mov_b32_e32 v140, v142
	v_mov_b32_e32 v141, v139
	v_mov_b32_e32 v139, v143
	v_pk_add_f32 v[142:143], v[108:109], v[124:125] neg_lo:[0,1] neg_hi:[0,1]
	v_pk_add_f32 v[18:19], v[18:19], v[120:121]
	v_pk_add_f32 v[146:147], v[142:143], v[144:145] op_sel:[0,1] op_sel_hi:[1,0] neg_lo:[0,1] neg_hi:[0,1]
	v_pk_add_f32 v[142:143], v[142:143], v[144:145] op_sel:[0,1] op_sel_hi:[1,0]
	v_pk_add_f32 v[112:113], v[112:113], v[128:129]
	v_mov_b32_e32 v144, v146
	v_mov_b32_e32 v145, v143
	v_mov_b32_e32 v143, v147
	v_pk_mul_f32 v[146:147], v[136:137], v[38:39] op_sel:[0,0] op_sel_hi:[0,1]
	v_pk_add_f32 v[120:121], v[18:19], v[112:113]
	v_pk_add_f32 v[18:19], v[18:19], v[112:113] neg_lo:[0,1] neg_hi:[0,1]
	v_pk_add_f32 v[106:107], v[106:107], v[122:123]
	v_pk_add_f32 v[112:113], v[114:115], v[130:131]
	v_pk_fma_f32 v[136:137], v[136:137], v[38:39], v[146:147] op_sel:[1,1,0] op_sel_hi:[1,0,1] neg_lo:[1,0,0]
	v_pk_mul_f32 v[146:147], v[140:141], v[34:35] op_sel:[0,0] op_sel_hi:[0,1]
	v_pk_add_f32 v[108:109], v[108:109], v[124:125]
	v_pk_add_f32 v[114:115], v[106:107], v[112:113]
	v_pk_add_f32 v[106:107], v[106:107], v[112:113] neg_lo:[0,1] neg_hi:[0,1]
	v_pk_add_f32 v[112:113], v[116:117], v[132:133]
	v_pk_fma_f32 v[140:141], v[140:141], v[34:35], v[146:147] op_sel:[1,1,0] op_sel_hi:[1,0,1] neg_lo:[1,0,0]
	v_pk_mul_f32 v[146:147], v[144:145], v[20:21] op_sel:[0,0] op_sel_hi:[0,1]
	v_pk_add_f32 v[110:111], v[110:111], v[126:127] neg_lo:[0,1] neg_hi:[0,1]
	v_pk_add_f32 v[116:117], v[108:109], v[112:113]
	v_pk_add_f32 v[108:109], v[108:109], v[112:113] neg_lo:[0,1] neg_hi:[0,1]
	v_pk_mul_f32 v[112:113], v[18:19], v[34:35] op_sel:[0,0] op_sel_hi:[0,1]
	v_pk_fma_f32 v[144:145], v[144:145], v[20:21], v[146:147] op_sel:[1,1,0] op_sel_hi:[1,0,1] neg_lo:[1,0,0]
	v_pk_add_f32 v[146:147], v[104:105], v[118:119]
	v_pk_fma_f32 v[18:19], v[18:19], v[34:35], v[112:113] op_sel:[1,1,0] op_sel_hi:[1,0,1] neg_lo:[1,0,0]
	v_pk_mul_f32 v[112:113], v[106:107], v[46:47] op_sel:[0,0] op_sel_hi:[0,1]
	v_pk_add_f32 v[104:105], v[104:105], v[118:119] neg_lo:[0,1] neg_hi:[0,1]
	v_pk_add_f32 v[150:151], v[146:147], v[148:149]
	v_pk_fma_f32 v[106:107], v[106:107], v[46:47], v[112:113] op_sel:[1,1,0] op_sel_hi:[1,0,1] neg_lo:[1,0,0]
	v_pk_mul_f32 v[112:113], v[108:109], v[48:49] op_sel:[0,0] op_sel_hi:[0,1]
	v_pk_add_f32 v[118:119], v[104:105], v[110:111] op_sel:[0,1] op_sel_hi:[1,0] neg_lo:[0,1] neg_hi:[0,1]
	v_pk_add_f32 v[104:105], v[104:105], v[110:111] op_sel:[0,1] op_sel_hi:[1,0]
	v_pk_fma_f32 v[108:109], v[108:109], v[48:49], v[112:113] op_sel:[1,1,0] op_sel_hi:[1,0,1] neg_lo:[1,0,0]
	v_pk_mul_f32 v[112:113], v[134:135], v[20:21] op_sel:[0,0] op_sel_hi:[0,1]
	v_pk_mul_f32 v[122:123], v[138:139], v[48:49] op_sel:[0,0] op_sel_hi:[0,1]
	v_pk_add_f32 v[128:129], v[150:151], v[114:115]
	v_pk_add_f32 v[130:131], v[120:121], v[116:117]
	v_mov_b32_e32 v110, v118
	v_mov_b32_e32 v111, v105
	v_pk_fma_f32 v[112:113], v[134:135], v[20:21], v[112:113] op_sel:[1,1,0] op_sel_hi:[1,0,1] neg_lo:[1,0,0]
	v_pk_fma_f32 v[122:123], v[138:139], v[48:49], v[122:123] op_sel:[1,1,0] op_sel_hi:[1,0,1] neg_lo:[1,0,0]
	v_pk_mul_f32 v[124:125], v[142:143], v[58:59] op_sel:[0,0] op_sel_hi:[0,1]
	v_pk_add_f32 v[132:133], v[128:129], v[130:131]
	v_pk_add_f32 v[128:129], v[128:129], v[130:131] neg_lo:[0,1] neg_hi:[0,1]
	v_pk_add_f32 v[126:127], v[110:111], v[140:141]
	v_pk_add_f32 v[130:131], v[136:137], v[144:145]
	v_pk_add_f32 v[138:139], v[146:147], v[148:149] neg_lo:[0,1] neg_hi:[0,1]
	v_mov_b32_e32 v105, v119
	v_pk_fma_f32 v[124:125], v[142:143], v[58:59], v[124:125] op_sel:[1,1,0] op_sel_hi:[1,0,1] neg_lo:[1,0,0]
	v_pk_add_f32 v[114:115], v[150:151], v[114:115] neg_lo:[0,1] neg_hi:[0,1]
	v_pk_add_f32 v[116:117], v[120:121], v[116:117] neg_lo:[0,1] neg_hi:[0,1]
	v_pk_add_f32 v[134:135], v[126:127], v[130:131]
	v_pk_add_f32 v[126:127], v[126:127], v[130:131] neg_lo:[0,1] neg_hi:[0,1]
	v_pk_add_f32 v[130:131], v[136:137], v[144:145] neg_lo:[0,1] neg_hi:[0,1]
	v_pk_add_f32 v[110:111], v[110:111], v[140:141] neg_lo:[0,1] neg_hi:[0,1]
	v_pk_add_f32 v[140:141], v[138:139], v[106:107]
	v_pk_add_f32 v[142:143], v[18:19], v[108:109]
	v_pk_add_f32 v[18:19], v[18:19], v[108:109] neg_lo:[0,1] neg_hi:[0,1]
	v_pk_add_f32 v[106:107], v[138:139], v[106:107] neg_lo:[0,1] neg_hi:[0,1]
	v_pk_add_f32 v[118:119], v[104:105], v[122:123]
	v_pk_add_f32 v[138:139], v[112:113], v[124:125]
	v_pk_add_f32 v[112:113], v[112:113], v[124:125] neg_lo:[0,1] neg_hi:[0,1]
	v_pk_add_f32 v[104:105], v[104:105], v[122:123] neg_lo:[0,1] neg_hi:[0,1]
	v_pk_add_f32 v[120:121], v[114:115], v[116:117] op_sel:[0,1] op_sel_hi:[1,0] neg_lo:[0,1] neg_hi:[0,1]
	v_pk_add_f32 v[114:115], v[114:115], v[116:117] op_sel:[0,1] op_sel_hi:[1,0]
	v_pk_add_f32 v[136:137], v[110:111], v[130:131] op_sel:[0,1] op_sel_hi:[1,0] neg_lo:[0,1] neg_hi:[0,1]
	v_pk_add_f32 v[110:111], v[110:111], v[130:131] op_sel:[0,1] op_sel_hi:[1,0]
	v_pk_add_f32 v[108:109], v[106:107], v[18:19] op_sel:[0,1] op_sel_hi:[1,0] neg_lo:[0,1] neg_hi:[0,1]
	v_pk_add_f32 v[18:19], v[106:107], v[18:19] op_sel:[0,1] op_sel_hi:[1,0]
	v_pk_add_f32 v[122:123], v[104:105], v[112:113] op_sel:[0,1] op_sel_hi:[1,0] neg_lo:[0,1] neg_hi:[0,1]
	v_pk_add_f32 v[104:105], v[104:105], v[112:113] op_sel:[0,1] op_sel_hi:[1,0]
	v_mov_b32_e32 v116, v120
	v_mov_b32_e32 v117, v115
	v_mov_b32_e32 v130, v136
	v_mov_b32_e32 v131, v111
	v_pk_add_f32 v[144:145], v[140:141], v[142:143]
	v_pk_add_f32 v[140:141], v[140:141], v[142:143] neg_lo:[0,1] neg_hi:[0,1]
	v_mov_b32_e32 v106, v108
	v_mov_b32_e32 v107, v19
	v_pk_add_f32 v[142:143], v[118:119], v[138:139]
	v_pk_add_f32 v[118:119], v[118:119], v[138:139] neg_lo:[0,1] neg_hi:[0,1]
	v_mov_b32_e32 v112, v122
	v_mov_b32_e32 v113, v105
	ds_write2_b64 v1, v[132:133], v[134:135] offset1:34
	ds_write2_b64 v1, v[144:145], v[142:143] offset0:68 offset1:102
	ds_write2_b64 v1, v[116:117], v[130:131] offset0:136 offset1:170
	ds_write2_b64 v1, v[106:107], v[112:113] offset0:204 offset1:238
	ds_write2_b64 v26, v[128:129], v[126:127] offset0:16 offset1:50
	ds_write2_b64 v26, v[140:141], v[118:119] offset0:84 offset1:118
	v_mov_b32_e32 v115, v121
	v_mov_b32_e32 v111, v137
	v_mov_b32_e32 v19, v109
	v_mov_b32_e32 v105, v123
	v_mov_b32_e32 v1, v0
	ds_write2_b64 v26, v[114:115], v[110:111] offset0:152 offset1:186
	ds_write2_b64 v26, v[18:19], v[104:105] offset0:220 offset1:254
	s_waitcnt lgkmcnt(0)
	s_barrier
	s_nop 0
	v_and_b32_e32 v18, 0x1ff, v1
	v_lshlrev_b32_e32 v1, 4, v1
	v_and_or_b32 v1, v1, s29, v18
	v_cvt_f32_u32_e32 v18, v18
	v_ashrrev_i32_e32 v19, 4, v1
	v_lshlrev_b32_e32 v19, 3, v19
	v_lshlrev_b32_e32 v1, 3, v1
	v_add3_u32 v1, 0, v19, v1
	v_mul_f32_e32 v19, 0x39000000, v18
	v_cos_f32_e32 v18, v19
	v_sin_f32_e32 v19, v19
	ds_read_b64 v[104:105], v1
	ds_read_b64 v[106:107], v1 offset:4352
	ds_read_b64 v[108:109], v1 offset:8704
	ds_read_b64 v[110:111], v1 offset:13056
	ds_read_b64 v[112:113], v1 offset:17408
	ds_read_b64 v[114:115], v1 offset:21760
	ds_read_b64 v[116:117], v1 offset:26112
	ds_read_b64 v[118:119], v1 offset:30464
	ds_read_b64 v[120:121], v1 offset:34816
	ds_read_b64 v[122:123], v1 offset:39168
	ds_read_b64 v[124:125], v1 offset:43520
	ds_read_b64 v[126:127], v1 offset:47872
	ds_read_b64 v[128:129], v1 offset:52224
	ds_read_b64 v[130:131], v1 offset:56576
	ds_read_b64 v[132:133], v1 offset:60928
	ds_read_b64 v[134:135], v1 offset:65280
	s_nop 1
	s_nop 0
	v_pk_mul_f32 v[136:137], v[18:19], v[18:19] op_sel:[0,0] op_sel_hi:[0,1]
	s_waitcnt lgkmcnt(14)
	v_pk_mul_f32 v[164:165], v[106:107], v[18:19] op_sel:[0,0] op_sel_hi:[0,1]
	v_pk_fma_f32 v[136:137], v[18:19], v[18:19], v[136:137] op_sel:[1,1,0] op_sel_hi:[1,0,1] neg_lo:[1,0,0]
	s_nop 0
	v_pk_mul_f32 v[140:141], v[136:137], v[136:137] op_sel:[0,0] op_sel_hi:[0,1]
	v_pk_mul_f32 v[138:139], v[136:137], v[18:19] op_sel:[0,0] op_sel_hi:[0,1]
	s_nop 0
	v_pk_fma_f32 v[140:141], v[136:137], v[136:137], v[140:141] op_sel:[1,1,0] op_sel_hi:[1,0,1] neg_lo:[1,0,0]
	v_pk_fma_f32 v[138:139], v[136:137], v[18:19], v[138:139] op_sel:[1,1,0] op_sel_hi:[1,0,1] neg_lo:[1,0,0]
	s_nop 0
	v_pk_mul_f32 v[148:149], v[140:141], v[140:141] op_sel:[0,0] op_sel_hi:[0,1]
	v_pk_mul_f32 v[142:143], v[140:141], v[18:19] op_sel:[0,0] op_sel_hi:[0,1]
	v_pk_mul_f32 v[144:145], v[138:139], v[138:139] op_sel:[0,0] op_sel_hi:[0,1]
	v_pk_mul_f32 v[146:147], v[140:141], v[138:139] op_sel:[0,0] op_sel_hi:[0,1]
	s_nop 0
	v_pk_fma_f32 v[148:149], v[140:141], v[140:141], v[148:149] op_sel:[1,1,0] op_sel_hi:[1,0,1] neg_lo:[1,0,0]
	v_pk_fma_f32 v[142:143], v[140:141], v[18:19], v[142:143] op_sel:[1,1,0] op_sel_hi:[1,0,1] neg_lo:[1,0,0]
	v_pk_fma_f32 v[144:145], v[138:139], v[138:139], v[144:145] op_sel:[1,1,0] op_sel_hi:[1,0,1] neg_lo:[1,0,0]
	v_pk_fma_f32 v[146:147], v[140:141], v[138:139], v[146:147] op_sel:[1,1,0] op_sel_hi:[1,0,1] neg_lo:[1,0,0]
	s_nop 0
	v_pk_mul_f32 v[150:151], v[148:149], v[18:19] op_sel:[0,0] op_sel_hi:[0,1]
	v_pk_mul_f32 v[152:153], v[142:143], v[142:143] op_sel:[0,0] op_sel_hi:[0,1]
	v_pk_mul_f32 v[154:155], v[148:149], v[138:139] op_sel:[0,0] op_sel_hi:[0,1]
	v_pk_mul_f32 v[156:157], v[144:145], v[144:145] op_sel:[0,0] op_sel_hi:[0,1]
	v_pk_mul_f32 v[158:159], v[148:149], v[142:143] op_sel:[0,0] op_sel_hi:[0,1]
	v_pk_mul_f32 v[160:161], v[146:147], v[146:147] op_sel:[0,0] op_sel_hi:[0,1]
	s_nop 0
	v_pk_fma_f32 v[150:151], v[148:149], v[18:19], v[150:151] op_sel:[1,1,0] op_sel_hi:[1,0,1] neg_lo:[1,0,0]
	v_pk_fma_f32 v[18:19], v[106:107], v[18:19], v[164:165] op_sel:[1,1,0] op_sel_hi:[1,0,1] neg_lo:[1,0,0]
	s_waitcnt lgkmcnt(13)
	v_pk_mul_f32 v[106:107], v[108:109], v[136:137] op_sel:[0,0] op_sel_hi:[0,1]
	v_pk_fma_f32 v[152:153], v[142:143], v[142:143], v[152:153] op_sel:[1,1,0] op_sel_hi:[1,0,1] neg_lo:[1,0,0]
	v_pk_fma_f32 v[154:155], v[148:149], v[138:139], v[154:155] op_sel:[1,1,0] op_sel_hi:[1,0,1] neg_lo:[1,0,0]
	v_pk_fma_f32 v[156:157], v[144:145], v[144:145], v[156:157] op_sel:[1,1,0] op_sel_hi:[1,0,1] neg_lo:[1,0,0]
	v_pk_fma_f32 v[158:159], v[148:149], v[142:143], v[158:159] op_sel:[1,1,0] op_sel_hi:[1,0,1] neg_lo:[1,0,0]
	v_pk_fma_f32 v[160:161], v[146:147], v[146:147], v[160:161] op_sel:[1,1,0] op_sel_hi:[1,0,1] neg_lo:[1,0,0]
	s_nop 0
	v_pk_fma_f32 v[106:107], v[108:109], v[136:137], v[106:107] op_sel:[1,1,0] op_sel_hi:[1,0,1] neg_lo:[1,0,0]
	s_waitcnt lgkmcnt(12)
	v_pk_mul_f32 v[108:109], v[110:111], v[138:139] op_sel:[0,0] op_sel_hi:[0,1]
	v_pk_mul_f32 v[162:163], v[148:149], v[146:147] op_sel:[0,0] op_sel_hi:[0,1]
	s_nop 0
	v_pk_fma_f32 v[108:109], v[110:111], v[138:139], v[108:109] op_sel:[1,1,0] op_sel_hi:[1,0,1] neg_lo:[1,0,0]
	s_waitcnt lgkmcnt(11)
	v_pk_mul_f32 v[110:111], v[112:113], v[140:141] op_sel:[0,0] op_sel_hi:[0,1]
	v_pk_fma_f32 v[162:163], v[148:149], v[146:147], v[162:163] op_sel:[1,1,0] op_sel_hi:[1,0,1] neg_lo:[1,0,0]
	s_nop 0
	v_pk_fma_f32 v[110:111], v[112:113], v[140:141], v[110:111] op_sel:[1,1,0] op_sel_hi:[1,0,1] neg_lo:[1,0,0]
	s_waitcnt lgkmcnt(10)
	v_pk_mul_f32 v[112:113], v[114:115], v[142:143] op_sel:[0,0] op_sel_hi:[0,1]
	s_nop 0
	v_pk_fma_f32 v[112:113], v[114:115], v[142:143], v[112:113] op_sel:[1,1,0] op_sel_hi:[1,0,1] neg_lo:[1,0,0]
	s_waitcnt lgkmcnt(9)
	v_pk_mul_f32 v[114:115], v[116:117], v[144:145] op_sel:[0,0] op_sel_hi:[0,1]
	s_nop 0
	v_pk_fma_f32 v[114:115], v[116:117], v[144:145], v[114:115] op_sel:[1,1,0] op_sel_hi:[1,0,1] neg_lo:[1,0,0]
	s_waitcnt lgkmcnt(8)
	v_pk_mul_f32 v[116:117], v[118:119], v[146:147] op_sel:[0,0] op_sel_hi:[0,1]
	s_nop 0
	v_pk_fma_f32 v[116:117], v[118:119], v[146:147], v[116:117] op_sel:[1,1,0] op_sel_hi:[1,0,1] neg_lo:[1,0,0]
	s_waitcnt lgkmcnt(7)
	v_pk_mul_f32 v[118:119], v[120:121], v[148:149] op_sel:[0,0] op_sel_hi:[0,1]
	s_nop 0
	v_pk_fma_f32 v[118:119], v[120:121], v[148:149], v[118:119] op_sel:[1,1,0] op_sel_hi:[1,0,1] neg_lo:[1,0,0]
	s_waitcnt lgkmcnt(6)
	v_pk_mul_f32 v[120:121], v[122:123], v[150:151] op_sel:[0,0] op_sel_hi:[0,1]
	s_nop 0
	v_pk_fma_f32 v[120:121], v[122:123], v[150:151], v[120:121] op_sel:[1,1,0] op_sel_hi:[1,0,1] neg_lo:[1,0,0]
	s_waitcnt lgkmcnt(5)
	v_pk_mul_f32 v[122:123], v[124:125], v[152:153] op_sel:[0,0] op_sel_hi:[0,1]
	s_nop 0
	v_pk_fma_f32 v[122:123], v[124:125], v[152:153], v[122:123] op_sel:[1,1,0] op_sel_hi:[1,0,1] neg_lo:[1,0,0]
	s_waitcnt lgkmcnt(4)
	v_pk_mul_f32 v[124:125], v[126:127], v[154:155] op_sel:[0,0] op_sel_hi:[0,1]
	s_nop 0
	v_pk_fma_f32 v[124:125], v[126:127], v[154:155], v[124:125] op_sel:[1,1,0] op_sel_hi:[1,0,1] neg_lo:[1,0,0]
	s_waitcnt lgkmcnt(3)
	v_pk_mul_f32 v[126:127], v[128:129], v[156:157] op_sel:[0,0] op_sel_hi:[0,1]
	s_nop 0
	v_pk_fma_f32 v[126:127], v[128:129], v[156:157], v[126:127] op_sel:[1,1,0] op_sel_hi:[1,0,1] neg_lo:[1,0,0]
	s_waitcnt lgkmcnt(2)
	v_pk_mul_f32 v[128:129], v[130:131], v[158:159] op_sel:[0,0] op_sel_hi:[0,1]
	s_nop 0
	v_pk_fma_f32 v[128:129], v[130:131], v[158:159], v[128:129] op_sel:[1,1,0] op_sel_hi:[1,0,1] neg_lo:[1,0,0]
	s_waitcnt lgkmcnt(1)
	v_pk_mul_f32 v[130:131], v[132:133], v[160:161] op_sel:[0,0] op_sel_hi:[0,1]
	v_pk_add_f32 v[148:149], v[110:111], v[126:127]
	v_pk_fma_f32 v[130:131], v[132:133], v[160:161], v[130:131] op_sel:[1,1,0] op_sel_hi:[1,0,1] neg_lo:[1,0,0]
	s_waitcnt lgkmcnt(0)
	v_pk_mul_f32 v[132:133], v[134:135], v[162:163] op_sel:[0,0] op_sel_hi:[0,1]
	v_pk_add_f32 v[136:137], v[112:113], v[128:129] neg_lo:[0,1] neg_hi:[0,1]
	v_pk_fma_f32 v[132:133], v[134:135], v[162:163], v[132:133] op_sel:[1,1,0] op_sel_hi:[1,0,1] neg_lo:[1,0,0]
	v_pk_add_f32 v[134:135], v[18:19], v[120:121] neg_lo:[0,1] neg_hi:[0,1]
	v_pk_add_f32 v[140:141], v[114:115], v[130:131] neg_lo:[0,1] neg_hi:[0,1]
	v_pk_add_f32 v[138:139], v[134:135], v[136:137] op_sel:[0,1] op_sel_hi:[1,0] neg_lo:[0,1] neg_hi:[0,1]
	v_pk_add_f32 v[134:135], v[134:135], v[136:137] op_sel:[0,1] op_sel_hi:[1,0]
	v_mov_b32_e32 v136, v138
	v_mov_b32_e32 v137, v135
	v_mov_b32_e32 v135, v139
	v_pk_add_f32 v[138:139], v[106:107], v[122:123] neg_lo:[0,1] neg_hi:[0,1]
	v_pk_add_f32 v[144:145], v[116:117], v[132:133] neg_lo:[0,1] neg_hi:[0,1]
	v_pk_add_f32 v[142:143], v[138:139], v[140:141] op_sel:[0,1] op_sel_hi:[1,0] neg_lo:[0,1] neg_hi:[0,1]
	v_pk_add_f32 v[138:139], v[138:139], v[140:141] op_sel:[0,1] op_sel_hi:[1,0]
	v_mov_b32_e32 v140, v142
	v_mov_b32_e32 v141, v139
	v_mov_b32_e32 v139, v143
	v_pk_add_f32 v[142:143], v[108:109], v[124:125] neg_lo:[0,1] neg_hi:[0,1]
	v_pk_add_f32 v[18:19], v[18:19], v[120:121]
	v_pk_add_f32 v[146:147], v[142:143], v[144:145] op_sel:[0,1] op_sel_hi:[1,0] neg_lo:[0,1] neg_hi:[0,1]
	v_pk_add_f32 v[142:143], v[142:143], v[144:145] op_sel:[0,1] op_sel_hi:[1,0]
	v_pk_add_f32 v[112:113], v[112:113], v[128:129]
	v_mov_b32_e32 v144, v146
	v_mov_b32_e32 v145, v143
	v_mov_b32_e32 v143, v147
	v_pk_mul_f32 v[146:147], v[136:137], v[38:39] op_sel:[0,0] op_sel_hi:[0,1]
	v_pk_add_f32 v[120:121], v[18:19], v[112:113]
	v_pk_add_f32 v[18:19], v[18:19], v[112:113] neg_lo:[0,1] neg_hi:[0,1]
	v_pk_add_f32 v[106:107], v[106:107], v[122:123]
	v_pk_add_f32 v[112:113], v[114:115], v[130:131]
	v_pk_fma_f32 v[136:137], v[136:137], v[38:39], v[146:147] op_sel:[1,1,0] op_sel_hi:[1,0,1] neg_lo:[1,0,0]
	v_pk_mul_f32 v[146:147], v[140:141], v[34:35] op_sel:[0,0] op_sel_hi:[0,1]
	v_pk_add_f32 v[108:109], v[108:109], v[124:125]
	v_pk_add_f32 v[114:115], v[106:107], v[112:113]
	v_pk_add_f32 v[106:107], v[106:107], v[112:113] neg_lo:[0,1] neg_hi:[0,1]
	v_pk_add_f32 v[112:113], v[116:117], v[132:133]
	v_pk_fma_f32 v[140:141], v[140:141], v[34:35], v[146:147] op_sel:[1,1,0] op_sel_hi:[1,0,1] neg_lo:[1,0,0]
	v_pk_mul_f32 v[146:147], v[144:145], v[20:21] op_sel:[0,0] op_sel_hi:[0,1]
	v_pk_add_f32 v[110:111], v[110:111], v[126:127] neg_lo:[0,1] neg_hi:[0,1]
	v_pk_add_f32 v[116:117], v[108:109], v[112:113]
	v_pk_add_f32 v[108:109], v[108:109], v[112:113] neg_lo:[0,1] neg_hi:[0,1]
	v_pk_mul_f32 v[112:113], v[18:19], v[34:35] op_sel:[0,0] op_sel_hi:[0,1]
	v_pk_fma_f32 v[144:145], v[144:145], v[20:21], v[146:147] op_sel:[1,1,0] op_sel_hi:[1,0,1] neg_lo:[1,0,0]
	v_pk_add_f32 v[146:147], v[104:105], v[118:119]
	v_pk_fma_f32 v[18:19], v[18:19], v[34:35], v[112:113] op_sel:[1,1,0] op_sel_hi:[1,0,1] neg_lo:[1,0,0]
	v_pk_mul_f32 v[112:113], v[106:107], v[46:47] op_sel:[0,0] op_sel_hi:[0,1]
	v_pk_add_f32 v[104:105], v[104:105], v[118:119] neg_lo:[0,1] neg_hi:[0,1]
	v_pk_add_f32 v[150:151], v[146:147], v[148:149]
	v_pk_fma_f32 v[106:107], v[106:107], v[46:47], v[112:113] op_sel:[1,1,0] op_sel_hi:[1,0,1] neg_lo:[1,0,0]
	v_pk_mul_f32 v[112:113], v[108:109], v[48:49] op_sel:[0,0] op_sel_hi:[0,1]
	v_pk_add_f32 v[118:119], v[104:105], v[110:111] op_sel:[0,1] op_sel_hi:[1,0] neg_lo:[0,1] neg_hi:[0,1]
	v_pk_add_f32 v[104:105], v[104:105], v[110:111] op_sel:[0,1] op_sel_hi:[1,0]
	v_pk_fma_f32 v[108:109], v[108:109], v[48:49], v[112:113] op_sel:[1,1,0] op_sel_hi:[1,0,1] neg_lo:[1,0,0]
	v_pk_mul_f32 v[112:113], v[134:135], v[20:21] op_sel:[0,0] op_sel_hi:[0,1]
	v_pk_mul_f32 v[122:123], v[138:139], v[48:49] op_sel:[0,0] op_sel_hi:[0,1]
	v_pk_add_f32 v[128:129], v[150:151], v[114:115]
	v_pk_add_f32 v[130:131], v[120:121], v[116:117]
	v_mov_b32_e32 v110, v118
	v_mov_b32_e32 v111, v105
	v_pk_fma_f32 v[112:113], v[134:135], v[20:21], v[112:113] op_sel:[1,1,0] op_sel_hi:[1,0,1] neg_lo:[1,0,0]
	v_pk_fma_f32 v[122:123], v[138:139], v[48:49], v[122:123] op_sel:[1,1,0] op_sel_hi:[1,0,1] neg_lo:[1,0,0]
	v_pk_mul_f32 v[124:125], v[142:143], v[58:59] op_sel:[0,0] op_sel_hi:[0,1]
	v_pk_add_f32 v[132:133], v[128:129], v[130:131]
	v_pk_add_f32 v[128:129], v[128:129], v[130:131] neg_lo:[0,1] neg_hi:[0,1]
	v_pk_add_f32 v[126:127], v[110:111], v[140:141]
	v_pk_add_f32 v[130:131], v[136:137], v[144:145]
	v_pk_add_f32 v[138:139], v[146:147], v[148:149] neg_lo:[0,1] neg_hi:[0,1]
	v_mov_b32_e32 v105, v119
	v_pk_fma_f32 v[124:125], v[142:143], v[58:59], v[124:125] op_sel:[1,1,0] op_sel_hi:[1,0,1] neg_lo:[1,0,0]
	v_pk_add_f32 v[114:115], v[150:151], v[114:115] neg_lo:[0,1] neg_hi:[0,1]
	v_pk_add_f32 v[116:117], v[120:121], v[116:117] neg_lo:[0,1] neg_hi:[0,1]
	v_pk_add_f32 v[134:135], v[126:127], v[130:131]
	v_pk_add_f32 v[126:127], v[126:127], v[130:131] neg_lo:[0,1] neg_hi:[0,1]
	v_pk_add_f32 v[130:131], v[136:137], v[144:145] neg_lo:[0,1] neg_hi:[0,1]
	v_pk_add_f32 v[110:111], v[110:111], v[140:141] neg_lo:[0,1] neg_hi:[0,1]
	v_pk_add_f32 v[140:141], v[138:139], v[106:107]
	v_pk_add_f32 v[142:143], v[18:19], v[108:109]
	v_pk_add_f32 v[18:19], v[18:19], v[108:109] neg_lo:[0,1] neg_hi:[0,1]
	v_pk_add_f32 v[106:107], v[138:139], v[106:107] neg_lo:[0,1] neg_hi:[0,1]
	v_pk_add_f32 v[118:119], v[104:105], v[122:123]
	v_pk_add_f32 v[138:139], v[112:113], v[124:125]
	v_pk_add_f32 v[112:113], v[112:113], v[124:125] neg_lo:[0,1] neg_hi:[0,1]
	v_pk_add_f32 v[104:105], v[104:105], v[122:123] neg_lo:[0,1] neg_hi:[0,1]
	v_pk_add_f32 v[120:121], v[114:115], v[116:117] op_sel:[0,1] op_sel_hi:[1,0] neg_lo:[0,1] neg_hi:[0,1]
	v_pk_add_f32 v[114:115], v[114:115], v[116:117] op_sel:[0,1] op_sel_hi:[1,0]
	v_pk_add_f32 v[136:137], v[110:111], v[130:131] op_sel:[0,1] op_sel_hi:[1,0] neg_lo:[0,1] neg_hi:[0,1]
	v_pk_add_f32 v[110:111], v[110:111], v[130:131] op_sel:[0,1] op_sel_hi:[1,0]
	v_pk_add_f32 v[108:109], v[106:107], v[18:19] op_sel:[0,1] op_sel_hi:[1,0] neg_lo:[0,1] neg_hi:[0,1]
	v_pk_add_f32 v[18:19], v[106:107], v[18:19] op_sel:[0,1] op_sel_hi:[1,0]
	v_pk_add_f32 v[122:123], v[104:105], v[112:113] op_sel:[0,1] op_sel_hi:[1,0] neg_lo:[0,1] neg_hi:[0,1]
	v_pk_add_f32 v[104:105], v[104:105], v[112:113] op_sel:[0,1] op_sel_hi:[1,0]
	v_mov_b32_e32 v117, v115
	v_mov_b32_e32 v131, v111
	v_mov_b32_e32 v107, v19
	v_mov_b32_e32 v113, v105
	v_mov_b32_e32 v115, v121
	v_mov_b32_e32 v111, v137
	v_mov_b32_e32 v19, v109
	v_mov_b32_e32 v105, v123
	v_mov_b32_e32 v116, v120
	v_mov_b32_e32 v130, v136
	v_pk_add_f32 v[144:145], v[140:141], v[142:143]
	v_pk_add_f32 v[140:141], v[140:141], v[142:143] neg_lo:[0,1] neg_hi:[0,1]
	v_mov_b32_e32 v106, v108
	v_pk_add_f32 v[142:143], v[118:119], v[138:139]
	v_pk_add_f32 v[118:119], v[118:119], v[138:139] neg_lo:[0,1] neg_hi:[0,1]
	v_mov_b32_e32 v112, v122
	ds_write_b64 v1, v[132:133]
	ds_write_b64 v1, v[134:135] offset:4352
	ds_write_b64 v1, v[144:145] offset:8704
	ds_write_b64 v1, v[142:143] offset:13056
	ds_write_b64 v1, v[116:117] offset:17408
	ds_write_b64 v1, v[130:131] offset:21760
	ds_write_b64 v1, v[106:107] offset:26112
	ds_write_b64 v1, v[112:113] offset:30464
	ds_write_b64 v1, v[128:129] offset:34816
	ds_write_b64 v1, v[126:127] offset:39168
	ds_write_b64 v1, v[140:141] offset:43520
	ds_write_b64 v1, v[118:119] offset:47872
	ds_write_b64 v1, v[114:115] offset:52224
	ds_write_b64 v1, v[110:111] offset:56576
	ds_write_b64 v1, v[18:19] offset:60928
	ds_write_b64 v1, v[104:105] offset:65280
	v_mov_b32_e32 v1, v0
	s_waitcnt lgkmcnt(0)
	s_barrier
	v_pk_mul_f32 v[18:19], v[84:85], v[62:63] op_sel_hi:[0,1]
	v_lshlrev_b32_e32 v26, 2, v1
	v_and_b32_e32 v26, -8, v26
	v_lshlrev_b32_e32 v1, 6, v1
	v_add3_u32 v1, 0, v26, v1
	ds_read2_b64 v[104:107], v1 offset1:1
	ds_read2_b64 v[108:111], v1 offset0:2 offset1:3
	v_lshlrev_b32_e32 v63, 16, v14
	v_lshlrev_b32_e32 v62, 16, v10
	v_mov_b32_e32 v26, v83
	v_and_b32_e32 v113, 0xffff0000, v14
	v_and_b32_e32 v112, 0xffff0000, v10
	v_pk_fma_f32 v[18:19], v[26:27], v[62:63], v[18:19] op_sel_hi:[0,1,1]
	v_pk_fma_f32 v[18:19], v[82:83], v[112:113], v[18:19] op_sel_hi:[0,1,1]
	v_pk_add_f32 v[18:19], v[80:81], v[18:19] op_sel_hi:[0,1]
	s_waitcnt lgkmcnt(1)
	v_pk_fma_f32 v[100:101], v[78:79], v[100:101], v[104:105] op_sel_hi:[0,1,1]
	v_pk_mul_f32 v[104:105], v[26:27], v[112:113] op_sel_hi:[0,1]
	v_pk_mul_f32 v[18:19], v[18:19], v[100:101]
	v_lshlrev_b32_e32 v101, 16, v15
	v_lshlrev_b32_e32 v100, 16, v11
	v_pk_fma_f32 v[62:63], v[84:85], v[62:63], v[104:105] op_sel_hi:[0,1,1]
	v_pk_fma_f32 v[62:63], v[82:83], v[100:101], v[62:63] op_sel_hi:[0,1,1]
	v_pk_add_f32 v[62:63], v[80:81], v[62:63] op_sel_hi:[0,1]
	v_pk_fma_f32 v[102:103], v[78:79], v[102:103], v[106:107] op_sel_hi:[0,1,1]
	v_pk_mul_f32 v[62:63], v[62:63], v[102:103]
	v_and_b32_e32 v102, 0xffff0000, v11
	v_pk_mul_f32 v[10:11], v[26:27], v[100:101] op_sel_hi:[0,1]
	v_and_b32_e32 v103, 0xffff0000, v15
	v_pk_fma_f32 v[10:11], v[84:85], v[112:113], v[10:11] op_sel_hi:[0,1,1]
	v_pk_fma_f32 v[10:11], v[82:83], v[102:103], v[10:11] op_sel_hi:[0,1,1]
	v_pk_add_f32 v[10:11], v[80:81], v[10:11] op_sel_hi:[0,1]
	s_waitcnt lgkmcnt(0)
	v_pk_fma_f32 v[14:15], v[78:79], v[98:99], v[108:109] op_sel_hi:[0,1,1]
	v_pk_mul_f32 v[10:11], v[10:11], v[14:15]
	v_pk_mul_f32 v[14:15], v[26:27], v[102:103] op_sel_hi:[0,1]
	v_lshlrev_b32_e32 v105, 16, v16
	v_lshlrev_b32_e32 v104, 16, v12
	v_pk_fma_f32 v[14:15], v[84:85], v[100:101], v[14:15] op_sel_hi:[0,1,1]
	v_pk_fma_f32 v[14:15], v[82:83], v[104:105], v[14:15] op_sel_hi:[0,1,1]
	v_pk_add_f32 v[14:15], v[80:81], v[14:15] op_sel_hi:[0,1]
	v_pk_fma_f32 v[96:97], v[78:79], v[96:97], v[110:111] op_sel_hi:[0,1,1]
	v_add_u32_e32 v28, 0x8800, v1
	v_pk_mul_f32 v[14:15], v[14:15], v[96:97]
	ds_write2_b64 v1, v[18:19], v[62:63] offset1:1
	ds_write2_b64 v28, v[88:89], v[90:91] offset1:1
	v_add_u32_e32 v28, 0x8810, v1
	ds_write2_b64 v1, v[10:11], v[14:15] offset0:2 offset1:3
	ds_write2_b64 v28, v[88:89], v[90:91] offset1:1
	ds_read2_b64 v[96:99], v1 offset0:4 offset1:5
	v_pk_mul_f32 v[100:101], v[26:27], v[104:105] op_sel_hi:[0,1]
	v_and_b32_e32 v107, 0xffff0000, v16
	v_and_b32_e32 v106, 0xffff0000, v12
	v_pk_fma_f32 v[100:101], v[84:85], v[102:103], v[100:101] op_sel_hi:[0,1,1]
	v_pk_fma_f32 v[100:101], v[82:83], v[106:107], v[100:101] op_sel_hi:[0,1,1]
	v_pk_add_f32 v[108:109], v[80:81], v[100:101] op_sel_hi:[0,1]
	ds_read2_b64 v[100:103], v1 offset0:6 offset1:7
	s_waitcnt lgkmcnt(1)
	v_pk_fma_f32 v[94:95], v[78:79], v[94:95], v[96:97] op_sel_hi:[0,1,1]
	v_pk_mul_f32 v[94:95], v[108:109], v[94:95]
	v_pk_mul_f32 v[108:109], v[26:27], v[106:107] op_sel_hi:[0,1]
	v_lshlrev_b32_e32 v97, 16, v17
	v_lshlrev_b32_e32 v96, 16, v13
	v_pk_fma_f32 v[104:105], v[84:85], v[104:105], v[108:109] op_sel_hi:[0,1,1]
	v_pk_fma_f32 v[104:105], v[82:83], v[96:97], v[104:105] op_sel_hi:[0,1,1]
	v_pk_add_f32 v[104:105], v[80:81], v[104:105] op_sel_hi:[0,1]
	v_pk_fma_f32 v[92:93], v[78:79], v[92:93], v[98:99] op_sel_hi:[0,1,1]
	v_add_u32_e32 v12, 0x8820, v1
	v_pk_mul_f32 v[92:93], v[104:105], v[92:93]
	ds_write2_b64 v1, v[94:95], v[92:93] offset0:4 offset1:5
	ds_write2_b64 v12, v[88:89], v[90:91] offset1:1
	v_and_b32_e32 v16, 0xffff0000, v13
	v_pk_mul_f32 v[12:13], v[26:27], v[96:97] op_sel_hi:[0,1]
	v_and_b32_e32 v17, 0xffff0000, v17
	v_pk_fma_f32 v[12:13], v[84:85], v[106:107], v[12:13] op_sel_hi:[0,1,1]
	v_pk_fma_f32 v[12:13], v[82:83], v[16:17], v[12:13] op_sel_hi:[0,1,1]
	v_pk_mul_f32 v[16:17], v[26:27], v[16:17] op_sel_hi:[0,1]
	v_pk_fma_f32 v[16:17], v[84:85], v[96:97], v[16:17] op_sel_hi:[0,1,1]
	v_pk_fma_f32 v[16:17], v[82:83], v[60:61], v[16:17] op_sel_hi:[0,1,1]
	v_pk_add_f32 v[16:17], v[80:81], v[16:17] op_sel_hi:[0,1]
	s_waitcnt lgkmcnt(2)
	v_pk_fma_f32 v[60:61], v[78:79], v[64:65], v[102:103] op_sel_hi:[0,1,1]
	v_pk_mul_f32 v[16:17], v[16:17], v[60:61]
	v_lshl_add_u64 v[60:61], v[66:67], 0, s[4:5]
	v_add_co_u32_e32 v96, vcc, s3, v60
	v_pk_add_f32 v[12:13], v[80:81], v[12:13] op_sel_hi:[0,1]
	s_nop 0
	v_addc_co_u32_e32 v97, vcc, 0, v61, vcc
	v_add_co_u32_e32 v64, vcc, s22, v60
	v_pk_fma_f32 v[86:87], v[78:79], v[86:87], v[100:101] op_sel_hi:[0,1,1]
	s_nop 0
	v_addc_co_u32_e32 v65, vcc, 0, v61, vcc
	v_add_co_u32_e32 v98, vcc, s23, v60
	v_pk_mul_f32 v[12:13], v[12:13], v[86:87]
	s_nop 0
	v_addc_co_u32_e32 v99, vcc, 0, v61, vcc
	v_add_u32_e32 v28, 0x8830, v1
	ds_write2_b64 v1, v[12:13], v[16:17] offset0:6 offset1:7
	ds_write2_b64 v28, v[88:89], v[90:91] offset1:1
	v_add_co_u32_e32 v102, vcc, s89, v60
	v_mov_b32_e32 v1, v0
	s_waitcnt lgkmcnt(0)
	s_barrier
	global_load_dwordx2 v[90:91], v[64:65], off offset:-4096
	global_load_dwordx2 v[88:89], v[64:65], off
	global_load_dwordx2 v[86:87], v[98:99], off offset:-4096
	s_nop 0
	global_load_dwordx2 v[64:65], v[98:99], off
	v_addc_co_u32_e32 v103, vcc, 0, v61, vcc
	global_load_dwordx2 v[100:101], v[60:61], off
	global_load_dwordx2 v[98:99], v[96:97], off offset:-4096
	s_nop 0
	global_load_dwordx2 v[96:97], v[96:97], off
	s_nop 0
	global_load_dwordx2 v[60:61], v[102:103], off
	s_nop 0
	v_and_b32_e32 v26, 0x1ff, v1
	v_lshlrev_b32_e32 v1, 4, v1
	v_and_or_b32 v1, v1, s29, v26
	v_ashrrev_i32_e32 v28, 4, v1
	v_lshlrev_b32_e32 v28, 3, v28
	v_lshlrev_b32_e32 v1, 3, v1
	v_add3_u32 v1, 0, v28, v1
	ds_read_b64 v[104:105], v1
	ds_read_b64 v[106:107], v1 offset:4352
	ds_read_b64 v[108:109], v1 offset:8704
	ds_read_b64 v[110:111], v1 offset:13056
	ds_read_b64 v[112:113], v1 offset:17408
	ds_read_b64 v[114:115], v1 offset:21760
	ds_read_b64 v[116:117], v1 offset:26112
	ds_read_b64 v[118:119], v1 offset:30464
	ds_read_b64 v[120:121], v1 offset:34816
	ds_read_b64 v[122:123], v1 offset:39168
	ds_read_b64 v[124:125], v1 offset:43520
	ds_read_b64 v[126:127], v1 offset:47872
	ds_read_b64 v[128:129], v1 offset:56576
	ds_read_b64 v[130:131], v1 offset:60928
	ds_read_b64 v[132:133], v1 offset:65280
	ds_read_b64 v[134:135], v1 offset:52224
	s_waitcnt lgkmcnt(6)
	v_pk_add_f32 v[136:137], v[106:107], v[122:123] neg_lo:[0,1] neg_hi:[0,1]
	s_waitcnt lgkmcnt(3)
	v_pk_add_f32 v[138:139], v[114:115], v[128:129] neg_lo:[0,1] neg_hi:[0,1]
	s_waitcnt lgkmcnt(2)
	v_pk_add_f32 v[142:143], v[116:117], v[130:131] neg_lo:[0,1] neg_hi:[0,1]
	v_pk_add_f32 v[140:141], v[136:137], v[138:139] op_sel:[0,1] op_sel_hi:[1,0]
	v_pk_add_f32 v[136:137], v[136:137], v[138:139] op_sel:[0,1] op_sel_hi:[1,0] neg_lo:[0,1] neg_hi:[0,1]
	v_mov_b32_e32 v138, v140
	v_mov_b32_e32 v139, v137
	v_mov_b32_e32 v137, v141
	v_pk_add_f32 v[140:141], v[108:109], v[124:125] neg_lo:[0,1] neg_hi:[0,1]
	s_waitcnt lgkmcnt(1)
	v_pk_add_f32 v[146:147], v[118:119], v[132:133] neg_lo:[0,1] neg_hi:[0,1]
	v_pk_add_f32 v[144:145], v[140:141], v[142:143] op_sel:[0,1] op_sel_hi:[1,0]
	v_pk_add_f32 v[140:141], v[140:141], v[142:143] op_sel:[0,1] op_sel_hi:[1,0] neg_lo:[0,1] neg_hi:[0,1]
	v_mov_b32_e32 v142, v144
	v_mov_b32_e32 v143, v141
	v_mov_b32_e32 v141, v145
	v_pk_add_f32 v[144:145], v[110:111], v[126:127] neg_lo:[0,1] neg_hi:[0,1]
	v_pk_add_f32 v[106:107], v[106:107], v[122:123]
	v_pk_add_f32 v[114:115], v[114:115], v[128:129]
	v_pk_add_f32 v[148:149], v[144:145], v[146:147] op_sel:[0,1] op_sel_hi:[1,0]
	v_pk_add_f32 v[144:145], v[144:145], v[146:147] op_sel:[0,1] op_sel_hi:[1,0] neg_lo:[0,1] neg_hi:[0,1]
	v_pk_add_f32 v[122:123], v[106:107], v[114:115]
	v_pk_add_f32 v[106:107], v[106:107], v[114:115] neg_lo:[0,1] neg_hi:[0,1]
	v_pk_add_f32 v[108:109], v[108:109], v[124:125]
	v_pk_add_f32 v[114:115], v[116:117], v[130:131]
	v_mov_b32_e32 v146, v148
	v_mov_b32_e32 v147, v145
	v_mov_b32_e32 v145, v149
	v_pk_mul_f32 v[148:149], v[138:139], v[40:41] op_sel:[0,0] op_sel_hi:[0,1]
	v_pk_add_f32 v[116:117], v[108:109], v[114:115]
	v_pk_add_f32 v[108:109], v[108:109], v[114:115] neg_lo:[0,1] neg_hi:[0,1]
	v_pk_add_f32 v[110:111], v[110:111], v[126:127]
	v_pk_add_f32 v[114:115], v[118:119], v[132:133]
	v_cvt_f32_u32_e32 v26, v26
	v_pk_fma_f32 v[138:139], v[138:139], v[40:41], v[148:149] op_sel:[1,1,0] op_sel_hi:[1,0,1] neg_lo:[1,0,0]
	v_pk_mul_f32 v[148:149], v[142:143], v[24:25] op_sel:[0,0] op_sel_hi:[0,1]
	v_pk_add_f32 v[118:119], v[110:111], v[114:115]
	v_pk_add_f32 v[110:111], v[110:111], v[114:115] neg_lo:[0,1] neg_hi:[0,1]
	v_pk_mul_f32 v[114:115], v[106:107], v[24:25] op_sel:[0,0] op_sel_hi:[0,1]
	v_pk_fma_f32 v[142:143], v[142:143], v[24:25], v[148:149] op_sel:[1,1,0] op_sel_hi:[1,0,1] neg_lo:[1,0,0]
	v_pk_mul_f32 v[148:149], v[146:147], v[22:23] op_sel:[0,0] op_sel_hi:[0,1]
	s_waitcnt lgkmcnt(0)
	v_pk_add_f32 v[150:151], v[112:113], v[134:135]
	v_pk_fma_f32 v[106:107], v[106:107], v[24:25], v[114:115] op_sel:[1,1,0] op_sel_hi:[1,0,1] neg_lo:[1,0,0]
	v_pk_mul_f32 v[114:115], v[108:109], v[42:43] op_sel:[0,0] op_sel_hi:[0,1]
	v_pk_fma_f32 v[146:147], v[146:147], v[22:23], v[148:149] op_sel:[1,1,0] op_sel_hi:[1,0,1] neg_lo:[1,0,0]
	v_pk_add_f32 v[148:149], v[104:105], v[120:121]
	v_pk_fma_f32 v[108:109], v[108:109], v[42:43], v[114:115] op_sel:[1,1,0] op_sel_hi:[1,0,1] neg_lo:[1,0,0]
	v_pk_mul_f32 v[114:115], v[110:111], v[36:37] op_sel:[0,0] op_sel_hi:[0,1]
	v_pk_add_f32 v[104:105], v[104:105], v[120:121] neg_lo:[0,1] neg_hi:[0,1]
	v_pk_add_f32 v[112:113], v[112:113], v[134:135] neg_lo:[0,1] neg_hi:[0,1]
	v_pk_fma_f32 v[110:111], v[110:111], v[36:37], v[114:115] op_sel:[1,1,0] op_sel_hi:[1,0,1] neg_lo:[1,0,0]
	v_pk_mul_f32 v[114:115], v[136:137], v[22:23] op_sel:[0,0] op_sel_hi:[0,1]
	v_mul_f32_e32 v26, 0x39000000, v26
	v_pk_add_f32 v[120:121], v[104:105], v[112:113] op_sel:[0,1] op_sel_hi:[1,0] neg_lo:[0,1] neg_hi:[0,1]
	v_pk_add_f32 v[104:105], v[104:105], v[112:113] op_sel:[0,1] op_sel_hi:[1,0]
	v_pk_fma_f32 v[114:115], v[136:137], v[22:23], v[114:115] op_sel:[1,1,0] op_sel_hi:[1,0,1] neg_lo:[1,0,0]
	v_pk_mul_f32 v[124:125], v[140:141], v[36:37] op_sel:[0,0] op_sel_hi:[0,1]
	v_pk_mul_f32 v[126:127], v[144:145], v[44:45] op_sel:[0,0] op_sel_hi:[0,1]
	v_mov_b32_e32 v112, v120
	v_mov_b32_e32 v113, v105
	v_mov_b32_e32 v105, v121
	v_cos_f32_e32 v102, v26
	v_sin_f32_e32 v26, v26
	v_pk_add_f32 v[152:153], v[148:149], v[150:151]
	v_pk_fma_f32 v[124:125], v[140:141], v[36:37], v[124:125] op_sel:[1,1,0] op_sel_hi:[1,0,1] neg_lo:[1,0,0]
	v_pk_fma_f32 v[126:127], v[144:145], v[44:45], v[126:127] op_sel:[1,1,0] op_sel_hi:[1,0,1] neg_lo:[1,0,0]
	v_pk_add_f32 v[120:121], v[104:105], v[142:143] neg_lo:[0,1] neg_hi:[0,1]
	v_pk_add_f32 v[104:105], v[104:105], v[142:143]
	v_pk_add_f32 v[142:143], v[112:113], v[124:125] neg_lo:[0,1] neg_hi:[0,1]
	v_pk_add_f32 v[144:145], v[114:115], v[126:127] neg_lo:[0,1] neg_hi:[0,1]
	v_pk_add_f32 v[114:115], v[114:115], v[126:127]
	v_pk_add_f32 v[112:113], v[112:113], v[124:125]
	v_pk_add_f32 v[128:129], v[152:153], v[116:117]
	v_pk_add_f32 v[130:131], v[122:123], v[118:119]
	v_pk_add_f32 v[124:125], v[112:113], v[114:115]
	v_pk_add_f32 v[112:113], v[112:113], v[114:115] neg_lo:[0,1] neg_hi:[0,1]
	v_pk_add_f32 v[114:115], v[142:143], v[144:145] op_sel:[0,1] op_sel_hi:[1,0]
	v_pk_add_f32 v[126:127], v[142:143], v[144:145] op_sel:[0,1] op_sel_hi:[1,0] neg_lo:[0,1] neg_hi:[0,1]
	s_nop 1
	v_pk_add_f32 v[132:133], v[128:129], v[130:131]
	v_xor_b32_e32 v103, 0x80000000, v26
	v_pk_mul_f32 v[144:145], v[102:103], v[102:103] op_sel:[0,0] op_sel_hi:[0,1]
	v_pk_add_f32 v[128:129], v[128:129], v[130:131] neg_lo:[0,1] neg_hi:[0,1]
	v_pk_add_f32 v[130:131], v[148:149], v[150:151] neg_lo:[0,1] neg_hi:[0,1]
	v_pk_fma_f32 v[144:145], v[102:103], v[102:103], v[144:145] op_sel:[1,1,0] op_sel_hi:[1,0,1] neg_lo:[1,0,0]
	v_pk_add_f32 v[116:117], v[152:153], v[116:117] neg_lo:[0,1] neg_hi:[0,1]
	v_pk_mul_f32 v[148:149], v[144:145], v[144:145] op_sel:[0,0] op_sel_hi:[0,1]
	v_pk_add_f32 v[118:119], v[122:123], v[118:119] neg_lo:[0,1] neg_hi:[0,1]
	v_pk_fma_f32 v[148:149], v[144:145], v[144:145], v[148:149] op_sel:[1,1,0] op_sel_hi:[1,0,1] neg_lo:[1,0,0]
	v_pk_add_f32 v[136:137], v[130:131], v[108:109] neg_lo:[0,1] neg_hi:[0,1]
	v_pk_mul_f32 v[156:157], v[148:149], v[148:149] op_sel:[0,0] op_sel_hi:[0,1]
	v_pk_add_f32 v[122:123], v[116:117], v[118:119] op_sel:[0,1] op_sel_hi:[1,0]
	v_pk_add_f32 v[116:117], v[116:117], v[118:119] op_sel:[0,1] op_sel_hi:[1,0] neg_lo:[0,1] neg_hi:[0,1]
	v_pk_add_f32 v[140:141], v[106:107], v[110:111] neg_lo:[0,1] neg_hi:[0,1]
	v_pk_add_f32 v[106:107], v[106:107], v[110:111]
	v_pk_add_f32 v[108:109], v[130:131], v[108:109]
	v_pk_add_f32 v[134:135], v[138:139], v[146:147] neg_lo:[0,1] neg_hi:[0,1]
	v_pk_add_f32 v[138:139], v[138:139], v[146:147]
	v_pk_mul_f32 v[146:147], v[144:145], v[102:103] op_sel:[0,0] op_sel_hi:[0,1]
	v_pk_mul_f32 v[150:151], v[148:149], v[102:103] op_sel:[0,0] op_sel_hi:[0,1]
	v_pk_fma_f32 v[156:157], v[148:149], v[148:149], v[156:157] op_sel:[1,1,0] op_sel_hi:[1,0,1] neg_lo:[1,0,0]
	v_mov_b32_e32 v118, v116
	v_pk_mul_f32 v[158:159], v[156:157], v[102:103] op_sel:[0,0] op_sel_hi:[0,1]
	v_mov_b32_e32 v119, v123
	v_pk_add_f32 v[110:111], v[108:109], v[106:107]
	v_pk_add_f32 v[106:107], v[108:109], v[106:107] neg_lo:[0,1] neg_hi:[0,1]
	v_pk_add_f32 v[108:109], v[136:137], v[140:141] op_sel:[0,1] op_sel_hi:[1,0]
	v_pk_add_f32 v[130:131], v[136:137], v[140:141] op_sel:[0,1] op_sel_hi:[1,0] neg_lo:[0,1] neg_hi:[0,1]
	v_pk_add_f32 v[140:141], v[104:105], v[138:139]
	v_pk_add_f32 v[104:105], v[104:105], v[138:139] neg_lo:[0,1] neg_hi:[0,1]
	v_mov_b32_e32 v142, v126
	v_mov_b32_e32 v143, v115
	v_pk_fma_f32 v[146:147], v[144:145], v[102:103], v[146:147] op_sel:[1,1,0] op_sel_hi:[1,0,1] neg_lo:[1,0,0]
	v_pk_fma_f32 v[150:151], v[148:149], v[102:103], v[150:151] op_sel:[1,1,0] op_sel_hi:[1,0,1] neg_lo:[1,0,0]
	v_pk_fma_f32 v[158:159], v[156:157], v[102:103], v[158:159] op_sel:[1,1,0] op_sel_hi:[1,0,1] neg_lo:[1,0,0]
	v_mov_b32_e32 v123, v117
	v_pk_mul_f32 v[152:153], v[146:147], v[146:147] op_sel:[0,0] op_sel_hi:[0,1]
	v_pk_mul_f32 v[160:161], v[150:151], v[150:151] op_sel:[0,0] op_sel_hi:[0,1]
	v_pk_mul_f32 v[116:117], v[122:123], v[148:149] op_sel:[0,0] op_sel_hi:[0,1]
	v_mov_b32_e32 v115, v127
	v_pk_mul_f32 v[126:127], v[104:105], v[158:159] op_sel:[0,0] op_sel_hi:[0,1]
	v_mov_b32_e32 v137, v109
	v_pk_fma_f32 v[152:153], v[146:147], v[146:147], v[152:153] op_sel:[1,1,0] op_sel_hi:[1,0,1] neg_lo:[1,0,0]
	v_pk_mul_f32 v[154:155], v[148:149], v[146:147] op_sel:[0,0] op_sel_hi:[0,1]
	v_pk_fma_f32 v[160:161], v[150:151], v[150:151], v[160:161] op_sel:[1,1,0] op_sel_hi:[1,0,1] neg_lo:[1,0,0]
	v_pk_mul_f32 v[162:163], v[156:157], v[146:147] op_sel:[0,0] op_sel_hi:[0,1]
	v_pk_fma_f32 v[116:117], v[122:123], v[148:149], v[116:117] op_sel:[1,1,0] op_sel_hi:[1,0,1] neg_lo:[1,0,0]
	v_mov_b32_e32 v109, v131
	v_pk_mul_f32 v[122:123], v[108:109], v[152:153] op_sel:[0,0] op_sel_hi:[0,1]
	v_pk_fma_f32 v[104:105], v[104:105], v[158:159], v[126:127] op_sel:[1,1,0] op_sel_hi:[1,0,1] neg_lo:[1,0,0]
	v_pk_mul_f32 v[126:127], v[106:107], v[160:161] op_sel:[0,0] op_sel_hi:[0,1]
	v_pk_fma_f32 v[154:155], v[148:149], v[146:147], v[154:155] op_sel:[1,1,0] op_sel_hi:[1,0,1] neg_lo:[1,0,0]
	v_pk_fma_f32 v[162:163], v[156:157], v[146:147], v[162:163] op_sel:[1,1,0] op_sel_hi:[1,0,1] neg_lo:[1,0,0]
	v_pk_mul_f32 v[164:165], v[152:153], v[152:153] op_sel:[0,0] op_sel_hi:[0,1]
	s_nop 0
	v_pk_fma_f32 v[108:109], v[108:109], v[152:153], v[122:123] op_sel:[1,1,0] op_sel_hi:[1,0,1] neg_lo:[1,0,0]
	v_pk_add_f32 v[138:139], v[120:121], v[134:135] op_sel:[0,1] op_sel_hi:[1,0]
	v_pk_mul_f32 v[122:123], v[114:115], v[154:155] op_sel:[0,0] op_sel_hi:[0,1]
	v_pk_fma_f32 v[106:107], v[106:107], v[160:161], v[126:127] op_sel:[1,1,0] op_sel_hi:[1,0,1] neg_lo:[1,0,0]
	v_pk_mul_f32 v[126:127], v[112:113], v[162:163] op_sel:[0,0] op_sel_hi:[0,1]
	v_pk_add_f32 v[120:121], v[120:121], v[134:135] op_sel:[0,1] op_sel_hi:[1,0] neg_lo:[0,1] neg_hi:[0,1]
	v_pk_fma_f32 v[164:165], v[152:153], v[152:153], v[164:165] op_sel:[1,1,0] op_sel_hi:[1,0,1] neg_lo:[1,0,0]
	v_pk_mul_f32 v[166:167], v[156:157], v[150:151] op_sel:[0,0] op_sel_hi:[0,1]
	v_pk_mul_f32 v[168:169], v[154:155], v[154:155] op_sel:[0,0] op_sel_hi:[0,1]
	v_pk_mul_f32 v[170:171], v[156:157], v[154:155] op_sel:[0,0] op_sel_hi:[0,1]
	v_pk_fma_f32 v[114:115], v[114:115], v[154:155], v[122:123] op_sel:[1,1,0] op_sel_hi:[1,0,1] neg_lo:[1,0,0]
	v_pk_mul_f32 v[122:123], v[128:129], v[156:157] op_sel:[0,0] op_sel_hi:[0,1]
	v_pk_fma_f32 v[112:113], v[112:113], v[162:163], v[126:127] op_sel:[1,1,0] op_sel_hi:[1,0,1] neg_lo:[1,0,0]
	s_nop 0
	v_pk_mul_f32 v[126:127], v[118:119], v[164:165] op_sel:[0,0] op_sel_hi:[0,1]
	v_mov_b32_e32 v136, v130
	v_mov_b32_e32 v134, v120
	v_mov_b32_e32 v135, v139
	v_pk_fma_f32 v[166:167], v[156:157], v[150:151], v[166:167] op_sel:[1,1,0] op_sel_hi:[1,0,1] neg_lo:[1,0,0]
	v_pk_fma_f32 v[168:169], v[154:155], v[154:155], v[168:169] op_sel:[1,1,0] op_sel_hi:[1,0,1] neg_lo:[1,0,0]
	v_pk_fma_f32 v[170:171], v[156:157], v[154:155], v[170:171] op_sel:[1,1,0] op_sel_hi:[1,0,1] neg_lo:[1,0,0]
	v_pk_mul_f32 v[172:173], v[140:141], v[102:103] op_sel:[0,0] op_sel_hi:[0,1]
	v_mov_b32_e32 v139, v121
	v_pk_fma_f32 v[102:103], v[140:141], v[102:103], v[172:173] op_sel:[1,1,0] op_sel_hi:[1,0,1] neg_lo:[1,0,0]
	v_pk_mul_f32 v[140:141], v[110:111], v[144:145] op_sel:[0,0] op_sel_hi:[0,1]
	v_pk_mul_f32 v[120:121], v[138:139], v[150:151] op_sel:[0,0] op_sel_hi:[0,1]
	v_pk_fma_f32 v[122:123], v[128:129], v[156:157], v[122:123] op_sel:[1,1,0] op_sel_hi:[1,0,1] neg_lo:[1,0,0]
	v_pk_fma_f32 v[118:119], v[118:119], v[164:165], v[126:127] op_sel:[1,1,0] op_sel_hi:[1,0,1] neg_lo:[1,0,0]
	v_pk_mul_f32 v[126:127], v[134:135], v[166:167] op_sel:[0,0] op_sel_hi:[0,1]
	v_pk_mul_f32 v[128:129], v[136:137], v[168:169] op_sel:[0,0] op_sel_hi:[0,1]
	v_pk_mul_f32 v[130:131], v[142:143], v[170:171] op_sel:[0,0] op_sel_hi:[0,1]
	s_nop 0
	v_pk_fma_f32 v[110:111], v[110:111], v[144:145], v[140:141] op_sel:[1,1,0] op_sel_hi:[1,0,1] neg_lo:[1,0,0]
	v_pk_mul_f32 v[140:141], v[124:125], v[146:147] op_sel:[0,0] op_sel_hi:[0,1]
	v_pk_fma_f32 v[120:121], v[138:139], v[150:151], v[120:121] op_sel:[1,1,0] op_sel_hi:[1,0,1] neg_lo:[1,0,0]
	v_pk_fma_f32 v[126:127], v[134:135], v[166:167], v[126:127] op_sel:[1,1,0] op_sel_hi:[1,0,1] neg_lo:[1,0,0]
	v_pk_fma_f32 v[128:129], v[136:137], v[168:169], v[128:129] op_sel:[1,1,0] op_sel_hi:[1,0,1] neg_lo:[1,0,0]
	v_pk_fma_f32 v[130:131], v[142:143], v[170:171], v[130:131] op_sel:[1,1,0] op_sel_hi:[1,0,1] neg_lo:[1,0,0]
	s_nop 0
	v_pk_fma_f32 v[124:125], v[124:125], v[146:147], v[140:141] op_sel:[1,1,0] op_sel_hi:[1,0,1] neg_lo:[1,0,0]
	ds_write_b64 v1, v[132:133]
	ds_write_b64 v1, v[102:103] offset:4352
	ds_write_b64 v1, v[110:111] offset:8704
	ds_write_b64 v1, v[124:125] offset:13056
	ds_write_b64 v1, v[116:117] offset:17408
	ds_write_b64 v1, v[120:121] offset:21760
	ds_write_b64 v1, v[108:109] offset:26112
	ds_write_b64 v1, v[114:115] offset:30464
	ds_write_b64 v1, v[122:123] offset:34816
	ds_write_b64 v1, v[104:105] offset:39168
	ds_write_b64 v1, v[106:107] offset:43520
	ds_write_b64 v1, v[112:113] offset:47872
	ds_write_b64 v1, v[118:119] offset:52224
	ds_write_b64 v1, v[126:127] offset:56576
	ds_write_b64 v1, v[128:129] offset:60928
	ds_write_b64 v1, v[130:131] offset:65280
	v_mov_b32_e32 v1, v0
	s_waitcnt lgkmcnt(0)
	s_barrier
	s_nop 0
	v_and_b32_e32 v26, 31, v1
	v_lshlrev_b32_e32 v1, 4, v1
	v_and_or_b32 v1, v1, s25, v26
	v_ashrrev_i32_e32 v28, 4, v1
	v_lshlrev_b32_e32 v28, 3, v28
	v_lshlrev_b32_e32 v1, 3, v1
	v_add3_u32 v1, 0, v28, v1
	ds_read2_b64 v[102:105], v1 offset1:34
	ds_read2_b64 v[106:109], v1 offset0:68 offset1:102
	ds_read2_b64 v[110:113], v1 offset0:136 offset1:170
	v_add_u32_e32 v28, 0x800, v1
	ds_read2_b64 v[114:117], v28 offset0:16 offset1:50
	ds_read2_b64 v[118:121], v28 offset0:152 offset1:186
	ds_read2_b64 v[122:125], v1 offset0:204 offset1:238
	ds_read2_b64 v[126:129], v28 offset0:84 offset1:118
	ds_read2_b64 v[130:133], v28 offset0:220 offset1:254
	s_waitcnt lgkmcnt(4)
	v_pk_add_f32 v[136:137], v[104:105], v[116:117] neg_lo:[0,1] neg_hi:[0,1]
	v_pk_add_f32 v[104:105], v[104:105], v[116:117]
	s_waitcnt lgkmcnt(3)
	v_pk_add_f32 v[138:139], v[112:113], v[120:121] neg_lo:[0,1] neg_hi:[0,1]
	v_pk_add_f32 v[112:113], v[112:113], v[120:121]
	v_pk_add_f32 v[140:141], v[136:137], v[138:139] op_sel:[0,1] op_sel_hi:[1,0]
	v_pk_add_f32 v[136:137], v[136:137], v[138:139] op_sel:[0,1] op_sel_hi:[1,0] neg_lo:[0,1] neg_hi:[0,1]
	v_mov_b32_e32 v138, v140
	v_mov_b32_e32 v139, v137
	v_mov_b32_e32 v137, v141
	s_waitcnt lgkmcnt(1)
	v_pk_add_f32 v[140:141], v[106:107], v[126:127] neg_lo:[0,1] neg_hi:[0,1]
	s_waitcnt lgkmcnt(0)
	v_pk_add_f32 v[142:143], v[122:123], v[130:131] neg_lo:[0,1] neg_hi:[0,1]
	v_pk_add_f32 v[146:147], v[124:125], v[132:133] neg_lo:[0,1] neg_hi:[0,1]
	v_pk_add_f32 v[144:145], v[140:141], v[142:143] op_sel:[0,1] op_sel_hi:[1,0]
	v_pk_add_f32 v[140:141], v[140:141], v[142:143] op_sel:[0,1] op_sel_hi:[1,0] neg_lo:[0,1] neg_hi:[0,1]
	v_mov_b32_e32 v142, v144
	v_mov_b32_e32 v143, v141
	v_mov_b32_e32 v141, v145
	v_pk_add_f32 v[144:145], v[108:109], v[128:129] neg_lo:[0,1] neg_hi:[0,1]
	v_pk_add_f32 v[116:117], v[104:105], v[112:113]
	v_pk_add_f32 v[148:149], v[144:145], v[146:147] op_sel:[0,1] op_sel_hi:[1,0]
	v_pk_add_f32 v[144:145], v[144:145], v[146:147] op_sel:[0,1] op_sel_hi:[1,0] neg_lo:[0,1] neg_hi:[0,1]
	v_pk_add_f32 v[104:105], v[104:105], v[112:113] neg_lo:[0,1] neg_hi:[0,1]
	v_pk_add_f32 v[106:107], v[106:107], v[126:127]
	v_pk_add_f32 v[112:113], v[122:123], v[130:131]
	v_mov_b32_e32 v146, v148
	v_mov_b32_e32 v147, v145
	v_mov_b32_e32 v145, v149
	v_pk_mul_f32 v[148:149], v[138:139], v[40:41] op_sel:[0,0] op_sel_hi:[0,1]
	v_pk_add_f32 v[120:121], v[106:107], v[112:113]
	v_pk_add_f32 v[106:107], v[106:107], v[112:113] neg_lo:[0,1] neg_hi:[0,1]
	v_pk_add_f32 v[108:109], v[108:109], v[128:129]
	v_pk_add_f32 v[112:113], v[124:125], v[132:133]
	v_pk_fma_f32 v[138:139], v[138:139], v[40:41], v[148:149] op_sel:[1,1,0] op_sel_hi:[1,0,1] neg_lo:[1,0,0]
	v_pk_mul_f32 v[148:149], v[142:143], v[24:25] op_sel:[0,0] op_sel_hi:[0,1]
	v_pk_add_f32 v[150:151], v[110:111], v[118:119]
	v_pk_add_f32 v[122:123], v[108:109], v[112:113]
	v_pk_add_f32 v[108:109], v[108:109], v[112:113] neg_lo:[0,1] neg_hi:[0,1]
	v_pk_mul_f32 v[112:113], v[104:105], v[24:25] op_sel:[0,0] op_sel_hi:[0,1]
	v_pk_fma_f32 v[142:143], v[142:143], v[24:25], v[148:149] op_sel:[1,1,0] op_sel_hi:[1,0,1] neg_lo:[1,0,0]
	v_pk_mul_f32 v[148:149], v[146:147], v[22:23] op_sel:[0,0] op_sel_hi:[0,1]
	v_pk_add_f32 v[110:111], v[110:111], v[118:119] neg_lo:[0,1] neg_hi:[0,1]
	v_pk_fma_f32 v[104:105], v[104:105], v[24:25], v[112:113] op_sel:[1,1,0] op_sel_hi:[1,0,1] neg_lo:[1,0,0]
	v_pk_mul_f32 v[112:113], v[106:107], v[42:43] op_sel:[0,0] op_sel_hi:[0,1]
	v_pk_fma_f32 v[146:147], v[146:147], v[22:23], v[148:149] op_sel:[1,1,0] op_sel_hi:[1,0,1] neg_lo:[1,0,0]
	v_pk_add_f32 v[148:149], v[102:103], v[114:115]
	v_pk_fma_f32 v[106:107], v[106:107], v[42:43], v[112:113] op_sel:[1,1,0] op_sel_hi:[1,0,1] neg_lo:[1,0,0]
	v_pk_mul_f32 v[112:113], v[108:109], v[36:37] op_sel:[0,0] op_sel_hi:[0,1]
	v_pk_add_f32 v[102:103], v[102:103], v[114:115] neg_lo:[0,1] neg_hi:[0,1]
	v_cvt_f32_ubyte0_e32 v26, v26
	v_pk_fma_f32 v[108:109], v[108:109], v[36:37], v[112:113] op_sel:[1,1,0] op_sel_hi:[1,0,1] neg_lo:[1,0,0]
	v_pk_mul_f32 v[112:113], v[136:137], v[22:23] op_sel:[0,0] op_sel_hi:[0,1]
	v_pk_add_f32 v[114:115], v[102:103], v[110:111] op_sel:[0,1] op_sel_hi:[1,0] neg_lo:[0,1] neg_hi:[0,1]
	v_pk_add_f32 v[102:103], v[102:103], v[110:111] op_sel:[0,1] op_sel_hi:[1,0]
	v_mul_f32_e32 v26, 0x3b000000, v26
	v_pk_fma_f32 v[112:113], v[136:137], v[22:23], v[112:113] op_sel:[1,1,0] op_sel_hi:[1,0,1] neg_lo:[1,0,0]
	v_pk_mul_f32 v[124:125], v[140:141], v[36:37] op_sel:[0,0] op_sel_hi:[0,1]
	v_pk_mul_f32 v[126:127], v[144:145], v[44:45] op_sel:[0,0] op_sel_hi:[0,1]
	v_mov_b32_e32 v110, v114
	v_mov_b32_e32 v111, v103
	v_mov_b32_e32 v103, v115
	v_cos_f32_e32 v134, v26
	v_sin_f32_e32 v26, v26
	v_pk_add_f32 v[152:153], v[148:149], v[150:151]
	v_pk_fma_f32 v[124:125], v[140:141], v[36:37], v[124:125] op_sel:[1,1,0] op_sel_hi:[1,0,1] neg_lo:[1,0,0]
	v_pk_fma_f32 v[126:127], v[144:145], v[44:45], v[126:127] op_sel:[1,1,0] op_sel_hi:[1,0,1] neg_lo:[1,0,0]
	v_pk_add_f32 v[114:115], v[102:103], v[142:143] neg_lo:[0,1] neg_hi:[0,1]
	v_pk_add_f32 v[102:103], v[102:103], v[142:143]
	v_pk_add_f32 v[142:143], v[110:111], v[124:125] neg_lo:[0,1] neg_hi:[0,1]
	v_pk_add_f32 v[144:145], v[112:113], v[126:127] neg_lo:[0,1] neg_hi:[0,1]
	v_pk_add_f32 v[112:113], v[112:113], v[126:127]
	v_pk_add_f32 v[110:111], v[110:111], v[124:125]
	v_pk_add_f32 v[128:129], v[152:153], v[120:121]
	v_pk_add_f32 v[130:131], v[116:117], v[122:123]
	v_pk_add_f32 v[124:125], v[110:111], v[112:113]
	v_pk_add_f32 v[110:111], v[110:111], v[112:113] neg_lo:[0,1] neg_hi:[0,1]
	v_pk_add_f32 v[112:113], v[142:143], v[144:145] op_sel:[0,1] op_sel_hi:[1,0]
	v_pk_add_f32 v[126:127], v[142:143], v[144:145] op_sel:[0,1] op_sel_hi:[1,0] neg_lo:[0,1] neg_hi:[0,1]
	s_nop 1
	v_pk_add_f32 v[132:133], v[128:129], v[130:131]
	v_xor_b32_e32 v135, 0x80000000, v26
	v_pk_mul_f32 v[144:145], v[134:135], v[134:135] op_sel:[0,0] op_sel_hi:[0,1]
	v_pk_add_f32 v[128:129], v[128:129], v[130:131] neg_lo:[0,1] neg_hi:[0,1]
	v_pk_add_f32 v[130:131], v[148:149], v[150:151] neg_lo:[0,1] neg_hi:[0,1]
	v_pk_fma_f32 v[144:145], v[134:135], v[134:135], v[144:145] op_sel:[1,1,0] op_sel_hi:[1,0,1] neg_lo:[1,0,0]
	v_pk_add_f32 v[120:121], v[152:153], v[120:121] neg_lo:[0,1] neg_hi:[0,1]
	v_pk_mul_f32 v[148:149], v[144:145], v[144:145] op_sel:[0,0] op_sel_hi:[0,1]
	v_pk_add_f32 v[116:117], v[116:117], v[122:123] neg_lo:[0,1] neg_hi:[0,1]
	v_pk_fma_f32 v[148:149], v[144:145], v[144:145], v[148:149] op_sel:[1,1,0] op_sel_hi:[1,0,1] neg_lo:[1,0,0]
	v_pk_add_f32 v[136:137], v[130:131], v[106:107] neg_lo:[0,1] neg_hi:[0,1]
	v_pk_mul_f32 v[156:157], v[148:149], v[148:149] op_sel:[0,0] op_sel_hi:[0,1]
	v_pk_add_f32 v[140:141], v[104:105], v[108:109] neg_lo:[0,1] neg_hi:[0,1]
	v_pk_add_f32 v[104:105], v[104:105], v[108:109]
	v_pk_add_f32 v[106:107], v[130:131], v[106:107]
	v_pk_add_f32 v[118:119], v[138:139], v[146:147] neg_lo:[0,1] neg_hi:[0,1]
	v_pk_add_f32 v[138:139], v[138:139], v[146:147]
	v_pk_mul_f32 v[150:151], v[148:149], v[134:135] op_sel:[0,0] op_sel_hi:[0,1]
	v_pk_fma_f32 v[156:157], v[148:149], v[148:149], v[156:157] op_sel:[1,1,0] op_sel_hi:[1,0,1] neg_lo:[1,0,0]
	v_pk_add_f32 v[122:123], v[120:121], v[116:117] op_sel:[0,1] op_sel_hi:[1,0]
	v_pk_mul_f32 v[158:159], v[156:157], v[134:135] op_sel:[0,0] op_sel_hi:[0,1]
	v_pk_add_f32 v[116:117], v[120:121], v[116:117] op_sel:[0,1] op_sel_hi:[1,0] neg_lo:[0,1] neg_hi:[0,1]
	v_pk_add_f32 v[108:109], v[106:107], v[104:105]
	v_pk_add_f32 v[104:105], v[106:107], v[104:105] neg_lo:[0,1] neg_hi:[0,1]
	v_pk_add_f32 v[106:107], v[136:137], v[140:141] op_sel:[0,1] op_sel_hi:[1,0]
	v_pk_add_f32 v[130:131], v[136:137], v[140:141] op_sel:[0,1] op_sel_hi:[1,0] neg_lo:[0,1] neg_hi:[0,1]
	v_pk_add_f32 v[140:141], v[102:103], v[138:139]
	v_pk_add_f32 v[102:103], v[102:103], v[138:139] neg_lo:[0,1] neg_hi:[0,1]
	v_mov_b32_e32 v142, v126
	v_mov_b32_e32 v143, v113
	v_pk_mul_f32 v[146:147], v[144:145], v[134:135] op_sel:[0,0] op_sel_hi:[0,1]
	v_pk_fma_f32 v[150:151], v[148:149], v[134:135], v[150:151] op_sel:[1,1,0] op_sel_hi:[1,0,1] neg_lo:[1,0,0]
	v_pk_fma_f32 v[158:159], v[156:157], v[134:135], v[158:159] op_sel:[1,1,0] op_sel_hi:[1,0,1] neg_lo:[1,0,0]
	v_mov_b32_e32 v113, v127
	v_pk_mul_f32 v[160:161], v[150:151], v[150:151] op_sel:[0,0] op_sel_hi:[0,1]
	v_pk_mul_f32 v[126:127], v[102:103], v[158:159] op_sel:[0,0] op_sel_hi:[0,1]
	v_mov_b32_e32 v120, v116
	v_mov_b32_e32 v121, v123
	v_pk_fma_f32 v[146:147], v[144:145], v[134:135], v[146:147] op_sel:[1,1,0] op_sel_hi:[1,0,1] neg_lo:[1,0,0]
	v_pk_fma_f32 v[160:161], v[150:151], v[150:151], v[160:161] op_sel:[1,1,0] op_sel_hi:[1,0,1] neg_lo:[1,0,0]
	v_mov_b32_e32 v123, v117
	v_pk_mul_f32 v[152:153], v[146:147], v[146:147] op_sel:[0,0] op_sel_hi:[0,1]
	v_pk_mul_f32 v[162:163], v[156:157], v[146:147] op_sel:[0,0] op_sel_hi:[0,1]
	v_pk_mul_f32 v[116:117], v[122:123], v[148:149] op_sel:[0,0] op_sel_hi:[0,1]
	v_pk_fma_f32 v[102:103], v[102:103], v[158:159], v[126:127] op_sel:[1,1,0] op_sel_hi:[1,0,1] neg_lo:[1,0,0]
	v_pk_mul_f32 v[126:127], v[104:105], v[160:161] op_sel:[0,0] op_sel_hi:[0,1]
	v_mov_b32_e32 v137, v107
	v_pk_fma_f32 v[152:153], v[146:147], v[146:147], v[152:153] op_sel:[1,1,0] op_sel_hi:[1,0,1] neg_lo:[1,0,0]
	v_pk_mul_f32 v[154:155], v[148:149], v[146:147] op_sel:[0,0] op_sel_hi:[0,1]
	v_pk_fma_f32 v[162:163], v[156:157], v[146:147], v[162:163] op_sel:[1,1,0] op_sel_hi:[1,0,1] neg_lo:[1,0,0]
	v_pk_fma_f32 v[116:117], v[122:123], v[148:149], v[116:117] op_sel:[1,1,0] op_sel_hi:[1,0,1] neg_lo:[1,0,0]
	v_mov_b32_e32 v107, v131
	v_pk_mul_f32 v[164:165], v[152:153], v[152:153] op_sel:[0,0] op_sel_hi:[0,1]
	v_pk_mul_f32 v[122:123], v[106:107], v[152:153] op_sel:[0,0] op_sel_hi:[0,1]
	v_pk_fma_f32 v[104:105], v[104:105], v[160:161], v[126:127] op_sel:[1,1,0] op_sel_hi:[1,0,1] neg_lo:[1,0,0]
	v_pk_mul_f32 v[126:127], v[110:111], v[162:163] op_sel:[0,0] op_sel_hi:[0,1]
	v_pk_add_f32 v[138:139], v[114:115], v[118:119] op_sel:[0,1] op_sel_hi:[1,0]
	v_pk_add_f32 v[114:115], v[114:115], v[118:119] op_sel:[0,1] op_sel_hi:[1,0] neg_lo:[0,1] neg_hi:[0,1]
	v_pk_fma_f32 v[154:155], v[148:149], v[146:147], v[154:155] op_sel:[1,1,0] op_sel_hi:[1,0,1] neg_lo:[1,0,0]
	v_pk_fma_f32 v[164:165], v[152:153], v[152:153], v[164:165] op_sel:[1,1,0] op_sel_hi:[1,0,1] neg_lo:[1,0,0]
	v_pk_mul_f32 v[166:167], v[156:157], v[150:151] op_sel:[0,0] op_sel_hi:[0,1]
	v_pk_fma_f32 v[106:107], v[106:107], v[152:153], v[122:123] op_sel:[1,1,0] op_sel_hi:[1,0,1] neg_lo:[1,0,0]
	v_pk_fma_f32 v[110:111], v[110:111], v[162:163], v[126:127] op_sel:[1,1,0] op_sel_hi:[1,0,1] neg_lo:[1,0,0]
	s_nop 0
	v_mov_b32_e32 v118, v114
	v_pk_mul_f32 v[122:123], v[112:113], v[154:155] op_sel:[0,0] op_sel_hi:[0,1]
	v_pk_mul_f32 v[126:127], v[120:121], v[164:165] op_sel:[0,0] op_sel_hi:[0,1]
	v_mov_b32_e32 v119, v139
	v_pk_fma_f32 v[166:167], v[156:157], v[150:151], v[166:167] op_sel:[1,1,0] op_sel_hi:[1,0,1] neg_lo:[1,0,0]
	v_pk_mul_f32 v[168:169], v[154:155], v[154:155] op_sel:[0,0] op_sel_hi:[0,1]
	v_pk_mul_f32 v[170:171], v[156:157], v[154:155] op_sel:[0,0] op_sel_hi:[0,1]
	v_pk_fma_f32 v[112:113], v[112:113], v[154:155], v[122:123] op_sel:[1,1,0] op_sel_hi:[1,0,1] neg_lo:[1,0,0]
	v_pk_mul_f32 v[122:123], v[128:129], v[156:157] op_sel:[0,0] op_sel_hi:[0,1]
	v_pk_fma_f32 v[120:121], v[120:121], v[164:165], v[126:127] op_sel:[1,1,0] op_sel_hi:[1,0,1] neg_lo:[1,0,0]
	s_nop 0
	v_pk_mul_f32 v[126:127], v[118:119], v[166:167] op_sel:[0,0] op_sel_hi:[0,1]
	v_mov_b32_e32 v136, v130
	v_pk_fma_f32 v[168:169], v[154:155], v[154:155], v[168:169] op_sel:[1,1,0] op_sel_hi:[1,0,1] neg_lo:[1,0,0]
	v_pk_fma_f32 v[170:171], v[156:157], v[154:155], v[170:171] op_sel:[1,1,0] op_sel_hi:[1,0,1] neg_lo:[1,0,0]
	v_pk_mul_f32 v[172:173], v[140:141], v[134:135] op_sel:[0,0] op_sel_hi:[0,1]
	v_mov_b32_e32 v139, v115
	v_pk_fma_f32 v[134:135], v[140:141], v[134:135], v[172:173] op_sel:[1,1,0] op_sel_hi:[1,0,1] neg_lo:[1,0,0]
	v_pk_mul_f32 v[140:141], v[108:109], v[144:145] op_sel:[0,0] op_sel_hi:[0,1]
	v_pk_mul_f32 v[114:115], v[138:139], v[150:151] op_sel:[0,0] op_sel_hi:[0,1]
	v_pk_fma_f32 v[122:123], v[128:129], v[156:157], v[122:123] op_sel:[1,1,0] op_sel_hi:[1,0,1] neg_lo:[1,0,0]
	v_pk_fma_f32 v[118:119], v[118:119], v[166:167], v[126:127] op_sel:[1,1,0] op_sel_hi:[1,0,1] neg_lo:[1,0,0]
	v_pk_mul_f32 v[126:127], v[136:137], v[168:169] op_sel:[0,0] op_sel_hi:[0,1]
	v_pk_mul_f32 v[128:129], v[142:143], v[170:171] op_sel:[0,0] op_sel_hi:[0,1]
	s_nop 0
	v_pk_fma_f32 v[108:109], v[108:109], v[144:145], v[140:141] op_sel:[1,1,0] op_sel_hi:[1,0,1] neg_lo:[1,0,0]
	v_pk_mul_f32 v[140:141], v[124:125], v[146:147] op_sel:[0,0] op_sel_hi:[0,1]
	v_pk_fma_f32 v[114:115], v[138:139], v[150:151], v[114:115] op_sel:[1,1,0] op_sel_hi:[1,0,1] neg_lo:[1,0,0]
	s_nop 0
	v_pk_fma_f32 v[124:125], v[124:125], v[146:147], v[140:141] op_sel:[1,1,0] op_sel_hi:[1,0,1] neg_lo:[1,0,0]
	v_pk_fma_f32 v[126:127], v[136:137], v[168:169], v[126:127] op_sel:[1,1,0] op_sel_hi:[1,0,1] neg_lo:[1,0,0]
	v_pk_fma_f32 v[128:129], v[142:143], v[170:171], v[128:129] op_sel:[1,1,0] op_sel_hi:[1,0,1] neg_lo:[1,0,0]
	ds_write2_b64 v1, v[132:133], v[134:135] offset1:34
	ds_write2_b64 v1, v[108:109], v[124:125] offset0:68 offset1:102
	ds_write2_b64 v1, v[116:117], v[114:115] offset0:136 offset1:170
	ds_write2_b64 v1, v[106:107], v[112:113] offset0:204 offset1:238
	ds_write2_b64 v28, v[122:123], v[102:103] offset0:16 offset1:50
	ds_write2_b64 v28, v[104:105], v[110:111] offset0:84 offset1:118
	ds_write2_b64 v28, v[120:121], v[118:119] offset0:152 offset1:186
	ds_write2_b64 v28, v[126:127], v[128:129] offset0:220 offset1:254
	v_mov_b32_e32 v1, v0
	s_waitcnt lgkmcnt(0)
	s_barrier
	s_nop 0
	v_and_b32_e32 v26, 1, v1
	v_lshlrev_b32_e32 v1, 4, v1
	v_and_b32_e32 v1, 0xffffffe0, v1
	v_ashrrev_i32_e32 v28, 1, v1
	v_add_u32_e32 v28, 0, v28
	v_lshlrev_b32_e32 v1, 3, v1
	v_lshlrev_b32_e32 v30, 3, v26
	v_add3_u32 v1, v28, v1, v30
	ds_read2_b64 v[102:105], v1 offset1:2
	ds_read2_b64 v[106:109], v1 offset0:4 offset1:6
	ds_read2_b64 v[110:113], v1 offset0:8 offset1:10
	ds_read2_b64 v[114:117], v1 offset0:17 offset1:19
	ds_read2_b64 v[118:121], v1 offset0:25 offset1:27
	ds_read2_b64 v[122:125], v1 offset0:12 offset1:14
	ds_read2_b64 v[126:129], v1 offset0:21 offset1:23
	ds_read2_b64 v[130:133], v1 offset0:29 offset1:31
	s_waitcnt lgkmcnt(4)
	v_pk_add_f32 v[136:137], v[104:105], v[116:117] neg_lo:[0,1] neg_hi:[0,1]
	s_waitcnt lgkmcnt(3)
	v_pk_add_f32 v[138:139], v[112:113], v[120:121] neg_lo:[0,1] neg_hi:[0,1]
	v_pk_add_f32 v[104:105], v[104:105], v[116:117]
	v_pk_add_f32 v[140:141], v[136:137], v[138:139] op_sel:[0,1] op_sel_hi:[1,0]
	v_pk_add_f32 v[136:137], v[136:137], v[138:139] op_sel:[0,1] op_sel_hi:[1,0] neg_lo:[0,1] neg_hi:[0,1]
	v_mov_b32_e32 v138, v140
	v_mov_b32_e32 v139, v137
	v_mov_b32_e32 v137, v141
	s_waitcnt lgkmcnt(1)
	v_pk_add_f32 v[140:141], v[106:107], v[126:127] neg_lo:[0,1] neg_hi:[0,1]
	s_waitcnt lgkmcnt(0)
	v_pk_add_f32 v[142:143], v[122:123], v[130:131] neg_lo:[0,1] neg_hi:[0,1]
	v_pk_add_f32 v[146:147], v[124:125], v[132:133] neg_lo:[0,1] neg_hi:[0,1]
	v_pk_add_f32 v[144:145], v[140:141], v[142:143] op_sel:[0,1] op_sel_hi:[1,0]
	v_pk_add_f32 v[140:141], v[140:141], v[142:143] op_sel:[0,1] op_sel_hi:[1,0] neg_lo:[0,1] neg_hi:[0,1]
	v_mov_b32_e32 v142, v144
	v_mov_b32_e32 v143, v141
	v_mov_b32_e32 v141, v145
	v_pk_add_f32 v[144:145], v[108:109], v[128:129] neg_lo:[0,1] neg_hi:[0,1]
	v_pk_add_f32 v[112:113], v[112:113], v[120:121]
	v_pk_add_f32 v[148:149], v[144:145], v[146:147] op_sel:[0,1] op_sel_hi:[1,0]
	v_pk_add_f32 v[144:145], v[144:145], v[146:147] op_sel:[0,1] op_sel_hi:[1,0] neg_lo:[0,1] neg_hi:[0,1]
	v_mov_b32_e32 v146, v148
	v_mov_b32_e32 v147, v145
	v_mov_b32_e32 v145, v149
	v_pk_mul_f32 v[148:149], v[138:139], v[40:41] op_sel:[0,0] op_sel_hi:[0,1]
	v_pk_add_f32 v[116:117], v[104:105], v[112:113]
	v_pk_fma_f32 v[40:41], v[138:139], v[40:41], v[148:149] op_sel:[1,1,0] op_sel_hi:[1,0,1] neg_lo:[1,0,0]
	v_pk_mul_f32 v[138:139], v[142:143], v[24:25] op_sel:[0,0] op_sel_hi:[0,1]
	v_pk_add_f32 v[104:105], v[104:105], v[112:113] neg_lo:[0,1] neg_hi:[0,1]
	v_pk_add_f32 v[106:107], v[106:107], v[126:127]
	v_pk_add_f32 v[112:113], v[122:123], v[130:131]
	v_pk_fma_f32 v[138:139], v[142:143], v[24:25], v[138:139] op_sel:[1,1,0] op_sel_hi:[1,0,1] neg_lo:[1,0,0]
	v_pk_mul_f32 v[142:143], v[146:147], v[22:23] op_sel:[0,0] op_sel_hi:[0,1]
	v_pk_add_f32 v[108:109], v[108:109], v[128:129]
	v_pk_add_f32 v[120:121], v[106:107], v[112:113]
	v_pk_add_f32 v[106:107], v[106:107], v[112:113] neg_lo:[0,1] neg_hi:[0,1]
	v_pk_add_f32 v[112:113], v[124:125], v[132:133]
	v_pk_fma_f32 v[142:143], v[146:147], v[22:23], v[142:143] op_sel:[1,1,0] op_sel_hi:[1,0,1] neg_lo:[1,0,0]
	v_pk_add_f32 v[146:147], v[102:103], v[114:115]
	v_pk_add_f32 v[148:149], v[110:111], v[118:119]
	v_pk_add_f32 v[122:123], v[108:109], v[112:113]
	v_pk_add_f32 v[108:109], v[108:109], v[112:113] neg_lo:[0,1] neg_hi:[0,1]
	v_pk_mul_f32 v[112:113], v[104:105], v[24:25] op_sel:[0,0] op_sel_hi:[0,1]
	v_pk_add_f32 v[102:103], v[102:103], v[114:115] neg_lo:[0,1] neg_hi:[0,1]
	v_pk_fma_f32 v[24:25], v[104:105], v[24:25], v[112:113] op_sel:[1,1,0] op_sel_hi:[1,0,1] neg_lo:[1,0,0]
	v_pk_mul_f32 v[104:105], v[106:107], v[42:43] op_sel:[0,0] op_sel_hi:[0,1]
	v_pk_add_f32 v[110:111], v[110:111], v[118:119] neg_lo:[0,1] neg_hi:[0,1]
	v_cvt_f32_ubyte0_e32 v26, v26
	v_pk_fma_f32 v[42:43], v[106:107], v[42:43], v[104:105] op_sel:[1,1,0] op_sel_hi:[1,0,1] neg_lo:[1,0,0]
	v_pk_mul_f32 v[104:105], v[108:109], v[36:37] op_sel:[0,0] op_sel_hi:[0,1]
	v_pk_mul_f32 v[106:107], v[136:137], v[22:23] op_sel:[0,0] op_sel_hi:[0,1]
	v_pk_add_f32 v[114:115], v[102:103], v[110:111] op_sel:[0,1] op_sel_hi:[1,0] neg_lo:[0,1] neg_hi:[0,1]
	v_pk_add_f32 v[102:103], v[102:103], v[110:111] op_sel:[0,1] op_sel_hi:[1,0]
	v_mul_f32_e32 v26, 0x3d000000, v26
	v_pk_fma_f32 v[104:105], v[108:109], v[36:37], v[104:105] op_sel:[1,1,0] op_sel_hi:[1,0,1] neg_lo:[1,0,0]
	v_pk_fma_f32 v[22:23], v[136:137], v[22:23], v[106:107] op_sel:[1,1,0] op_sel_hi:[1,0,1] neg_lo:[1,0,0]
	v_pk_mul_f32 v[106:107], v[140:141], v[36:37] op_sel:[0,0] op_sel_hi:[0,1]
	v_mov_b32_e32 v110, v114
	v_pk_fma_f32 v[36:37], v[140:141], v[36:37], v[106:107] op_sel:[1,1,0] op_sel_hi:[1,0,1] neg_lo:[1,0,0]
	v_mov_b32_e32 v111, v103
	v_cos_f32_e32 v134, v26
	v_sin_f32_e32 v26, v26
	v_pk_mul_f32 v[106:107], v[144:145], v[44:45] op_sel:[0,0] op_sel_hi:[0,1]
	v_pk_add_f32 v[128:129], v[110:111], v[36:37] neg_lo:[0,1] neg_hi:[0,1]
	v_pk_fma_f32 v[44:45], v[144:145], v[44:45], v[106:107] op_sel:[1,1,0] op_sel_hi:[1,0,1] neg_lo:[1,0,0]
	v_pk_add_f32 v[36:37], v[110:111], v[36:37]
	v_pk_add_f32 v[130:131], v[22:23], v[44:45] neg_lo:[0,1] neg_hi:[0,1]
	v_pk_add_f32 v[22:23], v[22:23], v[44:45]
	v_pk_add_f32 v[110:111], v[128:129], v[130:131] op_sel:[0,1] op_sel_hi:[1,0] neg_lo:[0,1] neg_hi:[0,1]
	v_pk_add_f32 v[44:45], v[36:37], v[22:23]
	v_pk_add_f32 v[22:23], v[36:37], v[22:23] neg_lo:[0,1] neg_hi:[0,1]
	v_pk_add_f32 v[36:37], v[128:129], v[130:131] op_sel:[0,1] op_sel_hi:[1,0]
	s_nop 1
	v_pk_add_f32 v[150:151], v[146:147], v[148:149]
	v_xor_b32_e32 v135, 0x80000000, v26
	v_pk_mul_f32 v[130:131], v[134:135], v[134:135] op_sel:[0,0] op_sel_hi:[0,1]
	v_pk_add_f32 v[118:119], v[40:41], v[142:143] neg_lo:[0,1] neg_hi:[0,1]
	v_pk_fma_f32 v[130:131], v[134:135], v[134:135], v[130:131] op_sel:[1,1,0] op_sel_hi:[1,0,1] neg_lo:[1,0,0]
	v_pk_add_f32 v[40:41], v[40:41], v[142:143]
	v_pk_mul_f32 v[132:133], v[130:131], v[134:135] op_sel:[0,0] op_sel_hi:[0,1]
	v_pk_mul_f32 v[136:137], v[130:131], v[130:131] op_sel:[0,0] op_sel_hi:[0,1]
	v_pk_add_f32 v[106:107], v[150:151], v[120:121]
	v_pk_fma_f32 v[132:133], v[130:131], v[134:135], v[132:133] op_sel:[1,1,0] op_sel_hi:[1,0,1] neg_lo:[1,0,0]
	v_pk_fma_f32 v[136:137], v[130:131], v[130:131], v[136:137] op_sel:[1,1,0] op_sel_hi:[1,0,1] neg_lo:[1,0,0]
	v_pk_add_f32 v[108:109], v[116:117], v[122:123]
	v_pk_mul_f32 v[142:143], v[136:137], v[132:133] op_sel:[0,0] op_sel_hi:[0,1]
	v_pk_add_f32 v[116:117], v[116:117], v[122:123] neg_lo:[0,1] neg_hi:[0,1]
	v_pk_add_f32 v[122:123], v[146:147], v[148:149] neg_lo:[0,1] neg_hi:[0,1]
	v_mov_b32_e32 v103, v115
	v_mov_b32_e32 v128, v110
	v_mov_b32_e32 v129, v37
	v_pk_fma_f32 v[142:143], v[136:137], v[132:133], v[142:143] op_sel:[1,1,0] op_sel_hi:[1,0,1] neg_lo:[1,0,0]
	v_pk_mul_f32 v[144:145], v[136:137], v[136:137] op_sel:[0,0] op_sel_hi:[0,1]
	v_mov_b32_e32 v37, v111
	v_pk_mul_f32 v[110:111], v[36:37], v[142:143] op_sel:[0,0] op_sel_hi:[0,1]
	v_pk_add_f32 v[112:113], v[106:107], v[108:109]
	v_pk_add_f32 v[106:107], v[106:107], v[108:109] neg_lo:[0,1] neg_hi:[0,1]
	v_pk_add_f32 v[124:125], v[122:123], v[42:43] neg_lo:[0,1] neg_hi:[0,1]
	v_pk_add_f32 v[126:127], v[24:25], v[104:105] neg_lo:[0,1] neg_hi:[0,1]
	v_pk_add_f32 v[24:25], v[24:25], v[104:105]
	v_pk_add_f32 v[42:43], v[122:123], v[42:43]
	v_pk_add_f32 v[114:115], v[102:103], v[138:139] neg_lo:[0,1] neg_hi:[0,1]
	v_pk_add_f32 v[102:103], v[102:103], v[138:139]
	v_pk_mul_f32 v[138:139], v[136:137], v[134:135] op_sel:[0,0] op_sel_hi:[0,1]
	v_pk_fma_f32 v[144:145], v[136:137], v[136:137], v[144:145] op_sel:[1,1,0] op_sel_hi:[1,0,1] neg_lo:[1,0,0]
	v_pk_fma_f32 v[36:37], v[36:37], v[142:143], v[110:111] op_sel:[1,1,0] op_sel_hi:[1,0,1] neg_lo:[1,0,0]
	v_pk_add_f32 v[104:105], v[42:43], v[24:25]
	v_pk_mul_f32 v[146:147], v[144:145], v[134:135] op_sel:[0,0] op_sel_hi:[0,1]
	v_pk_mul_f32 v[110:111], v[106:107], v[144:145] op_sel:[0,0] op_sel_hi:[0,1]
	v_pk_add_f32 v[24:25], v[42:43], v[24:25] neg_lo:[0,1] neg_hi:[0,1]
	v_pk_add_f32 v[42:43], v[124:125], v[126:127] op_sel:[0,1] op_sel_hi:[1,0]
	v_pk_add_f32 v[122:123], v[124:125], v[126:127] op_sel:[0,1] op_sel_hi:[1,0] neg_lo:[0,1] neg_hi:[0,1]
	v_pk_add_f32 v[126:127], v[102:103], v[40:41]
	v_pk_add_f32 v[40:41], v[102:103], v[40:41] neg_lo:[0,1] neg_hi:[0,1]
	v_pk_add_f32 v[102:103], v[114:115], v[118:119] op_sel:[0,1] op_sel_hi:[1,0]
	v_pk_add_f32 v[114:115], v[114:115], v[118:119] op_sel:[0,1] op_sel_hi:[1,0] neg_lo:[0,1] neg_hi:[0,1]
	v_pk_fma_f32 v[138:139], v[136:137], v[134:135], v[138:139] op_sel:[1,1,0] op_sel_hi:[1,0,1] neg_lo:[1,0,0]
	v_pk_fma_f32 v[146:147], v[144:145], v[134:135], v[146:147] op_sel:[1,1,0] op_sel_hi:[1,0,1] neg_lo:[1,0,0]
	v_pk_fma_f32 v[106:107], v[106:107], v[144:145], v[110:111] op_sel:[1,1,0] op_sel_hi:[1,0,1] neg_lo:[1,0,0]
	v_pk_add_f32 v[108:109], v[150:151], v[120:121] neg_lo:[0,1] neg_hi:[0,1]
	v_pk_mul_f32 v[148:149], v[138:139], v[138:139] op_sel:[0,0] op_sel_hi:[0,1]
	v_pk_mul_f32 v[110:111], v[40:41], v[146:147] op_sel:[0,0] op_sel_hi:[0,1]
	v_mov_b32_e32 v118, v114
	v_mov_b32_e32 v119, v103
	v_pk_mul_f32 v[140:141], v[132:133], v[132:133] op_sel:[0,0] op_sel_hi:[0,1]
	v_pk_fma_f32 v[148:149], v[138:139], v[138:139], v[148:149] op_sel:[1,1,0] op_sel_hi:[1,0,1] neg_lo:[1,0,0]
	v_pk_mul_f32 v[150:151], v[144:145], v[132:133] op_sel:[0,0] op_sel_hi:[0,1]
	v_mov_b32_e32 v103, v115
	v_pk_mul_f32 v[114:115], v[102:103], v[138:139] op_sel:[0,0] op_sel_hi:[0,1]
	v_pk_fma_f32 v[40:41], v[40:41], v[146:147], v[110:111] op_sel:[1,1,0] op_sel_hi:[1,0,1] neg_lo:[1,0,0]
	v_pk_mul_f32 v[110:111], v[24:25], v[148:149] op_sel:[0,0] op_sel_hi:[0,1]
	v_pk_add_f32 v[120:121], v[108:109], v[116:117] op_sel:[0,1] op_sel_hi:[1,0]
	v_pk_add_f32 v[108:109], v[108:109], v[116:117] op_sel:[0,1] op_sel_hi:[1,0] neg_lo:[0,1] neg_hi:[0,1]
	v_mov_b32_e32 v125, v43
	v_pk_fma_f32 v[140:141], v[132:133], v[132:133], v[140:141] op_sel:[1,1,0] op_sel_hi:[1,0,1] neg_lo:[1,0,0]
	v_pk_fma_f32 v[150:151], v[144:145], v[132:133], v[150:151] op_sel:[1,1,0] op_sel_hi:[1,0,1] neg_lo:[1,0,0]
	v_pk_mul_f32 v[154:155], v[144:145], v[138:139] op_sel:[0,0] op_sel_hi:[0,1]
	v_pk_fma_f32 v[102:103], v[102:103], v[138:139], v[114:115] op_sel:[1,1,0] op_sel_hi:[1,0,1] neg_lo:[1,0,0]
	v_mov_b32_e32 v43, v123
	v_pk_mul_f32 v[152:153], v[140:141], v[140:141] op_sel:[0,0] op_sel_hi:[0,1]
	v_pk_mul_f32 v[114:115], v[42:43], v[140:141] op_sel:[0,0] op_sel_hi:[0,1]
	v_pk_fma_f32 v[24:25], v[24:25], v[148:149], v[110:111] op_sel:[1,1,0] op_sel_hi:[1,0,1] neg_lo:[1,0,0]
	v_pk_mul_f32 v[110:111], v[22:23], v[150:151] op_sel:[0,0] op_sel_hi:[0,1]
	v_mov_b32_e32 v116, v108
	v_mov_b32_e32 v117, v121
	v_pk_fma_f32 v[152:153], v[140:141], v[140:141], v[152:153] op_sel:[1,1,0] op_sel_hi:[1,0,1] neg_lo:[1,0,0]
	v_pk_fma_f32 v[154:155], v[144:145], v[138:139], v[154:155] op_sel:[1,1,0] op_sel_hi:[1,0,1] neg_lo:[1,0,0]
	v_pk_mul_f32 v[156:157], v[142:143], v[142:143] op_sel:[0,0] op_sel_hi:[0,1]
	v_pk_mul_f32 v[158:159], v[144:145], v[142:143] op_sel:[0,0] op_sel_hi:[0,1]
	v_pk_fma_f32 v[42:43], v[42:43], v[140:141], v[114:115] op_sel:[1,1,0] op_sel_hi:[1,0,1] neg_lo:[1,0,0]
	v_pk_fma_f32 v[22:23], v[22:23], v[150:151], v[110:111] op_sel:[1,1,0] op_sel_hi:[1,0,1] neg_lo:[1,0,0]
	s_nop 0
	v_pk_mul_f32 v[110:111], v[116:117], v[152:153] op_sel:[0,0] op_sel_hi:[0,1]
	v_pk_mul_f32 v[114:115], v[118:119], v[154:155] op_sel:[0,0] op_sel_hi:[0,1]
	v_mov_b32_e32 v124, v122
	v_pk_fma_f32 v[156:157], v[142:143], v[142:143], v[156:157] op_sel:[1,1,0] op_sel_hi:[1,0,1] neg_lo:[1,0,0]
	v_pk_fma_f32 v[158:159], v[144:145], v[142:143], v[158:159] op_sel:[1,1,0] op_sel_hi:[1,0,1] neg_lo:[1,0,0]
	v_pk_mul_f32 v[160:161], v[126:127], v[134:135] op_sel:[0,0] op_sel_hi:[0,1]
	v_mov_b32_e32 v121, v109
	v_pk_fma_f32 v[126:127], v[126:127], v[134:135], v[160:161] op_sel:[1,1,0] op_sel_hi:[1,0,1] neg_lo:[1,0,0]
	v_pk_mul_f32 v[108:109], v[120:121], v[136:137] op_sel:[0,0] op_sel_hi:[0,1]
	v_pk_fma_f32 v[110:111], v[116:117], v[152:153], v[110:111] op_sel:[1,1,0] op_sel_hi:[1,0,1] neg_lo:[1,0,0]
	v_pk_fma_f32 v[114:115], v[118:119], v[154:155], v[114:115] op_sel:[1,1,0] op_sel_hi:[1,0,1] neg_lo:[1,0,0]
	v_pk_mul_f32 v[116:117], v[124:125], v[156:157] op_sel:[0,0] op_sel_hi:[0,1]
	v_pk_mul_f32 v[118:119], v[128:129], v[158:159] op_sel:[0,0] op_sel_hi:[0,1]
	v_pk_mul_f32 v[134:135], v[104:105], v[130:131] op_sel:[0,0] op_sel_hi:[0,1]
	s_nop 0
	v_pk_fma_f32 v[108:109], v[120:121], v[136:137], v[108:109] op_sel:[1,1,0] op_sel_hi:[1,0,1] neg_lo:[1,0,0]
	v_pk_fma_f32 v[104:105], v[104:105], v[130:131], v[134:135] op_sel:[1,1,0] op_sel_hi:[1,0,1] neg_lo:[1,0,0]
	v_pk_mul_f32 v[130:131], v[44:45], v[132:133] op_sel:[0,0] op_sel_hi:[0,1]
	v_pk_fma_f32 v[116:117], v[124:125], v[156:157], v[116:117] op_sel:[1,1,0] op_sel_hi:[1,0,1] neg_lo:[1,0,0]
	v_pk_fma_f32 v[118:119], v[128:129], v[158:159], v[118:119] op_sel:[1,1,0] op_sel_hi:[1,0,1] neg_lo:[1,0,0]
	s_nop 0
	v_pk_fma_f32 v[44:45], v[44:45], v[132:133], v[130:131] op_sel:[1,1,0] op_sel_hi:[1,0,1] neg_lo:[1,0,0]
	ds_write2_b64 v1, v[112:113], v[126:127] offset1:2
	ds_write2_b64 v1, v[104:105], v[44:45] offset0:4 offset1:6
	ds_write2_b64 v1, v[108:109], v[102:103] offset0:8 offset1:10
	ds_write2_b64 v1, v[42:43], v[36:37] offset0:12 offset1:14
	ds_write2_b64 v1, v[106:107], v[40:41] offset0:17 offset1:19
	ds_write2_b64 v1, v[24:25], v[22:23] offset0:21 offset1:23
	ds_write2_b64 v1, v[110:111], v[114:115] offset0:25 offset1:27
	ds_write2_b64 v1, v[116:117], v[118:119] offset0:29 offset1:31
	v_mov_b32_e32 v1, v0
	s_waitcnt lgkmcnt(0)
	s_barrier
	s_waitcnt vmcnt(3)
	v_lshlrev_b32_e32 v36, 16, v100
	v_and_b32_e32 v22, -8, v1
	v_lshlrev_b32_e32 v23, 4, v1
	v_add3_u32 v26, 0, v22, v23
	ds_read2_b64 v[22:25], v26 offset1:1
	v_and_b32_e32 v37, 0xffff0000, v100
	v_lshlrev_b32_e32 v40, 16, v101
	v_and_b32_e32 v41, 0xffff0000, v101
	s_waitcnt lgkmcnt(0)
	v_pk_add_f32 v[42:43], v[22:23], v[24:25]
	v_pk_add_f32 v[22:23], v[22:23], v[24:25] neg_lo:[0,1] neg_hi:[0,1]
	v_pk_mul_f32 v[24:25], v[42:43], v[36:37] op_sel:[0,0] op_sel_hi:[0,1]
	s_nop 0
	v_pk_fma_f32 v[24:25], v[42:43], v[36:37], v[24:25] op_sel:[1,1,0] op_sel_hi:[1,0,1] neg_lo:[1,0,0]
	v_pk_mul_f32 v[36:37], v[22:23], v[40:41] op_sel:[0,0] op_sel_hi:[0,1]
	s_nop 0
	v_pk_fma_f32 v[22:23], v[22:23], v[40:41], v[36:37] op_sel:[1,1,0] op_sel_hi:[1,0,1] neg_lo:[1,0,0]
	s_waitcnt vmcnt(2)
	v_lshlrev_b32_e32 v40, 16, v99
	v_pk_add_f32 v[36:37], v[24:25], v[22:23]
	v_pk_add_f32 v[22:23], v[24:25], v[22:23] neg_lo:[0,1] neg_hi:[0,1]
	ds_write2_b64 v26, v[36:37], v[22:23] offset1:1
	v_add_u32_e32 v22, 0x200, v1
	v_and_b32_e32 v23, -8, v22
	v_lshlrev_b32_e32 v22, 4, v22
	v_add3_u32 v26, 0, v23, v22
	ds_read2_b64 v[22:25], v26 offset1:1
	v_lshlrev_b32_e32 v36, 16, v98
	v_and_b32_e32 v37, 0xffff0000, v98
	v_and_b32_e32 v41, 0xffff0000, v99
	s_waitcnt lgkmcnt(0)
	v_pk_add_f32 v[42:43], v[22:23], v[24:25]
	v_pk_add_f32 v[22:23], v[22:23], v[24:25] neg_lo:[0,1] neg_hi:[0,1]
	v_pk_mul_f32 v[24:25], v[42:43], v[36:37] op_sel:[0,0] op_sel_hi:[0,1]
	s_nop 0
	v_pk_fma_f32 v[24:25], v[42:43], v[36:37], v[24:25] op_sel:[1,1,0] op_sel_hi:[1,0,1] neg_lo:[1,0,0]
	v_pk_mul_f32 v[36:37], v[22:23], v[40:41] op_sel:[0,0] op_sel_hi:[0,1]
	s_nop 0
	v_pk_fma_f32 v[22:23], v[22:23], v[40:41], v[36:37] op_sel:[1,1,0] op_sel_hi:[1,0,1] neg_lo:[1,0,0]
	s_waitcnt vmcnt(1)
	v_lshlrev_b32_e32 v40, 16, v97
	v_pk_add_f32 v[36:37], v[24:25], v[22:23]
	v_pk_add_f32 v[22:23], v[24:25], v[22:23] neg_lo:[0,1] neg_hi:[0,1]
	ds_write2_b64 v26, v[36:37], v[22:23] offset1:1
	v_add_u32_e32 v22, 0x400, v1
	v_and_b32_e32 v23, -8, v22
	v_lshlrev_b32_e32 v22, 4, v22
	v_add3_u32 v26, 0, v23, v22
	ds_read2_b64 v[22:25], v26 offset1:1
	v_lshlrev_b32_e32 v36, 16, v96
	v_and_b32_e32 v37, 0xffff0000, v96
	v_and_b32_e32 v41, 0xffff0000, v97
	s_waitcnt lgkmcnt(0)
	v_pk_add_f32 v[42:43], v[22:23], v[24:25]
	v_pk_add_f32 v[22:23], v[22:23], v[24:25] neg_lo:[0,1] neg_hi:[0,1]
	v_pk_mul_f32 v[24:25], v[42:43], v[36:37] op_sel:[0,0] op_sel_hi:[0,1]
	s_nop 0
	v_pk_fma_f32 v[24:25], v[42:43], v[36:37], v[24:25] op_sel:[1,1,0] op_sel_hi:[1,0,1] neg_lo:[1,0,0]
	v_pk_mul_f32 v[36:37], v[22:23], v[40:41] op_sel:[0,0] op_sel_hi:[0,1]
	s_nop 0
	v_pk_fma_f32 v[22:23], v[22:23], v[40:41], v[36:37] op_sel:[1,1,0] op_sel_hi:[1,0,1] neg_lo:[1,0,0]
	v_lshlrev_b32_e32 v40, 16, v91
	v_pk_add_f32 v[36:37], v[24:25], v[22:23]
	v_pk_add_f32 v[22:23], v[24:25], v[22:23] neg_lo:[0,1] neg_hi:[0,1]
	ds_write2_b64 v26, v[36:37], v[22:23] offset1:1
	v_add_u32_e32 v22, 0x600, v1
	v_and_b32_e32 v23, -8, v22
	v_lshlrev_b32_e32 v22, 4, v22
	v_add3_u32 v26, 0, v23, v22
	ds_read2_b64 v[22:25], v26 offset1:1
	v_lshlrev_b32_e32 v36, 16, v90
	v_and_b32_e32 v37, 0xffff0000, v90
	v_and_b32_e32 v41, 0xffff0000, v91
	s_waitcnt lgkmcnt(0)
	v_pk_add_f32 v[42:43], v[22:23], v[24:25]
	v_pk_add_f32 v[22:23], v[22:23], v[24:25] neg_lo:[0,1] neg_hi:[0,1]
	v_pk_mul_f32 v[24:25], v[42:43], v[36:37] op_sel:[0,0] op_sel_hi:[0,1]
	s_nop 0
	v_pk_fma_f32 v[24:25], v[42:43], v[36:37], v[24:25] op_sel:[1,1,0] op_sel_hi:[1,0,1] neg_lo:[1,0,0]
	v_pk_mul_f32 v[36:37], v[22:23], v[40:41] op_sel:[0,0] op_sel_hi:[0,1]
	s_nop 0
	v_pk_fma_f32 v[22:23], v[22:23], v[40:41], v[36:37] op_sel:[1,1,0] op_sel_hi:[1,0,1] neg_lo:[1,0,0]
	v_lshlrev_b32_e32 v40, 16, v89
	v_pk_add_f32 v[36:37], v[24:25], v[22:23]
	v_pk_add_f32 v[22:23], v[24:25], v[22:23] neg_lo:[0,1] neg_hi:[0,1]
	ds_write2_b64 v26, v[36:37], v[22:23] offset1:1
	v_add_u32_e32 v22, 0x800, v1
	v_and_b32_e32 v23, -8, v22
	v_lshlrev_b32_e32 v22, 4, v22
	v_add3_u32 v26, 0, v23, v22
	ds_read2_b64 v[22:25], v26 offset1:1
	v_lshlrev_b32_e32 v36, 16, v88
	v_and_b32_e32 v37, 0xffff0000, v88
	v_and_b32_e32 v41, 0xffff0000, v89
	s_waitcnt lgkmcnt(0)
	v_pk_add_f32 v[42:43], v[22:23], v[24:25]
	v_pk_add_f32 v[22:23], v[22:23], v[24:25] neg_lo:[0,1] neg_hi:[0,1]
	v_pk_mul_f32 v[24:25], v[42:43], v[36:37] op_sel:[0,0] op_sel_hi:[0,1]
	s_nop 0
	v_pk_fma_f32 v[24:25], v[42:43], v[36:37], v[24:25] op_sel:[1,1,0] op_sel_hi:[1,0,1] neg_lo:[1,0,0]
	v_pk_mul_f32 v[36:37], v[22:23], v[40:41] op_sel:[0,0] op_sel_hi:[0,1]
	s_nop 0
	v_pk_fma_f32 v[22:23], v[22:23], v[40:41], v[36:37] op_sel:[1,1,0] op_sel_hi:[1,0,1] neg_lo:[1,0,0]
	v_lshlrev_b32_e32 v40, 16, v87
	v_pk_add_f32 v[36:37], v[24:25], v[22:23]
	v_pk_add_f32 v[22:23], v[24:25], v[22:23] neg_lo:[0,1] neg_hi:[0,1]
	ds_write2_b64 v26, v[36:37], v[22:23] offset1:1
	v_add_u32_e32 v22, 0xa00, v1
	v_and_b32_e32 v23, -8, v22
	v_lshlrev_b32_e32 v22, 4, v22
	v_add3_u32 v26, 0, v23, v22
	ds_read2_b64 v[22:25], v26 offset1:1
	v_lshlrev_b32_e32 v36, 16, v86
	v_and_b32_e32 v37, 0xffff0000, v86
	v_and_b32_e32 v41, 0xffff0000, v87
	s_waitcnt lgkmcnt(0)
	v_pk_add_f32 v[42:43], v[22:23], v[24:25]
	v_pk_add_f32 v[22:23], v[22:23], v[24:25] neg_lo:[0,1] neg_hi:[0,1]
	v_pk_mul_f32 v[24:25], v[42:43], v[36:37] op_sel:[0,0] op_sel_hi:[0,1]
	s_nop 0
	v_pk_fma_f32 v[24:25], v[42:43], v[36:37], v[24:25] op_sel:[1,1,0] op_sel_hi:[1,0,1] neg_lo:[1,0,0]
	v_pk_mul_f32 v[36:37], v[22:23], v[40:41] op_sel:[0,0] op_sel_hi:[0,1]
	s_nop 0
	v_pk_fma_f32 v[22:23], v[22:23], v[40:41], v[36:37] op_sel:[1,1,0] op_sel_hi:[1,0,1] neg_lo:[1,0,0]
	v_lshlrev_b32_e32 v40, 16, v65
	v_pk_add_f32 v[36:37], v[24:25], v[22:23]
	v_pk_add_f32 v[22:23], v[24:25], v[22:23] neg_lo:[0,1] neg_hi:[0,1]
	ds_write2_b64 v26, v[36:37], v[22:23] offset1:1
	v_add_u32_e32 v22, 0xc00, v1
	v_and_b32_e32 v23, -8, v22
	v_lshlrev_b32_e32 v22, 4, v22
	v_add3_u32 v26, 0, v23, v22
	ds_read2_b64 v[22:25], v26 offset1:1
	v_lshlrev_b32_e32 v36, 16, v64
	v_and_b32_e32 v37, 0xffff0000, v64
	v_and_b32_e32 v41, 0xffff0000, v65
	v_add_u32_e32 v1, 0xe00, v1
	s_waitcnt lgkmcnt(0)
	v_pk_add_f32 v[42:43], v[22:23], v[24:25]
	v_pk_add_f32 v[22:23], v[22:23], v[24:25] neg_lo:[0,1] neg_hi:[0,1]
	v_pk_mul_f32 v[24:25], v[42:43], v[36:37] op_sel:[0,0] op_sel_hi:[0,1]
	s_nop 0
	v_pk_fma_f32 v[24:25], v[42:43], v[36:37], v[24:25] op_sel:[1,1,0] op_sel_hi:[1,0,1] neg_lo:[1,0,0]
	v_pk_mul_f32 v[36:37], v[22:23], v[40:41] op_sel:[0,0] op_sel_hi:[0,1]
	s_nop 0
	v_pk_fma_f32 v[22:23], v[22:23], v[40:41], v[36:37] op_sel:[1,1,0] op_sel_hi:[1,0,1] neg_lo:[1,0,0]
	s_waitcnt vmcnt(0)
	v_lshlrev_b32_e32 v40, 16, v61
	v_pk_add_f32 v[36:37], v[24:25], v[22:23]
	v_pk_add_f32 v[22:23], v[24:25], v[22:23] neg_lo:[0,1] neg_hi:[0,1]
	ds_write2_b64 v26, v[36:37], v[22:23] offset1:1
	v_and_b32_e32 v22, -8, v1
	v_lshlrev_b32_e32 v1, 4, v1
	v_add3_u32 v1, 0, v22, v1
	ds_read2_b64 v[22:25], v1 offset1:1
	v_lshlrev_b32_e32 v36, 16, v60
	v_and_b32_e32 v37, 0xffff0000, v60
	v_and_b32_e32 v41, 0xffff0000, v61
	s_waitcnt lgkmcnt(0)
	v_pk_add_f32 v[42:43], v[22:23], v[24:25]
	v_pk_add_f32 v[22:23], v[22:23], v[24:25] neg_lo:[0,1] neg_hi:[0,1]
	v_pk_mul_f32 v[24:25], v[42:43], v[36:37] op_sel:[0,0] op_sel_hi:[0,1]
	s_nop 0
	v_pk_fma_f32 v[24:25], v[42:43], v[36:37], v[24:25] op_sel:[1,1,0] op_sel_hi:[1,0,1] neg_lo:[1,0,0]
	v_pk_mul_f32 v[36:37], v[22:23], v[40:41] op_sel:[0,0] op_sel_hi:[0,1]
	s_nop 0
	v_pk_fma_f32 v[22:23], v[22:23], v[40:41], v[36:37] op_sel:[1,1,0] op_sel_hi:[1,0,1] neg_lo:[1,0,0]
	s_nop 0
	v_pk_add_f32 v[36:37], v[24:25], v[22:23]
	v_pk_add_f32 v[22:23], v[24:25], v[22:23] neg_lo:[0,1] neg_hi:[0,1]
	ds_write2_b64 v1, v[36:37], v[22:23] offset1:1
	v_mov_b32_e32 v1, v0
	s_waitcnt lgkmcnt(0)
	s_barrier
	s_nop 0
	v_and_b32_e32 v22, 1, v1
	v_lshlrev_b32_e32 v1, 4, v1
	v_and_b32_e32 v1, 0xffffffe0, v1
	v_ashrrev_i32_e32 v23, 1, v1
	v_lshlrev_b32_e32 v24, 3, v22
	v_cvt_f32_ubyte0_e32 v22, v22
	v_add_u32_e32 v23, 0, v23
	v_lshlrev_b32_e32 v1, 3, v1
	v_mul_f32_e32 v22, 0x3d000000, v22
	v_add3_u32 v1, v23, v1, v24
	v_cos_f32_e32 v36, v22
	v_sin_f32_e32 v37, v22
	ds_read2_b64 v[22:25], v1 offset1:2
	ds_read2_b64 v[40:43], v1 offset0:4 offset1:6
	ds_read2_b64 v[86:89], v1 offset0:8 offset1:10
	ds_read2_b64 v[96:99], v1 offset0:12 offset1:14
	ds_read2_b64 v[100:103], v1 offset0:17 offset1:19
	ds_read2_b64 v[104:107], v1 offset0:21 offset1:23
	ds_read2_b64 v[108:111], v1 offset0:25 offset1:27
	ds_read2_b64 v[112:115], v1 offset0:29 offset1:31
	s_nop 1
	s_nop 0
	v_pk_mul_f32 v[44:45], v[36:37], v[36:37] op_sel:[0,0] op_sel_hi:[0,1]
	s_waitcnt lgkmcnt(7)
	v_pk_mul_f32 v[136:137], v[24:25], v[36:37] op_sel:[0,0] op_sel_hi:[0,1]
	v_pk_fma_f32 v[44:45], v[36:37], v[36:37], v[44:45] op_sel:[1,1,0] op_sel_hi:[1,0,1] neg_lo:[1,0,0]
	s_nop 0
	v_pk_fma_f32 v[24:25], v[24:25], v[36:37], v[136:137] op_sel:[1,1,0] op_sel_hi:[1,0,1] neg_lo:[1,0,0]
	v_pk_mul_f32 v[64:65], v[44:45], v[44:45] op_sel:[0,0] op_sel_hi:[0,1]
	v_pk_mul_f32 v[60:61], v[44:45], v[36:37] op_sel:[0,0] op_sel_hi:[0,1]
	s_nop 0
	v_pk_fma_f32 v[64:65], v[44:45], v[44:45], v[64:65] op_sel:[1,1,0] op_sel_hi:[1,0,1] neg_lo:[1,0,0]
	v_pk_fma_f32 v[60:61], v[44:45], v[36:37], v[60:61] op_sel:[1,1,0] op_sel_hi:[1,0,1] neg_lo:[1,0,0]
	s_nop 0
	v_pk_mul_f32 v[120:121], v[64:65], v[64:65] op_sel:[0,0] op_sel_hi:[0,1]
	v_pk_mul_f32 v[90:91], v[64:65], v[36:37] op_sel:[0,0] op_sel_hi:[0,1]
	v_pk_mul_f32 v[116:117], v[60:61], v[60:61] op_sel:[0,0] op_sel_hi:[0,1]
	v_pk_mul_f32 v[118:119], v[64:65], v[60:61] op_sel:[0,0] op_sel_hi:[0,1]
	s_nop 0
	v_pk_fma_f32 v[120:121], v[64:65], v[64:65], v[120:121] op_sel:[1,1,0] op_sel_hi:[1,0,1] neg_lo:[1,0,0]
	v_pk_fma_f32 v[90:91], v[64:65], v[36:37], v[90:91] op_sel:[1,1,0] op_sel_hi:[1,0,1] neg_lo:[1,0,0]
	v_pk_fma_f32 v[116:117], v[60:61], v[60:61], v[116:117] op_sel:[1,1,0] op_sel_hi:[1,0,1] neg_lo:[1,0,0]
	v_pk_fma_f32 v[118:119], v[64:65], v[60:61], v[118:119] op_sel:[1,1,0] op_sel_hi:[1,0,1] neg_lo:[1,0,0]
	s_nop 0
	v_pk_mul_f32 v[122:123], v[120:121], v[36:37] op_sel:[0,0] op_sel_hi:[0,1]
	v_pk_mul_f32 v[126:127], v[120:121], v[60:61] op_sel:[0,0] op_sel_hi:[0,1]
	v_pk_mul_f32 v[128:129], v[116:117], v[116:117] op_sel:[0,0] op_sel_hi:[0,1]
	v_pk_mul_f32 v[130:131], v[120:121], v[90:91] op_sel:[0,0] op_sel_hi:[0,1]
	v_pk_mul_f32 v[124:125], v[90:91], v[90:91] op_sel:[0,0] op_sel_hi:[0,1]
	v_pk_mul_f32 v[132:133], v[118:119], v[118:119] op_sel:[0,0] op_sel_hi:[0,1]
	s_nop 0
	v_pk_fma_f32 v[122:123], v[120:121], v[36:37], v[122:123] op_sel:[1,1,0] op_sel_hi:[1,0,1] neg_lo:[1,0,0]
	s_waitcnt lgkmcnt(6)
	v_pk_mul_f32 v[36:37], v[40:41], v[44:45] op_sel:[0,0] op_sel_hi:[0,1]
	v_pk_fma_f32 v[126:127], v[120:121], v[60:61], v[126:127] op_sel:[1,1,0] op_sel_hi:[1,0,1] neg_lo:[1,0,0]
	v_pk_fma_f32 v[128:129], v[116:117], v[116:117], v[128:129] op_sel:[1,1,0] op_sel_hi:[1,0,1] neg_lo:[1,0,0]
	v_pk_fma_f32 v[130:131], v[120:121], v[90:91], v[130:131] op_sel:[1,1,0] op_sel_hi:[1,0,1] neg_lo:[1,0,0]
	v_pk_fma_f32 v[124:125], v[90:91], v[90:91], v[124:125] op_sel:[1,1,0] op_sel_hi:[1,0,1] neg_lo:[1,0,0]
	v_pk_fma_f32 v[132:133], v[118:119], v[118:119], v[132:133] op_sel:[1,1,0] op_sel_hi:[1,0,1] neg_lo:[1,0,0]
	s_nop 0
	v_pk_fma_f32 v[36:37], v[40:41], v[44:45], v[36:37] op_sel:[1,1,0] op_sel_hi:[1,0,1] neg_lo:[1,0,0]
	v_pk_mul_f32 v[40:41], v[42:43], v[60:61] op_sel:[0,0] op_sel_hi:[0,1]
	s_waitcnt lgkmcnt(5)
	v_pk_mul_f32 v[44:45], v[88:89], v[90:91] op_sel:[0,0] op_sel_hi:[0,1]
	v_pk_mul_f32 v[134:135], v[120:121], v[118:119] op_sel:[0,0] op_sel_hi:[0,1]
	v_pk_fma_f32 v[40:41], v[42:43], v[60:61], v[40:41] op_sel:[1,1,0] op_sel_hi:[1,0,1] neg_lo:[1,0,0]
	v_pk_mul_f32 v[42:43], v[86:87], v[64:65] op_sel:[0,0] op_sel_hi:[0,1]
	s_waitcnt lgkmcnt(4)
	v_pk_mul_f32 v[60:61], v[96:97], v[116:117] op_sel:[0,0] op_sel_hi:[0,1]
	v_pk_fma_f32 v[44:45], v[88:89], v[90:91], v[44:45] op_sel:[1,1,0] op_sel_hi:[1,0,1] neg_lo:[1,0,0]
	s_waitcnt lgkmcnt(3)
	v_pk_mul_f32 v[88:89], v[102:103], v[122:123] op_sel:[0,0] op_sel_hi:[0,1]
	s_waitcnt lgkmcnt(2)
	v_pk_mul_f32 v[90:91], v[104:105], v[124:125] op_sel:[0,0] op_sel_hi:[0,1]
	v_pk_fma_f32 v[134:135], v[120:121], v[118:119], v[134:135] op_sel:[1,1,0] op_sel_hi:[1,0,1] neg_lo:[1,0,0]
	v_pk_fma_f32 v[42:43], v[86:87], v[64:65], v[42:43] op_sel:[1,1,0] op_sel_hi:[1,0,1] neg_lo:[1,0,0]
	v_pk_mul_f32 v[64:65], v[98:99], v[118:119] op_sel:[0,0] op_sel_hi:[0,1]
	v_pk_mul_f32 v[86:87], v[100:101], v[120:121] op_sel:[0,0] op_sel_hi:[0,1]
	v_pk_fma_f32 v[60:61], v[96:97], v[116:117], v[60:61] op_sel:[1,1,0] op_sel_hi:[1,0,1] neg_lo:[1,0,0]
	v_pk_mul_f32 v[96:97], v[106:107], v[126:127] op_sel:[0,0] op_sel_hi:[0,1]
	v_pk_fma_f32 v[88:89], v[102:103], v[122:123], v[88:89] op_sel:[1,1,0] op_sel_hi:[1,0,1] neg_lo:[1,0,0]
	s_waitcnt lgkmcnt(0)
	v_pk_mul_f32 v[102:103], v[112:113], v[132:133] op_sel:[0,0] op_sel_hi:[0,1]
	v_pk_fma_f32 v[64:65], v[98:99], v[118:119], v[64:65] op_sel:[1,1,0] op_sel_hi:[1,0,1] neg_lo:[1,0,0]
	v_pk_fma_f32 v[86:87], v[100:101], v[120:121], v[86:87] op_sel:[1,1,0] op_sel_hi:[1,0,1] neg_lo:[1,0,0]
	v_pk_mul_f32 v[98:99], v[108:109], v[128:129] op_sel:[0,0] op_sel_hi:[0,1]
	v_pk_mul_f32 v[100:101], v[110:111], v[130:131] op_sel:[0,0] op_sel_hi:[0,1]
	v_pk_fma_f32 v[96:97], v[106:107], v[126:127], v[96:97] op_sel:[1,1,0] op_sel_hi:[1,0,1] neg_lo:[1,0,0]
	v_pk_add_f32 v[106:107], v[24:25], v[88:89] neg_lo:[0,1] neg_hi:[0,1]
	v_pk_fma_f32 v[98:99], v[108:109], v[128:129], v[98:99] op_sel:[1,1,0] op_sel_hi:[1,0,1] neg_lo:[1,0,0]
	v_pk_fma_f32 v[100:101], v[110:111], v[130:131], v[100:101] op_sel:[1,1,0] op_sel_hi:[1,0,1] neg_lo:[1,0,0]
	v_pk_fma_f32 v[90:91], v[104:105], v[124:125], v[90:91] op_sel:[1,1,0] op_sel_hi:[1,0,1] neg_lo:[1,0,0]
	v_pk_fma_f32 v[102:103], v[112:113], v[132:133], v[102:103] op_sel:[1,1,0] op_sel_hi:[1,0,1] neg_lo:[1,0,0]
	v_pk_mul_f32 v[104:105], v[114:115], v[134:135] op_sel:[0,0] op_sel_hi:[0,1]
	v_pk_add_f32 v[24:25], v[24:25], v[88:89]
	v_pk_add_f32 v[108:109], v[44:45], v[100:101] neg_lo:[0,1] neg_hi:[0,1]
	v_pk_add_f32 v[112:113], v[60:61], v[102:103] neg_lo:[0,1] neg_hi:[0,1]
	v_pk_add_f32 v[110:111], v[106:107], v[108:109] op_sel:[0,1] op_sel_hi:[1,0] neg_lo:[0,1] neg_hi:[0,1]
	v_pk_add_f32 v[106:107], v[106:107], v[108:109] op_sel:[0,1] op_sel_hi:[1,0]
	v_mov_b32_e32 v108, v110
	v_mov_b32_e32 v109, v107
	v_mov_b32_e32 v107, v111
	v_pk_add_f32 v[110:111], v[36:37], v[90:91] neg_lo:[0,1] neg_hi:[0,1]
	v_pk_fma_f32 v[104:105], v[114:115], v[134:135], v[104:105] op_sel:[1,1,0] op_sel_hi:[1,0,1] neg_lo:[1,0,0]
	v_pk_add_f32 v[44:45], v[44:45], v[100:101]
	v_pk_add_f32 v[114:115], v[110:111], v[112:113] op_sel:[0,1] op_sel_hi:[1,0] neg_lo:[0,1] neg_hi:[0,1]
	v_pk_add_f32 v[110:111], v[110:111], v[112:113] op_sel:[0,1] op_sel_hi:[1,0]
	v_mov_b32_e32 v112, v114
	v_mov_b32_e32 v113, v111
	v_mov_b32_e32 v111, v115
	v_pk_add_f32 v[114:115], v[40:41], v[96:97] neg_lo:[0,1] neg_hi:[0,1]
	v_pk_add_f32 v[116:117], v[64:65], v[104:105] neg_lo:[0,1] neg_hi:[0,1]
	v_pk_add_f32 v[88:89], v[24:25], v[44:45]
	v_pk_add_f32 v[118:119], v[114:115], v[116:117] op_sel:[0,1] op_sel_hi:[1,0] neg_lo:[0,1] neg_hi:[0,1]
	v_pk_add_f32 v[114:115], v[114:115], v[116:117] op_sel:[0,1] op_sel_hi:[1,0]
	v_mov_b32_e32 v116, v118
	v_mov_b32_e32 v117, v115
	v_mov_b32_e32 v115, v119
	v_pk_mul_f32 v[118:119], v[108:109], v[38:39] op_sel:[0,0] op_sel_hi:[0,1]
	v_pk_add_f32 v[24:25], v[24:25], v[44:45] neg_lo:[0,1] neg_hi:[0,1]
	v_pk_add_f32 v[36:37], v[36:37], v[90:91]
	v_pk_add_f32 v[44:45], v[60:61], v[102:103]
	v_pk_fma_f32 v[108:109], v[108:109], v[38:39], v[118:119] op_sel:[1,1,0] op_sel_hi:[1,0,1] neg_lo:[1,0,0]
	v_pk_mul_f32 v[118:119], v[112:113], v[34:35] op_sel:[0,0] op_sel_hi:[0,1]
	v_pk_add_f32 v[40:41], v[40:41], v[96:97]
	v_pk_add_f32 v[60:61], v[36:37], v[44:45]
	v_pk_add_f32 v[36:37], v[36:37], v[44:45] neg_lo:[0,1] neg_hi:[0,1]
	v_pk_add_f32 v[44:45], v[64:65], v[104:105]
	v_pk_fma_f32 v[112:113], v[112:113], v[34:35], v[118:119] op_sel:[1,1,0] op_sel_hi:[1,0,1] neg_lo:[1,0,0]
	v_pk_mul_f32 v[118:119], v[116:117], v[20:21] op_sel:[0,0] op_sel_hi:[0,1]
	v_pk_add_f32 v[120:121], v[42:43], v[98:99]
	v_pk_add_f32 v[64:65], v[40:41], v[44:45]
	v_pk_add_f32 v[40:41], v[40:41], v[44:45] neg_lo:[0,1] neg_hi:[0,1]
	v_pk_mul_f32 v[44:45], v[24:25], v[34:35] op_sel:[0,0] op_sel_hi:[0,1]
	v_pk_fma_f32 v[116:117], v[116:117], v[20:21], v[118:119] op_sel:[1,1,0] op_sel_hi:[1,0,1] neg_lo:[1,0,0]
	v_pk_add_f32 v[118:119], v[22:23], v[86:87]
	v_pk_fma_f32 v[24:25], v[24:25], v[34:35], v[44:45] op_sel:[1,1,0] op_sel_hi:[1,0,1] neg_lo:[1,0,0]
	v_pk_mul_f32 v[44:45], v[36:37], v[46:47] op_sel:[0,0] op_sel_hi:[0,1]
	v_pk_add_f32 v[22:23], v[22:23], v[86:87] neg_lo:[0,1] neg_hi:[0,1]
	v_pk_add_f32 v[42:43], v[42:43], v[98:99] neg_lo:[0,1] neg_hi:[0,1]
	v_pk_add_f32 v[122:123], v[118:119], v[120:121]
	v_pk_fma_f32 v[36:37], v[36:37], v[46:47], v[44:45] op_sel:[1,1,0] op_sel_hi:[1,0,1] neg_lo:[1,0,0]
	v_pk_mul_f32 v[44:45], v[40:41], v[48:49] op_sel:[0,0] op_sel_hi:[0,1]
	v_pk_add_f32 v[86:87], v[22:23], v[42:43] op_sel:[0,1] op_sel_hi:[1,0] neg_lo:[0,1] neg_hi:[0,1]
	v_pk_add_f32 v[22:23], v[22:23], v[42:43] op_sel:[0,1] op_sel_hi:[1,0]
	v_pk_fma_f32 v[40:41], v[40:41], v[48:49], v[44:45] op_sel:[1,1,0] op_sel_hi:[1,0,1] neg_lo:[1,0,0]
	v_pk_mul_f32 v[44:45], v[106:107], v[20:21] op_sel:[0,0] op_sel_hi:[0,1]
	v_pk_mul_f32 v[90:91], v[110:111], v[48:49] op_sel:[0,0] op_sel_hi:[0,1]
	v_pk_add_f32 v[100:101], v[122:123], v[60:61]
	v_pk_add_f32 v[102:103], v[88:89], v[64:65]
	v_mov_b32_e32 v42, v86
	v_mov_b32_e32 v43, v23
	v_pk_fma_f32 v[44:45], v[106:107], v[20:21], v[44:45] op_sel:[1,1,0] op_sel_hi:[1,0,1] neg_lo:[1,0,0]
	v_pk_fma_f32 v[90:91], v[110:111], v[48:49], v[90:91] op_sel:[1,1,0] op_sel_hi:[1,0,1] neg_lo:[1,0,0]
	v_pk_mul_f32 v[96:97], v[114:115], v[58:59] op_sel:[0,0] op_sel_hi:[0,1]
	v_pk_add_f32 v[104:105], v[100:101], v[102:103]
	v_pk_add_f32 v[100:101], v[100:101], v[102:103] neg_lo:[0,1] neg_hi:[0,1]
	v_pk_add_f32 v[98:99], v[42:43], v[112:113]
	v_pk_add_f32 v[102:103], v[108:109], v[116:117]
	v_pk_add_f32 v[110:111], v[118:119], v[120:121] neg_lo:[0,1] neg_hi:[0,1]
	v_mov_b32_e32 v23, v87
	v_pk_fma_f32 v[96:97], v[114:115], v[58:59], v[96:97] op_sel:[1,1,0] op_sel_hi:[1,0,1] neg_lo:[1,0,0]
	v_pk_add_f32 v[60:61], v[122:123], v[60:61] neg_lo:[0,1] neg_hi:[0,1]
	v_pk_add_f32 v[64:65], v[88:89], v[64:65] neg_lo:[0,1] neg_hi:[0,1]
	v_pk_add_f32 v[106:107], v[98:99], v[102:103]
	v_pk_add_f32 v[98:99], v[98:99], v[102:103] neg_lo:[0,1] neg_hi:[0,1]
	v_pk_add_f32 v[102:103], v[108:109], v[116:117] neg_lo:[0,1] neg_hi:[0,1]
	v_pk_add_f32 v[42:43], v[42:43], v[112:113] neg_lo:[0,1] neg_hi:[0,1]
	v_pk_add_f32 v[112:113], v[110:111], v[36:37]
	v_pk_add_f32 v[114:115], v[24:25], v[40:41]
	v_pk_add_f32 v[24:25], v[24:25], v[40:41] neg_lo:[0,1] neg_hi:[0,1]
	v_pk_add_f32 v[36:37], v[110:111], v[36:37] neg_lo:[0,1] neg_hi:[0,1]
	v_pk_add_f32 v[86:87], v[22:23], v[90:91]
	v_pk_add_f32 v[110:111], v[44:45], v[96:97]
	v_pk_add_f32 v[44:45], v[44:45], v[96:97] neg_lo:[0,1] neg_hi:[0,1]
	v_pk_add_f32 v[22:23], v[22:23], v[90:91] neg_lo:[0,1] neg_hi:[0,1]
	v_pk_add_f32 v[88:89], v[60:61], v[64:65] op_sel:[0,1] op_sel_hi:[1,0] neg_lo:[0,1] neg_hi:[0,1]
	v_pk_add_f32 v[60:61], v[60:61], v[64:65] op_sel:[0,1] op_sel_hi:[1,0]
	v_pk_add_f32 v[108:109], v[42:43], v[102:103] op_sel:[0,1] op_sel_hi:[1,0] neg_lo:[0,1] neg_hi:[0,1]
	v_pk_add_f32 v[42:43], v[42:43], v[102:103] op_sel:[0,1] op_sel_hi:[1,0]
	v_pk_add_f32 v[40:41], v[36:37], v[24:25] op_sel:[0,1] op_sel_hi:[1,0] neg_lo:[0,1] neg_hi:[0,1]
	v_pk_add_f32 v[24:25], v[36:37], v[24:25] op_sel:[0,1] op_sel_hi:[1,0]
	v_pk_add_f32 v[90:91], v[22:23], v[44:45] op_sel:[0,1] op_sel_hi:[1,0] neg_lo:[0,1] neg_hi:[0,1]
	v_pk_add_f32 v[22:23], v[22:23], v[44:45] op_sel:[0,1] op_sel_hi:[1,0]
	v_mov_b32_e32 v65, v61
	v_mov_b32_e32 v103, v43
	v_mov_b32_e32 v37, v25
	v_mov_b32_e32 v45, v23
	v_mov_b32_e32 v61, v89
	v_mov_b32_e32 v43, v109
	v_mov_b32_e32 v25, v41
	v_mov_b32_e32 v23, v91
	v_mov_b32_e32 v64, v88
	v_mov_b32_e32 v102, v108
	v_pk_add_f32 v[116:117], v[112:113], v[114:115]
	v_pk_add_f32 v[112:113], v[112:113], v[114:115] neg_lo:[0,1] neg_hi:[0,1]
	v_mov_b32_e32 v36, v40
	v_pk_add_f32 v[114:115], v[86:87], v[110:111]
	v_pk_add_f32 v[86:87], v[86:87], v[110:111] neg_lo:[0,1] neg_hi:[0,1]
	v_mov_b32_e32 v44, v90
	ds_write2_b64 v1, v[104:105], v[106:107] offset1:2
	ds_write2_b64 v1, v[116:117], v[114:115] offset0:4 offset1:6
	ds_write2_b64 v1, v[64:65], v[102:103] offset0:8 offset1:10
	ds_write2_b64 v1, v[36:37], v[44:45] offset0:12 offset1:14
	ds_write2_b64 v1, v[100:101], v[98:99] offset0:17 offset1:19
	ds_write2_b64 v1, v[112:113], v[86:87] offset0:21 offset1:23
	ds_write2_b64 v1, v[60:61], v[42:43] offset0:25 offset1:27
	ds_write2_b64 v1, v[24:25], v[22:23] offset0:29 offset1:31
	v_mov_b32_e32 v1, v0
	s_waitcnt lgkmcnt(0)
	s_barrier
	s_nop 0
	v_and_b32_e32 v22, 31, v1
	v_lshlrev_b32_e32 v1, 4, v1
	v_and_or_b32 v1, v1, s25, v22
	v_ashrrev_i32_e32 v23, 4, v1
	v_lshlrev_b32_e32 v23, 3, v23
	v_lshlrev_b32_e32 v1, 3, v1
	v_cvt_f32_ubyte0_e32 v22, v22
	v_add3_u32 v1, 0, v23, v1
	v_mul_f32_e32 v22, 0x3b000000, v22
	v_cos_f32_e32 v36, v22
	v_sin_f32_e32 v37, v22
	v_add_u32_e32 v26, 0x800, v1
	ds_read2_b64 v[22:25], v1 offset1:34
	ds_read2_b64 v[40:43], v1 offset0:68 offset1:102
	ds_read2_b64 v[86:89], v1 offset0:136 offset1:170
	ds_read2_b64 v[96:99], v1 offset0:204 offset1:238
	ds_read2_b64 v[100:103], v26 offset0:16 offset1:50
	ds_read2_b64 v[104:107], v26 offset0:84 offset1:118
	ds_read2_b64 v[108:111], v26 offset0:152 offset1:186
	ds_read2_b64 v[112:115], v26 offset0:220 offset1:254
	s_nop 1
	s_nop 0
	v_pk_mul_f32 v[44:45], v[36:37], v[36:37] op_sel:[0,0] op_sel_hi:[0,1]
	s_waitcnt lgkmcnt(7)
	v_pk_mul_f32 v[136:137], v[24:25], v[36:37] op_sel:[0,0] op_sel_hi:[0,1]
	v_pk_fma_f32 v[44:45], v[36:37], v[36:37], v[44:45] op_sel:[1,1,0] op_sel_hi:[1,0,1] neg_lo:[1,0,0]
	s_nop 0
	v_pk_fma_f32 v[24:25], v[24:25], v[36:37], v[136:137] op_sel:[1,1,0] op_sel_hi:[1,0,1] neg_lo:[1,0,0]
	v_pk_mul_f32 v[64:65], v[44:45], v[44:45] op_sel:[0,0] op_sel_hi:[0,1]
	v_pk_mul_f32 v[60:61], v[44:45], v[36:37] op_sel:[0,0] op_sel_hi:[0,1]
	s_nop 0
	v_pk_fma_f32 v[64:65], v[44:45], v[44:45], v[64:65] op_sel:[1,1,0] op_sel_hi:[1,0,1] neg_lo:[1,0,0]
	v_pk_fma_f32 v[60:61], v[44:45], v[36:37], v[60:61] op_sel:[1,1,0] op_sel_hi:[1,0,1] neg_lo:[1,0,0]
	s_nop 0
	v_pk_mul_f32 v[120:121], v[64:65], v[64:65] op_sel:[0,0] op_sel_hi:[0,1]
	v_pk_mul_f32 v[90:91], v[64:65], v[36:37] op_sel:[0,0] op_sel_hi:[0,1]
	v_pk_mul_f32 v[116:117], v[60:61], v[60:61] op_sel:[0,0] op_sel_hi:[0,1]
	v_pk_mul_f32 v[118:119], v[64:65], v[60:61] op_sel:[0,0] op_sel_hi:[0,1]
	s_nop 0
	v_pk_fma_f32 v[120:121], v[64:65], v[64:65], v[120:121] op_sel:[1,1,0] op_sel_hi:[1,0,1] neg_lo:[1,0,0]
	v_pk_fma_f32 v[90:91], v[64:65], v[36:37], v[90:91] op_sel:[1,1,0] op_sel_hi:[1,0,1] neg_lo:[1,0,0]
	v_pk_fma_f32 v[116:117], v[60:61], v[60:61], v[116:117] op_sel:[1,1,0] op_sel_hi:[1,0,1] neg_lo:[1,0,0]
	v_pk_fma_f32 v[118:119], v[64:65], v[60:61], v[118:119] op_sel:[1,1,0] op_sel_hi:[1,0,1] neg_lo:[1,0,0]
	s_nop 0
	v_pk_mul_f32 v[122:123], v[120:121], v[36:37] op_sel:[0,0] op_sel_hi:[0,1]
	v_pk_mul_f32 v[126:127], v[120:121], v[60:61] op_sel:[0,0] op_sel_hi:[0,1]
	v_pk_mul_f32 v[128:129], v[116:117], v[116:117] op_sel:[0,0] op_sel_hi:[0,1]
	v_pk_mul_f32 v[130:131], v[120:121], v[90:91] op_sel:[0,0] op_sel_hi:[0,1]
	v_pk_mul_f32 v[124:125], v[90:91], v[90:91] op_sel:[0,0] op_sel_hi:[0,1]
	v_pk_mul_f32 v[132:133], v[118:119], v[118:119] op_sel:[0,0] op_sel_hi:[0,1]
	s_nop 0
	v_pk_fma_f32 v[122:123], v[120:121], v[36:37], v[122:123] op_sel:[1,1,0] op_sel_hi:[1,0,1] neg_lo:[1,0,0]
	s_waitcnt lgkmcnt(6)
	v_pk_mul_f32 v[36:37], v[40:41], v[44:45] op_sel:[0,0] op_sel_hi:[0,1]
	v_pk_fma_f32 v[126:127], v[120:121], v[60:61], v[126:127] op_sel:[1,1,0] op_sel_hi:[1,0,1] neg_lo:[1,0,0]
	v_pk_fma_f32 v[128:129], v[116:117], v[116:117], v[128:129] op_sel:[1,1,0] op_sel_hi:[1,0,1] neg_lo:[1,0,0]
	v_pk_fma_f32 v[130:131], v[120:121], v[90:91], v[130:131] op_sel:[1,1,0] op_sel_hi:[1,0,1] neg_lo:[1,0,0]
	v_pk_fma_f32 v[124:125], v[90:91], v[90:91], v[124:125] op_sel:[1,1,0] op_sel_hi:[1,0,1] neg_lo:[1,0,0]
	v_pk_fma_f32 v[132:133], v[118:119], v[118:119], v[132:133] op_sel:[1,1,0] op_sel_hi:[1,0,1] neg_lo:[1,0,0]
	s_nop 0
	v_pk_fma_f32 v[36:37], v[40:41], v[44:45], v[36:37] op_sel:[1,1,0] op_sel_hi:[1,0,1] neg_lo:[1,0,0]
	v_pk_mul_f32 v[40:41], v[42:43], v[60:61] op_sel:[0,0] op_sel_hi:[0,1]
	s_waitcnt lgkmcnt(5)
	v_pk_mul_f32 v[44:45], v[88:89], v[90:91] op_sel:[0,0] op_sel_hi:[0,1]
	v_pk_mul_f32 v[134:135], v[120:121], v[118:119] op_sel:[0,0] op_sel_hi:[0,1]
	v_pk_fma_f32 v[40:41], v[42:43], v[60:61], v[40:41] op_sel:[1,1,0] op_sel_hi:[1,0,1] neg_lo:[1,0,0]
	v_pk_mul_f32 v[42:43], v[86:87], v[64:65] op_sel:[0,0] op_sel_hi:[0,1]
	s_waitcnt lgkmcnt(4)
	v_pk_mul_f32 v[60:61], v[96:97], v[116:117] op_sel:[0,0] op_sel_hi:[0,1]
	v_pk_fma_f32 v[44:45], v[88:89], v[90:91], v[44:45] op_sel:[1,1,0] op_sel_hi:[1,0,1] neg_lo:[1,0,0]
	s_waitcnt lgkmcnt(3)
	v_pk_mul_f32 v[88:89], v[102:103], v[122:123] op_sel:[0,0] op_sel_hi:[0,1]
	s_waitcnt lgkmcnt(2)
	v_pk_mul_f32 v[90:91], v[104:105], v[124:125] op_sel:[0,0] op_sel_hi:[0,1]
	v_pk_fma_f32 v[134:135], v[120:121], v[118:119], v[134:135] op_sel:[1,1,0] op_sel_hi:[1,0,1] neg_lo:[1,0,0]
	v_pk_fma_f32 v[42:43], v[86:87], v[64:65], v[42:43] op_sel:[1,1,0] op_sel_hi:[1,0,1] neg_lo:[1,0,0]
	v_pk_mul_f32 v[64:65], v[98:99], v[118:119] op_sel:[0,0] op_sel_hi:[0,1]
	v_pk_mul_f32 v[86:87], v[100:101], v[120:121] op_sel:[0,0] op_sel_hi:[0,1]
	v_pk_fma_f32 v[60:61], v[96:97], v[116:117], v[60:61] op_sel:[1,1,0] op_sel_hi:[1,0,1] neg_lo:[1,0,0]
	v_pk_mul_f32 v[96:97], v[106:107], v[126:127] op_sel:[0,0] op_sel_hi:[0,1]
	v_pk_fma_f32 v[88:89], v[102:103], v[122:123], v[88:89] op_sel:[1,1,0] op_sel_hi:[1,0,1] neg_lo:[1,0,0]
	s_waitcnt lgkmcnt(0)
	v_pk_mul_f32 v[102:103], v[112:113], v[132:133] op_sel:[0,0] op_sel_hi:[0,1]
	v_pk_fma_f32 v[64:65], v[98:99], v[118:119], v[64:65] op_sel:[1,1,0] op_sel_hi:[1,0,1] neg_lo:[1,0,0]
	v_pk_fma_f32 v[86:87], v[100:101], v[120:121], v[86:87] op_sel:[1,1,0] op_sel_hi:[1,0,1] neg_lo:[1,0,0]
	v_pk_mul_f32 v[98:99], v[108:109], v[128:129] op_sel:[0,0] op_sel_hi:[0,1]
	v_pk_mul_f32 v[100:101], v[110:111], v[130:131] op_sel:[0,0] op_sel_hi:[0,1]
	v_pk_fma_f32 v[96:97], v[106:107], v[126:127], v[96:97] op_sel:[1,1,0] op_sel_hi:[1,0,1] neg_lo:[1,0,0]
	v_pk_add_f32 v[106:107], v[24:25], v[88:89] neg_lo:[0,1] neg_hi:[0,1]
	v_pk_fma_f32 v[98:99], v[108:109], v[128:129], v[98:99] op_sel:[1,1,0] op_sel_hi:[1,0,1] neg_lo:[1,0,0]
	v_pk_fma_f32 v[100:101], v[110:111], v[130:131], v[100:101] op_sel:[1,1,0] op_sel_hi:[1,0,1] neg_lo:[1,0,0]
	v_pk_fma_f32 v[90:91], v[104:105], v[124:125], v[90:91] op_sel:[1,1,0] op_sel_hi:[1,0,1] neg_lo:[1,0,0]
	v_pk_fma_f32 v[102:103], v[112:113], v[132:133], v[102:103] op_sel:[1,1,0] op_sel_hi:[1,0,1] neg_lo:[1,0,0]
	v_pk_mul_f32 v[104:105], v[114:115], v[134:135] op_sel:[0,0] op_sel_hi:[0,1]
	v_pk_add_f32 v[24:25], v[24:25], v[88:89]
	v_pk_add_f32 v[108:109], v[44:45], v[100:101] neg_lo:[0,1] neg_hi:[0,1]
	v_pk_add_f32 v[112:113], v[60:61], v[102:103] neg_lo:[0,1] neg_hi:[0,1]
	v_pk_add_f32 v[110:111], v[106:107], v[108:109] op_sel:[0,1] op_sel_hi:[1,0] neg_lo:[0,1] neg_hi:[0,1]
	v_pk_add_f32 v[106:107], v[106:107], v[108:109] op_sel:[0,1] op_sel_hi:[1,0]
	v_mov_b32_e32 v108, v110
	v_mov_b32_e32 v109, v107
	v_mov_b32_e32 v107, v111
	v_pk_add_f32 v[110:111], v[36:37], v[90:91] neg_lo:[0,1] neg_hi:[0,1]
	v_pk_fma_f32 v[104:105], v[114:115], v[134:135], v[104:105] op_sel:[1,1,0] op_sel_hi:[1,0,1] neg_lo:[1,0,0]
	v_pk_add_f32 v[44:45], v[44:45], v[100:101]
	v_pk_add_f32 v[114:115], v[110:111], v[112:113] op_sel:[0,1] op_sel_hi:[1,0] neg_lo:[0,1] neg_hi:[0,1]
	v_pk_add_f32 v[110:111], v[110:111], v[112:113] op_sel:[0,1] op_sel_hi:[1,0]
	v_mov_b32_e32 v112, v114
	v_mov_b32_e32 v113, v111
	v_mov_b32_e32 v111, v115
	v_pk_add_f32 v[114:115], v[40:41], v[96:97] neg_lo:[0,1] neg_hi:[0,1]
	v_pk_add_f32 v[116:117], v[64:65], v[104:105] neg_lo:[0,1] neg_hi:[0,1]
	v_pk_add_f32 v[88:89], v[24:25], v[44:45]
	v_pk_add_f32 v[118:119], v[114:115], v[116:117] op_sel:[0,1] op_sel_hi:[1,0] neg_lo:[0,1] neg_hi:[0,1]
	v_pk_add_f32 v[114:115], v[114:115], v[116:117] op_sel:[0,1] op_sel_hi:[1,0]
	v_mov_b32_e32 v116, v118
	v_mov_b32_e32 v117, v115
	v_mov_b32_e32 v115, v119
	v_pk_mul_f32 v[118:119], v[108:109], v[38:39] op_sel:[0,0] op_sel_hi:[0,1]
	v_pk_add_f32 v[24:25], v[24:25], v[44:45] neg_lo:[0,1] neg_hi:[0,1]
	v_pk_add_f32 v[36:37], v[36:37], v[90:91]
	v_pk_add_f32 v[44:45], v[60:61], v[102:103]
	v_pk_fma_f32 v[108:109], v[108:109], v[38:39], v[118:119] op_sel:[1,1,0] op_sel_hi:[1,0,1] neg_lo:[1,0,0]
	v_pk_mul_f32 v[118:119], v[112:113], v[34:35] op_sel:[0,0] op_sel_hi:[0,1]
	v_pk_add_f32 v[40:41], v[40:41], v[96:97]
	v_pk_add_f32 v[60:61], v[36:37], v[44:45]
	v_pk_add_f32 v[36:37], v[36:37], v[44:45] neg_lo:[0,1] neg_hi:[0,1]
	v_pk_add_f32 v[44:45], v[64:65], v[104:105]
	v_pk_fma_f32 v[112:113], v[112:113], v[34:35], v[118:119] op_sel:[1,1,0] op_sel_hi:[1,0,1] neg_lo:[1,0,0]
	v_pk_mul_f32 v[118:119], v[116:117], v[20:21] op_sel:[0,0] op_sel_hi:[0,1]
	v_pk_add_f32 v[120:121], v[42:43], v[98:99]
	v_pk_add_f32 v[64:65], v[40:41], v[44:45]
	v_pk_add_f32 v[40:41], v[40:41], v[44:45] neg_lo:[0,1] neg_hi:[0,1]
	v_pk_mul_f32 v[44:45], v[24:25], v[34:35] op_sel:[0,0] op_sel_hi:[0,1]
	v_pk_fma_f32 v[116:117], v[116:117], v[20:21], v[118:119] op_sel:[1,1,0] op_sel_hi:[1,0,1] neg_lo:[1,0,0]
	v_pk_add_f32 v[118:119], v[22:23], v[86:87]
	v_pk_fma_f32 v[24:25], v[24:25], v[34:35], v[44:45] op_sel:[1,1,0] op_sel_hi:[1,0,1] neg_lo:[1,0,0]
	v_pk_mul_f32 v[44:45], v[36:37], v[46:47] op_sel:[0,0] op_sel_hi:[0,1]
	v_pk_add_f32 v[22:23], v[22:23], v[86:87] neg_lo:[0,1] neg_hi:[0,1]
	v_pk_add_f32 v[42:43], v[42:43], v[98:99] neg_lo:[0,1] neg_hi:[0,1]
	v_pk_add_f32 v[122:123], v[118:119], v[120:121]
	v_pk_fma_f32 v[36:37], v[36:37], v[46:47], v[44:45] op_sel:[1,1,0] op_sel_hi:[1,0,1] neg_lo:[1,0,0]
	v_pk_mul_f32 v[44:45], v[40:41], v[48:49] op_sel:[0,0] op_sel_hi:[0,1]
	v_pk_add_f32 v[86:87], v[22:23], v[42:43] op_sel:[0,1] op_sel_hi:[1,0] neg_lo:[0,1] neg_hi:[0,1]
	v_pk_add_f32 v[22:23], v[22:23], v[42:43] op_sel:[0,1] op_sel_hi:[1,0]
	v_pk_fma_f32 v[40:41], v[40:41], v[48:49], v[44:45] op_sel:[1,1,0] op_sel_hi:[1,0,1] neg_lo:[1,0,0]
	v_pk_mul_f32 v[44:45], v[106:107], v[20:21] op_sel:[0,0] op_sel_hi:[0,1]
	v_pk_mul_f32 v[90:91], v[110:111], v[48:49] op_sel:[0,0] op_sel_hi:[0,1]
	v_pk_add_f32 v[100:101], v[122:123], v[60:61]
	v_pk_add_f32 v[102:103], v[88:89], v[64:65]
	v_mov_b32_e32 v42, v86
	v_mov_b32_e32 v43, v23
	v_pk_fma_f32 v[44:45], v[106:107], v[20:21], v[44:45] op_sel:[1,1,0] op_sel_hi:[1,0,1] neg_lo:[1,0,0]
	v_pk_fma_f32 v[90:91], v[110:111], v[48:49], v[90:91] op_sel:[1,1,0] op_sel_hi:[1,0,1] neg_lo:[1,0,0]
	v_pk_mul_f32 v[96:97], v[114:115], v[58:59] op_sel:[0,0] op_sel_hi:[0,1]
	v_pk_add_f32 v[104:105], v[100:101], v[102:103]
	v_pk_add_f32 v[100:101], v[100:101], v[102:103] neg_lo:[0,1] neg_hi:[0,1]
	v_pk_add_f32 v[98:99], v[42:43], v[112:113]
	v_pk_add_f32 v[102:103], v[108:109], v[116:117]
	v_pk_add_f32 v[110:111], v[118:119], v[120:121] neg_lo:[0,1] neg_hi:[0,1]
	v_mov_b32_e32 v23, v87
	v_pk_fma_f32 v[96:97], v[114:115], v[58:59], v[96:97] op_sel:[1,1,0] op_sel_hi:[1,0,1] neg_lo:[1,0,0]
	v_pk_add_f32 v[60:61], v[122:123], v[60:61] neg_lo:[0,1] neg_hi:[0,1]
	v_pk_add_f32 v[64:65], v[88:89], v[64:65] neg_lo:[0,1] neg_hi:[0,1]
	v_pk_add_f32 v[106:107], v[98:99], v[102:103]
	v_pk_add_f32 v[98:99], v[98:99], v[102:103] neg_lo:[0,1] neg_hi:[0,1]
	v_pk_add_f32 v[102:103], v[108:109], v[116:117] neg_lo:[0,1] neg_hi:[0,1]
	v_pk_add_f32 v[42:43], v[42:43], v[112:113] neg_lo:[0,1] neg_hi:[0,1]
	v_pk_add_f32 v[112:113], v[110:111], v[36:37]
	v_pk_add_f32 v[114:115], v[24:25], v[40:41]
	v_pk_add_f32 v[24:25], v[24:25], v[40:41] neg_lo:[0,1] neg_hi:[0,1]
	v_pk_add_f32 v[36:37], v[110:111], v[36:37] neg_lo:[0,1] neg_hi:[0,1]
	v_pk_add_f32 v[86:87], v[22:23], v[90:91]
	v_pk_add_f32 v[110:111], v[44:45], v[96:97]
	v_pk_add_f32 v[44:45], v[44:45], v[96:97] neg_lo:[0,1] neg_hi:[0,1]
	v_pk_add_f32 v[22:23], v[22:23], v[90:91] neg_lo:[0,1] neg_hi:[0,1]
	v_pk_add_f32 v[88:89], v[60:61], v[64:65] op_sel:[0,1] op_sel_hi:[1,0] neg_lo:[0,1] neg_hi:[0,1]
	v_pk_add_f32 v[60:61], v[60:61], v[64:65] op_sel:[0,1] op_sel_hi:[1,0]
	v_pk_add_f32 v[108:109], v[42:43], v[102:103] op_sel:[0,1] op_sel_hi:[1,0] neg_lo:[0,1] neg_hi:[0,1]
	v_pk_add_f32 v[42:43], v[42:43], v[102:103] op_sel:[0,1] op_sel_hi:[1,0]
	v_pk_add_f32 v[40:41], v[36:37], v[24:25] op_sel:[0,1] op_sel_hi:[1,0] neg_lo:[0,1] neg_hi:[0,1]
	v_pk_add_f32 v[24:25], v[36:37], v[24:25] op_sel:[0,1] op_sel_hi:[1,0]
	v_pk_add_f32 v[90:91], v[22:23], v[44:45] op_sel:[0,1] op_sel_hi:[1,0] neg_lo:[0,1] neg_hi:[0,1]
	v_pk_add_f32 v[22:23], v[22:23], v[44:45] op_sel:[0,1] op_sel_hi:[1,0]
	v_mov_b32_e32 v64, v88
	v_mov_b32_e32 v65, v61
	v_mov_b32_e32 v102, v108
	v_mov_b32_e32 v103, v43
	v_pk_add_f32 v[116:117], v[112:113], v[114:115]
	v_pk_add_f32 v[112:113], v[112:113], v[114:115] neg_lo:[0,1] neg_hi:[0,1]
	v_mov_b32_e32 v36, v40
	v_mov_b32_e32 v37, v25
	v_pk_add_f32 v[114:115], v[86:87], v[110:111]
	v_pk_add_f32 v[86:87], v[86:87], v[110:111] neg_lo:[0,1] neg_hi:[0,1]
	v_mov_b32_e32 v44, v90
	v_mov_b32_e32 v45, v23
	ds_write2_b64 v1, v[104:105], v[106:107] offset1:34
	ds_write2_b64 v1, v[116:117], v[114:115] offset0:68 offset1:102
	ds_write2_b64 v1, v[64:65], v[102:103] offset0:136 offset1:170
	ds_write2_b64 v1, v[36:37], v[44:45] offset0:204 offset1:238
	ds_write2_b64 v26, v[100:101], v[98:99] offset0:16 offset1:50
	ds_write2_b64 v26, v[112:113], v[86:87] offset0:84 offset1:118
	v_mov_b32_e32 v61, v89
	v_mov_b32_e32 v43, v109
	v_mov_b32_e32 v25, v41
	v_mov_b32_e32 v23, v91
	v_mov_b32_e32 v1, v0
	ds_write2_b64 v26, v[60:61], v[42:43] offset0:152 offset1:186
	ds_write2_b64 v26, v[24:25], v[22:23] offset0:220 offset1:254
	s_waitcnt lgkmcnt(0)
	s_barrier
	v_lshlrev_b32_e32 v26, 16, v6
	v_and_b32_e32 v22, 0x1ff, v1
	v_lshlrev_b32_e32 v1, 4, v1
	v_and_or_b32 v1, v1, s29, v22
	v_cvt_f32_u32_e32 v22, v22
	v_ashrrev_i32_e32 v23, 4, v1
	v_lshlrev_b32_e32 v23, 3, v23
	v_lshlrev_b32_e32 v1, 3, v1
	v_add3_u32 v1, 0, v23, v1
	v_mul_f32_e32 v23, 0x39000000, v22
	v_cos_f32_e32 v22, v23
	v_sin_f32_e32 v23, v23
	ds_read_b64 v[24:25], v1
	ds_read_b64 v[36:37], v1 offset:4352
	ds_read_b64 v[40:41], v1 offset:8704
	ds_read_b64 v[42:43], v1 offset:13056
	ds_read_b64 v[44:45], v1 offset:17408
	ds_read_b64 v[60:61], v1 offset:21760
	ds_read_b64 v[64:65], v1 offset:26112
	ds_read_b64 v[86:87], v1 offset:30464
	ds_read_b64 v[88:89], v1 offset:34816
	ds_read_b64 v[90:91], v1 offset:39168
	ds_read_b64 v[96:97], v1 offset:43520
	ds_read_b64 v[98:99], v1 offset:47872
	ds_read_b64 v[100:101], v1 offset:52224
	ds_read_b64 v[102:103], v1 offset:56576
	ds_read_b64 v[104:105], v1 offset:60928
	ds_read_b64 v[106:107], v1 offset:65280
	s_nop 1
	v_and_b32_e32 v6, 0xffff0000, v6
	v_pk_mul_f32 v[108:109], v[22:23], v[22:23] op_sel:[0,0] op_sel_hi:[0,1]
	s_waitcnt lgkmcnt(14)
	v_pk_mul_f32 v[136:137], v[36:37], v[22:23] op_sel:[0,0] op_sel_hi:[0,1]
	v_mov_b32_e32 v30, v6
	v_pk_fma_f32 v[108:109], v[22:23], v[22:23], v[108:109] op_sel:[1,1,0] op_sel_hi:[1,0,1] neg_lo:[1,0,0]
	s_nop 0
	v_pk_mul_f32 v[112:113], v[108:109], v[108:109] op_sel:[0,0] op_sel_hi:[0,1]
	v_pk_mul_f32 v[110:111], v[108:109], v[22:23] op_sel:[0,0] op_sel_hi:[0,1]
	s_nop 0
	v_pk_fma_f32 v[112:113], v[108:109], v[108:109], v[112:113] op_sel:[1,1,0] op_sel_hi:[1,0,1] neg_lo:[1,0,0]
	v_pk_fma_f32 v[110:111], v[108:109], v[22:23], v[110:111] op_sel:[1,1,0] op_sel_hi:[1,0,1] neg_lo:[1,0,0]
	s_nop 0
	v_pk_mul_f32 v[120:121], v[112:113], v[112:113] op_sel:[0,0] op_sel_hi:[0,1]
	v_pk_mul_f32 v[114:115], v[112:113], v[22:23] op_sel:[0,0] op_sel_hi:[0,1]
	v_pk_mul_f32 v[116:117], v[110:111], v[110:111] op_sel:[0,0] op_sel_hi:[0,1]
	v_pk_mul_f32 v[118:119], v[112:113], v[110:111] op_sel:[0,0] op_sel_hi:[0,1]
	s_nop 0
	v_pk_fma_f32 v[120:121], v[112:113], v[112:113], v[120:121] op_sel:[1,1,0] op_sel_hi:[1,0,1] neg_lo:[1,0,0]
	v_pk_fma_f32 v[114:115], v[112:113], v[22:23], v[114:115] op_sel:[1,1,0] op_sel_hi:[1,0,1] neg_lo:[1,0,0]
	v_pk_fma_f32 v[116:117], v[110:111], v[110:111], v[116:117] op_sel:[1,1,0] op_sel_hi:[1,0,1] neg_lo:[1,0,0]
	v_pk_fma_f32 v[118:119], v[112:113], v[110:111], v[118:119] op_sel:[1,1,0] op_sel_hi:[1,0,1] neg_lo:[1,0,0]
	s_nop 0
	v_pk_mul_f32 v[122:123], v[120:121], v[22:23] op_sel:[0,0] op_sel_hi:[0,1]
	v_pk_mul_f32 v[124:125], v[114:115], v[114:115] op_sel:[0,0] op_sel_hi:[0,1]
	v_pk_mul_f32 v[126:127], v[120:121], v[110:111] op_sel:[0,0] op_sel_hi:[0,1]
	v_pk_mul_f32 v[128:129], v[116:117], v[116:117] op_sel:[0,0] op_sel_hi:[0,1]
	v_pk_mul_f32 v[130:131], v[120:121], v[114:115] op_sel:[0,0] op_sel_hi:[0,1]
	v_pk_mul_f32 v[132:133], v[118:119], v[118:119] op_sel:[0,0] op_sel_hi:[0,1]
	s_nop 0
	v_pk_fma_f32 v[122:123], v[120:121], v[22:23], v[122:123] op_sel:[1,1,0] op_sel_hi:[1,0,1] neg_lo:[1,0,0]
	v_pk_fma_f32 v[22:23], v[36:37], v[22:23], v[136:137] op_sel:[1,1,0] op_sel_hi:[1,0,1] neg_lo:[1,0,0]
	s_waitcnt lgkmcnt(13)
	v_pk_mul_f32 v[36:37], v[40:41], v[108:109] op_sel:[0,0] op_sel_hi:[0,1]
	v_pk_fma_f32 v[124:125], v[114:115], v[114:115], v[124:125] op_sel:[1,1,0] op_sel_hi:[1,0,1] neg_lo:[1,0,0]
	v_pk_fma_f32 v[126:127], v[120:121], v[110:111], v[126:127] op_sel:[1,1,0] op_sel_hi:[1,0,1] neg_lo:[1,0,0]
	v_pk_fma_f32 v[128:129], v[116:117], v[116:117], v[128:129] op_sel:[1,1,0] op_sel_hi:[1,0,1] neg_lo:[1,0,0]
	v_pk_fma_f32 v[130:131], v[120:121], v[114:115], v[130:131] op_sel:[1,1,0] op_sel_hi:[1,0,1] neg_lo:[1,0,0]
	v_pk_fma_f32 v[132:133], v[118:119], v[118:119], v[132:133] op_sel:[1,1,0] op_sel_hi:[1,0,1] neg_lo:[1,0,0]
	s_nop 0
	v_pk_fma_f32 v[36:37], v[40:41], v[108:109], v[36:37] op_sel:[1,1,0] op_sel_hi:[1,0,1] neg_lo:[1,0,0]
	s_waitcnt lgkmcnt(12)
	v_pk_mul_f32 v[40:41], v[42:43], v[110:111] op_sel:[0,0] op_sel_hi:[0,1]
	v_pk_mul_f32 v[134:135], v[120:121], v[118:119] op_sel:[0,0] op_sel_hi:[0,1]
	s_nop 0
	v_pk_fma_f32 v[40:41], v[42:43], v[110:111], v[40:41] op_sel:[1,1,0] op_sel_hi:[1,0,1] neg_lo:[1,0,0]
	s_waitcnt lgkmcnt(11)
	v_pk_mul_f32 v[42:43], v[44:45], v[112:113] op_sel:[0,0] op_sel_hi:[0,1]
	v_pk_fma_f32 v[134:135], v[120:121], v[118:119], v[134:135] op_sel:[1,1,0] op_sel_hi:[1,0,1] neg_lo:[1,0,0]
	s_nop 0
	v_pk_fma_f32 v[42:43], v[44:45], v[112:113], v[42:43] op_sel:[1,1,0] op_sel_hi:[1,0,1] neg_lo:[1,0,0]
	s_waitcnt lgkmcnt(10)
	v_pk_mul_f32 v[44:45], v[60:61], v[114:115] op_sel:[0,0] op_sel_hi:[0,1]
	s_nop 0
	v_pk_fma_f32 v[44:45], v[60:61], v[114:115], v[44:45] op_sel:[1,1,0] op_sel_hi:[1,0,1] neg_lo:[1,0,0]
	s_waitcnt lgkmcnt(9)
	v_pk_mul_f32 v[60:61], v[64:65], v[116:117] op_sel:[0,0] op_sel_hi:[0,1]
	s_nop 0
	v_pk_fma_f32 v[60:61], v[64:65], v[116:117], v[60:61] op_sel:[1,1,0] op_sel_hi:[1,0,1] neg_lo:[1,0,0]
	s_waitcnt lgkmcnt(8)
	v_pk_mul_f32 v[64:65], v[86:87], v[118:119] op_sel:[0,0] op_sel_hi:[0,1]
	s_nop 0
	v_pk_fma_f32 v[64:65], v[86:87], v[118:119], v[64:65] op_sel:[1,1,0] op_sel_hi:[1,0,1] neg_lo:[1,0,0]
	s_waitcnt lgkmcnt(7)
	v_pk_mul_f32 v[86:87], v[88:89], v[120:121] op_sel:[0,0] op_sel_hi:[0,1]
	s_nop 0
	v_pk_fma_f32 v[86:87], v[88:89], v[120:121], v[86:87] op_sel:[1,1,0] op_sel_hi:[1,0,1] neg_lo:[1,0,0]
	s_waitcnt lgkmcnt(6)
	v_pk_mul_f32 v[88:89], v[90:91], v[122:123] op_sel:[0,0] op_sel_hi:[0,1]
	s_nop 0
	v_pk_fma_f32 v[88:89], v[90:91], v[122:123], v[88:89] op_sel:[1,1,0] op_sel_hi:[1,0,1] neg_lo:[1,0,0]
	s_waitcnt lgkmcnt(5)
	v_pk_mul_f32 v[90:91], v[96:97], v[124:125] op_sel:[0,0] op_sel_hi:[0,1]
	s_nop 0
	v_pk_fma_f32 v[90:91], v[96:97], v[124:125], v[90:91] op_sel:[1,1,0] op_sel_hi:[1,0,1] neg_lo:[1,0,0]
	s_waitcnt lgkmcnt(4)
	v_pk_mul_f32 v[96:97], v[98:99], v[126:127] op_sel:[0,0] op_sel_hi:[0,1]
	s_nop 0
	v_pk_fma_f32 v[96:97], v[98:99], v[126:127], v[96:97] op_sel:[1,1,0] op_sel_hi:[1,0,1] neg_lo:[1,0,0]
	s_waitcnt lgkmcnt(3)
	v_pk_mul_f32 v[98:99], v[100:101], v[128:129] op_sel:[0,0] op_sel_hi:[0,1]
	s_nop 0
	v_pk_fma_f32 v[98:99], v[100:101], v[128:129], v[98:99] op_sel:[1,1,0] op_sel_hi:[1,0,1] neg_lo:[1,0,0]
	s_waitcnt lgkmcnt(2)
	v_pk_mul_f32 v[100:101], v[102:103], v[130:131] op_sel:[0,0] op_sel_hi:[0,1]
	s_nop 0
	v_pk_fma_f32 v[100:101], v[102:103], v[130:131], v[100:101] op_sel:[1,1,0] op_sel_hi:[1,0,1] neg_lo:[1,0,0]
	s_waitcnt lgkmcnt(1)
	v_pk_mul_f32 v[102:103], v[104:105], v[132:133] op_sel:[0,0] op_sel_hi:[0,1]
	s_nop 0
	v_pk_fma_f32 v[102:103], v[104:105], v[132:133], v[102:103] op_sel:[1,1,0] op_sel_hi:[1,0,1] neg_lo:[1,0,0]
	s_waitcnt lgkmcnt(0)
	v_pk_mul_f32 v[104:105], v[106:107], v[134:135] op_sel:[0,0] op_sel_hi:[0,1]
	v_pk_add_f32 v[108:109], v[44:45], v[100:101] neg_lo:[0,1] neg_hi:[0,1]
	v_pk_fma_f32 v[104:105], v[106:107], v[134:135], v[104:105] op_sel:[1,1,0] op_sel_hi:[1,0,1] neg_lo:[1,0,0]
	v_pk_add_f32 v[106:107], v[22:23], v[88:89] neg_lo:[0,1] neg_hi:[0,1]
	v_pk_add_f32 v[112:113], v[60:61], v[102:103] neg_lo:[0,1] neg_hi:[0,1]
	v_pk_add_f32 v[110:111], v[106:107], v[108:109] op_sel:[0,1] op_sel_hi:[1,0] neg_lo:[0,1] neg_hi:[0,1]
	v_pk_add_f32 v[106:107], v[106:107], v[108:109] op_sel:[0,1] op_sel_hi:[1,0]
	v_mov_b32_e32 v108, v110
	v_mov_b32_e32 v109, v107
	v_mov_b32_e32 v107, v111
	v_pk_add_f32 v[110:111], v[36:37], v[90:91] neg_lo:[0,1] neg_hi:[0,1]
	v_pk_add_f32 v[116:117], v[64:65], v[104:105] neg_lo:[0,1] neg_hi:[0,1]
	v_pk_add_f32 v[114:115], v[110:111], v[112:113] op_sel:[0,1] op_sel_hi:[1,0] neg_lo:[0,1] neg_hi:[0,1]
	v_pk_add_f32 v[110:111], v[110:111], v[112:113] op_sel:[0,1] op_sel_hi:[1,0]
	v_mov_b32_e32 v112, v114
	v_mov_b32_e32 v113, v111
	v_mov_b32_e32 v111, v115
	v_pk_add_f32 v[114:115], v[40:41], v[96:97] neg_lo:[0,1] neg_hi:[0,1]
	v_pk_add_f32 v[22:23], v[22:23], v[88:89]
	v_pk_add_f32 v[44:45], v[44:45], v[100:101]
	v_pk_add_f32 v[118:119], v[114:115], v[116:117] op_sel:[0,1] op_sel_hi:[1,0] neg_lo:[0,1] neg_hi:[0,1]
	v_pk_add_f32 v[114:115], v[114:115], v[116:117] op_sel:[0,1] op_sel_hi:[1,0]
	v_pk_add_f32 v[88:89], v[22:23], v[44:45]
	v_pk_add_f32 v[22:23], v[22:23], v[44:45] neg_lo:[0,1] neg_hi:[0,1]
	v_pk_add_f32 v[36:37], v[36:37], v[90:91]
	v_pk_add_f32 v[44:45], v[60:61], v[102:103]
	v_mov_b32_e32 v116, v118
	v_mov_b32_e32 v117, v115
	v_mov_b32_e32 v115, v119
	v_pk_mul_f32 v[118:119], v[108:109], v[38:39] op_sel:[0,0] op_sel_hi:[0,1]
	v_pk_add_f32 v[60:61], v[36:37], v[44:45]
	v_pk_fma_f32 v[38:39], v[108:109], v[38:39], v[118:119] op_sel:[1,1,0] op_sel_hi:[1,0,1] neg_lo:[1,0,0]
	v_pk_mul_f32 v[108:109], v[112:113], v[34:35] op_sel:[0,0] op_sel_hi:[0,1]
	v_pk_add_f32 v[36:37], v[36:37], v[44:45] neg_lo:[0,1] neg_hi:[0,1]
	v_pk_add_f32 v[40:41], v[40:41], v[96:97]
	v_pk_add_f32 v[44:45], v[64:65], v[104:105]
	v_pk_fma_f32 v[108:109], v[112:113], v[34:35], v[108:109] op_sel:[1,1,0] op_sel_hi:[1,0,1] neg_lo:[1,0,0]
	v_pk_mul_f32 v[112:113], v[116:117], v[20:21] op_sel:[0,0] op_sel_hi:[0,1]
	v_pk_add_f32 v[118:119], v[42:43], v[98:99]
	v_pk_add_f32 v[64:65], v[40:41], v[44:45]
	v_pk_add_f32 v[40:41], v[40:41], v[44:45] neg_lo:[0,1] neg_hi:[0,1]
	v_pk_mul_f32 v[44:45], v[22:23], v[34:35] op_sel:[0,0] op_sel_hi:[0,1]
	v_pk_fma_f32 v[112:113], v[116:117], v[20:21], v[112:113] op_sel:[1,1,0] op_sel_hi:[1,0,1] neg_lo:[1,0,0]
	v_pk_add_f32 v[116:117], v[24:25], v[86:87]
	v_pk_fma_f32 v[22:23], v[22:23], v[34:35], v[44:45] op_sel:[1,1,0] op_sel_hi:[1,0,1] neg_lo:[1,0,0]
	v_pk_mul_f32 v[34:35], v[36:37], v[46:47] op_sel:[0,0] op_sel_hi:[0,1]
	v_pk_add_f32 v[24:25], v[24:25], v[86:87] neg_lo:[0,1] neg_hi:[0,1]
	v_pk_fma_f32 v[34:35], v[36:37], v[46:47], v[34:35] op_sel:[1,1,0] op_sel_hi:[1,0,1] neg_lo:[1,0,0]
	v_pk_mul_f32 v[36:37], v[40:41], v[48:49] op_sel:[0,0] op_sel_hi:[0,1]
	v_pk_add_f32 v[42:43], v[42:43], v[98:99] neg_lo:[0,1] neg_hi:[0,1]
	v_pk_fma_f32 v[36:37], v[40:41], v[48:49], v[36:37] op_sel:[1,1,0] op_sel_hi:[1,0,1] neg_lo:[1,0,0]
	v_pk_mul_f32 v[40:41], v[106:107], v[20:21] op_sel:[0,0] op_sel_hi:[0,1]
	v_pk_add_f32 v[120:121], v[116:117], v[118:119]
	v_pk_fma_f32 v[20:21], v[106:107], v[20:21], v[40:41] op_sel:[1,1,0] op_sel_hi:[1,0,1] neg_lo:[1,0,0]
	v_pk_mul_f32 v[40:41], v[110:111], v[48:49] op_sel:[0,0] op_sel_hi:[0,1]
	v_pk_add_f32 v[86:87], v[24:25], v[42:43] op_sel:[0,1] op_sel_hi:[1,0] neg_lo:[0,1] neg_hi:[0,1]
	v_pk_add_f32 v[24:25], v[24:25], v[42:43] op_sel:[0,1] op_sel_hi:[1,0]
	v_pk_fma_f32 v[40:41], v[110:111], v[48:49], v[40:41] op_sel:[1,1,0] op_sel_hi:[1,0,1] neg_lo:[1,0,0]
	v_pk_mul_f32 v[44:45], v[114:115], v[58:59] op_sel:[0,0] op_sel_hi:[0,1]
	v_pk_add_f32 v[46:47], v[120:121], v[60:61]
	v_pk_add_f32 v[48:49], v[88:89], v[64:65]
	v_mov_b32_e32 v42, v86
	v_mov_b32_e32 v43, v25
	v_pk_add_f32 v[98:99], v[116:117], v[118:119] neg_lo:[0,1] neg_hi:[0,1]
	v_mov_b32_e32 v25, v87
	v_pk_fma_f32 v[44:45], v[114:115], v[58:59], v[44:45] op_sel:[1,1,0] op_sel_hi:[1,0,1] neg_lo:[1,0,0]
	v_pk_add_f32 v[58:59], v[46:47], v[48:49]
	v_pk_add_f32 v[46:47], v[46:47], v[48:49] neg_lo:[0,1] neg_hi:[0,1]
	v_pk_add_f32 v[48:49], v[120:121], v[60:61] neg_lo:[0,1] neg_hi:[0,1]
	v_pk_add_f32 v[60:61], v[88:89], v[64:65] neg_lo:[0,1] neg_hi:[0,1]
	v_pk_add_f32 v[88:89], v[42:43], v[108:109]
	v_pk_add_f32 v[90:91], v[38:39], v[112:113]
	v_pk_add_f32 v[38:39], v[38:39], v[112:113] neg_lo:[0,1] neg_hi:[0,1]
	v_pk_add_f32 v[42:43], v[42:43], v[108:109] neg_lo:[0,1] neg_hi:[0,1]
	v_pk_add_f32 v[100:101], v[98:99], v[34:35]
	v_pk_add_f32 v[102:103], v[22:23], v[36:37]
	v_pk_add_f32 v[22:23], v[22:23], v[36:37] neg_lo:[0,1] neg_hi:[0,1]
	v_pk_add_f32 v[34:35], v[98:99], v[34:35] neg_lo:[0,1] neg_hi:[0,1]
	v_pk_add_f32 v[86:87], v[24:25], v[40:41]
	v_pk_add_f32 v[98:99], v[20:21], v[44:45]
	v_pk_add_f32 v[20:21], v[20:21], v[44:45] neg_lo:[0,1] neg_hi:[0,1]
	v_pk_add_f32 v[24:25], v[24:25], v[40:41] neg_lo:[0,1] neg_hi:[0,1]
	v_pk_add_f32 v[64:65], v[48:49], v[60:61] op_sel:[0,1] op_sel_hi:[1,0] neg_lo:[0,1] neg_hi:[0,1]
	v_pk_add_f32 v[48:49], v[48:49], v[60:61] op_sel:[0,1] op_sel_hi:[1,0]
	v_pk_add_f32 v[96:97], v[88:89], v[90:91]
	v_pk_add_f32 v[88:89], v[88:89], v[90:91] neg_lo:[0,1] neg_hi:[0,1]
	v_pk_add_f32 v[90:91], v[42:43], v[38:39] op_sel:[0,1] op_sel_hi:[1,0] neg_lo:[0,1] neg_hi:[0,1]
	v_pk_add_f32 v[38:39], v[42:43], v[38:39] op_sel:[0,1] op_sel_hi:[1,0]
	v_pk_add_f32 v[36:37], v[34:35], v[22:23] op_sel:[0,1] op_sel_hi:[1,0] neg_lo:[0,1] neg_hi:[0,1]
	v_pk_add_f32 v[22:23], v[34:35], v[22:23] op_sel:[0,1] op_sel_hi:[1,0]
	v_pk_add_f32 v[40:41], v[24:25], v[20:21] op_sel:[0,1] op_sel_hi:[1,0] neg_lo:[0,1] neg_hi:[0,1]
	v_pk_add_f32 v[20:21], v[24:25], v[20:21] op_sel:[0,1] op_sel_hi:[1,0]
	v_mov_b32_e32 v61, v49
	v_mov_b32_e32 v43, v39
	v_mov_b32_e32 v35, v23
	v_mov_b32_e32 v25, v21
	v_mov_b32_e32 v49, v65
	v_mov_b32_e32 v39, v91
	v_mov_b32_e32 v23, v37
	v_mov_b32_e32 v21, v41
	v_mov_b32_e32 v60, v64
	v_mov_b32_e32 v42, v90
	v_pk_add_f32 v[104:105], v[100:101], v[102:103]
	v_pk_add_f32 v[100:101], v[100:101], v[102:103] neg_lo:[0,1] neg_hi:[0,1]
	v_mov_b32_e32 v34, v36
	v_pk_add_f32 v[102:103], v[86:87], v[98:99]
	v_pk_add_f32 v[86:87], v[86:87], v[98:99] neg_lo:[0,1] neg_hi:[0,1]
	v_mov_b32_e32 v24, v40
	ds_write_b64 v1, v[58:59]
	ds_write_b64 v1, v[96:97] offset:4352
	ds_write_b64 v1, v[104:105] offset:8704
	ds_write_b64 v1, v[102:103] offset:13056
	ds_write_b64 v1, v[60:61] offset:17408
	ds_write_b64 v1, v[42:43] offset:21760
	ds_write_b64 v1, v[34:35] offset:26112
	ds_write_b64 v1, v[24:25] offset:30464
	ds_write_b64 v1, v[46:47] offset:34816
	ds_write_b64 v1, v[88:89] offset:39168
	ds_write_b64 v1, v[100:101] offset:43520
	ds_write_b64 v1, v[86:87] offset:47872
	ds_write_b64 v1, v[48:49] offset:52224
	ds_write_b64 v1, v[38:39] offset:56576
	ds_write_b64 v1, v[22:23] offset:60928
	ds_write_b64 v1, v[20:21] offset:65280
	v_mov_b32_e32 v1, v0
	v_lshlrev_b32_e32 v65, 16, v9
	s_waitcnt lgkmcnt(0)
	s_barrier
	v_and_b32_e32 v47, 0xffff0000, v9
	v_lshlrev_b32_e32 v20, 2, v1
	v_and_b32_e32 v60, 0xffff0000, v8
	v_mov_b32_e32 v46, v65
	v_lshlrev_b32_e32 v24, 3, v1
	v_and_b32_e32 v20, -8, v20
	v_lshlrev_b32_e32 v1, 6, v1
	v_mov_b32_e32 v64, v60
	v_pk_mul_f32 v[86:87], v[74:75], v[46:47] op_sel_hi:[0,1]
	v_add3_u32 v1, 0, v20, v1
	v_pk_fma_f32 v[86:87], v[76:77], v[64:65], v[86:87] op_sel_hi:[0,1,1]
	v_mov_b32_e32 v46, v77
	v_mov_b32_e32 v32, v47
	v_mov_b32_e32 v75, v76
	ds_read2_b64 v[20:23], v1 offset1:1
	ds_read2_b64 v[34:37], v1 offset0:2 offset1:3
	ds_read2_b64 v[38:41], v1 offset0:4 offset1:5
	ds_read2_b64 v[42:45], v1 offset0:6 offset1:7
	v_pk_fma_f32 v[32:33], v[46:47], v[32:33], v[86:87] op_sel_hi:[0,1,1]
	v_and_b32_e32 v87, 16, v8
	v_and_b32_e32 v86, 0xffff0000, v7
	v_lshlrev_b32_e32 v7, 16, v7
	v_pk_mul_f32 v[30:31], v[74:75], v[30:31]
	v_and_b32_e32 v61, 16, v9
	v_lshlrev_b32_e32 v9, 16, v8
	v_mov_b32_e32 v8, v86
	v_pk_fma_f32 v[30:31], v[74:75], v[26:27], v[30:31] op_sel:[0,0,1] op_sel_hi:[1,0,0]
	v_pk_mov_b32 v[86:87], v[6:7], v[86:87] op_sel:[1,0]
	v_mov_b32_e32 v88, v18
	v_mov_b32_e32 v89, v62
	s_waitcnt lgkmcnt(3)
	v_mov_b32_e32 v90, v20
	v_mov_b32_e32 v91, v22
	v_pk_fma_f32 v[30:31], v[46:47], v[6:7], v[30:31] op_sel_hi:[0,1,1]
	v_pk_mul_f32 v[86:87], v[74:75], v[86:87] op_sel_hi:[0,1]
	v_pk_mov_b32 v[60:61], v[8:9], v[60:61] op_sel:[1,0]
	v_pk_fma_f32 v[88:89], v[70:71], v[88:89], v[90:91] op_sel_hi:[0,1,1]
	v_pk_add_f32 v[30:31], v[72:73], v[30:31] op_sel_hi:[0,1]
	v_pk_fma_f32 v[6:7], v[76:77], v[6:7], v[86:87] op_sel_hi:[0,1,1]
	v_pk_mul_f32 v[60:61], v[74:75], v[60:61] op_sel_hi:[0,1]
	v_pk_mul_f32 v[30:31], v[30:31], v[88:89]
	v_mov_b32_e32 v88, v10
	v_mov_b32_e32 v89, v14
	s_waitcnt lgkmcnt(2)
	v_mov_b32_e32 v90, v34
	v_mov_b32_e32 v91, v36
	v_pk_fma_f32 v[6:7], v[46:47], v[8:9], v[6:7] op_sel_hi:[0,1,1]
	v_pk_fma_f32 v[8:9], v[76:77], v[8:9], v[60:61] op_sel_hi:[0,1,1]
	v_pk_fma_f32 v[88:89], v[70:71], v[88:89], v[90:91] op_sel_hi:[0,1,1]
	v_pk_add_f32 v[6:7], v[72:73], v[6:7] op_sel_hi:[0,1]
	v_pk_fma_f32 v[8:9], v[46:47], v[64:65], v[8:9] op_sel_hi:[0,1,1]
	v_mov_b32_e32 v60, v12
	v_mov_b32_e32 v61, v16
	s_waitcnt lgkmcnt(0)
	v_mov_b32_e32 v64, v42
	v_mov_b32_e32 v65, v44
	v_pk_mul_f32 v[6:7], v[6:7], v[88:89]
	v_mov_b32_e32 v86, v94
	v_mov_b32_e32 v87, v92
	v_mov_b32_e32 v88, v38
	v_mov_b32_e32 v89, v40
	v_pk_fma_f32 v[60:61], v[70:71], v[60:61], v[64:65] op_sel_hi:[0,1,1]
	v_lshlrev_b32_e32 v65, 16, v5
	v_lshlrev_b32_e32 v48, 16, v2
	v_and_b32_e32 v59, 0xffff0000, v5
	v_pk_fma_f32 v[86:87], v[70:71], v[86:87], v[88:89] op_sel_hi:[0,1,1]
	v_pk_add_f32 v[8:9], v[72:73], v[8:9] op_sel_hi:[0,1]
	v_mov_b32_e32 v58, v65
	v_and_b32_e32 v2, 0xffff0000, v2
	v_pk_mul_f32 v[8:9], v[8:9], v[86:87]
	v_pk_mul_f32 v[86:87], v[74:75], v[58:59] op_sel_hi:[0,1]
	v_mov_b32_e32 v28, v59
	v_and_b32_e32 v59, 16, v4
	v_and_b32_e32 v58, 0xffff0000, v3
	v_lshlrev_b32_e32 v3, 16, v3
	v_mov_b32_e32 v26, v2
	v_mov_b32_e32 v14, v11
	v_mov_b32_e32 v36, v35
	v_pk_add_f32 v[32:33], v[72:73], v[32:33] op_sel_hi:[0,1]
	v_mov_b32_e32 v22, v21
	v_pk_mul_f32 v[20:21], v[74:75], v[26:27]
	v_pk_fma_f32 v[10:11], v[70:71], v[14:15], v[36:37] op_sel_hi:[0,1,1]
	v_pk_mov_b32 v[14:15], v[2:3], v[58:59] op_sel:[1,0]
	v_pk_mul_f32 v[32:33], v[32:33], v[60:61]
	v_and_b32_e32 v61, 16, v5
	v_and_b32_e32 v60, 0xffff0000, v4
	v_lshlrev_b32_e32 v5, 16, v4
	v_mov_b32_e32 v4, v58
	v_pk_fma_f32 v[20:21], v[74:75], v[48:49], v[20:21] op_sel:[0,0,1] op_sel_hi:[1,0,0]
	v_pk_mul_f32 v[14:15], v[74:75], v[14:15] op_sel_hi:[0,1]
	v_pk_fma_f32 v[20:21], v[46:47], v[2:3], v[20:21] op_sel_hi:[0,1,1]
	v_pk_fma_f32 v[2:3], v[76:77], v[2:3], v[14:15] op_sel_hi:[0,1,1]
	v_pk_mov_b32 v[14:15], v[4:5], v[60:61] op_sel:[1,0]
	v_mov_b32_e32 v64, v60
	v_pk_mul_f32 v[14:15], v[74:75], v[14:15] op_sel_hi:[0,1]
	v_pk_fma_f32 v[2:3], v[46:47], v[4:5], v[2:3] op_sel_hi:[0,1,1]
	v_pk_fma_f32 v[4:5], v[76:77], v[4:5], v[14:15] op_sel_hi:[0,1,1]
	v_pk_fma_f32 v[86:87], v[76:77], v[64:65], v[86:87] op_sel_hi:[0,1,1]
	v_pk_add_f32 v[2:3], v[72:73], v[2:3] op_sel_hi:[0,1]
	v_mov_b32_e32 v92, v95
	v_mov_b32_e32 v40, v39
	v_pk_fma_f32 v[4:5], v[46:47], v[64:65], v[4:5] op_sel_hi:[0,1,1]
	v_pk_fma_f32 v[28:29], v[46:47], v[28:29], v[86:87] op_sel_hi:[0,1,1]
	v_mov_b32_e32 v62, v19
	v_pk_mul_f32 v[10:11], v[2:3], v[10:11]
	v_pk_fma_f32 v[2:3], v[70:71], v[92:93], v[40:41] op_sel_hi:[0,1,1]
	v_pk_add_f32 v[4:5], v[72:73], v[4:5] op_sel_hi:[0,1]
	v_mov_b32_e32 v16, v13
	v_mov_b32_e32 v44, v43
	v_ashrrev_i32_e32 v25, 31, v24
	v_pk_add_f32 v[28:29], v[72:73], v[28:29] op_sel_hi:[0,1]
	v_pk_fma_f32 v[18:19], v[70:71], v[62:63], v[22:23] op_sel_hi:[0,1,1]
	v_pk_add_f32 v[20:21], v[72:73], v[20:21] op_sel_hi:[0,1]
	v_pk_mul_f32 v[14:15], v[4:5], v[2:3]
	v_pk_fma_f32 v[2:3], v[70:71], v[16:17], v[44:45] op_sel_hi:[0,1,1]
	v_lshl_add_u64 v[16:17], v[24:25], 1, s[42:43]
	v_pk_mul_f32 v[18:19], v[20:21], v[18:19]
	v_pk_mul_f32 v[12:13], v[28:29], v[2:3]
	v_cvt_pk_bf16_f32 v2, v30, v31
	v_cvt_pk_bf16_f32 v3, v6, v7
	v_cvt_pk_bf16_f32 v4, v8, v9
	v_cvt_pk_bf16_f32 v5, v32, v33
	v_add_co_u32_e32 v6, vcc, 0x2000, v16
	global_store_dwordx4 v[16:17], v[2:5], off
	s_nop 0
	v_addc_co_u32_e32 v7, vcc, 0, v17, vcc
	v_cvt_pk_bf16_f32 v2, v18, v19
	v_cvt_pk_bf16_f32 v3, v10, v11
	v_cvt_pk_bf16_f32 v4, v14, v15
	v_cvt_pk_bf16_f32 v5, v12, v13
	global_store_dwordx4 v[6:7], v[2:5], off
	s_barrier
.LBB0_409:
	s_and_b64 vcc, exec, s[30:31]
	s_mov_b32 s62, 0xf800000
	s_mov_b32 s63, 0x7003000
	s_cbranch_vccz .LBB0_382
	v_mov_b32_e32 v51, v0
	v_mov_b32_e32 v58, 0
	v_lshlrev_b32_e32 v2, 4, v51
	v_ashrrev_i32_e32 v3, 31, v2
	v_lshl_add_u64 v[4:5], v[2:3], 1, s[52:53]
	global_load_dwordx4 v[34:37], v[4:5], off offset:16
	global_load_dwordx4 v[38:41], v[4:5], off
	v_cmp_lt_i32_e32 vcc, 0, v51
	v_mov_b32_e32 v60, 0
	v_mov_b32_e32 v234, 0
	s_and_saveexec_b64 s[4:5], vcc
	s_cbranch_execz .LBB0_412
	global_load_ushort v234, v[4:5], off offset:-2
.LBB0_412:
	s_or_b64 exec, exec, s[4:5]
	s_movk_i32 s3, 0x1ff
	v_cmp_gt_i32_e64 s[38:39], s3, v51
	v_mov_b32_e32 v235, 0
	s_and_saveexec_b64 s[4:5], s[38:39]
	s_cbranch_execz .LBB0_414
	global_load_ushort v235, v[4:5], off offset:32
.LBB0_414:
	s_or_b64 exec, exec, s[4:5]
	s_add_u32 s4, s52, 0x4000
	s_addc_u32 s5, s53, 0
	v_lshl_add_u64 v[4:5], v[2:3], 1, s[4:5]
	global_load_dwordx4 v[42:45], v[4:5], off offset:16
	global_load_dwordx4 v[46:49], v[4:5], off
	v_mov_b32_e32 v59, 0
	v_mov_b32_e32 v61, 0
	v_mov_b32_e32 v243, 0
	s_and_saveexec_b64 s[4:5], vcc
	s_cbranch_execz .LBB0_416
	global_load_ushort v243, v[4:5], off offset:-2
.LBB0_416:
	s_or_b64 exec, exec, s[4:5]
	v_mov_b32_e32 v244, 0
	s_and_saveexec_b64 s[4:5], s[38:39]
	s_cbranch_execz .LBB0_418
	global_load_ushort v244, v[4:5], off offset:32
.LBB0_418:
	s_or_b64 exec, exec, s[4:5]
	v_lshl_add_u64 v[4:5], v[2:3], 1, s[50:51]
	global_load_dwordx4 v[26:29], v[4:5], off offset:16
	global_load_dwordx4 v[30:33], v[4:5], off
	v_mov_b32_e32 v101, 0
	v_mov_b32_e32 v75, 0
	v_mov_b32_e32 v245, 0
	s_and_saveexec_b64 s[4:5], vcc
	s_cbranch_execz .LBB0_420
	global_load_ushort v245, v[4:5], off offset:-2
.LBB0_420:
	s_or_b64 exec, exec, s[4:5]
	v_mov_b32_e32 v246, 0
	s_and_saveexec_b64 s[4:5], s[38:39]
	s_cbranch_execz .LBB0_422
	global_load_ushort v246, v[4:5], off offset:32
.LBB0_422:
	s_or_b64 exec, exec, s[4:5]
	s_add_u32 s4, s50, 0x4000
	s_addc_u32 s5, s51, 0
	v_lshl_add_u64 v[4:5], v[2:3], 1, s[4:5]
	global_load_dwordx4 v[18:21], v[4:5], off offset:16
	global_load_dwordx4 v[22:25], v[4:5], off
	v_mov_b32_e32 v99, 0
	v_mov_b32_e32 v73, 0
	v_mov_b32_e32 v247, 0
	s_and_saveexec_b64 s[4:5], vcc
	s_cbranch_execz .LBB0_424
	global_load_ushort v247, v[4:5], off offset:-2
.LBB0_424:
	s_or_b64 exec, exec, s[4:5]
	v_mov_b32_e32 v248, 0
	s_and_saveexec_b64 s[4:5], s[38:39]
	s_cbranch_execz .LBB0_426
	global_load_ushort v248, v[4:5], off offset:32
.LBB0_426:
	s_or_b64 exec, exec, s[4:5]
	v_lshl_add_u64 v[4:5], v[2:3], 1, s[48:49]
	global_load_dwordx4 v[10:13], v[4:5], off offset:16
	global_load_dwordx4 v[14:17], v[4:5], off
	v_mov_b32_e32 v81, 0
	v_mov_b32_e32 v71, 0
	v_mov_b32_e32 v249, 0
	s_and_saveexec_b64 s[4:5], vcc
	s_cbranch_execz .LBB0_428
	global_load_ushort v249, v[4:5], off offset:-2
.LBB0_428:
	s_or_b64 exec, exec, s[4:5]
	v_mov_b32_e32 v250, 0
	s_and_saveexec_b64 s[4:5], s[38:39]
	s_cbranch_execz .LBB0_430
	global_load_ushort v250, v[4:5], off offset:32
.LBB0_430:
	s_or_b64 exec, exec, s[4:5]
	s_add_u32 s4, s48, 0x4000
	s_addc_u32 s5, s49, 0
	v_lshl_add_u64 v[62:63], v[2:3], 1, s[4:5]
	global_load_dwordx4 v[2:5], v[62:63], off offset:16
	global_load_dwordx4 v[6:9], v[62:63], off
	v_mov_b32_e32 v79, 0
	v_mov_b32_e32 v1, 0
	v_mov_b32_e32 v251, 0
	s_and_saveexec_b64 s[4:5], vcc
	s_cbranch_execz .LBB0_432
	global_load_ushort v251, v[62:63], off offset:-2
.LBB0_432:
	s_or_b64 exec, exec, s[4:5]
	v_mov_b32_e32 v252, 0
	s_and_saveexec_b64 s[4:5], s[38:39]
	s_cbranch_execz .LBB0_381
	global_load_ushort v252, v[62:63], off offset:32
	s_branch .LBB0_381
